# plus: each k-iteration's first two global prefetch loads issued before the workgroup barrier instead of after it
# baseline (speedup 1.0000x reference)
; template <bool trans>
; DI void gemm_core(const GTile& tl, const GTile& nx, bool has_next  , bool chain  , bool pre, u32x4 (&ra)[4], u32x4 (&rb)[4], char* smem, f32x16 (&acc)[2][4]) {
;     ...
;   const int nk = K / 64;
;   if (!pre) { G_LOAD(0); G_STORE(0); G_LOAD(1); }
;   for (int kt = 0; kt < nk; ++kt) {
;     __syncthreads();
;     G_COMPUTE(kt & 1, kt);
;   }
.LBB0_103:
	v_lshl_add_u64 v[190:191], s[0:1], 0, v[192:193]
	v_lshl_add_u64 v[188:189], s[6:7], 0, v[192:193]
	s_waitcnt lgkmcnt(0)
	s_barrier
	global_load_dwordx4 v[218:221], v[190:191], off offset:256
	global_load_dwordx4 v[222:225], v[188:189], off offset:256
	s_lshr_b32 s1, s33, 1
	s_and_b32 s0, s33, 0xc0
	v_and_b32_e32 v10, 31, v8
	s_and_b32 s1, s1, 0xfffff80
	v_or_b32_e32 v12, s1, v10
	v_or_b32_e32 v10, s0, v10
	v_add3_u32 v215, 16, v11, v9
	v_lshrrev_b32_e32 v8, 1, v8
	v_mul_u32_u24_e32 v242, 0x90, v10
	v_and_b32_e32 v243, 16, v8
	v_add_u32_e32 v209, 0x12000, v215
	v_mul_lo_u32 v208, v12, s45
	v_add3_u32 v205, 16, v242, v243
	v_add_u32_e32 v210, 0x1b000, v215
	ds_write_b128 v209, v[0:3]
	s_waitcnt vmcnt(6)
	ds_write_b128 v210, v[4:7]
	v_add3_u32 v204, 16, v208, v243
	ds_read_b128 v[0:3], v205 offset:36864
	ds_read_b128 v[4:7], v205 offset:41472
	ds_read_b128 v[8:11], v204
	ds_read_b128 v[12:15], v204 offset:4608
	v_lshl_add_u64 v[184:185], v[190:191], 0, s[42:43]
	v_lshl_add_u64 v[186:187], s[28:29], 0, v[192:193]
	v_lshl_add_u64 v[194:195], v[190:191], 0, s[34:35]
	v_lshl_add_u64 v[196:197], s[26:27], 0, v[192:193]
	s_setprio 1
	s_waitcnt lgkmcnt(1)
	v_mfma_f32_32x32x16_bf16 v[112:127], v[8:11], v[0:3], 0
	v_mfma_f32_32x32x16_bf16 v[48:63], v[8:11], v[4:7], 0
	s_waitcnt lgkmcnt(0)
	v_mfma_f32_32x32x16_bf16 v[96:111], v[12:15], v[0:3], 0
	v_mfma_f32_32x32x16_bf16 v[32:47], v[12:15], v[4:7], 0
	ds_read_b128 v[8:11], v204 offset:9216
	ds_read_b128 v[12:15], v204 offset:13824
	s_waitcnt lgkmcnt(1)
	v_mfma_f32_32x32x16_bf16 v[80:95], v[8:11], v[0:3], 0
	v_mfma_f32_32x32x16_bf16 v[16:31], v[8:11], v[4:7], 0
	s_waitcnt lgkmcnt(0)
	v_mfma_f32_32x32x16_bf16 v[64:79], v[12:15], v[0:3], 0
	v_mfma_f32_32x32x16_bf16 v[0:15], v[12:15], v[4:7], 0
	s_setprio 0
	global_load_dwordx4 v[226:229], v[194:195], off offset:256
	global_load_dwordx4 v[230:233], v[196:197], off offset:256
	v_add_u32_e32 v212, 0x14400, v215
	v_add_u32_e32 v211, 0x1d400, v215
	ds_write_b128 v212, v[176:179]
	s_waitcnt vmcnt(7)
	ds_write_b128 v211, v[180:183]
	ds_read_b128 v[176:179], v205 offset:36896
	ds_read_b128 v[180:183], v205 offset:41504
	ds_read_b128 v[198:201], v204 offset:32
	ds_read_b128 v[234:237], v204 offset:4640
	s_setprio 1
	s_waitcnt lgkmcnt(1)
	v_mfma_f32_32x32x16_bf16 v[112:127], v[198:201], v[176:179], v[112:127]
	v_mfma_f32_32x32x16_bf16 v[48:63], v[198:201], v[180:183], v[48:63]
	s_waitcnt lgkmcnt(0)
	v_mfma_f32_32x32x16_bf16 v[96:111], v[234:237], v[176:179], v[96:111]
	v_mfma_f32_32x32x16_bf16 v[32:47], v[234:237], v[180:183], v[32:47]
	ds_read_b128 v[198:201], v204 offset:9248
	ds_read_b128 v[234:237], v204 offset:13856
	s_waitcnt lgkmcnt(1)
	v_mfma_f32_32x32x16_bf16 v[80:95], v[198:201], v[176:179], v[80:95]
	v_mfma_f32_32x32x16_bf16 v[16:31], v[198:201], v[180:183], v[16:31]
	s_waitcnt lgkmcnt(0)
	v_mfma_f32_32x32x16_bf16 v[64:79], v[234:237], v[176:179], v[64:79]
	v_mfma_f32_32x32x16_bf16 v[0:15], v[234:237], v[180:183], v[0:15]
	s_setprio 0
	global_load_dwordx4 v[176:179], v[184:185], off offset:256
	global_load_dwordx4 v[180:183], v[186:187], off offset:256
	v_add_u32_e32 v214, 0x16800, v215
	v_add_u32_e32 v213, 0x1f800, v215
	ds_write_b128 v214, v[168:171]
	s_waitcnt vmcnt(8)
	ds_write_b128 v213, v[172:175]
	ds_read_b128 v[168:171], v205 offset:36928
	ds_read_b128 v[172:175], v205 offset:41536
	ds_read_b128 v[198:201], v204 offset:64
	ds_read_b128 v[234:237], v204 offset:4672
	s_setprio 1
	s_waitcnt lgkmcnt(1)
	v_mfma_f32_32x32x16_bf16 v[112:127], v[198:201], v[168:171], v[112:127]
	v_mfma_f32_32x32x16_bf16 v[48:63], v[198:201], v[172:175], v[48:63]
	s_waitcnt lgkmcnt(0)
	v_mfma_f32_32x32x16_bf16 v[96:111], v[234:237], v[168:171], v[96:111]
	v_mfma_f32_32x32x16_bf16 v[32:47], v[234:237], v[172:175], v[32:47]
	ds_read_b128 v[198:201], v204 offset:9280
	ds_read_b128 v[234:237], v204 offset:13888
	s_waitcnt lgkmcnt(1)
	v_mfma_f32_32x32x16_bf16 v[80:95], v[198:201], v[168:171], v[80:95]
	v_mfma_f32_32x32x16_bf16 v[16:31], v[198:201], v[172:175], v[16:31]
	s_waitcnt lgkmcnt(0)
	v_mfma_f32_32x32x16_bf16 v[64:79], v[234:237], v[168:171], v[64:79]
	v_mfma_f32_32x32x16_bf16 v[0:15], v[234:237], v[172:175], v[0:15]
	s_setprio 0
	v_add_co_u32_e32 v198, vcc, s44, v190
	v_add_u32_e32 v217, 0x18c00, v215
	s_nop 0
	v_addc_co_u32_e32 v199, vcc, 0, v191, vcc
	v_add_co_u32_e32 v200, vcc, s44, v188
	v_add_u32_e32 v216, 0x21c00, v215
	s_nop 0
	v_addc_co_u32_e32 v201, vcc, 0, v189, vcc
	global_load_dwordx4 v[168:171], v[198:199], off offset:256
	global_load_dwordx4 v[172:175], v[200:201], off offset:256
	s_waitcnt vmcnt(8)
	ds_write_b128 v217, v[164:167]
	ds_write_b128 v216, v[160:163]
	ds_read_b128 v[160:163], v205 offset:36960
	ds_read_b128 v[164:167], v205 offset:41568
	ds_read_b128 v[234:237], v204 offset:96
	ds_read_b128 v[238:241], v204 offset:4704
	s_setprio 1
	s_waitcnt lgkmcnt(1)
	v_mfma_f32_32x32x16_bf16 v[112:127], v[234:237], v[160:163], v[112:127]
	v_mfma_f32_32x32x16_bf16 v[48:63], v[234:237], v[164:167], v[48:63]
	s_waitcnt lgkmcnt(0)
	v_mfma_f32_32x32x16_bf16 v[96:111], v[238:241], v[160:163], v[96:111]
	v_mfma_f32_32x32x16_bf16 v[32:47], v[238:241], v[164:167], v[32:47]
	ds_read_b128 v[234:237], v204 offset:9312
	ds_read_b128 v[238:241], v204 offset:13920
	s_waitcnt lgkmcnt(1)
	v_mfma_f32_32x32x16_bf16 v[80:95], v[234:237], v[160:163], v[80:95]
	v_mfma_f32_32x32x16_bf16 v[16:31], v[234:237], v[164:167], v[16:31]
	s_waitcnt lgkmcnt(0)
	v_mfma_f32_32x32x16_bf16 v[64:79], v[238:241], v[160:163], v[64:79]
	v_mfma_f32_32x32x16_bf16 v[0:15], v[238:241], v[164:167], v[0:15]
	s_setprio 0
	global_load_dwordx4 v[160:163], v[190:191], off offset:384
	global_load_dwordx4 v[164:167], v[188:189], off offset:384
	s_barrier
; template <bool trans>
; DI void gemm_core(const GTile& tl, const GTile& nx, bool has_next  , bool chain  , bool pre, u32x4 (&ra)[4], u32x4 (&rb)[4], char* smem, f32x16 (&acc)[2][4]) {
;     ...
;   const int nk = K / 64;
;   if (!pre) { G_LOAD(0); G_STORE(0); G_LOAD(1); }
;   for (int kt = 0; kt < nk; ++kt) {
;     __syncthreads();
;     G_COMPUTE(kt & 1, kt);
;   }
	s_add_i32 s0, 16, 0x12000
	v_add3_u32 v192, s0, v208, v243
	s_add_i32 s0, 16, 0x1b000
	v_add3_u32 v208, s0, v242, v243
	s_waitcnt vmcnt(9)
	ds_write_b128 v215, v[218:221]
	s_waitcnt vmcnt(8)
	ds_write_b128 v215, v[222:225] offset:36864
	ds_read_b128 v[218:221], v208
	ds_read_b128 v[222:225], v208 offset:4608
	ds_read_b128 v[234:237], v192
	ds_read_b128 v[238:241], v192 offset:4608
	s_setprio 1
	s_waitcnt lgkmcnt(1)
	v_mfma_f32_32x32x16_bf16 v[112:127], v[234:237], v[218:221], v[112:127]
	v_mfma_f32_32x32x16_bf16 v[48:63], v[234:237], v[222:225], v[48:63]
	s_waitcnt lgkmcnt(0)
	v_mfma_f32_32x32x16_bf16 v[96:111], v[238:241], v[218:221], v[96:111]
	v_mfma_f32_32x32x16_bf16 v[32:47], v[238:241], v[222:225], v[32:47]
	ds_read_b128 v[234:237], v192 offset:9216
	ds_read_b128 v[238:241], v192 offset:13824
	s_waitcnt lgkmcnt(1)
	v_mfma_f32_32x32x16_bf16 v[80:95], v[234:237], v[218:221], v[80:95]
	v_mfma_f32_32x32x16_bf16 v[16:31], v[234:237], v[222:225], v[16:31]
	s_waitcnt lgkmcnt(0)
	v_mfma_f32_32x32x16_bf16 v[64:79], v[238:241], v[218:221], v[64:79]
	v_mfma_f32_32x32x16_bf16 v[0:15], v[238:241], v[222:225], v[0:15]
	s_setprio 0
	global_load_dwordx4 v[218:221], v[194:195], off offset:384
	global_load_dwordx4 v[222:225], v[196:197], off offset:384
	s_waitcnt vmcnt(9)
	ds_write_b128 v215, v[226:229] offset:9216
	s_waitcnt vmcnt(8)
	ds_write_b128 v215, v[230:233] offset:46080
	ds_read_b128 v[226:229], v208 offset:32
	ds_read_b128 v[230:233], v208 offset:4640
	ds_read_b128 v[234:237], v192 offset:32
	ds_read_b128 v[238:241], v192 offset:4640
	s_setprio 1
	s_waitcnt lgkmcnt(1)
	v_mfma_f32_32x32x16_bf16 v[112:127], v[234:237], v[226:229], v[112:127]
	v_mfma_f32_32x32x16_bf16 v[48:63], v[234:237], v[230:233], v[48:63]
	s_waitcnt lgkmcnt(0)
	v_mfma_f32_32x32x16_bf16 v[96:111], v[238:241], v[226:229], v[96:111]
	v_mfma_f32_32x32x16_bf16 v[32:47], v[238:241], v[230:233], v[32:47]
	ds_read_b128 v[234:237], v192 offset:9248
	ds_read_b128 v[238:241], v192 offset:13856
	s_waitcnt lgkmcnt(1)
	v_mfma_f32_32x32x16_bf16 v[80:95], v[234:237], v[226:229], v[80:95]
	v_mfma_f32_32x32x16_bf16 v[16:31], v[234:237], v[230:233], v[16:31]
	s_waitcnt lgkmcnt(0)
	v_mfma_f32_32x32x16_bf16 v[64:79], v[238:241], v[226:229], v[64:79]
	v_mfma_f32_32x32x16_bf16 v[0:15], v[238:241], v[230:233], v[0:15]
	s_setprio 0
	global_load_dwordx4 v[226:229], v[184:185], off offset:384
	global_load_dwordx4 v[230:233], v[186:187], off offset:384
	s_waitcnt vmcnt(9)
	ds_write_b128 v215, v[176:179] offset:18432
	s_waitcnt vmcnt(8)
	ds_write_b128 v215, v[180:183] offset:55296
	ds_read_b128 v[176:179], v208 offset:64
	ds_read_b128 v[180:183], v208 offset:4672
	ds_read_b128 v[234:237], v192 offset:64
	ds_read_b128 v[238:241], v192 offset:4672
	s_setprio 1
	s_waitcnt lgkmcnt(1)
	v_mfma_f32_32x32x16_bf16 v[112:127], v[234:237], v[176:179], v[112:127]
	v_mfma_f32_32x32x16_bf16 v[48:63], v[234:237], v[180:183], v[48:63]
	s_waitcnt lgkmcnt(0)
	v_mfma_f32_32x32x16_bf16 v[96:111], v[238:241], v[176:179], v[96:111]
	v_mfma_f32_32x32x16_bf16 v[32:47], v[238:241], v[180:183], v[32:47]
	ds_read_b128 v[234:237], v192 offset:9280
	ds_read_b128 v[238:241], v192 offset:13888
	s_waitcnt lgkmcnt(1)
	v_mfma_f32_32x32x16_bf16 v[80:95], v[234:237], v[176:179], v[80:95]
	v_mfma_f32_32x32x16_bf16 v[16:31], v[234:237], v[180:183], v[16:31]
	s_waitcnt lgkmcnt(0)
	v_mfma_f32_32x32x16_bf16 v[64:79], v[238:241], v[176:179], v[64:79]
	v_mfma_f32_32x32x16_bf16 v[0:15], v[238:241], v[180:183], v[0:15]
	s_setprio 0
	global_load_dwordx4 v[176:179], v[198:199], off offset:384
	global_load_dwordx4 v[180:183], v[200:201], off offset:384
	s_waitcnt vmcnt(9)
	ds_write_b128 v215, v[168:171] offset:27648
	s_waitcnt vmcnt(8)
	ds_write_b128 v215, v[172:175] offset:64512
	ds_read_b128 v[168:171], v208 offset:96
	ds_read_b128 v[172:175], v208 offset:4704
	ds_read_b128 v[234:237], v192 offset:96
	ds_read_b128 v[238:241], v192 offset:4704
	s_setprio 1
	s_waitcnt lgkmcnt(1)
	v_mfma_f32_32x32x16_bf16 v[112:127], v[234:237], v[168:171], v[112:127]
	v_mfma_f32_32x32x16_bf16 v[48:63], v[234:237], v[172:175], v[48:63]
	s_waitcnt lgkmcnt(0)
	v_mfma_f32_32x32x16_bf16 v[96:111], v[238:241], v[168:171], v[96:111]
	v_mfma_f32_32x32x16_bf16 v[32:47], v[238:241], v[172:175], v[32:47]
	ds_read_b128 v[234:237], v192 offset:9312
	ds_read_b128 v[238:241], v192 offset:13920
	s_waitcnt lgkmcnt(1)
	v_mfma_f32_32x32x16_bf16 v[80:95], v[234:237], v[168:171], v[80:95]
	v_mfma_f32_32x32x16_bf16 v[16:31], v[234:237], v[172:175], v[16:31]
	s_waitcnt lgkmcnt(0)
	v_mfma_f32_32x32x16_bf16 v[64:79], v[238:241], v[168:171], v[64:79]
	v_mfma_f32_32x32x16_bf16 v[0:15], v[238:241], v[172:175], v[0:15]
	s_setprio 0
	global_load_dwordx4 v[168:171], v[190:191], off offset:512
	global_load_dwordx4 v[172:175], v[188:189], off offset:512
	s_barrier
; template <bool trans>
; DI void gemm_core(const GTile& tl, const GTile& nx, bool has_next  , bool chain  , bool pre, u32x4 (&ra)[4], u32x4 (&rb)[4], char* smem, f32x16 (&acc)[2][4]) {
;     ...
;   const int nk = K / 64;
;   if (!pre) { G_LOAD(0); G_STORE(0); G_LOAD(1); }
;   for (int kt = 0; kt < nk; ++kt) {
;     __syncthreads();
;     G_COMPUTE(kt & 1, kt);
;   }
	s_waitcnt vmcnt(9)
	ds_write_b128 v209, v[160:163]
	s_waitcnt vmcnt(8)
	ds_write_b128 v210, v[164:167]
	ds_read_b128 v[160:163], v205 offset:36864
	ds_read_b128 v[164:167], v205 offset:41472
	ds_read_b128 v[234:237], v204
	ds_read_b128 v[238:241], v204 offset:4608
	s_setprio 1
	s_waitcnt lgkmcnt(1)
	v_mfma_f32_32x32x16_bf16 v[112:127], v[234:237], v[160:163], v[112:127]
	v_mfma_f32_32x32x16_bf16 v[48:63], v[234:237], v[164:167], v[48:63]
	s_waitcnt lgkmcnt(0)
	v_mfma_f32_32x32x16_bf16 v[96:111], v[238:241], v[160:163], v[96:111]
	v_mfma_f32_32x32x16_bf16 v[32:47], v[238:241], v[164:167], v[32:47]
	ds_read_b128 v[234:237], v204 offset:9216
	ds_read_b128 v[238:241], v204 offset:13824
	s_waitcnt vmcnt(7)
	ds_write_b128 v212, v[218:221]
	s_waitcnt vmcnt(6)
	ds_write_b128 v211, v[222:225]
	ds_read_b128 v[218:221], v205 offset:36896
	ds_read_b128 v[222:225], v205 offset:41504
	s_waitcnt lgkmcnt(5)
	v_mfma_f32_32x32x16_bf16 v[80:95], v[234:237], v[160:163], v[80:95]
	v_mfma_f32_32x32x16_bf16 v[16:31], v[234:237], v[164:167], v[16:31]
	ds_read_b128 v[234:237], v204 offset:32
	s_waitcnt lgkmcnt(5)
	v_mfma_f32_32x32x16_bf16 v[64:79], v[238:241], v[160:163], v[64:79]
	v_mfma_f32_32x32x16_bf16 v[0:15], v[238:241], v[164:167], v[0:15]
	ds_read_b128 v[238:241], v204 offset:4640
	s_setprio 0
	global_load_dwordx4 v[160:163], v[194:195], off offset:512
	global_load_dwordx4 v[164:167], v[196:197], off offset:512
	s_setprio 1
	s_waitcnt lgkmcnt(1)
	v_mfma_f32_32x32x16_bf16 v[112:127], v[234:237], v[218:221], v[112:127]
	v_mfma_f32_32x32x16_bf16 v[48:63], v[234:237], v[222:225], v[48:63]
	s_waitcnt lgkmcnt(0)
	v_mfma_f32_32x32x16_bf16 v[96:111], v[238:241], v[218:221], v[96:111]
	v_mfma_f32_32x32x16_bf16 v[32:47], v[238:241], v[222:225], v[32:47]
	ds_read_b128 v[234:237], v204 offset:9248
	ds_read_b128 v[238:241], v204 offset:13856
	s_waitcnt vmcnt(7)
	ds_write_b128 v214, v[226:229]
	s_waitcnt vmcnt(6)
	ds_write_b128 v213, v[230:233]
	ds_read_b128 v[226:229], v205 offset:36928
	ds_read_b128 v[230:233], v205 offset:41536
	s_waitcnt lgkmcnt(5)
	v_mfma_f32_32x32x16_bf16 v[80:95], v[234:237], v[218:221], v[80:95]
	v_mfma_f32_32x32x16_bf16 v[16:31], v[234:237], v[222:225], v[16:31]
	ds_read_b128 v[234:237], v204 offset:64
	s_waitcnt lgkmcnt(5)
	v_mfma_f32_32x32x16_bf16 v[64:79], v[238:241], v[218:221], v[64:79]
	v_mfma_f32_32x32x16_bf16 v[0:15], v[238:241], v[222:225], v[0:15]
	ds_read_b128 v[238:241], v204 offset:4672
	s_setprio 0
	global_load_dwordx4 v[218:221], v[184:185], off offset:512
	global_load_dwordx4 v[222:225], v[186:187], off offset:512
	s_setprio 1
	s_waitcnt lgkmcnt(1)
	v_mfma_f32_32x32x16_bf16 v[112:127], v[234:237], v[226:229], v[112:127]
	v_mfma_f32_32x32x16_bf16 v[48:63], v[234:237], v[230:233], v[48:63]
	s_waitcnt lgkmcnt(0)
	v_mfma_f32_32x32x16_bf16 v[96:111], v[238:241], v[226:229], v[96:111]
	v_mfma_f32_32x32x16_bf16 v[32:47], v[238:241], v[230:233], v[32:47]
	ds_read_b128 v[234:237], v204 offset:9280
	ds_read_b128 v[238:241], v204 offset:13888
	s_waitcnt vmcnt(7)
	ds_write_b128 v217, v[176:179]
	s_waitcnt vmcnt(6)
	ds_write_b128 v216, v[180:183]
	ds_read_b128 v[176:179], v205 offset:36960
	ds_read_b128 v[180:183], v205 offset:41568
	s_waitcnt lgkmcnt(5)
	v_mfma_f32_32x32x16_bf16 v[80:95], v[234:237], v[226:229], v[80:95]
	v_mfma_f32_32x32x16_bf16 v[16:31], v[234:237], v[230:233], v[16:31]
	ds_read_b128 v[234:237], v204 offset:96
	s_waitcnt lgkmcnt(5)
	v_mfma_f32_32x32x16_bf16 v[64:79], v[238:241], v[226:229], v[64:79]
	v_mfma_f32_32x32x16_bf16 v[0:15], v[238:241], v[230:233], v[0:15]
	ds_read_b128 v[238:241], v204 offset:4704
	s_setprio 0
	global_load_dwordx4 v[226:229], v[198:199], off offset:512
	global_load_dwordx4 v[230:233], v[200:201], off offset:512
	s_setprio 1
	s_waitcnt lgkmcnt(1)
	v_mfma_f32_32x32x16_bf16 v[112:127], v[234:237], v[176:179], v[112:127]
	v_mfma_f32_32x32x16_bf16 v[48:63], v[234:237], v[180:183], v[48:63]
	s_waitcnt lgkmcnt(0)
	v_mfma_f32_32x32x16_bf16 v[96:111], v[238:241], v[176:179], v[96:111]
	v_mfma_f32_32x32x16_bf16 v[32:47], v[238:241], v[180:183], v[32:47]
	ds_read_b128 v[234:237], v204 offset:9312
	ds_read_b128 v[238:241], v204 offset:13920
	s_waitcnt lgkmcnt(1)
	v_mfma_f32_32x32x16_bf16 v[80:95], v[234:237], v[176:179], v[80:95]
	v_mfma_f32_32x32x16_bf16 v[16:31], v[234:237], v[180:183], v[16:31]
	s_waitcnt lgkmcnt(0)
	v_mfma_f32_32x32x16_bf16 v[64:79], v[238:241], v[176:179], v[64:79]
	v_mfma_f32_32x32x16_bf16 v[0:15], v[238:241], v[180:183], v[0:15]
	s_setprio 0
	global_load_dwordx4 v[176:179], v[190:191], off offset:640
	global_load_dwordx4 v[180:183], v[188:189], off offset:640
	s_barrier
; template <bool trans>
; DI void gemm_core(const GTile& tl, const GTile& nx, bool has_next  , bool chain  , bool pre, u32x4 (&ra)[4], u32x4 (&rb)[4], char* smem, f32x16 (&acc)[2][4]) {
;     ...
;   const int nk = K / 64;
;   if (!pre) { G_LOAD(0); G_STORE(0); G_LOAD(1); }
;   for (int kt = 0; kt < nk; ++kt) {
;     __syncthreads();
;     G_COMPUTE(kt & 1, kt);
;   }
	s_waitcnt vmcnt(9)
	ds_write_b128 v215, v[168:171]
	s_waitcnt vmcnt(8)
	ds_write_b128 v215, v[172:175] offset:36864
	ds_read_b128 v[168:171], v208
	ds_read_b128 v[172:175], v208 offset:4608
	ds_read_b128 v[234:237], v192
	ds_read_b128 v[238:241], v192 offset:4608
	s_setprio 1
	s_waitcnt lgkmcnt(1)
	v_mfma_f32_32x32x16_bf16 v[112:127], v[234:237], v[168:171], v[112:127]
	v_mfma_f32_32x32x16_bf16 v[48:63], v[234:237], v[172:175], v[48:63]
	s_waitcnt lgkmcnt(0)
	v_mfma_f32_32x32x16_bf16 v[96:111], v[238:241], v[168:171], v[96:111]
	v_mfma_f32_32x32x16_bf16 v[32:47], v[238:241], v[172:175], v[32:47]
	ds_read_b128 v[234:237], v192 offset:9216
	ds_read_b128 v[238:241], v192 offset:13824
	s_waitcnt vmcnt(7)
	ds_write_b128 v215, v[160:163] offset:9216
	s_waitcnt vmcnt(6)
	ds_write_b128 v215, v[164:167] offset:46080
	ds_read_b128 v[160:163], v208 offset:32
	ds_read_b128 v[164:167], v208 offset:4640
	s_waitcnt lgkmcnt(5)
	v_mfma_f32_32x32x16_bf16 v[80:95], v[234:237], v[168:171], v[80:95]
	v_mfma_f32_32x32x16_bf16 v[16:31], v[234:237], v[172:175], v[16:31]
	ds_read_b128 v[234:237], v192 offset:32
	s_waitcnt lgkmcnt(5)
	v_mfma_f32_32x32x16_bf16 v[64:79], v[238:241], v[168:171], v[64:79]
	v_mfma_f32_32x32x16_bf16 v[0:15], v[238:241], v[172:175], v[0:15]
	ds_read_b128 v[238:241], v192 offset:4640
	s_setprio 0
	global_load_dwordx4 v[168:171], v[194:195], off offset:640
	global_load_dwordx4 v[172:175], v[196:197], off offset:640
	s_setprio 1
	s_waitcnt lgkmcnt(1)
	v_mfma_f32_32x32x16_bf16 v[112:127], v[234:237], v[160:163], v[112:127]
	v_mfma_f32_32x32x16_bf16 v[48:63], v[234:237], v[164:167], v[48:63]
	s_waitcnt lgkmcnt(0)
	v_mfma_f32_32x32x16_bf16 v[96:111], v[238:241], v[160:163], v[96:111]
	v_mfma_f32_32x32x16_bf16 v[32:47], v[238:241], v[164:167], v[32:47]
	ds_read_b128 v[234:237], v192 offset:9248
	ds_read_b128 v[238:241], v192 offset:13856
	s_waitcnt vmcnt(7)
	ds_write_b128 v215, v[218:221] offset:18432
	s_waitcnt vmcnt(6)
	ds_write_b128 v215, v[222:225] offset:55296
	ds_read_b128 v[218:221], v208 offset:64
	ds_read_b128 v[222:225], v208 offset:4672
	s_waitcnt lgkmcnt(5)
	v_mfma_f32_32x32x16_bf16 v[80:95], v[234:237], v[160:163], v[80:95]
	v_mfma_f32_32x32x16_bf16 v[16:31], v[234:237], v[164:167], v[16:31]
	ds_read_b128 v[234:237], v192 offset:64
	s_waitcnt lgkmcnt(5)
	v_mfma_f32_32x32x16_bf16 v[64:79], v[238:241], v[160:163], v[64:79]
	v_mfma_f32_32x32x16_bf16 v[0:15], v[238:241], v[164:167], v[0:15]
	ds_read_b128 v[238:241], v192 offset:4672
	s_setprio 0
	global_load_dwordx4 v[160:163], v[184:185], off offset:640
	global_load_dwordx4 v[164:167], v[186:187], off offset:640
	s_setprio 1
	s_waitcnt lgkmcnt(1)
	v_mfma_f32_32x32x16_bf16 v[112:127], v[234:237], v[218:221], v[112:127]
	v_mfma_f32_32x32x16_bf16 v[48:63], v[234:237], v[222:225], v[48:63]
	s_waitcnt lgkmcnt(0)
	v_mfma_f32_32x32x16_bf16 v[96:111], v[238:241], v[218:221], v[96:111]
	v_mfma_f32_32x32x16_bf16 v[32:47], v[238:241], v[222:225], v[32:47]
	ds_read_b128 v[234:237], v192 offset:9280
	ds_read_b128 v[238:241], v192 offset:13888
	s_waitcnt vmcnt(7)
	ds_write_b128 v215, v[226:229] offset:27648
	s_waitcnt vmcnt(6)
	ds_write_b128 v215, v[230:233] offset:64512
	ds_read_b128 v[226:229], v208 offset:96
	ds_read_b128 v[230:233], v208 offset:4704
	s_waitcnt lgkmcnt(5)
	v_mfma_f32_32x32x16_bf16 v[80:95], v[234:237], v[218:221], v[80:95]
	v_mfma_f32_32x32x16_bf16 v[16:31], v[234:237], v[222:225], v[16:31]
	ds_read_b128 v[234:237], v192 offset:96
	s_waitcnt lgkmcnt(5)
	v_mfma_f32_32x32x16_bf16 v[64:79], v[238:241], v[218:221], v[64:79]
	v_mfma_f32_32x32x16_bf16 v[0:15], v[238:241], v[222:225], v[0:15]
	ds_read_b128 v[238:241], v192 offset:4704
	s_setprio 0
	global_load_dwordx4 v[218:221], v[198:199], off offset:640
	global_load_dwordx4 v[222:225], v[200:201], off offset:640
	s_setprio 1
	s_waitcnt lgkmcnt(1)
	v_mfma_f32_32x32x16_bf16 v[112:127], v[234:237], v[226:229], v[112:127]
	v_mfma_f32_32x32x16_bf16 v[48:63], v[234:237], v[230:233], v[48:63]
	s_waitcnt lgkmcnt(0)
	v_mfma_f32_32x32x16_bf16 v[96:111], v[238:241], v[226:229], v[96:111]
	v_mfma_f32_32x32x16_bf16 v[32:47], v[238:241], v[230:233], v[32:47]
	ds_read_b128 v[234:237], v192 offset:9312
	ds_read_b128 v[238:241], v192 offset:13920
	s_waitcnt lgkmcnt(1)
	v_mfma_f32_32x32x16_bf16 v[80:95], v[234:237], v[226:229], v[80:95]
	v_mfma_f32_32x32x16_bf16 v[16:31], v[234:237], v[230:233], v[16:31]
	s_waitcnt lgkmcnt(0)
	v_mfma_f32_32x32x16_bf16 v[64:79], v[238:241], v[226:229], v[64:79]
	v_mfma_f32_32x32x16_bf16 v[0:15], v[238:241], v[230:233], v[0:15]
	s_setprio 0
	global_load_dwordx4 v[226:229], v[190:191], off offset:768
	global_load_dwordx4 v[230:233], v[188:189], off offset:768
	s_barrier
; template <bool trans>
; DI void gemm_core(const GTile& tl, const GTile& nx, bool has_next  , bool chain  , bool pre, u32x4 (&ra)[4], u32x4 (&rb)[4], char* smem, f32x16 (&acc)[2][4]) {
;     ...
;   const int nk = K / 64;
;   if (!pre) { G_LOAD(0); G_STORE(0); G_LOAD(1); }
;   for (int kt = 0; kt < nk; ++kt) {
;     __syncthreads();
;     G_COMPUTE(kt & 1, kt);
;   }
	s_waitcnt vmcnt(9)
	ds_write_b128 v209, v[176:179]
	s_waitcnt vmcnt(8)
	ds_write_b128 v210, v[180:183]
	ds_read_b128 v[176:179], v205 offset:36864
	ds_read_b128 v[180:183], v205 offset:41472
	ds_read_b128 v[234:237], v204
	ds_read_b128 v[238:241], v204 offset:4608
	s_setprio 1
	s_waitcnt lgkmcnt(1)
	v_mfma_f32_32x32x16_bf16 v[112:127], v[234:237], v[176:179], v[112:127]
	v_mfma_f32_32x32x16_bf16 v[48:63], v[234:237], v[180:183], v[48:63]
	s_waitcnt lgkmcnt(0)
	v_mfma_f32_32x32x16_bf16 v[96:111], v[238:241], v[176:179], v[96:111]
	v_mfma_f32_32x32x16_bf16 v[32:47], v[238:241], v[180:183], v[32:47]
	ds_read_b128 v[234:237], v204 offset:9216
	ds_read_b128 v[238:241], v204 offset:13824
	s_waitcnt vmcnt(7)
	ds_write_b128 v212, v[168:171]
	s_waitcnt vmcnt(6)
	ds_write_b128 v211, v[172:175]
	ds_read_b128 v[168:171], v205 offset:36896
	ds_read_b128 v[172:175], v205 offset:41504
	s_waitcnt lgkmcnt(5)
	v_mfma_f32_32x32x16_bf16 v[80:95], v[234:237], v[176:179], v[80:95]
	v_mfma_f32_32x32x16_bf16 v[16:31], v[234:237], v[180:183], v[16:31]
	ds_read_b128 v[234:237], v204 offset:32
	s_waitcnt lgkmcnt(5)
	v_mfma_f32_32x32x16_bf16 v[64:79], v[238:241], v[176:179], v[64:79]
	v_mfma_f32_32x32x16_bf16 v[0:15], v[238:241], v[180:183], v[0:15]
	ds_read_b128 v[238:241], v204 offset:4640
	s_setprio 0
	global_load_dwordx4 v[176:179], v[194:195], off offset:768
	global_load_dwordx4 v[180:183], v[196:197], off offset:768
	s_setprio 1
	s_waitcnt lgkmcnt(1)
	v_mfma_f32_32x32x16_bf16 v[112:127], v[234:237], v[168:171], v[112:127]
	v_mfma_f32_32x32x16_bf16 v[48:63], v[234:237], v[172:175], v[48:63]
	s_waitcnt lgkmcnt(0)
	v_mfma_f32_32x32x16_bf16 v[96:111], v[238:241], v[168:171], v[96:111]
	v_mfma_f32_32x32x16_bf16 v[32:47], v[238:241], v[172:175], v[32:47]
	ds_read_b128 v[234:237], v204 offset:9248
	ds_read_b128 v[238:241], v204 offset:13856
	s_waitcnt vmcnt(7)
	ds_write_b128 v214, v[160:163]
	s_waitcnt vmcnt(6)
	ds_write_b128 v213, v[164:167]
	ds_read_b128 v[160:163], v205 offset:36928
	ds_read_b128 v[164:167], v205 offset:41536
	s_waitcnt lgkmcnt(5)
	v_mfma_f32_32x32x16_bf16 v[80:95], v[234:237], v[168:171], v[80:95]
	v_mfma_f32_32x32x16_bf16 v[16:31], v[234:237], v[172:175], v[16:31]
	ds_read_b128 v[234:237], v204 offset:64
	s_waitcnt lgkmcnt(5)
	v_mfma_f32_32x32x16_bf16 v[64:79], v[238:241], v[168:171], v[64:79]
	v_mfma_f32_32x32x16_bf16 v[0:15], v[238:241], v[172:175], v[0:15]
	ds_read_b128 v[238:241], v204 offset:4672
	s_setprio 0
	global_load_dwordx4 v[168:171], v[184:185], off offset:768
	global_load_dwordx4 v[172:175], v[186:187], off offset:768
	s_setprio 1
	s_waitcnt lgkmcnt(1)
	v_mfma_f32_32x32x16_bf16 v[112:127], v[234:237], v[160:163], v[112:127]
	v_mfma_f32_32x32x16_bf16 v[48:63], v[234:237], v[164:167], v[48:63]
	s_waitcnt lgkmcnt(0)
	v_mfma_f32_32x32x16_bf16 v[96:111], v[238:241], v[160:163], v[96:111]
	v_mfma_f32_32x32x16_bf16 v[32:47], v[238:241], v[164:167], v[32:47]
	ds_read_b128 v[234:237], v204 offset:9280
	ds_read_b128 v[238:241], v204 offset:13888
	s_waitcnt vmcnt(7)
	ds_write_b128 v217, v[218:221]
	s_waitcnt vmcnt(6)
	ds_write_b128 v216, v[222:225]
	ds_read_b128 v[218:221], v205 offset:36960
	ds_read_b128 v[222:225], v205 offset:41568
	s_waitcnt lgkmcnt(5)
	v_mfma_f32_32x32x16_bf16 v[80:95], v[234:237], v[160:163], v[80:95]
	v_mfma_f32_32x32x16_bf16 v[16:31], v[234:237], v[164:167], v[16:31]
	ds_read_b128 v[234:237], v204 offset:96
	s_waitcnt lgkmcnt(5)
	v_mfma_f32_32x32x16_bf16 v[64:79], v[238:241], v[160:163], v[64:79]
	v_mfma_f32_32x32x16_bf16 v[0:15], v[238:241], v[164:167], v[0:15]
	ds_read_b128 v[238:241], v204 offset:4704
	s_setprio 0
	global_load_dwordx4 v[160:163], v[198:199], off offset:768
	global_load_dwordx4 v[164:167], v[200:201], off offset:768
	s_setprio 1
	s_waitcnt lgkmcnt(1)
	v_mfma_f32_32x32x16_bf16 v[112:127], v[234:237], v[218:221], v[112:127]
	v_mfma_f32_32x32x16_bf16 v[48:63], v[234:237], v[222:225], v[48:63]
	s_waitcnt lgkmcnt(0)
	v_mfma_f32_32x32x16_bf16 v[96:111], v[238:241], v[218:221], v[96:111]
	v_mfma_f32_32x32x16_bf16 v[32:47], v[238:241], v[222:225], v[32:47]
	ds_read_b128 v[234:237], v204 offset:9312
	ds_read_b128 v[238:241], v204 offset:13920
	s_waitcnt lgkmcnt(1)
	v_mfma_f32_32x32x16_bf16 v[80:95], v[234:237], v[218:221], v[80:95]
	v_mfma_f32_32x32x16_bf16 v[16:31], v[234:237], v[222:225], v[16:31]
	s_waitcnt lgkmcnt(0)
	v_mfma_f32_32x32x16_bf16 v[64:79], v[238:241], v[218:221], v[64:79]
	v_mfma_f32_32x32x16_bf16 v[0:15], v[238:241], v[222:225], v[0:15]
	s_setprio 0
	global_load_dwordx4 v[218:221], v[190:191], off offset:896
	global_load_dwordx4 v[222:225], v[188:189], off offset:896
	s_barrier
; template <bool trans>
; DI void gemm_core(const GTile& tl, const GTile& nx, bool has_next  , bool chain  , bool pre, u32x4 (&ra)[4], u32x4 (&rb)[4], char* smem, f32x16 (&acc)[2][4]) {
;     ...
;   const int nk = K / 64;
;   if (!pre) { G_LOAD(0); G_STORE(0); G_LOAD(1); }
;   for (int kt = 0; kt < nk; ++kt) {
;     __syncthreads();
;     G_COMPUTE(kt & 1, kt);
;   }
	s_waitcnt vmcnt(9)
	ds_write_b128 v215, v[226:229]
	s_waitcnt vmcnt(8)
	ds_write_b128 v215, v[230:233] offset:36864
	ds_read_b128 v[226:229], v208
	ds_read_b128 v[230:233], v208 offset:4608
	ds_read_b128 v[234:237], v192
	ds_read_b128 v[238:241], v192 offset:4608
	s_setprio 1
	s_waitcnt lgkmcnt(1)
	v_mfma_f32_32x32x16_bf16 v[112:127], v[234:237], v[226:229], v[112:127]
	v_mfma_f32_32x32x16_bf16 v[48:63], v[234:237], v[230:233], v[48:63]
	s_waitcnt lgkmcnt(0)
	v_mfma_f32_32x32x16_bf16 v[96:111], v[238:241], v[226:229], v[96:111]
	v_mfma_f32_32x32x16_bf16 v[32:47], v[238:241], v[230:233], v[32:47]
	ds_read_b128 v[234:237], v192 offset:9216
	ds_read_b128 v[238:241], v192 offset:13824
	s_waitcnt vmcnt(7)
	ds_write_b128 v215, v[176:179] offset:9216
	s_waitcnt vmcnt(6)
	ds_write_b128 v215, v[180:183] offset:46080
	ds_read_b128 v[176:179], v208 offset:32
	ds_read_b128 v[180:183], v208 offset:4640
	s_waitcnt lgkmcnt(5)
	v_mfma_f32_32x32x16_bf16 v[80:95], v[234:237], v[226:229], v[80:95]
	v_mfma_f32_32x32x16_bf16 v[16:31], v[234:237], v[230:233], v[16:31]
	ds_read_b128 v[234:237], v192 offset:32
	s_waitcnt lgkmcnt(5)
	v_mfma_f32_32x32x16_bf16 v[64:79], v[238:241], v[226:229], v[64:79]
	v_mfma_f32_32x32x16_bf16 v[0:15], v[238:241], v[230:233], v[0:15]
	ds_read_b128 v[238:241], v192 offset:4640
	s_setprio 0
	global_load_dwordx4 v[226:229], v[194:195], off offset:896
	global_load_dwordx4 v[230:233], v[196:197], off offset:896
	s_setprio 1
	s_waitcnt lgkmcnt(1)
	v_mfma_f32_32x32x16_bf16 v[112:127], v[234:237], v[176:179], v[112:127]
	v_mfma_f32_32x32x16_bf16 v[48:63], v[234:237], v[180:183], v[48:63]
	s_waitcnt lgkmcnt(0)
	v_mfma_f32_32x32x16_bf16 v[96:111], v[238:241], v[176:179], v[96:111]
	v_mfma_f32_32x32x16_bf16 v[32:47], v[238:241], v[180:183], v[32:47]
	ds_read_b128 v[234:237], v192 offset:9248
	ds_read_b128 v[238:241], v192 offset:13856
	s_waitcnt vmcnt(7)
	ds_write_b128 v215, v[168:171] offset:18432
	s_waitcnt vmcnt(6)
	ds_write_b128 v215, v[172:175] offset:55296
	ds_read_b128 v[168:171], v208 offset:64
	ds_read_b128 v[172:175], v208 offset:4672
	s_waitcnt lgkmcnt(5)
	v_mfma_f32_32x32x16_bf16 v[80:95], v[234:237], v[176:179], v[80:95]
	v_mfma_f32_32x32x16_bf16 v[16:31], v[234:237], v[180:183], v[16:31]
	ds_read_b128 v[234:237], v192 offset:64
	s_waitcnt lgkmcnt(5)
	v_mfma_f32_32x32x16_bf16 v[64:79], v[238:241], v[176:179], v[64:79]
	v_mfma_f32_32x32x16_bf16 v[0:15], v[238:241], v[180:183], v[0:15]
	ds_read_b128 v[238:241], v192 offset:4672
	s_setprio 0
	global_load_dwordx4 v[176:179], v[184:185], off offset:896
	global_load_dwordx4 v[180:183], v[186:187], off offset:896
	s_setprio 1
	s_waitcnt lgkmcnt(1)
	v_mfma_f32_32x32x16_bf16 v[112:127], v[234:237], v[168:171], v[112:127]
	v_mfma_f32_32x32x16_bf16 v[48:63], v[234:237], v[172:175], v[48:63]
	s_waitcnt lgkmcnt(0)
	v_mfma_f32_32x32x16_bf16 v[96:111], v[238:241], v[168:171], v[96:111]
	v_mfma_f32_32x32x16_bf16 v[32:47], v[238:241], v[172:175], v[32:47]
	ds_read_b128 v[234:237], v192 offset:9280
	ds_read_b128 v[238:241], v192 offset:13888
	s_waitcnt vmcnt(7)
	ds_write_b128 v215, v[160:163] offset:27648
	s_waitcnt vmcnt(6)
	ds_write_b128 v215, v[164:167] offset:64512
	ds_read_b128 v[160:163], v208 offset:96
	ds_read_b128 v[164:167], v208 offset:4704
	s_waitcnt lgkmcnt(5)
	v_mfma_f32_32x32x16_bf16 v[80:95], v[234:237], v[168:171], v[80:95]
	v_mfma_f32_32x32x16_bf16 v[16:31], v[234:237], v[172:175], v[16:31]
	ds_read_b128 v[234:237], v192 offset:96
	s_waitcnt lgkmcnt(5)
	v_mfma_f32_32x32x16_bf16 v[64:79], v[238:241], v[168:171], v[64:79]
	v_mfma_f32_32x32x16_bf16 v[0:15], v[238:241], v[172:175], v[0:15]
	ds_read_b128 v[238:241], v192 offset:4704
	s_setprio 0
	global_load_dwordx4 v[168:171], v[198:199], off offset:896
	global_load_dwordx4 v[172:175], v[200:201], off offset:896
	s_setprio 1
	s_waitcnt lgkmcnt(1)
	v_mfma_f32_32x32x16_bf16 v[112:127], v[234:237], v[160:163], v[112:127]
	v_mfma_f32_32x32x16_bf16 v[48:63], v[234:237], v[164:167], v[48:63]
	s_waitcnt lgkmcnt(0)
	v_mfma_f32_32x32x16_bf16 v[96:111], v[238:241], v[160:163], v[96:111]
	v_mfma_f32_32x32x16_bf16 v[32:47], v[238:241], v[164:167], v[32:47]
	ds_read_b128 v[234:237], v192 offset:9312
	ds_read_b128 v[238:241], v192 offset:13920
	s_waitcnt lgkmcnt(1)
	v_mfma_f32_32x32x16_bf16 v[80:95], v[234:237], v[160:163], v[80:95]
	v_mfma_f32_32x32x16_bf16 v[16:31], v[234:237], v[164:167], v[16:31]
	s_waitcnt lgkmcnt(0)
	v_mfma_f32_32x32x16_bf16 v[64:79], v[238:241], v[160:163], v[64:79]
	v_mfma_f32_32x32x16_bf16 v[0:15], v[238:241], v[164:167], v[0:15]
	s_setprio 0
	global_load_dwordx4 v[160:163], v[190:191], off offset:1024
	global_load_dwordx4 v[164:167], v[188:189], off offset:1024
	s_barrier
; template <bool trans>
; DI void gemm_core(const GTile& tl, const GTile& nx, bool has_next  , bool chain  , bool pre, u32x4 (&ra)[4], u32x4 (&rb)[4], char* smem, f32x16 (&acc)[2][4]) {
;     ...
;   const int nk = K / 64;
;   if (!pre) { G_LOAD(0); G_STORE(0); G_LOAD(1); }
;   for (int kt = 0; kt < nk; ++kt) {
;     __syncthreads();
;     G_COMPUTE(kt & 1, kt);
;   }
	s_waitcnt vmcnt(9)
	ds_write_b128 v209, v[218:221]
	s_waitcnt vmcnt(8)
	ds_write_b128 v210, v[222:225]
	ds_read_b128 v[218:221], v205 offset:36864
	ds_read_b128 v[222:225], v205 offset:41472
	ds_read_b128 v[234:237], v204
	ds_read_b128 v[238:241], v204 offset:4608
	s_setprio 1
	s_waitcnt lgkmcnt(1)
	v_mfma_f32_32x32x16_bf16 v[112:127], v[234:237], v[218:221], v[112:127]
	v_mfma_f32_32x32x16_bf16 v[48:63], v[234:237], v[222:225], v[48:63]
	s_waitcnt lgkmcnt(0)
	v_mfma_f32_32x32x16_bf16 v[96:111], v[238:241], v[218:221], v[96:111]
	v_mfma_f32_32x32x16_bf16 v[32:47], v[238:241], v[222:225], v[32:47]
	ds_read_b128 v[234:237], v204 offset:9216
	ds_read_b128 v[238:241], v204 offset:13824
	s_waitcnt vmcnt(7)
	ds_write_b128 v212, v[226:229]
	s_waitcnt vmcnt(6)
	ds_write_b128 v211, v[230:233]
	ds_read_b128 v[226:229], v205 offset:36896
	ds_read_b128 v[230:233], v205 offset:41504
	s_waitcnt lgkmcnt(5)
	v_mfma_f32_32x32x16_bf16 v[80:95], v[234:237], v[218:221], v[80:95]
	v_mfma_f32_32x32x16_bf16 v[16:31], v[234:237], v[222:225], v[16:31]
	ds_read_b128 v[234:237], v204 offset:32
	s_waitcnt lgkmcnt(5)
	v_mfma_f32_32x32x16_bf16 v[64:79], v[238:241], v[218:221], v[64:79]
	v_mfma_f32_32x32x16_bf16 v[0:15], v[238:241], v[222:225], v[0:15]
	ds_read_b128 v[238:241], v204 offset:4640
	s_setprio 0
	global_load_dwordx4 v[218:221], v[194:195], off offset:1024
	global_load_dwordx4 v[222:225], v[196:197], off offset:1024
	s_setprio 1
	s_waitcnt lgkmcnt(1)
	v_mfma_f32_32x32x16_bf16 v[112:127], v[234:237], v[226:229], v[112:127]
	v_mfma_f32_32x32x16_bf16 v[48:63], v[234:237], v[230:233], v[48:63]
	s_waitcnt lgkmcnt(0)
	v_mfma_f32_32x32x16_bf16 v[96:111], v[238:241], v[226:229], v[96:111]
	v_mfma_f32_32x32x16_bf16 v[32:47], v[238:241], v[230:233], v[32:47]
	ds_read_b128 v[234:237], v204 offset:9248
	ds_read_b128 v[238:241], v204 offset:13856
	s_waitcnt vmcnt(7)
	ds_write_b128 v214, v[176:179]
	s_waitcnt vmcnt(6)
	ds_write_b128 v213, v[180:183]
	ds_read_b128 v[176:179], v205 offset:36928
	ds_read_b128 v[180:183], v205 offset:41536
	s_waitcnt lgkmcnt(5)
	v_mfma_f32_32x32x16_bf16 v[80:95], v[234:237], v[226:229], v[80:95]
	v_mfma_f32_32x32x16_bf16 v[16:31], v[234:237], v[230:233], v[16:31]
	ds_read_b128 v[234:237], v204 offset:64
	s_waitcnt lgkmcnt(5)
	v_mfma_f32_32x32x16_bf16 v[64:79], v[238:241], v[226:229], v[64:79]
	v_mfma_f32_32x32x16_bf16 v[0:15], v[238:241], v[230:233], v[0:15]
	ds_read_b128 v[238:241], v204 offset:4672
	s_setprio 0
	global_load_dwordx4 v[226:229], v[184:185], off offset:1024
	global_load_dwordx4 v[230:233], v[186:187], off offset:1024
	s_setprio 1
	s_waitcnt lgkmcnt(1)
	v_mfma_f32_32x32x16_bf16 v[112:127], v[234:237], v[176:179], v[112:127]
	v_mfma_f32_32x32x16_bf16 v[48:63], v[234:237], v[180:183], v[48:63]
	s_waitcnt lgkmcnt(0)
	v_mfma_f32_32x32x16_bf16 v[96:111], v[238:241], v[176:179], v[96:111]
	v_mfma_f32_32x32x16_bf16 v[32:47], v[238:241], v[180:183], v[32:47]
	ds_read_b128 v[234:237], v204 offset:9280
	ds_read_b128 v[238:241], v204 offset:13888
	s_waitcnt vmcnt(7)
	ds_write_b128 v217, v[168:171]
	s_waitcnt vmcnt(6)
	ds_write_b128 v216, v[172:175]
	ds_read_b128 v[168:171], v205 offset:36960
	ds_read_b128 v[172:175], v205 offset:41568
	s_waitcnt lgkmcnt(5)
	v_mfma_f32_32x32x16_bf16 v[80:95], v[234:237], v[176:179], v[80:95]
	v_mfma_f32_32x32x16_bf16 v[16:31], v[234:237], v[180:183], v[16:31]
	ds_read_b128 v[234:237], v204 offset:96
	s_waitcnt lgkmcnt(5)
	v_mfma_f32_32x32x16_bf16 v[64:79], v[238:241], v[176:179], v[64:79]
	v_mfma_f32_32x32x16_bf16 v[0:15], v[238:241], v[180:183], v[0:15]
	ds_read_b128 v[238:241], v204 offset:4704
	s_setprio 0
	global_load_dwordx4 v[176:179], v[198:199], off offset:1024
	global_load_dwordx4 v[180:183], v[200:201], off offset:1024
	s_setprio 1
	s_waitcnt lgkmcnt(1)
	v_mfma_f32_32x32x16_bf16 v[112:127], v[234:237], v[168:171], v[112:127]
	v_mfma_f32_32x32x16_bf16 v[48:63], v[234:237], v[172:175], v[48:63]
	s_waitcnt lgkmcnt(0)
	v_mfma_f32_32x32x16_bf16 v[96:111], v[238:241], v[168:171], v[96:111]
	v_mfma_f32_32x32x16_bf16 v[32:47], v[238:241], v[172:175], v[32:47]
	ds_read_b128 v[234:237], v204 offset:9312
	ds_read_b128 v[238:241], v204 offset:13920
	s_waitcnt lgkmcnt(1)
	v_mfma_f32_32x32x16_bf16 v[80:95], v[234:237], v[168:171], v[80:95]
	v_mfma_f32_32x32x16_bf16 v[16:31], v[234:237], v[172:175], v[16:31]
	s_waitcnt lgkmcnt(0)
	v_mfma_f32_32x32x16_bf16 v[64:79], v[238:241], v[168:171], v[64:79]
	v_mfma_f32_32x32x16_bf16 v[0:15], v[238:241], v[172:175], v[0:15]
	s_setprio 0
	global_load_dwordx4 v[168:171], v[190:191], off offset:1152
	global_load_dwordx4 v[172:175], v[188:189], off offset:1152
	s_barrier
; template <bool trans>
; DI void gemm_core(const GTile& tl, const GTile& nx, bool has_next  , bool chain  , bool pre, u32x4 (&ra)[4], u32x4 (&rb)[4], char* smem, f32x16 (&acc)[2][4]) {
;     ...
;   const int nk = K / 64;
;   if (!pre) { G_LOAD(0); G_STORE(0); G_LOAD(1); }
;   for (int kt = 0; kt < nk; ++kt) {
;     __syncthreads();
;     G_COMPUTE(kt & 1, kt);
;   }
	s_waitcnt vmcnt(9)
	ds_write_b128 v215, v[160:163]
	s_waitcnt vmcnt(8)
	ds_write_b128 v215, v[164:167] offset:36864
	ds_read_b128 v[160:163], v208
	ds_read_b128 v[164:167], v208 offset:4608
	ds_read_b128 v[234:237], v192
	ds_read_b128 v[238:241], v192 offset:4608
	s_setprio 1
	s_waitcnt lgkmcnt(1)
	v_mfma_f32_32x32x16_bf16 v[112:127], v[234:237], v[160:163], v[112:127]
	v_mfma_f32_32x32x16_bf16 v[48:63], v[234:237], v[164:167], v[48:63]
	s_waitcnt lgkmcnt(0)
	v_mfma_f32_32x32x16_bf16 v[96:111], v[238:241], v[160:163], v[96:111]
	v_mfma_f32_32x32x16_bf16 v[32:47], v[238:241], v[164:167], v[32:47]
	ds_read_b128 v[234:237], v192 offset:9216
	ds_read_b128 v[238:241], v192 offset:13824
	s_waitcnt vmcnt(7)
	ds_write_b128 v215, v[218:221] offset:9216
	s_waitcnt vmcnt(6)
	ds_write_b128 v215, v[222:225] offset:46080
	ds_read_b128 v[218:221], v208 offset:32
	ds_read_b128 v[222:225], v208 offset:4640
	s_waitcnt lgkmcnt(5)
	v_mfma_f32_32x32x16_bf16 v[80:95], v[234:237], v[160:163], v[80:95]
	v_mfma_f32_32x32x16_bf16 v[16:31], v[234:237], v[164:167], v[16:31]
	ds_read_b128 v[234:237], v192 offset:32
	s_waitcnt lgkmcnt(5)
	v_mfma_f32_32x32x16_bf16 v[64:79], v[238:241], v[160:163], v[64:79]
	v_mfma_f32_32x32x16_bf16 v[0:15], v[238:241], v[164:167], v[0:15]
	ds_read_b128 v[238:241], v192 offset:4640
	s_setprio 0
	global_load_dwordx4 v[160:163], v[194:195], off offset:1152
	global_load_dwordx4 v[164:167], v[196:197], off offset:1152
	s_setprio 1
	s_waitcnt lgkmcnt(1)
	v_mfma_f32_32x32x16_bf16 v[112:127], v[234:237], v[218:221], v[112:127]
	v_mfma_f32_32x32x16_bf16 v[48:63], v[234:237], v[222:225], v[48:63]
	s_waitcnt lgkmcnt(0)
	v_mfma_f32_32x32x16_bf16 v[96:111], v[238:241], v[218:221], v[96:111]
	v_mfma_f32_32x32x16_bf16 v[32:47], v[238:241], v[222:225], v[32:47]
	ds_read_b128 v[234:237], v192 offset:9248
	ds_read_b128 v[238:241], v192 offset:13856
	s_waitcnt vmcnt(7)
	ds_write_b128 v215, v[226:229] offset:18432
	s_waitcnt vmcnt(6)
	ds_write_b128 v215, v[230:233] offset:55296
	ds_read_b128 v[226:229], v208 offset:64
	ds_read_b128 v[230:233], v208 offset:4672
	s_waitcnt lgkmcnt(5)
	v_mfma_f32_32x32x16_bf16 v[80:95], v[234:237], v[218:221], v[80:95]
	v_mfma_f32_32x32x16_bf16 v[16:31], v[234:237], v[222:225], v[16:31]
	ds_read_b128 v[234:237], v192 offset:64
	s_waitcnt lgkmcnt(5)
	v_mfma_f32_32x32x16_bf16 v[64:79], v[238:241], v[218:221], v[64:79]
	v_mfma_f32_32x32x16_bf16 v[0:15], v[238:241], v[222:225], v[0:15]
	ds_read_b128 v[238:241], v192 offset:4672
	s_setprio 0
	global_load_dwordx4 v[218:221], v[184:185], off offset:1152
	global_load_dwordx4 v[222:225], v[186:187], off offset:1152
	s_setprio 1
	s_waitcnt lgkmcnt(1)
	v_mfma_f32_32x32x16_bf16 v[112:127], v[234:237], v[226:229], v[112:127]
	v_mfma_f32_32x32x16_bf16 v[48:63], v[234:237], v[230:233], v[48:63]
	s_waitcnt lgkmcnt(0)
	v_mfma_f32_32x32x16_bf16 v[96:111], v[238:241], v[226:229], v[96:111]
	v_mfma_f32_32x32x16_bf16 v[32:47], v[238:241], v[230:233], v[32:47]
	ds_read_b128 v[234:237], v192 offset:9280
	ds_read_b128 v[238:241], v192 offset:13888
	s_waitcnt vmcnt(7)
	ds_write_b128 v215, v[176:179] offset:27648
	s_waitcnt vmcnt(6)
	ds_write_b128 v215, v[180:183] offset:64512
	ds_read_b128 v[176:179], v208 offset:96
	ds_read_b128 v[180:183], v208 offset:4704
	s_waitcnt lgkmcnt(5)
	v_mfma_f32_32x32x16_bf16 v[80:95], v[234:237], v[226:229], v[80:95]
	v_mfma_f32_32x32x16_bf16 v[16:31], v[234:237], v[230:233], v[16:31]
	ds_read_b128 v[234:237], v192 offset:96
	s_waitcnt lgkmcnt(5)
	v_mfma_f32_32x32x16_bf16 v[64:79], v[238:241], v[226:229], v[64:79]
	v_mfma_f32_32x32x16_bf16 v[0:15], v[238:241], v[230:233], v[0:15]
	ds_read_b128 v[238:241], v192 offset:4704
	s_setprio 0
	global_load_dwordx4 v[226:229], v[198:199], off offset:1152
	global_load_dwordx4 v[230:233], v[200:201], off offset:1152
	s_setprio 1
	s_waitcnt lgkmcnt(1)
	v_mfma_f32_32x32x16_bf16 v[112:127], v[234:237], v[176:179], v[112:127]
	v_mfma_f32_32x32x16_bf16 v[48:63], v[234:237], v[180:183], v[48:63]
	s_waitcnt lgkmcnt(0)
	v_mfma_f32_32x32x16_bf16 v[96:111], v[238:241], v[176:179], v[96:111]
	v_mfma_f32_32x32x16_bf16 v[32:47], v[238:241], v[180:183], v[32:47]
	ds_read_b128 v[234:237], v192 offset:9312
	ds_read_b128 v[238:241], v192 offset:13920
	s_waitcnt lgkmcnt(1)
	v_mfma_f32_32x32x16_bf16 v[80:95], v[234:237], v[176:179], v[80:95]
	v_mfma_f32_32x32x16_bf16 v[16:31], v[234:237], v[180:183], v[16:31]
	s_waitcnt lgkmcnt(0)
	v_mfma_f32_32x32x16_bf16 v[64:79], v[238:241], v[176:179], v[64:79]
	v_mfma_f32_32x32x16_bf16 v[0:15], v[238:241], v[180:183], v[0:15]
	s_setprio 0
	global_load_dwordx4 v[176:179], v[190:191], off offset:1280
	global_load_dwordx4 v[180:183], v[188:189], off offset:1280
	s_barrier
; template <bool trans>
; DI void gemm_core(const GTile& tl, const GTile& nx, bool has_next  , bool chain  , bool pre, u32x4 (&ra)[4], u32x4 (&rb)[4], char* smem, f32x16 (&acc)[2][4]) {
;     ...
;   const int nk = K / 64;
;   if (!pre) { G_LOAD(0); G_STORE(0); G_LOAD(1); }
;   for (int kt = 0; kt < nk; ++kt) {
;     __syncthreads();
;     G_COMPUTE(kt & 1, kt);
;   }
	s_waitcnt vmcnt(9)
	ds_write_b128 v209, v[168:171]
	s_waitcnt vmcnt(8)
	ds_write_b128 v210, v[172:175]
	ds_read_b128 v[168:171], v205 offset:36864
	ds_read_b128 v[172:175], v205 offset:41472
	ds_read_b128 v[234:237], v204
	ds_read_b128 v[238:241], v204 offset:4608
	s_setprio 1
	s_waitcnt lgkmcnt(1)
	v_mfma_f32_32x32x16_bf16 v[112:127], v[234:237], v[168:171], v[112:127]
	v_mfma_f32_32x32x16_bf16 v[48:63], v[234:237], v[172:175], v[48:63]
	s_waitcnt lgkmcnt(0)
	v_mfma_f32_32x32x16_bf16 v[96:111], v[238:241], v[168:171], v[96:111]
	v_mfma_f32_32x32x16_bf16 v[32:47], v[238:241], v[172:175], v[32:47]
	ds_read_b128 v[234:237], v204 offset:9216
	ds_read_b128 v[238:241], v204 offset:13824
	s_waitcnt vmcnt(7)
	ds_write_b128 v212, v[160:163]
	s_waitcnt vmcnt(6)
	ds_write_b128 v211, v[164:167]
	ds_read_b128 v[160:163], v205 offset:36896
	ds_read_b128 v[164:167], v205 offset:41504
	s_waitcnt lgkmcnt(5)
	v_mfma_f32_32x32x16_bf16 v[80:95], v[234:237], v[168:171], v[80:95]
	v_mfma_f32_32x32x16_bf16 v[16:31], v[234:237], v[172:175], v[16:31]
	ds_read_b128 v[234:237], v204 offset:32
	s_waitcnt lgkmcnt(5)
	v_mfma_f32_32x32x16_bf16 v[64:79], v[238:241], v[168:171], v[64:79]
	v_mfma_f32_32x32x16_bf16 v[0:15], v[238:241], v[172:175], v[0:15]
	ds_read_b128 v[238:241], v204 offset:4640
	s_setprio 0
	global_load_dwordx4 v[168:171], v[194:195], off offset:1280
	global_load_dwordx4 v[172:175], v[196:197], off offset:1280
	s_setprio 1
	s_waitcnt lgkmcnt(1)
	v_mfma_f32_32x32x16_bf16 v[112:127], v[234:237], v[160:163], v[112:127]
	v_mfma_f32_32x32x16_bf16 v[48:63], v[234:237], v[164:167], v[48:63]
	s_waitcnt lgkmcnt(0)
	v_mfma_f32_32x32x16_bf16 v[96:111], v[238:241], v[160:163], v[96:111]
	v_mfma_f32_32x32x16_bf16 v[32:47], v[238:241], v[164:167], v[32:47]
	ds_read_b128 v[234:237], v204 offset:9248
	ds_read_b128 v[238:241], v204 offset:13856
	s_waitcnt vmcnt(7)
	ds_write_b128 v214, v[218:221]
	s_waitcnt vmcnt(6)
	ds_write_b128 v213, v[222:225]
	ds_read_b128 v[218:221], v205 offset:36928
	ds_read_b128 v[222:225], v205 offset:41536
	s_waitcnt lgkmcnt(5)
	v_mfma_f32_32x32x16_bf16 v[80:95], v[234:237], v[160:163], v[80:95]
	v_mfma_f32_32x32x16_bf16 v[16:31], v[234:237], v[164:167], v[16:31]
	ds_read_b128 v[234:237], v204 offset:64
	s_waitcnt lgkmcnt(5)
	v_mfma_f32_32x32x16_bf16 v[64:79], v[238:241], v[160:163], v[64:79]
	v_mfma_f32_32x32x16_bf16 v[0:15], v[238:241], v[164:167], v[0:15]
	ds_read_b128 v[238:241], v204 offset:4672
	s_setprio 0
	global_load_dwordx4 v[160:163], v[184:185], off offset:1280
	global_load_dwordx4 v[164:167], v[186:187], off offset:1280
	s_setprio 1
	s_waitcnt lgkmcnt(1)
	v_mfma_f32_32x32x16_bf16 v[112:127], v[234:237], v[218:221], v[112:127]
	v_mfma_f32_32x32x16_bf16 v[48:63], v[234:237], v[222:225], v[48:63]
	s_waitcnt lgkmcnt(0)
	v_mfma_f32_32x32x16_bf16 v[96:111], v[238:241], v[218:221], v[96:111]
	v_mfma_f32_32x32x16_bf16 v[32:47], v[238:241], v[222:225], v[32:47]
	ds_read_b128 v[234:237], v204 offset:9280
	ds_read_b128 v[238:241], v204 offset:13888
	s_waitcnt vmcnt(7)
	ds_write_b128 v217, v[226:229]
	s_waitcnt vmcnt(6)
	ds_write_b128 v216, v[230:233]
	ds_read_b128 v[226:229], v205 offset:36960
	ds_read_b128 v[230:233], v205 offset:41568
	s_waitcnt lgkmcnt(5)
	v_mfma_f32_32x32x16_bf16 v[80:95], v[234:237], v[218:221], v[80:95]
	v_mfma_f32_32x32x16_bf16 v[16:31], v[234:237], v[222:225], v[16:31]
	ds_read_b128 v[234:237], v204 offset:96
	s_waitcnt lgkmcnt(5)
	v_mfma_f32_32x32x16_bf16 v[64:79], v[238:241], v[218:221], v[64:79]
	v_mfma_f32_32x32x16_bf16 v[0:15], v[238:241], v[222:225], v[0:15]
	ds_read_b128 v[238:241], v204 offset:4704
	s_setprio 0
	global_load_dwordx4 v[218:221], v[198:199], off offset:1280
	global_load_dwordx4 v[222:225], v[200:201], off offset:1280
	s_setprio 1
	s_waitcnt lgkmcnt(1)
	v_mfma_f32_32x32x16_bf16 v[112:127], v[234:237], v[226:229], v[112:127]
	v_mfma_f32_32x32x16_bf16 v[48:63], v[234:237], v[230:233], v[48:63]
	s_waitcnt lgkmcnt(0)
	v_mfma_f32_32x32x16_bf16 v[96:111], v[238:241], v[226:229], v[96:111]
	v_mfma_f32_32x32x16_bf16 v[32:47], v[238:241], v[230:233], v[32:47]
	ds_read_b128 v[234:237], v204 offset:9312
	ds_read_b128 v[238:241], v204 offset:13920
	s_waitcnt lgkmcnt(1)
	v_mfma_f32_32x32x16_bf16 v[80:95], v[234:237], v[226:229], v[80:95]
	v_mfma_f32_32x32x16_bf16 v[16:31], v[234:237], v[230:233], v[16:31]
	s_waitcnt lgkmcnt(0)
	v_mfma_f32_32x32x16_bf16 v[64:79], v[238:241], v[226:229], v[64:79]
	v_mfma_f32_32x32x16_bf16 v[0:15], v[238:241], v[230:233], v[0:15]
	s_setprio 0
	global_load_dwordx4 v[226:229], v[190:191], off offset:1408
	global_load_dwordx4 v[230:233], v[188:189], off offset:1408
	s_barrier
; template <bool trans>
; DI void gemm_core(const GTile& tl, const GTile& nx, bool has_next  , bool chain  , bool pre, u32x4 (&ra)[4], u32x4 (&rb)[4], char* smem, f32x16 (&acc)[2][4]) {
;     ...
;   const int nk = K / 64;
;   if (!pre) { G_LOAD(0); G_STORE(0); G_LOAD(1); }
;   for (int kt = 0; kt < nk; ++kt) {
;     __syncthreads();
;     G_COMPUTE(kt & 1, kt);
;   }
	s_waitcnt vmcnt(9)
	ds_write_b128 v215, v[176:179]
	s_waitcnt vmcnt(8)
	ds_write_b128 v215, v[180:183] offset:36864
	ds_read_b128 v[176:179], v208
	ds_read_b128 v[180:183], v208 offset:4608
	ds_read_b128 v[234:237], v192
	ds_read_b128 v[238:241], v192 offset:4608
	s_setprio 1
	s_waitcnt lgkmcnt(1)
	v_mfma_f32_32x32x16_bf16 v[112:127], v[234:237], v[176:179], v[112:127]
	v_mfma_f32_32x32x16_bf16 v[48:63], v[234:237], v[180:183], v[48:63]
	s_waitcnt lgkmcnt(0)
	v_mfma_f32_32x32x16_bf16 v[96:111], v[238:241], v[176:179], v[96:111]
	v_mfma_f32_32x32x16_bf16 v[32:47], v[238:241], v[180:183], v[32:47]
	ds_read_b128 v[234:237], v192 offset:9216
	ds_read_b128 v[238:241], v192 offset:13824
	s_waitcnt vmcnt(7)
	ds_write_b128 v215, v[168:171] offset:9216
	s_waitcnt vmcnt(6)
	ds_write_b128 v215, v[172:175] offset:46080
	ds_read_b128 v[168:171], v208 offset:32
	ds_read_b128 v[172:175], v208 offset:4640
	s_waitcnt lgkmcnt(5)
	v_mfma_f32_32x32x16_bf16 v[80:95], v[234:237], v[176:179], v[80:95]
	v_mfma_f32_32x32x16_bf16 v[16:31], v[234:237], v[180:183], v[16:31]
	ds_read_b128 v[234:237], v192 offset:32
	s_waitcnt lgkmcnt(5)
	v_mfma_f32_32x32x16_bf16 v[64:79], v[238:241], v[176:179], v[64:79]
	v_mfma_f32_32x32x16_bf16 v[0:15], v[238:241], v[180:183], v[0:15]
	ds_read_b128 v[238:241], v192 offset:4640
	s_setprio 0
	global_load_dwordx4 v[176:179], v[194:195], off offset:1408
	global_load_dwordx4 v[180:183], v[196:197], off offset:1408
	s_setprio 1
	s_waitcnt lgkmcnt(1)
	v_mfma_f32_32x32x16_bf16 v[112:127], v[234:237], v[168:171], v[112:127]
	v_mfma_f32_32x32x16_bf16 v[48:63], v[234:237], v[172:175], v[48:63]
	s_waitcnt lgkmcnt(0)
	v_mfma_f32_32x32x16_bf16 v[96:111], v[238:241], v[168:171], v[96:111]
	v_mfma_f32_32x32x16_bf16 v[32:47], v[238:241], v[172:175], v[32:47]
	ds_read_b128 v[234:237], v192 offset:9248
	ds_read_b128 v[238:241], v192 offset:13856
	s_waitcnt vmcnt(7)
	ds_write_b128 v215, v[160:163] offset:18432
	s_waitcnt vmcnt(6)
	ds_write_b128 v215, v[164:167] offset:55296
	ds_read_b128 v[160:163], v208 offset:64
	ds_read_b128 v[164:167], v208 offset:4672
	s_waitcnt lgkmcnt(5)
	v_mfma_f32_32x32x16_bf16 v[80:95], v[234:237], v[168:171], v[80:95]
	v_mfma_f32_32x32x16_bf16 v[16:31], v[234:237], v[172:175], v[16:31]
	ds_read_b128 v[234:237], v192 offset:64
	s_waitcnt lgkmcnt(5)
	v_mfma_f32_32x32x16_bf16 v[64:79], v[238:241], v[168:171], v[64:79]
	v_mfma_f32_32x32x16_bf16 v[0:15], v[238:241], v[172:175], v[0:15]
	ds_read_b128 v[238:241], v192 offset:4672
	s_setprio 0
	global_load_dwordx4 v[168:171], v[184:185], off offset:1408
	global_load_dwordx4 v[172:175], v[186:187], off offset:1408
	s_setprio 1
	s_waitcnt lgkmcnt(1)
	v_mfma_f32_32x32x16_bf16 v[112:127], v[234:237], v[160:163], v[112:127]
	v_mfma_f32_32x32x16_bf16 v[48:63], v[234:237], v[164:167], v[48:63]
	s_waitcnt lgkmcnt(0)
	v_mfma_f32_32x32x16_bf16 v[96:111], v[238:241], v[160:163], v[96:111]
	v_mfma_f32_32x32x16_bf16 v[32:47], v[238:241], v[164:167], v[32:47]
	ds_read_b128 v[234:237], v192 offset:9280
	ds_read_b128 v[238:241], v192 offset:13888
	s_waitcnt vmcnt(7)
	ds_write_b128 v215, v[218:221] offset:27648
	s_waitcnt vmcnt(6)
	ds_write_b128 v215, v[222:225] offset:64512
	ds_read_b128 v[218:221], v208 offset:96
	ds_read_b128 v[222:225], v208 offset:4704
	s_waitcnt lgkmcnt(5)
	v_mfma_f32_32x32x16_bf16 v[80:95], v[234:237], v[160:163], v[80:95]
	v_mfma_f32_32x32x16_bf16 v[16:31], v[234:237], v[164:167], v[16:31]
	ds_read_b128 v[234:237], v192 offset:96
	s_waitcnt lgkmcnt(5)
	v_mfma_f32_32x32x16_bf16 v[64:79], v[238:241], v[160:163], v[64:79]
	v_mfma_f32_32x32x16_bf16 v[0:15], v[238:241], v[164:167], v[0:15]
	ds_read_b128 v[238:241], v192 offset:4704
	s_setprio 0
	global_load_dwordx4 v[160:163], v[198:199], off offset:1408
	global_load_dwordx4 v[164:167], v[200:201], off offset:1408
	s_setprio 1
	s_waitcnt lgkmcnt(1)
	v_mfma_f32_32x32x16_bf16 v[112:127], v[234:237], v[218:221], v[112:127]
	v_mfma_f32_32x32x16_bf16 v[48:63], v[234:237], v[222:225], v[48:63]
	s_waitcnt lgkmcnt(0)
	v_mfma_f32_32x32x16_bf16 v[96:111], v[238:241], v[218:221], v[96:111]
	v_mfma_f32_32x32x16_bf16 v[32:47], v[238:241], v[222:225], v[32:47]
	ds_read_b128 v[234:237], v192 offset:9312
	ds_read_b128 v[238:241], v192 offset:13920
	s_waitcnt lgkmcnt(1)
	v_mfma_f32_32x32x16_bf16 v[80:95], v[234:237], v[218:221], v[80:95]
	v_mfma_f32_32x32x16_bf16 v[16:31], v[234:237], v[222:225], v[16:31]
	s_waitcnt lgkmcnt(0)
	v_mfma_f32_32x32x16_bf16 v[64:79], v[238:241], v[218:221], v[64:79]
	v_mfma_f32_32x32x16_bf16 v[0:15], v[238:241], v[222:225], v[0:15]
	s_setprio 0
	global_load_dwordx4 v[218:221], v[190:191], off offset:1536
	global_load_dwordx4 v[222:225], v[188:189], off offset:1536
	s_barrier
; template <bool trans>
; DI void gemm_core(const GTile& tl, const GTile& nx, bool has_next  , bool chain  , bool pre, u32x4 (&ra)[4], u32x4 (&rb)[4], char* smem, f32x16 (&acc)[2][4]) {
;     ...
;   const int nk = K / 64;
;   if (!pre) { G_LOAD(0); G_STORE(0); G_LOAD(1); }
;   for (int kt = 0; kt < nk; ++kt) {
;     __syncthreads();
;     G_COMPUTE(kt & 1, kt);
;   }
	s_waitcnt vmcnt(9)
	ds_write_b128 v209, v[226:229]
	s_waitcnt vmcnt(8)
	ds_write_b128 v210, v[230:233]
	ds_read_b128 v[226:229], v205 offset:36864
	ds_read_b128 v[230:233], v205 offset:41472
	ds_read_b128 v[234:237], v204
	ds_read_b128 v[238:241], v204 offset:4608
	s_setprio 1
	s_waitcnt lgkmcnt(1)
	v_mfma_f32_32x32x16_bf16 v[112:127], v[234:237], v[226:229], v[112:127]
	v_mfma_f32_32x32x16_bf16 v[48:63], v[234:237], v[230:233], v[48:63]
	s_waitcnt lgkmcnt(0)
	v_mfma_f32_32x32x16_bf16 v[96:111], v[238:241], v[226:229], v[96:111]
	v_mfma_f32_32x32x16_bf16 v[32:47], v[238:241], v[230:233], v[32:47]
	ds_read_b128 v[234:237], v204 offset:9216
	ds_read_b128 v[238:241], v204 offset:13824
	s_waitcnt vmcnt(7)
	ds_write_b128 v212, v[176:179]
	s_waitcnt vmcnt(6)
	ds_write_b128 v211, v[180:183]
	ds_read_b128 v[176:179], v205 offset:36896
	ds_read_b128 v[180:183], v205 offset:41504
	s_waitcnt lgkmcnt(5)
	v_mfma_f32_32x32x16_bf16 v[80:95], v[234:237], v[226:229], v[80:95]
	v_mfma_f32_32x32x16_bf16 v[16:31], v[234:237], v[230:233], v[16:31]
	ds_read_b128 v[234:237], v204 offset:32
	s_waitcnt lgkmcnt(5)
	v_mfma_f32_32x32x16_bf16 v[64:79], v[238:241], v[226:229], v[64:79]
	v_mfma_f32_32x32x16_bf16 v[0:15], v[238:241], v[230:233], v[0:15]
	ds_read_b128 v[238:241], v204 offset:4640
	s_setprio 0
	global_load_dwordx4 v[226:229], v[194:195], off offset:1536
	global_load_dwordx4 v[230:233], v[196:197], off offset:1536
	s_setprio 1
	s_waitcnt lgkmcnt(1)
	v_mfma_f32_32x32x16_bf16 v[112:127], v[234:237], v[176:179], v[112:127]
	v_mfma_f32_32x32x16_bf16 v[48:63], v[234:237], v[180:183], v[48:63]
	s_waitcnt lgkmcnt(0)
	v_mfma_f32_32x32x16_bf16 v[96:111], v[238:241], v[176:179], v[96:111]
	v_mfma_f32_32x32x16_bf16 v[32:47], v[238:241], v[180:183], v[32:47]
	ds_read_b128 v[234:237], v204 offset:9248
	ds_read_b128 v[238:241], v204 offset:13856
	s_waitcnt vmcnt(7)
	ds_write_b128 v214, v[168:171]
	s_waitcnt vmcnt(6)
	ds_write_b128 v213, v[172:175]
	ds_read_b128 v[168:171], v205 offset:36928
	ds_read_b128 v[172:175], v205 offset:41536
	s_waitcnt lgkmcnt(5)
	v_mfma_f32_32x32x16_bf16 v[80:95], v[234:237], v[176:179], v[80:95]
	v_mfma_f32_32x32x16_bf16 v[16:31], v[234:237], v[180:183], v[16:31]
	ds_read_b128 v[234:237], v204 offset:64
	s_waitcnt lgkmcnt(5)
	v_mfma_f32_32x32x16_bf16 v[64:79], v[238:241], v[176:179], v[64:79]
	v_mfma_f32_32x32x16_bf16 v[0:15], v[238:241], v[180:183], v[0:15]
	ds_read_b128 v[238:241], v204 offset:4672
	s_setprio 0
	global_load_dwordx4 v[176:179], v[184:185], off offset:1536
	global_load_dwordx4 v[180:183], v[186:187], off offset:1536
	s_setprio 1
	s_waitcnt lgkmcnt(1)
	v_mfma_f32_32x32x16_bf16 v[112:127], v[234:237], v[168:171], v[112:127]
	v_mfma_f32_32x32x16_bf16 v[48:63], v[234:237], v[172:175], v[48:63]
	s_waitcnt lgkmcnt(0)
	v_mfma_f32_32x32x16_bf16 v[96:111], v[238:241], v[168:171], v[96:111]
	v_mfma_f32_32x32x16_bf16 v[32:47], v[238:241], v[172:175], v[32:47]
	ds_read_b128 v[234:237], v204 offset:9280
	ds_read_b128 v[238:241], v204 offset:13888
	s_waitcnt vmcnt(7)
	ds_write_b128 v217, v[160:163]
	s_waitcnt vmcnt(6)
	ds_write_b128 v216, v[164:167]
	ds_read_b128 v[160:163], v205 offset:36960
	ds_read_b128 v[164:167], v205 offset:41568
	s_waitcnt lgkmcnt(5)
	v_mfma_f32_32x32x16_bf16 v[80:95], v[234:237], v[168:171], v[80:95]
	v_mfma_f32_32x32x16_bf16 v[16:31], v[234:237], v[172:175], v[16:31]
	ds_read_b128 v[234:237], v204 offset:96
	s_waitcnt lgkmcnt(5)
	v_mfma_f32_32x32x16_bf16 v[64:79], v[238:241], v[168:171], v[64:79]
	v_mfma_f32_32x32x16_bf16 v[0:15], v[238:241], v[172:175], v[0:15]
	ds_read_b128 v[238:241], v204 offset:4704
	s_setprio 0
	global_load_dwordx4 v[168:171], v[198:199], off offset:1536
	global_load_dwordx4 v[172:175], v[200:201], off offset:1536
	s_setprio 1
	s_waitcnt lgkmcnt(1)
	v_mfma_f32_32x32x16_bf16 v[112:127], v[234:237], v[160:163], v[112:127]
	v_mfma_f32_32x32x16_bf16 v[48:63], v[234:237], v[164:167], v[48:63]
	s_waitcnt lgkmcnt(0)
	v_mfma_f32_32x32x16_bf16 v[96:111], v[238:241], v[160:163], v[96:111]
	v_mfma_f32_32x32x16_bf16 v[32:47], v[238:241], v[164:167], v[32:47]
	ds_read_b128 v[234:237], v204 offset:9312
	ds_read_b128 v[238:241], v204 offset:13920
	s_waitcnt lgkmcnt(1)
	v_mfma_f32_32x32x16_bf16 v[80:95], v[234:237], v[160:163], v[80:95]
	v_mfma_f32_32x32x16_bf16 v[16:31], v[234:237], v[164:167], v[16:31]
	s_waitcnt lgkmcnt(0)
	v_mfma_f32_32x32x16_bf16 v[64:79], v[238:241], v[160:163], v[64:79]
	v_mfma_f32_32x32x16_bf16 v[0:15], v[238:241], v[164:167], v[0:15]
	s_setprio 0
	global_load_dwordx4 v[160:163], v[190:191], off offset:1664
	global_load_dwordx4 v[164:167], v[188:189], off offset:1664
	s_barrier
; template <bool trans>
; DI void gemm_core(const GTile& tl, const GTile& nx, bool has_next  , bool chain  , bool pre, u32x4 (&ra)[4], u32x4 (&rb)[4], char* smem, f32x16 (&acc)[2][4]) {
;     ...
;   const int nk = K / 64;
;   if (!pre) { G_LOAD(0); G_STORE(0); G_LOAD(1); }
;   for (int kt = 0; kt < nk; ++kt) {
;     __syncthreads();
;     G_COMPUTE(kt & 1, kt);
;   }
	s_waitcnt vmcnt(9)
	ds_write_b128 v215, v[218:221]
	s_waitcnt vmcnt(8)
	ds_write_b128 v215, v[222:225] offset:36864
	ds_read_b128 v[218:221], v208
	ds_read_b128 v[222:225], v208 offset:4608
	ds_read_b128 v[234:237], v192
	ds_read_b128 v[238:241], v192 offset:4608
	s_setprio 1
	s_waitcnt lgkmcnt(1)
	v_mfma_f32_32x32x16_bf16 v[112:127], v[234:237], v[218:221], v[112:127]
	v_mfma_f32_32x32x16_bf16 v[48:63], v[234:237], v[222:225], v[48:63]
	s_waitcnt lgkmcnt(0)
	v_mfma_f32_32x32x16_bf16 v[96:111], v[238:241], v[218:221], v[96:111]
	v_mfma_f32_32x32x16_bf16 v[32:47], v[238:241], v[222:225], v[32:47]
	ds_read_b128 v[234:237], v192 offset:9216
	ds_read_b128 v[238:241], v192 offset:13824
	s_waitcnt vmcnt(7)
	ds_write_b128 v215, v[226:229] offset:9216
	s_waitcnt vmcnt(6)
	ds_write_b128 v215, v[230:233] offset:46080
	ds_read_b128 v[226:229], v208 offset:32
	ds_read_b128 v[230:233], v208 offset:4640
	s_waitcnt lgkmcnt(5)
	v_mfma_f32_32x32x16_bf16 v[80:95], v[234:237], v[218:221], v[80:95]
	v_mfma_f32_32x32x16_bf16 v[16:31], v[234:237], v[222:225], v[16:31]
	ds_read_b128 v[234:237], v192 offset:32
	s_waitcnt lgkmcnt(5)
	v_mfma_f32_32x32x16_bf16 v[64:79], v[238:241], v[218:221], v[64:79]
	v_mfma_f32_32x32x16_bf16 v[0:15], v[238:241], v[222:225], v[0:15]
	ds_read_b128 v[238:241], v192 offset:4640
	s_setprio 0
	global_load_dwordx4 v[218:221], v[194:195], off offset:1664
	global_load_dwordx4 v[222:225], v[196:197], off offset:1664
	s_setprio 1
	s_waitcnt lgkmcnt(1)
	v_mfma_f32_32x32x16_bf16 v[112:127], v[234:237], v[226:229], v[112:127]
	v_mfma_f32_32x32x16_bf16 v[48:63], v[234:237], v[230:233], v[48:63]
	s_waitcnt lgkmcnt(0)
	v_mfma_f32_32x32x16_bf16 v[96:111], v[238:241], v[226:229], v[96:111]
	v_mfma_f32_32x32x16_bf16 v[32:47], v[238:241], v[230:233], v[32:47]
	ds_read_b128 v[234:237], v192 offset:9248
	ds_read_b128 v[238:241], v192 offset:13856
	s_waitcnt vmcnt(7)
	ds_write_b128 v215, v[176:179] offset:18432
	s_waitcnt vmcnt(6)
	ds_write_b128 v215, v[180:183] offset:55296
	ds_read_b128 v[176:179], v208 offset:64
	ds_read_b128 v[180:183], v208 offset:4672
	s_waitcnt lgkmcnt(5)
	v_mfma_f32_32x32x16_bf16 v[80:95], v[234:237], v[226:229], v[80:95]
	v_mfma_f32_32x32x16_bf16 v[16:31], v[234:237], v[230:233], v[16:31]
	ds_read_b128 v[234:237], v192 offset:64
	s_waitcnt lgkmcnt(5)
	v_mfma_f32_32x32x16_bf16 v[64:79], v[238:241], v[226:229], v[64:79]
	v_mfma_f32_32x32x16_bf16 v[0:15], v[238:241], v[230:233], v[0:15]
	ds_read_b128 v[238:241], v192 offset:4672
	s_setprio 0
	global_load_dwordx4 v[226:229], v[184:185], off offset:1664
	global_load_dwordx4 v[230:233], v[186:187], off offset:1664
	s_setprio 1
	s_waitcnt lgkmcnt(1)
	v_mfma_f32_32x32x16_bf16 v[112:127], v[234:237], v[176:179], v[112:127]
	v_mfma_f32_32x32x16_bf16 v[48:63], v[234:237], v[180:183], v[48:63]
	s_waitcnt lgkmcnt(0)
	v_mfma_f32_32x32x16_bf16 v[96:111], v[238:241], v[176:179], v[96:111]
	v_mfma_f32_32x32x16_bf16 v[32:47], v[238:241], v[180:183], v[32:47]
	ds_read_b128 v[234:237], v192 offset:9280
	ds_read_b128 v[238:241], v192 offset:13888
	s_waitcnt vmcnt(7)
	ds_write_b128 v215, v[168:171] offset:27648
	s_waitcnt vmcnt(6)
	ds_write_b128 v215, v[172:175] offset:64512
	ds_read_b128 v[168:171], v208 offset:96
	ds_read_b128 v[172:175], v208 offset:4704
	s_waitcnt lgkmcnt(5)
	v_mfma_f32_32x32x16_bf16 v[80:95], v[234:237], v[176:179], v[80:95]
	v_mfma_f32_32x32x16_bf16 v[16:31], v[234:237], v[180:183], v[16:31]
	ds_read_b128 v[234:237], v192 offset:96
	s_waitcnt lgkmcnt(5)
	v_mfma_f32_32x32x16_bf16 v[64:79], v[238:241], v[176:179], v[64:79]
	v_mfma_f32_32x32x16_bf16 v[0:15], v[238:241], v[180:183], v[0:15]
	ds_read_b128 v[238:241], v192 offset:4704
	s_setprio 0
	global_load_dwordx4 v[176:179], v[198:199], off offset:1664
	global_load_dwordx4 v[180:183], v[200:201], off offset:1664
	s_setprio 1
	s_waitcnt lgkmcnt(1)
	v_mfma_f32_32x32x16_bf16 v[112:127], v[234:237], v[168:171], v[112:127]
	v_mfma_f32_32x32x16_bf16 v[48:63], v[234:237], v[172:175], v[48:63]
	s_waitcnt lgkmcnt(0)
	v_mfma_f32_32x32x16_bf16 v[96:111], v[238:241], v[168:171], v[96:111]
	v_mfma_f32_32x32x16_bf16 v[32:47], v[238:241], v[172:175], v[32:47]
	ds_read_b128 v[234:237], v192 offset:9312
	ds_read_b128 v[238:241], v192 offset:13920
	s_waitcnt lgkmcnt(1)
	v_mfma_f32_32x32x16_bf16 v[80:95], v[234:237], v[168:171], v[80:95]
	v_mfma_f32_32x32x16_bf16 v[16:31], v[234:237], v[172:175], v[16:31]
	s_waitcnt lgkmcnt(0)
	v_mfma_f32_32x32x16_bf16 v[64:79], v[238:241], v[168:171], v[64:79]
	v_mfma_f32_32x32x16_bf16 v[0:15], v[238:241], v[172:175], v[0:15]
	s_setprio 0
	global_load_dwordx4 v[168:171], v[190:191], off offset:1792
	global_load_dwordx4 v[172:175], v[188:189], off offset:1792
	s_barrier
; template <bool trans>
; DI void gemm_core(const GTile& tl, const GTile& nx, bool has_next  , bool chain  , bool pre, u32x4 (&ra)[4], u32x4 (&rb)[4], char* smem, f32x16 (&acc)[2][4]) {
;     ...
;   const int nk = K / 64;
;   if (!pre) { G_LOAD(0); G_STORE(0); G_LOAD(1); }
;   for (int kt = 0; kt < nk; ++kt) {
;     __syncthreads();
;     G_COMPUTE(kt & 1, kt);
;   }
	s_waitcnt vmcnt(9)
	ds_write_b128 v209, v[160:163]
	s_waitcnt vmcnt(8)
	ds_write_b128 v210, v[164:167]
	ds_read_b128 v[160:163], v205 offset:36864
	ds_read_b128 v[164:167], v205 offset:41472
	ds_read_b128 v[234:237], v204
	ds_read_b128 v[238:241], v204 offset:4608
	s_setprio 1
	s_waitcnt lgkmcnt(1)
	v_mfma_f32_32x32x16_bf16 v[112:127], v[234:237], v[160:163], v[112:127]
	v_mfma_f32_32x32x16_bf16 v[48:63], v[234:237], v[164:167], v[48:63]
	s_waitcnt lgkmcnt(0)
	v_mfma_f32_32x32x16_bf16 v[96:111], v[238:241], v[160:163], v[96:111]
	v_mfma_f32_32x32x16_bf16 v[32:47], v[238:241], v[164:167], v[32:47]
	ds_read_b128 v[234:237], v204 offset:9216
	ds_read_b128 v[238:241], v204 offset:13824
	s_waitcnt vmcnt(7)
	ds_write_b128 v212, v[218:221]
	s_waitcnt vmcnt(6)
	ds_write_b128 v211, v[222:225]
	ds_read_b128 v[218:221], v205 offset:36896
	ds_read_b128 v[222:225], v205 offset:41504
	s_waitcnt lgkmcnt(5)
	v_mfma_f32_32x32x16_bf16 v[80:95], v[234:237], v[160:163], v[80:95]
	v_mfma_f32_32x32x16_bf16 v[16:31], v[234:237], v[164:167], v[16:31]
	ds_read_b128 v[234:237], v204 offset:32
	s_waitcnt lgkmcnt(5)
	v_mfma_f32_32x32x16_bf16 v[64:79], v[238:241], v[160:163], v[64:79]
	v_mfma_f32_32x32x16_bf16 v[0:15], v[238:241], v[164:167], v[0:15]
	ds_read_b128 v[238:241], v204 offset:4640
	s_setprio 0
	global_load_dwordx4 v[160:163], v[194:195], off offset:1792
	global_load_dwordx4 v[164:167], v[196:197], off offset:1792
	s_setprio 1
	s_waitcnt lgkmcnt(1)
	v_mfma_f32_32x32x16_bf16 v[112:127], v[234:237], v[218:221], v[112:127]
	v_mfma_f32_32x32x16_bf16 v[48:63], v[234:237], v[222:225], v[48:63]
	s_waitcnt lgkmcnt(0)
	v_mfma_f32_32x32x16_bf16 v[96:111], v[238:241], v[218:221], v[96:111]
	v_mfma_f32_32x32x16_bf16 v[32:47], v[238:241], v[222:225], v[32:47]
	ds_read_b128 v[234:237], v204 offset:9248
	ds_read_b128 v[238:241], v204 offset:13856
	s_waitcnt vmcnt(7)
	ds_write_b128 v214, v[226:229]
	s_waitcnt vmcnt(6)
	ds_write_b128 v213, v[230:233]
	ds_read_b128 v[226:229], v205 offset:36928
	ds_read_b128 v[230:233], v205 offset:41536
	s_waitcnt lgkmcnt(5)
	v_mfma_f32_32x32x16_bf16 v[80:95], v[234:237], v[218:221], v[80:95]
	v_mfma_f32_32x32x16_bf16 v[16:31], v[234:237], v[222:225], v[16:31]
	ds_read_b128 v[234:237], v204 offset:64
	s_waitcnt lgkmcnt(5)
	v_mfma_f32_32x32x16_bf16 v[64:79], v[238:241], v[218:221], v[64:79]
	v_mfma_f32_32x32x16_bf16 v[0:15], v[238:241], v[222:225], v[0:15]
	ds_read_b128 v[238:241], v204 offset:4672
	s_setprio 0
	global_load_dwordx4 v[218:221], v[184:185], off offset:1792
	global_load_dwordx4 v[222:225], v[186:187], off offset:1792
	s_setprio 1
	s_waitcnt lgkmcnt(1)
	v_mfma_f32_32x32x16_bf16 v[112:127], v[234:237], v[226:229], v[112:127]
	v_mfma_f32_32x32x16_bf16 v[48:63], v[234:237], v[230:233], v[48:63]
	s_waitcnt lgkmcnt(0)
	v_mfma_f32_32x32x16_bf16 v[96:111], v[238:241], v[226:229], v[96:111]
	v_mfma_f32_32x32x16_bf16 v[32:47], v[238:241], v[230:233], v[32:47]
	ds_read_b128 v[234:237], v204 offset:9280
	ds_read_b128 v[238:241], v204 offset:13888
	s_waitcnt vmcnt(7)
	ds_write_b128 v217, v[176:179]
	s_waitcnt vmcnt(6)
	ds_write_b128 v216, v[180:183]
	ds_read_b128 v[176:179], v205 offset:36960
	ds_read_b128 v[180:183], v205 offset:41568
	s_waitcnt lgkmcnt(5)
	v_mfma_f32_32x32x16_bf16 v[80:95], v[234:237], v[226:229], v[80:95]
	v_mfma_f32_32x32x16_bf16 v[16:31], v[234:237], v[230:233], v[16:31]
	ds_read_b128 v[234:237], v204 offset:96
	s_waitcnt lgkmcnt(5)
	v_mfma_f32_32x32x16_bf16 v[64:79], v[238:241], v[226:229], v[64:79]
	v_mfma_f32_32x32x16_bf16 v[0:15], v[238:241], v[230:233], v[0:15]
	ds_read_b128 v[238:241], v204 offset:4704
	s_setprio 0
	global_load_dwordx4 v[226:229], v[198:199], off offset:1792
	global_load_dwordx4 v[230:233], v[200:201], off offset:1792
	s_setprio 1
	s_waitcnt lgkmcnt(1)
	v_mfma_f32_32x32x16_bf16 v[112:127], v[234:237], v[176:179], v[112:127]
	v_mfma_f32_32x32x16_bf16 v[48:63], v[234:237], v[180:183], v[48:63]
	s_waitcnt lgkmcnt(0)
	v_mfma_f32_32x32x16_bf16 v[96:111], v[238:241], v[176:179], v[96:111]
	v_mfma_f32_32x32x16_bf16 v[32:47], v[238:241], v[180:183], v[32:47]
	ds_read_b128 v[234:237], v204 offset:9312
	ds_read_b128 v[238:241], v204 offset:13920
	s_waitcnt lgkmcnt(1)
	v_mfma_f32_32x32x16_bf16 v[80:95], v[234:237], v[176:179], v[80:95]
	v_mfma_f32_32x32x16_bf16 v[16:31], v[234:237], v[180:183], v[16:31]
	s_waitcnt lgkmcnt(0)
	v_mfma_f32_32x32x16_bf16 v[64:79], v[238:241], v[176:179], v[64:79]
	v_mfma_f32_32x32x16_bf16 v[0:15], v[238:241], v[180:183], v[0:15]
	s_setprio 0
	global_load_dwordx4 v[176:179], v[190:191], off offset:1920
	global_load_dwordx4 v[180:183], v[188:189], off offset:1920
	s_barrier
; template <bool trans>
; DI void gemm_core(const GTile& tl, const GTile& nx, bool has_next  , bool chain  , bool pre, u32x4 (&ra)[4], u32x4 (&rb)[4], char* smem, f32x16 (&acc)[2][4]) {
;     ...
;   const int nk = K / 64;
;   if (!pre) { G_LOAD(0); G_STORE(0); G_LOAD(1); }
;   for (int kt = 0; kt < nk; ++kt) {
;     __syncthreads();
;     G_COMPUTE(kt & 1, kt);
;   }
	s_waitcnt vmcnt(9)
	ds_write_b128 v215, v[168:171]
	s_waitcnt vmcnt(8)
	ds_write_b128 v215, v[172:175] offset:36864
	ds_read_b128 v[168:171], v208
	ds_read_b128 v[172:175], v208 offset:4608
	ds_read_b128 v[234:237], v192
	ds_read_b128 v[238:241], v192 offset:4608
	s_setprio 1
	s_waitcnt lgkmcnt(1)
	v_mfma_f32_32x32x16_bf16 v[112:127], v[234:237], v[168:171], v[112:127]
	v_mfma_f32_32x32x16_bf16 v[48:63], v[234:237], v[172:175], v[48:63]
	s_waitcnt lgkmcnt(0)
	v_mfma_f32_32x32x16_bf16 v[96:111], v[238:241], v[168:171], v[96:111]
	v_mfma_f32_32x32x16_bf16 v[32:47], v[238:241], v[172:175], v[32:47]
	ds_read_b128 v[234:237], v192 offset:9216
	ds_read_b128 v[238:241], v192 offset:13824
	s_waitcnt vmcnt(7)
	ds_write_b128 v215, v[160:163] offset:9216
	s_waitcnt vmcnt(6)
	ds_write_b128 v215, v[164:167] offset:46080
	ds_read_b128 v[160:163], v208 offset:32
	ds_read_b128 v[164:167], v208 offset:4640
	s_waitcnt lgkmcnt(5)
	v_mfma_f32_32x32x16_bf16 v[80:95], v[234:237], v[168:171], v[80:95]
	v_mfma_f32_32x32x16_bf16 v[16:31], v[234:237], v[172:175], v[16:31]
	ds_read_b128 v[234:237], v192 offset:32
	s_waitcnt lgkmcnt(5)
	v_mfma_f32_32x32x16_bf16 v[64:79], v[238:241], v[168:171], v[64:79]
	v_mfma_f32_32x32x16_bf16 v[0:15], v[238:241], v[172:175], v[0:15]
	ds_read_b128 v[238:241], v192 offset:4640
	s_setprio 0
	global_load_dwordx4 v[168:171], v[194:195], off offset:1920
	global_load_dwordx4 v[172:175], v[196:197], off offset:1920
	s_setprio 1
	s_waitcnt lgkmcnt(1)
	v_mfma_f32_32x32x16_bf16 v[112:127], v[234:237], v[160:163], v[112:127]
	v_mfma_f32_32x32x16_bf16 v[48:63], v[234:237], v[164:167], v[48:63]
	s_waitcnt lgkmcnt(0)
	v_mfma_f32_32x32x16_bf16 v[96:111], v[238:241], v[160:163], v[96:111]
	v_mfma_f32_32x32x16_bf16 v[32:47], v[238:241], v[164:167], v[32:47]
	ds_read_b128 v[234:237], v192 offset:9248
	ds_read_b128 v[238:241], v192 offset:13856
	s_waitcnt vmcnt(7)
	ds_write_b128 v215, v[218:221] offset:18432
	s_waitcnt vmcnt(6)
	ds_write_b128 v215, v[222:225] offset:55296
	ds_read_b128 v[218:221], v208 offset:64
	ds_read_b128 v[222:225], v208 offset:4672
	s_waitcnt lgkmcnt(5)
	v_mfma_f32_32x32x16_bf16 v[80:95], v[234:237], v[160:163], v[80:95]
	v_mfma_f32_32x32x16_bf16 v[16:31], v[234:237], v[164:167], v[16:31]
	ds_read_b128 v[234:237], v192 offset:64
	s_waitcnt lgkmcnt(5)
	v_mfma_f32_32x32x16_bf16 v[64:79], v[238:241], v[160:163], v[64:79]
	v_mfma_f32_32x32x16_bf16 v[0:15], v[238:241], v[164:167], v[0:15]
	ds_read_b128 v[238:241], v192 offset:4672
	s_setprio 0
	global_load_dwordx4 v[160:163], v[184:185], off offset:1920
	global_load_dwordx4 v[164:167], v[186:187], off offset:1920
	s_setprio 1
	s_waitcnt lgkmcnt(1)
	v_mfma_f32_32x32x16_bf16 v[112:127], v[234:237], v[218:221], v[112:127]
	v_mfma_f32_32x32x16_bf16 v[48:63], v[234:237], v[222:225], v[48:63]
	s_waitcnt lgkmcnt(0)
	v_mfma_f32_32x32x16_bf16 v[96:111], v[238:241], v[218:221], v[96:111]
	v_mfma_f32_32x32x16_bf16 v[32:47], v[238:241], v[222:225], v[32:47]
	ds_read_b128 v[234:237], v192 offset:9280
	ds_read_b128 v[238:241], v192 offset:13888
	s_waitcnt vmcnt(7)
	ds_write_b128 v215, v[226:229] offset:27648
	s_waitcnt vmcnt(6)
	ds_write_b128 v215, v[230:233] offset:64512
	ds_read_b128 v[226:229], v208 offset:96
	ds_read_b128 v[230:233], v208 offset:4704
	s_waitcnt lgkmcnt(5)
	v_mfma_f32_32x32x16_bf16 v[80:95], v[234:237], v[218:221], v[80:95]
	v_mfma_f32_32x32x16_bf16 v[16:31], v[234:237], v[222:225], v[16:31]
	ds_read_b128 v[234:237], v192 offset:96
	s_waitcnt lgkmcnt(5)
	v_mfma_f32_32x32x16_bf16 v[64:79], v[238:241], v[218:221], v[64:79]
	v_mfma_f32_32x32x16_bf16 v[0:15], v[238:241], v[222:225], v[0:15]
	ds_read_b128 v[238:241], v192 offset:4704
	s_setprio 0
	global_load_dwordx4 v[218:221], v[198:199], off offset:1920
	global_load_dwordx4 v[222:225], v[200:201], off offset:1920
	s_setprio 1
	s_waitcnt lgkmcnt(1)
	v_mfma_f32_32x32x16_bf16 v[112:127], v[234:237], v[226:229], v[112:127]
	v_mfma_f32_32x32x16_bf16 v[48:63], v[234:237], v[230:233], v[48:63]
	s_waitcnt lgkmcnt(0)
	v_mfma_f32_32x32x16_bf16 v[96:111], v[238:241], v[226:229], v[96:111]
	v_mfma_f32_32x32x16_bf16 v[32:47], v[238:241], v[230:233], v[32:47]
	ds_read_b128 v[234:237], v192 offset:9312
	ds_read_b128 v[238:241], v192 offset:13920
	s_waitcnt lgkmcnt(1)
	v_mfma_f32_32x32x16_bf16 v[80:95], v[234:237], v[226:229], v[80:95]
	v_mfma_f32_32x32x16_bf16 v[16:31], v[234:237], v[230:233], v[16:31]
	s_waitcnt lgkmcnt(0)
	v_mfma_f32_32x32x16_bf16 v[64:79], v[238:241], v[226:229], v[64:79]
	v_mfma_f32_32x32x16_bf16 v[0:15], v[238:241], v[230:233], v[0:15]
	s_setprio 0
	global_load_dwordx4 v[226:229], v[190:191], off offset:2048
	global_load_dwordx4 v[230:233], v[188:189], off offset:2048
	s_barrier
; template <bool trans>
; DI void gemm_core(const GTile& tl, const GTile& nx, bool has_next  , bool chain  , bool pre, u32x4 (&ra)[4], u32x4 (&rb)[4], char* smem, f32x16 (&acc)[2][4]) {
;     ...
;   const int nk = K / 64;
;   if (!pre) { G_LOAD(0); G_STORE(0); G_LOAD(1); }
;   for (int kt = 0; kt < nk; ++kt) {
;     __syncthreads();
;     G_COMPUTE(kt & 1, kt);
;   }
	s_waitcnt vmcnt(9)
	ds_write_b128 v209, v[176:179]
	s_waitcnt vmcnt(8)
	ds_write_b128 v210, v[180:183]
	ds_read_b128 v[176:179], v205 offset:36864
	ds_read_b128 v[180:183], v205 offset:41472
	ds_read_b128 v[234:237], v204
	ds_read_b128 v[238:241], v204 offset:4608
	s_setprio 1
	s_waitcnt lgkmcnt(1)
	v_mfma_f32_32x32x16_bf16 v[112:127], v[234:237], v[176:179], v[112:127]
	v_mfma_f32_32x32x16_bf16 v[48:63], v[234:237], v[180:183], v[48:63]
	s_waitcnt lgkmcnt(0)
	v_mfma_f32_32x32x16_bf16 v[96:111], v[238:241], v[176:179], v[96:111]
	v_mfma_f32_32x32x16_bf16 v[32:47], v[238:241], v[180:183], v[32:47]
	ds_read_b128 v[234:237], v204 offset:9216
	ds_read_b128 v[238:241], v204 offset:13824
	s_waitcnt vmcnt(7)
	ds_write_b128 v212, v[168:171]
	s_waitcnt vmcnt(6)
	ds_write_b128 v211, v[172:175]
	ds_read_b128 v[168:171], v205 offset:36896
	ds_read_b128 v[172:175], v205 offset:41504
	s_waitcnt lgkmcnt(5)
	v_mfma_f32_32x32x16_bf16 v[80:95], v[234:237], v[176:179], v[80:95]
	v_mfma_f32_32x32x16_bf16 v[16:31], v[234:237], v[180:183], v[16:31]
	ds_read_b128 v[234:237], v204 offset:32
	s_waitcnt lgkmcnt(5)
	v_mfma_f32_32x32x16_bf16 v[64:79], v[238:241], v[176:179], v[64:79]
	v_mfma_f32_32x32x16_bf16 v[0:15], v[238:241], v[180:183], v[0:15]
	ds_read_b128 v[238:241], v204 offset:4640
	s_setprio 0
	global_load_dwordx4 v[176:179], v[194:195], off offset:2048
	global_load_dwordx4 v[180:183], v[196:197], off offset:2048
	s_setprio 1
	s_waitcnt lgkmcnt(1)
	v_mfma_f32_32x32x16_bf16 v[112:127], v[234:237], v[168:171], v[112:127]
	v_mfma_f32_32x32x16_bf16 v[48:63], v[234:237], v[172:175], v[48:63]
	s_waitcnt lgkmcnt(0)
	v_mfma_f32_32x32x16_bf16 v[96:111], v[238:241], v[168:171], v[96:111]
	v_mfma_f32_32x32x16_bf16 v[32:47], v[238:241], v[172:175], v[32:47]
	ds_read_b128 v[234:237], v204 offset:9248
	ds_read_b128 v[238:241], v204 offset:13856
	s_waitcnt vmcnt(7)
	ds_write_b128 v214, v[160:163]
	s_waitcnt vmcnt(6)
	ds_write_b128 v213, v[164:167]
	ds_read_b128 v[160:163], v205 offset:36928
	ds_read_b128 v[164:167], v205 offset:41536
	s_waitcnt lgkmcnt(5)
	v_mfma_f32_32x32x16_bf16 v[80:95], v[234:237], v[168:171], v[80:95]
	v_mfma_f32_32x32x16_bf16 v[16:31], v[234:237], v[172:175], v[16:31]
	ds_read_b128 v[234:237], v204 offset:64
	s_waitcnt lgkmcnt(5)
	v_mfma_f32_32x32x16_bf16 v[64:79], v[238:241], v[168:171], v[64:79]
	v_mfma_f32_32x32x16_bf16 v[0:15], v[238:241], v[172:175], v[0:15]
	ds_read_b128 v[238:241], v204 offset:4672
	s_setprio 0
	global_load_dwordx4 v[168:171], v[184:185], off offset:2048
	global_load_dwordx4 v[172:175], v[186:187], off offset:2048
	s_setprio 1
	s_waitcnt lgkmcnt(1)
	v_mfma_f32_32x32x16_bf16 v[112:127], v[234:237], v[160:163], v[112:127]
	v_mfma_f32_32x32x16_bf16 v[48:63], v[234:237], v[164:167], v[48:63]
	s_waitcnt lgkmcnt(0)
	v_mfma_f32_32x32x16_bf16 v[96:111], v[238:241], v[160:163], v[96:111]
	v_mfma_f32_32x32x16_bf16 v[32:47], v[238:241], v[164:167], v[32:47]
	ds_read_b128 v[234:237], v204 offset:9280
	ds_read_b128 v[238:241], v204 offset:13888
	s_waitcnt vmcnt(7)
	ds_write_b128 v217, v[218:221]
	s_waitcnt vmcnt(6)
	ds_write_b128 v216, v[222:225]
	ds_read_b128 v[218:221], v205 offset:36960
	ds_read_b128 v[222:225], v205 offset:41568
	s_waitcnt lgkmcnt(5)
	v_mfma_f32_32x32x16_bf16 v[80:95], v[234:237], v[160:163], v[80:95]
	v_mfma_f32_32x32x16_bf16 v[16:31], v[234:237], v[164:167], v[16:31]
	ds_read_b128 v[234:237], v204 offset:96
	s_waitcnt lgkmcnt(5)
	v_mfma_f32_32x32x16_bf16 v[64:79], v[238:241], v[160:163], v[64:79]
	v_mfma_f32_32x32x16_bf16 v[0:15], v[238:241], v[164:167], v[0:15]
	ds_read_b128 v[238:241], v204 offset:4704
	s_setprio 0
	global_load_dwordx4 v[160:163], v[198:199], off offset:2048
	global_load_dwordx4 v[164:167], v[200:201], off offset:2048
	s_setprio 1
	s_waitcnt lgkmcnt(1)
	v_mfma_f32_32x32x16_bf16 v[112:127], v[234:237], v[218:221], v[112:127]
	v_mfma_f32_32x32x16_bf16 v[48:63], v[234:237], v[222:225], v[48:63]
	s_waitcnt lgkmcnt(0)
	v_mfma_f32_32x32x16_bf16 v[96:111], v[238:241], v[218:221], v[96:111]
	v_mfma_f32_32x32x16_bf16 v[32:47], v[238:241], v[222:225], v[32:47]
	ds_read_b128 v[234:237], v204 offset:9312
	ds_read_b128 v[238:241], v204 offset:13920
	s_waitcnt lgkmcnt(1)
	v_mfma_f32_32x32x16_bf16 v[80:95], v[234:237], v[218:221], v[80:95]
	v_mfma_f32_32x32x16_bf16 v[16:31], v[234:237], v[222:225], v[16:31]
	s_waitcnt lgkmcnt(0)
	v_mfma_f32_32x32x16_bf16 v[64:79], v[238:241], v[218:221], v[64:79]
	v_mfma_f32_32x32x16_bf16 v[0:15], v[238:241], v[222:225], v[0:15]
	s_setprio 0
	global_load_dwordx4 v[218:221], v[190:191], off offset:2176
	global_load_dwordx4 v[222:225], v[188:189], off offset:2176
	s_barrier
; template <bool trans>
; DI void gemm_core(const GTile& tl, const GTile& nx, bool has_next  , bool chain  , bool pre, u32x4 (&ra)[4], u32x4 (&rb)[4], char* smem, f32x16 (&acc)[2][4]) {
;     ...
;   const int nk = K / 64;
;   if (!pre) { G_LOAD(0); G_STORE(0); G_LOAD(1); }
;   for (int kt = 0; kt < nk; ++kt) {
;     __syncthreads();
;     G_COMPUTE(kt & 1, kt);
;   }
	s_waitcnt vmcnt(9)
	ds_write_b128 v215, v[226:229]
	s_waitcnt vmcnt(8)
	ds_write_b128 v215, v[230:233] offset:36864
	ds_read_b128 v[226:229], v208
	ds_read_b128 v[230:233], v208 offset:4608
	ds_read_b128 v[234:237], v192
	ds_read_b128 v[238:241], v192 offset:4608
	s_setprio 1
	s_waitcnt lgkmcnt(1)
	v_mfma_f32_32x32x16_bf16 v[112:127], v[234:237], v[226:229], v[112:127]
	v_mfma_f32_32x32x16_bf16 v[48:63], v[234:237], v[230:233], v[48:63]
	s_waitcnt lgkmcnt(0)
	v_mfma_f32_32x32x16_bf16 v[96:111], v[238:241], v[226:229], v[96:111]
	v_mfma_f32_32x32x16_bf16 v[32:47], v[238:241], v[230:233], v[32:47]
	ds_read_b128 v[234:237], v192 offset:9216
	ds_read_b128 v[238:241], v192 offset:13824
	s_waitcnt vmcnt(7)
	ds_write_b128 v215, v[176:179] offset:9216
	s_waitcnt vmcnt(6)
	ds_write_b128 v215, v[180:183] offset:46080
	ds_read_b128 v[176:179], v208 offset:32
	ds_read_b128 v[180:183], v208 offset:4640
	s_waitcnt lgkmcnt(5)
	v_mfma_f32_32x32x16_bf16 v[80:95], v[234:237], v[226:229], v[80:95]
	v_mfma_f32_32x32x16_bf16 v[16:31], v[234:237], v[230:233], v[16:31]
	ds_read_b128 v[234:237], v192 offset:32
	s_waitcnt lgkmcnt(5)
	v_mfma_f32_32x32x16_bf16 v[64:79], v[238:241], v[226:229], v[64:79]
	v_mfma_f32_32x32x16_bf16 v[0:15], v[238:241], v[230:233], v[0:15]
	ds_read_b128 v[238:241], v192 offset:4640
	s_setprio 0
	global_load_dwordx4 v[226:229], v[194:195], off offset:2176
	global_load_dwordx4 v[230:233], v[196:197], off offset:2176
	s_setprio 1
	s_waitcnt lgkmcnt(1)
	v_mfma_f32_32x32x16_bf16 v[112:127], v[234:237], v[176:179], v[112:127]
	v_mfma_f32_32x32x16_bf16 v[48:63], v[234:237], v[180:183], v[48:63]
	s_waitcnt lgkmcnt(0)
	v_mfma_f32_32x32x16_bf16 v[96:111], v[238:241], v[176:179], v[96:111]
	v_mfma_f32_32x32x16_bf16 v[32:47], v[238:241], v[180:183], v[32:47]
	ds_read_b128 v[234:237], v192 offset:9248
	ds_read_b128 v[238:241], v192 offset:13856
	s_waitcnt vmcnt(7)
	ds_write_b128 v215, v[168:171] offset:18432
	s_waitcnt vmcnt(6)
	ds_write_b128 v215, v[172:175] offset:55296
	ds_read_b128 v[168:171], v208 offset:64
	ds_read_b128 v[172:175], v208 offset:4672
	s_waitcnt lgkmcnt(5)
	v_mfma_f32_32x32x16_bf16 v[80:95], v[234:237], v[176:179], v[80:95]
	v_mfma_f32_32x32x16_bf16 v[16:31], v[234:237], v[180:183], v[16:31]
	ds_read_b128 v[234:237], v192 offset:64
	s_waitcnt lgkmcnt(5)
	v_mfma_f32_32x32x16_bf16 v[64:79], v[238:241], v[176:179], v[64:79]
	v_mfma_f32_32x32x16_bf16 v[0:15], v[238:241], v[180:183], v[0:15]
	ds_read_b128 v[238:241], v192 offset:4672
	s_setprio 0
	global_load_dwordx4 v[176:179], v[184:185], off offset:2176
	global_load_dwordx4 v[180:183], v[186:187], off offset:2176
	s_setprio 1
	s_waitcnt lgkmcnt(1)
	v_mfma_f32_32x32x16_bf16 v[112:127], v[234:237], v[168:171], v[112:127]
	v_mfma_f32_32x32x16_bf16 v[48:63], v[234:237], v[172:175], v[48:63]
	s_waitcnt lgkmcnt(0)
	v_mfma_f32_32x32x16_bf16 v[96:111], v[238:241], v[168:171], v[96:111]
	v_mfma_f32_32x32x16_bf16 v[32:47], v[238:241], v[172:175], v[32:47]
	ds_read_b128 v[234:237], v192 offset:9280
	ds_read_b128 v[238:241], v192 offset:13888
	s_waitcnt vmcnt(7)
	ds_write_b128 v215, v[160:163] offset:27648
	s_waitcnt vmcnt(6)
	ds_write_b128 v215, v[164:167] offset:64512
	ds_read_b128 v[160:163], v208 offset:96
	ds_read_b128 v[164:167], v208 offset:4704
	s_waitcnt lgkmcnt(5)
	v_mfma_f32_32x32x16_bf16 v[80:95], v[234:237], v[168:171], v[80:95]
	v_mfma_f32_32x32x16_bf16 v[16:31], v[234:237], v[172:175], v[16:31]
	ds_read_b128 v[234:237], v192 offset:96
	s_waitcnt lgkmcnt(5)
	v_mfma_f32_32x32x16_bf16 v[64:79], v[238:241], v[168:171], v[64:79]
	v_mfma_f32_32x32x16_bf16 v[0:15], v[238:241], v[172:175], v[0:15]
	ds_read_b128 v[238:241], v192 offset:4704
	s_setprio 0
	global_load_dwordx4 v[168:171], v[198:199], off offset:2176
	global_load_dwordx4 v[172:175], v[200:201], off offset:2176
	s_setprio 1
	s_waitcnt lgkmcnt(1)
	v_mfma_f32_32x32x16_bf16 v[112:127], v[234:237], v[160:163], v[112:127]
	v_mfma_f32_32x32x16_bf16 v[48:63], v[234:237], v[164:167], v[48:63]
	s_waitcnt lgkmcnt(0)
	v_mfma_f32_32x32x16_bf16 v[96:111], v[238:241], v[160:163], v[96:111]
	v_mfma_f32_32x32x16_bf16 v[32:47], v[238:241], v[164:167], v[32:47]
	ds_read_b128 v[234:237], v192 offset:9312
	ds_read_b128 v[238:241], v192 offset:13920
	s_waitcnt lgkmcnt(1)
	v_mfma_f32_32x32x16_bf16 v[80:95], v[234:237], v[160:163], v[80:95]
	v_mfma_f32_32x32x16_bf16 v[16:31], v[234:237], v[164:167], v[16:31]
	s_waitcnt lgkmcnt(0)
	v_mfma_f32_32x32x16_bf16 v[64:79], v[238:241], v[160:163], v[64:79]
	v_mfma_f32_32x32x16_bf16 v[0:15], v[238:241], v[164:167], v[0:15]
	s_setprio 0
	global_load_dwordx4 v[160:163], v[190:191], off offset:2304
	global_load_dwordx4 v[164:167], v[188:189], off offset:2304
	s_barrier
; template <bool trans>
; DI void gemm_core(const GTile& tl, const GTile& nx, bool has_next  , bool chain  , bool pre, u32x4 (&ra)[4], u32x4 (&rb)[4], char* smem, f32x16 (&acc)[2][4]) {
;     ...
;   const int nk = K / 64;
;   if (!pre) { G_LOAD(0); G_STORE(0); G_LOAD(1); }
;   for (int kt = 0; kt < nk; ++kt) {
;     __syncthreads();
;     G_COMPUTE(kt & 1, kt);
;   }
	s_waitcnt vmcnt(9)
	ds_write_b128 v209, v[218:221]
	s_waitcnt vmcnt(8)
	ds_write_b128 v210, v[222:225]
	ds_read_b128 v[218:221], v205 offset:36864
	ds_read_b128 v[222:225], v205 offset:41472
	ds_read_b128 v[234:237], v204
	ds_read_b128 v[238:241], v204 offset:4608
	s_setprio 1
	s_waitcnt lgkmcnt(1)
	v_mfma_f32_32x32x16_bf16 v[112:127], v[234:237], v[218:221], v[112:127]
	v_mfma_f32_32x32x16_bf16 v[48:63], v[234:237], v[222:225], v[48:63]
	s_waitcnt lgkmcnt(0)
	v_mfma_f32_32x32x16_bf16 v[96:111], v[238:241], v[218:221], v[96:111]
	v_mfma_f32_32x32x16_bf16 v[32:47], v[238:241], v[222:225], v[32:47]
	ds_read_b128 v[234:237], v204 offset:9216
	ds_read_b128 v[238:241], v204 offset:13824
	s_waitcnt vmcnt(7)
	ds_write_b128 v212, v[226:229]
	s_waitcnt vmcnt(6)
	ds_write_b128 v211, v[230:233]
	ds_read_b128 v[226:229], v205 offset:36896
	ds_read_b128 v[230:233], v205 offset:41504
	s_waitcnt lgkmcnt(5)
	v_mfma_f32_32x32x16_bf16 v[80:95], v[234:237], v[218:221], v[80:95]
	v_mfma_f32_32x32x16_bf16 v[16:31], v[234:237], v[222:225], v[16:31]
	ds_read_b128 v[234:237], v204 offset:32
	s_waitcnt lgkmcnt(5)
	v_mfma_f32_32x32x16_bf16 v[64:79], v[238:241], v[218:221], v[64:79]
	v_mfma_f32_32x32x16_bf16 v[0:15], v[238:241], v[222:225], v[0:15]
	ds_read_b128 v[238:241], v204 offset:4640
	s_setprio 0
	global_load_dwordx4 v[218:221], v[194:195], off offset:2304
	global_load_dwordx4 v[222:225], v[196:197], off offset:2304
	s_setprio 1
	s_waitcnt lgkmcnt(1)
	v_mfma_f32_32x32x16_bf16 v[112:127], v[234:237], v[226:229], v[112:127]
	v_mfma_f32_32x32x16_bf16 v[48:63], v[234:237], v[230:233], v[48:63]
	s_waitcnt lgkmcnt(0)
	v_mfma_f32_32x32x16_bf16 v[96:111], v[238:241], v[226:229], v[96:111]
	v_mfma_f32_32x32x16_bf16 v[32:47], v[238:241], v[230:233], v[32:47]
	ds_read_b128 v[234:237], v204 offset:9248
	ds_read_b128 v[238:241], v204 offset:13856
	s_waitcnt vmcnt(7)
	ds_write_b128 v214, v[176:179]
	s_waitcnt vmcnt(6)
	ds_write_b128 v213, v[180:183]
	ds_read_b128 v[176:179], v205 offset:36928
	ds_read_b128 v[180:183], v205 offset:41536
	s_waitcnt lgkmcnt(5)
	v_mfma_f32_32x32x16_bf16 v[80:95], v[234:237], v[226:229], v[80:95]
	v_mfma_f32_32x32x16_bf16 v[16:31], v[234:237], v[230:233], v[16:31]
	ds_read_b128 v[234:237], v204 offset:64
	s_waitcnt lgkmcnt(5)
	v_mfma_f32_32x32x16_bf16 v[64:79], v[238:241], v[226:229], v[64:79]
	v_mfma_f32_32x32x16_bf16 v[0:15], v[238:241], v[230:233], v[0:15]
	ds_read_b128 v[238:241], v204 offset:4672
	s_setprio 0
	global_load_dwordx4 v[226:229], v[184:185], off offset:2304
	global_load_dwordx4 v[230:233], v[186:187], off offset:2304
	s_setprio 1
	s_waitcnt lgkmcnt(1)
	v_mfma_f32_32x32x16_bf16 v[112:127], v[234:237], v[176:179], v[112:127]
	v_mfma_f32_32x32x16_bf16 v[48:63], v[234:237], v[180:183], v[48:63]
	s_waitcnt lgkmcnt(0)
	v_mfma_f32_32x32x16_bf16 v[96:111], v[238:241], v[176:179], v[96:111]
	v_mfma_f32_32x32x16_bf16 v[32:47], v[238:241], v[180:183], v[32:47]
	ds_read_b128 v[234:237], v204 offset:9280
	ds_read_b128 v[238:241], v204 offset:13888
	s_waitcnt vmcnt(7)
	ds_write_b128 v217, v[168:171]
	s_waitcnt vmcnt(6)
	ds_write_b128 v216, v[172:175]
	ds_read_b128 v[168:171], v205 offset:36960
	ds_read_b128 v[172:175], v205 offset:41568
	s_waitcnt lgkmcnt(5)
	v_mfma_f32_32x32x16_bf16 v[80:95], v[234:237], v[176:179], v[80:95]
	v_mfma_f32_32x32x16_bf16 v[16:31], v[234:237], v[180:183], v[16:31]
	ds_read_b128 v[234:237], v204 offset:96
	s_waitcnt lgkmcnt(5)
	v_mfma_f32_32x32x16_bf16 v[64:79], v[238:241], v[176:179], v[64:79]
	v_mfma_f32_32x32x16_bf16 v[0:15], v[238:241], v[180:183], v[0:15]
	ds_read_b128 v[238:241], v204 offset:4704
	s_setprio 0
	global_load_dwordx4 v[176:179], v[198:199], off offset:2304
	global_load_dwordx4 v[180:183], v[200:201], off offset:2304
	s_setprio 1
	s_waitcnt lgkmcnt(1)
	v_mfma_f32_32x32x16_bf16 v[112:127], v[234:237], v[168:171], v[112:127]
	v_mfma_f32_32x32x16_bf16 v[48:63], v[234:237], v[172:175], v[48:63]
	s_waitcnt lgkmcnt(0)
	v_mfma_f32_32x32x16_bf16 v[96:111], v[238:241], v[168:171], v[96:111]
	v_mfma_f32_32x32x16_bf16 v[32:47], v[238:241], v[172:175], v[32:47]
	ds_read_b128 v[234:237], v204 offset:9312
	ds_read_b128 v[238:241], v204 offset:13920
	s_waitcnt lgkmcnt(1)
	v_mfma_f32_32x32x16_bf16 v[80:95], v[234:237], v[168:171], v[80:95]
	v_mfma_f32_32x32x16_bf16 v[16:31], v[234:237], v[172:175], v[16:31]
	s_waitcnt lgkmcnt(0)
	v_mfma_f32_32x32x16_bf16 v[64:79], v[238:241], v[168:171], v[64:79]
	v_mfma_f32_32x32x16_bf16 v[0:15], v[238:241], v[172:175], v[0:15]
	s_setprio 0
	global_load_dwordx4 v[168:171], v[190:191], off offset:2432
	global_load_dwordx4 v[172:175], v[188:189], off offset:2432
	s_barrier
; template <bool trans>
; DI void gemm_core(const GTile& tl, const GTile& nx, bool has_next  , bool chain  , bool pre, u32x4 (&ra)[4], u32x4 (&rb)[4], char* smem, f32x16 (&acc)[2][4]) {
;     ...
;   const int nk = K / 64;
;   if (!pre) { G_LOAD(0); G_STORE(0); G_LOAD(1); }
;   for (int kt = 0; kt < nk; ++kt) {
;     __syncthreads();
;     G_COMPUTE(kt & 1, kt);
;   }
	s_waitcnt vmcnt(9)
	ds_write_b128 v215, v[160:163]
	s_waitcnt vmcnt(8)
	ds_write_b128 v215, v[164:167] offset:36864
	ds_read_b128 v[160:163], v208
	ds_read_b128 v[164:167], v208 offset:4608
	ds_read_b128 v[234:237], v192
	ds_read_b128 v[238:241], v192 offset:4608
	s_setprio 1
	s_waitcnt lgkmcnt(1)
	v_mfma_f32_32x32x16_bf16 v[112:127], v[234:237], v[160:163], v[112:127]
	v_mfma_f32_32x32x16_bf16 v[48:63], v[234:237], v[164:167], v[48:63]
	s_waitcnt lgkmcnt(0)
	v_mfma_f32_32x32x16_bf16 v[96:111], v[238:241], v[160:163], v[96:111]
	v_mfma_f32_32x32x16_bf16 v[32:47], v[238:241], v[164:167], v[32:47]
	ds_read_b128 v[234:237], v192 offset:9216
	ds_read_b128 v[238:241], v192 offset:13824
	s_waitcnt vmcnt(7)
	ds_write_b128 v215, v[218:221] offset:9216
	s_waitcnt vmcnt(6)
	ds_write_b128 v215, v[222:225] offset:46080
	ds_read_b128 v[218:221], v208 offset:32
	ds_read_b128 v[222:225], v208 offset:4640
	s_waitcnt lgkmcnt(5)
	v_mfma_f32_32x32x16_bf16 v[80:95], v[234:237], v[160:163], v[80:95]
	v_mfma_f32_32x32x16_bf16 v[16:31], v[234:237], v[164:167], v[16:31]
	ds_read_b128 v[234:237], v192 offset:32
	s_waitcnt lgkmcnt(5)
	v_mfma_f32_32x32x16_bf16 v[64:79], v[238:241], v[160:163], v[64:79]
	v_mfma_f32_32x32x16_bf16 v[0:15], v[238:241], v[164:167], v[0:15]
	ds_read_b128 v[238:241], v192 offset:4640
	s_setprio 0
	global_load_dwordx4 v[160:163], v[194:195], off offset:2432
	global_load_dwordx4 v[164:167], v[196:197], off offset:2432
	s_setprio 1
	s_waitcnt lgkmcnt(1)
	v_mfma_f32_32x32x16_bf16 v[112:127], v[234:237], v[218:221], v[112:127]
	v_mfma_f32_32x32x16_bf16 v[48:63], v[234:237], v[222:225], v[48:63]
	s_waitcnt lgkmcnt(0)
	v_mfma_f32_32x32x16_bf16 v[96:111], v[238:241], v[218:221], v[96:111]
	v_mfma_f32_32x32x16_bf16 v[32:47], v[238:241], v[222:225], v[32:47]
	ds_read_b128 v[234:237], v192 offset:9248
	ds_read_b128 v[238:241], v192 offset:13856
	s_waitcnt vmcnt(7)
	ds_write_b128 v215, v[226:229] offset:18432
	s_waitcnt vmcnt(6)
	ds_write_b128 v215, v[230:233] offset:55296
	ds_read_b128 v[226:229], v208 offset:64
	ds_read_b128 v[230:233], v208 offset:4672
	s_waitcnt lgkmcnt(5)
	v_mfma_f32_32x32x16_bf16 v[80:95], v[234:237], v[218:221], v[80:95]
	v_mfma_f32_32x32x16_bf16 v[16:31], v[234:237], v[222:225], v[16:31]
	ds_read_b128 v[234:237], v192 offset:64
	s_waitcnt lgkmcnt(5)
	v_mfma_f32_32x32x16_bf16 v[64:79], v[238:241], v[218:221], v[64:79]
	v_mfma_f32_32x32x16_bf16 v[0:15], v[238:241], v[222:225], v[0:15]
	ds_read_b128 v[238:241], v192 offset:4672
	s_setprio 0
	global_load_dwordx4 v[218:221], v[184:185], off offset:2432
	global_load_dwordx4 v[222:225], v[186:187], off offset:2432
	s_setprio 1
	s_waitcnt lgkmcnt(1)
	v_mfma_f32_32x32x16_bf16 v[112:127], v[234:237], v[226:229], v[112:127]
	v_mfma_f32_32x32x16_bf16 v[48:63], v[234:237], v[230:233], v[48:63]
	s_waitcnt lgkmcnt(0)
	v_mfma_f32_32x32x16_bf16 v[96:111], v[238:241], v[226:229], v[96:111]
	v_mfma_f32_32x32x16_bf16 v[32:47], v[238:241], v[230:233], v[32:47]
	ds_read_b128 v[234:237], v192 offset:9280
	ds_read_b128 v[238:241], v192 offset:13888
	s_waitcnt vmcnt(7)
	ds_write_b128 v215, v[176:179] offset:27648
	s_waitcnt vmcnt(6)
	ds_write_b128 v215, v[180:183] offset:64512
	ds_read_b128 v[176:179], v208 offset:96
	ds_read_b128 v[180:183], v208 offset:4704
	s_waitcnt lgkmcnt(5)
	v_mfma_f32_32x32x16_bf16 v[80:95], v[234:237], v[226:229], v[80:95]
	v_mfma_f32_32x32x16_bf16 v[16:31], v[234:237], v[230:233], v[16:31]
	ds_read_b128 v[234:237], v192 offset:96
	s_waitcnt lgkmcnt(5)
	v_mfma_f32_32x32x16_bf16 v[64:79], v[238:241], v[226:229], v[64:79]
	v_mfma_f32_32x32x16_bf16 v[0:15], v[238:241], v[230:233], v[0:15]
	ds_read_b128 v[238:241], v192 offset:4704
	s_setprio 0
	global_load_dwordx4 v[226:229], v[198:199], off offset:2432
	global_load_dwordx4 v[230:233], v[200:201], off offset:2432
	s_setprio 1
	s_waitcnt lgkmcnt(1)
	v_mfma_f32_32x32x16_bf16 v[112:127], v[234:237], v[176:179], v[112:127]
	v_mfma_f32_32x32x16_bf16 v[48:63], v[234:237], v[180:183], v[48:63]
	s_waitcnt lgkmcnt(0)
	v_mfma_f32_32x32x16_bf16 v[96:111], v[238:241], v[176:179], v[96:111]
	v_mfma_f32_32x32x16_bf16 v[32:47], v[238:241], v[180:183], v[32:47]
	ds_read_b128 v[234:237], v192 offset:9312
	ds_read_b128 v[238:241], v192 offset:13920
	s_waitcnt lgkmcnt(1)
	v_mfma_f32_32x32x16_bf16 v[80:95], v[234:237], v[176:179], v[80:95]
	v_mfma_f32_32x32x16_bf16 v[16:31], v[234:237], v[180:183], v[16:31]
	s_waitcnt lgkmcnt(0)
	v_mfma_f32_32x32x16_bf16 v[64:79], v[238:241], v[176:179], v[64:79]
	v_mfma_f32_32x32x16_bf16 v[0:15], v[238:241], v[180:183], v[0:15]
	s_setprio 0
	global_load_dwordx4 v[176:179], v[190:191], off offset:2560
	global_load_dwordx4 v[180:183], v[188:189], off offset:2560
	s_barrier
; template <bool trans>
; DI void gemm_core(const GTile& tl, const GTile& nx, bool has_next  , bool chain  , bool pre, u32x4 (&ra)[4], u32x4 (&rb)[4], char* smem, f32x16 (&acc)[2][4]) {
;     ...
;   const int nk = K / 64;
;   if (!pre) { G_LOAD(0); G_STORE(0); G_LOAD(1); }
;   for (int kt = 0; kt < nk; ++kt) {
;     __syncthreads();
;     G_COMPUTE(kt & 1, kt);
;   }
	s_waitcnt vmcnt(9)
	ds_write_b128 v209, v[168:171]
	s_waitcnt vmcnt(8)
	ds_write_b128 v210, v[172:175]
	ds_read_b128 v[168:171], v205 offset:36864
	ds_read_b128 v[172:175], v205 offset:41472
	ds_read_b128 v[234:237], v204
	ds_read_b128 v[238:241], v204 offset:4608
	s_setprio 1
	s_waitcnt lgkmcnt(1)
	v_mfma_f32_32x32x16_bf16 v[112:127], v[234:237], v[168:171], v[112:127]
	v_mfma_f32_32x32x16_bf16 v[48:63], v[234:237], v[172:175], v[48:63]
	s_waitcnt lgkmcnt(0)
	v_mfma_f32_32x32x16_bf16 v[96:111], v[238:241], v[168:171], v[96:111]
	v_mfma_f32_32x32x16_bf16 v[32:47], v[238:241], v[172:175], v[32:47]
	ds_read_b128 v[234:237], v204 offset:9216
	ds_read_b128 v[238:241], v204 offset:13824
	s_waitcnt vmcnt(7)
	ds_write_b128 v212, v[160:163]
	s_waitcnt vmcnt(6)
	ds_write_b128 v211, v[164:167]
	ds_read_b128 v[160:163], v205 offset:36896
	ds_read_b128 v[164:167], v205 offset:41504
	s_waitcnt lgkmcnt(5)
	v_mfma_f32_32x32x16_bf16 v[80:95], v[234:237], v[168:171], v[80:95]
	v_mfma_f32_32x32x16_bf16 v[16:31], v[234:237], v[172:175], v[16:31]
	ds_read_b128 v[234:237], v204 offset:32
	s_waitcnt lgkmcnt(5)
	v_mfma_f32_32x32x16_bf16 v[64:79], v[238:241], v[168:171], v[64:79]
	v_mfma_f32_32x32x16_bf16 v[0:15], v[238:241], v[172:175], v[0:15]
	ds_read_b128 v[238:241], v204 offset:4640
	s_setprio 0
	global_load_dwordx4 v[168:171], v[194:195], off offset:2560
	global_load_dwordx4 v[172:175], v[196:197], off offset:2560
	s_setprio 1
	s_waitcnt lgkmcnt(1)
	v_mfma_f32_32x32x16_bf16 v[112:127], v[234:237], v[160:163], v[112:127]
	v_mfma_f32_32x32x16_bf16 v[48:63], v[234:237], v[164:167], v[48:63]
	s_waitcnt lgkmcnt(0)
	v_mfma_f32_32x32x16_bf16 v[96:111], v[238:241], v[160:163], v[96:111]
	v_mfma_f32_32x32x16_bf16 v[32:47], v[238:241], v[164:167], v[32:47]
	ds_read_b128 v[234:237], v204 offset:9248
	ds_read_b128 v[238:241], v204 offset:13856
	s_waitcnt vmcnt(7)
	ds_write_b128 v214, v[218:221]
	s_waitcnt vmcnt(6)
	ds_write_b128 v213, v[222:225]
	ds_read_b128 v[218:221], v205 offset:36928
	ds_read_b128 v[222:225], v205 offset:41536
	s_waitcnt lgkmcnt(5)
	v_mfma_f32_32x32x16_bf16 v[80:95], v[234:237], v[160:163], v[80:95]
	v_mfma_f32_32x32x16_bf16 v[16:31], v[234:237], v[164:167], v[16:31]
	ds_read_b128 v[234:237], v204 offset:64
	s_waitcnt lgkmcnt(5)
	v_mfma_f32_32x32x16_bf16 v[64:79], v[238:241], v[160:163], v[64:79]
	v_mfma_f32_32x32x16_bf16 v[0:15], v[238:241], v[164:167], v[0:15]
	ds_read_b128 v[238:241], v204 offset:4672
	s_setprio 0
	global_load_dwordx4 v[160:163], v[184:185], off offset:2560
	global_load_dwordx4 v[164:167], v[186:187], off offset:2560
	s_setprio 1
	s_waitcnt lgkmcnt(1)
	v_mfma_f32_32x32x16_bf16 v[112:127], v[234:237], v[218:221], v[112:127]
	v_mfma_f32_32x32x16_bf16 v[48:63], v[234:237], v[222:225], v[48:63]
	s_waitcnt lgkmcnt(0)
	v_mfma_f32_32x32x16_bf16 v[96:111], v[238:241], v[218:221], v[96:111]
	v_mfma_f32_32x32x16_bf16 v[32:47], v[238:241], v[222:225], v[32:47]
	ds_read_b128 v[234:237], v204 offset:9280
	ds_read_b128 v[238:241], v204 offset:13888
	s_waitcnt vmcnt(7)
	ds_write_b128 v217, v[226:229]
	s_waitcnt vmcnt(6)
	ds_write_b128 v216, v[230:233]
	ds_read_b128 v[226:229], v205 offset:36960
	ds_read_b128 v[230:233], v205 offset:41568
	s_waitcnt lgkmcnt(5)
	v_mfma_f32_32x32x16_bf16 v[80:95], v[234:237], v[218:221], v[80:95]
	v_mfma_f32_32x32x16_bf16 v[16:31], v[234:237], v[222:225], v[16:31]
	ds_read_b128 v[234:237], v204 offset:96
	s_waitcnt lgkmcnt(5)
	v_mfma_f32_32x32x16_bf16 v[64:79], v[238:241], v[218:221], v[64:79]
	v_mfma_f32_32x32x16_bf16 v[0:15], v[238:241], v[222:225], v[0:15]
	ds_read_b128 v[238:241], v204 offset:4704
	s_setprio 0
	global_load_dwordx4 v[218:221], v[198:199], off offset:2560
	global_load_dwordx4 v[222:225], v[200:201], off offset:2560
	s_setprio 1
	s_waitcnt lgkmcnt(1)
	v_mfma_f32_32x32x16_bf16 v[112:127], v[234:237], v[226:229], v[112:127]
	v_mfma_f32_32x32x16_bf16 v[48:63], v[234:237], v[230:233], v[48:63]
	s_waitcnt lgkmcnt(0)
	v_mfma_f32_32x32x16_bf16 v[96:111], v[238:241], v[226:229], v[96:111]
	v_mfma_f32_32x32x16_bf16 v[32:47], v[238:241], v[230:233], v[32:47]
	ds_read_b128 v[234:237], v204 offset:9312
	ds_read_b128 v[238:241], v204 offset:13920
	s_waitcnt lgkmcnt(1)
	v_mfma_f32_32x32x16_bf16 v[80:95], v[234:237], v[226:229], v[80:95]
	v_mfma_f32_32x32x16_bf16 v[16:31], v[234:237], v[230:233], v[16:31]
	s_waitcnt lgkmcnt(0)
	v_mfma_f32_32x32x16_bf16 v[64:79], v[238:241], v[226:229], v[64:79]
	v_mfma_f32_32x32x16_bf16 v[0:15], v[238:241], v[230:233], v[0:15]
	s_setprio 0
	global_load_dwordx4 v[226:229], v[190:191], off offset:2688
	global_load_dwordx4 v[230:233], v[188:189], off offset:2688
	s_barrier
; template <bool trans>
; DI void gemm_core(const GTile& tl, const GTile& nx, bool has_next  , bool chain  , bool pre, u32x4 (&ra)[4], u32x4 (&rb)[4], char* smem, f32x16 (&acc)[2][4]) {
;     ...
;   const int nk = K / 64;
;   if (!pre) { G_LOAD(0); G_STORE(0); G_LOAD(1); }
;   for (int kt = 0; kt < nk; ++kt) {
;     __syncthreads();
;     G_COMPUTE(kt & 1, kt);
;   }
	s_waitcnt vmcnt(9)
	ds_write_b128 v215, v[176:179]
	s_waitcnt vmcnt(8)
	ds_write_b128 v215, v[180:183] offset:36864
	ds_read_b128 v[176:179], v208
	ds_read_b128 v[180:183], v208 offset:4608
	ds_read_b128 v[234:237], v192
	ds_read_b128 v[238:241], v192 offset:4608
	s_setprio 1
	s_waitcnt lgkmcnt(1)
	v_mfma_f32_32x32x16_bf16 v[112:127], v[234:237], v[176:179], v[112:127]
	v_mfma_f32_32x32x16_bf16 v[48:63], v[234:237], v[180:183], v[48:63]
	s_waitcnt lgkmcnt(0)
	v_mfma_f32_32x32x16_bf16 v[96:111], v[238:241], v[176:179], v[96:111]
	v_mfma_f32_32x32x16_bf16 v[32:47], v[238:241], v[180:183], v[32:47]
	ds_read_b128 v[234:237], v192 offset:9216
	ds_read_b128 v[238:241], v192 offset:13824
	s_waitcnt vmcnt(7)
	ds_write_b128 v215, v[168:171] offset:9216
	s_waitcnt vmcnt(6)
	ds_write_b128 v215, v[172:175] offset:46080
	ds_read_b128 v[168:171], v208 offset:32
	ds_read_b128 v[172:175], v208 offset:4640
	s_waitcnt lgkmcnt(5)
	v_mfma_f32_32x32x16_bf16 v[80:95], v[234:237], v[176:179], v[80:95]
	v_mfma_f32_32x32x16_bf16 v[16:31], v[234:237], v[180:183], v[16:31]
	ds_read_b128 v[234:237], v192 offset:32
	s_waitcnt lgkmcnt(5)
	v_mfma_f32_32x32x16_bf16 v[64:79], v[238:241], v[176:179], v[64:79]
	v_mfma_f32_32x32x16_bf16 v[0:15], v[238:241], v[180:183], v[0:15]
	ds_read_b128 v[238:241], v192 offset:4640
	s_setprio 0
	global_load_dwordx4 v[176:179], v[194:195], off offset:2688
	global_load_dwordx4 v[180:183], v[196:197], off offset:2688
	s_setprio 1
	s_waitcnt lgkmcnt(1)
	v_mfma_f32_32x32x16_bf16 v[112:127], v[234:237], v[168:171], v[112:127]
	v_mfma_f32_32x32x16_bf16 v[48:63], v[234:237], v[172:175], v[48:63]
	s_waitcnt lgkmcnt(0)
	v_mfma_f32_32x32x16_bf16 v[96:111], v[238:241], v[168:171], v[96:111]
	v_mfma_f32_32x32x16_bf16 v[32:47], v[238:241], v[172:175], v[32:47]
	ds_read_b128 v[234:237], v192 offset:9248
	ds_read_b128 v[238:241], v192 offset:13856
	s_waitcnt vmcnt(7)
	ds_write_b128 v215, v[160:163] offset:18432
	s_waitcnt vmcnt(6)
	ds_write_b128 v215, v[164:167] offset:55296
	ds_read_b128 v[160:163], v208 offset:64
	ds_read_b128 v[164:167], v208 offset:4672
	s_waitcnt lgkmcnt(5)
	v_mfma_f32_32x32x16_bf16 v[80:95], v[234:237], v[168:171], v[80:95]
	v_mfma_f32_32x32x16_bf16 v[16:31], v[234:237], v[172:175], v[16:31]
	ds_read_b128 v[234:237], v192 offset:64
	s_waitcnt lgkmcnt(5)
	v_mfma_f32_32x32x16_bf16 v[64:79], v[238:241], v[168:171], v[64:79]
	v_mfma_f32_32x32x16_bf16 v[0:15], v[238:241], v[172:175], v[0:15]
	ds_read_b128 v[238:241], v192 offset:4672
	s_setprio 0
	global_load_dwordx4 v[168:171], v[184:185], off offset:2688
	global_load_dwordx4 v[172:175], v[186:187], off offset:2688
	s_setprio 1
	s_waitcnt lgkmcnt(1)
	v_mfma_f32_32x32x16_bf16 v[112:127], v[234:237], v[160:163], v[112:127]
	v_mfma_f32_32x32x16_bf16 v[48:63], v[234:237], v[164:167], v[48:63]
	s_waitcnt lgkmcnt(0)
	v_mfma_f32_32x32x16_bf16 v[96:111], v[238:241], v[160:163], v[96:111]
	v_mfma_f32_32x32x16_bf16 v[32:47], v[238:241], v[164:167], v[32:47]
	ds_read_b128 v[234:237], v192 offset:9280
	ds_read_b128 v[238:241], v192 offset:13888
	s_waitcnt vmcnt(7)
	ds_write_b128 v215, v[218:221] offset:27648
	s_waitcnt vmcnt(6)
	ds_write_b128 v215, v[222:225] offset:64512
	ds_read_b128 v[218:221], v208 offset:96
	ds_read_b128 v[222:225], v208 offset:4704
	s_waitcnt lgkmcnt(5)
	v_mfma_f32_32x32x16_bf16 v[80:95], v[234:237], v[160:163], v[80:95]
	v_mfma_f32_32x32x16_bf16 v[16:31], v[234:237], v[164:167], v[16:31]
	ds_read_b128 v[234:237], v192 offset:96
	s_waitcnt lgkmcnt(5)
	v_mfma_f32_32x32x16_bf16 v[64:79], v[238:241], v[160:163], v[64:79]
	v_mfma_f32_32x32x16_bf16 v[0:15], v[238:241], v[164:167], v[0:15]
	ds_read_b128 v[238:241], v192 offset:4704
	s_setprio 0
	global_load_dwordx4 v[160:163], v[198:199], off offset:2688
	global_load_dwordx4 v[164:167], v[200:201], off offset:2688
	s_setprio 1
	s_waitcnt lgkmcnt(1)
	v_mfma_f32_32x32x16_bf16 v[112:127], v[234:237], v[218:221], v[112:127]
	v_mfma_f32_32x32x16_bf16 v[48:63], v[234:237], v[222:225], v[48:63]
	s_waitcnt lgkmcnt(0)
	v_mfma_f32_32x32x16_bf16 v[96:111], v[238:241], v[218:221], v[96:111]
	v_mfma_f32_32x32x16_bf16 v[32:47], v[238:241], v[222:225], v[32:47]
	ds_read_b128 v[234:237], v192 offset:9312
	ds_read_b128 v[238:241], v192 offset:13920
	s_waitcnt lgkmcnt(1)
	v_mfma_f32_32x32x16_bf16 v[80:95], v[234:237], v[218:221], v[80:95]
	v_mfma_f32_32x32x16_bf16 v[16:31], v[234:237], v[222:225], v[16:31]
	s_waitcnt lgkmcnt(0)
	v_mfma_f32_32x32x16_bf16 v[64:79], v[238:241], v[218:221], v[64:79]
	v_mfma_f32_32x32x16_bf16 v[0:15], v[238:241], v[222:225], v[0:15]
	s_setprio 0
	global_load_dwordx4 v[218:221], v[190:191], off offset:2816
	global_load_dwordx4 v[222:225], v[188:189], off offset:2816
	s_barrier
; template <bool trans>
; DI void gemm_core(const GTile& tl, const GTile& nx, bool has_next  , bool chain  , bool pre, u32x4 (&ra)[4], u32x4 (&rb)[4], char* smem, f32x16 (&acc)[2][4]) {
;     ...
;   const int nk = K / 64;
;   if (!pre) { G_LOAD(0); G_STORE(0); G_LOAD(1); }
;   for (int kt = 0; kt < nk; ++kt) {
;     __syncthreads();
;     G_COMPUTE(kt & 1, kt);
;   }
	s_waitcnt vmcnt(9)
	ds_write_b128 v209, v[226:229]
	s_waitcnt vmcnt(8)
	ds_write_b128 v210, v[230:233]
	ds_read_b128 v[226:229], v205 offset:36864
	ds_read_b128 v[230:233], v205 offset:41472
	ds_read_b128 v[234:237], v204
	ds_read_b128 v[238:241], v204 offset:4608
	s_setprio 1
	s_waitcnt lgkmcnt(1)
	v_mfma_f32_32x32x16_bf16 v[112:127], v[234:237], v[226:229], v[112:127]
	v_mfma_f32_32x32x16_bf16 v[48:63], v[234:237], v[230:233], v[48:63]
	s_waitcnt lgkmcnt(0)
	v_mfma_f32_32x32x16_bf16 v[96:111], v[238:241], v[226:229], v[96:111]
	v_mfma_f32_32x32x16_bf16 v[32:47], v[238:241], v[230:233], v[32:47]
	ds_read_b128 v[234:237], v204 offset:9216
	ds_read_b128 v[238:241], v204 offset:13824
	s_waitcnt vmcnt(7)
	ds_write_b128 v212, v[176:179]
	s_waitcnt vmcnt(6)
	ds_write_b128 v211, v[180:183]
	ds_read_b128 v[176:179], v205 offset:36896
	ds_read_b128 v[180:183], v205 offset:41504
	s_waitcnt lgkmcnt(5)
	v_mfma_f32_32x32x16_bf16 v[80:95], v[234:237], v[226:229], v[80:95]
	v_mfma_f32_32x32x16_bf16 v[16:31], v[234:237], v[230:233], v[16:31]
	ds_read_b128 v[234:237], v204 offset:32
	s_waitcnt lgkmcnt(5)
	v_mfma_f32_32x32x16_bf16 v[64:79], v[238:241], v[226:229], v[64:79]
	v_mfma_f32_32x32x16_bf16 v[0:15], v[238:241], v[230:233], v[0:15]
	ds_read_b128 v[238:241], v204 offset:4640
	s_setprio 0
	global_load_dwordx4 v[226:229], v[194:195], off offset:2816
	global_load_dwordx4 v[230:233], v[196:197], off offset:2816
	s_setprio 1
	s_waitcnt lgkmcnt(1)
	v_mfma_f32_32x32x16_bf16 v[112:127], v[234:237], v[176:179], v[112:127]
	v_mfma_f32_32x32x16_bf16 v[48:63], v[234:237], v[180:183], v[48:63]
	s_waitcnt lgkmcnt(0)
	v_mfma_f32_32x32x16_bf16 v[96:111], v[238:241], v[176:179], v[96:111]
	v_mfma_f32_32x32x16_bf16 v[32:47], v[238:241], v[180:183], v[32:47]
	ds_read_b128 v[234:237], v204 offset:9248
	ds_read_b128 v[238:241], v204 offset:13856
	s_waitcnt vmcnt(7)
	ds_write_b128 v214, v[168:171]
	s_waitcnt vmcnt(6)
	ds_write_b128 v213, v[172:175]
	ds_read_b128 v[168:171], v205 offset:36928
	ds_read_b128 v[172:175], v205 offset:41536
	s_waitcnt lgkmcnt(5)
	v_mfma_f32_32x32x16_bf16 v[80:95], v[234:237], v[176:179], v[80:95]
	v_mfma_f32_32x32x16_bf16 v[16:31], v[234:237], v[180:183], v[16:31]
	ds_read_b128 v[234:237], v204 offset:64
	s_waitcnt lgkmcnt(5)
	v_mfma_f32_32x32x16_bf16 v[64:79], v[238:241], v[176:179], v[64:79]
	v_mfma_f32_32x32x16_bf16 v[0:15], v[238:241], v[180:183], v[0:15]
	ds_read_b128 v[238:241], v204 offset:4672
	s_setprio 0
	global_load_dwordx4 v[176:179], v[184:185], off offset:2816
	global_load_dwordx4 v[180:183], v[186:187], off offset:2816
	s_setprio 1
	s_waitcnt lgkmcnt(1)
	v_mfma_f32_32x32x16_bf16 v[112:127], v[234:237], v[168:171], v[112:127]
	v_mfma_f32_32x32x16_bf16 v[48:63], v[234:237], v[172:175], v[48:63]
	s_waitcnt lgkmcnt(0)
	v_mfma_f32_32x32x16_bf16 v[96:111], v[238:241], v[168:171], v[96:111]
	v_mfma_f32_32x32x16_bf16 v[32:47], v[238:241], v[172:175], v[32:47]
	ds_read_b128 v[234:237], v204 offset:9280
	ds_read_b128 v[238:241], v204 offset:13888
	s_waitcnt vmcnt(7)
	ds_write_b128 v217, v[160:163]
	s_waitcnt vmcnt(6)
	ds_write_b128 v216, v[164:167]
	ds_read_b128 v[160:163], v205 offset:36960
	ds_read_b128 v[164:167], v205 offset:41568
	s_waitcnt lgkmcnt(5)
	v_mfma_f32_32x32x16_bf16 v[80:95], v[234:237], v[168:171], v[80:95]
	v_mfma_f32_32x32x16_bf16 v[16:31], v[234:237], v[172:175], v[16:31]
	ds_read_b128 v[234:237], v204 offset:96
	s_waitcnt lgkmcnt(5)
	v_mfma_f32_32x32x16_bf16 v[64:79], v[238:241], v[168:171], v[64:79]
	v_mfma_f32_32x32x16_bf16 v[0:15], v[238:241], v[172:175], v[0:15]
	ds_read_b128 v[238:241], v204 offset:4704
	s_setprio 0
	global_load_dwordx4 v[168:171], v[198:199], off offset:2816
	global_load_dwordx4 v[172:175], v[200:201], off offset:2816
	s_setprio 1
	s_waitcnt lgkmcnt(1)
	v_mfma_f32_32x32x16_bf16 v[112:127], v[234:237], v[160:163], v[112:127]
	v_mfma_f32_32x32x16_bf16 v[48:63], v[234:237], v[164:167], v[48:63]
	s_waitcnt lgkmcnt(0)
	v_mfma_f32_32x32x16_bf16 v[96:111], v[238:241], v[160:163], v[96:111]
	v_mfma_f32_32x32x16_bf16 v[32:47], v[238:241], v[164:167], v[32:47]
	ds_read_b128 v[234:237], v204 offset:9312
	ds_read_b128 v[238:241], v204 offset:13920
	s_waitcnt lgkmcnt(1)
	v_mfma_f32_32x32x16_bf16 v[80:95], v[234:237], v[160:163], v[80:95]
	v_mfma_f32_32x32x16_bf16 v[16:31], v[234:237], v[164:167], v[16:31]
	s_waitcnt lgkmcnt(0)
	v_mfma_f32_32x32x16_bf16 v[64:79], v[238:241], v[160:163], v[64:79]
	v_mfma_f32_32x32x16_bf16 v[0:15], v[238:241], v[164:167], v[0:15]
	s_setprio 0
	global_load_dwordx4 v[160:163], v[190:191], off offset:2944
	global_load_dwordx4 v[164:167], v[188:189], off offset:2944
	s_barrier
; template <bool trans>
; DI void gemm_core(const GTile& tl, const GTile& nx, bool has_next  , bool chain  , bool pre, u32x4 (&ra)[4], u32x4 (&rb)[4], char* smem, f32x16 (&acc)[2][4]) {
;     ...
;   const int nk = K / 64;
;   if (!pre) { G_LOAD(0); G_STORE(0); G_LOAD(1); }
;   for (int kt = 0; kt < nk; ++kt) {
;     __syncthreads();
;     G_COMPUTE(kt & 1, kt);
;   }
	s_waitcnt vmcnt(9)
	ds_write_b128 v215, v[218:221]
	s_waitcnt vmcnt(8)
	ds_write_b128 v215, v[222:225] offset:36864
	ds_read_b128 v[218:221], v208
	ds_read_b128 v[222:225], v208 offset:4608
	ds_read_b128 v[234:237], v192
	ds_read_b128 v[238:241], v192 offset:4608
	s_setprio 1
	s_waitcnt lgkmcnt(1)
	v_mfma_f32_32x32x16_bf16 v[112:127], v[234:237], v[218:221], v[112:127]
	v_mfma_f32_32x32x16_bf16 v[48:63], v[234:237], v[222:225], v[48:63]
	s_waitcnt lgkmcnt(0)
	v_mfma_f32_32x32x16_bf16 v[96:111], v[238:241], v[218:221], v[96:111]
	v_mfma_f32_32x32x16_bf16 v[32:47], v[238:241], v[222:225], v[32:47]
	ds_read_b128 v[234:237], v192 offset:9216
	ds_read_b128 v[238:241], v192 offset:13824
	s_waitcnt vmcnt(7)
	ds_write_b128 v215, v[226:229] offset:9216
	s_waitcnt vmcnt(6)
	ds_write_b128 v215, v[230:233] offset:46080
	ds_read_b128 v[226:229], v208 offset:32
	ds_read_b128 v[230:233], v208 offset:4640
	s_waitcnt lgkmcnt(5)
	v_mfma_f32_32x32x16_bf16 v[80:95], v[234:237], v[218:221], v[80:95]
	v_mfma_f32_32x32x16_bf16 v[16:31], v[234:237], v[222:225], v[16:31]
	ds_read_b128 v[234:237], v192 offset:32
	s_waitcnt lgkmcnt(5)
	v_mfma_f32_32x32x16_bf16 v[64:79], v[238:241], v[218:221], v[64:79]
	v_mfma_f32_32x32x16_bf16 v[0:15], v[238:241], v[222:225], v[0:15]
	ds_read_b128 v[238:241], v192 offset:4640
	s_setprio 0
	global_load_dwordx4 v[218:221], v[194:195], off offset:2944
	global_load_dwordx4 v[222:225], v[196:197], off offset:2944
	s_setprio 1
	s_waitcnt lgkmcnt(1)
	v_mfma_f32_32x32x16_bf16 v[112:127], v[234:237], v[226:229], v[112:127]
	v_mfma_f32_32x32x16_bf16 v[48:63], v[234:237], v[230:233], v[48:63]
	s_waitcnt lgkmcnt(0)
	v_mfma_f32_32x32x16_bf16 v[96:111], v[238:241], v[226:229], v[96:111]
	v_mfma_f32_32x32x16_bf16 v[32:47], v[238:241], v[230:233], v[32:47]
	ds_read_b128 v[234:237], v192 offset:9248
	ds_read_b128 v[238:241], v192 offset:13856
	s_waitcnt vmcnt(7)
	ds_write_b128 v215, v[176:179] offset:18432
	s_waitcnt vmcnt(6)
	ds_write_b128 v215, v[180:183] offset:55296
	ds_read_b128 v[176:179], v208 offset:64
	ds_read_b128 v[180:183], v208 offset:4672
	s_waitcnt lgkmcnt(5)
	v_mfma_f32_32x32x16_bf16 v[80:95], v[234:237], v[226:229], v[80:95]
	v_mfma_f32_32x32x16_bf16 v[16:31], v[234:237], v[230:233], v[16:31]
	ds_read_b128 v[234:237], v192 offset:64
	s_waitcnt lgkmcnt(5)
	v_mfma_f32_32x32x16_bf16 v[64:79], v[238:241], v[226:229], v[64:79]
	v_mfma_f32_32x32x16_bf16 v[0:15], v[238:241], v[230:233], v[0:15]
	ds_read_b128 v[238:241], v192 offset:4672
	s_setprio 0
	global_load_dwordx4 v[226:229], v[184:185], off offset:2944
	global_load_dwordx4 v[230:233], v[186:187], off offset:2944
	s_setprio 1
	s_waitcnt lgkmcnt(1)
	v_mfma_f32_32x32x16_bf16 v[112:127], v[234:237], v[176:179], v[112:127]
	v_mfma_f32_32x32x16_bf16 v[48:63], v[234:237], v[180:183], v[48:63]
	s_waitcnt lgkmcnt(0)
	v_mfma_f32_32x32x16_bf16 v[96:111], v[238:241], v[176:179], v[96:111]
	v_mfma_f32_32x32x16_bf16 v[32:47], v[238:241], v[180:183], v[32:47]
	ds_read_b128 v[234:237], v192 offset:9280
	ds_read_b128 v[238:241], v192 offset:13888
	s_waitcnt vmcnt(7)
	ds_write_b128 v215, v[168:171] offset:27648
	s_waitcnt vmcnt(6)
	ds_write_b128 v215, v[172:175] offset:64512
	ds_read_b128 v[168:171], v208 offset:96
	ds_read_b128 v[172:175], v208 offset:4704
	s_waitcnt lgkmcnt(5)
	v_mfma_f32_32x32x16_bf16 v[80:95], v[234:237], v[176:179], v[80:95]
	v_mfma_f32_32x32x16_bf16 v[16:31], v[234:237], v[180:183], v[16:31]
	ds_read_b128 v[234:237], v192 offset:96
	s_waitcnt lgkmcnt(5)
	v_mfma_f32_32x32x16_bf16 v[64:79], v[238:241], v[176:179], v[64:79]
	v_mfma_f32_32x32x16_bf16 v[0:15], v[238:241], v[180:183], v[0:15]
	ds_read_b128 v[238:241], v192 offset:4704
	s_setprio 0
	global_load_dwordx4 v[176:179], v[198:199], off offset:2944
	global_load_dwordx4 v[180:183], v[200:201], off offset:2944
	s_setprio 1
	s_waitcnt lgkmcnt(1)
	v_mfma_f32_32x32x16_bf16 v[112:127], v[234:237], v[168:171], v[112:127]
	v_mfma_f32_32x32x16_bf16 v[48:63], v[234:237], v[172:175], v[48:63]
	s_waitcnt lgkmcnt(0)
	v_mfma_f32_32x32x16_bf16 v[96:111], v[238:241], v[168:171], v[96:111]
	v_mfma_f32_32x32x16_bf16 v[32:47], v[238:241], v[172:175], v[32:47]
	ds_read_b128 v[234:237], v192 offset:9312
	ds_read_b128 v[238:241], v192 offset:13920
	s_waitcnt lgkmcnt(1)
	v_mfma_f32_32x32x16_bf16 v[80:95], v[234:237], v[168:171], v[80:95]
	v_mfma_f32_32x32x16_bf16 v[16:31], v[234:237], v[172:175], v[16:31]
	s_waitcnt lgkmcnt(0)
	v_mfma_f32_32x32x16_bf16 v[64:79], v[238:241], v[168:171], v[64:79]
	v_mfma_f32_32x32x16_bf16 v[0:15], v[238:241], v[172:175], v[0:15]
	s_setprio 0
	global_load_dwordx4 v[168:171], v[190:191], off offset:3072
	global_load_dwordx4 v[172:175], v[188:189], off offset:3072
	s_barrier
; template <bool trans>
; DI void gemm_core(const GTile& tl, const GTile& nx, bool has_next  , bool chain  , bool pre, u32x4 (&ra)[4], u32x4 (&rb)[4], char* smem, f32x16 (&acc)[2][4]) {
;     ...
;   const int nk = K / 64;
;   if (!pre) { G_LOAD(0); G_STORE(0); G_LOAD(1); }
;   for (int kt = 0; kt < nk; ++kt) {
;     __syncthreads();
;     G_COMPUTE(kt & 1, kt);
;   }
	s_waitcnt vmcnt(9)
	ds_write_b128 v209, v[160:163]
	s_waitcnt vmcnt(8)
	ds_write_b128 v210, v[164:167]
	ds_read_b128 v[160:163], v205 offset:36864
	ds_read_b128 v[164:167], v205 offset:41472
	ds_read_b128 v[234:237], v204
	ds_read_b128 v[238:241], v204 offset:4608
	s_setprio 1
	s_waitcnt lgkmcnt(1)
	v_mfma_f32_32x32x16_bf16 v[112:127], v[234:237], v[160:163], v[112:127]
	v_mfma_f32_32x32x16_bf16 v[48:63], v[234:237], v[164:167], v[48:63]
	s_waitcnt lgkmcnt(0)
	v_mfma_f32_32x32x16_bf16 v[96:111], v[238:241], v[160:163], v[96:111]
	v_mfma_f32_32x32x16_bf16 v[32:47], v[238:241], v[164:167], v[32:47]
	ds_read_b128 v[234:237], v204 offset:9216
	ds_read_b128 v[238:241], v204 offset:13824
	s_waitcnt vmcnt(7)
	ds_write_b128 v212, v[218:221]
	s_waitcnt vmcnt(6)
	ds_write_b128 v211, v[222:225]
	ds_read_b128 v[218:221], v205 offset:36896
	ds_read_b128 v[222:225], v205 offset:41504
	s_waitcnt lgkmcnt(5)
	v_mfma_f32_32x32x16_bf16 v[80:95], v[234:237], v[160:163], v[80:95]
	v_mfma_f32_32x32x16_bf16 v[16:31], v[234:237], v[164:167], v[16:31]
	ds_read_b128 v[234:237], v204 offset:32
	s_waitcnt lgkmcnt(5)
	v_mfma_f32_32x32x16_bf16 v[64:79], v[238:241], v[160:163], v[64:79]
	v_mfma_f32_32x32x16_bf16 v[0:15], v[238:241], v[164:167], v[0:15]
	ds_read_b128 v[238:241], v204 offset:4640
	s_setprio 0
	global_load_dwordx4 v[160:163], v[194:195], off offset:3072
	global_load_dwordx4 v[164:167], v[196:197], off offset:3072
	s_setprio 1
	s_waitcnt lgkmcnt(1)
	v_mfma_f32_32x32x16_bf16 v[112:127], v[234:237], v[218:221], v[112:127]
	v_mfma_f32_32x32x16_bf16 v[48:63], v[234:237], v[222:225], v[48:63]
	s_waitcnt lgkmcnt(0)
	v_mfma_f32_32x32x16_bf16 v[96:111], v[238:241], v[218:221], v[96:111]
	v_mfma_f32_32x32x16_bf16 v[32:47], v[238:241], v[222:225], v[32:47]
	ds_read_b128 v[234:237], v204 offset:9248
	ds_read_b128 v[238:241], v204 offset:13856
	s_waitcnt vmcnt(7)
	ds_write_b128 v214, v[226:229]
	s_waitcnt vmcnt(6)
	ds_write_b128 v213, v[230:233]
	ds_read_b128 v[226:229], v205 offset:36928
	ds_read_b128 v[230:233], v205 offset:41536
	s_waitcnt lgkmcnt(5)
	v_mfma_f32_32x32x16_bf16 v[80:95], v[234:237], v[218:221], v[80:95]
	v_mfma_f32_32x32x16_bf16 v[16:31], v[234:237], v[222:225], v[16:31]
	ds_read_b128 v[234:237], v204 offset:64
	s_waitcnt lgkmcnt(5)
	v_mfma_f32_32x32x16_bf16 v[64:79], v[238:241], v[218:221], v[64:79]
	v_mfma_f32_32x32x16_bf16 v[0:15], v[238:241], v[222:225], v[0:15]
	ds_read_b128 v[238:241], v204 offset:4672
	s_setprio 0
	global_load_dwordx4 v[218:221], v[184:185], off offset:3072
	global_load_dwordx4 v[222:225], v[186:187], off offset:3072
	s_setprio 1
	s_waitcnt lgkmcnt(1)
	v_mfma_f32_32x32x16_bf16 v[112:127], v[234:237], v[226:229], v[112:127]
	v_mfma_f32_32x32x16_bf16 v[48:63], v[234:237], v[230:233], v[48:63]
	s_waitcnt lgkmcnt(0)
	v_mfma_f32_32x32x16_bf16 v[96:111], v[238:241], v[226:229], v[96:111]
	v_mfma_f32_32x32x16_bf16 v[32:47], v[238:241], v[230:233], v[32:47]
	ds_read_b128 v[234:237], v204 offset:9280
	ds_read_b128 v[238:241], v204 offset:13888
	s_waitcnt vmcnt(7)
	ds_write_b128 v217, v[176:179]
	s_waitcnt vmcnt(6)
	ds_write_b128 v216, v[180:183]
	ds_read_b128 v[176:179], v205 offset:36960
	ds_read_b128 v[180:183], v205 offset:41568
	s_waitcnt lgkmcnt(5)
	v_mfma_f32_32x32x16_bf16 v[80:95], v[234:237], v[226:229], v[80:95]
	v_mfma_f32_32x32x16_bf16 v[16:31], v[234:237], v[230:233], v[16:31]
	ds_read_b128 v[234:237], v204 offset:96
	s_waitcnt lgkmcnt(5)
	v_mfma_f32_32x32x16_bf16 v[64:79], v[238:241], v[226:229], v[64:79]
	v_mfma_f32_32x32x16_bf16 v[0:15], v[238:241], v[230:233], v[0:15]
	ds_read_b128 v[238:241], v204 offset:4704
	s_setprio 0
	global_load_dwordx4 v[226:229], v[198:199], off offset:3072
	global_load_dwordx4 v[230:233], v[200:201], off offset:3072
	s_setprio 1
	s_waitcnt lgkmcnt(1)
	v_mfma_f32_32x32x16_bf16 v[112:127], v[234:237], v[176:179], v[112:127]
	v_mfma_f32_32x32x16_bf16 v[48:63], v[234:237], v[180:183], v[48:63]
	s_waitcnt lgkmcnt(0)
	v_mfma_f32_32x32x16_bf16 v[96:111], v[238:241], v[176:179], v[96:111]
	v_mfma_f32_32x32x16_bf16 v[32:47], v[238:241], v[180:183], v[32:47]
	ds_read_b128 v[234:237], v204 offset:9312
	ds_read_b128 v[238:241], v204 offset:13920
	s_waitcnt lgkmcnt(1)
	v_mfma_f32_32x32x16_bf16 v[80:95], v[234:237], v[176:179], v[80:95]
	v_mfma_f32_32x32x16_bf16 v[16:31], v[234:237], v[180:183], v[16:31]
	s_waitcnt lgkmcnt(0)
	v_mfma_f32_32x32x16_bf16 v[64:79], v[238:241], v[176:179], v[64:79]
	v_mfma_f32_32x32x16_bf16 v[0:15], v[238:241], v[180:183], v[0:15]
	s_setprio 0
	global_load_dwordx4 v[176:179], v[190:191], off offset:3200
	global_load_dwordx4 v[180:183], v[188:189], off offset:3200
	s_barrier
; template <bool trans>
; DI void gemm_core(const GTile& tl, const GTile& nx, bool has_next  , bool chain  , bool pre, u32x4 (&ra)[4], u32x4 (&rb)[4], char* smem, f32x16 (&acc)[2][4]) {
;     ...
;   const int nk = K / 64;
;   if (!pre) { G_LOAD(0); G_STORE(0); G_LOAD(1); }
;   for (int kt = 0; kt < nk; ++kt) {
;     __syncthreads();
;     G_COMPUTE(kt & 1, kt);
;   }
	s_waitcnt vmcnt(9)
	ds_write_b128 v215, v[168:171]
	s_waitcnt vmcnt(8)
	ds_write_b128 v215, v[172:175] offset:36864
	ds_read_b128 v[168:171], v208
	ds_read_b128 v[172:175], v208 offset:4608
	ds_read_b128 v[234:237], v192
	ds_read_b128 v[238:241], v192 offset:4608
	s_setprio 1
	s_waitcnt lgkmcnt(1)
	v_mfma_f32_32x32x16_bf16 v[112:127], v[234:237], v[168:171], v[112:127]
	v_mfma_f32_32x32x16_bf16 v[48:63], v[234:237], v[172:175], v[48:63]
	s_waitcnt lgkmcnt(0)
	v_mfma_f32_32x32x16_bf16 v[96:111], v[238:241], v[168:171], v[96:111]
	v_mfma_f32_32x32x16_bf16 v[32:47], v[238:241], v[172:175], v[32:47]
	ds_read_b128 v[234:237], v192 offset:9216
	ds_read_b128 v[238:241], v192 offset:13824
	s_waitcnt vmcnt(7)
	ds_write_b128 v215, v[160:163] offset:9216
	s_waitcnt vmcnt(6)
	ds_write_b128 v215, v[164:167] offset:46080
	ds_read_b128 v[160:163], v208 offset:32
	ds_read_b128 v[164:167], v208 offset:4640
	s_waitcnt lgkmcnt(5)
	v_mfma_f32_32x32x16_bf16 v[80:95], v[234:237], v[168:171], v[80:95]
	v_mfma_f32_32x32x16_bf16 v[16:31], v[234:237], v[172:175], v[16:31]
	ds_read_b128 v[234:237], v192 offset:32
	s_waitcnt lgkmcnt(5)
	v_mfma_f32_32x32x16_bf16 v[64:79], v[238:241], v[168:171], v[64:79]
	v_mfma_f32_32x32x16_bf16 v[0:15], v[238:241], v[172:175], v[0:15]
	ds_read_b128 v[238:241], v192 offset:4640
	s_setprio 0
	global_load_dwordx4 v[168:171], v[194:195], off offset:3200
	global_load_dwordx4 v[172:175], v[196:197], off offset:3200
	s_setprio 1
	s_waitcnt lgkmcnt(1)
	v_mfma_f32_32x32x16_bf16 v[112:127], v[234:237], v[160:163], v[112:127]
	v_mfma_f32_32x32x16_bf16 v[48:63], v[234:237], v[164:167], v[48:63]
	s_waitcnt lgkmcnt(0)
	v_mfma_f32_32x32x16_bf16 v[96:111], v[238:241], v[160:163], v[96:111]
	v_mfma_f32_32x32x16_bf16 v[32:47], v[238:241], v[164:167], v[32:47]
	ds_read_b128 v[234:237], v192 offset:9248
	ds_read_b128 v[238:241], v192 offset:13856
	s_waitcnt vmcnt(7)
	ds_write_b128 v215, v[218:221] offset:18432
	s_waitcnt vmcnt(6)
	ds_write_b128 v215, v[222:225] offset:55296
	ds_read_b128 v[218:221], v208 offset:64
	ds_read_b128 v[222:225], v208 offset:4672
	s_waitcnt lgkmcnt(5)
	v_mfma_f32_32x32x16_bf16 v[80:95], v[234:237], v[160:163], v[80:95]
	v_mfma_f32_32x32x16_bf16 v[16:31], v[234:237], v[164:167], v[16:31]
	ds_read_b128 v[234:237], v192 offset:64
	s_waitcnt lgkmcnt(5)
	v_mfma_f32_32x32x16_bf16 v[64:79], v[238:241], v[160:163], v[64:79]
	v_mfma_f32_32x32x16_bf16 v[0:15], v[238:241], v[164:167], v[0:15]
	ds_read_b128 v[238:241], v192 offset:4672
	s_setprio 0
	global_load_dwordx4 v[160:163], v[184:185], off offset:3200
	global_load_dwordx4 v[164:167], v[186:187], off offset:3200
	s_setprio 1
	s_waitcnt lgkmcnt(1)
	v_mfma_f32_32x32x16_bf16 v[112:127], v[234:237], v[218:221], v[112:127]
	v_mfma_f32_32x32x16_bf16 v[48:63], v[234:237], v[222:225], v[48:63]
	s_waitcnt lgkmcnt(0)
	v_mfma_f32_32x32x16_bf16 v[96:111], v[238:241], v[218:221], v[96:111]
	v_mfma_f32_32x32x16_bf16 v[32:47], v[238:241], v[222:225], v[32:47]
	ds_read_b128 v[234:237], v192 offset:9280
	ds_read_b128 v[238:241], v192 offset:13888
	s_waitcnt vmcnt(7)
	ds_write_b128 v215, v[226:229] offset:27648
	s_waitcnt vmcnt(6)
	ds_write_b128 v215, v[230:233] offset:64512
	ds_read_b128 v[226:229], v208 offset:96
	ds_read_b128 v[230:233], v208 offset:4704
	s_waitcnt lgkmcnt(5)
	v_mfma_f32_32x32x16_bf16 v[80:95], v[234:237], v[218:221], v[80:95]
	v_mfma_f32_32x32x16_bf16 v[16:31], v[234:237], v[222:225], v[16:31]
	ds_read_b128 v[234:237], v192 offset:96
	s_waitcnt lgkmcnt(5)
	v_mfma_f32_32x32x16_bf16 v[64:79], v[238:241], v[218:221], v[64:79]
	v_mfma_f32_32x32x16_bf16 v[0:15], v[238:241], v[222:225], v[0:15]
	ds_read_b128 v[238:241], v192 offset:4704
	s_setprio 0
	global_load_dwordx4 v[218:221], v[198:199], off offset:3200
	global_load_dwordx4 v[222:225], v[200:201], off offset:3200
	s_setprio 1
	s_waitcnt lgkmcnt(1)
	v_mfma_f32_32x32x16_bf16 v[112:127], v[234:237], v[226:229], v[112:127]
	v_mfma_f32_32x32x16_bf16 v[48:63], v[234:237], v[230:233], v[48:63]
	s_waitcnt lgkmcnt(0)
	v_mfma_f32_32x32x16_bf16 v[96:111], v[238:241], v[226:229], v[96:111]
	v_mfma_f32_32x32x16_bf16 v[32:47], v[238:241], v[230:233], v[32:47]
	ds_read_b128 v[234:237], v192 offset:9312
	ds_read_b128 v[238:241], v192 offset:13920
	s_waitcnt lgkmcnt(1)
	v_mfma_f32_32x32x16_bf16 v[80:95], v[234:237], v[226:229], v[80:95]
	v_mfma_f32_32x32x16_bf16 v[16:31], v[234:237], v[230:233], v[16:31]
	s_waitcnt lgkmcnt(0)
	v_mfma_f32_32x32x16_bf16 v[64:79], v[238:241], v[226:229], v[64:79]
	v_mfma_f32_32x32x16_bf16 v[0:15], v[238:241], v[230:233], v[0:15]
	s_setprio 0
	global_load_dwordx4 v[226:229], v[190:191], off offset:3328
	global_load_dwordx4 v[230:233], v[188:189], off offset:3328
	s_barrier
; template <bool trans>
; DI void gemm_core(const GTile& tl, const GTile& nx, bool has_next  , bool chain  , bool pre, u32x4 (&ra)[4], u32x4 (&rb)[4], char* smem, f32x16 (&acc)[2][4]) {
;     ...
;   const int nk = K / 64;
;   if (!pre) { G_LOAD(0); G_STORE(0); G_LOAD(1); }
;   for (int kt = 0; kt < nk; ++kt) {
;     __syncthreads();
;     G_COMPUTE(kt & 1, kt);
;   }
	s_waitcnt vmcnt(9)
	ds_write_b128 v209, v[176:179]
	s_waitcnt vmcnt(8)
	ds_write_b128 v210, v[180:183]
	ds_read_b128 v[176:179], v205 offset:36864
	ds_read_b128 v[180:183], v205 offset:41472
	ds_read_b128 v[234:237], v204
	ds_read_b128 v[238:241], v204 offset:4608
	s_setprio 1
	s_waitcnt lgkmcnt(1)
	v_mfma_f32_32x32x16_bf16 v[112:127], v[234:237], v[176:179], v[112:127]
	v_mfma_f32_32x32x16_bf16 v[48:63], v[234:237], v[180:183], v[48:63]
	s_waitcnt lgkmcnt(0)
	v_mfma_f32_32x32x16_bf16 v[96:111], v[238:241], v[176:179], v[96:111]
	v_mfma_f32_32x32x16_bf16 v[32:47], v[238:241], v[180:183], v[32:47]
	ds_read_b128 v[234:237], v204 offset:9216
	ds_read_b128 v[238:241], v204 offset:13824
	s_waitcnt vmcnt(7)
	ds_write_b128 v212, v[168:171]
	s_waitcnt vmcnt(6)
	ds_write_b128 v211, v[172:175]
	ds_read_b128 v[168:171], v205 offset:36896
	ds_read_b128 v[172:175], v205 offset:41504
	s_waitcnt lgkmcnt(5)
	v_mfma_f32_32x32x16_bf16 v[80:95], v[234:237], v[176:179], v[80:95]
	v_mfma_f32_32x32x16_bf16 v[16:31], v[234:237], v[180:183], v[16:31]
	ds_read_b128 v[234:237], v204 offset:32
	s_waitcnt lgkmcnt(5)
	v_mfma_f32_32x32x16_bf16 v[64:79], v[238:241], v[176:179], v[64:79]
	v_mfma_f32_32x32x16_bf16 v[0:15], v[238:241], v[180:183], v[0:15]
	ds_read_b128 v[238:241], v204 offset:4640
	s_setprio 0
	global_load_dwordx4 v[176:179], v[194:195], off offset:3328
	global_load_dwordx4 v[180:183], v[196:197], off offset:3328
	s_setprio 1
	s_waitcnt lgkmcnt(1)
	v_mfma_f32_32x32x16_bf16 v[112:127], v[234:237], v[168:171], v[112:127]
	v_mfma_f32_32x32x16_bf16 v[48:63], v[234:237], v[172:175], v[48:63]
	s_waitcnt lgkmcnt(0)
	v_mfma_f32_32x32x16_bf16 v[96:111], v[238:241], v[168:171], v[96:111]
	v_mfma_f32_32x32x16_bf16 v[32:47], v[238:241], v[172:175], v[32:47]
	ds_read_b128 v[234:237], v204 offset:9248
	ds_read_b128 v[238:241], v204 offset:13856
	s_waitcnt vmcnt(7)
	ds_write_b128 v214, v[160:163]
	s_waitcnt vmcnt(6)
	ds_write_b128 v213, v[164:167]
	ds_read_b128 v[160:163], v205 offset:36928
	ds_read_b128 v[164:167], v205 offset:41536
	s_waitcnt lgkmcnt(5)
	v_mfma_f32_32x32x16_bf16 v[80:95], v[234:237], v[168:171], v[80:95]
	v_mfma_f32_32x32x16_bf16 v[16:31], v[234:237], v[172:175], v[16:31]
	ds_read_b128 v[234:237], v204 offset:64
	s_waitcnt lgkmcnt(5)
	v_mfma_f32_32x32x16_bf16 v[64:79], v[238:241], v[168:171], v[64:79]
	v_mfma_f32_32x32x16_bf16 v[0:15], v[238:241], v[172:175], v[0:15]
	ds_read_b128 v[238:241], v204 offset:4672
	s_setprio 0
	global_load_dwordx4 v[168:171], v[184:185], off offset:3328
	global_load_dwordx4 v[172:175], v[186:187], off offset:3328
	s_setprio 1
	s_waitcnt lgkmcnt(1)
	v_mfma_f32_32x32x16_bf16 v[112:127], v[234:237], v[160:163], v[112:127]
	v_mfma_f32_32x32x16_bf16 v[48:63], v[234:237], v[164:167], v[48:63]
	s_waitcnt lgkmcnt(0)
	v_mfma_f32_32x32x16_bf16 v[96:111], v[238:241], v[160:163], v[96:111]
	v_mfma_f32_32x32x16_bf16 v[32:47], v[238:241], v[164:167], v[32:47]
	ds_read_b128 v[234:237], v204 offset:9280
	ds_read_b128 v[238:241], v204 offset:13888
	s_waitcnt vmcnt(7)
	ds_write_b128 v217, v[218:221]
	s_waitcnt vmcnt(6)
	ds_write_b128 v216, v[222:225]
	ds_read_b128 v[218:221], v205 offset:36960
	ds_read_b128 v[222:225], v205 offset:41568
	s_waitcnt lgkmcnt(5)
	v_mfma_f32_32x32x16_bf16 v[80:95], v[234:237], v[160:163], v[80:95]
	v_mfma_f32_32x32x16_bf16 v[16:31], v[234:237], v[164:167], v[16:31]
	ds_read_b128 v[234:237], v204 offset:96
	s_waitcnt lgkmcnt(5)
	v_mfma_f32_32x32x16_bf16 v[64:79], v[238:241], v[160:163], v[64:79]
	v_mfma_f32_32x32x16_bf16 v[0:15], v[238:241], v[164:167], v[0:15]
	ds_read_b128 v[238:241], v204 offset:4704
	s_setprio 0
	global_load_dwordx4 v[160:163], v[198:199], off offset:3328
	global_load_dwordx4 v[164:167], v[200:201], off offset:3328
	s_setprio 1
	s_waitcnt lgkmcnt(1)
	v_mfma_f32_32x32x16_bf16 v[112:127], v[234:237], v[218:221], v[112:127]
	v_mfma_f32_32x32x16_bf16 v[48:63], v[234:237], v[222:225], v[48:63]
	s_waitcnt lgkmcnt(0)
	v_mfma_f32_32x32x16_bf16 v[96:111], v[238:241], v[218:221], v[96:111]
	v_mfma_f32_32x32x16_bf16 v[32:47], v[238:241], v[222:225], v[32:47]
	ds_read_b128 v[234:237], v204 offset:9312
	ds_read_b128 v[238:241], v204 offset:13920
	s_waitcnt lgkmcnt(1)
	v_mfma_f32_32x32x16_bf16 v[80:95], v[234:237], v[218:221], v[80:95]
	v_mfma_f32_32x32x16_bf16 v[16:31], v[234:237], v[222:225], v[16:31]
	s_waitcnt lgkmcnt(0)
	v_mfma_f32_32x32x16_bf16 v[64:79], v[238:241], v[218:221], v[64:79]
	v_mfma_f32_32x32x16_bf16 v[0:15], v[238:241], v[222:225], v[0:15]
	s_setprio 0
	global_load_dwordx4 v[218:221], v[190:191], off offset:3456
	global_load_dwordx4 v[222:225], v[188:189], off offset:3456
	s_barrier
; template <bool trans>
; DI void gemm_core(const GTile& tl, const GTile& nx, bool has_next  , bool chain  , bool pre, u32x4 (&ra)[4], u32x4 (&rb)[4], char* smem, f32x16 (&acc)[2][4]) {
;     ...
;   const int nk = K / 64;
;   if (!pre) { G_LOAD(0); G_STORE(0); G_LOAD(1); }
;   for (int kt = 0; kt < nk; ++kt) {
;     __syncthreads();
;     G_COMPUTE(kt & 1, kt);
;   }
	s_waitcnt vmcnt(9)
	ds_write_b128 v215, v[226:229]
	s_waitcnt vmcnt(8)
	ds_write_b128 v215, v[230:233] offset:36864
	ds_read_b128 v[226:229], v208
	ds_read_b128 v[230:233], v208 offset:4608
	ds_read_b128 v[234:237], v192
	ds_read_b128 v[238:241], v192 offset:4608
	s_setprio 1
	s_waitcnt lgkmcnt(1)
	v_mfma_f32_32x32x16_bf16 v[112:127], v[234:237], v[226:229], v[112:127]
	v_mfma_f32_32x32x16_bf16 v[48:63], v[234:237], v[230:233], v[48:63]
	s_waitcnt lgkmcnt(0)
	v_mfma_f32_32x32x16_bf16 v[96:111], v[238:241], v[226:229], v[96:111]
	v_mfma_f32_32x32x16_bf16 v[32:47], v[238:241], v[230:233], v[32:47]
	ds_read_b128 v[234:237], v192 offset:9216
	ds_read_b128 v[238:241], v192 offset:13824
	s_waitcnt vmcnt(7)
	ds_write_b128 v215, v[176:179] offset:9216
	s_waitcnt vmcnt(6)
	ds_write_b128 v215, v[180:183] offset:46080
	ds_read_b128 v[176:179], v208 offset:32
	ds_read_b128 v[180:183], v208 offset:4640
	s_waitcnt lgkmcnt(5)
	v_mfma_f32_32x32x16_bf16 v[80:95], v[234:237], v[226:229], v[80:95]
	v_mfma_f32_32x32x16_bf16 v[16:31], v[234:237], v[230:233], v[16:31]
	ds_read_b128 v[234:237], v192 offset:32
	s_waitcnt lgkmcnt(5)
	v_mfma_f32_32x32x16_bf16 v[64:79], v[238:241], v[226:229], v[64:79]
	v_mfma_f32_32x32x16_bf16 v[0:15], v[238:241], v[230:233], v[0:15]
	ds_read_b128 v[238:241], v192 offset:4640
	s_setprio 0
	global_load_dwordx4 v[226:229], v[194:195], off offset:3456
	global_load_dwordx4 v[230:233], v[196:197], off offset:3456
	s_setprio 1
	s_waitcnt lgkmcnt(1)
	v_mfma_f32_32x32x16_bf16 v[112:127], v[234:237], v[176:179], v[112:127]
	v_mfma_f32_32x32x16_bf16 v[48:63], v[234:237], v[180:183], v[48:63]
	s_waitcnt lgkmcnt(0)
	v_mfma_f32_32x32x16_bf16 v[96:111], v[238:241], v[176:179], v[96:111]
	v_mfma_f32_32x32x16_bf16 v[32:47], v[238:241], v[180:183], v[32:47]
	ds_read_b128 v[234:237], v192 offset:9248
	ds_read_b128 v[238:241], v192 offset:13856
	s_waitcnt vmcnt(7)
	ds_write_b128 v215, v[168:171] offset:18432
	s_waitcnt vmcnt(6)
	ds_write_b128 v215, v[172:175] offset:55296
	ds_read_b128 v[168:171], v208 offset:64
	ds_read_b128 v[172:175], v208 offset:4672
	s_waitcnt lgkmcnt(5)
	v_mfma_f32_32x32x16_bf16 v[80:95], v[234:237], v[176:179], v[80:95]
	v_mfma_f32_32x32x16_bf16 v[16:31], v[234:237], v[180:183], v[16:31]
	ds_read_b128 v[234:237], v192 offset:64
	s_waitcnt lgkmcnt(5)
	v_mfma_f32_32x32x16_bf16 v[64:79], v[238:241], v[176:179], v[64:79]
	v_mfma_f32_32x32x16_bf16 v[0:15], v[238:241], v[180:183], v[0:15]
	ds_read_b128 v[238:241], v192 offset:4672
	s_setprio 0
	global_load_dwordx4 v[176:179], v[184:185], off offset:3456
	global_load_dwordx4 v[180:183], v[186:187], off offset:3456
	s_setprio 1
	s_waitcnt lgkmcnt(1)
	v_mfma_f32_32x32x16_bf16 v[112:127], v[234:237], v[168:171], v[112:127]
	v_mfma_f32_32x32x16_bf16 v[48:63], v[234:237], v[172:175], v[48:63]
	s_waitcnt lgkmcnt(0)
	v_mfma_f32_32x32x16_bf16 v[96:111], v[238:241], v[168:171], v[96:111]
	v_mfma_f32_32x32x16_bf16 v[32:47], v[238:241], v[172:175], v[32:47]
	ds_read_b128 v[234:237], v192 offset:9280
	ds_read_b128 v[238:241], v192 offset:13888
	s_waitcnt vmcnt(7)
	ds_write_b128 v215, v[160:163] offset:27648
	s_waitcnt vmcnt(6)
	ds_write_b128 v215, v[164:167] offset:64512
	ds_read_b128 v[160:163], v208 offset:96
	ds_read_b128 v[164:167], v208 offset:4704
	s_waitcnt lgkmcnt(5)
	v_mfma_f32_32x32x16_bf16 v[80:95], v[234:237], v[168:171], v[80:95]
	v_mfma_f32_32x32x16_bf16 v[16:31], v[234:237], v[172:175], v[16:31]
	ds_read_b128 v[234:237], v192 offset:96
	s_waitcnt lgkmcnt(5)
	v_mfma_f32_32x32x16_bf16 v[64:79], v[238:241], v[168:171], v[64:79]
	v_mfma_f32_32x32x16_bf16 v[0:15], v[238:241], v[172:175], v[0:15]
	ds_read_b128 v[238:241], v192 offset:4704
	s_setprio 0
	global_load_dwordx4 v[168:171], v[198:199], off offset:3456
	global_load_dwordx4 v[172:175], v[200:201], off offset:3456
	s_setprio 1
	s_waitcnt lgkmcnt(1)
	v_mfma_f32_32x32x16_bf16 v[112:127], v[234:237], v[160:163], v[112:127]
	v_mfma_f32_32x32x16_bf16 v[48:63], v[234:237], v[164:167], v[48:63]
	s_waitcnt lgkmcnt(0)
	v_mfma_f32_32x32x16_bf16 v[96:111], v[238:241], v[160:163], v[96:111]
	v_mfma_f32_32x32x16_bf16 v[32:47], v[238:241], v[164:167], v[32:47]
	ds_read_b128 v[234:237], v192 offset:9312
	ds_read_b128 v[238:241], v192 offset:13920
	s_waitcnt lgkmcnt(1)
	v_mfma_f32_32x32x16_bf16 v[80:95], v[234:237], v[160:163], v[80:95]
	v_mfma_f32_32x32x16_bf16 v[16:31], v[234:237], v[164:167], v[16:31]
	s_waitcnt lgkmcnt(0)
	v_mfma_f32_32x32x16_bf16 v[64:79], v[238:241], v[160:163], v[64:79]
	v_mfma_f32_32x32x16_bf16 v[0:15], v[238:241], v[164:167], v[0:15]
	s_setprio 0
	global_load_dwordx4 v[160:163], v[190:191], off offset:3584
	global_load_dwordx4 v[164:167], v[188:189], off offset:3584
	s_barrier
; template <bool trans>
; DI void gemm_core(const GTile& tl, const GTile& nx, bool has_next  , bool chain  , bool pre, u32x4 (&ra)[4], u32x4 (&rb)[4], char* smem, f32x16 (&acc)[2][4]) {
;     ...
;   const int nk = K / 64;
;   if (!pre) { G_LOAD(0); G_STORE(0); G_LOAD(1); }
;   for (int kt = 0; kt < nk; ++kt) {
;     __syncthreads();
;     G_COMPUTE(kt & 1, kt);
;   }
	s_waitcnt vmcnt(9)
	ds_write_b128 v209, v[218:221]
	s_waitcnt vmcnt(8)
	ds_write_b128 v210, v[222:225]
	ds_read_b128 v[218:221], v205 offset:36864
	ds_read_b128 v[222:225], v205 offset:41472
	ds_read_b128 v[234:237], v204
	ds_read_b128 v[238:241], v204 offset:4608
	s_setprio 1
	s_waitcnt lgkmcnt(1)
	v_mfma_f32_32x32x16_bf16 v[112:127], v[234:237], v[218:221], v[112:127]
	v_mfma_f32_32x32x16_bf16 v[48:63], v[234:237], v[222:225], v[48:63]
	s_waitcnt lgkmcnt(0)
	v_mfma_f32_32x32x16_bf16 v[96:111], v[238:241], v[218:221], v[96:111]
	v_mfma_f32_32x32x16_bf16 v[32:47], v[238:241], v[222:225], v[32:47]
	ds_read_b128 v[234:237], v204 offset:9216
	ds_read_b128 v[238:241], v204 offset:13824
	s_waitcnt vmcnt(7)
	ds_write_b128 v212, v[226:229]
	s_waitcnt vmcnt(6)
	ds_write_b128 v211, v[230:233]
	ds_read_b128 v[226:229], v205 offset:36896
	ds_read_b128 v[230:233], v205 offset:41504
	s_waitcnt lgkmcnt(5)
	v_mfma_f32_32x32x16_bf16 v[80:95], v[234:237], v[218:221], v[80:95]
	v_mfma_f32_32x32x16_bf16 v[16:31], v[234:237], v[222:225], v[16:31]
	ds_read_b128 v[234:237], v204 offset:32
	s_waitcnt lgkmcnt(5)
	v_mfma_f32_32x32x16_bf16 v[64:79], v[238:241], v[218:221], v[64:79]
	v_mfma_f32_32x32x16_bf16 v[0:15], v[238:241], v[222:225], v[0:15]
	ds_read_b128 v[238:241], v204 offset:4640
	s_setprio 0
	global_load_dwordx4 v[218:221], v[194:195], off offset:3584
	global_load_dwordx4 v[222:225], v[196:197], off offset:3584
	s_setprio 1
	s_waitcnt lgkmcnt(1)
	v_mfma_f32_32x32x16_bf16 v[112:127], v[234:237], v[226:229], v[112:127]
	v_mfma_f32_32x32x16_bf16 v[48:63], v[234:237], v[230:233], v[48:63]
	s_waitcnt lgkmcnt(0)
	v_mfma_f32_32x32x16_bf16 v[96:111], v[238:241], v[226:229], v[96:111]
	v_mfma_f32_32x32x16_bf16 v[32:47], v[238:241], v[230:233], v[32:47]
	ds_read_b128 v[234:237], v204 offset:9248
	ds_read_b128 v[238:241], v204 offset:13856
	s_waitcnt vmcnt(7)
	ds_write_b128 v214, v[176:179]
	s_waitcnt vmcnt(6)
	ds_write_b128 v213, v[180:183]
	ds_read_b128 v[176:179], v205 offset:36928
	ds_read_b128 v[180:183], v205 offset:41536
	s_waitcnt lgkmcnt(5)
	v_mfma_f32_32x32x16_bf16 v[80:95], v[234:237], v[226:229], v[80:95]
	v_mfma_f32_32x32x16_bf16 v[16:31], v[234:237], v[230:233], v[16:31]
	ds_read_b128 v[234:237], v204 offset:64
	s_waitcnt lgkmcnt(5)
	v_mfma_f32_32x32x16_bf16 v[64:79], v[238:241], v[226:229], v[64:79]
	v_mfma_f32_32x32x16_bf16 v[0:15], v[238:241], v[230:233], v[0:15]
	ds_read_b128 v[238:241], v204 offset:4672
	s_setprio 0
	global_load_dwordx4 v[226:229], v[184:185], off offset:3584
	global_load_dwordx4 v[230:233], v[186:187], off offset:3584
	s_setprio 1
	s_waitcnt lgkmcnt(1)
	v_mfma_f32_32x32x16_bf16 v[112:127], v[234:237], v[176:179], v[112:127]
	v_mfma_f32_32x32x16_bf16 v[48:63], v[234:237], v[180:183], v[48:63]
	s_waitcnt lgkmcnt(0)
	v_mfma_f32_32x32x16_bf16 v[96:111], v[238:241], v[176:179], v[96:111]
	v_mfma_f32_32x32x16_bf16 v[32:47], v[238:241], v[180:183], v[32:47]
	ds_read_b128 v[234:237], v204 offset:9280
	ds_read_b128 v[238:241], v204 offset:13888
	s_waitcnt vmcnt(7)
	ds_write_b128 v217, v[168:171]
	s_waitcnt vmcnt(6)
	ds_write_b128 v216, v[172:175]
	ds_read_b128 v[168:171], v205 offset:36960
	ds_read_b128 v[172:175], v205 offset:41568
	s_waitcnt lgkmcnt(5)
	v_mfma_f32_32x32x16_bf16 v[80:95], v[234:237], v[176:179], v[80:95]
	v_mfma_f32_32x32x16_bf16 v[16:31], v[234:237], v[180:183], v[16:31]
	ds_read_b128 v[234:237], v204 offset:96
	s_waitcnt lgkmcnt(5)
	v_mfma_f32_32x32x16_bf16 v[64:79], v[238:241], v[176:179], v[64:79]
	v_mfma_f32_32x32x16_bf16 v[0:15], v[238:241], v[180:183], v[0:15]
	ds_read_b128 v[238:241], v204 offset:4704
	s_setprio 0
	global_load_dwordx4 v[176:179], v[198:199], off offset:3584
	global_load_dwordx4 v[180:183], v[200:201], off offset:3584
	s_setprio 1
	s_waitcnt lgkmcnt(1)
	v_mfma_f32_32x32x16_bf16 v[112:127], v[234:237], v[168:171], v[112:127]
	v_mfma_f32_32x32x16_bf16 v[48:63], v[234:237], v[172:175], v[48:63]
	s_waitcnt lgkmcnt(0)
	v_mfma_f32_32x32x16_bf16 v[96:111], v[238:241], v[168:171], v[96:111]
	v_mfma_f32_32x32x16_bf16 v[32:47], v[238:241], v[172:175], v[32:47]
	ds_read_b128 v[234:237], v204 offset:9312
	ds_read_b128 v[238:241], v204 offset:13920
	s_waitcnt lgkmcnt(1)
	v_mfma_f32_32x32x16_bf16 v[80:95], v[234:237], v[168:171], v[80:95]
	v_mfma_f32_32x32x16_bf16 v[16:31], v[234:237], v[172:175], v[16:31]
	s_waitcnt lgkmcnt(0)
	v_mfma_f32_32x32x16_bf16 v[64:79], v[238:241], v[168:171], v[64:79]
	v_mfma_f32_32x32x16_bf16 v[0:15], v[238:241], v[172:175], v[0:15]
	s_setprio 0
	global_load_dwordx4 v[168:171], v[190:191], off offset:3712
	global_load_dwordx4 v[172:175], v[188:189], off offset:3712
	s_barrier
; template <bool trans>
; DI void gemm_core(const GTile& tl, const GTile& nx, bool has_next  , bool chain  , bool pre, u32x4 (&ra)[4], u32x4 (&rb)[4], char* smem, f32x16 (&acc)[2][4]) {
;     ...
;   const int nk = K / 64;
;   if (!pre) { G_LOAD(0); G_STORE(0); G_LOAD(1); }
;   for (int kt = 0; kt < nk; ++kt) {
;     __syncthreads();
;     G_COMPUTE(kt & 1, kt);
;   }
	s_waitcnt vmcnt(9)
	ds_write_b128 v215, v[160:163]
	s_waitcnt vmcnt(8)
	ds_write_b128 v215, v[164:167] offset:36864
	ds_read_b128 v[160:163], v208
	ds_read_b128 v[164:167], v208 offset:4608
	ds_read_b128 v[234:237], v192
	ds_read_b128 v[238:241], v192 offset:4608
	s_setprio 1
	s_waitcnt lgkmcnt(1)
	v_mfma_f32_32x32x16_bf16 v[112:127], v[234:237], v[160:163], v[112:127]
	v_mfma_f32_32x32x16_bf16 v[48:63], v[234:237], v[164:167], v[48:63]
	s_waitcnt lgkmcnt(0)
	v_mfma_f32_32x32x16_bf16 v[96:111], v[238:241], v[160:163], v[96:111]
	v_mfma_f32_32x32x16_bf16 v[32:47], v[238:241], v[164:167], v[32:47]
	ds_read_b128 v[234:237], v192 offset:9216
	ds_read_b128 v[238:241], v192 offset:13824
	s_waitcnt vmcnt(7)
	ds_write_b128 v215, v[218:221] offset:9216
	s_waitcnt vmcnt(6)
	ds_write_b128 v215, v[222:225] offset:46080
	ds_read_b128 v[218:221], v208 offset:32
	ds_read_b128 v[222:225], v208 offset:4640
	s_waitcnt lgkmcnt(5)
	v_mfma_f32_32x32x16_bf16 v[80:95], v[234:237], v[160:163], v[80:95]
	v_mfma_f32_32x32x16_bf16 v[16:31], v[234:237], v[164:167], v[16:31]
	ds_read_b128 v[234:237], v192 offset:32
	s_waitcnt lgkmcnt(5)
	v_mfma_f32_32x32x16_bf16 v[64:79], v[238:241], v[160:163], v[64:79]
	v_mfma_f32_32x32x16_bf16 v[0:15], v[238:241], v[164:167], v[0:15]
	ds_read_b128 v[238:241], v192 offset:4640
	s_setprio 0
	global_load_dwordx4 v[160:163], v[194:195], off offset:3712
	global_load_dwordx4 v[164:167], v[196:197], off offset:3712
	s_setprio 1
	s_waitcnt lgkmcnt(1)
	v_mfma_f32_32x32x16_bf16 v[112:127], v[234:237], v[218:221], v[112:127]
	v_mfma_f32_32x32x16_bf16 v[48:63], v[234:237], v[222:225], v[48:63]
	s_waitcnt lgkmcnt(0)
	v_mfma_f32_32x32x16_bf16 v[96:111], v[238:241], v[218:221], v[96:111]
	v_mfma_f32_32x32x16_bf16 v[32:47], v[238:241], v[222:225], v[32:47]
	ds_read_b128 v[234:237], v192 offset:9248
	ds_read_b128 v[238:241], v192 offset:13856
	s_waitcnt vmcnt(7)
	ds_write_b128 v215, v[226:229] offset:18432
	s_waitcnt vmcnt(6)
	ds_write_b128 v215, v[230:233] offset:55296
	ds_read_b128 v[226:229], v208 offset:64
	ds_read_b128 v[230:233], v208 offset:4672
	s_waitcnt lgkmcnt(5)
	v_mfma_f32_32x32x16_bf16 v[80:95], v[234:237], v[218:221], v[80:95]
	v_mfma_f32_32x32x16_bf16 v[16:31], v[234:237], v[222:225], v[16:31]
	ds_read_b128 v[234:237], v192 offset:64
	s_waitcnt lgkmcnt(5)
	v_mfma_f32_32x32x16_bf16 v[64:79], v[238:241], v[218:221], v[64:79]
	v_mfma_f32_32x32x16_bf16 v[0:15], v[238:241], v[222:225], v[0:15]
	ds_read_b128 v[238:241], v192 offset:4672
	s_setprio 0
	global_load_dwordx4 v[218:221], v[184:185], off offset:3712
	global_load_dwordx4 v[222:225], v[186:187], off offset:3712
	s_setprio 1
	s_waitcnt lgkmcnt(1)
	v_mfma_f32_32x32x16_bf16 v[112:127], v[234:237], v[226:229], v[112:127]
	v_mfma_f32_32x32x16_bf16 v[48:63], v[234:237], v[230:233], v[48:63]
	s_waitcnt lgkmcnt(0)
	v_mfma_f32_32x32x16_bf16 v[96:111], v[238:241], v[226:229], v[96:111]
	v_mfma_f32_32x32x16_bf16 v[32:47], v[238:241], v[230:233], v[32:47]
	ds_read_b128 v[234:237], v192 offset:9280
	ds_read_b128 v[238:241], v192 offset:13888
	s_waitcnt vmcnt(7)
	ds_write_b128 v215, v[176:179] offset:27648
	s_waitcnt vmcnt(6)
	ds_write_b128 v215, v[180:183] offset:64512
	ds_read_b128 v[176:179], v208 offset:96
	ds_read_b128 v[180:183], v208 offset:4704
	s_waitcnt lgkmcnt(5)
	v_mfma_f32_32x32x16_bf16 v[80:95], v[234:237], v[226:229], v[80:95]
	v_mfma_f32_32x32x16_bf16 v[16:31], v[234:237], v[230:233], v[16:31]
	ds_read_b128 v[234:237], v192 offset:96
	s_waitcnt lgkmcnt(5)
	v_mfma_f32_32x32x16_bf16 v[64:79], v[238:241], v[226:229], v[64:79]
	v_mfma_f32_32x32x16_bf16 v[0:15], v[238:241], v[230:233], v[0:15]
	ds_read_b128 v[238:241], v192 offset:4704
	s_setprio 0
	global_load_dwordx4 v[226:229], v[198:199], off offset:3712
	global_load_dwordx4 v[230:233], v[200:201], off offset:3712
	s_setprio 1
	s_waitcnt lgkmcnt(1)
	v_mfma_f32_32x32x16_bf16 v[112:127], v[234:237], v[176:179], v[112:127]
	v_mfma_f32_32x32x16_bf16 v[48:63], v[234:237], v[180:183], v[48:63]
	s_waitcnt lgkmcnt(0)
	v_mfma_f32_32x32x16_bf16 v[96:111], v[238:241], v[176:179], v[96:111]
	v_mfma_f32_32x32x16_bf16 v[32:47], v[238:241], v[180:183], v[32:47]
	ds_read_b128 v[234:237], v192 offset:9312
	ds_read_b128 v[238:241], v192 offset:13920
	s_waitcnt lgkmcnt(1)
	v_mfma_f32_32x32x16_bf16 v[80:95], v[234:237], v[176:179], v[80:95]
	v_mfma_f32_32x32x16_bf16 v[16:31], v[234:237], v[180:183], v[16:31]
	s_waitcnt lgkmcnt(0)
	v_mfma_f32_32x32x16_bf16 v[64:79], v[238:241], v[176:179], v[64:79]
	v_mfma_f32_32x32x16_bf16 v[0:15], v[238:241], v[180:183], v[0:15]
	s_setprio 0
	global_load_dwordx4 v[176:179], v[190:191], off offset:3840
	global_load_dwordx4 v[180:183], v[188:189], off offset:3840
	s_barrier
; template <bool trans>
; DI void gemm_core(const GTile& tl, const GTile& nx, bool has_next  , bool chain  , bool pre, u32x4 (&ra)[4], u32x4 (&rb)[4], char* smem, f32x16 (&acc)[2][4]) {
;     ...
;   const int nk = K / 64;
;   if (!pre) { G_LOAD(0); G_STORE(0); G_LOAD(1); }
;   for (int kt = 0; kt < nk; ++kt) {
;     __syncthreads();
;     G_COMPUTE(kt & 1, kt);
;   }
	s_waitcnt vmcnt(9)
	ds_write_b128 v209, v[168:171]
	s_waitcnt vmcnt(8)
	ds_write_b128 v210, v[172:175]
	ds_read_b128 v[168:171], v205 offset:36864
	ds_read_b128 v[172:175], v205 offset:41472
	ds_read_b128 v[234:237], v204
	ds_read_b128 v[238:241], v204 offset:4608
	s_setprio 1
	s_waitcnt lgkmcnt(1)
	v_mfma_f32_32x32x16_bf16 v[112:127], v[234:237], v[168:171], v[112:127]
	v_mfma_f32_32x32x16_bf16 v[48:63], v[234:237], v[172:175], v[48:63]
	s_waitcnt lgkmcnt(0)
	v_mfma_f32_32x32x16_bf16 v[96:111], v[238:241], v[168:171], v[96:111]
	v_mfma_f32_32x32x16_bf16 v[32:47], v[238:241], v[172:175], v[32:47]
	ds_read_b128 v[234:237], v204 offset:9216
	ds_read_b128 v[238:241], v204 offset:13824
	s_waitcnt lgkmcnt(1)
	v_mfma_f32_32x32x16_bf16 v[80:95], v[234:237], v[168:171], v[80:95]
	v_mfma_f32_32x32x16_bf16 v[16:31], v[234:237], v[172:175], v[16:31]
	s_waitcnt lgkmcnt(0)
	v_mfma_f32_32x32x16_bf16 v[64:79], v[238:241], v[168:171], v[64:79]
	v_mfma_f32_32x32x16_bf16 v[0:15], v[238:241], v[172:175], v[0:15]
	s_setprio 0
	global_load_dwordx4 v[234:237], v[194:195], off offset:3840
	global_load_dwordx4 v[238:241], v[196:197], off offset:3840
	s_waitcnt vmcnt(9)
	ds_write_b128 v212, v[160:163]
	s_waitcnt vmcnt(8)
	ds_write_b128 v211, v[164:167]
	ds_read_b128 v[160:163], v205 offset:36896
	ds_read_b128 v[164:167], v205 offset:41504
	ds_read_b128 v[168:171], v204 offset:32
	ds_read_b128 v[172:175], v204 offset:4640
	s_setprio 1
	s_waitcnt lgkmcnt(1)
	v_mfma_f32_32x32x16_bf16 v[112:127], v[168:171], v[160:163], v[112:127]
	v_mfma_f32_32x32x16_bf16 v[48:63], v[168:171], v[164:167], v[48:63]
	s_waitcnt lgkmcnt(0)
	v_mfma_f32_32x32x16_bf16 v[96:111], v[172:175], v[160:163], v[96:111]
	v_mfma_f32_32x32x16_bf16 v[32:47], v[172:175], v[164:167], v[32:47]
	ds_read_b128 v[168:171], v204 offset:9248
	ds_read_b128 v[172:175], v204 offset:13856
	s_waitcnt lgkmcnt(1)
	v_mfma_f32_32x32x16_bf16 v[80:95], v[168:171], v[160:163], v[80:95]
	v_mfma_f32_32x32x16_bf16 v[16:31], v[168:171], v[164:167], v[16:31]
	s_waitcnt lgkmcnt(0)
	v_mfma_f32_32x32x16_bf16 v[64:79], v[172:175], v[160:163], v[64:79]
	v_mfma_f32_32x32x16_bf16 v[0:15], v[172:175], v[164:167], v[0:15]
	s_setprio 0
	global_load_dwordx4 v[242:245], v[184:185], off offset:3840
	global_load_dwordx4 v[246:249], v[186:187], off offset:3840
	s_waitcnt vmcnt(9)
	ds_write_b128 v214, v[218:221]
	s_waitcnt vmcnt(8)
	ds_write_b128 v213, v[222:225]
	ds_read_b128 v[160:163], v205 offset:36928
	ds_read_b128 v[164:167], v205 offset:41536
	ds_read_b128 v[168:171], v204 offset:64
	ds_read_b128 v[172:175], v204 offset:4672
	s_setprio 1
	s_waitcnt lgkmcnt(1)
	v_mfma_f32_32x32x16_bf16 v[112:127], v[168:171], v[160:163], v[112:127]
	v_mfma_f32_32x32x16_bf16 v[48:63], v[168:171], v[164:167], v[48:63]
	s_waitcnt lgkmcnt(0)
	v_mfma_f32_32x32x16_bf16 v[96:111], v[172:175], v[160:163], v[96:111]
	v_mfma_f32_32x32x16_bf16 v[32:47], v[172:175], v[164:167], v[32:47]
	ds_read_b128 v[168:171], v204 offset:9280
	ds_read_b128 v[172:175], v204 offset:13888
	s_waitcnt lgkmcnt(1)
	v_mfma_f32_32x32x16_bf16 v[80:95], v[168:171], v[160:163], v[80:95]
	v_mfma_f32_32x32x16_bf16 v[16:31], v[168:171], v[164:167], v[16:31]
	s_waitcnt lgkmcnt(0)
	v_mfma_f32_32x32x16_bf16 v[64:79], v[172:175], v[160:163], v[64:79]
	v_mfma_f32_32x32x16_bf16 v[0:15], v[172:175], v[164:167], v[0:15]
	s_setprio 0
	global_load_dwordx4 v[218:221], v[198:199], off offset:3840
	global_load_dwordx4 v[222:225], v[200:201], off offset:3840
	s_waitcnt vmcnt(9)
	ds_write_b128 v217, v[226:229]
	s_waitcnt vmcnt(8)
	ds_write_b128 v216, v[230:233]
	ds_read_b128 v[160:163], v205 offset:36960
	ds_read_b128 v[164:167], v205 offset:41568
	ds_read_b128 v[168:171], v204 offset:96
	ds_read_b128 v[172:175], v204 offset:4704
	s_setprio 1
	s_waitcnt lgkmcnt(1)
	v_mfma_f32_32x32x16_bf16 v[112:127], v[168:171], v[160:163], v[112:127]
	v_mfma_f32_32x32x16_bf16 v[48:63], v[168:171], v[164:167], v[48:63]
	s_waitcnt lgkmcnt(0)
	v_mfma_f32_32x32x16_bf16 v[96:111], v[172:175], v[160:163], v[96:111]
	v_mfma_f32_32x32x16_bf16 v[32:47], v[172:175], v[164:167], v[32:47]
	ds_read_b128 v[168:171], v204 offset:9312
	ds_read_b128 v[172:175], v204 offset:13920
	s_waitcnt lgkmcnt(1)
	v_mfma_f32_32x32x16_bf16 v[80:95], v[168:171], v[160:163], v[80:95]
	v_mfma_f32_32x32x16_bf16 v[16:31], v[168:171], v[164:167], v[16:31]
	s_waitcnt lgkmcnt(0)
	v_mfma_f32_32x32x16_bf16 v[64:79], v[172:175], v[160:163], v[64:79]
	v_mfma_f32_32x32x16_bf16 v[0:15], v[172:175], v[164:167], v[0:15]
	s_setprio 0
	global_load_dwordx4 v[160:163], v[190:191], off offset:3968
	global_load_dwordx4 v[164:167], v[188:189], off offset:3968
	s_barrier
; template <bool trans>
; DI void gemm_core(const GTile& tl, const GTile& nx, bool has_next  , bool chain  , bool pre, u32x4 (&ra)[4], u32x4 (&rb)[4], char* smem, f32x16 (&acc)[2][4]) {
;     ...
;   const int nk = K / 64;
;   if (!pre) { G_LOAD(0); G_STORE(0); G_LOAD(1); }
;   for (int kt = 0; kt < nk; ++kt) {
;     __syncthreads();
;     G_COMPUTE(kt & 1, kt);
;   }
	s_waitcnt vmcnt(9)
	ds_write_b128 v215, v[176:179]
	s_waitcnt vmcnt(8)
	ds_write_b128 v215, v[180:183] offset:36864
	ds_read_b128 v[168:171], v208
	ds_read_b128 v[172:175], v208 offset:4608
	ds_read_b128 v[176:179], v192
	ds_read_b128 v[180:183], v192 offset:4608
	s_setprio 1
	s_waitcnt lgkmcnt(1)
	v_mfma_f32_32x32x16_bf16 v[112:127], v[176:179], v[168:171], v[112:127]
	v_mfma_f32_32x32x16_bf16 v[48:63], v[176:179], v[172:175], v[48:63]
	s_waitcnt lgkmcnt(0)
	v_mfma_f32_32x32x16_bf16 v[96:111], v[180:183], v[168:171], v[96:111]
	v_mfma_f32_32x32x16_bf16 v[32:47], v[180:183], v[172:175], v[32:47]
	ds_read_b128 v[176:179], v192 offset:9216
	ds_read_b128 v[180:183], v192 offset:13824
	s_waitcnt lgkmcnt(1)
	v_mfma_f32_32x32x16_bf16 v[80:95], v[176:179], v[168:171], v[80:95]
	v_mfma_f32_32x32x16_bf16 v[16:31], v[176:179], v[172:175], v[16:31]
	s_waitcnt lgkmcnt(0)
	v_mfma_f32_32x32x16_bf16 v[64:79], v[180:183], v[168:171], v[64:79]
	v_mfma_f32_32x32x16_bf16 v[0:15], v[180:183], v[172:175], v[0:15]
	s_setprio 0
	global_load_dwordx4 v[168:171], v[194:195], off offset:3968
	global_load_dwordx4 v[172:175], v[196:197], off offset:3968
	s_waitcnt vmcnt(9)
	ds_write_b128 v215, v[234:237] offset:9216
	s_waitcnt vmcnt(8)
	ds_write_b128 v215, v[238:241] offset:46080
	ds_read_b128 v[176:179], v208 offset:32
	ds_read_b128 v[180:183], v208 offset:4640
	ds_read_b128 v[188:191], v192 offset:32
	ds_read_b128 v[194:197], v192 offset:4640
	s_setprio 1
	s_waitcnt lgkmcnt(1)
	v_mfma_f32_32x32x16_bf16 v[112:127], v[188:191], v[176:179], v[112:127]
	v_mfma_f32_32x32x16_bf16 v[48:63], v[188:191], v[180:183], v[48:63]
	s_waitcnt lgkmcnt(0)
	v_mfma_f32_32x32x16_bf16 v[96:111], v[194:197], v[176:179], v[96:111]
	v_mfma_f32_32x32x16_bf16 v[32:47], v[194:197], v[180:183], v[32:47]
	ds_read_b128 v[188:191], v192 offset:9248
	ds_read_b128 v[194:197], v192 offset:13856
	s_waitcnt lgkmcnt(1)
	v_mfma_f32_32x32x16_bf16 v[80:95], v[188:191], v[176:179], v[80:95]
	v_mfma_f32_32x32x16_bf16 v[16:31], v[188:191], v[180:183], v[16:31]
	s_waitcnt lgkmcnt(0)
	v_mfma_f32_32x32x16_bf16 v[64:79], v[194:197], v[176:179], v[64:79]
	v_mfma_f32_32x32x16_bf16 v[0:15], v[194:197], v[180:183], v[0:15]
	s_setprio 0
	global_load_dwordx4 v[176:179], v[184:185], off offset:3968
	global_load_dwordx4 v[180:183], v[186:187], off offset:3968
	s_waitcnt vmcnt(9)
	ds_write_b128 v215, v[242:245] offset:18432
	s_waitcnt vmcnt(8)
	ds_write_b128 v215, v[246:249] offset:55296
	ds_read_b128 v[184:187], v208 offset:64
	ds_read_b128 v[188:191], v208 offset:4672
	ds_read_b128 v[194:197], v192 offset:64
	ds_read_b128 v[226:229], v192 offset:4672
	s_setprio 1
	s_waitcnt lgkmcnt(1)
	v_mfma_f32_32x32x16_bf16 v[112:127], v[194:197], v[184:187], v[112:127]
	v_mfma_f32_32x32x16_bf16 v[48:63], v[194:197], v[188:191], v[48:63]
	s_waitcnt lgkmcnt(0)
	v_mfma_f32_32x32x16_bf16 v[96:111], v[226:229], v[184:187], v[96:111]
	v_mfma_f32_32x32x16_bf16 v[32:47], v[226:229], v[188:191], v[32:47]
	ds_read_b128 v[194:197], v192 offset:9280
	ds_read_b128 v[226:229], v192 offset:13888
	s_waitcnt lgkmcnt(1)
	v_mfma_f32_32x32x16_bf16 v[80:95], v[194:197], v[184:187], v[80:95]
	v_mfma_f32_32x32x16_bf16 v[16:31], v[194:197], v[188:191], v[16:31]
	s_waitcnt lgkmcnt(0)
	v_mfma_f32_32x32x16_bf16 v[64:79], v[226:229], v[184:187], v[64:79]
	v_mfma_f32_32x32x16_bf16 v[0:15], v[226:229], v[188:191], v[0:15]
	s_setprio 0
	global_load_dwordx4 v[184:187], v[198:199], off offset:3968
	global_load_dwordx4 v[188:191], v[200:201], off offset:3968
	s_waitcnt vmcnt(9)
	ds_write_b128 v215, v[218:221] offset:27648
	s_waitcnt vmcnt(8)
	ds_write_b128 v215, v[222:225] offset:64512
	ds_read_b128 v[194:197], v208 offset:96
	ds_read_b128 v[198:201], v208 offset:4704
	ds_read_b128 v[218:221], v192 offset:96
	ds_read_b128 v[222:225], v192 offset:4704
	s_setprio 1
	s_waitcnt lgkmcnt(1)
	v_mfma_f32_32x32x16_bf16 v[112:127], v[218:221], v[194:197], v[112:127]
	v_mfma_f32_32x32x16_bf16 v[48:63], v[218:221], v[198:201], v[48:63]
	s_waitcnt lgkmcnt(0)
	v_mfma_f32_32x32x16_bf16 v[96:111], v[222:225], v[194:197], v[96:111]
	v_mfma_f32_32x32x16_bf16 v[32:47], v[222:225], v[198:201], v[32:47]
	ds_read_b128 v[218:221], v192 offset:9312
	ds_read_b128 v[222:225], v192 offset:13920
	s_waitcnt lgkmcnt(1)
	v_mfma_f32_32x32x16_bf16 v[80:95], v[218:221], v[194:197], v[80:95]
	v_mfma_f32_32x32x16_bf16 v[16:31], v[218:221], v[198:201], v[16:31]
	s_waitcnt lgkmcnt(0)
	v_mfma_f32_32x32x16_bf16 v[64:79], v[222:225], v[194:197], v[64:79]
	v_mfma_f32_32x32x16_bf16 v[0:15], v[222:225], v[198:201], v[0:15]
	s_setprio 0
	s_barrier
; template <bool trans>
; DI void gemm_core(const GTile& tl, const GTile& nx, bool has_next  , bool chain  , bool pre, u32x4 (&ra)[4], u32x4 (&rb)[4], char* smem, f32x16 (&acc)[2][4]) {
;     ...
;   const int nk = K / 64;
;   if (!pre) { G_LOAD(0); G_STORE(0); G_LOAD(1); }
;   for (int kt = 0; kt < nk; ++kt) {
;     __syncthreads();
;     G_COMPUTE(kt & 1, kt);
;   }
	s_waitcnt vmcnt(7)
	ds_write_b128 v209, v[160:163]
	s_waitcnt vmcnt(6)
	ds_write_b128 v210, v[164:167]
	ds_read_b128 v[194:197], v205 offset:36864
	ds_read_b128 v[198:201], v205 offset:41472
	ds_read_b128 v[218:221], v204
	ds_read_b128 v[222:225], v204 offset:4608
	s_setprio 1
	s_waitcnt lgkmcnt(1)
	v_mfma_f32_32x32x16_bf16 v[112:127], v[218:221], v[194:197], v[112:127]
	v_mfma_f32_32x32x16_bf16 v[48:63], v[218:221], v[198:201], v[48:63]
	s_waitcnt lgkmcnt(0)
	v_mfma_f32_32x32x16_bf16 v[96:111], v[222:225], v[194:197], v[96:111]
	v_mfma_f32_32x32x16_bf16 v[32:47], v[222:225], v[198:201], v[32:47]
	ds_read_b128 v[218:221], v204 offset:9216
	ds_read_b128 v[222:225], v204 offset:13824
	s_waitcnt lgkmcnt(1)
	v_mfma_f32_32x32x16_bf16 v[80:95], v[218:221], v[194:197], v[80:95]
	v_mfma_f32_32x32x16_bf16 v[16:31], v[218:221], v[198:201], v[16:31]
	s_waitcnt lgkmcnt(0)
	v_mfma_f32_32x32x16_bf16 v[64:79], v[222:225], v[194:197], v[64:79]
	v_mfma_f32_32x32x16_bf16 v[0:15], v[222:225], v[198:201], v[0:15]
	s_setprio 0
	s_waitcnt vmcnt(5)
	ds_write_b128 v212, v[168:171]
	s_waitcnt vmcnt(4)
	ds_write_b128 v211, v[172:175]
	ds_read_b128 v[194:197], v205 offset:36896
	ds_read_b128 v[198:201], v205 offset:41504
	ds_read_b128 v[218:221], v204 offset:32
	ds_read_b128 v[222:225], v204 offset:4640
	s_setprio 1
	s_waitcnt lgkmcnt(1)
	v_mfma_f32_32x32x16_bf16 v[112:127], v[218:221], v[194:197], v[112:127]
	v_mfma_f32_32x32x16_bf16 v[48:63], v[218:221], v[198:201], v[48:63]
	s_waitcnt lgkmcnt(0)
	v_mfma_f32_32x32x16_bf16 v[96:111], v[222:225], v[194:197], v[96:111]
	v_mfma_f32_32x32x16_bf16 v[32:47], v[222:225], v[198:201], v[32:47]
	ds_read_b128 v[218:221], v204 offset:9248
	ds_read_b128 v[222:225], v204 offset:13856
	s_waitcnt lgkmcnt(1)
	v_mfma_f32_32x32x16_bf16 v[80:95], v[218:221], v[194:197], v[80:95]
	v_mfma_f32_32x32x16_bf16 v[16:31], v[218:221], v[198:201], v[16:31]
	s_waitcnt lgkmcnt(0)
	v_mfma_f32_32x32x16_bf16 v[64:79], v[222:225], v[194:197], v[64:79]
	v_mfma_f32_32x32x16_bf16 v[0:15], v[222:225], v[198:201], v[0:15]
	s_setprio 0
	s_waitcnt vmcnt(3)
	ds_write_b128 v214, v[176:179]
	s_waitcnt vmcnt(2)
	ds_write_b128 v213, v[180:183]
	ds_read_b128 v[194:197], v205 offset:36928
	ds_read_b128 v[198:201], v205 offset:41536
	ds_read_b128 v[210:213], v204 offset:64
	ds_read_b128 v[218:221], v204 offset:4672
	s_setprio 1
	s_waitcnt lgkmcnt(1)
	v_mfma_f32_32x32x16_bf16 v[112:127], v[210:213], v[194:197], v[112:127]
	v_mfma_f32_32x32x16_bf16 v[48:63], v[210:213], v[198:201], v[48:63]
	s_waitcnt lgkmcnt(0)
	v_mfma_f32_32x32x16_bf16 v[96:111], v[218:221], v[194:197], v[96:111]
	v_mfma_f32_32x32x16_bf16 v[32:47], v[218:221], v[198:201], v[32:47]
	ds_read_b128 v[210:213], v204 offset:9280
	ds_read_b128 v[218:221], v204 offset:13888
	s_waitcnt lgkmcnt(1)
	v_mfma_f32_32x32x16_bf16 v[80:95], v[210:213], v[194:197], v[80:95]
	v_mfma_f32_32x32x16_bf16 v[16:31], v[210:213], v[198:201], v[16:31]
	s_waitcnt lgkmcnt(0)
	v_mfma_f32_32x32x16_bf16 v[64:79], v[218:221], v[194:197], v[64:79]
	v_mfma_f32_32x32x16_bf16 v[0:15], v[218:221], v[198:201], v[0:15]
	s_setprio 0
	s_waitcnt vmcnt(1)
	ds_write_b128 v217, v[184:187]
	s_waitcnt vmcnt(0)
	ds_write_b128 v216, v[188:191]
	ds_read_b128 v[194:197], v205 offset:36960
	ds_read_b128 v[198:201], v205 offset:41568
	ds_read_b128 v[210:213], v204 offset:96
	ds_read_b128 v[214:217], v204 offset:4704
	s_setprio 1
	s_waitcnt lgkmcnt(1)
	v_mfma_f32_32x32x16_bf16 v[112:127], v[210:213], v[194:197], v[112:127]
	v_mfma_f32_32x32x16_bf16 v[48:63], v[210:213], v[198:201], v[48:63]
	s_waitcnt lgkmcnt(0)
	v_mfma_f32_32x32x16_bf16 v[96:111], v[214:217], v[194:197], v[96:111]
	v_mfma_f32_32x32x16_bf16 v[32:47], v[214:217], v[198:201], v[32:47]
	ds_read_b128 v[210:213], v204 offset:9312
	ds_read_b128 v[214:217], v204 offset:13920
	s_waitcnt lgkmcnt(1)
	v_mfma_f32_32x32x16_bf16 v[80:95], v[210:213], v[194:197], v[80:95]
	v_mfma_f32_32x32x16_bf16 v[16:31], v[210:213], v[198:201], v[16:31]
	s_waitcnt lgkmcnt(0)
	v_mfma_f32_32x32x16_bf16 v[64:79], v[214:217], v[194:197], v[64:79]
	v_mfma_f32_32x32x16_bf16 v[0:15], v[214:217], v[198:201], v[0:15]
	s_setprio 0
	s_barrier
; template <bool trans>
; DI void gemm_core(const GTile& tl, const GTile& nx, bool has_next  , bool chain  , bool pre, u32x4 (&ra)[4], u32x4 (&rb)[4], char* smem, f32x16 (&acc)[2][4]) {
;     ...
;   const int nk = K / 64;
;   if (!pre) { G_LOAD(0); G_STORE(0); G_LOAD(1); }
;   for (int kt = 0; kt < nk; ++kt) {
;     __syncthreads();
;     G_COMPUTE(kt & 1, kt);
;   }
;   if (!has_next) __syncthreads();
	ds_read_b128 v[194:197], v208
	ds_read_b128 v[198:201], v208 offset:4608
	ds_read_b128 v[210:213], v192
	ds_read_b128 v[214:217], v192 offset:4608
	s_setprio 1
	s_waitcnt lgkmcnt(1)
	v_mfma_f32_32x32x16_bf16 v[112:127], v[210:213], v[194:197], v[112:127]
	v_mfma_f32_32x32x16_bf16 v[48:63], v[210:213], v[198:201], v[48:63]
	s_waitcnt lgkmcnt(0)
	v_mfma_f32_32x32x16_bf16 v[96:111], v[214:217], v[194:197], v[96:111]
	v_mfma_f32_32x32x16_bf16 v[32:47], v[214:217], v[198:201], v[32:47]
	ds_read_b128 v[210:213], v192 offset:9216
	ds_read_b128 v[214:217], v192 offset:13824
	s_waitcnt lgkmcnt(1)
	v_mfma_f32_32x32x16_bf16 v[80:95], v[210:213], v[194:197], v[80:95]
	v_mfma_f32_32x32x16_bf16 v[16:31], v[210:213], v[198:201], v[16:31]
	s_waitcnt lgkmcnt(0)
	v_mfma_f32_32x32x16_bf16 v[64:79], v[214:217], v[194:197], v[64:79]
	v_mfma_f32_32x32x16_bf16 v[0:15], v[214:217], v[198:201], v[0:15]
	s_setprio 0
	ds_read_b128 v[194:197], v208 offset:32
	ds_read_b128 v[198:201], v208 offset:4640
	ds_read_b128 v[210:213], v192 offset:32
	ds_read_b128 v[214:217], v192 offset:4640
	s_setprio 1
	s_waitcnt lgkmcnt(1)
	v_mfma_f32_32x32x16_bf16 v[112:127], v[210:213], v[194:197], v[112:127]
	v_mfma_f32_32x32x16_bf16 v[48:63], v[210:213], v[198:201], v[48:63]
	s_waitcnt lgkmcnt(0)
	v_mfma_f32_32x32x16_bf16 v[96:111], v[214:217], v[194:197], v[96:111]
	v_mfma_f32_32x32x16_bf16 v[32:47], v[214:217], v[198:201], v[32:47]
	ds_read_b128 v[210:213], v192 offset:9248
	ds_read_b128 v[214:217], v192 offset:13856
	s_waitcnt lgkmcnt(1)
	v_mfma_f32_32x32x16_bf16 v[80:95], v[210:213], v[194:197], v[80:95]
	v_mfma_f32_32x32x16_bf16 v[16:31], v[210:213], v[198:201], v[16:31]
	s_waitcnt lgkmcnt(0)
	v_mfma_f32_32x32x16_bf16 v[64:79], v[214:217], v[194:197], v[64:79]
	v_mfma_f32_32x32x16_bf16 v[0:15], v[214:217], v[198:201], v[0:15]
	s_setprio 0
	ds_read_b128 v[194:197], v208 offset:64
	ds_read_b128 v[198:201], v208 offset:4672
	ds_read_b128 v[210:213], v192 offset:64
	ds_read_b128 v[214:217], v192 offset:4672
	s_setprio 1
	s_waitcnt lgkmcnt(1)
	v_mfma_f32_32x32x16_bf16 v[112:127], v[210:213], v[194:197], v[112:127]
	v_mfma_f32_32x32x16_bf16 v[48:63], v[210:213], v[198:201], v[48:63]
	s_waitcnt lgkmcnt(0)
	v_mfma_f32_32x32x16_bf16 v[96:111], v[214:217], v[194:197], v[96:111]
	v_mfma_f32_32x32x16_bf16 v[32:47], v[214:217], v[198:201], v[32:47]
	ds_read_b128 v[210:213], v192 offset:9280
	ds_read_b128 v[214:217], v192 offset:13888
	s_waitcnt lgkmcnt(1)
	v_mfma_f32_32x32x16_bf16 v[80:95], v[210:213], v[194:197], v[80:95]
	v_mfma_f32_32x32x16_bf16 v[16:31], v[210:213], v[198:201], v[16:31]
	s_waitcnt lgkmcnt(0)
	v_mfma_f32_32x32x16_bf16 v[64:79], v[214:217], v[194:197], v[64:79]
	v_mfma_f32_32x32x16_bf16 v[0:15], v[214:217], v[198:201], v[0:15]
	s_setprio 0
	ds_read_b128 v[194:197], v208 offset:96
	ds_read_b128 v[198:201], v208 offset:4704
	ds_read_b128 v[208:211], v192 offset:96
	ds_read_b128 v[212:215], v192 offset:4704
	s_setprio 1
	s_waitcnt lgkmcnt(1)
	v_mfma_f32_32x32x16_bf16 v[112:127], v[208:211], v[194:197], v[112:127]
	v_mfma_f32_32x32x16_bf16 v[48:63], v[208:211], v[198:201], v[48:63]
	s_waitcnt lgkmcnt(0)
	v_mfma_f32_32x32x16_bf16 v[96:111], v[212:215], v[194:197], v[96:111]
	v_mfma_f32_32x32x16_bf16 v[32:47], v[212:215], v[198:201], v[32:47]
	ds_read_b128 v[208:211], v192 offset:9312
	ds_read_b128 v[212:215], v192 offset:13920
	s_waitcnt lgkmcnt(1)
	v_mfma_f32_32x32x16_bf16 v[80:95], v[208:211], v[194:197], v[80:95]
	v_mfma_f32_32x32x16_bf16 v[16:31], v[208:211], v[198:201], v[16:31]
	s_waitcnt lgkmcnt(0)
	v_mfma_f32_32x32x16_bf16 v[64:79], v[212:215], v[194:197], v[64:79]
	v_mfma_f32_32x32x16_bf16 v[0:15], v[212:215], v[198:201], v[0:15]
	s_setprio 0
	s_andn2_b64 vcc, exec, s[48:49]
	s_cbranch_vccnz .LBB0_105
	s_barrier

; template <bool trans>
; DI void gemm_core(const GTile& tl, const GTile& nx, bool has_next  , bool chain  , bool pre, u32x4 (&ra)[4], u32x4 (&rb)[4], char* smem, f32x16 (&acc)[2][4]) {
;     ...
;   const int lrow = tid >> 3, kc = tid & 7;
;   const unsigned aoff = (unsigned)(lrow * lda + kc * 8) * 2u, boff = (unsigned)(lrow * ldb + kc * 8) * 2u;
;   const char* ag = (const char*)(A + (size_t)m0 * lda);
;   const char* bg = (const char*)(Bt + (size_t)n0 * ldb);
;   const unsigned aoffn = (unsigned)(lrow * nx.lda + kc * 8) * 2u, boffn = (unsigned)(lrow * nx.ldb + kc * 8) * 2u;
;   const char* agn = (const char*)(nx.A + (size_t)nx.m0 * nx.lda);
;   const char* bgn = (const char*)(nx.Bt + (size_t)nx.n0 * nx.ldb);
;     ...
;   const int nk = K / 64;
;   if (!pre) { G_LOAD(0); G_STORE(0); G_LOAD(1); }
;   for (int kt = 0; kt < nk; ++kt) {
;     __syncthreads();
;     G_COMPUTE(kt & 1, kt);
;   }
.LBB0_111:
	v_lshl_add_u64 v[136:137], s[0:1], 0, v[192:193]
	v_lshl_add_u64 v[138:139], s[2:3], 0, v[192:193]
	s_waitcnt lgkmcnt(0)
	s_barrier
	global_load_dwordx4 v[184:187], v[136:137], off offset:256
	global_load_dwordx4 v[188:191], v[138:139], off offset:256
	s_and_b32 s1, s36, 0x1f80000
	s_and_b32 s0, s38, 0xffffff00
	s_and_b32 s4, s33, 0xc0
	s_lshl_b32 s1, s1, 1
	s_add_u32 s2, s16, s1
	s_addc_u32 s3, s17, 0
	s_ashr_i32 s1, s0, 31
	s_lshl_b64 s[0:1], s[0:1], 12
	s_add_u32 s0, s22, s0
	s_addc_u32 s1, s23, s1
	s_lshr_b32 s5, s33, 1
	v_and_b32_e32 v11, 31, v8
	s_and_b32 s5, s5, 0xfffff80
	v_or_b32_e32 v12, s5, v11
	v_or_b32_e32 v11, s4, v11
	v_add3_u32 v148, 16, v10, v9
	v_lshrrev_b32_e32 v8, 1, v8
	v_mul_u32_u24_e32 v150, 0x90, v11
	v_lshl_add_u64 v[130:131], s[2:3], 0, v[192:193]
	v_lshl_add_u64 v[128:129], s[0:1], 0, v[192:193]
	v_and_b32_e32 v204, 16, v8
	v_add_u32_e32 v192, 0x12000, v148
	v_mul_lo_u32 v149, v12, s45
	v_add3_u32 v152, 16, v150, v204
	v_add_u32_e32 v159, 0x1b000, v148
	ds_write_b128 v192, v[0:3]
	s_waitcnt vmcnt(5)
	ds_write_b128 v159, v[4:7]
	v_add3_u32 v151, 16, v149, v204
	ds_read_b128 v[0:3], v152 offset:36864
	ds_read_b128 v[4:7], v152 offset:41472
	ds_read_b128 v[8:11], v151
	ds_read_b128 v[12:15], v151 offset:4608
	v_lshl_add_u64 v[140:141], v[136:137], 0, s[34:35]
	v_lshl_add_u64 v[142:143], v[138:139], 0, s[34:35]
	v_lshl_add_u64 v[132:133], v[136:137], 0, s[42:43]
	v_lshl_add_u64 v[134:135], v[138:139], 0, s[42:43]
	s_setprio 1
	s_waitcnt lgkmcnt(1)
	v_mfma_f32_32x32x16_bf16 v[112:127], v[0:3], v[8:11], 0
	v_mfma_f32_32x32x16_bf16 v[48:63], v[4:7], v[8:11], 0
	s_waitcnt lgkmcnt(0)
	v_mfma_f32_32x32x16_bf16 v[96:111], v[0:3], v[12:15], 0
	v_mfma_f32_32x32x16_bf16 v[32:47], v[4:7], v[12:15], 0
	ds_read_b128 v[8:11], v151 offset:9216
	ds_read_b128 v[12:15], v151 offset:13824
	s_waitcnt lgkmcnt(1)
	v_mfma_f32_32x32x16_bf16 v[80:95], v[0:3], v[8:11], 0
	v_mfma_f32_32x32x16_bf16 v[16:31], v[4:7], v[8:11], 0
	s_waitcnt lgkmcnt(0)
	v_mfma_f32_32x32x16_bf16 v[64:79], v[0:3], v[12:15], 0
	v_mfma_f32_32x32x16_bf16 v[0:15], v[4:7], v[12:15], 0
	s_setprio 0
	global_load_dwordx4 v[194:197], v[140:141], off offset:256
	global_load_dwordx4 v[198:201], v[142:143], off offset:256
	v_add_u32_e32 v158, 0x14400, v148
	v_add_u32_e32 v157, 0x1d400, v148
	ds_write_b128 v158, v[176:179]
	s_waitcnt vmcnt(6)
	ds_write_b128 v157, v[180:183]
	ds_read_b128 v[144:147], v152 offset:36896
	ds_read_b128 v[176:179], v152 offset:41504
	ds_read_b128 v[180:183], v151 offset:32
	ds_read_b128 v[208:211], v151 offset:4640
	s_setprio 1
	s_waitcnt lgkmcnt(1)
	v_mfma_f32_32x32x16_bf16 v[112:127], v[144:147], v[180:183], v[112:127]
	v_mfma_f32_32x32x16_bf16 v[48:63], v[176:179], v[180:183], v[48:63]
	s_waitcnt lgkmcnt(0)
	v_mfma_f32_32x32x16_bf16 v[96:111], v[144:147], v[208:211], v[96:111]
	v_mfma_f32_32x32x16_bf16 v[32:47], v[176:179], v[208:211], v[32:47]
	ds_read_b128 v[180:183], v151 offset:9248
	ds_read_b128 v[208:211], v151 offset:13856
	s_waitcnt lgkmcnt(1)
	v_mfma_f32_32x32x16_bf16 v[80:95], v[144:147], v[180:183], v[80:95]
	v_mfma_f32_32x32x16_bf16 v[16:31], v[176:179], v[180:183], v[16:31]
	s_waitcnt lgkmcnt(0)
	v_mfma_f32_32x32x16_bf16 v[64:79], v[144:147], v[208:211], v[64:79]
	v_mfma_f32_32x32x16_bf16 v[0:15], v[176:179], v[208:211], v[0:15]
	s_setprio 0
	global_load_dwordx4 v[176:179], v[132:133], off offset:256
	global_load_dwordx4 v[180:183], v[134:135], off offset:256
	v_add_u32_e32 v154, 0x16800, v148
	v_add_u32_e32 v153, 0x1f800, v148
	ds_write_b128 v154, v[168:171]
	s_waitcnt vmcnt(7)
	ds_write_b128 v153, v[172:175]
	ds_read_b128 v[144:147], v152 offset:36928
	ds_read_b128 v[168:171], v152 offset:41536
	ds_read_b128 v[172:175], v151 offset:64
	ds_read_b128 v[208:211], v151 offset:4672
	s_setprio 1
	s_waitcnt lgkmcnt(1)
	v_mfma_f32_32x32x16_bf16 v[112:127], v[144:147], v[172:175], v[112:127]
	v_mfma_f32_32x32x16_bf16 v[48:63], v[168:171], v[172:175], v[48:63]
	s_waitcnt lgkmcnt(0)
	v_mfma_f32_32x32x16_bf16 v[96:111], v[144:147], v[208:211], v[96:111]
	v_mfma_f32_32x32x16_bf16 v[32:47], v[168:171], v[208:211], v[32:47]
	ds_read_b128 v[172:175], v151 offset:9280
	ds_read_b128 v[208:211], v151 offset:13888
	s_waitcnt lgkmcnt(1)
	v_mfma_f32_32x32x16_bf16 v[80:95], v[144:147], v[172:175], v[80:95]
	v_mfma_f32_32x32x16_bf16 v[16:31], v[168:171], v[172:175], v[16:31]
	s_waitcnt lgkmcnt(0)
	v_mfma_f32_32x32x16_bf16 v[64:79], v[144:147], v[208:211], v[64:79]
	v_mfma_f32_32x32x16_bf16 v[0:15], v[168:171], v[208:211], v[0:15]
	s_setprio 0
	v_add_co_u32_e32 v144, vcc, s44, v136
	v_add_u32_e32 v156, 0x18c00, v148
	s_nop 0
	v_addc_co_u32_e32 v145, vcc, 0, v137, vcc
	v_add_co_u32_e32 v146, vcc, s44, v138
	v_add_u32_e32 v155, 0x21c00, v148
	s_nop 0
	v_addc_co_u32_e32 v147, vcc, 0, v139, vcc
	global_load_dwordx4 v[168:171], v[144:145], off offset:256
	global_load_dwordx4 v[172:175], v[146:147], off offset:256
	ds_write_b128 v156, v[160:163]
	s_waitcnt vmcnt(8)
	ds_write_b128 v155, v[164:167]
	ds_read_b128 v[160:163], v152 offset:36960
	ds_read_b128 v[164:167], v152 offset:41568
	ds_read_b128 v[208:211], v151 offset:96
	ds_read_b128 v[212:215], v151 offset:4704
	s_setprio 1
	s_waitcnt lgkmcnt(1)
	v_mfma_f32_32x32x16_bf16 v[112:127], v[160:163], v[208:211], v[112:127]
	v_mfma_f32_32x32x16_bf16 v[48:63], v[164:167], v[208:211], v[48:63]
	s_waitcnt lgkmcnt(0)
	v_mfma_f32_32x32x16_bf16 v[96:111], v[160:163], v[212:215], v[96:111]
	v_mfma_f32_32x32x16_bf16 v[32:47], v[164:167], v[212:215], v[32:47]
	ds_read_b128 v[208:211], v151 offset:9312
	ds_read_b128 v[212:215], v151 offset:13920
	s_waitcnt lgkmcnt(1)
	v_mfma_f32_32x32x16_bf16 v[80:95], v[160:163], v[208:211], v[80:95]
	v_mfma_f32_32x32x16_bf16 v[16:31], v[164:167], v[208:211], v[16:31]
	s_waitcnt lgkmcnt(0)
	v_mfma_f32_32x32x16_bf16 v[64:79], v[160:163], v[212:215], v[64:79]
	v_mfma_f32_32x32x16_bf16 v[0:15], v[164:167], v[212:215], v[0:15]
	s_setprio 0
	global_load_dwordx4 v[160:163], v[136:137], off offset:384
	global_load_dwordx4 v[164:167], v[138:139], off offset:384
	s_barrier
; template <bool trans>
; DI void gemm_core(const GTile& tl, const GTile& nx, bool has_next  , bool chain  , bool pre, u32x4 (&ra)[4], u32x4 (&rb)[4], char* smem, f32x16 (&acc)[2][4]) {
;     ...
;   const int nk = K / 64;
;   if (!pre) { G_LOAD(0); G_STORE(0); G_LOAD(1); }
;   for (int kt = 0; kt < nk; ++kt) {
;     __syncthreads();
;     G_COMPUTE(kt & 1, kt);
;   }
	s_add_i32 s0, 16, 0x12000
	v_add3_u32 v149, s0, v149, v204
	s_add_i32 s0, 16, 0x1b000
	v_add3_u32 v150, s0, v150, v204
	s_waitcnt vmcnt(9)
	ds_write_b128 v148, v[184:187]
	s_waitcnt vmcnt(8)
	ds_write_b128 v148, v[188:191] offset:36864
	ds_read_b128 v[184:187], v150
	ds_read_b128 v[188:191], v150 offset:4608
	ds_read_b128 v[208:211], v149
	ds_read_b128 v[212:215], v149 offset:4608
	s_setprio 1
	s_waitcnt lgkmcnt(1)
	v_mfma_f32_32x32x16_bf16 v[112:127], v[184:187], v[208:211], v[112:127]
	v_mfma_f32_32x32x16_bf16 v[48:63], v[188:191], v[208:211], v[48:63]
	s_waitcnt lgkmcnt(0)
	v_mfma_f32_32x32x16_bf16 v[96:111], v[184:187], v[212:215], v[96:111]
	v_mfma_f32_32x32x16_bf16 v[32:47], v[188:191], v[212:215], v[32:47]
	ds_read_b128 v[208:211], v149 offset:9216
	ds_read_b128 v[212:215], v149 offset:13824
	s_waitcnt lgkmcnt(1)
	v_mfma_f32_32x32x16_bf16 v[80:95], v[184:187], v[208:211], v[80:95]
	v_mfma_f32_32x32x16_bf16 v[16:31], v[188:191], v[208:211], v[16:31]
	s_waitcnt lgkmcnt(0)
	v_mfma_f32_32x32x16_bf16 v[64:79], v[184:187], v[212:215], v[64:79]
	v_mfma_f32_32x32x16_bf16 v[0:15], v[188:191], v[212:215], v[0:15]
	s_setprio 0
	global_load_dwordx4 v[184:187], v[140:141], off offset:384
	global_load_dwordx4 v[188:191], v[142:143], off offset:384
	s_waitcnt vmcnt(9)
	ds_write_b128 v148, v[194:197] offset:9216
	s_waitcnt vmcnt(8)
	ds_write_b128 v148, v[198:201] offset:46080
	ds_read_b128 v[194:197], v150 offset:32
	ds_read_b128 v[198:201], v150 offset:4640
	ds_read_b128 v[208:211], v149 offset:32
	ds_read_b128 v[212:215], v149 offset:4640
	s_setprio 1
	s_waitcnt lgkmcnt(1)
	v_mfma_f32_32x32x16_bf16 v[112:127], v[194:197], v[208:211], v[112:127]
	v_mfma_f32_32x32x16_bf16 v[48:63], v[198:201], v[208:211], v[48:63]
	s_waitcnt lgkmcnt(0)
	v_mfma_f32_32x32x16_bf16 v[96:111], v[194:197], v[212:215], v[96:111]
	v_mfma_f32_32x32x16_bf16 v[32:47], v[198:201], v[212:215], v[32:47]
	ds_read_b128 v[208:211], v149 offset:9248
	ds_read_b128 v[212:215], v149 offset:13856
	s_waitcnt lgkmcnt(1)
	v_mfma_f32_32x32x16_bf16 v[80:95], v[194:197], v[208:211], v[80:95]
	v_mfma_f32_32x32x16_bf16 v[16:31], v[198:201], v[208:211], v[16:31]
	s_waitcnt lgkmcnt(0)
	v_mfma_f32_32x32x16_bf16 v[64:79], v[194:197], v[212:215], v[64:79]
	v_mfma_f32_32x32x16_bf16 v[0:15], v[198:201], v[212:215], v[0:15]
	s_setprio 0
	global_load_dwordx4 v[194:197], v[132:133], off offset:384
	global_load_dwordx4 v[198:201], v[134:135], off offset:384
	s_waitcnt vmcnt(9)
	ds_write_b128 v148, v[176:179] offset:18432
	s_waitcnt vmcnt(8)
	ds_write_b128 v148, v[180:183] offset:55296
	ds_read_b128 v[176:179], v150 offset:64
	ds_read_b128 v[180:183], v150 offset:4672
	ds_read_b128 v[208:211], v149 offset:64
	ds_read_b128 v[212:215], v149 offset:4672
	s_setprio 1
	s_waitcnt lgkmcnt(1)
	v_mfma_f32_32x32x16_bf16 v[112:127], v[176:179], v[208:211], v[112:127]
	v_mfma_f32_32x32x16_bf16 v[48:63], v[180:183], v[208:211], v[48:63]
	s_waitcnt lgkmcnt(0)
	v_mfma_f32_32x32x16_bf16 v[96:111], v[176:179], v[212:215], v[96:111]
	v_mfma_f32_32x32x16_bf16 v[32:47], v[180:183], v[212:215], v[32:47]
	ds_read_b128 v[208:211], v149 offset:9280
	ds_read_b128 v[212:215], v149 offset:13888
	s_waitcnt lgkmcnt(1)
	v_mfma_f32_32x32x16_bf16 v[80:95], v[176:179], v[208:211], v[80:95]
	v_mfma_f32_32x32x16_bf16 v[16:31], v[180:183], v[208:211], v[16:31]
	s_waitcnt lgkmcnt(0)
	v_mfma_f32_32x32x16_bf16 v[64:79], v[176:179], v[212:215], v[64:79]
	v_mfma_f32_32x32x16_bf16 v[0:15], v[180:183], v[212:215], v[0:15]
	s_setprio 0
	global_load_dwordx4 v[176:179], v[144:145], off offset:384
	global_load_dwordx4 v[180:183], v[146:147], off offset:384
	s_waitcnt vmcnt(9)
	ds_write_b128 v148, v[168:171] offset:27648
	s_waitcnt vmcnt(8)
	ds_write_b128 v148, v[172:175] offset:64512
	ds_read_b128 v[168:171], v150 offset:96
	ds_read_b128 v[172:175], v150 offset:4704
	ds_read_b128 v[208:211], v149 offset:96
	ds_read_b128 v[212:215], v149 offset:4704
	s_setprio 1
	s_waitcnt lgkmcnt(1)
	v_mfma_f32_32x32x16_bf16 v[112:127], v[168:171], v[208:211], v[112:127]
	v_mfma_f32_32x32x16_bf16 v[48:63], v[172:175], v[208:211], v[48:63]
	s_waitcnt lgkmcnt(0)
	v_mfma_f32_32x32x16_bf16 v[96:111], v[168:171], v[212:215], v[96:111]
	v_mfma_f32_32x32x16_bf16 v[32:47], v[172:175], v[212:215], v[32:47]
	ds_read_b128 v[208:211], v149 offset:9312
	ds_read_b128 v[212:215], v149 offset:13920
	s_waitcnt lgkmcnt(1)
	v_mfma_f32_32x32x16_bf16 v[80:95], v[168:171], v[208:211], v[80:95]
	v_mfma_f32_32x32x16_bf16 v[16:31], v[172:175], v[208:211], v[16:31]
	s_waitcnt lgkmcnt(0)
	v_mfma_f32_32x32x16_bf16 v[64:79], v[168:171], v[212:215], v[64:79]
	v_mfma_f32_32x32x16_bf16 v[0:15], v[172:175], v[212:215], v[0:15]
	s_setprio 0
	global_load_dwordx4 v[168:171], v[136:137], off offset:512
	global_load_dwordx4 v[172:175], v[138:139], off offset:512
	s_barrier
; template <bool trans>
; DI void gemm_core(const GTile& tl, const GTile& nx, bool has_next  , bool chain  , bool pre, u32x4 (&ra)[4], u32x4 (&rb)[4], char* smem, f32x16 (&acc)[2][4]) {
;     ...
;   const int nk = K / 64;
;   if (!pre) { G_LOAD(0); G_STORE(0); G_LOAD(1); }
;   for (int kt = 0; kt < nk; ++kt) {
;     __syncthreads();
;     G_COMPUTE(kt & 1, kt);
;   }
	s_waitcnt vmcnt(9)
	ds_write_b128 v192, v[160:163]
	s_waitcnt vmcnt(8)
	ds_write_b128 v159, v[164:167]
	ds_read_b128 v[160:163], v152 offset:36864
	ds_read_b128 v[164:167], v152 offset:41472
	ds_read_b128 v[208:211], v151
	ds_read_b128 v[212:215], v151 offset:4608
	s_setprio 1
	s_waitcnt lgkmcnt(1)
	v_mfma_f32_32x32x16_bf16 v[112:127], v[160:163], v[208:211], v[112:127]
	v_mfma_f32_32x32x16_bf16 v[48:63], v[164:167], v[208:211], v[48:63]
	s_waitcnt lgkmcnt(0)
	v_mfma_f32_32x32x16_bf16 v[96:111], v[160:163], v[212:215], v[96:111]
	v_mfma_f32_32x32x16_bf16 v[32:47], v[164:167], v[212:215], v[32:47]
	ds_read_b128 v[208:211], v151 offset:9216
	ds_read_b128 v[212:215], v151 offset:13824
	s_waitcnt vmcnt(7)
	ds_write_b128 v158, v[184:187]
	s_waitcnt vmcnt(6)
	ds_write_b128 v157, v[188:191]
	ds_read_b128 v[184:187], v152 offset:36896
	ds_read_b128 v[188:191], v152 offset:41504
	s_waitcnt lgkmcnt(5)
	v_mfma_f32_32x32x16_bf16 v[80:95], v[160:163], v[208:211], v[80:95]
	v_mfma_f32_32x32x16_bf16 v[16:31], v[164:167], v[208:211], v[16:31]
	ds_read_b128 v[208:211], v151 offset:32
	s_waitcnt lgkmcnt(5)
	v_mfma_f32_32x32x16_bf16 v[64:79], v[160:163], v[212:215], v[64:79]
	v_mfma_f32_32x32x16_bf16 v[0:15], v[164:167], v[212:215], v[0:15]
	ds_read_b128 v[212:215], v151 offset:4640
	s_setprio 0
	global_load_dwordx4 v[160:163], v[140:141], off offset:512
	global_load_dwordx4 v[164:167], v[142:143], off offset:512
	s_setprio 1
	s_waitcnt lgkmcnt(1)
	v_mfma_f32_32x32x16_bf16 v[112:127], v[184:187], v[208:211], v[112:127]
	v_mfma_f32_32x32x16_bf16 v[48:63], v[188:191], v[208:211], v[48:63]
	s_waitcnt lgkmcnt(0)
	v_mfma_f32_32x32x16_bf16 v[96:111], v[184:187], v[212:215], v[96:111]
	v_mfma_f32_32x32x16_bf16 v[32:47], v[188:191], v[212:215], v[32:47]
	ds_read_b128 v[208:211], v151 offset:9248
	ds_read_b128 v[212:215], v151 offset:13856
	s_waitcnt vmcnt(7)
	ds_write_b128 v154, v[194:197]
	s_waitcnt vmcnt(6)
	ds_write_b128 v153, v[198:201]
	ds_read_b128 v[194:197], v152 offset:36928
	ds_read_b128 v[198:201], v152 offset:41536
	s_waitcnt lgkmcnt(5)
	v_mfma_f32_32x32x16_bf16 v[80:95], v[184:187], v[208:211], v[80:95]
	v_mfma_f32_32x32x16_bf16 v[16:31], v[188:191], v[208:211], v[16:31]
	ds_read_b128 v[208:211], v151 offset:64
	s_waitcnt lgkmcnt(5)
	v_mfma_f32_32x32x16_bf16 v[64:79], v[184:187], v[212:215], v[64:79]
	v_mfma_f32_32x32x16_bf16 v[0:15], v[188:191], v[212:215], v[0:15]
	ds_read_b128 v[212:215], v151 offset:4672
	s_setprio 0
	global_load_dwordx4 v[184:187], v[132:133], off offset:512
	global_load_dwordx4 v[188:191], v[134:135], off offset:512
	s_setprio 1
	s_waitcnt lgkmcnt(1)
	v_mfma_f32_32x32x16_bf16 v[112:127], v[194:197], v[208:211], v[112:127]
	v_mfma_f32_32x32x16_bf16 v[48:63], v[198:201], v[208:211], v[48:63]
	s_waitcnt lgkmcnt(0)
	v_mfma_f32_32x32x16_bf16 v[96:111], v[194:197], v[212:215], v[96:111]
	v_mfma_f32_32x32x16_bf16 v[32:47], v[198:201], v[212:215], v[32:47]
	ds_read_b128 v[208:211], v151 offset:9280
	ds_read_b128 v[212:215], v151 offset:13888
	s_waitcnt vmcnt(7)
	ds_write_b128 v156, v[176:179]
	s_waitcnt vmcnt(6)
	ds_write_b128 v155, v[180:183]
	ds_read_b128 v[176:179], v152 offset:36960
	ds_read_b128 v[180:183], v152 offset:41568
	s_waitcnt lgkmcnt(5)
	v_mfma_f32_32x32x16_bf16 v[80:95], v[194:197], v[208:211], v[80:95]
	v_mfma_f32_32x32x16_bf16 v[16:31], v[198:201], v[208:211], v[16:31]
	ds_read_b128 v[208:211], v151 offset:96
	s_waitcnt lgkmcnt(5)
	v_mfma_f32_32x32x16_bf16 v[64:79], v[194:197], v[212:215], v[64:79]
	v_mfma_f32_32x32x16_bf16 v[0:15], v[198:201], v[212:215], v[0:15]
	ds_read_b128 v[212:215], v151 offset:4704
	s_setprio 0
	global_load_dwordx4 v[194:197], v[144:145], off offset:512
	global_load_dwordx4 v[198:201], v[146:147], off offset:512
	s_setprio 1
	s_waitcnt lgkmcnt(1)
	v_mfma_f32_32x32x16_bf16 v[112:127], v[176:179], v[208:211], v[112:127]
	v_mfma_f32_32x32x16_bf16 v[48:63], v[180:183], v[208:211], v[48:63]
	s_waitcnt lgkmcnt(0)
	v_mfma_f32_32x32x16_bf16 v[96:111], v[176:179], v[212:215], v[96:111]
	v_mfma_f32_32x32x16_bf16 v[32:47], v[180:183], v[212:215], v[32:47]
	ds_read_b128 v[208:211], v151 offset:9312
	ds_read_b128 v[212:215], v151 offset:13920
	s_waitcnt lgkmcnt(1)
	v_mfma_f32_32x32x16_bf16 v[80:95], v[176:179], v[208:211], v[80:95]
	v_mfma_f32_32x32x16_bf16 v[16:31], v[180:183], v[208:211], v[16:31]
	s_waitcnt lgkmcnt(0)
	v_mfma_f32_32x32x16_bf16 v[64:79], v[176:179], v[212:215], v[64:79]
	v_mfma_f32_32x32x16_bf16 v[0:15], v[180:183], v[212:215], v[0:15]
	s_setprio 0
	global_load_dwordx4 v[176:179], v[136:137], off offset:640
	global_load_dwordx4 v[180:183], v[138:139], off offset:640
	s_barrier
; template <bool trans>
; DI void gemm_core(const GTile& tl, const GTile& nx, bool has_next  , bool chain  , bool pre, u32x4 (&ra)[4], u32x4 (&rb)[4], char* smem, f32x16 (&acc)[2][4]) {
;     ...
;   const int nk = K / 64;
;   if (!pre) { G_LOAD(0); G_STORE(0); G_LOAD(1); }
;   for (int kt = 0; kt < nk; ++kt) {
;     __syncthreads();
;     G_COMPUTE(kt & 1, kt);
;   }
	s_waitcnt vmcnt(9)
	ds_write_b128 v148, v[168:171]
	s_waitcnt vmcnt(8)
	ds_write_b128 v148, v[172:175] offset:36864
	ds_read_b128 v[168:171], v150
	ds_read_b128 v[172:175], v150 offset:4608
	ds_read_b128 v[208:211], v149
	ds_read_b128 v[212:215], v149 offset:4608
	s_setprio 1
	s_waitcnt lgkmcnt(1)
	v_mfma_f32_32x32x16_bf16 v[112:127], v[168:171], v[208:211], v[112:127]
	v_mfma_f32_32x32x16_bf16 v[48:63], v[172:175], v[208:211], v[48:63]
	s_waitcnt lgkmcnt(0)
	v_mfma_f32_32x32x16_bf16 v[96:111], v[168:171], v[212:215], v[96:111]
	v_mfma_f32_32x32x16_bf16 v[32:47], v[172:175], v[212:215], v[32:47]
	ds_read_b128 v[208:211], v149 offset:9216
	ds_read_b128 v[212:215], v149 offset:13824
	s_waitcnt vmcnt(7)
	ds_write_b128 v148, v[160:163] offset:9216
	s_waitcnt vmcnt(6)
	ds_write_b128 v148, v[164:167] offset:46080
	ds_read_b128 v[160:163], v150 offset:32
	ds_read_b128 v[164:167], v150 offset:4640
	s_waitcnt lgkmcnt(5)
	v_mfma_f32_32x32x16_bf16 v[80:95], v[168:171], v[208:211], v[80:95]
	v_mfma_f32_32x32x16_bf16 v[16:31], v[172:175], v[208:211], v[16:31]
	ds_read_b128 v[208:211], v149 offset:32
	s_waitcnt lgkmcnt(5)
	v_mfma_f32_32x32x16_bf16 v[64:79], v[168:171], v[212:215], v[64:79]
	v_mfma_f32_32x32x16_bf16 v[0:15], v[172:175], v[212:215], v[0:15]
	ds_read_b128 v[212:215], v149 offset:4640
	s_setprio 0
	global_load_dwordx4 v[168:171], v[140:141], off offset:640
	global_load_dwordx4 v[172:175], v[142:143], off offset:640
	s_setprio 1
	s_waitcnt lgkmcnt(1)
	v_mfma_f32_32x32x16_bf16 v[112:127], v[160:163], v[208:211], v[112:127]
	v_mfma_f32_32x32x16_bf16 v[48:63], v[164:167], v[208:211], v[48:63]
	s_waitcnt lgkmcnt(0)
	v_mfma_f32_32x32x16_bf16 v[96:111], v[160:163], v[212:215], v[96:111]
	v_mfma_f32_32x32x16_bf16 v[32:47], v[164:167], v[212:215], v[32:47]
	ds_read_b128 v[208:211], v149 offset:9248
	ds_read_b128 v[212:215], v149 offset:13856
	s_waitcnt vmcnt(7)
	ds_write_b128 v148, v[184:187] offset:18432
	s_waitcnt vmcnt(6)
	ds_write_b128 v148, v[188:191] offset:55296
	ds_read_b128 v[184:187], v150 offset:64
	ds_read_b128 v[188:191], v150 offset:4672
	s_waitcnt lgkmcnt(5)
	v_mfma_f32_32x32x16_bf16 v[80:95], v[160:163], v[208:211], v[80:95]
	v_mfma_f32_32x32x16_bf16 v[16:31], v[164:167], v[208:211], v[16:31]
	ds_read_b128 v[208:211], v149 offset:64
	s_waitcnt lgkmcnt(5)
	v_mfma_f32_32x32x16_bf16 v[64:79], v[160:163], v[212:215], v[64:79]
	v_mfma_f32_32x32x16_bf16 v[0:15], v[164:167], v[212:215], v[0:15]
	ds_read_b128 v[212:215], v149 offset:4672
	s_setprio 0
	global_load_dwordx4 v[160:163], v[132:133], off offset:640
	global_load_dwordx4 v[164:167], v[134:135], off offset:640
	s_setprio 1
	s_waitcnt lgkmcnt(1)
	v_mfma_f32_32x32x16_bf16 v[112:127], v[184:187], v[208:211], v[112:127]
	v_mfma_f32_32x32x16_bf16 v[48:63], v[188:191], v[208:211], v[48:63]
	s_waitcnt lgkmcnt(0)
	v_mfma_f32_32x32x16_bf16 v[96:111], v[184:187], v[212:215], v[96:111]
	v_mfma_f32_32x32x16_bf16 v[32:47], v[188:191], v[212:215], v[32:47]
	ds_read_b128 v[208:211], v149 offset:9280
	ds_read_b128 v[212:215], v149 offset:13888
	s_waitcnt vmcnt(7)
	ds_write_b128 v148, v[194:197] offset:27648
	s_waitcnt vmcnt(6)
	ds_write_b128 v148, v[198:201] offset:64512
	ds_read_b128 v[194:197], v150 offset:96
	ds_read_b128 v[198:201], v150 offset:4704
	s_waitcnt lgkmcnt(5)
	v_mfma_f32_32x32x16_bf16 v[80:95], v[184:187], v[208:211], v[80:95]
	v_mfma_f32_32x32x16_bf16 v[16:31], v[188:191], v[208:211], v[16:31]
	ds_read_b128 v[208:211], v149 offset:96
	s_waitcnt lgkmcnt(5)
	v_mfma_f32_32x32x16_bf16 v[64:79], v[184:187], v[212:215], v[64:79]
	v_mfma_f32_32x32x16_bf16 v[0:15], v[188:191], v[212:215], v[0:15]
	ds_read_b128 v[212:215], v149 offset:4704
	s_setprio 0
	global_load_dwordx4 v[184:187], v[144:145], off offset:640
	global_load_dwordx4 v[188:191], v[146:147], off offset:640
	s_setprio 1
	s_waitcnt lgkmcnt(1)
	v_mfma_f32_32x32x16_bf16 v[112:127], v[194:197], v[208:211], v[112:127]
	v_mfma_f32_32x32x16_bf16 v[48:63], v[198:201], v[208:211], v[48:63]
	s_waitcnt lgkmcnt(0)
	v_mfma_f32_32x32x16_bf16 v[96:111], v[194:197], v[212:215], v[96:111]
	v_mfma_f32_32x32x16_bf16 v[32:47], v[198:201], v[212:215], v[32:47]
	ds_read_b128 v[208:211], v149 offset:9312
	ds_read_b128 v[212:215], v149 offset:13920
	s_waitcnt lgkmcnt(1)
	v_mfma_f32_32x32x16_bf16 v[80:95], v[194:197], v[208:211], v[80:95]
	v_mfma_f32_32x32x16_bf16 v[16:31], v[198:201], v[208:211], v[16:31]
	s_waitcnt lgkmcnt(0)
	v_mfma_f32_32x32x16_bf16 v[64:79], v[194:197], v[212:215], v[64:79]
	v_mfma_f32_32x32x16_bf16 v[0:15], v[198:201], v[212:215], v[0:15]
	s_setprio 0
	global_load_dwordx4 v[194:197], v[136:137], off offset:768
	global_load_dwordx4 v[198:201], v[138:139], off offset:768
	s_barrier
; template <bool trans>
; DI void gemm_core(const GTile& tl, const GTile& nx, bool has_next  , bool chain  , bool pre, u32x4 (&ra)[4], u32x4 (&rb)[4], char* smem, f32x16 (&acc)[2][4]) {
;     ...
;   const int nk = K / 64;
;   if (!pre) { G_LOAD(0); G_STORE(0); G_LOAD(1); }
;   for (int kt = 0; kt < nk; ++kt) {
;     __syncthreads();
;     G_COMPUTE(kt & 1, kt);
;   }
	s_waitcnt vmcnt(9)
	ds_write_b128 v192, v[176:179]
	s_waitcnt vmcnt(8)
	ds_write_b128 v159, v[180:183]
	ds_read_b128 v[176:179], v152 offset:36864
	ds_read_b128 v[180:183], v152 offset:41472
	ds_read_b128 v[208:211], v151
	ds_read_b128 v[212:215], v151 offset:4608
	s_setprio 1
	s_waitcnt lgkmcnt(1)
	v_mfma_f32_32x32x16_bf16 v[112:127], v[176:179], v[208:211], v[112:127]
	v_mfma_f32_32x32x16_bf16 v[48:63], v[180:183], v[208:211], v[48:63]
	s_waitcnt lgkmcnt(0)
	v_mfma_f32_32x32x16_bf16 v[96:111], v[176:179], v[212:215], v[96:111]
	v_mfma_f32_32x32x16_bf16 v[32:47], v[180:183], v[212:215], v[32:47]
	ds_read_b128 v[208:211], v151 offset:9216
	ds_read_b128 v[212:215], v151 offset:13824
	s_waitcnt vmcnt(7)
	ds_write_b128 v158, v[168:171]
	s_waitcnt vmcnt(6)
	ds_write_b128 v157, v[172:175]
	ds_read_b128 v[168:171], v152 offset:36896
	ds_read_b128 v[172:175], v152 offset:41504
	s_waitcnt lgkmcnt(5)
	v_mfma_f32_32x32x16_bf16 v[80:95], v[176:179], v[208:211], v[80:95]
	v_mfma_f32_32x32x16_bf16 v[16:31], v[180:183], v[208:211], v[16:31]
	ds_read_b128 v[208:211], v151 offset:32
	s_waitcnt lgkmcnt(5)
	v_mfma_f32_32x32x16_bf16 v[64:79], v[176:179], v[212:215], v[64:79]
	v_mfma_f32_32x32x16_bf16 v[0:15], v[180:183], v[212:215], v[0:15]
	ds_read_b128 v[212:215], v151 offset:4640
	s_setprio 0
	global_load_dwordx4 v[176:179], v[140:141], off offset:768
	global_load_dwordx4 v[180:183], v[142:143], off offset:768
	s_setprio 1
	s_waitcnt lgkmcnt(1)
	v_mfma_f32_32x32x16_bf16 v[112:127], v[168:171], v[208:211], v[112:127]
	v_mfma_f32_32x32x16_bf16 v[48:63], v[172:175], v[208:211], v[48:63]
	s_waitcnt lgkmcnt(0)
	v_mfma_f32_32x32x16_bf16 v[96:111], v[168:171], v[212:215], v[96:111]
	v_mfma_f32_32x32x16_bf16 v[32:47], v[172:175], v[212:215], v[32:47]
	ds_read_b128 v[208:211], v151 offset:9248
	ds_read_b128 v[212:215], v151 offset:13856
	s_waitcnt vmcnt(7)
	ds_write_b128 v154, v[160:163]
	s_waitcnt vmcnt(6)
	ds_write_b128 v153, v[164:167]
	ds_read_b128 v[160:163], v152 offset:36928
	ds_read_b128 v[164:167], v152 offset:41536
	s_waitcnt lgkmcnt(5)
	v_mfma_f32_32x32x16_bf16 v[80:95], v[168:171], v[208:211], v[80:95]
	v_mfma_f32_32x32x16_bf16 v[16:31], v[172:175], v[208:211], v[16:31]
	ds_read_b128 v[208:211], v151 offset:64
	s_waitcnt lgkmcnt(5)
	v_mfma_f32_32x32x16_bf16 v[64:79], v[168:171], v[212:215], v[64:79]
	v_mfma_f32_32x32x16_bf16 v[0:15], v[172:175], v[212:215], v[0:15]
	ds_read_b128 v[212:215], v151 offset:4672
	s_setprio 0
	global_load_dwordx4 v[168:171], v[132:133], off offset:768
	global_load_dwordx4 v[172:175], v[134:135], off offset:768
	s_setprio 1
	s_waitcnt lgkmcnt(1)
	v_mfma_f32_32x32x16_bf16 v[112:127], v[160:163], v[208:211], v[112:127]
	v_mfma_f32_32x32x16_bf16 v[48:63], v[164:167], v[208:211], v[48:63]
	s_waitcnt lgkmcnt(0)
	v_mfma_f32_32x32x16_bf16 v[96:111], v[160:163], v[212:215], v[96:111]
	v_mfma_f32_32x32x16_bf16 v[32:47], v[164:167], v[212:215], v[32:47]
	ds_read_b128 v[208:211], v151 offset:9280
	ds_read_b128 v[212:215], v151 offset:13888
	s_waitcnt vmcnt(7)
	ds_write_b128 v156, v[184:187]
	s_waitcnt vmcnt(6)
	ds_write_b128 v155, v[188:191]
	ds_read_b128 v[184:187], v152 offset:36960
	ds_read_b128 v[188:191], v152 offset:41568
	s_waitcnt lgkmcnt(5)
	v_mfma_f32_32x32x16_bf16 v[80:95], v[160:163], v[208:211], v[80:95]
	v_mfma_f32_32x32x16_bf16 v[16:31], v[164:167], v[208:211], v[16:31]
	ds_read_b128 v[208:211], v151 offset:96
	s_waitcnt lgkmcnt(5)
	v_mfma_f32_32x32x16_bf16 v[64:79], v[160:163], v[212:215], v[64:79]
	v_mfma_f32_32x32x16_bf16 v[0:15], v[164:167], v[212:215], v[0:15]
	ds_read_b128 v[212:215], v151 offset:4704
	s_setprio 0
	global_load_dwordx4 v[160:163], v[144:145], off offset:768
	global_load_dwordx4 v[164:167], v[146:147], off offset:768
	s_setprio 1
	s_waitcnt lgkmcnt(1)
	v_mfma_f32_32x32x16_bf16 v[112:127], v[184:187], v[208:211], v[112:127]
	v_mfma_f32_32x32x16_bf16 v[48:63], v[188:191], v[208:211], v[48:63]
	s_waitcnt lgkmcnt(0)
	v_mfma_f32_32x32x16_bf16 v[96:111], v[184:187], v[212:215], v[96:111]
	v_mfma_f32_32x32x16_bf16 v[32:47], v[188:191], v[212:215], v[32:47]
	ds_read_b128 v[208:211], v151 offset:9312
	ds_read_b128 v[212:215], v151 offset:13920
	s_waitcnt lgkmcnt(1)
	v_mfma_f32_32x32x16_bf16 v[80:95], v[184:187], v[208:211], v[80:95]
	v_mfma_f32_32x32x16_bf16 v[16:31], v[188:191], v[208:211], v[16:31]
	s_waitcnt lgkmcnt(0)
	v_mfma_f32_32x32x16_bf16 v[64:79], v[184:187], v[212:215], v[64:79]
	v_mfma_f32_32x32x16_bf16 v[0:15], v[188:191], v[212:215], v[0:15]
	s_setprio 0
	global_load_dwordx4 v[184:187], v[136:137], off offset:896
	global_load_dwordx4 v[188:191], v[138:139], off offset:896
	s_barrier
; template <bool trans>
; DI void gemm_core(const GTile& tl, const GTile& nx, bool has_next  , bool chain  , bool pre, u32x4 (&ra)[4], u32x4 (&rb)[4], char* smem, f32x16 (&acc)[2][4]) {
;     ...
;   const int nk = K / 64;
;   if (!pre) { G_LOAD(0); G_STORE(0); G_LOAD(1); }
;   for (int kt = 0; kt < nk; ++kt) {
;     __syncthreads();
;     G_COMPUTE(kt & 1, kt);
;   }
	s_waitcnt vmcnt(9)
	ds_write_b128 v148, v[194:197]
	s_waitcnt vmcnt(8)
	ds_write_b128 v148, v[198:201] offset:36864
	ds_read_b128 v[194:197], v150
	ds_read_b128 v[198:201], v150 offset:4608
	ds_read_b128 v[208:211], v149
	ds_read_b128 v[212:215], v149 offset:4608
	s_setprio 1
	s_waitcnt lgkmcnt(1)
	v_mfma_f32_32x32x16_bf16 v[112:127], v[194:197], v[208:211], v[112:127]
	v_mfma_f32_32x32x16_bf16 v[48:63], v[198:201], v[208:211], v[48:63]
	s_waitcnt lgkmcnt(0)
	v_mfma_f32_32x32x16_bf16 v[96:111], v[194:197], v[212:215], v[96:111]
	v_mfma_f32_32x32x16_bf16 v[32:47], v[198:201], v[212:215], v[32:47]
	ds_read_b128 v[208:211], v149 offset:9216
	ds_read_b128 v[212:215], v149 offset:13824
	s_waitcnt vmcnt(7)
	ds_write_b128 v148, v[176:179] offset:9216
	s_waitcnt vmcnt(6)
	ds_write_b128 v148, v[180:183] offset:46080
	ds_read_b128 v[176:179], v150 offset:32
	ds_read_b128 v[180:183], v150 offset:4640
	s_waitcnt lgkmcnt(5)
	v_mfma_f32_32x32x16_bf16 v[80:95], v[194:197], v[208:211], v[80:95]
	v_mfma_f32_32x32x16_bf16 v[16:31], v[198:201], v[208:211], v[16:31]
	ds_read_b128 v[208:211], v149 offset:32
	s_waitcnt lgkmcnt(5)
	v_mfma_f32_32x32x16_bf16 v[64:79], v[194:197], v[212:215], v[64:79]
	v_mfma_f32_32x32x16_bf16 v[0:15], v[198:201], v[212:215], v[0:15]
	ds_read_b128 v[212:215], v149 offset:4640
	s_setprio 0
	global_load_dwordx4 v[194:197], v[140:141], off offset:896
	global_load_dwordx4 v[198:201], v[142:143], off offset:896
	s_setprio 1
	s_waitcnt lgkmcnt(1)
	v_mfma_f32_32x32x16_bf16 v[112:127], v[176:179], v[208:211], v[112:127]
	v_mfma_f32_32x32x16_bf16 v[48:63], v[180:183], v[208:211], v[48:63]
	s_waitcnt lgkmcnt(0)
	v_mfma_f32_32x32x16_bf16 v[96:111], v[176:179], v[212:215], v[96:111]
	v_mfma_f32_32x32x16_bf16 v[32:47], v[180:183], v[212:215], v[32:47]
	ds_read_b128 v[208:211], v149 offset:9248
	ds_read_b128 v[212:215], v149 offset:13856
	s_waitcnt vmcnt(7)
	ds_write_b128 v148, v[168:171] offset:18432
	s_waitcnt vmcnt(6)
	ds_write_b128 v148, v[172:175] offset:55296
	ds_read_b128 v[168:171], v150 offset:64
	ds_read_b128 v[172:175], v150 offset:4672
	s_waitcnt lgkmcnt(5)
	v_mfma_f32_32x32x16_bf16 v[80:95], v[176:179], v[208:211], v[80:95]
	v_mfma_f32_32x32x16_bf16 v[16:31], v[180:183], v[208:211], v[16:31]
	ds_read_b128 v[208:211], v149 offset:64
	s_waitcnt lgkmcnt(5)
	v_mfma_f32_32x32x16_bf16 v[64:79], v[176:179], v[212:215], v[64:79]
	v_mfma_f32_32x32x16_bf16 v[0:15], v[180:183], v[212:215], v[0:15]
	ds_read_b128 v[212:215], v149 offset:4672
	s_setprio 0
	global_load_dwordx4 v[176:179], v[132:133], off offset:896
	global_load_dwordx4 v[180:183], v[134:135], off offset:896
	s_setprio 1
	s_waitcnt lgkmcnt(1)
	v_mfma_f32_32x32x16_bf16 v[112:127], v[168:171], v[208:211], v[112:127]
	v_mfma_f32_32x32x16_bf16 v[48:63], v[172:175], v[208:211], v[48:63]
	s_waitcnt lgkmcnt(0)
	v_mfma_f32_32x32x16_bf16 v[96:111], v[168:171], v[212:215], v[96:111]
	v_mfma_f32_32x32x16_bf16 v[32:47], v[172:175], v[212:215], v[32:47]
	ds_read_b128 v[208:211], v149 offset:9280
	ds_read_b128 v[212:215], v149 offset:13888
	s_waitcnt vmcnt(7)
	ds_write_b128 v148, v[160:163] offset:27648
	s_waitcnt vmcnt(6)
	ds_write_b128 v148, v[164:167] offset:64512
	ds_read_b128 v[160:163], v150 offset:96
	ds_read_b128 v[164:167], v150 offset:4704
	s_waitcnt lgkmcnt(5)
	v_mfma_f32_32x32x16_bf16 v[80:95], v[168:171], v[208:211], v[80:95]
	v_mfma_f32_32x32x16_bf16 v[16:31], v[172:175], v[208:211], v[16:31]
	ds_read_b128 v[208:211], v149 offset:96
	s_waitcnt lgkmcnt(5)
	v_mfma_f32_32x32x16_bf16 v[64:79], v[168:171], v[212:215], v[64:79]
	v_mfma_f32_32x32x16_bf16 v[0:15], v[172:175], v[212:215], v[0:15]
	ds_read_b128 v[212:215], v149 offset:4704
	s_setprio 0
	global_load_dwordx4 v[168:171], v[144:145], off offset:896
	global_load_dwordx4 v[172:175], v[146:147], off offset:896
	s_setprio 1
	s_waitcnt lgkmcnt(1)
	v_mfma_f32_32x32x16_bf16 v[112:127], v[160:163], v[208:211], v[112:127]
	v_mfma_f32_32x32x16_bf16 v[48:63], v[164:167], v[208:211], v[48:63]
	s_waitcnt lgkmcnt(0)
	v_mfma_f32_32x32x16_bf16 v[96:111], v[160:163], v[212:215], v[96:111]
	v_mfma_f32_32x32x16_bf16 v[32:47], v[164:167], v[212:215], v[32:47]
	ds_read_b128 v[208:211], v149 offset:9312
	ds_read_b128 v[212:215], v149 offset:13920
	s_waitcnt lgkmcnt(1)
	v_mfma_f32_32x32x16_bf16 v[80:95], v[160:163], v[208:211], v[80:95]
	v_mfma_f32_32x32x16_bf16 v[16:31], v[164:167], v[208:211], v[16:31]
	s_waitcnt lgkmcnt(0)
	v_mfma_f32_32x32x16_bf16 v[64:79], v[160:163], v[212:215], v[64:79]
	v_mfma_f32_32x32x16_bf16 v[0:15], v[164:167], v[212:215], v[0:15]
	s_setprio 0
	global_load_dwordx4 v[160:163], v[136:137], off offset:1024
	global_load_dwordx4 v[164:167], v[138:139], off offset:1024
	s_barrier
; template <bool trans>
; DI void gemm_core(const GTile& tl, const GTile& nx, bool has_next  , bool chain  , bool pre, u32x4 (&ra)[4], u32x4 (&rb)[4], char* smem, f32x16 (&acc)[2][4]) {
;     ...
;   const int nk = K / 64;
;   if (!pre) { G_LOAD(0); G_STORE(0); G_LOAD(1); }
;   for (int kt = 0; kt < nk; ++kt) {
;     __syncthreads();
;     G_COMPUTE(kt & 1, kt);
;   }
	s_waitcnt vmcnt(9)
	ds_write_b128 v192, v[184:187]
	s_waitcnt vmcnt(8)
	ds_write_b128 v159, v[188:191]
	ds_read_b128 v[184:187], v152 offset:36864
	ds_read_b128 v[188:191], v152 offset:41472
	ds_read_b128 v[208:211], v151
	ds_read_b128 v[212:215], v151 offset:4608
	s_setprio 1
	s_waitcnt lgkmcnt(1)
	v_mfma_f32_32x32x16_bf16 v[112:127], v[184:187], v[208:211], v[112:127]
	v_mfma_f32_32x32x16_bf16 v[48:63], v[188:191], v[208:211], v[48:63]
	s_waitcnt lgkmcnt(0)
	v_mfma_f32_32x32x16_bf16 v[96:111], v[184:187], v[212:215], v[96:111]
	v_mfma_f32_32x32x16_bf16 v[32:47], v[188:191], v[212:215], v[32:47]
	ds_read_b128 v[208:211], v151 offset:9216
	ds_read_b128 v[212:215], v151 offset:13824
	s_waitcnt vmcnt(7)
	ds_write_b128 v158, v[194:197]
	s_waitcnt vmcnt(6)
	ds_write_b128 v157, v[198:201]
	ds_read_b128 v[194:197], v152 offset:36896
	ds_read_b128 v[198:201], v152 offset:41504
	s_waitcnt lgkmcnt(5)
	v_mfma_f32_32x32x16_bf16 v[80:95], v[184:187], v[208:211], v[80:95]
	v_mfma_f32_32x32x16_bf16 v[16:31], v[188:191], v[208:211], v[16:31]
	ds_read_b128 v[208:211], v151 offset:32
	s_waitcnt lgkmcnt(5)
	v_mfma_f32_32x32x16_bf16 v[64:79], v[184:187], v[212:215], v[64:79]
	v_mfma_f32_32x32x16_bf16 v[0:15], v[188:191], v[212:215], v[0:15]
	ds_read_b128 v[212:215], v151 offset:4640
	s_setprio 0
	global_load_dwordx4 v[184:187], v[140:141], off offset:1024
	global_load_dwordx4 v[188:191], v[142:143], off offset:1024
	s_setprio 1
	s_waitcnt lgkmcnt(1)
	v_mfma_f32_32x32x16_bf16 v[112:127], v[194:197], v[208:211], v[112:127]
	v_mfma_f32_32x32x16_bf16 v[48:63], v[198:201], v[208:211], v[48:63]
	s_waitcnt lgkmcnt(0)
	v_mfma_f32_32x32x16_bf16 v[96:111], v[194:197], v[212:215], v[96:111]
	v_mfma_f32_32x32x16_bf16 v[32:47], v[198:201], v[212:215], v[32:47]
	ds_read_b128 v[208:211], v151 offset:9248
	ds_read_b128 v[212:215], v151 offset:13856
	s_waitcnt vmcnt(7)
	ds_write_b128 v154, v[176:179]
	s_waitcnt vmcnt(6)
	ds_write_b128 v153, v[180:183]
	ds_read_b128 v[176:179], v152 offset:36928
	ds_read_b128 v[180:183], v152 offset:41536
	s_waitcnt lgkmcnt(5)
	v_mfma_f32_32x32x16_bf16 v[80:95], v[194:197], v[208:211], v[80:95]
	v_mfma_f32_32x32x16_bf16 v[16:31], v[198:201], v[208:211], v[16:31]
	ds_read_b128 v[208:211], v151 offset:64
	s_waitcnt lgkmcnt(5)
	v_mfma_f32_32x32x16_bf16 v[64:79], v[194:197], v[212:215], v[64:79]
	v_mfma_f32_32x32x16_bf16 v[0:15], v[198:201], v[212:215], v[0:15]
	ds_read_b128 v[212:215], v151 offset:4672
	s_setprio 0
	global_load_dwordx4 v[194:197], v[132:133], off offset:1024
	global_load_dwordx4 v[198:201], v[134:135], off offset:1024
	s_setprio 1
	s_waitcnt lgkmcnt(1)
	v_mfma_f32_32x32x16_bf16 v[112:127], v[176:179], v[208:211], v[112:127]
	v_mfma_f32_32x32x16_bf16 v[48:63], v[180:183], v[208:211], v[48:63]
	s_waitcnt lgkmcnt(0)
	v_mfma_f32_32x32x16_bf16 v[96:111], v[176:179], v[212:215], v[96:111]
	v_mfma_f32_32x32x16_bf16 v[32:47], v[180:183], v[212:215], v[32:47]
	ds_read_b128 v[208:211], v151 offset:9280
	ds_read_b128 v[212:215], v151 offset:13888
	s_waitcnt vmcnt(7)
	ds_write_b128 v156, v[168:171]
	s_waitcnt vmcnt(6)
	ds_write_b128 v155, v[172:175]
	ds_read_b128 v[168:171], v152 offset:36960
	ds_read_b128 v[172:175], v152 offset:41568
	s_waitcnt lgkmcnt(5)
	v_mfma_f32_32x32x16_bf16 v[80:95], v[176:179], v[208:211], v[80:95]
	v_mfma_f32_32x32x16_bf16 v[16:31], v[180:183], v[208:211], v[16:31]
	ds_read_b128 v[208:211], v151 offset:96
	s_waitcnt lgkmcnt(5)
	v_mfma_f32_32x32x16_bf16 v[64:79], v[176:179], v[212:215], v[64:79]
	v_mfma_f32_32x32x16_bf16 v[0:15], v[180:183], v[212:215], v[0:15]
	ds_read_b128 v[212:215], v151 offset:4704
	s_setprio 0
	global_load_dwordx4 v[176:179], v[144:145], off offset:1024
	global_load_dwordx4 v[180:183], v[146:147], off offset:1024
	s_setprio 1
	s_waitcnt lgkmcnt(1)
	v_mfma_f32_32x32x16_bf16 v[112:127], v[168:171], v[208:211], v[112:127]
	v_mfma_f32_32x32x16_bf16 v[48:63], v[172:175], v[208:211], v[48:63]
	s_waitcnt lgkmcnt(0)
	v_mfma_f32_32x32x16_bf16 v[96:111], v[168:171], v[212:215], v[96:111]
	v_mfma_f32_32x32x16_bf16 v[32:47], v[172:175], v[212:215], v[32:47]
	ds_read_b128 v[208:211], v151 offset:9312
	ds_read_b128 v[212:215], v151 offset:13920
	s_waitcnt lgkmcnt(1)
	v_mfma_f32_32x32x16_bf16 v[80:95], v[168:171], v[208:211], v[80:95]
	v_mfma_f32_32x32x16_bf16 v[16:31], v[172:175], v[208:211], v[16:31]
	s_waitcnt lgkmcnt(0)
	v_mfma_f32_32x32x16_bf16 v[64:79], v[168:171], v[212:215], v[64:79]
	v_mfma_f32_32x32x16_bf16 v[0:15], v[172:175], v[212:215], v[0:15]
	s_setprio 0
	global_load_dwordx4 v[168:171], v[136:137], off offset:1152
	global_load_dwordx4 v[172:175], v[138:139], off offset:1152
	s_barrier
; template <bool trans>
; DI void gemm_core(const GTile& tl, const GTile& nx, bool has_next  , bool chain  , bool pre, u32x4 (&ra)[4], u32x4 (&rb)[4], char* smem, f32x16 (&acc)[2][4]) {
;     ...
;   const int nk = K / 64;
;   if (!pre) { G_LOAD(0); G_STORE(0); G_LOAD(1); }
;   for (int kt = 0; kt < nk; ++kt) {
;     __syncthreads();
;     G_COMPUTE(kt & 1, kt);
;   }
	s_waitcnt vmcnt(9)
	ds_write_b128 v148, v[160:163]
	s_waitcnt vmcnt(8)
	ds_write_b128 v148, v[164:167] offset:36864
	ds_read_b128 v[160:163], v150
	ds_read_b128 v[164:167], v150 offset:4608
	ds_read_b128 v[208:211], v149
	ds_read_b128 v[212:215], v149 offset:4608
	s_setprio 1
	s_waitcnt lgkmcnt(1)
	v_mfma_f32_32x32x16_bf16 v[112:127], v[160:163], v[208:211], v[112:127]
	v_mfma_f32_32x32x16_bf16 v[48:63], v[164:167], v[208:211], v[48:63]
	s_waitcnt lgkmcnt(0)
	v_mfma_f32_32x32x16_bf16 v[96:111], v[160:163], v[212:215], v[96:111]
	v_mfma_f32_32x32x16_bf16 v[32:47], v[164:167], v[212:215], v[32:47]
	ds_read_b128 v[208:211], v149 offset:9216
	ds_read_b128 v[212:215], v149 offset:13824
	s_waitcnt vmcnt(7)
	ds_write_b128 v148, v[184:187] offset:9216
	s_waitcnt vmcnt(6)
	ds_write_b128 v148, v[188:191] offset:46080
	ds_read_b128 v[184:187], v150 offset:32
	ds_read_b128 v[188:191], v150 offset:4640
	s_waitcnt lgkmcnt(5)
	v_mfma_f32_32x32x16_bf16 v[80:95], v[160:163], v[208:211], v[80:95]
	v_mfma_f32_32x32x16_bf16 v[16:31], v[164:167], v[208:211], v[16:31]
	ds_read_b128 v[208:211], v149 offset:32
	s_waitcnt lgkmcnt(5)
	v_mfma_f32_32x32x16_bf16 v[64:79], v[160:163], v[212:215], v[64:79]
	v_mfma_f32_32x32x16_bf16 v[0:15], v[164:167], v[212:215], v[0:15]
	ds_read_b128 v[212:215], v149 offset:4640
	s_setprio 0
	global_load_dwordx4 v[160:163], v[140:141], off offset:1152
	global_load_dwordx4 v[164:167], v[142:143], off offset:1152
	s_setprio 1
	s_waitcnt lgkmcnt(1)
	v_mfma_f32_32x32x16_bf16 v[112:127], v[184:187], v[208:211], v[112:127]
	v_mfma_f32_32x32x16_bf16 v[48:63], v[188:191], v[208:211], v[48:63]
	s_waitcnt lgkmcnt(0)
	v_mfma_f32_32x32x16_bf16 v[96:111], v[184:187], v[212:215], v[96:111]
	v_mfma_f32_32x32x16_bf16 v[32:47], v[188:191], v[212:215], v[32:47]
	ds_read_b128 v[208:211], v149 offset:9248
	ds_read_b128 v[212:215], v149 offset:13856
	s_waitcnt vmcnt(7)
	ds_write_b128 v148, v[194:197] offset:18432
	s_waitcnt vmcnt(6)
	ds_write_b128 v148, v[198:201] offset:55296
	ds_read_b128 v[194:197], v150 offset:64
	ds_read_b128 v[198:201], v150 offset:4672
	s_waitcnt lgkmcnt(5)
	v_mfma_f32_32x32x16_bf16 v[80:95], v[184:187], v[208:211], v[80:95]
	v_mfma_f32_32x32x16_bf16 v[16:31], v[188:191], v[208:211], v[16:31]
	ds_read_b128 v[208:211], v149 offset:64
	s_waitcnt lgkmcnt(5)
	v_mfma_f32_32x32x16_bf16 v[64:79], v[184:187], v[212:215], v[64:79]
	v_mfma_f32_32x32x16_bf16 v[0:15], v[188:191], v[212:215], v[0:15]
	ds_read_b128 v[212:215], v149 offset:4672
	s_setprio 0
	global_load_dwordx4 v[184:187], v[132:133], off offset:1152
	global_load_dwordx4 v[188:191], v[134:135], off offset:1152
	s_setprio 1
	s_waitcnt lgkmcnt(1)
	v_mfma_f32_32x32x16_bf16 v[112:127], v[194:197], v[208:211], v[112:127]
	v_mfma_f32_32x32x16_bf16 v[48:63], v[198:201], v[208:211], v[48:63]
	s_waitcnt lgkmcnt(0)
	v_mfma_f32_32x32x16_bf16 v[96:111], v[194:197], v[212:215], v[96:111]
	v_mfma_f32_32x32x16_bf16 v[32:47], v[198:201], v[212:215], v[32:47]
	ds_read_b128 v[208:211], v149 offset:9280
	ds_read_b128 v[212:215], v149 offset:13888
	s_waitcnt vmcnt(7)
	ds_write_b128 v148, v[176:179] offset:27648
	s_waitcnt vmcnt(6)
	ds_write_b128 v148, v[180:183] offset:64512
	ds_read_b128 v[176:179], v150 offset:96
	ds_read_b128 v[180:183], v150 offset:4704
	s_waitcnt lgkmcnt(5)
	v_mfma_f32_32x32x16_bf16 v[80:95], v[194:197], v[208:211], v[80:95]
	v_mfma_f32_32x32x16_bf16 v[16:31], v[198:201], v[208:211], v[16:31]
	ds_read_b128 v[208:211], v149 offset:96
	s_waitcnt lgkmcnt(5)
	v_mfma_f32_32x32x16_bf16 v[64:79], v[194:197], v[212:215], v[64:79]
	v_mfma_f32_32x32x16_bf16 v[0:15], v[198:201], v[212:215], v[0:15]
	ds_read_b128 v[212:215], v149 offset:4704
	s_setprio 0
	global_load_dwordx4 v[194:197], v[144:145], off offset:1152
	global_load_dwordx4 v[198:201], v[146:147], off offset:1152
	s_setprio 1
	s_waitcnt lgkmcnt(1)
	v_mfma_f32_32x32x16_bf16 v[112:127], v[176:179], v[208:211], v[112:127]
	v_mfma_f32_32x32x16_bf16 v[48:63], v[180:183], v[208:211], v[48:63]
	s_waitcnt lgkmcnt(0)
	v_mfma_f32_32x32x16_bf16 v[96:111], v[176:179], v[212:215], v[96:111]
	v_mfma_f32_32x32x16_bf16 v[32:47], v[180:183], v[212:215], v[32:47]
	ds_read_b128 v[208:211], v149 offset:9312
	ds_read_b128 v[212:215], v149 offset:13920
	s_waitcnt lgkmcnt(1)
	v_mfma_f32_32x32x16_bf16 v[80:95], v[176:179], v[208:211], v[80:95]
	v_mfma_f32_32x32x16_bf16 v[16:31], v[180:183], v[208:211], v[16:31]
	s_waitcnt lgkmcnt(0)
	v_mfma_f32_32x32x16_bf16 v[64:79], v[176:179], v[212:215], v[64:79]
	v_mfma_f32_32x32x16_bf16 v[0:15], v[180:183], v[212:215], v[0:15]
	s_setprio 0
	global_load_dwordx4 v[176:179], v[136:137], off offset:1280
	global_load_dwordx4 v[180:183], v[138:139], off offset:1280
	s_barrier
; template <bool trans>
; DI void gemm_core(const GTile& tl, const GTile& nx, bool has_next  , bool chain  , bool pre, u32x4 (&ra)[4], u32x4 (&rb)[4], char* smem, f32x16 (&acc)[2][4]) {
;     ...
;   const int nk = K / 64;
;   if (!pre) { G_LOAD(0); G_STORE(0); G_LOAD(1); }
;   for (int kt = 0; kt < nk; ++kt) {
;     __syncthreads();
;     G_COMPUTE(kt & 1, kt);
;   }
	s_waitcnt vmcnt(9)
	ds_write_b128 v192, v[168:171]
	s_waitcnt vmcnt(8)
	ds_write_b128 v159, v[172:175]
	ds_read_b128 v[168:171], v152 offset:36864
	ds_read_b128 v[172:175], v152 offset:41472
	ds_read_b128 v[208:211], v151
	ds_read_b128 v[212:215], v151 offset:4608
	s_setprio 1
	s_waitcnt lgkmcnt(1)
	v_mfma_f32_32x32x16_bf16 v[112:127], v[168:171], v[208:211], v[112:127]
	v_mfma_f32_32x32x16_bf16 v[48:63], v[172:175], v[208:211], v[48:63]
	s_waitcnt lgkmcnt(0)
	v_mfma_f32_32x32x16_bf16 v[96:111], v[168:171], v[212:215], v[96:111]
	v_mfma_f32_32x32x16_bf16 v[32:47], v[172:175], v[212:215], v[32:47]
	ds_read_b128 v[208:211], v151 offset:9216
	ds_read_b128 v[212:215], v151 offset:13824
	s_waitcnt vmcnt(7)
	ds_write_b128 v158, v[160:163]
	s_waitcnt vmcnt(6)
	ds_write_b128 v157, v[164:167]
	ds_read_b128 v[160:163], v152 offset:36896
	ds_read_b128 v[164:167], v152 offset:41504
	s_waitcnt lgkmcnt(5)
	v_mfma_f32_32x32x16_bf16 v[80:95], v[168:171], v[208:211], v[80:95]
	v_mfma_f32_32x32x16_bf16 v[16:31], v[172:175], v[208:211], v[16:31]
	ds_read_b128 v[208:211], v151 offset:32
	s_waitcnt lgkmcnt(5)
	v_mfma_f32_32x32x16_bf16 v[64:79], v[168:171], v[212:215], v[64:79]
	v_mfma_f32_32x32x16_bf16 v[0:15], v[172:175], v[212:215], v[0:15]
	ds_read_b128 v[212:215], v151 offset:4640
	s_setprio 0
	global_load_dwordx4 v[168:171], v[140:141], off offset:1280
	global_load_dwordx4 v[172:175], v[142:143], off offset:1280
	s_setprio 1
	s_waitcnt lgkmcnt(1)
	v_mfma_f32_32x32x16_bf16 v[112:127], v[160:163], v[208:211], v[112:127]
	v_mfma_f32_32x32x16_bf16 v[48:63], v[164:167], v[208:211], v[48:63]
	s_waitcnt lgkmcnt(0)
	v_mfma_f32_32x32x16_bf16 v[96:111], v[160:163], v[212:215], v[96:111]
	v_mfma_f32_32x32x16_bf16 v[32:47], v[164:167], v[212:215], v[32:47]
	ds_read_b128 v[208:211], v151 offset:9248
	ds_read_b128 v[212:215], v151 offset:13856
	s_waitcnt vmcnt(7)
	ds_write_b128 v154, v[184:187]
	s_waitcnt vmcnt(6)
	ds_write_b128 v153, v[188:191]
	ds_read_b128 v[184:187], v152 offset:36928
	ds_read_b128 v[188:191], v152 offset:41536
	s_waitcnt lgkmcnt(5)
	v_mfma_f32_32x32x16_bf16 v[80:95], v[160:163], v[208:211], v[80:95]
	v_mfma_f32_32x32x16_bf16 v[16:31], v[164:167], v[208:211], v[16:31]
	ds_read_b128 v[208:211], v151 offset:64
	s_waitcnt lgkmcnt(5)
	v_mfma_f32_32x32x16_bf16 v[64:79], v[160:163], v[212:215], v[64:79]
	v_mfma_f32_32x32x16_bf16 v[0:15], v[164:167], v[212:215], v[0:15]
	ds_read_b128 v[212:215], v151 offset:4672
	s_setprio 0
	global_load_dwordx4 v[160:163], v[132:133], off offset:1280
	global_load_dwordx4 v[164:167], v[134:135], off offset:1280
	s_setprio 1
	s_waitcnt lgkmcnt(1)
	v_mfma_f32_32x32x16_bf16 v[112:127], v[184:187], v[208:211], v[112:127]
	v_mfma_f32_32x32x16_bf16 v[48:63], v[188:191], v[208:211], v[48:63]
	s_waitcnt lgkmcnt(0)
	v_mfma_f32_32x32x16_bf16 v[96:111], v[184:187], v[212:215], v[96:111]
	v_mfma_f32_32x32x16_bf16 v[32:47], v[188:191], v[212:215], v[32:47]
	ds_read_b128 v[208:211], v151 offset:9280
	ds_read_b128 v[212:215], v151 offset:13888
	s_waitcnt vmcnt(7)
	ds_write_b128 v156, v[194:197]
	s_waitcnt vmcnt(6)
	ds_write_b128 v155, v[198:201]
	ds_read_b128 v[194:197], v152 offset:36960
	ds_read_b128 v[198:201], v152 offset:41568
	s_waitcnt lgkmcnt(5)
	v_mfma_f32_32x32x16_bf16 v[80:95], v[184:187], v[208:211], v[80:95]
	v_mfma_f32_32x32x16_bf16 v[16:31], v[188:191], v[208:211], v[16:31]
	ds_read_b128 v[208:211], v151 offset:96
	s_waitcnt lgkmcnt(5)
	v_mfma_f32_32x32x16_bf16 v[64:79], v[184:187], v[212:215], v[64:79]
	v_mfma_f32_32x32x16_bf16 v[0:15], v[188:191], v[212:215], v[0:15]
	ds_read_b128 v[212:215], v151 offset:4704
	s_setprio 0
	global_load_dwordx4 v[184:187], v[144:145], off offset:1280
	global_load_dwordx4 v[188:191], v[146:147], off offset:1280
	s_setprio 1
	s_waitcnt lgkmcnt(1)
	v_mfma_f32_32x32x16_bf16 v[112:127], v[194:197], v[208:211], v[112:127]
	v_mfma_f32_32x32x16_bf16 v[48:63], v[198:201], v[208:211], v[48:63]
	s_waitcnt lgkmcnt(0)
	v_mfma_f32_32x32x16_bf16 v[96:111], v[194:197], v[212:215], v[96:111]
	v_mfma_f32_32x32x16_bf16 v[32:47], v[198:201], v[212:215], v[32:47]
	ds_read_b128 v[208:211], v151 offset:9312
	ds_read_b128 v[212:215], v151 offset:13920
	s_waitcnt lgkmcnt(1)
	v_mfma_f32_32x32x16_bf16 v[80:95], v[194:197], v[208:211], v[80:95]
	v_mfma_f32_32x32x16_bf16 v[16:31], v[198:201], v[208:211], v[16:31]
	s_waitcnt lgkmcnt(0)
	v_mfma_f32_32x32x16_bf16 v[64:79], v[194:197], v[212:215], v[64:79]
	v_mfma_f32_32x32x16_bf16 v[0:15], v[198:201], v[212:215], v[0:15]
	s_setprio 0
	global_load_dwordx4 v[194:197], v[136:137], off offset:1408
	global_load_dwordx4 v[198:201], v[138:139], off offset:1408
	s_barrier
; template <bool trans>
; DI void gemm_core(const GTile& tl, const GTile& nx, bool has_next  , bool chain  , bool pre, u32x4 (&ra)[4], u32x4 (&rb)[4], char* smem, f32x16 (&acc)[2][4]) {
;     ...
;   const int nk = K / 64;
;   if (!pre) { G_LOAD(0); G_STORE(0); G_LOAD(1); }
;   for (int kt = 0; kt < nk; ++kt) {
;     __syncthreads();
;     G_COMPUTE(kt & 1, kt);
;   }
	s_waitcnt vmcnt(9)
	ds_write_b128 v148, v[176:179]
	s_waitcnt vmcnt(8)
	ds_write_b128 v148, v[180:183] offset:36864
	ds_read_b128 v[176:179], v150
	ds_read_b128 v[180:183], v150 offset:4608
	ds_read_b128 v[208:211], v149
	ds_read_b128 v[212:215], v149 offset:4608
	s_setprio 1
	s_waitcnt lgkmcnt(1)
	v_mfma_f32_32x32x16_bf16 v[112:127], v[176:179], v[208:211], v[112:127]
	v_mfma_f32_32x32x16_bf16 v[48:63], v[180:183], v[208:211], v[48:63]
	s_waitcnt lgkmcnt(0)
	v_mfma_f32_32x32x16_bf16 v[96:111], v[176:179], v[212:215], v[96:111]
	v_mfma_f32_32x32x16_bf16 v[32:47], v[180:183], v[212:215], v[32:47]
	ds_read_b128 v[208:211], v149 offset:9216
	ds_read_b128 v[212:215], v149 offset:13824
	s_waitcnt vmcnt(7)
	ds_write_b128 v148, v[168:171] offset:9216
	s_waitcnt vmcnt(6)
	ds_write_b128 v148, v[172:175] offset:46080
	ds_read_b128 v[168:171], v150 offset:32
	ds_read_b128 v[172:175], v150 offset:4640
	s_waitcnt lgkmcnt(5)
	v_mfma_f32_32x32x16_bf16 v[80:95], v[176:179], v[208:211], v[80:95]
	v_mfma_f32_32x32x16_bf16 v[16:31], v[180:183], v[208:211], v[16:31]
	ds_read_b128 v[208:211], v149 offset:32
	s_waitcnt lgkmcnt(5)
	v_mfma_f32_32x32x16_bf16 v[64:79], v[176:179], v[212:215], v[64:79]
	v_mfma_f32_32x32x16_bf16 v[0:15], v[180:183], v[212:215], v[0:15]
	ds_read_b128 v[212:215], v149 offset:4640
	s_setprio 0
	global_load_dwordx4 v[176:179], v[140:141], off offset:1408
	global_load_dwordx4 v[180:183], v[142:143], off offset:1408
	s_setprio 1
	s_waitcnt lgkmcnt(1)
	v_mfma_f32_32x32x16_bf16 v[112:127], v[168:171], v[208:211], v[112:127]
	v_mfma_f32_32x32x16_bf16 v[48:63], v[172:175], v[208:211], v[48:63]
	s_waitcnt lgkmcnt(0)
	v_mfma_f32_32x32x16_bf16 v[96:111], v[168:171], v[212:215], v[96:111]
	v_mfma_f32_32x32x16_bf16 v[32:47], v[172:175], v[212:215], v[32:47]
	ds_read_b128 v[208:211], v149 offset:9248
	ds_read_b128 v[212:215], v149 offset:13856
	s_waitcnt vmcnt(7)
	ds_write_b128 v148, v[160:163] offset:18432
	s_waitcnt vmcnt(6)
	ds_write_b128 v148, v[164:167] offset:55296
	ds_read_b128 v[160:163], v150 offset:64
	ds_read_b128 v[164:167], v150 offset:4672
	s_waitcnt lgkmcnt(5)
	v_mfma_f32_32x32x16_bf16 v[80:95], v[168:171], v[208:211], v[80:95]
	v_mfma_f32_32x32x16_bf16 v[16:31], v[172:175], v[208:211], v[16:31]
	ds_read_b128 v[208:211], v149 offset:64
	s_waitcnt lgkmcnt(5)
	v_mfma_f32_32x32x16_bf16 v[64:79], v[168:171], v[212:215], v[64:79]
	v_mfma_f32_32x32x16_bf16 v[0:15], v[172:175], v[212:215], v[0:15]
	ds_read_b128 v[212:215], v149 offset:4672
	s_setprio 0
	global_load_dwordx4 v[168:171], v[132:133], off offset:1408
	global_load_dwordx4 v[172:175], v[134:135], off offset:1408
	s_setprio 1
	s_waitcnt lgkmcnt(1)
	v_mfma_f32_32x32x16_bf16 v[112:127], v[160:163], v[208:211], v[112:127]
	v_mfma_f32_32x32x16_bf16 v[48:63], v[164:167], v[208:211], v[48:63]
	s_waitcnt lgkmcnt(0)
	v_mfma_f32_32x32x16_bf16 v[96:111], v[160:163], v[212:215], v[96:111]
	v_mfma_f32_32x32x16_bf16 v[32:47], v[164:167], v[212:215], v[32:47]
	ds_read_b128 v[208:211], v149 offset:9280
	ds_read_b128 v[212:215], v149 offset:13888
	s_waitcnt vmcnt(7)
	ds_write_b128 v148, v[184:187] offset:27648
	s_waitcnt vmcnt(6)
	ds_write_b128 v148, v[188:191] offset:64512
	ds_read_b128 v[184:187], v150 offset:96
	ds_read_b128 v[188:191], v150 offset:4704
	s_waitcnt lgkmcnt(5)
	v_mfma_f32_32x32x16_bf16 v[80:95], v[160:163], v[208:211], v[80:95]
	v_mfma_f32_32x32x16_bf16 v[16:31], v[164:167], v[208:211], v[16:31]
	ds_read_b128 v[208:211], v149 offset:96
	s_waitcnt lgkmcnt(5)
	v_mfma_f32_32x32x16_bf16 v[64:79], v[160:163], v[212:215], v[64:79]
	v_mfma_f32_32x32x16_bf16 v[0:15], v[164:167], v[212:215], v[0:15]
	ds_read_b128 v[212:215], v149 offset:4704
	s_setprio 0
	global_load_dwordx4 v[160:163], v[144:145], off offset:1408
	global_load_dwordx4 v[164:167], v[146:147], off offset:1408
	s_setprio 1
	s_waitcnt lgkmcnt(1)
	v_mfma_f32_32x32x16_bf16 v[112:127], v[184:187], v[208:211], v[112:127]
	v_mfma_f32_32x32x16_bf16 v[48:63], v[188:191], v[208:211], v[48:63]
	s_waitcnt lgkmcnt(0)
	v_mfma_f32_32x32x16_bf16 v[96:111], v[184:187], v[212:215], v[96:111]
	v_mfma_f32_32x32x16_bf16 v[32:47], v[188:191], v[212:215], v[32:47]
	ds_read_b128 v[208:211], v149 offset:9312
	ds_read_b128 v[212:215], v149 offset:13920
	s_waitcnt lgkmcnt(1)
	v_mfma_f32_32x32x16_bf16 v[80:95], v[184:187], v[208:211], v[80:95]
	v_mfma_f32_32x32x16_bf16 v[16:31], v[188:191], v[208:211], v[16:31]
	s_waitcnt lgkmcnt(0)
	v_mfma_f32_32x32x16_bf16 v[64:79], v[184:187], v[212:215], v[64:79]
	v_mfma_f32_32x32x16_bf16 v[0:15], v[188:191], v[212:215], v[0:15]
	s_setprio 0
	global_load_dwordx4 v[184:187], v[136:137], off offset:1536
	global_load_dwordx4 v[188:191], v[138:139], off offset:1536
	s_barrier
; template <bool trans>
; DI void gemm_core(const GTile& tl, const GTile& nx, bool has_next  , bool chain  , bool pre, u32x4 (&ra)[4], u32x4 (&rb)[4], char* smem, f32x16 (&acc)[2][4]) {
;     ...
;   const int nk = K / 64;
;   if (!pre) { G_LOAD(0); G_STORE(0); G_LOAD(1); }
;   for (int kt = 0; kt < nk; ++kt) {
;     __syncthreads();
;     G_COMPUTE(kt & 1, kt);
;   }
	s_waitcnt vmcnt(9)
	ds_write_b128 v192, v[194:197]
	s_waitcnt vmcnt(8)
	ds_write_b128 v159, v[198:201]
	ds_read_b128 v[194:197], v152 offset:36864
	ds_read_b128 v[198:201], v152 offset:41472
	ds_read_b128 v[208:211], v151
	ds_read_b128 v[212:215], v151 offset:4608
	s_setprio 1
	s_waitcnt lgkmcnt(1)
	v_mfma_f32_32x32x16_bf16 v[112:127], v[194:197], v[208:211], v[112:127]
	v_mfma_f32_32x32x16_bf16 v[48:63], v[198:201], v[208:211], v[48:63]
	s_waitcnt lgkmcnt(0)
	v_mfma_f32_32x32x16_bf16 v[96:111], v[194:197], v[212:215], v[96:111]
	v_mfma_f32_32x32x16_bf16 v[32:47], v[198:201], v[212:215], v[32:47]
	ds_read_b128 v[208:211], v151 offset:9216
	ds_read_b128 v[212:215], v151 offset:13824
	s_waitcnt vmcnt(7)
	ds_write_b128 v158, v[176:179]
	s_waitcnt vmcnt(6)
	ds_write_b128 v157, v[180:183]
	ds_read_b128 v[176:179], v152 offset:36896
	ds_read_b128 v[180:183], v152 offset:41504
	s_waitcnt lgkmcnt(5)
	v_mfma_f32_32x32x16_bf16 v[80:95], v[194:197], v[208:211], v[80:95]
	v_mfma_f32_32x32x16_bf16 v[16:31], v[198:201], v[208:211], v[16:31]
	ds_read_b128 v[208:211], v151 offset:32
	s_waitcnt lgkmcnt(5)
	v_mfma_f32_32x32x16_bf16 v[64:79], v[194:197], v[212:215], v[64:79]
	v_mfma_f32_32x32x16_bf16 v[0:15], v[198:201], v[212:215], v[0:15]
	ds_read_b128 v[212:215], v151 offset:4640
	s_setprio 0
	global_load_dwordx4 v[194:197], v[140:141], off offset:1536
	global_load_dwordx4 v[198:201], v[142:143], off offset:1536
	s_setprio 1
	s_waitcnt lgkmcnt(1)
	v_mfma_f32_32x32x16_bf16 v[112:127], v[176:179], v[208:211], v[112:127]
	v_mfma_f32_32x32x16_bf16 v[48:63], v[180:183], v[208:211], v[48:63]
	s_waitcnt lgkmcnt(0)
	v_mfma_f32_32x32x16_bf16 v[96:111], v[176:179], v[212:215], v[96:111]
	v_mfma_f32_32x32x16_bf16 v[32:47], v[180:183], v[212:215], v[32:47]
	ds_read_b128 v[208:211], v151 offset:9248
	ds_read_b128 v[212:215], v151 offset:13856
	s_waitcnt vmcnt(7)
	ds_write_b128 v154, v[168:171]
	s_waitcnt vmcnt(6)
	ds_write_b128 v153, v[172:175]
	ds_read_b128 v[168:171], v152 offset:36928
	ds_read_b128 v[172:175], v152 offset:41536
	s_waitcnt lgkmcnt(5)
	v_mfma_f32_32x32x16_bf16 v[80:95], v[176:179], v[208:211], v[80:95]
	v_mfma_f32_32x32x16_bf16 v[16:31], v[180:183], v[208:211], v[16:31]
	ds_read_b128 v[208:211], v151 offset:64
	s_waitcnt lgkmcnt(5)
	v_mfma_f32_32x32x16_bf16 v[64:79], v[176:179], v[212:215], v[64:79]
	v_mfma_f32_32x32x16_bf16 v[0:15], v[180:183], v[212:215], v[0:15]
	ds_read_b128 v[212:215], v151 offset:4672
	s_setprio 0
	global_load_dwordx4 v[176:179], v[132:133], off offset:1536
	global_load_dwordx4 v[180:183], v[134:135], off offset:1536
	s_setprio 1
	s_waitcnt lgkmcnt(1)
	v_mfma_f32_32x32x16_bf16 v[112:127], v[168:171], v[208:211], v[112:127]
	v_mfma_f32_32x32x16_bf16 v[48:63], v[172:175], v[208:211], v[48:63]
	s_waitcnt lgkmcnt(0)
	v_mfma_f32_32x32x16_bf16 v[96:111], v[168:171], v[212:215], v[96:111]
	v_mfma_f32_32x32x16_bf16 v[32:47], v[172:175], v[212:215], v[32:47]
	ds_read_b128 v[208:211], v151 offset:9280
	ds_read_b128 v[212:215], v151 offset:13888
	s_waitcnt vmcnt(7)
	ds_write_b128 v156, v[160:163]
	s_waitcnt vmcnt(6)
	ds_write_b128 v155, v[164:167]
	ds_read_b128 v[160:163], v152 offset:36960
	ds_read_b128 v[164:167], v152 offset:41568
	s_waitcnt lgkmcnt(5)
	v_mfma_f32_32x32x16_bf16 v[80:95], v[168:171], v[208:211], v[80:95]
	v_mfma_f32_32x32x16_bf16 v[16:31], v[172:175], v[208:211], v[16:31]
	ds_read_b128 v[208:211], v151 offset:96
	s_waitcnt lgkmcnt(5)
	v_mfma_f32_32x32x16_bf16 v[64:79], v[168:171], v[212:215], v[64:79]
	v_mfma_f32_32x32x16_bf16 v[0:15], v[172:175], v[212:215], v[0:15]
	ds_read_b128 v[212:215], v151 offset:4704
	s_setprio 0
	global_load_dwordx4 v[168:171], v[144:145], off offset:1536
	global_load_dwordx4 v[172:175], v[146:147], off offset:1536
	s_setprio 1
	s_waitcnt lgkmcnt(1)
	v_mfma_f32_32x32x16_bf16 v[112:127], v[160:163], v[208:211], v[112:127]
	v_mfma_f32_32x32x16_bf16 v[48:63], v[164:167], v[208:211], v[48:63]
	s_waitcnt lgkmcnt(0)
	v_mfma_f32_32x32x16_bf16 v[96:111], v[160:163], v[212:215], v[96:111]
	v_mfma_f32_32x32x16_bf16 v[32:47], v[164:167], v[212:215], v[32:47]
	ds_read_b128 v[208:211], v151 offset:9312
	ds_read_b128 v[212:215], v151 offset:13920
	s_waitcnt lgkmcnt(1)
	v_mfma_f32_32x32x16_bf16 v[80:95], v[160:163], v[208:211], v[80:95]
	v_mfma_f32_32x32x16_bf16 v[16:31], v[164:167], v[208:211], v[16:31]
	s_waitcnt lgkmcnt(0)
	v_mfma_f32_32x32x16_bf16 v[64:79], v[160:163], v[212:215], v[64:79]
	v_mfma_f32_32x32x16_bf16 v[0:15], v[164:167], v[212:215], v[0:15]
	s_setprio 0
	global_load_dwordx4 v[160:163], v[136:137], off offset:1664
	global_load_dwordx4 v[164:167], v[138:139], off offset:1664
	s_barrier
; template <bool trans>
; DI void gemm_core(const GTile& tl, const GTile& nx, bool has_next  , bool chain  , bool pre, u32x4 (&ra)[4], u32x4 (&rb)[4], char* smem, f32x16 (&acc)[2][4]) {
;     ...
;   const int nk = K / 64;
;   if (!pre) { G_LOAD(0); G_STORE(0); G_LOAD(1); }
;   for (int kt = 0; kt < nk; ++kt) {
;     __syncthreads();
;     G_COMPUTE(kt & 1, kt);
;   }
	s_waitcnt vmcnt(9)
	ds_write_b128 v148, v[184:187]
	s_waitcnt vmcnt(8)
	ds_write_b128 v148, v[188:191] offset:36864
	ds_read_b128 v[184:187], v150
	ds_read_b128 v[188:191], v150 offset:4608
	ds_read_b128 v[208:211], v149
	ds_read_b128 v[212:215], v149 offset:4608
	s_setprio 1
	s_waitcnt lgkmcnt(1)
	v_mfma_f32_32x32x16_bf16 v[112:127], v[184:187], v[208:211], v[112:127]
	v_mfma_f32_32x32x16_bf16 v[48:63], v[188:191], v[208:211], v[48:63]
	s_waitcnt lgkmcnt(0)
	v_mfma_f32_32x32x16_bf16 v[96:111], v[184:187], v[212:215], v[96:111]
	v_mfma_f32_32x32x16_bf16 v[32:47], v[188:191], v[212:215], v[32:47]
	ds_read_b128 v[208:211], v149 offset:9216
	ds_read_b128 v[212:215], v149 offset:13824
	s_waitcnt vmcnt(7)
	ds_write_b128 v148, v[194:197] offset:9216
	s_waitcnt vmcnt(6)
	ds_write_b128 v148, v[198:201] offset:46080
	ds_read_b128 v[194:197], v150 offset:32
	ds_read_b128 v[198:201], v150 offset:4640
	s_waitcnt lgkmcnt(5)
	v_mfma_f32_32x32x16_bf16 v[80:95], v[184:187], v[208:211], v[80:95]
	v_mfma_f32_32x32x16_bf16 v[16:31], v[188:191], v[208:211], v[16:31]
	ds_read_b128 v[208:211], v149 offset:32
	s_waitcnt lgkmcnt(5)
	v_mfma_f32_32x32x16_bf16 v[64:79], v[184:187], v[212:215], v[64:79]
	v_mfma_f32_32x32x16_bf16 v[0:15], v[188:191], v[212:215], v[0:15]
	ds_read_b128 v[212:215], v149 offset:4640
	s_setprio 0
	global_load_dwordx4 v[184:187], v[140:141], off offset:1664
	global_load_dwordx4 v[188:191], v[142:143], off offset:1664
	s_setprio 1
	s_waitcnt lgkmcnt(1)
	v_mfma_f32_32x32x16_bf16 v[112:127], v[194:197], v[208:211], v[112:127]
	v_mfma_f32_32x32x16_bf16 v[48:63], v[198:201], v[208:211], v[48:63]
	s_waitcnt lgkmcnt(0)
	v_mfma_f32_32x32x16_bf16 v[96:111], v[194:197], v[212:215], v[96:111]
	v_mfma_f32_32x32x16_bf16 v[32:47], v[198:201], v[212:215], v[32:47]
	ds_read_b128 v[208:211], v149 offset:9248
	ds_read_b128 v[212:215], v149 offset:13856
	s_waitcnt vmcnt(7)
	ds_write_b128 v148, v[176:179] offset:18432
	s_waitcnt vmcnt(6)
	ds_write_b128 v148, v[180:183] offset:55296
	ds_read_b128 v[176:179], v150 offset:64
	ds_read_b128 v[180:183], v150 offset:4672
	s_waitcnt lgkmcnt(5)
	v_mfma_f32_32x32x16_bf16 v[80:95], v[194:197], v[208:211], v[80:95]
	v_mfma_f32_32x32x16_bf16 v[16:31], v[198:201], v[208:211], v[16:31]
	ds_read_b128 v[208:211], v149 offset:64
	s_waitcnt lgkmcnt(5)
	v_mfma_f32_32x32x16_bf16 v[64:79], v[194:197], v[212:215], v[64:79]
	v_mfma_f32_32x32x16_bf16 v[0:15], v[198:201], v[212:215], v[0:15]
	ds_read_b128 v[212:215], v149 offset:4672
	s_setprio 0
	global_load_dwordx4 v[194:197], v[132:133], off offset:1664
	global_load_dwordx4 v[198:201], v[134:135], off offset:1664
	s_setprio 1
	s_waitcnt lgkmcnt(1)
	v_mfma_f32_32x32x16_bf16 v[112:127], v[176:179], v[208:211], v[112:127]
	v_mfma_f32_32x32x16_bf16 v[48:63], v[180:183], v[208:211], v[48:63]
	s_waitcnt lgkmcnt(0)
	v_mfma_f32_32x32x16_bf16 v[96:111], v[176:179], v[212:215], v[96:111]
	v_mfma_f32_32x32x16_bf16 v[32:47], v[180:183], v[212:215], v[32:47]
	ds_read_b128 v[208:211], v149 offset:9280
	ds_read_b128 v[212:215], v149 offset:13888
	s_waitcnt vmcnt(7)
	ds_write_b128 v148, v[168:171] offset:27648
	s_waitcnt vmcnt(6)
	ds_write_b128 v148, v[172:175] offset:64512
	ds_read_b128 v[168:171], v150 offset:96
	ds_read_b128 v[172:175], v150 offset:4704
	s_waitcnt lgkmcnt(5)
	v_mfma_f32_32x32x16_bf16 v[80:95], v[176:179], v[208:211], v[80:95]
	v_mfma_f32_32x32x16_bf16 v[16:31], v[180:183], v[208:211], v[16:31]
	ds_read_b128 v[208:211], v149 offset:96
	s_waitcnt lgkmcnt(5)
	v_mfma_f32_32x32x16_bf16 v[64:79], v[176:179], v[212:215], v[64:79]
	v_mfma_f32_32x32x16_bf16 v[0:15], v[180:183], v[212:215], v[0:15]
	ds_read_b128 v[212:215], v149 offset:4704
	s_setprio 0
	global_load_dwordx4 v[176:179], v[144:145], off offset:1664
	global_load_dwordx4 v[180:183], v[146:147], off offset:1664
	s_setprio 1
	s_waitcnt lgkmcnt(1)
	v_mfma_f32_32x32x16_bf16 v[112:127], v[168:171], v[208:211], v[112:127]
	v_mfma_f32_32x32x16_bf16 v[48:63], v[172:175], v[208:211], v[48:63]
	s_waitcnt lgkmcnt(0)
	v_mfma_f32_32x32x16_bf16 v[96:111], v[168:171], v[212:215], v[96:111]
	v_mfma_f32_32x32x16_bf16 v[32:47], v[172:175], v[212:215], v[32:47]
	ds_read_b128 v[208:211], v149 offset:9312
	ds_read_b128 v[212:215], v149 offset:13920
	s_waitcnt lgkmcnt(1)
	v_mfma_f32_32x32x16_bf16 v[80:95], v[168:171], v[208:211], v[80:95]
	v_mfma_f32_32x32x16_bf16 v[16:31], v[172:175], v[208:211], v[16:31]
	s_waitcnt lgkmcnt(0)
	v_mfma_f32_32x32x16_bf16 v[64:79], v[168:171], v[212:215], v[64:79]
	v_mfma_f32_32x32x16_bf16 v[0:15], v[172:175], v[212:215], v[0:15]
	s_setprio 0
	global_load_dwordx4 v[168:171], v[136:137], off offset:1792
	global_load_dwordx4 v[172:175], v[138:139], off offset:1792
	s_barrier
; template <bool trans>
; DI void gemm_core(const GTile& tl, const GTile& nx, bool has_next  , bool chain  , bool pre, u32x4 (&ra)[4], u32x4 (&rb)[4], char* smem, f32x16 (&acc)[2][4]) {
;     ...
;   const int nk = K / 64;
;   if (!pre) { G_LOAD(0); G_STORE(0); G_LOAD(1); }
;   for (int kt = 0; kt < nk; ++kt) {
;     __syncthreads();
;     G_COMPUTE(kt & 1, kt);
;   }
	s_waitcnt vmcnt(9)
	ds_write_b128 v192, v[160:163]
	s_waitcnt vmcnt(8)
	ds_write_b128 v159, v[164:167]
	ds_read_b128 v[160:163], v152 offset:36864
	ds_read_b128 v[164:167], v152 offset:41472
	ds_read_b128 v[208:211], v151
	ds_read_b128 v[212:215], v151 offset:4608
	s_setprio 1
	s_waitcnt lgkmcnt(1)
	v_mfma_f32_32x32x16_bf16 v[112:127], v[160:163], v[208:211], v[112:127]
	v_mfma_f32_32x32x16_bf16 v[48:63], v[164:167], v[208:211], v[48:63]
	s_waitcnt lgkmcnt(0)
	v_mfma_f32_32x32x16_bf16 v[96:111], v[160:163], v[212:215], v[96:111]
	v_mfma_f32_32x32x16_bf16 v[32:47], v[164:167], v[212:215], v[32:47]
	ds_read_b128 v[208:211], v151 offset:9216
	ds_read_b128 v[212:215], v151 offset:13824
	s_waitcnt vmcnt(7)
	ds_write_b128 v158, v[184:187]
	s_waitcnt vmcnt(6)
	ds_write_b128 v157, v[188:191]
	ds_read_b128 v[184:187], v152 offset:36896
	ds_read_b128 v[188:191], v152 offset:41504
	s_waitcnt lgkmcnt(5)
	v_mfma_f32_32x32x16_bf16 v[80:95], v[160:163], v[208:211], v[80:95]
	v_mfma_f32_32x32x16_bf16 v[16:31], v[164:167], v[208:211], v[16:31]
	ds_read_b128 v[208:211], v151 offset:32
	s_waitcnt lgkmcnt(5)
	v_mfma_f32_32x32x16_bf16 v[64:79], v[160:163], v[212:215], v[64:79]
	v_mfma_f32_32x32x16_bf16 v[0:15], v[164:167], v[212:215], v[0:15]
	ds_read_b128 v[212:215], v151 offset:4640
	s_setprio 0
	global_load_dwordx4 v[160:163], v[140:141], off offset:1792
	global_load_dwordx4 v[164:167], v[142:143], off offset:1792
	s_setprio 1
	s_waitcnt lgkmcnt(1)
	v_mfma_f32_32x32x16_bf16 v[112:127], v[184:187], v[208:211], v[112:127]
	v_mfma_f32_32x32x16_bf16 v[48:63], v[188:191], v[208:211], v[48:63]
	s_waitcnt lgkmcnt(0)
	v_mfma_f32_32x32x16_bf16 v[96:111], v[184:187], v[212:215], v[96:111]
	v_mfma_f32_32x32x16_bf16 v[32:47], v[188:191], v[212:215], v[32:47]
	ds_read_b128 v[208:211], v151 offset:9248
	ds_read_b128 v[212:215], v151 offset:13856
	s_waitcnt vmcnt(7)
	ds_write_b128 v154, v[194:197]
	s_waitcnt vmcnt(6)
	ds_write_b128 v153, v[198:201]
	ds_read_b128 v[194:197], v152 offset:36928
	ds_read_b128 v[198:201], v152 offset:41536
	s_waitcnt lgkmcnt(5)
	v_mfma_f32_32x32x16_bf16 v[80:95], v[184:187], v[208:211], v[80:95]
	v_mfma_f32_32x32x16_bf16 v[16:31], v[188:191], v[208:211], v[16:31]
	ds_read_b128 v[208:211], v151 offset:64
	s_waitcnt lgkmcnt(5)
	v_mfma_f32_32x32x16_bf16 v[64:79], v[184:187], v[212:215], v[64:79]
	v_mfma_f32_32x32x16_bf16 v[0:15], v[188:191], v[212:215], v[0:15]
	ds_read_b128 v[212:215], v151 offset:4672
	s_setprio 0
	global_load_dwordx4 v[184:187], v[132:133], off offset:1792
	global_load_dwordx4 v[188:191], v[134:135], off offset:1792
	s_setprio 1
	s_waitcnt lgkmcnt(1)
	v_mfma_f32_32x32x16_bf16 v[112:127], v[194:197], v[208:211], v[112:127]
	v_mfma_f32_32x32x16_bf16 v[48:63], v[198:201], v[208:211], v[48:63]
	s_waitcnt lgkmcnt(0)
	v_mfma_f32_32x32x16_bf16 v[96:111], v[194:197], v[212:215], v[96:111]
	v_mfma_f32_32x32x16_bf16 v[32:47], v[198:201], v[212:215], v[32:47]
	ds_read_b128 v[208:211], v151 offset:9280
	ds_read_b128 v[212:215], v151 offset:13888
	s_waitcnt vmcnt(7)
	ds_write_b128 v156, v[176:179]
	s_waitcnt vmcnt(6)
	ds_write_b128 v155, v[180:183]
	ds_read_b128 v[176:179], v152 offset:36960
	ds_read_b128 v[180:183], v152 offset:41568
	s_waitcnt lgkmcnt(5)
	v_mfma_f32_32x32x16_bf16 v[80:95], v[194:197], v[208:211], v[80:95]
	v_mfma_f32_32x32x16_bf16 v[16:31], v[198:201], v[208:211], v[16:31]
	ds_read_b128 v[208:211], v151 offset:96
	s_waitcnt lgkmcnt(5)
	v_mfma_f32_32x32x16_bf16 v[64:79], v[194:197], v[212:215], v[64:79]
	v_mfma_f32_32x32x16_bf16 v[0:15], v[198:201], v[212:215], v[0:15]
	ds_read_b128 v[212:215], v151 offset:4704
	s_setprio 0
	global_load_dwordx4 v[194:197], v[144:145], off offset:1792
	global_load_dwordx4 v[198:201], v[146:147], off offset:1792
	s_setprio 1
	s_waitcnt lgkmcnt(1)
	v_mfma_f32_32x32x16_bf16 v[112:127], v[176:179], v[208:211], v[112:127]
	v_mfma_f32_32x32x16_bf16 v[48:63], v[180:183], v[208:211], v[48:63]
	s_waitcnt lgkmcnt(0)
	v_mfma_f32_32x32x16_bf16 v[96:111], v[176:179], v[212:215], v[96:111]
	v_mfma_f32_32x32x16_bf16 v[32:47], v[180:183], v[212:215], v[32:47]
	ds_read_b128 v[208:211], v151 offset:9312
	ds_read_b128 v[212:215], v151 offset:13920
	s_waitcnt lgkmcnt(1)
	v_mfma_f32_32x32x16_bf16 v[80:95], v[176:179], v[208:211], v[80:95]
	v_mfma_f32_32x32x16_bf16 v[16:31], v[180:183], v[208:211], v[16:31]
	s_waitcnt lgkmcnt(0)
	v_mfma_f32_32x32x16_bf16 v[64:79], v[176:179], v[212:215], v[64:79]
	v_mfma_f32_32x32x16_bf16 v[0:15], v[180:183], v[212:215], v[0:15]
	s_setprio 0
	global_load_dwordx4 v[176:179], v[136:137], off offset:1920
	global_load_dwordx4 v[180:183], v[138:139], off offset:1920
	s_barrier
; template <bool trans>
; DI void gemm_core(const GTile& tl, const GTile& nx, bool has_next  , bool chain  , bool pre, u32x4 (&ra)[4], u32x4 (&rb)[4], char* smem, f32x16 (&acc)[2][4]) {
;     ...
;   const int nk = K / 64;
;   if (!pre) { G_LOAD(0); G_STORE(0); G_LOAD(1); }
;   for (int kt = 0; kt < nk; ++kt) {
;     __syncthreads();
;     G_COMPUTE(kt & 1, kt);
;   }
	s_waitcnt vmcnt(9)
	ds_write_b128 v148, v[168:171]
	s_waitcnt vmcnt(8)
	ds_write_b128 v148, v[172:175] offset:36864
	ds_read_b128 v[168:171], v150
	ds_read_b128 v[172:175], v150 offset:4608
	ds_read_b128 v[208:211], v149
	ds_read_b128 v[212:215], v149 offset:4608
	s_setprio 1
	s_waitcnt lgkmcnt(1)
	v_mfma_f32_32x32x16_bf16 v[112:127], v[168:171], v[208:211], v[112:127]
	v_mfma_f32_32x32x16_bf16 v[48:63], v[172:175], v[208:211], v[48:63]
	s_waitcnt lgkmcnt(0)
	v_mfma_f32_32x32x16_bf16 v[96:111], v[168:171], v[212:215], v[96:111]
	v_mfma_f32_32x32x16_bf16 v[32:47], v[172:175], v[212:215], v[32:47]
	ds_read_b128 v[208:211], v149 offset:9216
	ds_read_b128 v[212:215], v149 offset:13824
	s_waitcnt vmcnt(7)
	ds_write_b128 v148, v[160:163] offset:9216
	s_waitcnt vmcnt(6)
	ds_write_b128 v148, v[164:167] offset:46080
	ds_read_b128 v[160:163], v150 offset:32
	ds_read_b128 v[164:167], v150 offset:4640
	s_waitcnt lgkmcnt(5)
	v_mfma_f32_32x32x16_bf16 v[80:95], v[168:171], v[208:211], v[80:95]
	v_mfma_f32_32x32x16_bf16 v[16:31], v[172:175], v[208:211], v[16:31]
	ds_read_b128 v[208:211], v149 offset:32
	s_waitcnt lgkmcnt(5)
	v_mfma_f32_32x32x16_bf16 v[64:79], v[168:171], v[212:215], v[64:79]
	v_mfma_f32_32x32x16_bf16 v[0:15], v[172:175], v[212:215], v[0:15]
	ds_read_b128 v[212:215], v149 offset:4640
	s_setprio 0
	global_load_dwordx4 v[168:171], v[140:141], off offset:1920
	global_load_dwordx4 v[172:175], v[142:143], off offset:1920
	s_setprio 1
	s_waitcnt lgkmcnt(1)
	v_mfma_f32_32x32x16_bf16 v[112:127], v[160:163], v[208:211], v[112:127]
	v_mfma_f32_32x32x16_bf16 v[48:63], v[164:167], v[208:211], v[48:63]
	s_waitcnt lgkmcnt(0)
	v_mfma_f32_32x32x16_bf16 v[96:111], v[160:163], v[212:215], v[96:111]
	v_mfma_f32_32x32x16_bf16 v[32:47], v[164:167], v[212:215], v[32:47]
	ds_read_b128 v[208:211], v149 offset:9248
	ds_read_b128 v[212:215], v149 offset:13856
	s_waitcnt vmcnt(7)
	ds_write_b128 v148, v[184:187] offset:18432
	s_waitcnt vmcnt(6)
	ds_write_b128 v148, v[188:191] offset:55296
	ds_read_b128 v[184:187], v150 offset:64
	ds_read_b128 v[188:191], v150 offset:4672
	s_waitcnt lgkmcnt(5)
	v_mfma_f32_32x32x16_bf16 v[80:95], v[160:163], v[208:211], v[80:95]
	v_mfma_f32_32x32x16_bf16 v[16:31], v[164:167], v[208:211], v[16:31]
	ds_read_b128 v[208:211], v149 offset:64
	s_waitcnt lgkmcnt(5)
	v_mfma_f32_32x32x16_bf16 v[64:79], v[160:163], v[212:215], v[64:79]
	v_mfma_f32_32x32x16_bf16 v[0:15], v[164:167], v[212:215], v[0:15]
	ds_read_b128 v[212:215], v149 offset:4672
	s_setprio 0
	global_load_dwordx4 v[160:163], v[132:133], off offset:1920
	global_load_dwordx4 v[164:167], v[134:135], off offset:1920
	s_setprio 1
	s_waitcnt lgkmcnt(1)
	v_mfma_f32_32x32x16_bf16 v[112:127], v[184:187], v[208:211], v[112:127]
	v_mfma_f32_32x32x16_bf16 v[48:63], v[188:191], v[208:211], v[48:63]
	s_waitcnt lgkmcnt(0)
	v_mfma_f32_32x32x16_bf16 v[96:111], v[184:187], v[212:215], v[96:111]
	v_mfma_f32_32x32x16_bf16 v[32:47], v[188:191], v[212:215], v[32:47]
	ds_read_b128 v[208:211], v149 offset:9280
	ds_read_b128 v[212:215], v149 offset:13888
	s_waitcnt vmcnt(7)
	ds_write_b128 v148, v[194:197] offset:27648
	s_waitcnt vmcnt(6)
	ds_write_b128 v148, v[198:201] offset:64512
	ds_read_b128 v[194:197], v150 offset:96
	ds_read_b128 v[198:201], v150 offset:4704
	s_waitcnt lgkmcnt(5)
	v_mfma_f32_32x32x16_bf16 v[80:95], v[184:187], v[208:211], v[80:95]
	v_mfma_f32_32x32x16_bf16 v[16:31], v[188:191], v[208:211], v[16:31]
	ds_read_b128 v[208:211], v149 offset:96
	s_waitcnt lgkmcnt(5)
	v_mfma_f32_32x32x16_bf16 v[64:79], v[184:187], v[212:215], v[64:79]
	v_mfma_f32_32x32x16_bf16 v[0:15], v[188:191], v[212:215], v[0:15]
	ds_read_b128 v[212:215], v149 offset:4704
	s_setprio 0
	global_load_dwordx4 v[184:187], v[144:145], off offset:1920
	global_load_dwordx4 v[188:191], v[146:147], off offset:1920
	s_setprio 1
	s_waitcnt lgkmcnt(1)
	v_mfma_f32_32x32x16_bf16 v[112:127], v[194:197], v[208:211], v[112:127]
	v_mfma_f32_32x32x16_bf16 v[48:63], v[198:201], v[208:211], v[48:63]
	s_waitcnt lgkmcnt(0)
	v_mfma_f32_32x32x16_bf16 v[96:111], v[194:197], v[212:215], v[96:111]
	v_mfma_f32_32x32x16_bf16 v[32:47], v[198:201], v[212:215], v[32:47]
	ds_read_b128 v[208:211], v149 offset:9312
	ds_read_b128 v[212:215], v149 offset:13920
	s_waitcnt lgkmcnt(1)
	v_mfma_f32_32x32x16_bf16 v[80:95], v[194:197], v[208:211], v[80:95]
	v_mfma_f32_32x32x16_bf16 v[16:31], v[198:201], v[208:211], v[16:31]
	s_waitcnt lgkmcnt(0)
	v_mfma_f32_32x32x16_bf16 v[64:79], v[194:197], v[212:215], v[64:79]
	v_mfma_f32_32x32x16_bf16 v[0:15], v[198:201], v[212:215], v[0:15]
	s_setprio 0
	global_load_dwordx4 v[194:197], v[136:137], off offset:2048
	global_load_dwordx4 v[198:201], v[138:139], off offset:2048
	s_barrier
; template <bool trans>
; DI void gemm_core(const GTile& tl, const GTile& nx, bool has_next  , bool chain  , bool pre, u32x4 (&ra)[4], u32x4 (&rb)[4], char* smem, f32x16 (&acc)[2][4]) {
;     ...
;   const int nk = K / 64;
;   if (!pre) { G_LOAD(0); G_STORE(0); G_LOAD(1); }
;   for (int kt = 0; kt < nk; ++kt) {
;     __syncthreads();
;     G_COMPUTE(kt & 1, kt);
;   }
	s_waitcnt vmcnt(9)
	ds_write_b128 v192, v[176:179]
	s_waitcnt vmcnt(8)
	ds_write_b128 v159, v[180:183]
	ds_read_b128 v[176:179], v152 offset:36864
	ds_read_b128 v[180:183], v152 offset:41472
	ds_read_b128 v[208:211], v151
	ds_read_b128 v[212:215], v151 offset:4608
	s_setprio 1
	s_waitcnt lgkmcnt(1)
	v_mfma_f32_32x32x16_bf16 v[112:127], v[176:179], v[208:211], v[112:127]
	v_mfma_f32_32x32x16_bf16 v[48:63], v[180:183], v[208:211], v[48:63]
	s_waitcnt lgkmcnt(0)
	v_mfma_f32_32x32x16_bf16 v[96:111], v[176:179], v[212:215], v[96:111]
	v_mfma_f32_32x32x16_bf16 v[32:47], v[180:183], v[212:215], v[32:47]
	ds_read_b128 v[208:211], v151 offset:9216
	ds_read_b128 v[212:215], v151 offset:13824
	s_waitcnt vmcnt(7)
	ds_write_b128 v158, v[168:171]
	s_waitcnt vmcnt(6)
	ds_write_b128 v157, v[172:175]
	ds_read_b128 v[168:171], v152 offset:36896
	ds_read_b128 v[172:175], v152 offset:41504
	s_waitcnt lgkmcnt(5)
	v_mfma_f32_32x32x16_bf16 v[80:95], v[176:179], v[208:211], v[80:95]
	v_mfma_f32_32x32x16_bf16 v[16:31], v[180:183], v[208:211], v[16:31]
	ds_read_b128 v[208:211], v151 offset:32
	s_waitcnt lgkmcnt(5)
	v_mfma_f32_32x32x16_bf16 v[64:79], v[176:179], v[212:215], v[64:79]
	v_mfma_f32_32x32x16_bf16 v[0:15], v[180:183], v[212:215], v[0:15]
	ds_read_b128 v[212:215], v151 offset:4640
	s_setprio 0
	global_load_dwordx4 v[176:179], v[140:141], off offset:2048
	global_load_dwordx4 v[180:183], v[142:143], off offset:2048
	s_setprio 1
	s_waitcnt lgkmcnt(1)
	v_mfma_f32_32x32x16_bf16 v[112:127], v[168:171], v[208:211], v[112:127]
	v_mfma_f32_32x32x16_bf16 v[48:63], v[172:175], v[208:211], v[48:63]
	s_waitcnt lgkmcnt(0)
	v_mfma_f32_32x32x16_bf16 v[96:111], v[168:171], v[212:215], v[96:111]
	v_mfma_f32_32x32x16_bf16 v[32:47], v[172:175], v[212:215], v[32:47]
	ds_read_b128 v[208:211], v151 offset:9248
	ds_read_b128 v[212:215], v151 offset:13856
	s_waitcnt vmcnt(7)
	ds_write_b128 v154, v[160:163]
	s_waitcnt vmcnt(6)
	ds_write_b128 v153, v[164:167]
	ds_read_b128 v[160:163], v152 offset:36928
	ds_read_b128 v[164:167], v152 offset:41536
	s_waitcnt lgkmcnt(5)
	v_mfma_f32_32x32x16_bf16 v[80:95], v[168:171], v[208:211], v[80:95]
	v_mfma_f32_32x32x16_bf16 v[16:31], v[172:175], v[208:211], v[16:31]
	ds_read_b128 v[208:211], v151 offset:64
	s_waitcnt lgkmcnt(5)
	v_mfma_f32_32x32x16_bf16 v[64:79], v[168:171], v[212:215], v[64:79]
	v_mfma_f32_32x32x16_bf16 v[0:15], v[172:175], v[212:215], v[0:15]
	ds_read_b128 v[212:215], v151 offset:4672
	s_setprio 0
	global_load_dwordx4 v[168:171], v[132:133], off offset:2048
	global_load_dwordx4 v[172:175], v[134:135], off offset:2048
	s_setprio 1
	s_waitcnt lgkmcnt(1)
	v_mfma_f32_32x32x16_bf16 v[112:127], v[160:163], v[208:211], v[112:127]
	v_mfma_f32_32x32x16_bf16 v[48:63], v[164:167], v[208:211], v[48:63]
	s_waitcnt lgkmcnt(0)
	v_mfma_f32_32x32x16_bf16 v[96:111], v[160:163], v[212:215], v[96:111]
	v_mfma_f32_32x32x16_bf16 v[32:47], v[164:167], v[212:215], v[32:47]
	ds_read_b128 v[208:211], v151 offset:9280
	ds_read_b128 v[212:215], v151 offset:13888
	s_waitcnt vmcnt(7)
	ds_write_b128 v156, v[184:187]
	s_waitcnt vmcnt(6)
	ds_write_b128 v155, v[188:191]
	ds_read_b128 v[184:187], v152 offset:36960
	ds_read_b128 v[188:191], v152 offset:41568
	s_waitcnt lgkmcnt(5)
	v_mfma_f32_32x32x16_bf16 v[80:95], v[160:163], v[208:211], v[80:95]
	v_mfma_f32_32x32x16_bf16 v[16:31], v[164:167], v[208:211], v[16:31]
	ds_read_b128 v[208:211], v151 offset:96
	s_waitcnt lgkmcnt(5)
	v_mfma_f32_32x32x16_bf16 v[64:79], v[160:163], v[212:215], v[64:79]
	v_mfma_f32_32x32x16_bf16 v[0:15], v[164:167], v[212:215], v[0:15]
	ds_read_b128 v[212:215], v151 offset:4704
	s_setprio 0
	global_load_dwordx4 v[160:163], v[144:145], off offset:2048
	global_load_dwordx4 v[164:167], v[146:147], off offset:2048
	s_setprio 1
	s_waitcnt lgkmcnt(1)
	v_mfma_f32_32x32x16_bf16 v[112:127], v[184:187], v[208:211], v[112:127]
	v_mfma_f32_32x32x16_bf16 v[48:63], v[188:191], v[208:211], v[48:63]
	s_waitcnt lgkmcnt(0)
	v_mfma_f32_32x32x16_bf16 v[96:111], v[184:187], v[212:215], v[96:111]
	v_mfma_f32_32x32x16_bf16 v[32:47], v[188:191], v[212:215], v[32:47]
	ds_read_b128 v[208:211], v151 offset:9312
	ds_read_b128 v[212:215], v151 offset:13920
	s_waitcnt lgkmcnt(1)
	v_mfma_f32_32x32x16_bf16 v[80:95], v[184:187], v[208:211], v[80:95]
	v_mfma_f32_32x32x16_bf16 v[16:31], v[188:191], v[208:211], v[16:31]
	s_waitcnt lgkmcnt(0)
	v_mfma_f32_32x32x16_bf16 v[64:79], v[184:187], v[212:215], v[64:79]
	v_mfma_f32_32x32x16_bf16 v[0:15], v[188:191], v[212:215], v[0:15]
	s_setprio 0
	global_load_dwordx4 v[184:187], v[136:137], off offset:2176
	global_load_dwordx4 v[188:191], v[138:139], off offset:2176
	s_barrier
; template <bool trans>
; DI void gemm_core(const GTile& tl, const GTile& nx, bool has_next  , bool chain  , bool pre, u32x4 (&ra)[4], u32x4 (&rb)[4], char* smem, f32x16 (&acc)[2][4]) {
;     ...
;   const int nk = K / 64;
;   if (!pre) { G_LOAD(0); G_STORE(0); G_LOAD(1); }
;   for (int kt = 0; kt < nk; ++kt) {
;     __syncthreads();
;     G_COMPUTE(kt & 1, kt);
;   }
	s_waitcnt vmcnt(9)
	ds_write_b128 v148, v[194:197]
	s_waitcnt vmcnt(8)
	ds_write_b128 v148, v[198:201] offset:36864
	ds_read_b128 v[194:197], v150
	ds_read_b128 v[198:201], v150 offset:4608
	ds_read_b128 v[208:211], v149
	ds_read_b128 v[212:215], v149 offset:4608
	s_setprio 1
	s_waitcnt lgkmcnt(1)
	v_mfma_f32_32x32x16_bf16 v[112:127], v[194:197], v[208:211], v[112:127]
	v_mfma_f32_32x32x16_bf16 v[48:63], v[198:201], v[208:211], v[48:63]
	s_waitcnt lgkmcnt(0)
	v_mfma_f32_32x32x16_bf16 v[96:111], v[194:197], v[212:215], v[96:111]
	v_mfma_f32_32x32x16_bf16 v[32:47], v[198:201], v[212:215], v[32:47]
	ds_read_b128 v[208:211], v149 offset:9216
	ds_read_b128 v[212:215], v149 offset:13824
	s_waitcnt vmcnt(7)
	ds_write_b128 v148, v[176:179] offset:9216
	s_waitcnt vmcnt(6)
	ds_write_b128 v148, v[180:183] offset:46080
	ds_read_b128 v[176:179], v150 offset:32
	ds_read_b128 v[180:183], v150 offset:4640
	s_waitcnt lgkmcnt(5)
	v_mfma_f32_32x32x16_bf16 v[80:95], v[194:197], v[208:211], v[80:95]
	v_mfma_f32_32x32x16_bf16 v[16:31], v[198:201], v[208:211], v[16:31]
	ds_read_b128 v[208:211], v149 offset:32
	s_waitcnt lgkmcnt(5)
	v_mfma_f32_32x32x16_bf16 v[64:79], v[194:197], v[212:215], v[64:79]
	v_mfma_f32_32x32x16_bf16 v[0:15], v[198:201], v[212:215], v[0:15]
	ds_read_b128 v[212:215], v149 offset:4640
	s_setprio 0
	global_load_dwordx4 v[194:197], v[140:141], off offset:2176
	global_load_dwordx4 v[198:201], v[142:143], off offset:2176
	s_setprio 1
	s_waitcnt lgkmcnt(1)
	v_mfma_f32_32x32x16_bf16 v[112:127], v[176:179], v[208:211], v[112:127]
	v_mfma_f32_32x32x16_bf16 v[48:63], v[180:183], v[208:211], v[48:63]
	s_waitcnt lgkmcnt(0)
	v_mfma_f32_32x32x16_bf16 v[96:111], v[176:179], v[212:215], v[96:111]
	v_mfma_f32_32x32x16_bf16 v[32:47], v[180:183], v[212:215], v[32:47]
	ds_read_b128 v[208:211], v149 offset:9248
	ds_read_b128 v[212:215], v149 offset:13856
	s_waitcnt vmcnt(7)
	ds_write_b128 v148, v[168:171] offset:18432
	s_waitcnt vmcnt(6)
	ds_write_b128 v148, v[172:175] offset:55296
	ds_read_b128 v[168:171], v150 offset:64
	ds_read_b128 v[172:175], v150 offset:4672
	s_waitcnt lgkmcnt(5)
	v_mfma_f32_32x32x16_bf16 v[80:95], v[176:179], v[208:211], v[80:95]
	v_mfma_f32_32x32x16_bf16 v[16:31], v[180:183], v[208:211], v[16:31]
	ds_read_b128 v[208:211], v149 offset:64
	s_waitcnt lgkmcnt(5)
	v_mfma_f32_32x32x16_bf16 v[64:79], v[176:179], v[212:215], v[64:79]
	v_mfma_f32_32x32x16_bf16 v[0:15], v[180:183], v[212:215], v[0:15]
	ds_read_b128 v[212:215], v149 offset:4672
	s_setprio 0
	global_load_dwordx4 v[176:179], v[132:133], off offset:2176
	global_load_dwordx4 v[180:183], v[134:135], off offset:2176
	s_setprio 1
	s_waitcnt lgkmcnt(1)
	v_mfma_f32_32x32x16_bf16 v[112:127], v[168:171], v[208:211], v[112:127]
	v_mfma_f32_32x32x16_bf16 v[48:63], v[172:175], v[208:211], v[48:63]
	s_waitcnt lgkmcnt(0)
	v_mfma_f32_32x32x16_bf16 v[96:111], v[168:171], v[212:215], v[96:111]
	v_mfma_f32_32x32x16_bf16 v[32:47], v[172:175], v[212:215], v[32:47]
	ds_read_b128 v[208:211], v149 offset:9280
	ds_read_b128 v[212:215], v149 offset:13888
	s_waitcnt vmcnt(7)
	ds_write_b128 v148, v[160:163] offset:27648
	s_waitcnt vmcnt(6)
	ds_write_b128 v148, v[164:167] offset:64512
	ds_read_b128 v[160:163], v150 offset:96
	ds_read_b128 v[164:167], v150 offset:4704
	s_waitcnt lgkmcnt(5)
	v_mfma_f32_32x32x16_bf16 v[80:95], v[168:171], v[208:211], v[80:95]
	v_mfma_f32_32x32x16_bf16 v[16:31], v[172:175], v[208:211], v[16:31]
	ds_read_b128 v[208:211], v149 offset:96
	s_waitcnt lgkmcnt(5)
	v_mfma_f32_32x32x16_bf16 v[64:79], v[168:171], v[212:215], v[64:79]
	v_mfma_f32_32x32x16_bf16 v[0:15], v[172:175], v[212:215], v[0:15]
	ds_read_b128 v[212:215], v149 offset:4704
	s_setprio 0
	global_load_dwordx4 v[168:171], v[144:145], off offset:2176
	global_load_dwordx4 v[172:175], v[146:147], off offset:2176
	s_setprio 1
	s_waitcnt lgkmcnt(1)
	v_mfma_f32_32x32x16_bf16 v[112:127], v[160:163], v[208:211], v[112:127]
	v_mfma_f32_32x32x16_bf16 v[48:63], v[164:167], v[208:211], v[48:63]
	s_waitcnt lgkmcnt(0)
	v_mfma_f32_32x32x16_bf16 v[96:111], v[160:163], v[212:215], v[96:111]
	v_mfma_f32_32x32x16_bf16 v[32:47], v[164:167], v[212:215], v[32:47]
	ds_read_b128 v[208:211], v149 offset:9312
	ds_read_b128 v[212:215], v149 offset:13920
	s_waitcnt lgkmcnt(1)
	v_mfma_f32_32x32x16_bf16 v[80:95], v[160:163], v[208:211], v[80:95]
	v_mfma_f32_32x32x16_bf16 v[16:31], v[164:167], v[208:211], v[16:31]
	s_waitcnt lgkmcnt(0)
	v_mfma_f32_32x32x16_bf16 v[64:79], v[160:163], v[212:215], v[64:79]
	v_mfma_f32_32x32x16_bf16 v[0:15], v[164:167], v[212:215], v[0:15]
	s_setprio 0
	global_load_dwordx4 v[160:163], v[136:137], off offset:2304
	global_load_dwordx4 v[164:167], v[138:139], off offset:2304
	s_barrier
; template <bool trans>
; DI void gemm_core(const GTile& tl, const GTile& nx, bool has_next  , bool chain  , bool pre, u32x4 (&ra)[4], u32x4 (&rb)[4], char* smem, f32x16 (&acc)[2][4]) {
;     ...
;   const int nk = K / 64;
;   if (!pre) { G_LOAD(0); G_STORE(0); G_LOAD(1); }
;   for (int kt = 0; kt < nk; ++kt) {
;     __syncthreads();
;     G_COMPUTE(kt & 1, kt);
;   }
	s_waitcnt vmcnt(9)
	ds_write_b128 v192, v[184:187]
	s_waitcnt vmcnt(8)
	ds_write_b128 v159, v[188:191]
	ds_read_b128 v[184:187], v152 offset:36864
	ds_read_b128 v[188:191], v152 offset:41472
	ds_read_b128 v[208:211], v151
	ds_read_b128 v[212:215], v151 offset:4608
	s_setprio 1
	s_waitcnt lgkmcnt(1)
	v_mfma_f32_32x32x16_bf16 v[112:127], v[184:187], v[208:211], v[112:127]
	v_mfma_f32_32x32x16_bf16 v[48:63], v[188:191], v[208:211], v[48:63]
	s_waitcnt lgkmcnt(0)
	v_mfma_f32_32x32x16_bf16 v[96:111], v[184:187], v[212:215], v[96:111]
	v_mfma_f32_32x32x16_bf16 v[32:47], v[188:191], v[212:215], v[32:47]
	ds_read_b128 v[208:211], v151 offset:9216
	ds_read_b128 v[212:215], v151 offset:13824
	s_waitcnt vmcnt(7)
	ds_write_b128 v158, v[194:197]
	s_waitcnt vmcnt(6)
	ds_write_b128 v157, v[198:201]
	ds_read_b128 v[194:197], v152 offset:36896
	ds_read_b128 v[198:201], v152 offset:41504
	s_waitcnt lgkmcnt(5)
	v_mfma_f32_32x32x16_bf16 v[80:95], v[184:187], v[208:211], v[80:95]
	v_mfma_f32_32x32x16_bf16 v[16:31], v[188:191], v[208:211], v[16:31]
	ds_read_b128 v[208:211], v151 offset:32
	s_waitcnt lgkmcnt(5)
	v_mfma_f32_32x32x16_bf16 v[64:79], v[184:187], v[212:215], v[64:79]
	v_mfma_f32_32x32x16_bf16 v[0:15], v[188:191], v[212:215], v[0:15]
	ds_read_b128 v[212:215], v151 offset:4640
	s_setprio 0
	global_load_dwordx4 v[184:187], v[140:141], off offset:2304
	global_load_dwordx4 v[188:191], v[142:143], off offset:2304
	s_setprio 1
	s_waitcnt lgkmcnt(1)
	v_mfma_f32_32x32x16_bf16 v[112:127], v[194:197], v[208:211], v[112:127]
	v_mfma_f32_32x32x16_bf16 v[48:63], v[198:201], v[208:211], v[48:63]
	s_waitcnt lgkmcnt(0)
	v_mfma_f32_32x32x16_bf16 v[96:111], v[194:197], v[212:215], v[96:111]
	v_mfma_f32_32x32x16_bf16 v[32:47], v[198:201], v[212:215], v[32:47]
	ds_read_b128 v[208:211], v151 offset:9248
	ds_read_b128 v[212:215], v151 offset:13856
	s_waitcnt vmcnt(7)
	ds_write_b128 v154, v[176:179]
	s_waitcnt vmcnt(6)
	ds_write_b128 v153, v[180:183]
	ds_read_b128 v[176:179], v152 offset:36928
	ds_read_b128 v[180:183], v152 offset:41536
	s_waitcnt lgkmcnt(5)
	v_mfma_f32_32x32x16_bf16 v[80:95], v[194:197], v[208:211], v[80:95]
	v_mfma_f32_32x32x16_bf16 v[16:31], v[198:201], v[208:211], v[16:31]
	ds_read_b128 v[208:211], v151 offset:64
	s_waitcnt lgkmcnt(5)
	v_mfma_f32_32x32x16_bf16 v[64:79], v[194:197], v[212:215], v[64:79]
	v_mfma_f32_32x32x16_bf16 v[0:15], v[198:201], v[212:215], v[0:15]
	ds_read_b128 v[212:215], v151 offset:4672
	s_setprio 0
	global_load_dwordx4 v[194:197], v[132:133], off offset:2304
	global_load_dwordx4 v[198:201], v[134:135], off offset:2304
	s_setprio 1
	s_waitcnt lgkmcnt(1)
	v_mfma_f32_32x32x16_bf16 v[112:127], v[176:179], v[208:211], v[112:127]
	v_mfma_f32_32x32x16_bf16 v[48:63], v[180:183], v[208:211], v[48:63]
	s_waitcnt lgkmcnt(0)
	v_mfma_f32_32x32x16_bf16 v[96:111], v[176:179], v[212:215], v[96:111]
	v_mfma_f32_32x32x16_bf16 v[32:47], v[180:183], v[212:215], v[32:47]
	ds_read_b128 v[208:211], v151 offset:9280
	ds_read_b128 v[212:215], v151 offset:13888
	s_waitcnt vmcnt(7)
	ds_write_b128 v156, v[168:171]
	s_waitcnt vmcnt(6)
	ds_write_b128 v155, v[172:175]
	ds_read_b128 v[168:171], v152 offset:36960
	ds_read_b128 v[172:175], v152 offset:41568
	s_waitcnt lgkmcnt(5)
	v_mfma_f32_32x32x16_bf16 v[80:95], v[176:179], v[208:211], v[80:95]
	v_mfma_f32_32x32x16_bf16 v[16:31], v[180:183], v[208:211], v[16:31]
	ds_read_b128 v[208:211], v151 offset:96
	s_waitcnt lgkmcnt(5)
	v_mfma_f32_32x32x16_bf16 v[64:79], v[176:179], v[212:215], v[64:79]
	v_mfma_f32_32x32x16_bf16 v[0:15], v[180:183], v[212:215], v[0:15]
	ds_read_b128 v[212:215], v151 offset:4704
	s_setprio 0
	global_load_dwordx4 v[176:179], v[144:145], off offset:2304
	global_load_dwordx4 v[180:183], v[146:147], off offset:2304
	s_setprio 1
	s_waitcnt lgkmcnt(1)
	v_mfma_f32_32x32x16_bf16 v[112:127], v[168:171], v[208:211], v[112:127]
	v_mfma_f32_32x32x16_bf16 v[48:63], v[172:175], v[208:211], v[48:63]
	s_waitcnt lgkmcnt(0)
	v_mfma_f32_32x32x16_bf16 v[96:111], v[168:171], v[212:215], v[96:111]
	v_mfma_f32_32x32x16_bf16 v[32:47], v[172:175], v[212:215], v[32:47]
	ds_read_b128 v[208:211], v151 offset:9312
	ds_read_b128 v[212:215], v151 offset:13920
	s_waitcnt lgkmcnt(1)
	v_mfma_f32_32x32x16_bf16 v[80:95], v[168:171], v[208:211], v[80:95]
	v_mfma_f32_32x32x16_bf16 v[16:31], v[172:175], v[208:211], v[16:31]
	s_waitcnt lgkmcnt(0)
	v_mfma_f32_32x32x16_bf16 v[64:79], v[168:171], v[212:215], v[64:79]
	v_mfma_f32_32x32x16_bf16 v[0:15], v[172:175], v[212:215], v[0:15]
	s_setprio 0
	global_load_dwordx4 v[168:171], v[136:137], off offset:2432
	global_load_dwordx4 v[172:175], v[138:139], off offset:2432
	s_barrier
; template <bool trans>
; DI void gemm_core(const GTile& tl, const GTile& nx, bool has_next  , bool chain  , bool pre, u32x4 (&ra)[4], u32x4 (&rb)[4], char* smem, f32x16 (&acc)[2][4]) {
;     ...
;   const int nk = K / 64;
;   if (!pre) { G_LOAD(0); G_STORE(0); G_LOAD(1); }
;   for (int kt = 0; kt < nk; ++kt) {
;     __syncthreads();
;     G_COMPUTE(kt & 1, kt);
;   }
	s_waitcnt vmcnt(9)
	ds_write_b128 v148, v[160:163]
	s_waitcnt vmcnt(8)
	ds_write_b128 v148, v[164:167] offset:36864
	ds_read_b128 v[160:163], v150
	ds_read_b128 v[164:167], v150 offset:4608
	ds_read_b128 v[208:211], v149
	ds_read_b128 v[212:215], v149 offset:4608
	s_setprio 1
	s_waitcnt lgkmcnt(1)
	v_mfma_f32_32x32x16_bf16 v[112:127], v[160:163], v[208:211], v[112:127]
	v_mfma_f32_32x32x16_bf16 v[48:63], v[164:167], v[208:211], v[48:63]
	s_waitcnt lgkmcnt(0)
	v_mfma_f32_32x32x16_bf16 v[96:111], v[160:163], v[212:215], v[96:111]
	v_mfma_f32_32x32x16_bf16 v[32:47], v[164:167], v[212:215], v[32:47]
	ds_read_b128 v[208:211], v149 offset:9216
	ds_read_b128 v[212:215], v149 offset:13824
	s_waitcnt vmcnt(7)
	ds_write_b128 v148, v[184:187] offset:9216
	s_waitcnt vmcnt(6)
	ds_write_b128 v148, v[188:191] offset:46080
	ds_read_b128 v[184:187], v150 offset:32
	ds_read_b128 v[188:191], v150 offset:4640
	s_waitcnt lgkmcnt(5)
	v_mfma_f32_32x32x16_bf16 v[80:95], v[160:163], v[208:211], v[80:95]
	v_mfma_f32_32x32x16_bf16 v[16:31], v[164:167], v[208:211], v[16:31]
	ds_read_b128 v[208:211], v149 offset:32
	s_waitcnt lgkmcnt(5)
	v_mfma_f32_32x32x16_bf16 v[64:79], v[160:163], v[212:215], v[64:79]
	v_mfma_f32_32x32x16_bf16 v[0:15], v[164:167], v[212:215], v[0:15]
	ds_read_b128 v[212:215], v149 offset:4640
	s_setprio 0
	global_load_dwordx4 v[160:163], v[140:141], off offset:2432
	global_load_dwordx4 v[164:167], v[142:143], off offset:2432
	s_setprio 1
	s_waitcnt lgkmcnt(1)
	v_mfma_f32_32x32x16_bf16 v[112:127], v[184:187], v[208:211], v[112:127]
	v_mfma_f32_32x32x16_bf16 v[48:63], v[188:191], v[208:211], v[48:63]
	s_waitcnt lgkmcnt(0)
	v_mfma_f32_32x32x16_bf16 v[96:111], v[184:187], v[212:215], v[96:111]
	v_mfma_f32_32x32x16_bf16 v[32:47], v[188:191], v[212:215], v[32:47]
	ds_read_b128 v[208:211], v149 offset:9248
	ds_read_b128 v[212:215], v149 offset:13856
	s_waitcnt vmcnt(7)
	ds_write_b128 v148, v[194:197] offset:18432
	s_waitcnt vmcnt(6)
	ds_write_b128 v148, v[198:201] offset:55296
	ds_read_b128 v[194:197], v150 offset:64
	ds_read_b128 v[198:201], v150 offset:4672
	s_waitcnt lgkmcnt(5)
	v_mfma_f32_32x32x16_bf16 v[80:95], v[184:187], v[208:211], v[80:95]
	v_mfma_f32_32x32x16_bf16 v[16:31], v[188:191], v[208:211], v[16:31]
	ds_read_b128 v[208:211], v149 offset:64
	s_waitcnt lgkmcnt(5)
	v_mfma_f32_32x32x16_bf16 v[64:79], v[184:187], v[212:215], v[64:79]
	v_mfma_f32_32x32x16_bf16 v[0:15], v[188:191], v[212:215], v[0:15]
	ds_read_b128 v[212:215], v149 offset:4672
	s_setprio 0
	global_load_dwordx4 v[184:187], v[132:133], off offset:2432
	global_load_dwordx4 v[188:191], v[134:135], off offset:2432
	s_setprio 1
	s_waitcnt lgkmcnt(1)
	v_mfma_f32_32x32x16_bf16 v[112:127], v[194:197], v[208:211], v[112:127]
	v_mfma_f32_32x32x16_bf16 v[48:63], v[198:201], v[208:211], v[48:63]
	s_waitcnt lgkmcnt(0)
	v_mfma_f32_32x32x16_bf16 v[96:111], v[194:197], v[212:215], v[96:111]
	v_mfma_f32_32x32x16_bf16 v[32:47], v[198:201], v[212:215], v[32:47]
	ds_read_b128 v[208:211], v149 offset:9280
	ds_read_b128 v[212:215], v149 offset:13888
	s_waitcnt vmcnt(7)
	ds_write_b128 v148, v[176:179] offset:27648
	s_waitcnt vmcnt(6)
	ds_write_b128 v148, v[180:183] offset:64512
	ds_read_b128 v[176:179], v150 offset:96
	ds_read_b128 v[180:183], v150 offset:4704
	s_waitcnt lgkmcnt(5)
	v_mfma_f32_32x32x16_bf16 v[80:95], v[194:197], v[208:211], v[80:95]
	v_mfma_f32_32x32x16_bf16 v[16:31], v[198:201], v[208:211], v[16:31]
	ds_read_b128 v[208:211], v149 offset:96
	s_waitcnt lgkmcnt(5)
	v_mfma_f32_32x32x16_bf16 v[64:79], v[194:197], v[212:215], v[64:79]
	v_mfma_f32_32x32x16_bf16 v[0:15], v[198:201], v[212:215], v[0:15]
	ds_read_b128 v[212:215], v149 offset:4704
	s_setprio 0
	global_load_dwordx4 v[194:197], v[144:145], off offset:2432
	global_load_dwordx4 v[198:201], v[146:147], off offset:2432
	s_setprio 1
	s_waitcnt lgkmcnt(1)
	v_mfma_f32_32x32x16_bf16 v[112:127], v[176:179], v[208:211], v[112:127]
	v_mfma_f32_32x32x16_bf16 v[48:63], v[180:183], v[208:211], v[48:63]
	s_waitcnt lgkmcnt(0)
	v_mfma_f32_32x32x16_bf16 v[96:111], v[176:179], v[212:215], v[96:111]
	v_mfma_f32_32x32x16_bf16 v[32:47], v[180:183], v[212:215], v[32:47]
	ds_read_b128 v[208:211], v149 offset:9312
	ds_read_b128 v[212:215], v149 offset:13920
	s_waitcnt lgkmcnt(1)
	v_mfma_f32_32x32x16_bf16 v[80:95], v[176:179], v[208:211], v[80:95]
	v_mfma_f32_32x32x16_bf16 v[16:31], v[180:183], v[208:211], v[16:31]
	s_waitcnt lgkmcnt(0)
	v_mfma_f32_32x32x16_bf16 v[64:79], v[176:179], v[212:215], v[64:79]
	v_mfma_f32_32x32x16_bf16 v[0:15], v[180:183], v[212:215], v[0:15]
	s_setprio 0
	global_load_dwordx4 v[176:179], v[136:137], off offset:2560
	global_load_dwordx4 v[180:183], v[138:139], off offset:2560
	s_barrier
; template <bool trans>
; DI void gemm_core(const GTile& tl, const GTile& nx, bool has_next  , bool chain  , bool pre, u32x4 (&ra)[4], u32x4 (&rb)[4], char* smem, f32x16 (&acc)[2][4]) {
;     ...
;   const int nk = K / 64;
;   if (!pre) { G_LOAD(0); G_STORE(0); G_LOAD(1); }
;   for (int kt = 0; kt < nk; ++kt) {
;     __syncthreads();
;     G_COMPUTE(kt & 1, kt);
;   }
	s_waitcnt vmcnt(9)
	ds_write_b128 v192, v[168:171]
	s_waitcnt vmcnt(8)
	ds_write_b128 v159, v[172:175]
	ds_read_b128 v[168:171], v152 offset:36864
	ds_read_b128 v[172:175], v152 offset:41472
	ds_read_b128 v[208:211], v151
	ds_read_b128 v[212:215], v151 offset:4608
	s_setprio 1
	s_waitcnt lgkmcnt(1)
	v_mfma_f32_32x32x16_bf16 v[112:127], v[168:171], v[208:211], v[112:127]
	v_mfma_f32_32x32x16_bf16 v[48:63], v[172:175], v[208:211], v[48:63]
	s_waitcnt lgkmcnt(0)
	v_mfma_f32_32x32x16_bf16 v[96:111], v[168:171], v[212:215], v[96:111]
	v_mfma_f32_32x32x16_bf16 v[32:47], v[172:175], v[212:215], v[32:47]
	ds_read_b128 v[208:211], v151 offset:9216
	ds_read_b128 v[212:215], v151 offset:13824
	s_waitcnt vmcnt(7)
	ds_write_b128 v158, v[160:163]
	s_waitcnt vmcnt(6)
	ds_write_b128 v157, v[164:167]
	ds_read_b128 v[160:163], v152 offset:36896
	ds_read_b128 v[164:167], v152 offset:41504
	s_waitcnt lgkmcnt(5)
	v_mfma_f32_32x32x16_bf16 v[80:95], v[168:171], v[208:211], v[80:95]
	v_mfma_f32_32x32x16_bf16 v[16:31], v[172:175], v[208:211], v[16:31]
	ds_read_b128 v[208:211], v151 offset:32
	s_waitcnt lgkmcnt(5)
	v_mfma_f32_32x32x16_bf16 v[64:79], v[168:171], v[212:215], v[64:79]
	v_mfma_f32_32x32x16_bf16 v[0:15], v[172:175], v[212:215], v[0:15]
	ds_read_b128 v[212:215], v151 offset:4640
	s_setprio 0
	global_load_dwordx4 v[168:171], v[140:141], off offset:2560
	global_load_dwordx4 v[172:175], v[142:143], off offset:2560
	s_setprio 1
	s_waitcnt lgkmcnt(1)
	v_mfma_f32_32x32x16_bf16 v[112:127], v[160:163], v[208:211], v[112:127]
	v_mfma_f32_32x32x16_bf16 v[48:63], v[164:167], v[208:211], v[48:63]
	s_waitcnt lgkmcnt(0)
	v_mfma_f32_32x32x16_bf16 v[96:111], v[160:163], v[212:215], v[96:111]
	v_mfma_f32_32x32x16_bf16 v[32:47], v[164:167], v[212:215], v[32:47]
	ds_read_b128 v[208:211], v151 offset:9248
	ds_read_b128 v[212:215], v151 offset:13856
	s_waitcnt vmcnt(7)
	ds_write_b128 v154, v[184:187]
	s_waitcnt vmcnt(6)
	ds_write_b128 v153, v[188:191]
	ds_read_b128 v[184:187], v152 offset:36928
	ds_read_b128 v[188:191], v152 offset:41536
	s_waitcnt lgkmcnt(5)
	v_mfma_f32_32x32x16_bf16 v[80:95], v[160:163], v[208:211], v[80:95]
	v_mfma_f32_32x32x16_bf16 v[16:31], v[164:167], v[208:211], v[16:31]
	ds_read_b128 v[208:211], v151 offset:64
	s_waitcnt lgkmcnt(5)
	v_mfma_f32_32x32x16_bf16 v[64:79], v[160:163], v[212:215], v[64:79]
	v_mfma_f32_32x32x16_bf16 v[0:15], v[164:167], v[212:215], v[0:15]
	ds_read_b128 v[212:215], v151 offset:4672
	s_setprio 0
	global_load_dwordx4 v[160:163], v[132:133], off offset:2560
	global_load_dwordx4 v[164:167], v[134:135], off offset:2560
	s_setprio 1
	s_waitcnt lgkmcnt(1)
	v_mfma_f32_32x32x16_bf16 v[112:127], v[184:187], v[208:211], v[112:127]
	v_mfma_f32_32x32x16_bf16 v[48:63], v[188:191], v[208:211], v[48:63]
	s_waitcnt lgkmcnt(0)
	v_mfma_f32_32x32x16_bf16 v[96:111], v[184:187], v[212:215], v[96:111]
	v_mfma_f32_32x32x16_bf16 v[32:47], v[188:191], v[212:215], v[32:47]
	ds_read_b128 v[208:211], v151 offset:9280
	ds_read_b128 v[212:215], v151 offset:13888
	s_waitcnt vmcnt(7)
	ds_write_b128 v156, v[194:197]
	s_waitcnt vmcnt(6)
	ds_write_b128 v155, v[198:201]
	ds_read_b128 v[194:197], v152 offset:36960
	ds_read_b128 v[198:201], v152 offset:41568
	s_waitcnt lgkmcnt(5)
	v_mfma_f32_32x32x16_bf16 v[80:95], v[184:187], v[208:211], v[80:95]
	v_mfma_f32_32x32x16_bf16 v[16:31], v[188:191], v[208:211], v[16:31]
	ds_read_b128 v[208:211], v151 offset:96
	s_waitcnt lgkmcnt(5)
	v_mfma_f32_32x32x16_bf16 v[64:79], v[184:187], v[212:215], v[64:79]
	v_mfma_f32_32x32x16_bf16 v[0:15], v[188:191], v[212:215], v[0:15]
	ds_read_b128 v[212:215], v151 offset:4704
	s_setprio 0
	global_load_dwordx4 v[184:187], v[144:145], off offset:2560
	global_load_dwordx4 v[188:191], v[146:147], off offset:2560
	s_setprio 1
	s_waitcnt lgkmcnt(1)
	v_mfma_f32_32x32x16_bf16 v[112:127], v[194:197], v[208:211], v[112:127]
	v_mfma_f32_32x32x16_bf16 v[48:63], v[198:201], v[208:211], v[48:63]
	s_waitcnt lgkmcnt(0)
	v_mfma_f32_32x32x16_bf16 v[96:111], v[194:197], v[212:215], v[96:111]
	v_mfma_f32_32x32x16_bf16 v[32:47], v[198:201], v[212:215], v[32:47]
	ds_read_b128 v[208:211], v151 offset:9312
	ds_read_b128 v[212:215], v151 offset:13920
	s_waitcnt lgkmcnt(1)
	v_mfma_f32_32x32x16_bf16 v[80:95], v[194:197], v[208:211], v[80:95]
	v_mfma_f32_32x32x16_bf16 v[16:31], v[198:201], v[208:211], v[16:31]
	s_waitcnt lgkmcnt(0)
	v_mfma_f32_32x32x16_bf16 v[64:79], v[194:197], v[212:215], v[64:79]
	v_mfma_f32_32x32x16_bf16 v[0:15], v[198:201], v[212:215], v[0:15]
	s_setprio 0
	global_load_dwordx4 v[194:197], v[136:137], off offset:2688
	global_load_dwordx4 v[198:201], v[138:139], off offset:2688
	s_barrier
; template <bool trans>
; DI void gemm_core(const GTile& tl, const GTile& nx, bool has_next  , bool chain  , bool pre, u32x4 (&ra)[4], u32x4 (&rb)[4], char* smem, f32x16 (&acc)[2][4]) {
;     ...
;   const int nk = K / 64;
;   if (!pre) { G_LOAD(0); G_STORE(0); G_LOAD(1); }
;   for (int kt = 0; kt < nk; ++kt) {
;     __syncthreads();
;     G_COMPUTE(kt & 1, kt);
;   }
	s_waitcnt vmcnt(9)
	ds_write_b128 v148, v[176:179]
	s_waitcnt vmcnt(8)
	ds_write_b128 v148, v[180:183] offset:36864
	ds_read_b128 v[176:179], v150
	ds_read_b128 v[180:183], v150 offset:4608
	ds_read_b128 v[208:211], v149
	ds_read_b128 v[212:215], v149 offset:4608
	s_setprio 1
	s_waitcnt lgkmcnt(1)
	v_mfma_f32_32x32x16_bf16 v[112:127], v[176:179], v[208:211], v[112:127]
	v_mfma_f32_32x32x16_bf16 v[48:63], v[180:183], v[208:211], v[48:63]
	s_waitcnt lgkmcnt(0)
	v_mfma_f32_32x32x16_bf16 v[96:111], v[176:179], v[212:215], v[96:111]
	v_mfma_f32_32x32x16_bf16 v[32:47], v[180:183], v[212:215], v[32:47]
	ds_read_b128 v[208:211], v149 offset:9216
	ds_read_b128 v[212:215], v149 offset:13824
	s_waitcnt vmcnt(7)
	ds_write_b128 v148, v[168:171] offset:9216
	s_waitcnt vmcnt(6)
	ds_write_b128 v148, v[172:175] offset:46080
	ds_read_b128 v[168:171], v150 offset:32
	ds_read_b128 v[172:175], v150 offset:4640
	s_waitcnt lgkmcnt(5)
	v_mfma_f32_32x32x16_bf16 v[80:95], v[176:179], v[208:211], v[80:95]
	v_mfma_f32_32x32x16_bf16 v[16:31], v[180:183], v[208:211], v[16:31]
	ds_read_b128 v[208:211], v149 offset:32
	s_waitcnt lgkmcnt(5)
	v_mfma_f32_32x32x16_bf16 v[64:79], v[176:179], v[212:215], v[64:79]
	v_mfma_f32_32x32x16_bf16 v[0:15], v[180:183], v[212:215], v[0:15]
	ds_read_b128 v[212:215], v149 offset:4640
	s_setprio 0
	global_load_dwordx4 v[176:179], v[140:141], off offset:2688
	global_load_dwordx4 v[180:183], v[142:143], off offset:2688
	s_setprio 1
	s_waitcnt lgkmcnt(1)
	v_mfma_f32_32x32x16_bf16 v[112:127], v[168:171], v[208:211], v[112:127]
	v_mfma_f32_32x32x16_bf16 v[48:63], v[172:175], v[208:211], v[48:63]
	s_waitcnt lgkmcnt(0)
	v_mfma_f32_32x32x16_bf16 v[96:111], v[168:171], v[212:215], v[96:111]
	v_mfma_f32_32x32x16_bf16 v[32:47], v[172:175], v[212:215], v[32:47]
	ds_read_b128 v[208:211], v149 offset:9248
	ds_read_b128 v[212:215], v149 offset:13856
	s_waitcnt vmcnt(7)
	ds_write_b128 v148, v[160:163] offset:18432
	s_waitcnt vmcnt(6)
	ds_write_b128 v148, v[164:167] offset:55296
	ds_read_b128 v[160:163], v150 offset:64
	ds_read_b128 v[164:167], v150 offset:4672
	s_waitcnt lgkmcnt(5)
	v_mfma_f32_32x32x16_bf16 v[80:95], v[168:171], v[208:211], v[80:95]
	v_mfma_f32_32x32x16_bf16 v[16:31], v[172:175], v[208:211], v[16:31]
	ds_read_b128 v[208:211], v149 offset:64
	s_waitcnt lgkmcnt(5)
	v_mfma_f32_32x32x16_bf16 v[64:79], v[168:171], v[212:215], v[64:79]
	v_mfma_f32_32x32x16_bf16 v[0:15], v[172:175], v[212:215], v[0:15]
	ds_read_b128 v[212:215], v149 offset:4672
	s_setprio 0
	global_load_dwordx4 v[168:171], v[132:133], off offset:2688
	global_load_dwordx4 v[172:175], v[134:135], off offset:2688
	s_setprio 1
	s_waitcnt lgkmcnt(1)
	v_mfma_f32_32x32x16_bf16 v[112:127], v[160:163], v[208:211], v[112:127]
	v_mfma_f32_32x32x16_bf16 v[48:63], v[164:167], v[208:211], v[48:63]
	s_waitcnt lgkmcnt(0)
	v_mfma_f32_32x32x16_bf16 v[96:111], v[160:163], v[212:215], v[96:111]
	v_mfma_f32_32x32x16_bf16 v[32:47], v[164:167], v[212:215], v[32:47]
	ds_read_b128 v[208:211], v149 offset:9280
	ds_read_b128 v[212:215], v149 offset:13888
	s_waitcnt vmcnt(7)
	ds_write_b128 v148, v[184:187] offset:27648
	s_waitcnt vmcnt(6)
	ds_write_b128 v148, v[188:191] offset:64512
	ds_read_b128 v[184:187], v150 offset:96
	ds_read_b128 v[188:191], v150 offset:4704
	s_waitcnt lgkmcnt(5)
	v_mfma_f32_32x32x16_bf16 v[80:95], v[160:163], v[208:211], v[80:95]
	v_mfma_f32_32x32x16_bf16 v[16:31], v[164:167], v[208:211], v[16:31]
	ds_read_b128 v[208:211], v149 offset:96
	s_waitcnt lgkmcnt(5)
	v_mfma_f32_32x32x16_bf16 v[64:79], v[160:163], v[212:215], v[64:79]
	v_mfma_f32_32x32x16_bf16 v[0:15], v[164:167], v[212:215], v[0:15]
	ds_read_b128 v[212:215], v149 offset:4704
	s_setprio 0
	global_load_dwordx4 v[160:163], v[144:145], off offset:2688
	global_load_dwordx4 v[164:167], v[146:147], off offset:2688
	s_setprio 1
	s_waitcnt lgkmcnt(1)
	v_mfma_f32_32x32x16_bf16 v[112:127], v[184:187], v[208:211], v[112:127]
	v_mfma_f32_32x32x16_bf16 v[48:63], v[188:191], v[208:211], v[48:63]
	s_waitcnt lgkmcnt(0)
	v_mfma_f32_32x32x16_bf16 v[96:111], v[184:187], v[212:215], v[96:111]
	v_mfma_f32_32x32x16_bf16 v[32:47], v[188:191], v[212:215], v[32:47]
	ds_read_b128 v[208:211], v149 offset:9312
	ds_read_b128 v[212:215], v149 offset:13920
	s_waitcnt lgkmcnt(1)
	v_mfma_f32_32x32x16_bf16 v[80:95], v[184:187], v[208:211], v[80:95]
	v_mfma_f32_32x32x16_bf16 v[16:31], v[188:191], v[208:211], v[16:31]
	s_waitcnt lgkmcnt(0)
	v_mfma_f32_32x32x16_bf16 v[64:79], v[184:187], v[212:215], v[64:79]
	v_mfma_f32_32x32x16_bf16 v[0:15], v[188:191], v[212:215], v[0:15]
	s_setprio 0
	global_load_dwordx4 v[184:187], v[136:137], off offset:2816
	global_load_dwordx4 v[188:191], v[138:139], off offset:2816
	s_barrier
; template <bool trans>
; DI void gemm_core(const GTile& tl, const GTile& nx, bool has_next  , bool chain  , bool pre, u32x4 (&ra)[4], u32x4 (&rb)[4], char* smem, f32x16 (&acc)[2][4]) {
;     ...
;   const int nk = K / 64;
;   if (!pre) { G_LOAD(0); G_STORE(0); G_LOAD(1); }
;   for (int kt = 0; kt < nk; ++kt) {
;     __syncthreads();
;     G_COMPUTE(kt & 1, kt);
;   }
	s_waitcnt vmcnt(9)
	ds_write_b128 v192, v[194:197]
	s_waitcnt vmcnt(8)
	ds_write_b128 v159, v[198:201]
	ds_read_b128 v[194:197], v152 offset:36864
	ds_read_b128 v[198:201], v152 offset:41472
	ds_read_b128 v[208:211], v151
	ds_read_b128 v[212:215], v151 offset:4608
	s_setprio 1
	s_waitcnt lgkmcnt(1)
	v_mfma_f32_32x32x16_bf16 v[112:127], v[194:197], v[208:211], v[112:127]
	v_mfma_f32_32x32x16_bf16 v[48:63], v[198:201], v[208:211], v[48:63]
	s_waitcnt lgkmcnt(0)
	v_mfma_f32_32x32x16_bf16 v[96:111], v[194:197], v[212:215], v[96:111]
	v_mfma_f32_32x32x16_bf16 v[32:47], v[198:201], v[212:215], v[32:47]
	ds_read_b128 v[208:211], v151 offset:9216
	ds_read_b128 v[212:215], v151 offset:13824
	s_waitcnt vmcnt(7)
	ds_write_b128 v158, v[176:179]
	s_waitcnt vmcnt(6)
	ds_write_b128 v157, v[180:183]
	ds_read_b128 v[176:179], v152 offset:36896
	ds_read_b128 v[180:183], v152 offset:41504
	s_waitcnt lgkmcnt(5)
	v_mfma_f32_32x32x16_bf16 v[80:95], v[194:197], v[208:211], v[80:95]
	v_mfma_f32_32x32x16_bf16 v[16:31], v[198:201], v[208:211], v[16:31]
	ds_read_b128 v[208:211], v151 offset:32
	s_waitcnt lgkmcnt(5)
	v_mfma_f32_32x32x16_bf16 v[64:79], v[194:197], v[212:215], v[64:79]
	v_mfma_f32_32x32x16_bf16 v[0:15], v[198:201], v[212:215], v[0:15]
	ds_read_b128 v[212:215], v151 offset:4640
	s_setprio 0
	global_load_dwordx4 v[194:197], v[140:141], off offset:2816
	global_load_dwordx4 v[198:201], v[142:143], off offset:2816
	s_setprio 1
	s_waitcnt lgkmcnt(1)
	v_mfma_f32_32x32x16_bf16 v[112:127], v[176:179], v[208:211], v[112:127]
	v_mfma_f32_32x32x16_bf16 v[48:63], v[180:183], v[208:211], v[48:63]
	s_waitcnt lgkmcnt(0)
	v_mfma_f32_32x32x16_bf16 v[96:111], v[176:179], v[212:215], v[96:111]
	v_mfma_f32_32x32x16_bf16 v[32:47], v[180:183], v[212:215], v[32:47]
	ds_read_b128 v[208:211], v151 offset:9248
	ds_read_b128 v[212:215], v151 offset:13856
	s_waitcnt vmcnt(7)
	ds_write_b128 v154, v[168:171]
	s_waitcnt vmcnt(6)
	ds_write_b128 v153, v[172:175]
	ds_read_b128 v[168:171], v152 offset:36928
	ds_read_b128 v[172:175], v152 offset:41536
	s_waitcnt lgkmcnt(5)
	v_mfma_f32_32x32x16_bf16 v[80:95], v[176:179], v[208:211], v[80:95]
	v_mfma_f32_32x32x16_bf16 v[16:31], v[180:183], v[208:211], v[16:31]
	ds_read_b128 v[208:211], v151 offset:64
	s_waitcnt lgkmcnt(5)
	v_mfma_f32_32x32x16_bf16 v[64:79], v[176:179], v[212:215], v[64:79]
	v_mfma_f32_32x32x16_bf16 v[0:15], v[180:183], v[212:215], v[0:15]
	ds_read_b128 v[212:215], v151 offset:4672
	s_setprio 0
	global_load_dwordx4 v[176:179], v[132:133], off offset:2816
	global_load_dwordx4 v[180:183], v[134:135], off offset:2816
	s_setprio 1
	s_waitcnt lgkmcnt(1)
	v_mfma_f32_32x32x16_bf16 v[112:127], v[168:171], v[208:211], v[112:127]
	v_mfma_f32_32x32x16_bf16 v[48:63], v[172:175], v[208:211], v[48:63]
	s_waitcnt lgkmcnt(0)
	v_mfma_f32_32x32x16_bf16 v[96:111], v[168:171], v[212:215], v[96:111]
	v_mfma_f32_32x32x16_bf16 v[32:47], v[172:175], v[212:215], v[32:47]
	ds_read_b128 v[208:211], v151 offset:9280
	ds_read_b128 v[212:215], v151 offset:13888
	s_waitcnt vmcnt(7)
	ds_write_b128 v156, v[160:163]
	s_waitcnt vmcnt(6)
	ds_write_b128 v155, v[164:167]
	ds_read_b128 v[160:163], v152 offset:36960
	ds_read_b128 v[164:167], v152 offset:41568
	s_waitcnt lgkmcnt(5)
	v_mfma_f32_32x32x16_bf16 v[80:95], v[168:171], v[208:211], v[80:95]
	v_mfma_f32_32x32x16_bf16 v[16:31], v[172:175], v[208:211], v[16:31]
	ds_read_b128 v[208:211], v151 offset:96
	s_waitcnt lgkmcnt(5)
	v_mfma_f32_32x32x16_bf16 v[64:79], v[168:171], v[212:215], v[64:79]
	v_mfma_f32_32x32x16_bf16 v[0:15], v[172:175], v[212:215], v[0:15]
	ds_read_b128 v[212:215], v151 offset:4704
	s_setprio 0
	global_load_dwordx4 v[168:171], v[144:145], off offset:2816
	global_load_dwordx4 v[172:175], v[146:147], off offset:2816
	s_setprio 1
	s_waitcnt lgkmcnt(1)
	v_mfma_f32_32x32x16_bf16 v[112:127], v[160:163], v[208:211], v[112:127]
	v_mfma_f32_32x32x16_bf16 v[48:63], v[164:167], v[208:211], v[48:63]
	s_waitcnt lgkmcnt(0)
	v_mfma_f32_32x32x16_bf16 v[96:111], v[160:163], v[212:215], v[96:111]
	v_mfma_f32_32x32x16_bf16 v[32:47], v[164:167], v[212:215], v[32:47]
	ds_read_b128 v[208:211], v151 offset:9312
	ds_read_b128 v[212:215], v151 offset:13920
	s_waitcnt lgkmcnt(1)
	v_mfma_f32_32x32x16_bf16 v[80:95], v[160:163], v[208:211], v[80:95]
	v_mfma_f32_32x32x16_bf16 v[16:31], v[164:167], v[208:211], v[16:31]
	s_waitcnt lgkmcnt(0)
	v_mfma_f32_32x32x16_bf16 v[64:79], v[160:163], v[212:215], v[64:79]
	v_mfma_f32_32x32x16_bf16 v[0:15], v[164:167], v[212:215], v[0:15]
	s_setprio 0
	global_load_dwordx4 v[160:163], v[136:137], off offset:2944
	global_load_dwordx4 v[164:167], v[138:139], off offset:2944
	s_barrier
; template <bool trans>
; DI void gemm_core(const GTile& tl, const GTile& nx, bool has_next  , bool chain  , bool pre, u32x4 (&ra)[4], u32x4 (&rb)[4], char* smem, f32x16 (&acc)[2][4]) {
;     ...
;   const int nk = K / 64;
;   if (!pre) { G_LOAD(0); G_STORE(0); G_LOAD(1); }
;   for (int kt = 0; kt < nk; ++kt) {
;     __syncthreads();
;     G_COMPUTE(kt & 1, kt);
;   }
	s_waitcnt vmcnt(9)
	ds_write_b128 v148, v[184:187]
	s_waitcnt vmcnt(8)
	ds_write_b128 v148, v[188:191] offset:36864
	ds_read_b128 v[184:187], v150
	ds_read_b128 v[188:191], v150 offset:4608
	ds_read_b128 v[208:211], v149
	ds_read_b128 v[212:215], v149 offset:4608
	s_setprio 1
	s_waitcnt lgkmcnt(1)
	v_mfma_f32_32x32x16_bf16 v[112:127], v[184:187], v[208:211], v[112:127]
	v_mfma_f32_32x32x16_bf16 v[48:63], v[188:191], v[208:211], v[48:63]
	s_waitcnt lgkmcnt(0)
	v_mfma_f32_32x32x16_bf16 v[96:111], v[184:187], v[212:215], v[96:111]
	v_mfma_f32_32x32x16_bf16 v[32:47], v[188:191], v[212:215], v[32:47]
	ds_read_b128 v[208:211], v149 offset:9216
	ds_read_b128 v[212:215], v149 offset:13824
	s_waitcnt vmcnt(7)
	ds_write_b128 v148, v[194:197] offset:9216
	s_waitcnt vmcnt(6)
	ds_write_b128 v148, v[198:201] offset:46080
	ds_read_b128 v[194:197], v150 offset:32
	ds_read_b128 v[198:201], v150 offset:4640
	s_waitcnt lgkmcnt(5)
	v_mfma_f32_32x32x16_bf16 v[80:95], v[184:187], v[208:211], v[80:95]
	v_mfma_f32_32x32x16_bf16 v[16:31], v[188:191], v[208:211], v[16:31]
	ds_read_b128 v[208:211], v149 offset:32
	s_waitcnt lgkmcnt(5)
	v_mfma_f32_32x32x16_bf16 v[64:79], v[184:187], v[212:215], v[64:79]
	v_mfma_f32_32x32x16_bf16 v[0:15], v[188:191], v[212:215], v[0:15]
	ds_read_b128 v[212:215], v149 offset:4640
	s_setprio 0
	global_load_dwordx4 v[184:187], v[140:141], off offset:2944
	global_load_dwordx4 v[188:191], v[142:143], off offset:2944
	s_setprio 1
	s_waitcnt lgkmcnt(1)
	v_mfma_f32_32x32x16_bf16 v[112:127], v[194:197], v[208:211], v[112:127]
	v_mfma_f32_32x32x16_bf16 v[48:63], v[198:201], v[208:211], v[48:63]
	s_waitcnt lgkmcnt(0)
	v_mfma_f32_32x32x16_bf16 v[96:111], v[194:197], v[212:215], v[96:111]
	v_mfma_f32_32x32x16_bf16 v[32:47], v[198:201], v[212:215], v[32:47]
	ds_read_b128 v[208:211], v149 offset:9248
	ds_read_b128 v[212:215], v149 offset:13856
	s_waitcnt vmcnt(7)
	ds_write_b128 v148, v[176:179] offset:18432
	s_waitcnt vmcnt(6)
	ds_write_b128 v148, v[180:183] offset:55296
	ds_read_b128 v[176:179], v150 offset:64
	ds_read_b128 v[180:183], v150 offset:4672
	s_waitcnt lgkmcnt(5)
	v_mfma_f32_32x32x16_bf16 v[80:95], v[194:197], v[208:211], v[80:95]
	v_mfma_f32_32x32x16_bf16 v[16:31], v[198:201], v[208:211], v[16:31]
	ds_read_b128 v[208:211], v149 offset:64
	s_waitcnt lgkmcnt(5)
	v_mfma_f32_32x32x16_bf16 v[64:79], v[194:197], v[212:215], v[64:79]
	v_mfma_f32_32x32x16_bf16 v[0:15], v[198:201], v[212:215], v[0:15]
	ds_read_b128 v[212:215], v149 offset:4672
	s_setprio 0
	global_load_dwordx4 v[194:197], v[132:133], off offset:2944
	global_load_dwordx4 v[198:201], v[134:135], off offset:2944
	s_setprio 1
	s_waitcnt lgkmcnt(1)
	v_mfma_f32_32x32x16_bf16 v[112:127], v[176:179], v[208:211], v[112:127]
	v_mfma_f32_32x32x16_bf16 v[48:63], v[180:183], v[208:211], v[48:63]
	s_waitcnt lgkmcnt(0)
	v_mfma_f32_32x32x16_bf16 v[96:111], v[176:179], v[212:215], v[96:111]
	v_mfma_f32_32x32x16_bf16 v[32:47], v[180:183], v[212:215], v[32:47]
	ds_read_b128 v[208:211], v149 offset:9280
	ds_read_b128 v[212:215], v149 offset:13888
	s_waitcnt vmcnt(7)
	ds_write_b128 v148, v[168:171] offset:27648
	s_waitcnt vmcnt(6)
	ds_write_b128 v148, v[172:175] offset:64512
	ds_read_b128 v[168:171], v150 offset:96
	ds_read_b128 v[172:175], v150 offset:4704
	s_waitcnt lgkmcnt(5)
	v_mfma_f32_32x32x16_bf16 v[80:95], v[176:179], v[208:211], v[80:95]
	v_mfma_f32_32x32x16_bf16 v[16:31], v[180:183], v[208:211], v[16:31]
	ds_read_b128 v[208:211], v149 offset:96
	s_waitcnt lgkmcnt(5)
	v_mfma_f32_32x32x16_bf16 v[64:79], v[176:179], v[212:215], v[64:79]
	v_mfma_f32_32x32x16_bf16 v[0:15], v[180:183], v[212:215], v[0:15]
	ds_read_b128 v[212:215], v149 offset:4704
	s_setprio 0
	global_load_dwordx4 v[176:179], v[144:145], off offset:2944
	global_load_dwordx4 v[180:183], v[146:147], off offset:2944
	s_setprio 1
	s_waitcnt lgkmcnt(1)
	v_mfma_f32_32x32x16_bf16 v[112:127], v[168:171], v[208:211], v[112:127]
	v_mfma_f32_32x32x16_bf16 v[48:63], v[172:175], v[208:211], v[48:63]
	s_waitcnt lgkmcnt(0)
	v_mfma_f32_32x32x16_bf16 v[96:111], v[168:171], v[212:215], v[96:111]
	v_mfma_f32_32x32x16_bf16 v[32:47], v[172:175], v[212:215], v[32:47]
	ds_read_b128 v[208:211], v149 offset:9312
	ds_read_b128 v[212:215], v149 offset:13920
	s_waitcnt lgkmcnt(1)
	v_mfma_f32_32x32x16_bf16 v[80:95], v[168:171], v[208:211], v[80:95]
	v_mfma_f32_32x32x16_bf16 v[16:31], v[172:175], v[208:211], v[16:31]
	s_waitcnt lgkmcnt(0)
	v_mfma_f32_32x32x16_bf16 v[64:79], v[168:171], v[212:215], v[64:79]
	v_mfma_f32_32x32x16_bf16 v[0:15], v[172:175], v[212:215], v[0:15]
	s_setprio 0
	global_load_dwordx4 v[168:171], v[136:137], off offset:3072
	global_load_dwordx4 v[172:175], v[138:139], off offset:3072
	s_barrier
; template <bool trans>
; DI void gemm_core(const GTile& tl, const GTile& nx, bool has_next  , bool chain  , bool pre, u32x4 (&ra)[4], u32x4 (&rb)[4], char* smem, f32x16 (&acc)[2][4]) {
;     ...
;   const int nk = K / 64;
;   if (!pre) { G_LOAD(0); G_STORE(0); G_LOAD(1); }
;   for (int kt = 0; kt < nk; ++kt) {
;     __syncthreads();
;     G_COMPUTE(kt & 1, kt);
;   }
	s_waitcnt vmcnt(9)
	ds_write_b128 v192, v[160:163]
	s_waitcnt vmcnt(8)
	ds_write_b128 v159, v[164:167]
	ds_read_b128 v[160:163], v152 offset:36864
	ds_read_b128 v[164:167], v152 offset:41472
	ds_read_b128 v[208:211], v151
	ds_read_b128 v[212:215], v151 offset:4608
	s_setprio 1
	s_waitcnt lgkmcnt(1)
	v_mfma_f32_32x32x16_bf16 v[112:127], v[160:163], v[208:211], v[112:127]
	v_mfma_f32_32x32x16_bf16 v[48:63], v[164:167], v[208:211], v[48:63]
	s_waitcnt lgkmcnt(0)
	v_mfma_f32_32x32x16_bf16 v[96:111], v[160:163], v[212:215], v[96:111]
	v_mfma_f32_32x32x16_bf16 v[32:47], v[164:167], v[212:215], v[32:47]
	ds_read_b128 v[208:211], v151 offset:9216
	ds_read_b128 v[212:215], v151 offset:13824
	s_waitcnt vmcnt(7)
	ds_write_b128 v158, v[184:187]
	s_waitcnt vmcnt(6)
	ds_write_b128 v157, v[188:191]
	ds_read_b128 v[184:187], v152 offset:36896
	ds_read_b128 v[188:191], v152 offset:41504
	s_waitcnt lgkmcnt(5)
	v_mfma_f32_32x32x16_bf16 v[80:95], v[160:163], v[208:211], v[80:95]
	v_mfma_f32_32x32x16_bf16 v[16:31], v[164:167], v[208:211], v[16:31]
	ds_read_b128 v[208:211], v151 offset:32
	s_waitcnt lgkmcnt(5)
	v_mfma_f32_32x32x16_bf16 v[64:79], v[160:163], v[212:215], v[64:79]
	v_mfma_f32_32x32x16_bf16 v[0:15], v[164:167], v[212:215], v[0:15]
	ds_read_b128 v[212:215], v151 offset:4640
	s_setprio 0
	global_load_dwordx4 v[160:163], v[140:141], off offset:3072
	global_load_dwordx4 v[164:167], v[142:143], off offset:3072
	s_setprio 1
	s_waitcnt lgkmcnt(1)
	v_mfma_f32_32x32x16_bf16 v[112:127], v[184:187], v[208:211], v[112:127]
	v_mfma_f32_32x32x16_bf16 v[48:63], v[188:191], v[208:211], v[48:63]
	s_waitcnt lgkmcnt(0)
	v_mfma_f32_32x32x16_bf16 v[96:111], v[184:187], v[212:215], v[96:111]
	v_mfma_f32_32x32x16_bf16 v[32:47], v[188:191], v[212:215], v[32:47]
	ds_read_b128 v[208:211], v151 offset:9248
	ds_read_b128 v[212:215], v151 offset:13856
	s_waitcnt vmcnt(7)
	ds_write_b128 v154, v[194:197]
	s_waitcnt vmcnt(6)
	ds_write_b128 v153, v[198:201]
	ds_read_b128 v[194:197], v152 offset:36928
	ds_read_b128 v[198:201], v152 offset:41536
	s_waitcnt lgkmcnt(5)
	v_mfma_f32_32x32x16_bf16 v[80:95], v[184:187], v[208:211], v[80:95]
	v_mfma_f32_32x32x16_bf16 v[16:31], v[188:191], v[208:211], v[16:31]
	ds_read_b128 v[208:211], v151 offset:64
	s_waitcnt lgkmcnt(5)
	v_mfma_f32_32x32x16_bf16 v[64:79], v[184:187], v[212:215], v[64:79]
	v_mfma_f32_32x32x16_bf16 v[0:15], v[188:191], v[212:215], v[0:15]
	ds_read_b128 v[212:215], v151 offset:4672
	s_setprio 0
	global_load_dwordx4 v[184:187], v[132:133], off offset:3072
	global_load_dwordx4 v[188:191], v[134:135], off offset:3072
	s_setprio 1
	s_waitcnt lgkmcnt(1)
	v_mfma_f32_32x32x16_bf16 v[112:127], v[194:197], v[208:211], v[112:127]
	v_mfma_f32_32x32x16_bf16 v[48:63], v[198:201], v[208:211], v[48:63]
	s_waitcnt lgkmcnt(0)
	v_mfma_f32_32x32x16_bf16 v[96:111], v[194:197], v[212:215], v[96:111]
	v_mfma_f32_32x32x16_bf16 v[32:47], v[198:201], v[212:215], v[32:47]
	ds_read_b128 v[208:211], v151 offset:9280
	ds_read_b128 v[212:215], v151 offset:13888
	s_waitcnt vmcnt(7)
	ds_write_b128 v156, v[176:179]
	s_waitcnt vmcnt(6)
	ds_write_b128 v155, v[180:183]
	ds_read_b128 v[176:179], v152 offset:36960
	ds_read_b128 v[180:183], v152 offset:41568
	s_waitcnt lgkmcnt(5)
	v_mfma_f32_32x32x16_bf16 v[80:95], v[194:197], v[208:211], v[80:95]
	v_mfma_f32_32x32x16_bf16 v[16:31], v[198:201], v[208:211], v[16:31]
	ds_read_b128 v[208:211], v151 offset:96
	s_waitcnt lgkmcnt(5)
	v_mfma_f32_32x32x16_bf16 v[64:79], v[194:197], v[212:215], v[64:79]
	v_mfma_f32_32x32x16_bf16 v[0:15], v[198:201], v[212:215], v[0:15]
	ds_read_b128 v[212:215], v151 offset:4704
	s_setprio 0
	global_load_dwordx4 v[194:197], v[144:145], off offset:3072
	global_load_dwordx4 v[198:201], v[146:147], off offset:3072
	s_setprio 1
	s_waitcnt lgkmcnt(1)
	v_mfma_f32_32x32x16_bf16 v[112:127], v[176:179], v[208:211], v[112:127]
	v_mfma_f32_32x32x16_bf16 v[48:63], v[180:183], v[208:211], v[48:63]
	s_waitcnt lgkmcnt(0)
	v_mfma_f32_32x32x16_bf16 v[96:111], v[176:179], v[212:215], v[96:111]
	v_mfma_f32_32x32x16_bf16 v[32:47], v[180:183], v[212:215], v[32:47]
	ds_read_b128 v[208:211], v151 offset:9312
	ds_read_b128 v[212:215], v151 offset:13920
	s_waitcnt lgkmcnt(1)
	v_mfma_f32_32x32x16_bf16 v[80:95], v[176:179], v[208:211], v[80:95]
	v_mfma_f32_32x32x16_bf16 v[16:31], v[180:183], v[208:211], v[16:31]
	s_waitcnt lgkmcnt(0)
	v_mfma_f32_32x32x16_bf16 v[64:79], v[176:179], v[212:215], v[64:79]
	v_mfma_f32_32x32x16_bf16 v[0:15], v[180:183], v[212:215], v[0:15]
	s_setprio 0
	global_load_dwordx4 v[176:179], v[136:137], off offset:3200
	global_load_dwordx4 v[180:183], v[138:139], off offset:3200
	s_barrier
; template <bool trans>
; DI void gemm_core(const GTile& tl, const GTile& nx, bool has_next  , bool chain  , bool pre, u32x4 (&ra)[4], u32x4 (&rb)[4], char* smem, f32x16 (&acc)[2][4]) {
;     ...
;   const int nk = K / 64;
;   if (!pre) { G_LOAD(0); G_STORE(0); G_LOAD(1); }
;   for (int kt = 0; kt < nk; ++kt) {
;     __syncthreads();
;     G_COMPUTE(kt & 1, kt);
;   }
	s_waitcnt vmcnt(9)
	ds_write_b128 v148, v[168:171]
	s_waitcnt vmcnt(8)
	ds_write_b128 v148, v[172:175] offset:36864
	ds_read_b128 v[168:171], v150
	ds_read_b128 v[172:175], v150 offset:4608
	ds_read_b128 v[208:211], v149
	ds_read_b128 v[212:215], v149 offset:4608
	s_setprio 1
	s_waitcnt lgkmcnt(1)
	v_mfma_f32_32x32x16_bf16 v[112:127], v[168:171], v[208:211], v[112:127]
	v_mfma_f32_32x32x16_bf16 v[48:63], v[172:175], v[208:211], v[48:63]
	s_waitcnt lgkmcnt(0)
	v_mfma_f32_32x32x16_bf16 v[96:111], v[168:171], v[212:215], v[96:111]
	v_mfma_f32_32x32x16_bf16 v[32:47], v[172:175], v[212:215], v[32:47]
	ds_read_b128 v[208:211], v149 offset:9216
	ds_read_b128 v[212:215], v149 offset:13824
	s_waitcnt vmcnt(7)
	ds_write_b128 v148, v[160:163] offset:9216
	s_waitcnt vmcnt(6)
	ds_write_b128 v148, v[164:167] offset:46080
	ds_read_b128 v[160:163], v150 offset:32
	ds_read_b128 v[164:167], v150 offset:4640
	s_waitcnt lgkmcnt(5)
	v_mfma_f32_32x32x16_bf16 v[80:95], v[168:171], v[208:211], v[80:95]
	v_mfma_f32_32x32x16_bf16 v[16:31], v[172:175], v[208:211], v[16:31]
	ds_read_b128 v[208:211], v149 offset:32
	s_waitcnt lgkmcnt(5)
	v_mfma_f32_32x32x16_bf16 v[64:79], v[168:171], v[212:215], v[64:79]
	v_mfma_f32_32x32x16_bf16 v[0:15], v[172:175], v[212:215], v[0:15]
	ds_read_b128 v[212:215], v149 offset:4640
	s_setprio 0
	global_load_dwordx4 v[168:171], v[140:141], off offset:3200
	global_load_dwordx4 v[172:175], v[142:143], off offset:3200
	s_setprio 1
	s_waitcnt lgkmcnt(1)
	v_mfma_f32_32x32x16_bf16 v[112:127], v[160:163], v[208:211], v[112:127]
	v_mfma_f32_32x32x16_bf16 v[48:63], v[164:167], v[208:211], v[48:63]
	s_waitcnt lgkmcnt(0)
	v_mfma_f32_32x32x16_bf16 v[96:111], v[160:163], v[212:215], v[96:111]
	v_mfma_f32_32x32x16_bf16 v[32:47], v[164:167], v[212:215], v[32:47]
	ds_read_b128 v[208:211], v149 offset:9248
	ds_read_b128 v[212:215], v149 offset:13856
	s_waitcnt vmcnt(7)
	ds_write_b128 v148, v[184:187] offset:18432
	s_waitcnt vmcnt(6)
	ds_write_b128 v148, v[188:191] offset:55296
	ds_read_b128 v[184:187], v150 offset:64
	ds_read_b128 v[188:191], v150 offset:4672
	s_waitcnt lgkmcnt(5)
	v_mfma_f32_32x32x16_bf16 v[80:95], v[160:163], v[208:211], v[80:95]
	v_mfma_f32_32x32x16_bf16 v[16:31], v[164:167], v[208:211], v[16:31]
	ds_read_b128 v[208:211], v149 offset:64
	s_waitcnt lgkmcnt(5)
	v_mfma_f32_32x32x16_bf16 v[64:79], v[160:163], v[212:215], v[64:79]
	v_mfma_f32_32x32x16_bf16 v[0:15], v[164:167], v[212:215], v[0:15]
	ds_read_b128 v[212:215], v149 offset:4672
	s_setprio 0
	global_load_dwordx4 v[160:163], v[132:133], off offset:3200
	global_load_dwordx4 v[164:167], v[134:135], off offset:3200
	s_setprio 1
	s_waitcnt lgkmcnt(1)
	v_mfma_f32_32x32x16_bf16 v[112:127], v[184:187], v[208:211], v[112:127]
	v_mfma_f32_32x32x16_bf16 v[48:63], v[188:191], v[208:211], v[48:63]
	s_waitcnt lgkmcnt(0)
	v_mfma_f32_32x32x16_bf16 v[96:111], v[184:187], v[212:215], v[96:111]
	v_mfma_f32_32x32x16_bf16 v[32:47], v[188:191], v[212:215], v[32:47]
	ds_read_b128 v[208:211], v149 offset:9280
	ds_read_b128 v[212:215], v149 offset:13888
	s_waitcnt vmcnt(7)
	ds_write_b128 v148, v[194:197] offset:27648
	s_waitcnt vmcnt(6)
	ds_write_b128 v148, v[198:201] offset:64512
	ds_read_b128 v[194:197], v150 offset:96
	ds_read_b128 v[198:201], v150 offset:4704
	s_waitcnt lgkmcnt(5)
	v_mfma_f32_32x32x16_bf16 v[80:95], v[184:187], v[208:211], v[80:95]
	v_mfma_f32_32x32x16_bf16 v[16:31], v[188:191], v[208:211], v[16:31]
	ds_read_b128 v[208:211], v149 offset:96
	s_waitcnt lgkmcnt(5)
	v_mfma_f32_32x32x16_bf16 v[64:79], v[184:187], v[212:215], v[64:79]
	v_mfma_f32_32x32x16_bf16 v[0:15], v[188:191], v[212:215], v[0:15]
	ds_read_b128 v[212:215], v149 offset:4704
	s_setprio 0
	global_load_dwordx4 v[184:187], v[144:145], off offset:3200
	global_load_dwordx4 v[188:191], v[146:147], off offset:3200
	s_setprio 1
	s_waitcnt lgkmcnt(1)
	v_mfma_f32_32x32x16_bf16 v[112:127], v[194:197], v[208:211], v[112:127]
	v_mfma_f32_32x32x16_bf16 v[48:63], v[198:201], v[208:211], v[48:63]
	s_waitcnt lgkmcnt(0)
	v_mfma_f32_32x32x16_bf16 v[96:111], v[194:197], v[212:215], v[96:111]
	v_mfma_f32_32x32x16_bf16 v[32:47], v[198:201], v[212:215], v[32:47]
	ds_read_b128 v[208:211], v149 offset:9312
	ds_read_b128 v[212:215], v149 offset:13920
	s_waitcnt lgkmcnt(1)
	v_mfma_f32_32x32x16_bf16 v[80:95], v[194:197], v[208:211], v[80:95]
	v_mfma_f32_32x32x16_bf16 v[16:31], v[198:201], v[208:211], v[16:31]
	s_waitcnt lgkmcnt(0)
	v_mfma_f32_32x32x16_bf16 v[64:79], v[194:197], v[212:215], v[64:79]
	v_mfma_f32_32x32x16_bf16 v[0:15], v[198:201], v[212:215], v[0:15]
	s_setprio 0
	global_load_dwordx4 v[194:197], v[136:137], off offset:3328
	global_load_dwordx4 v[198:201], v[138:139], off offset:3328
	s_barrier
; template <bool trans>
; DI void gemm_core(const GTile& tl, const GTile& nx, bool has_next  , bool chain  , bool pre, u32x4 (&ra)[4], u32x4 (&rb)[4], char* smem, f32x16 (&acc)[2][4]) {
;     ...
;   const int nk = K / 64;
;   if (!pre) { G_LOAD(0); G_STORE(0); G_LOAD(1); }
;   for (int kt = 0; kt < nk; ++kt) {
;     __syncthreads();
;     G_COMPUTE(kt & 1, kt);
;   }
	s_waitcnt vmcnt(9)
	ds_write_b128 v192, v[176:179]
	s_waitcnt vmcnt(8)
	ds_write_b128 v159, v[180:183]
	ds_read_b128 v[176:179], v152 offset:36864
	ds_read_b128 v[180:183], v152 offset:41472
	ds_read_b128 v[208:211], v151
	ds_read_b128 v[212:215], v151 offset:4608
	s_setprio 1
	s_waitcnt lgkmcnt(1)
	v_mfma_f32_32x32x16_bf16 v[112:127], v[176:179], v[208:211], v[112:127]
	v_mfma_f32_32x32x16_bf16 v[48:63], v[180:183], v[208:211], v[48:63]
	s_waitcnt lgkmcnt(0)
	v_mfma_f32_32x32x16_bf16 v[96:111], v[176:179], v[212:215], v[96:111]
	v_mfma_f32_32x32x16_bf16 v[32:47], v[180:183], v[212:215], v[32:47]
	ds_read_b128 v[208:211], v151 offset:9216
	ds_read_b128 v[212:215], v151 offset:13824
	s_waitcnt vmcnt(7)
	ds_write_b128 v158, v[168:171]
	s_waitcnt vmcnt(6)
	ds_write_b128 v157, v[172:175]
	ds_read_b128 v[168:171], v152 offset:36896
	ds_read_b128 v[172:175], v152 offset:41504
	s_waitcnt lgkmcnt(5)
	v_mfma_f32_32x32x16_bf16 v[80:95], v[176:179], v[208:211], v[80:95]
	v_mfma_f32_32x32x16_bf16 v[16:31], v[180:183], v[208:211], v[16:31]
	ds_read_b128 v[208:211], v151 offset:32
	s_waitcnt lgkmcnt(5)
	v_mfma_f32_32x32x16_bf16 v[64:79], v[176:179], v[212:215], v[64:79]
	v_mfma_f32_32x32x16_bf16 v[0:15], v[180:183], v[212:215], v[0:15]
	ds_read_b128 v[212:215], v151 offset:4640
	s_setprio 0
	global_load_dwordx4 v[176:179], v[140:141], off offset:3328
	global_load_dwordx4 v[180:183], v[142:143], off offset:3328
	s_setprio 1
	s_waitcnt lgkmcnt(1)
	v_mfma_f32_32x32x16_bf16 v[112:127], v[168:171], v[208:211], v[112:127]
	v_mfma_f32_32x32x16_bf16 v[48:63], v[172:175], v[208:211], v[48:63]
	s_waitcnt lgkmcnt(0)
	v_mfma_f32_32x32x16_bf16 v[96:111], v[168:171], v[212:215], v[96:111]
	v_mfma_f32_32x32x16_bf16 v[32:47], v[172:175], v[212:215], v[32:47]
	ds_read_b128 v[208:211], v151 offset:9248
	ds_read_b128 v[212:215], v151 offset:13856
	s_waitcnt vmcnt(7)
	ds_write_b128 v154, v[160:163]
	s_waitcnt vmcnt(6)
	ds_write_b128 v153, v[164:167]
	ds_read_b128 v[160:163], v152 offset:36928
	ds_read_b128 v[164:167], v152 offset:41536
	s_waitcnt lgkmcnt(5)
	v_mfma_f32_32x32x16_bf16 v[80:95], v[168:171], v[208:211], v[80:95]
	v_mfma_f32_32x32x16_bf16 v[16:31], v[172:175], v[208:211], v[16:31]
	ds_read_b128 v[208:211], v151 offset:64
	s_waitcnt lgkmcnt(5)
	v_mfma_f32_32x32x16_bf16 v[64:79], v[168:171], v[212:215], v[64:79]
	v_mfma_f32_32x32x16_bf16 v[0:15], v[172:175], v[212:215], v[0:15]
	ds_read_b128 v[212:215], v151 offset:4672
	s_setprio 0
	global_load_dwordx4 v[168:171], v[132:133], off offset:3328
	global_load_dwordx4 v[172:175], v[134:135], off offset:3328
	s_setprio 1
	s_waitcnt lgkmcnt(1)
	v_mfma_f32_32x32x16_bf16 v[112:127], v[160:163], v[208:211], v[112:127]
	v_mfma_f32_32x32x16_bf16 v[48:63], v[164:167], v[208:211], v[48:63]
	s_waitcnt lgkmcnt(0)
	v_mfma_f32_32x32x16_bf16 v[96:111], v[160:163], v[212:215], v[96:111]
	v_mfma_f32_32x32x16_bf16 v[32:47], v[164:167], v[212:215], v[32:47]
	ds_read_b128 v[208:211], v151 offset:9280
	ds_read_b128 v[212:215], v151 offset:13888
	s_waitcnt vmcnt(7)
	ds_write_b128 v156, v[184:187]
	s_waitcnt vmcnt(6)
	ds_write_b128 v155, v[188:191]
	ds_read_b128 v[184:187], v152 offset:36960
	ds_read_b128 v[188:191], v152 offset:41568
	s_waitcnt lgkmcnt(5)
	v_mfma_f32_32x32x16_bf16 v[80:95], v[160:163], v[208:211], v[80:95]
	v_mfma_f32_32x32x16_bf16 v[16:31], v[164:167], v[208:211], v[16:31]
	ds_read_b128 v[208:211], v151 offset:96
	s_waitcnt lgkmcnt(5)
	v_mfma_f32_32x32x16_bf16 v[64:79], v[160:163], v[212:215], v[64:79]
	v_mfma_f32_32x32x16_bf16 v[0:15], v[164:167], v[212:215], v[0:15]
	ds_read_b128 v[212:215], v151 offset:4704
	s_setprio 0
	global_load_dwordx4 v[160:163], v[144:145], off offset:3328
	global_load_dwordx4 v[164:167], v[146:147], off offset:3328
	s_setprio 1
	s_waitcnt lgkmcnt(1)
	v_mfma_f32_32x32x16_bf16 v[112:127], v[184:187], v[208:211], v[112:127]
	v_mfma_f32_32x32x16_bf16 v[48:63], v[188:191], v[208:211], v[48:63]
	s_waitcnt lgkmcnt(0)
	v_mfma_f32_32x32x16_bf16 v[96:111], v[184:187], v[212:215], v[96:111]
	v_mfma_f32_32x32x16_bf16 v[32:47], v[188:191], v[212:215], v[32:47]
	ds_read_b128 v[208:211], v151 offset:9312
	ds_read_b128 v[212:215], v151 offset:13920
	s_waitcnt lgkmcnt(1)
	v_mfma_f32_32x32x16_bf16 v[80:95], v[184:187], v[208:211], v[80:95]
	v_mfma_f32_32x32x16_bf16 v[16:31], v[188:191], v[208:211], v[16:31]
	s_waitcnt lgkmcnt(0)
	v_mfma_f32_32x32x16_bf16 v[64:79], v[184:187], v[212:215], v[64:79]
	v_mfma_f32_32x32x16_bf16 v[0:15], v[188:191], v[212:215], v[0:15]
	s_setprio 0
	global_load_dwordx4 v[184:187], v[136:137], off offset:3456
	global_load_dwordx4 v[188:191], v[138:139], off offset:3456
	s_barrier
; template <bool trans>
; DI void gemm_core(const GTile& tl, const GTile& nx, bool has_next  , bool chain  , bool pre, u32x4 (&ra)[4], u32x4 (&rb)[4], char* smem, f32x16 (&acc)[2][4]) {
;     ...
;   const int nk = K / 64;
;   if (!pre) { G_LOAD(0); G_STORE(0); G_LOAD(1); }
;   for (int kt = 0; kt < nk; ++kt) {
;     __syncthreads();
;     G_COMPUTE(kt & 1, kt);
;   }
	s_waitcnt vmcnt(9)
	ds_write_b128 v148, v[194:197]
	s_waitcnt vmcnt(8)
	ds_write_b128 v148, v[198:201] offset:36864
	ds_read_b128 v[194:197], v150
	ds_read_b128 v[198:201], v150 offset:4608
	ds_read_b128 v[208:211], v149
	ds_read_b128 v[212:215], v149 offset:4608
	s_setprio 1
	s_waitcnt lgkmcnt(1)
	v_mfma_f32_32x32x16_bf16 v[112:127], v[194:197], v[208:211], v[112:127]
	v_mfma_f32_32x32x16_bf16 v[48:63], v[198:201], v[208:211], v[48:63]
	s_waitcnt lgkmcnt(0)
	v_mfma_f32_32x32x16_bf16 v[96:111], v[194:197], v[212:215], v[96:111]
	v_mfma_f32_32x32x16_bf16 v[32:47], v[198:201], v[212:215], v[32:47]
	ds_read_b128 v[208:211], v149 offset:9216
	ds_read_b128 v[212:215], v149 offset:13824
	s_waitcnt vmcnt(7)
	ds_write_b128 v148, v[176:179] offset:9216
	s_waitcnt vmcnt(6)
	ds_write_b128 v148, v[180:183] offset:46080
	ds_read_b128 v[176:179], v150 offset:32
	ds_read_b128 v[180:183], v150 offset:4640
	s_waitcnt lgkmcnt(5)
	v_mfma_f32_32x32x16_bf16 v[80:95], v[194:197], v[208:211], v[80:95]
	v_mfma_f32_32x32x16_bf16 v[16:31], v[198:201], v[208:211], v[16:31]
	ds_read_b128 v[208:211], v149 offset:32
	s_waitcnt lgkmcnt(5)
	v_mfma_f32_32x32x16_bf16 v[64:79], v[194:197], v[212:215], v[64:79]
	v_mfma_f32_32x32x16_bf16 v[0:15], v[198:201], v[212:215], v[0:15]
	ds_read_b128 v[212:215], v149 offset:4640
	s_setprio 0
	global_load_dwordx4 v[194:197], v[140:141], off offset:3456
	global_load_dwordx4 v[198:201], v[142:143], off offset:3456
	s_setprio 1
	s_waitcnt lgkmcnt(1)
	v_mfma_f32_32x32x16_bf16 v[112:127], v[176:179], v[208:211], v[112:127]
	v_mfma_f32_32x32x16_bf16 v[48:63], v[180:183], v[208:211], v[48:63]
	s_waitcnt lgkmcnt(0)
	v_mfma_f32_32x32x16_bf16 v[96:111], v[176:179], v[212:215], v[96:111]
	v_mfma_f32_32x32x16_bf16 v[32:47], v[180:183], v[212:215], v[32:47]
	ds_read_b128 v[208:211], v149 offset:9248
	ds_read_b128 v[212:215], v149 offset:13856
	s_waitcnt vmcnt(7)
	ds_write_b128 v148, v[168:171] offset:18432
	s_waitcnt vmcnt(6)
	ds_write_b128 v148, v[172:175] offset:55296
	ds_read_b128 v[168:171], v150 offset:64
	ds_read_b128 v[172:175], v150 offset:4672
	s_waitcnt lgkmcnt(5)
	v_mfma_f32_32x32x16_bf16 v[80:95], v[176:179], v[208:211], v[80:95]
	v_mfma_f32_32x32x16_bf16 v[16:31], v[180:183], v[208:211], v[16:31]
	ds_read_b128 v[208:211], v149 offset:64
	s_waitcnt lgkmcnt(5)
	v_mfma_f32_32x32x16_bf16 v[64:79], v[176:179], v[212:215], v[64:79]
	v_mfma_f32_32x32x16_bf16 v[0:15], v[180:183], v[212:215], v[0:15]
	ds_read_b128 v[212:215], v149 offset:4672
	s_setprio 0
	global_load_dwordx4 v[176:179], v[132:133], off offset:3456
	global_load_dwordx4 v[180:183], v[134:135], off offset:3456
	s_setprio 1
	s_waitcnt lgkmcnt(1)
	v_mfma_f32_32x32x16_bf16 v[112:127], v[168:171], v[208:211], v[112:127]
	v_mfma_f32_32x32x16_bf16 v[48:63], v[172:175], v[208:211], v[48:63]
	s_waitcnt lgkmcnt(0)
	v_mfma_f32_32x32x16_bf16 v[96:111], v[168:171], v[212:215], v[96:111]
	v_mfma_f32_32x32x16_bf16 v[32:47], v[172:175], v[212:215], v[32:47]
	ds_read_b128 v[208:211], v149 offset:9280
	ds_read_b128 v[212:215], v149 offset:13888
	s_waitcnt vmcnt(7)
	ds_write_b128 v148, v[160:163] offset:27648
	s_waitcnt vmcnt(6)
	ds_write_b128 v148, v[164:167] offset:64512
	ds_read_b128 v[160:163], v150 offset:96
	ds_read_b128 v[164:167], v150 offset:4704
	s_waitcnt lgkmcnt(5)
	v_mfma_f32_32x32x16_bf16 v[80:95], v[168:171], v[208:211], v[80:95]
	v_mfma_f32_32x32x16_bf16 v[16:31], v[172:175], v[208:211], v[16:31]
	ds_read_b128 v[208:211], v149 offset:96
	s_waitcnt lgkmcnt(5)
	v_mfma_f32_32x32x16_bf16 v[64:79], v[168:171], v[212:215], v[64:79]
	v_mfma_f32_32x32x16_bf16 v[0:15], v[172:175], v[212:215], v[0:15]
	ds_read_b128 v[212:215], v149 offset:4704
	s_setprio 0
	global_load_dwordx4 v[168:171], v[144:145], off offset:3456
	global_load_dwordx4 v[172:175], v[146:147], off offset:3456
	s_setprio 1
	s_waitcnt lgkmcnt(1)
	v_mfma_f32_32x32x16_bf16 v[112:127], v[160:163], v[208:211], v[112:127]
	v_mfma_f32_32x32x16_bf16 v[48:63], v[164:167], v[208:211], v[48:63]
	s_waitcnt lgkmcnt(0)
	v_mfma_f32_32x32x16_bf16 v[96:111], v[160:163], v[212:215], v[96:111]
	v_mfma_f32_32x32x16_bf16 v[32:47], v[164:167], v[212:215], v[32:47]
	ds_read_b128 v[208:211], v149 offset:9312
	ds_read_b128 v[212:215], v149 offset:13920
	s_waitcnt lgkmcnt(1)
	v_mfma_f32_32x32x16_bf16 v[80:95], v[160:163], v[208:211], v[80:95]
	v_mfma_f32_32x32x16_bf16 v[16:31], v[164:167], v[208:211], v[16:31]
	s_waitcnt lgkmcnt(0)
	v_mfma_f32_32x32x16_bf16 v[64:79], v[160:163], v[212:215], v[64:79]
	v_mfma_f32_32x32x16_bf16 v[0:15], v[164:167], v[212:215], v[0:15]
	s_setprio 0
	global_load_dwordx4 v[160:163], v[136:137], off offset:3584
	global_load_dwordx4 v[164:167], v[138:139], off offset:3584
	s_barrier
; template <bool trans>
; DI void gemm_core(const GTile& tl, const GTile& nx, bool has_next  , bool chain  , bool pre, u32x4 (&ra)[4], u32x4 (&rb)[4], char* smem, f32x16 (&acc)[2][4]) {
;     ...
;   const int nk = K / 64;
;   if (!pre) { G_LOAD(0); G_STORE(0); G_LOAD(1); }
;   for (int kt = 0; kt < nk; ++kt) {
;     __syncthreads();
;     G_COMPUTE(kt & 1, kt);
;   }
	s_waitcnt vmcnt(9)
	ds_write_b128 v192, v[184:187]
	s_waitcnt vmcnt(8)
	ds_write_b128 v159, v[188:191]
	ds_read_b128 v[184:187], v152 offset:36864
	ds_read_b128 v[188:191], v152 offset:41472
	ds_read_b128 v[208:211], v151
	ds_read_b128 v[212:215], v151 offset:4608
	s_setprio 1
	s_waitcnt lgkmcnt(1)
	v_mfma_f32_32x32x16_bf16 v[112:127], v[184:187], v[208:211], v[112:127]
	v_mfma_f32_32x32x16_bf16 v[48:63], v[188:191], v[208:211], v[48:63]
	s_waitcnt lgkmcnt(0)
	v_mfma_f32_32x32x16_bf16 v[96:111], v[184:187], v[212:215], v[96:111]
	v_mfma_f32_32x32x16_bf16 v[32:47], v[188:191], v[212:215], v[32:47]
	ds_read_b128 v[208:211], v151 offset:9216
	ds_read_b128 v[212:215], v151 offset:13824
	s_waitcnt vmcnt(7)
	ds_write_b128 v158, v[194:197]
	s_waitcnt vmcnt(6)
	ds_write_b128 v157, v[198:201]
	ds_read_b128 v[194:197], v152 offset:36896
	ds_read_b128 v[198:201], v152 offset:41504
	s_waitcnt lgkmcnt(5)
	v_mfma_f32_32x32x16_bf16 v[80:95], v[184:187], v[208:211], v[80:95]
	v_mfma_f32_32x32x16_bf16 v[16:31], v[188:191], v[208:211], v[16:31]
	ds_read_b128 v[208:211], v151 offset:32
	s_waitcnt lgkmcnt(5)
	v_mfma_f32_32x32x16_bf16 v[64:79], v[184:187], v[212:215], v[64:79]
	v_mfma_f32_32x32x16_bf16 v[0:15], v[188:191], v[212:215], v[0:15]
	ds_read_b128 v[212:215], v151 offset:4640
	s_setprio 0
	global_load_dwordx4 v[184:187], v[140:141], off offset:3584
	global_load_dwordx4 v[188:191], v[142:143], off offset:3584
	s_setprio 1
	s_waitcnt lgkmcnt(1)
	v_mfma_f32_32x32x16_bf16 v[112:127], v[194:197], v[208:211], v[112:127]
	v_mfma_f32_32x32x16_bf16 v[48:63], v[198:201], v[208:211], v[48:63]
	s_waitcnt lgkmcnt(0)
	v_mfma_f32_32x32x16_bf16 v[96:111], v[194:197], v[212:215], v[96:111]
	v_mfma_f32_32x32x16_bf16 v[32:47], v[198:201], v[212:215], v[32:47]
	ds_read_b128 v[208:211], v151 offset:9248
	ds_read_b128 v[212:215], v151 offset:13856
	s_waitcnt vmcnt(7)
	ds_write_b128 v154, v[176:179]
	s_waitcnt vmcnt(6)
	ds_write_b128 v153, v[180:183]
	ds_read_b128 v[176:179], v152 offset:36928
	ds_read_b128 v[180:183], v152 offset:41536
	s_waitcnt lgkmcnt(5)
	v_mfma_f32_32x32x16_bf16 v[80:95], v[194:197], v[208:211], v[80:95]
	v_mfma_f32_32x32x16_bf16 v[16:31], v[198:201], v[208:211], v[16:31]
	ds_read_b128 v[208:211], v151 offset:64
	s_waitcnt lgkmcnt(5)
	v_mfma_f32_32x32x16_bf16 v[64:79], v[194:197], v[212:215], v[64:79]
	v_mfma_f32_32x32x16_bf16 v[0:15], v[198:201], v[212:215], v[0:15]
	ds_read_b128 v[212:215], v151 offset:4672
	s_setprio 0
	global_load_dwordx4 v[194:197], v[132:133], off offset:3584
	global_load_dwordx4 v[198:201], v[134:135], off offset:3584
	s_setprio 1
	s_waitcnt lgkmcnt(1)
	v_mfma_f32_32x32x16_bf16 v[112:127], v[176:179], v[208:211], v[112:127]
	v_mfma_f32_32x32x16_bf16 v[48:63], v[180:183], v[208:211], v[48:63]
	s_waitcnt lgkmcnt(0)
	v_mfma_f32_32x32x16_bf16 v[96:111], v[176:179], v[212:215], v[96:111]
	v_mfma_f32_32x32x16_bf16 v[32:47], v[180:183], v[212:215], v[32:47]
	ds_read_b128 v[208:211], v151 offset:9280
	ds_read_b128 v[212:215], v151 offset:13888
	s_waitcnt vmcnt(7)
	ds_write_b128 v156, v[168:171]
	s_waitcnt vmcnt(6)
	ds_write_b128 v155, v[172:175]
	ds_read_b128 v[168:171], v152 offset:36960
	ds_read_b128 v[172:175], v152 offset:41568
	s_waitcnt lgkmcnt(5)
	v_mfma_f32_32x32x16_bf16 v[80:95], v[176:179], v[208:211], v[80:95]
	v_mfma_f32_32x32x16_bf16 v[16:31], v[180:183], v[208:211], v[16:31]
	ds_read_b128 v[208:211], v151 offset:96
	s_waitcnt lgkmcnt(5)
	v_mfma_f32_32x32x16_bf16 v[64:79], v[176:179], v[212:215], v[64:79]
	v_mfma_f32_32x32x16_bf16 v[0:15], v[180:183], v[212:215], v[0:15]
	ds_read_b128 v[212:215], v151 offset:4704
	s_setprio 0
	global_load_dwordx4 v[176:179], v[144:145], off offset:3584
	global_load_dwordx4 v[180:183], v[146:147], off offset:3584
	s_setprio 1
	s_waitcnt lgkmcnt(1)
	v_mfma_f32_32x32x16_bf16 v[112:127], v[168:171], v[208:211], v[112:127]
	v_mfma_f32_32x32x16_bf16 v[48:63], v[172:175], v[208:211], v[48:63]
	s_waitcnt lgkmcnt(0)
	v_mfma_f32_32x32x16_bf16 v[96:111], v[168:171], v[212:215], v[96:111]
	v_mfma_f32_32x32x16_bf16 v[32:47], v[172:175], v[212:215], v[32:47]
	ds_read_b128 v[208:211], v151 offset:9312
	ds_read_b128 v[212:215], v151 offset:13920
	s_waitcnt lgkmcnt(1)
	v_mfma_f32_32x32x16_bf16 v[80:95], v[168:171], v[208:211], v[80:95]
	v_mfma_f32_32x32x16_bf16 v[16:31], v[172:175], v[208:211], v[16:31]
	s_waitcnt lgkmcnt(0)
	v_mfma_f32_32x32x16_bf16 v[64:79], v[168:171], v[212:215], v[64:79]
	v_mfma_f32_32x32x16_bf16 v[0:15], v[172:175], v[212:215], v[0:15]
	s_setprio 0
	global_load_dwordx4 v[168:171], v[136:137], off offset:3712
	global_load_dwordx4 v[172:175], v[138:139], off offset:3712
	s_barrier
; template <bool trans>
; DI void gemm_core(const GTile& tl, const GTile& nx, bool has_next  , bool chain  , bool pre, u32x4 (&ra)[4], u32x4 (&rb)[4], char* smem, f32x16 (&acc)[2][4]) {
;     ...
;   const int nk = K / 64;
;   if (!pre) { G_LOAD(0); G_STORE(0); G_LOAD(1); }
;   for (int kt = 0; kt < nk; ++kt) {
;     __syncthreads();
;     G_COMPUTE(kt & 1, kt);
;   }
	s_waitcnt vmcnt(9)
	ds_write_b128 v148, v[160:163]
	s_waitcnt vmcnt(8)
	ds_write_b128 v148, v[164:167] offset:36864
	ds_read_b128 v[160:163], v150
	ds_read_b128 v[164:167], v150 offset:4608
	ds_read_b128 v[208:211], v149
	ds_read_b128 v[212:215], v149 offset:4608
	s_setprio 1
	s_waitcnt lgkmcnt(1)
	v_mfma_f32_32x32x16_bf16 v[112:127], v[160:163], v[208:211], v[112:127]
	v_mfma_f32_32x32x16_bf16 v[48:63], v[164:167], v[208:211], v[48:63]
	s_waitcnt lgkmcnt(0)
	v_mfma_f32_32x32x16_bf16 v[96:111], v[160:163], v[212:215], v[96:111]
	v_mfma_f32_32x32x16_bf16 v[32:47], v[164:167], v[212:215], v[32:47]
	ds_read_b128 v[208:211], v149 offset:9216
	ds_read_b128 v[212:215], v149 offset:13824
	s_waitcnt vmcnt(7)
	ds_write_b128 v148, v[184:187] offset:9216
	s_waitcnt vmcnt(6)
	ds_write_b128 v148, v[188:191] offset:46080
	ds_read_b128 v[184:187], v150 offset:32
	ds_read_b128 v[188:191], v150 offset:4640
	s_waitcnt lgkmcnt(5)
	v_mfma_f32_32x32x16_bf16 v[80:95], v[160:163], v[208:211], v[80:95]
	v_mfma_f32_32x32x16_bf16 v[16:31], v[164:167], v[208:211], v[16:31]
	ds_read_b128 v[208:211], v149 offset:32
	s_waitcnt lgkmcnt(5)
	v_mfma_f32_32x32x16_bf16 v[64:79], v[160:163], v[212:215], v[64:79]
	v_mfma_f32_32x32x16_bf16 v[0:15], v[164:167], v[212:215], v[0:15]
	ds_read_b128 v[212:215], v149 offset:4640
	s_setprio 0
	global_load_dwordx4 v[160:163], v[140:141], off offset:3712
	global_load_dwordx4 v[164:167], v[142:143], off offset:3712
	s_setprio 1
	s_waitcnt lgkmcnt(1)
	v_mfma_f32_32x32x16_bf16 v[112:127], v[184:187], v[208:211], v[112:127]
	v_mfma_f32_32x32x16_bf16 v[48:63], v[188:191], v[208:211], v[48:63]
	s_waitcnt lgkmcnt(0)
	v_mfma_f32_32x32x16_bf16 v[96:111], v[184:187], v[212:215], v[96:111]
	v_mfma_f32_32x32x16_bf16 v[32:47], v[188:191], v[212:215], v[32:47]
	ds_read_b128 v[208:211], v149 offset:9248
	ds_read_b128 v[212:215], v149 offset:13856
	s_waitcnt vmcnt(7)
	ds_write_b128 v148, v[194:197] offset:18432
	s_waitcnt vmcnt(6)
	ds_write_b128 v148, v[198:201] offset:55296
	ds_read_b128 v[194:197], v150 offset:64
	ds_read_b128 v[198:201], v150 offset:4672
	s_waitcnt lgkmcnt(5)
	v_mfma_f32_32x32x16_bf16 v[80:95], v[184:187], v[208:211], v[80:95]
	v_mfma_f32_32x32x16_bf16 v[16:31], v[188:191], v[208:211], v[16:31]
	ds_read_b128 v[208:211], v149 offset:64
	s_waitcnt lgkmcnt(5)
	v_mfma_f32_32x32x16_bf16 v[64:79], v[184:187], v[212:215], v[64:79]
	v_mfma_f32_32x32x16_bf16 v[0:15], v[188:191], v[212:215], v[0:15]
	ds_read_b128 v[212:215], v149 offset:4672
	s_setprio 0
	global_load_dwordx4 v[184:187], v[132:133], off offset:3712
	global_load_dwordx4 v[188:191], v[134:135], off offset:3712
	s_setprio 1
	s_waitcnt lgkmcnt(1)
	v_mfma_f32_32x32x16_bf16 v[112:127], v[194:197], v[208:211], v[112:127]
	v_mfma_f32_32x32x16_bf16 v[48:63], v[198:201], v[208:211], v[48:63]
	s_waitcnt lgkmcnt(0)
	v_mfma_f32_32x32x16_bf16 v[96:111], v[194:197], v[212:215], v[96:111]
	v_mfma_f32_32x32x16_bf16 v[32:47], v[198:201], v[212:215], v[32:47]
	ds_read_b128 v[208:211], v149 offset:9280
	ds_read_b128 v[212:215], v149 offset:13888
	s_waitcnt vmcnt(7)
	ds_write_b128 v148, v[176:179] offset:27648
	s_waitcnt vmcnt(6)
	ds_write_b128 v148, v[180:183] offset:64512
	ds_read_b128 v[176:179], v150 offset:96
	ds_read_b128 v[180:183], v150 offset:4704
	s_waitcnt lgkmcnt(5)
	v_mfma_f32_32x32x16_bf16 v[80:95], v[194:197], v[208:211], v[80:95]
	v_mfma_f32_32x32x16_bf16 v[16:31], v[198:201], v[208:211], v[16:31]
	ds_read_b128 v[208:211], v149 offset:96
	s_waitcnt lgkmcnt(5)
	v_mfma_f32_32x32x16_bf16 v[64:79], v[194:197], v[212:215], v[64:79]
	v_mfma_f32_32x32x16_bf16 v[0:15], v[198:201], v[212:215], v[0:15]
	ds_read_b128 v[212:215], v149 offset:4704
	s_setprio 0
	global_load_dwordx4 v[194:197], v[144:145], off offset:3712
	global_load_dwordx4 v[198:201], v[146:147], off offset:3712
	s_setprio 1
	s_waitcnt lgkmcnt(1)
	v_mfma_f32_32x32x16_bf16 v[112:127], v[176:179], v[208:211], v[112:127]
	v_mfma_f32_32x32x16_bf16 v[48:63], v[180:183], v[208:211], v[48:63]
	s_waitcnt lgkmcnt(0)
	v_mfma_f32_32x32x16_bf16 v[96:111], v[176:179], v[212:215], v[96:111]
	v_mfma_f32_32x32x16_bf16 v[32:47], v[180:183], v[212:215], v[32:47]
	ds_read_b128 v[208:211], v149 offset:9312
	ds_read_b128 v[212:215], v149 offset:13920
	s_waitcnt lgkmcnt(1)
	v_mfma_f32_32x32x16_bf16 v[80:95], v[176:179], v[208:211], v[80:95]
	v_mfma_f32_32x32x16_bf16 v[16:31], v[180:183], v[208:211], v[16:31]
	s_waitcnt lgkmcnt(0)
	v_mfma_f32_32x32x16_bf16 v[64:79], v[176:179], v[212:215], v[64:79]
	v_mfma_f32_32x32x16_bf16 v[0:15], v[180:183], v[212:215], v[0:15]
	s_setprio 0
	global_load_dwordx4 v[176:179], v[136:137], off offset:3840
	global_load_dwordx4 v[180:183], v[138:139], off offset:3840
	s_barrier
; template <bool trans>
; DI void gemm_core(const GTile& tl, const GTile& nx, bool has_next  , bool chain  , bool pre, u32x4 (&ra)[4], u32x4 (&rb)[4], char* smem, f32x16 (&acc)[2][4]) {
;     ...
;   const int nk = K / 64;
;   if (!pre) { G_LOAD(0); G_STORE(0); G_LOAD(1); }
;   for (int kt = 0; kt < nk; ++kt) {
;     __syncthreads();
;     G_COMPUTE(kt & 1, kt);
;   }
	s_waitcnt vmcnt(9)
	ds_write_b128 v192, v[168:171]
	s_waitcnt vmcnt(8)
	ds_write_b128 v159, v[172:175]
	ds_read_b128 v[168:171], v152 offset:36864
	ds_read_b128 v[172:175], v152 offset:41472
	ds_read_b128 v[208:211], v151
	ds_read_b128 v[212:215], v151 offset:4608
	s_setprio 1
	s_waitcnt lgkmcnt(1)
	v_mfma_f32_32x32x16_bf16 v[112:127], v[168:171], v[208:211], v[112:127]
	v_mfma_f32_32x32x16_bf16 v[48:63], v[172:175], v[208:211], v[48:63]
	s_waitcnt lgkmcnt(0)
	v_mfma_f32_32x32x16_bf16 v[96:111], v[168:171], v[212:215], v[96:111]
	v_mfma_f32_32x32x16_bf16 v[32:47], v[172:175], v[212:215], v[32:47]
	ds_read_b128 v[208:211], v151 offset:9216
	ds_read_b128 v[212:215], v151 offset:13824
	s_waitcnt lgkmcnt(1)
	v_mfma_f32_32x32x16_bf16 v[80:95], v[168:171], v[208:211], v[80:95]
	v_mfma_f32_32x32x16_bf16 v[16:31], v[172:175], v[208:211], v[16:31]
	s_waitcnt lgkmcnt(0)
	v_mfma_f32_32x32x16_bf16 v[64:79], v[168:171], v[212:215], v[64:79]
	v_mfma_f32_32x32x16_bf16 v[0:15], v[172:175], v[212:215], v[0:15]
	s_setprio 0
	global_load_dwordx4 v[208:211], v[140:141], off offset:3840
	global_load_dwordx4 v[212:215], v[142:143], off offset:3840
	s_waitcnt vmcnt(9)
	ds_write_b128 v158, v[160:163]
	s_waitcnt vmcnt(8)
	ds_write_b128 v157, v[164:167]
	ds_read_b128 v[160:163], v152 offset:36896
	ds_read_b128 v[164:167], v152 offset:41504
	ds_read_b128 v[168:171], v151 offset:32
	ds_read_b128 v[172:175], v151 offset:4640
	s_setprio 1
	s_waitcnt lgkmcnt(1)
	v_mfma_f32_32x32x16_bf16 v[112:127], v[160:163], v[168:171], v[112:127]
	v_mfma_f32_32x32x16_bf16 v[48:63], v[164:167], v[168:171], v[48:63]
	s_waitcnt lgkmcnt(0)
	v_mfma_f32_32x32x16_bf16 v[96:111], v[160:163], v[172:175], v[96:111]
	v_mfma_f32_32x32x16_bf16 v[32:47], v[164:167], v[172:175], v[32:47]
	ds_read_b128 v[168:171], v151 offset:9248
	ds_read_b128 v[172:175], v151 offset:13856
	s_waitcnt lgkmcnt(1)
	v_mfma_f32_32x32x16_bf16 v[80:95], v[160:163], v[168:171], v[80:95]
	v_mfma_f32_32x32x16_bf16 v[16:31], v[164:167], v[168:171], v[16:31]
	s_waitcnt lgkmcnt(0)
	v_mfma_f32_32x32x16_bf16 v[64:79], v[160:163], v[172:175], v[64:79]
	v_mfma_f32_32x32x16_bf16 v[0:15], v[164:167], v[172:175], v[0:15]
	s_setprio 0
	global_load_dwordx4 v[216:219], v[132:133], off offset:3840
	global_load_dwordx4 v[220:223], v[134:135], off offset:3840
	s_waitcnt vmcnt(9)
	ds_write_b128 v154, v[184:187]
	s_waitcnt vmcnt(8)
	ds_write_b128 v153, v[188:191]
	ds_read_b128 v[160:163], v152 offset:36928
	ds_read_b128 v[164:167], v152 offset:41536
	ds_read_b128 v[168:171], v151 offset:64
	ds_read_b128 v[172:175], v151 offset:4672
	s_setprio 1
	s_waitcnt lgkmcnt(1)
	v_mfma_f32_32x32x16_bf16 v[112:127], v[160:163], v[168:171], v[112:127]
	v_mfma_f32_32x32x16_bf16 v[48:63], v[164:167], v[168:171], v[48:63]
	s_waitcnt lgkmcnt(0)
	v_mfma_f32_32x32x16_bf16 v[96:111], v[160:163], v[172:175], v[96:111]
	v_mfma_f32_32x32x16_bf16 v[32:47], v[164:167], v[172:175], v[32:47]
	ds_read_b128 v[168:171], v151 offset:9280
	ds_read_b128 v[172:175], v151 offset:13888
	s_waitcnt lgkmcnt(1)
	v_mfma_f32_32x32x16_bf16 v[80:95], v[160:163], v[168:171], v[80:95]
	v_mfma_f32_32x32x16_bf16 v[16:31], v[164:167], v[168:171], v[16:31]
	s_waitcnt lgkmcnt(0)
	v_mfma_f32_32x32x16_bf16 v[64:79], v[160:163], v[172:175], v[64:79]
	v_mfma_f32_32x32x16_bf16 v[0:15], v[164:167], v[172:175], v[0:15]
	s_setprio 0
	global_load_dwordx4 v[224:227], v[144:145], off offset:3840
	global_load_dwordx4 v[228:231], v[146:147], off offset:3840
	s_waitcnt vmcnt(9)
	ds_write_b128 v156, v[194:197]
	s_waitcnt vmcnt(8)
	ds_write_b128 v155, v[198:201]
	ds_read_b128 v[160:163], v152 offset:36960
	ds_read_b128 v[164:167], v152 offset:41568
	ds_read_b128 v[168:171], v151 offset:96
	ds_read_b128 v[172:175], v151 offset:4704
	s_setprio 1
	s_waitcnt lgkmcnt(1)
	v_mfma_f32_32x32x16_bf16 v[112:127], v[160:163], v[168:171], v[112:127]
	v_mfma_f32_32x32x16_bf16 v[48:63], v[164:167], v[168:171], v[48:63]
	s_waitcnt lgkmcnt(0)
	v_mfma_f32_32x32x16_bf16 v[96:111], v[160:163], v[172:175], v[96:111]
	v_mfma_f32_32x32x16_bf16 v[32:47], v[164:167], v[172:175], v[32:47]
	ds_read_b128 v[168:171], v151 offset:9312
	ds_read_b128 v[172:175], v151 offset:13920
	s_waitcnt lgkmcnt(1)
	v_mfma_f32_32x32x16_bf16 v[80:95], v[160:163], v[168:171], v[80:95]
	v_mfma_f32_32x32x16_bf16 v[16:31], v[164:167], v[168:171], v[16:31]
	s_waitcnt lgkmcnt(0)
	v_mfma_f32_32x32x16_bf16 v[64:79], v[160:163], v[172:175], v[64:79]
	v_mfma_f32_32x32x16_bf16 v[0:15], v[164:167], v[172:175], v[0:15]
	s_setprio 0
	global_load_dwordx4 v[160:163], v[136:137], off offset:3968
	global_load_dwordx4 v[164:167], v[138:139], off offset:3968
	s_barrier
; template <bool trans>
; DI void gemm_core(const GTile& tl, const GTile& nx, bool has_next  , bool chain  , bool pre, u32x4 (&ra)[4], u32x4 (&rb)[4], char* smem, f32x16 (&acc)[2][4]) {
;     ...
;   const int nk = K / 64;
;   if (!pre) { G_LOAD(0); G_STORE(0); G_LOAD(1); }
;   for (int kt = 0; kt < nk; ++kt) {
;     __syncthreads();
;     G_COMPUTE(kt & 1, kt);
;   }
;   if (!has_next) __syncthreads();
	s_waitcnt vmcnt(9)
	ds_write_b128 v148, v[176:179]
	s_waitcnt vmcnt(8)
	ds_write_b128 v148, v[180:183] offset:36864
	ds_read_b128 v[136:139], v150
	ds_read_b128 v[168:171], v150 offset:4608
	ds_read_b128 v[172:175], v149
	ds_read_b128 v[176:179], v149 offset:4608
	s_setprio 1
	s_waitcnt lgkmcnt(1)
	v_mfma_f32_32x32x16_bf16 v[112:127], v[136:139], v[172:175], v[112:127]
	v_mfma_f32_32x32x16_bf16 v[48:63], v[168:171], v[172:175], v[48:63]
	s_waitcnt lgkmcnt(0)
	v_mfma_f32_32x32x16_bf16 v[96:111], v[136:139], v[176:179], v[96:111]
	v_mfma_f32_32x32x16_bf16 v[32:47], v[168:171], v[176:179], v[32:47]
	ds_read_b128 v[172:175], v149 offset:9216
	ds_read_b128 v[176:179], v149 offset:13824
	s_waitcnt lgkmcnt(1)
	v_mfma_f32_32x32x16_bf16 v[80:95], v[136:139], v[172:175], v[80:95]
	v_mfma_f32_32x32x16_bf16 v[16:31], v[168:171], v[172:175], v[16:31]
	s_waitcnt lgkmcnt(0)
	v_mfma_f32_32x32x16_bf16 v[64:79], v[136:139], v[176:179], v[64:79]
	v_mfma_f32_32x32x16_bf16 v[0:15], v[168:171], v[176:179], v[0:15]
	s_setprio 0
	global_load_dwordx4 v[168:171], v[140:141], off offset:3968
	global_load_dwordx4 v[172:175], v[142:143], off offset:3968
	s_waitcnt vmcnt(9)
	ds_write_b128 v148, v[208:211] offset:9216
	s_waitcnt vmcnt(8)
	ds_write_b128 v148, v[212:215] offset:46080
	ds_read_b128 v[136:139], v150 offset:32
	ds_read_b128 v[140:143], v150 offset:4640
	ds_read_b128 v[176:179], v149 offset:32
	ds_read_b128 v[180:183], v149 offset:4640
	s_setprio 1
	s_waitcnt lgkmcnt(1)
	v_mfma_f32_32x32x16_bf16 v[112:127], v[136:139], v[176:179], v[112:127]
	v_mfma_f32_32x32x16_bf16 v[48:63], v[140:143], v[176:179], v[48:63]
	s_waitcnt lgkmcnt(0)
	v_mfma_f32_32x32x16_bf16 v[96:111], v[136:139], v[180:183], v[96:111]
	v_mfma_f32_32x32x16_bf16 v[32:47], v[140:143], v[180:183], v[32:47]
	ds_read_b128 v[176:179], v149 offset:9248
	ds_read_b128 v[180:183], v149 offset:13856
	s_waitcnt lgkmcnt(1)
	v_mfma_f32_32x32x16_bf16 v[80:95], v[136:139], v[176:179], v[80:95]
	v_mfma_f32_32x32x16_bf16 v[16:31], v[140:143], v[176:179], v[16:31]
	s_waitcnt lgkmcnt(0)
	v_mfma_f32_32x32x16_bf16 v[64:79], v[136:139], v[180:183], v[64:79]
	v_mfma_f32_32x32x16_bf16 v[0:15], v[140:143], v[180:183], v[0:15]
	s_setprio 0
	global_load_dwordx4 v[176:179], v[132:133], off offset:3968
	global_load_dwordx4 v[180:183], v[134:135], off offset:3968
	s_waitcnt vmcnt(9)
	ds_write_b128 v148, v[216:219] offset:18432
	s_waitcnt vmcnt(8)
	ds_write_b128 v148, v[220:223] offset:55296
	ds_read_b128 v[132:135], v150 offset:64
	ds_read_b128 v[136:139], v150 offset:4672
	ds_read_b128 v[140:143], v149 offset:64
	ds_read_b128 v[184:187], v149 offset:4672
	s_setprio 1
	s_waitcnt lgkmcnt(1)
	v_mfma_f32_32x32x16_bf16 v[112:127], v[132:135], v[140:143], v[112:127]
	v_mfma_f32_32x32x16_bf16 v[48:63], v[136:139], v[140:143], v[48:63]
	s_waitcnt lgkmcnt(0)
	v_mfma_f32_32x32x16_bf16 v[96:111], v[132:135], v[184:187], v[96:111]
	v_mfma_f32_32x32x16_bf16 v[32:47], v[136:139], v[184:187], v[32:47]
	ds_read_b128 v[140:143], v149 offset:9280
	ds_read_b128 v[184:187], v149 offset:13888
	s_waitcnt lgkmcnt(1)
	v_mfma_f32_32x32x16_bf16 v[80:95], v[132:135], v[140:143], v[80:95]
	v_mfma_f32_32x32x16_bf16 v[16:31], v[136:139], v[140:143], v[16:31]
	s_waitcnt lgkmcnt(0)
	v_mfma_f32_32x32x16_bf16 v[64:79], v[132:135], v[184:187], v[64:79]
	v_mfma_f32_32x32x16_bf16 v[0:15], v[136:139], v[184:187], v[0:15]
	s_setprio 0
	global_load_dwordx4 v[184:187], v[144:145], off offset:3968
	global_load_dwordx4 v[188:191], v[146:147], off offset:3968
	s_waitcnt vmcnt(9)
	ds_write_b128 v148, v[224:227] offset:27648
	s_waitcnt vmcnt(8)
	ds_write_b128 v148, v[228:231] offset:64512
	ds_read_b128 v[132:135], v150 offset:96
	ds_read_b128 v[136:139], v150 offset:4704
	ds_read_b128 v[140:143], v149 offset:96
	ds_read_b128 v[144:147], v149 offset:4704
	s_setprio 1
	s_waitcnt lgkmcnt(1)
	v_mfma_f32_32x32x16_bf16 v[112:127], v[132:135], v[140:143], v[112:127]
	v_mfma_f32_32x32x16_bf16 v[48:63], v[136:139], v[140:143], v[48:63]
	s_waitcnt lgkmcnt(0)
	v_mfma_f32_32x32x16_bf16 v[96:111], v[132:135], v[144:147], v[96:111]
	v_mfma_f32_32x32x16_bf16 v[32:47], v[136:139], v[144:147], v[32:47]
	ds_read_b128 v[140:143], v149 offset:9312
	ds_read_b128 v[144:147], v149 offset:13920
	s_waitcnt lgkmcnt(1)
	v_mfma_f32_32x32x16_bf16 v[80:95], v[132:135], v[140:143], v[80:95]
	v_mfma_f32_32x32x16_bf16 v[16:31], v[136:139], v[140:143], v[16:31]
	s_waitcnt lgkmcnt(0)
	v_mfma_f32_32x32x16_bf16 v[64:79], v[132:135], v[144:147], v[64:79]
	v_mfma_f32_32x32x16_bf16 v[0:15], v[136:139], v[144:147], v[0:15]
	s_setprio 0
	v_cndmask_b32_e64 v132, 0, 1, s[52:53]
	v_cmp_ne_u32_e64 s[4:5], 1, v132
	s_andn2_b64 vcc, exec, s[52:53]
	s_barrier
	s_waitcnt vmcnt(7)
	ds_write_b128 v192, v[160:163]
	s_waitcnt vmcnt(6)
	ds_write_b128 v159, v[164:167]
	s_cbranch_vccnz .LBB0_113
	global_load_dwordx4 v[160:163], v[130:131], off
	global_load_dwordx4 v[164:167], v[128:129], off

;   DI bf16_t* h() const { return (bf16_t*)(ws + OFF_H); }
; template <bool trans>
; DI void gemm_core(const GTile& tl, const GTile& nx, bool has_next  , bool chain  , bool pre, u32x4 (&ra)[4], u32x4 (&rb)[4], char* smem, f32x16 (&acc)[2][4]) {
;     ...
;   const int nk = K / 64;
;   if (!pre) { G_LOAD(0); G_STORE(0); G_LOAD(1); }
;   for (int kt = 0; kt < nk; ++kt) {
;     __syncthreads();
;     G_COMPUTE(kt & 1, kt);
; DI void phase_gemm_out(const Params& p, char* smem, const bf16_t* Wt, const float* R, float* O) {
;     ...
;     const int mt = t & 63, nt = t >> 6, tn = t + gridDim.x;
;     const bool has_next = tn < 64 * 8;
;     const GTile tl{p.h(), D, Wt, D, D, mt * 256, nt * 256}, nx{p.h(), D, Wt, D, D, (tn & 63) * 256, (tn >> 6) * 256};
.LBB0_749:
	v_lshl_add_u64 v[128:129], s[2:3], 0, v[184:185]
	v_lshl_add_u64 v[132:133], s[6:7], 0, v[184:185]
	s_waitcnt lgkmcnt(0)
	s_barrier
	global_load_dwordx4 v[198:201], v[128:129], off offset:256
	global_load_dwordx4 v[202:205], v[132:133], off offset:256
	s_add_i32 s38, s38, s96
	s_cmpk_lt_i32 s38, 0x200
	s_cselect_b64 s[14:15], -1, 0
	s_cmpk_gt_i32 s38, 0x1ff
	s_cselect_b64 s[12:13], -1, 0
	s_and_b32 s3, s28, 0x1f80000
	s_add_i32 s24, s25, s24
	s_and_b32 s2, s24, 0xffffff00
	s_and_b32 s40, s33, 0xc0
	s_lshl_b32 s3, s3, 1
	s_add_u32 s6, s18, s3
	s_addc_u32 s7, s19, 0
	s_ashr_i32 s3, s2, 31
	s_lshl_b64 s[2:3], s[2:3], 12
	s_add_u32 s2, s16, s2
	s_addc_u32 s3, s17, s3
	s_lshr_b32 s33, s33, 1
	v_and_b32_e32 v11, 31, v8
	s_and_b32 s33, s33, 0xfffff80
	v_or_b32_e32 v12, s33, v11
	v_or_b32_e32 v11, s40, v11
	v_add3_u32 v191, 16, v10, v9
	v_lshrrev_b32_e32 v8, 1, v8
	v_mul_u32_u24_e32 v131, 0x90, v11
	v_and_b32_e32 v134, 16, v8
	v_add_u32_e32 v195, 0x12000, v191
	v_mul_lo_u32 v130, v12, s35
	v_add3_u32 v192, 16, v131, v134
	v_add_u32_e32 v196, 0x1b000, v191
	ds_write_b128 v195, v[0:3]
	s_waitcnt vmcnt(5)
	ds_write_b128 v196, v[4:7]
	v_lshl_add_u64 v[188:189], s[6:7], 0, v[184:185]
	v_lshl_add_u64 v[186:187], s[2:3], 0, v[184:185]
	v_add3_u32 v184, 16, v130, v134
	ds_read_b128 v[0:3], v192 offset:36864
	ds_read_b128 v[4:7], v192 offset:41472
	ds_read_b128 v[8:11], v184
	ds_read_b128 v[12:15], v184 offset:4608
	v_lshl_add_u64 v[136:137], v[128:129], 0, s[0:1]
	v_lshl_add_u64 v[140:141], v[132:133], 0, s[0:1]
	v_lshl_add_u64 v[144:145], v[128:129], 0, s[8:9]
	v_lshl_add_u64 v[148:149], v[132:133], 0, s[8:9]
	s_setprio 1
	s_waitcnt lgkmcnt(1)
	v_mfma_f32_32x32x16_bf16 v[112:127], v[0:3], v[8:11], 0
	v_mfma_f32_32x32x16_bf16 v[48:63], v[4:7], v[8:11], 0
	s_waitcnt lgkmcnt(0)
	v_mfma_f32_32x32x16_bf16 v[96:111], v[0:3], v[12:15], 0
	v_mfma_f32_32x32x16_bf16 v[32:47], v[4:7], v[12:15], 0
	ds_read_b128 v[8:11], v184 offset:9216
	ds_read_b128 v[12:15], v184 offset:13824
	s_waitcnt lgkmcnt(1)
	v_mfma_f32_32x32x16_bf16 v[80:95], v[0:3], v[8:11], 0
	v_mfma_f32_32x32x16_bf16 v[16:31], v[4:7], v[8:11], 0
	s_waitcnt lgkmcnt(0)
	v_mfma_f32_32x32x16_bf16 v[64:79], v[0:3], v[12:15], 0
	v_mfma_f32_32x32x16_bf16 v[0:15], v[4:7], v[12:15], 0
	s_setprio 0
	global_load_dwordx4 v[208:211], v[136:137], off offset:256
	global_load_dwordx4 v[212:215], v[140:141], off offset:256
	v_add_u32_e32 v194, 0x14400, v191
	v_add_u32_e32 v193, 0x1d400, v191
	ds_write_b128 v194, v[176:179]
	s_waitcnt vmcnt(6)
	ds_write_b128 v193, v[180:183]
	ds_read_b128 v[150:153], v192 offset:36896
	ds_read_b128 v[154:157], v192 offset:41504
	ds_read_b128 v[176:179], v184 offset:32
	ds_read_b128 v[180:183], v184 offset:4640
	s_setprio 1
	s_waitcnt lgkmcnt(1)
	v_mfma_f32_32x32x16_bf16 v[112:127], v[150:153], v[176:179], v[112:127]
	v_mfma_f32_32x32x16_bf16 v[48:63], v[154:157], v[176:179], v[48:63]
	s_waitcnt lgkmcnt(0)
	v_mfma_f32_32x32x16_bf16 v[96:111], v[150:153], v[180:183], v[96:111]
	v_mfma_f32_32x32x16_bf16 v[32:47], v[154:157], v[180:183], v[32:47]
	ds_read_b128 v[176:179], v184 offset:9248
	ds_read_b128 v[180:183], v184 offset:13856
	s_waitcnt lgkmcnt(1)
	v_mfma_f32_32x32x16_bf16 v[80:95], v[150:153], v[176:179], v[80:95]
	v_mfma_f32_32x32x16_bf16 v[16:31], v[154:157], v[176:179], v[16:31]
	s_waitcnt lgkmcnt(0)
	v_mfma_f32_32x32x16_bf16 v[64:79], v[150:153], v[180:183], v[64:79]
	v_mfma_f32_32x32x16_bf16 v[0:15], v[154:157], v[180:183], v[0:15]
	s_setprio 0
	global_load_dwordx4 v[178:181], v[144:145], off offset:256
	global_load_dwordx4 v[216:219], v[148:149], off offset:256
	v_add_u32_e32 v177, 0x16800, v191
	v_add_u32_e32 v176, 0x1f800, v191
	ds_write_b128 v177, v[168:171]
	s_waitcnt vmcnt(7)
	ds_write_b128 v176, v[172:175]
	ds_read_b128 v[150:153], v192 offset:36928
	ds_read_b128 v[154:157], v192 offset:41536
	ds_read_b128 v[168:171], v184 offset:64
	ds_read_b128 v[172:175], v184 offset:4672
	s_setprio 1
	s_waitcnt lgkmcnt(1)
	v_mfma_f32_32x32x16_bf16 v[112:127], v[150:153], v[168:171], v[112:127]
	v_mfma_f32_32x32x16_bf16 v[48:63], v[154:157], v[168:171], v[48:63]
	s_waitcnt lgkmcnt(0)
	v_mfma_f32_32x32x16_bf16 v[96:111], v[150:153], v[172:175], v[96:111]
	v_mfma_f32_32x32x16_bf16 v[32:47], v[154:157], v[172:175], v[32:47]
	ds_read_b128 v[168:171], v184 offset:9280
	ds_read_b128 v[172:175], v184 offset:13888
	s_waitcnt lgkmcnt(1)
	v_mfma_f32_32x32x16_bf16 v[80:95], v[150:153], v[168:171], v[80:95]
	v_mfma_f32_32x32x16_bf16 v[16:31], v[154:157], v[168:171], v[16:31]
	s_waitcnt lgkmcnt(0)
	v_mfma_f32_32x32x16_bf16 v[64:79], v[150:153], v[172:175], v[64:79]
	v_mfma_f32_32x32x16_bf16 v[0:15], v[154:157], v[172:175], v[0:15]
	s_setprio 0
	v_add_co_u32_e32 v152, vcc, s34, v128
	v_add_u32_e32 v171, 0x18c00, v191
	s_nop 0
	v_addc_co_u32_e32 v153, vcc, 0, v129, vcc
	v_add_co_u32_e32 v156, vcc, s34, v132
	v_add_u32_e32 v170, 0x21c00, v191
	s_nop 0
	v_addc_co_u32_e32 v157, vcc, 0, v133, vcc
	global_load_dwordx4 v[172:175], v[152:153], off offset:256
	global_load_dwordx4 v[220:223], v[156:157], off offset:256
	ds_write_b128 v171, v[160:163]
	s_waitcnt vmcnt(8)
	ds_write_b128 v170, v[164:167]
	ds_read_b128 v[158:161], v192 offset:36960
	ds_read_b128 v[162:165], v192 offset:41568
	ds_read_b128 v[166:169], v184 offset:96
	ds_read_b128 v[224:227], v184 offset:4704
	s_setprio 1
	s_waitcnt lgkmcnt(1)
	v_mfma_f32_32x32x16_bf16 v[112:127], v[158:161], v[166:169], v[112:127]
	v_mfma_f32_32x32x16_bf16 v[48:63], v[162:165], v[166:169], v[48:63]
	s_waitcnt lgkmcnt(0)
	v_mfma_f32_32x32x16_bf16 v[96:111], v[158:161], v[224:227], v[96:111]
	v_mfma_f32_32x32x16_bf16 v[32:47], v[162:165], v[224:227], v[32:47]
	ds_read_b128 v[166:169], v184 offset:9312
	ds_read_b128 v[224:227], v184 offset:13920
	s_waitcnt lgkmcnt(1)
	v_mfma_f32_32x32x16_bf16 v[80:95], v[158:161], v[166:169], v[80:95]
	v_mfma_f32_32x32x16_bf16 v[16:31], v[162:165], v[166:169], v[16:31]
	s_waitcnt lgkmcnt(0)
	v_mfma_f32_32x32x16_bf16 v[64:79], v[158:161], v[224:227], v[64:79]
	v_mfma_f32_32x32x16_bf16 v[0:15], v[162:165], v[224:227], v[0:15]
	s_setprio 0
	global_load_dwordx4 v[158:161], v[128:129], off offset:384
	global_load_dwordx4 v[162:165], v[132:133], off offset:384
	s_barrier
; template <bool trans>
; DI void gemm_core(const GTile& tl, const GTile& nx, bool has_next  , bool chain  , bool pre, u32x4 (&ra)[4], u32x4 (&rb)[4], char* smem, f32x16 (&acc)[2][4]) {
;     ...
;   const int nk = K / 64;
;   if (!pre) { G_LOAD(0); G_STORE(0); G_LOAD(1); }
;   for (int kt = 0; kt < nk; ++kt) {
;     __syncthreads();
;     G_COMPUTE(kt & 1, kt);
	v_add3_u32 v169, s37, v131, v134
	s_waitcnt vmcnt(9)
	ds_write_b128 v191, v[198:201]
	s_waitcnt vmcnt(8)
	ds_write_b128 v191, v[202:205] offset:36864
	v_add3_u32 v168, s36, v130, v134
	ds_read_b128 v[198:201], v169
	ds_read_b128 v[202:205], v169 offset:4608
	ds_read_b128 v[224:227], v168
	ds_read_b128 v[228:231], v168 offset:4608
	s_setprio 1
	s_waitcnt lgkmcnt(1)
	v_mfma_f32_32x32x16_bf16 v[112:127], v[198:201], v[224:227], v[112:127]
	v_mfma_f32_32x32x16_bf16 v[48:63], v[202:205], v[224:227], v[48:63]
	s_waitcnt lgkmcnt(0)
	v_mfma_f32_32x32x16_bf16 v[96:111], v[198:201], v[228:231], v[96:111]
	v_mfma_f32_32x32x16_bf16 v[32:47], v[202:205], v[228:231], v[32:47]
	ds_read_b128 v[224:227], v168 offset:9216
	ds_read_b128 v[228:231], v168 offset:13824
	s_waitcnt lgkmcnt(1)
	v_mfma_f32_32x32x16_bf16 v[80:95], v[198:201], v[224:227], v[80:95]
	v_mfma_f32_32x32x16_bf16 v[16:31], v[202:205], v[224:227], v[16:31]
	s_waitcnt lgkmcnt(0)
	v_mfma_f32_32x32x16_bf16 v[64:79], v[198:201], v[228:231], v[64:79]
	v_mfma_f32_32x32x16_bf16 v[0:15], v[202:205], v[228:231], v[0:15]
	s_setprio 0
	global_load_dwordx4 v[198:201], v[136:137], off offset:384
	global_load_dwordx4 v[202:205], v[140:141], off offset:384
	s_waitcnt vmcnt(9)
	ds_write_b128 v191, v[208:211] offset:9216
	s_waitcnt vmcnt(8)
	ds_write_b128 v191, v[212:215] offset:46080
	ds_read_b128 v[208:211], v169 offset:32
	ds_read_b128 v[212:215], v169 offset:4640
	ds_read_b128 v[224:227], v168 offset:32
	ds_read_b128 v[228:231], v168 offset:4640
	s_setprio 1
	s_waitcnt lgkmcnt(1)
	v_mfma_f32_32x32x16_bf16 v[112:127], v[208:211], v[224:227], v[112:127]
	v_mfma_f32_32x32x16_bf16 v[48:63], v[212:215], v[224:227], v[48:63]
	s_waitcnt lgkmcnt(0)
	v_mfma_f32_32x32x16_bf16 v[96:111], v[208:211], v[228:231], v[96:111]
	v_mfma_f32_32x32x16_bf16 v[32:47], v[212:215], v[228:231], v[32:47]
	ds_read_b128 v[224:227], v168 offset:9248
	ds_read_b128 v[228:231], v168 offset:13856
	s_waitcnt lgkmcnt(1)
	v_mfma_f32_32x32x16_bf16 v[80:95], v[208:211], v[224:227], v[80:95]
	v_mfma_f32_32x32x16_bf16 v[16:31], v[212:215], v[224:227], v[16:31]
	s_waitcnt lgkmcnt(0)
	v_mfma_f32_32x32x16_bf16 v[64:79], v[208:211], v[228:231], v[64:79]
	v_mfma_f32_32x32x16_bf16 v[0:15], v[212:215], v[228:231], v[0:15]
	s_setprio 0
	global_load_dwordx4 v[208:211], v[144:145], off offset:384
	global_load_dwordx4 v[212:215], v[148:149], off offset:384
	s_waitcnt vmcnt(9)
	ds_write_b128 v191, v[178:181] offset:18432
	s_waitcnt vmcnt(8)
	ds_write_b128 v191, v[216:219] offset:55296
	ds_read_b128 v[178:181], v169 offset:64
	ds_read_b128 v[216:219], v169 offset:4672
	ds_read_b128 v[224:227], v168 offset:64
	ds_read_b128 v[228:231], v168 offset:4672
	s_setprio 1
	s_waitcnt lgkmcnt(1)
	v_mfma_f32_32x32x16_bf16 v[112:127], v[178:181], v[224:227], v[112:127]
	v_mfma_f32_32x32x16_bf16 v[48:63], v[216:219], v[224:227], v[48:63]
	s_waitcnt lgkmcnt(0)
	v_mfma_f32_32x32x16_bf16 v[96:111], v[178:181], v[228:231], v[96:111]
	v_mfma_f32_32x32x16_bf16 v[32:47], v[216:219], v[228:231], v[32:47]
	ds_read_b128 v[224:227], v168 offset:9280
	ds_read_b128 v[228:231], v168 offset:13888
	s_waitcnt lgkmcnt(1)
	v_mfma_f32_32x32x16_bf16 v[80:95], v[178:181], v[224:227], v[80:95]
	v_mfma_f32_32x32x16_bf16 v[16:31], v[216:219], v[224:227], v[16:31]
	s_waitcnt lgkmcnt(0)
	v_mfma_f32_32x32x16_bf16 v[64:79], v[178:181], v[228:231], v[64:79]
	v_mfma_f32_32x32x16_bf16 v[0:15], v[216:219], v[228:231], v[0:15]
	s_setprio 0
	global_load_dwordx4 v[178:181], v[152:153], off offset:384
	global_load_dwordx4 v[216:219], v[156:157], off offset:384
	s_waitcnt vmcnt(9)
	ds_write_b128 v191, v[172:175] offset:27648
	s_waitcnt vmcnt(8)
	ds_write_b128 v191, v[220:223] offset:64512
	ds_read_b128 v[172:175], v169 offset:96
	ds_read_b128 v[220:223], v169 offset:4704
	ds_read_b128 v[224:227], v168 offset:96
	ds_read_b128 v[228:231], v168 offset:4704
	s_setprio 1
	s_waitcnt lgkmcnt(1)
	v_mfma_f32_32x32x16_bf16 v[112:127], v[172:175], v[224:227], v[112:127]
	v_mfma_f32_32x32x16_bf16 v[48:63], v[220:223], v[224:227], v[48:63]
	s_waitcnt lgkmcnt(0)
	v_mfma_f32_32x32x16_bf16 v[96:111], v[172:175], v[228:231], v[96:111]
	v_mfma_f32_32x32x16_bf16 v[32:47], v[220:223], v[228:231], v[32:47]
	ds_read_b128 v[224:227], v168 offset:9312
	ds_read_b128 v[228:231], v168 offset:13920
	s_waitcnt lgkmcnt(1)
	v_mfma_f32_32x32x16_bf16 v[80:95], v[172:175], v[224:227], v[80:95]
	v_mfma_f32_32x32x16_bf16 v[16:31], v[220:223], v[224:227], v[16:31]
	s_waitcnt lgkmcnt(0)
	v_mfma_f32_32x32x16_bf16 v[64:79], v[172:175], v[228:231], v[64:79]
	v_mfma_f32_32x32x16_bf16 v[0:15], v[220:223], v[228:231], v[0:15]
	s_setprio 0
	global_load_dwordx4 v[172:175], v[128:129], off offset:512
	global_load_dwordx4 v[220:223], v[132:133], off offset:512
	s_barrier
; template <bool trans>
; DI void gemm_core(const GTile& tl, const GTile& nx, bool has_next  , bool chain  , bool pre, u32x4 (&ra)[4], u32x4 (&rb)[4], char* smem, f32x16 (&acc)[2][4]) {
;     ...
;   const int nk = K / 64;
;   if (!pre) { G_LOAD(0); G_STORE(0); G_LOAD(1); }
;   for (int kt = 0; kt < nk; ++kt) {
;     __syncthreads();
;     G_COMPUTE(kt & 1, kt);
	s_waitcnt vmcnt(9)
	ds_write_b128 v195, v[158:161]
	s_waitcnt vmcnt(8)
	ds_write_b128 v196, v[162:165]
	ds_read_b128 v[158:161], v192 offset:36864
	ds_read_b128 v[162:165], v192 offset:41472
	ds_read_b128 v[224:227], v184
	ds_read_b128 v[228:231], v184 offset:4608
	s_setprio 1
	s_waitcnt lgkmcnt(1)
	v_mfma_f32_32x32x16_bf16 v[112:127], v[158:161], v[224:227], v[112:127]
	v_mfma_f32_32x32x16_bf16 v[48:63], v[162:165], v[224:227], v[48:63]
	s_waitcnt lgkmcnt(0)
	v_mfma_f32_32x32x16_bf16 v[96:111], v[158:161], v[228:231], v[96:111]
	v_mfma_f32_32x32x16_bf16 v[32:47], v[162:165], v[228:231], v[32:47]
	ds_read_b128 v[224:227], v184 offset:9216
	ds_read_b128 v[228:231], v184 offset:13824
	s_waitcnt vmcnt(7)
	ds_write_b128 v194, v[198:201]
	s_waitcnt vmcnt(6)
	ds_write_b128 v193, v[202:205]
	ds_read_b128 v[198:201], v192 offset:36896
	ds_read_b128 v[202:205], v192 offset:41504
	s_waitcnt lgkmcnt(5)
	v_mfma_f32_32x32x16_bf16 v[80:95], v[158:161], v[224:227], v[80:95]
	v_mfma_f32_32x32x16_bf16 v[16:31], v[162:165], v[224:227], v[16:31]
	ds_read_b128 v[224:227], v184 offset:32
	s_waitcnt lgkmcnt(5)
	v_mfma_f32_32x32x16_bf16 v[64:79], v[158:161], v[228:231], v[64:79]
	v_mfma_f32_32x32x16_bf16 v[0:15], v[162:165], v[228:231], v[0:15]
	ds_read_b128 v[228:231], v184 offset:4640
	s_setprio 0
	global_load_dwordx4 v[158:161], v[136:137], off offset:512
	global_load_dwordx4 v[162:165], v[140:141], off offset:512
	s_setprio 1
	s_waitcnt lgkmcnt(1)
	v_mfma_f32_32x32x16_bf16 v[112:127], v[198:201], v[224:227], v[112:127]
	v_mfma_f32_32x32x16_bf16 v[48:63], v[202:205], v[224:227], v[48:63]
	s_waitcnt lgkmcnt(0)
	v_mfma_f32_32x32x16_bf16 v[96:111], v[198:201], v[228:231], v[96:111]
	v_mfma_f32_32x32x16_bf16 v[32:47], v[202:205], v[228:231], v[32:47]
	ds_read_b128 v[224:227], v184 offset:9248
	ds_read_b128 v[228:231], v184 offset:13856
	s_waitcnt vmcnt(7)
	ds_write_b128 v177, v[208:211]
	s_waitcnt vmcnt(6)
	ds_write_b128 v176, v[212:215]
	ds_read_b128 v[208:211], v192 offset:36928
	ds_read_b128 v[212:215], v192 offset:41536
	s_waitcnt lgkmcnt(5)
	v_mfma_f32_32x32x16_bf16 v[80:95], v[198:201], v[224:227], v[80:95]
	v_mfma_f32_32x32x16_bf16 v[16:31], v[202:205], v[224:227], v[16:31]
	ds_read_b128 v[224:227], v184 offset:64
	s_waitcnt lgkmcnt(5)
	v_mfma_f32_32x32x16_bf16 v[64:79], v[198:201], v[228:231], v[64:79]
	v_mfma_f32_32x32x16_bf16 v[0:15], v[202:205], v[228:231], v[0:15]
	ds_read_b128 v[228:231], v184 offset:4672
	s_setprio 0
	global_load_dwordx4 v[198:201], v[144:145], off offset:512
	global_load_dwordx4 v[202:205], v[148:149], off offset:512
	s_setprio 1
	s_waitcnt lgkmcnt(1)
	v_mfma_f32_32x32x16_bf16 v[112:127], v[208:211], v[224:227], v[112:127]
	v_mfma_f32_32x32x16_bf16 v[48:63], v[212:215], v[224:227], v[48:63]
	s_waitcnt lgkmcnt(0)
	v_mfma_f32_32x32x16_bf16 v[96:111], v[208:211], v[228:231], v[96:111]
	v_mfma_f32_32x32x16_bf16 v[32:47], v[212:215], v[228:231], v[32:47]
	ds_read_b128 v[224:227], v184 offset:9280
	ds_read_b128 v[228:231], v184 offset:13888
	s_waitcnt vmcnt(7)
	ds_write_b128 v171, v[178:181]
	s_waitcnt vmcnt(6)
	ds_write_b128 v170, v[216:219]
	ds_read_b128 v[178:181], v192 offset:36960
	ds_read_b128 v[216:219], v192 offset:41568
	s_waitcnt lgkmcnt(5)
	v_mfma_f32_32x32x16_bf16 v[80:95], v[208:211], v[224:227], v[80:95]
	v_mfma_f32_32x32x16_bf16 v[16:31], v[212:215], v[224:227], v[16:31]
	ds_read_b128 v[224:227], v184 offset:96
	s_waitcnt lgkmcnt(5)
	v_mfma_f32_32x32x16_bf16 v[64:79], v[208:211], v[228:231], v[64:79]
	v_mfma_f32_32x32x16_bf16 v[0:15], v[212:215], v[228:231], v[0:15]
	ds_read_b128 v[228:231], v184 offset:4704
	s_setprio 0
	global_load_dwordx4 v[208:211], v[152:153], off offset:512
	global_load_dwordx4 v[212:215], v[156:157], off offset:512
	s_setprio 1
	s_waitcnt lgkmcnt(1)
	v_mfma_f32_32x32x16_bf16 v[112:127], v[178:181], v[224:227], v[112:127]
	v_mfma_f32_32x32x16_bf16 v[48:63], v[216:219], v[224:227], v[48:63]
	s_waitcnt lgkmcnt(0)
	v_mfma_f32_32x32x16_bf16 v[96:111], v[178:181], v[228:231], v[96:111]
	v_mfma_f32_32x32x16_bf16 v[32:47], v[216:219], v[228:231], v[32:47]
	ds_read_b128 v[224:227], v184 offset:9312
	ds_read_b128 v[228:231], v184 offset:13920
	s_waitcnt lgkmcnt(1)
	v_mfma_f32_32x32x16_bf16 v[80:95], v[178:181], v[224:227], v[80:95]
	v_mfma_f32_32x32x16_bf16 v[16:31], v[216:219], v[224:227], v[16:31]
	s_waitcnt lgkmcnt(0)
	v_mfma_f32_32x32x16_bf16 v[64:79], v[178:181], v[228:231], v[64:79]
	v_mfma_f32_32x32x16_bf16 v[0:15], v[216:219], v[228:231], v[0:15]
	s_setprio 0
	global_load_dwordx4 v[178:181], v[128:129], off offset:640
	global_load_dwordx4 v[216:219], v[132:133], off offset:640
	s_barrier
; template <bool trans>
; DI void gemm_core(const GTile& tl, const GTile& nx, bool has_next  , bool chain  , bool pre, u32x4 (&ra)[4], u32x4 (&rb)[4], char* smem, f32x16 (&acc)[2][4]) {
;     ...
;   const int nk = K / 64;
;   if (!pre) { G_LOAD(0); G_STORE(0); G_LOAD(1); }
;   for (int kt = 0; kt < nk; ++kt) {
;     __syncthreads();
;     G_COMPUTE(kt & 1, kt);
	s_waitcnt vmcnt(9)
	ds_write_b128 v191, v[172:175]
	s_waitcnt vmcnt(8)
	ds_write_b128 v191, v[220:223] offset:36864
	ds_read_b128 v[172:175], v169
	ds_read_b128 v[220:223], v169 offset:4608
	ds_read_b128 v[224:227], v168
	ds_read_b128 v[228:231], v168 offset:4608
	s_setprio 1
	s_waitcnt lgkmcnt(1)
	v_mfma_f32_32x32x16_bf16 v[112:127], v[172:175], v[224:227], v[112:127]
	v_mfma_f32_32x32x16_bf16 v[48:63], v[220:223], v[224:227], v[48:63]
	s_waitcnt lgkmcnt(0)
	v_mfma_f32_32x32x16_bf16 v[96:111], v[172:175], v[228:231], v[96:111]
	v_mfma_f32_32x32x16_bf16 v[32:47], v[220:223], v[228:231], v[32:47]
	ds_read_b128 v[224:227], v168 offset:9216
	ds_read_b128 v[228:231], v168 offset:13824
	s_waitcnt vmcnt(7)
	ds_write_b128 v191, v[158:161] offset:9216
	s_waitcnt vmcnt(6)
	ds_write_b128 v191, v[162:165] offset:46080
	ds_read_b128 v[158:161], v169 offset:32
	ds_read_b128 v[162:165], v169 offset:4640
	s_waitcnt lgkmcnt(5)
	v_mfma_f32_32x32x16_bf16 v[80:95], v[172:175], v[224:227], v[80:95]
	v_mfma_f32_32x32x16_bf16 v[16:31], v[220:223], v[224:227], v[16:31]
	ds_read_b128 v[224:227], v168 offset:32
	s_waitcnt lgkmcnt(5)
	v_mfma_f32_32x32x16_bf16 v[64:79], v[172:175], v[228:231], v[64:79]
	v_mfma_f32_32x32x16_bf16 v[0:15], v[220:223], v[228:231], v[0:15]
	ds_read_b128 v[228:231], v168 offset:4640
	s_setprio 0
	global_load_dwordx4 v[172:175], v[136:137], off offset:640
	global_load_dwordx4 v[220:223], v[140:141], off offset:640
	s_setprio 1
	s_waitcnt lgkmcnt(1)
	v_mfma_f32_32x32x16_bf16 v[112:127], v[158:161], v[224:227], v[112:127]
	v_mfma_f32_32x32x16_bf16 v[48:63], v[162:165], v[224:227], v[48:63]
	s_waitcnt lgkmcnt(0)
	v_mfma_f32_32x32x16_bf16 v[96:111], v[158:161], v[228:231], v[96:111]
	v_mfma_f32_32x32x16_bf16 v[32:47], v[162:165], v[228:231], v[32:47]
	ds_read_b128 v[224:227], v168 offset:9248
	ds_read_b128 v[228:231], v168 offset:13856
	s_waitcnt vmcnt(7)
	ds_write_b128 v191, v[198:201] offset:18432
	s_waitcnt vmcnt(6)
	ds_write_b128 v191, v[202:205] offset:55296
	ds_read_b128 v[198:201], v169 offset:64
	ds_read_b128 v[202:205], v169 offset:4672
	s_waitcnt lgkmcnt(5)
	v_mfma_f32_32x32x16_bf16 v[80:95], v[158:161], v[224:227], v[80:95]
	v_mfma_f32_32x32x16_bf16 v[16:31], v[162:165], v[224:227], v[16:31]
	ds_read_b128 v[224:227], v168 offset:64
	s_waitcnt lgkmcnt(5)
	v_mfma_f32_32x32x16_bf16 v[64:79], v[158:161], v[228:231], v[64:79]
	v_mfma_f32_32x32x16_bf16 v[0:15], v[162:165], v[228:231], v[0:15]
	ds_read_b128 v[228:231], v168 offset:4672
	s_setprio 0
	global_load_dwordx4 v[158:161], v[144:145], off offset:640
	global_load_dwordx4 v[162:165], v[148:149], off offset:640
	s_setprio 1
	s_waitcnt lgkmcnt(1)
	v_mfma_f32_32x32x16_bf16 v[112:127], v[198:201], v[224:227], v[112:127]
	v_mfma_f32_32x32x16_bf16 v[48:63], v[202:205], v[224:227], v[48:63]
	s_waitcnt lgkmcnt(0)
	v_mfma_f32_32x32x16_bf16 v[96:111], v[198:201], v[228:231], v[96:111]
	v_mfma_f32_32x32x16_bf16 v[32:47], v[202:205], v[228:231], v[32:47]
	ds_read_b128 v[224:227], v168 offset:9280
	ds_read_b128 v[228:231], v168 offset:13888
	s_waitcnt vmcnt(7)
	ds_write_b128 v191, v[208:211] offset:27648
	s_waitcnt vmcnt(6)
	ds_write_b128 v191, v[212:215] offset:64512
	ds_read_b128 v[208:211], v169 offset:96
	ds_read_b128 v[212:215], v169 offset:4704
	s_waitcnt lgkmcnt(5)
	v_mfma_f32_32x32x16_bf16 v[80:95], v[198:201], v[224:227], v[80:95]
	v_mfma_f32_32x32x16_bf16 v[16:31], v[202:205], v[224:227], v[16:31]
	ds_read_b128 v[224:227], v168 offset:96
	s_waitcnt lgkmcnt(5)
	v_mfma_f32_32x32x16_bf16 v[64:79], v[198:201], v[228:231], v[64:79]
	v_mfma_f32_32x32x16_bf16 v[0:15], v[202:205], v[228:231], v[0:15]
	ds_read_b128 v[228:231], v168 offset:4704
	s_setprio 0
	global_load_dwordx4 v[198:201], v[152:153], off offset:640
	global_load_dwordx4 v[202:205], v[156:157], off offset:640
	s_setprio 1
	s_waitcnt lgkmcnt(1)
	v_mfma_f32_32x32x16_bf16 v[112:127], v[208:211], v[224:227], v[112:127]
	v_mfma_f32_32x32x16_bf16 v[48:63], v[212:215], v[224:227], v[48:63]
	s_waitcnt lgkmcnt(0)
	v_mfma_f32_32x32x16_bf16 v[96:111], v[208:211], v[228:231], v[96:111]
	v_mfma_f32_32x32x16_bf16 v[32:47], v[212:215], v[228:231], v[32:47]
	ds_read_b128 v[224:227], v168 offset:9312
	ds_read_b128 v[228:231], v168 offset:13920
	s_waitcnt lgkmcnt(1)
	v_mfma_f32_32x32x16_bf16 v[80:95], v[208:211], v[224:227], v[80:95]
	v_mfma_f32_32x32x16_bf16 v[16:31], v[212:215], v[224:227], v[16:31]
	s_waitcnt lgkmcnt(0)
	v_mfma_f32_32x32x16_bf16 v[64:79], v[208:211], v[228:231], v[64:79]
	v_mfma_f32_32x32x16_bf16 v[0:15], v[212:215], v[228:231], v[0:15]
	s_setprio 0
	global_load_dwordx4 v[208:211], v[128:129], off offset:768
	global_load_dwordx4 v[212:215], v[132:133], off offset:768
	s_barrier
; template <bool trans>
; DI void gemm_core(const GTile& tl, const GTile& nx, bool has_next  , bool chain  , bool pre, u32x4 (&ra)[4], u32x4 (&rb)[4], char* smem, f32x16 (&acc)[2][4]) {
;     ...
;   const int nk = K / 64;
;   if (!pre) { G_LOAD(0); G_STORE(0); G_LOAD(1); }
;   for (int kt = 0; kt < nk; ++kt) {
;     __syncthreads();
;     G_COMPUTE(kt & 1, kt);
	s_waitcnt vmcnt(9)
	ds_write_b128 v195, v[178:181]
	s_waitcnt vmcnt(8)
	ds_write_b128 v196, v[216:219]
	ds_read_b128 v[178:181], v192 offset:36864
	ds_read_b128 v[216:219], v192 offset:41472
	ds_read_b128 v[224:227], v184
	ds_read_b128 v[228:231], v184 offset:4608
	s_setprio 1
	s_waitcnt lgkmcnt(1)
	v_mfma_f32_32x32x16_bf16 v[112:127], v[178:181], v[224:227], v[112:127]
	v_mfma_f32_32x32x16_bf16 v[48:63], v[216:219], v[224:227], v[48:63]
	s_waitcnt lgkmcnt(0)
	v_mfma_f32_32x32x16_bf16 v[96:111], v[178:181], v[228:231], v[96:111]
	v_mfma_f32_32x32x16_bf16 v[32:47], v[216:219], v[228:231], v[32:47]
	ds_read_b128 v[224:227], v184 offset:9216
	ds_read_b128 v[228:231], v184 offset:13824
	s_waitcnt vmcnt(7)
	ds_write_b128 v194, v[172:175]
	s_waitcnt vmcnt(6)
	ds_write_b128 v193, v[220:223]
	ds_read_b128 v[172:175], v192 offset:36896
	ds_read_b128 v[220:223], v192 offset:41504
	s_waitcnt lgkmcnt(5)
	v_mfma_f32_32x32x16_bf16 v[80:95], v[178:181], v[224:227], v[80:95]
	v_mfma_f32_32x32x16_bf16 v[16:31], v[216:219], v[224:227], v[16:31]
	ds_read_b128 v[224:227], v184 offset:32
	s_waitcnt lgkmcnt(5)
	v_mfma_f32_32x32x16_bf16 v[64:79], v[178:181], v[228:231], v[64:79]
	v_mfma_f32_32x32x16_bf16 v[0:15], v[216:219], v[228:231], v[0:15]
	ds_read_b128 v[228:231], v184 offset:4640
	s_setprio 0
	global_load_dwordx4 v[178:181], v[136:137], off offset:768
	global_load_dwordx4 v[216:219], v[140:141], off offset:768
	s_setprio 1
	s_waitcnt lgkmcnt(1)
	v_mfma_f32_32x32x16_bf16 v[112:127], v[172:175], v[224:227], v[112:127]
	v_mfma_f32_32x32x16_bf16 v[48:63], v[220:223], v[224:227], v[48:63]
	s_waitcnt lgkmcnt(0)
	v_mfma_f32_32x32x16_bf16 v[96:111], v[172:175], v[228:231], v[96:111]
	v_mfma_f32_32x32x16_bf16 v[32:47], v[220:223], v[228:231], v[32:47]
	ds_read_b128 v[224:227], v184 offset:9248
	ds_read_b128 v[228:231], v184 offset:13856
	s_waitcnt vmcnt(7)
	ds_write_b128 v177, v[158:161]
	s_waitcnt vmcnt(6)
	ds_write_b128 v176, v[162:165]
	ds_read_b128 v[158:161], v192 offset:36928
	ds_read_b128 v[162:165], v192 offset:41536
	s_waitcnt lgkmcnt(5)
	v_mfma_f32_32x32x16_bf16 v[80:95], v[172:175], v[224:227], v[80:95]
	v_mfma_f32_32x32x16_bf16 v[16:31], v[220:223], v[224:227], v[16:31]
	ds_read_b128 v[224:227], v184 offset:64
	s_waitcnt lgkmcnt(5)
	v_mfma_f32_32x32x16_bf16 v[64:79], v[172:175], v[228:231], v[64:79]
	v_mfma_f32_32x32x16_bf16 v[0:15], v[220:223], v[228:231], v[0:15]
	ds_read_b128 v[228:231], v184 offset:4672
	s_setprio 0
	global_load_dwordx4 v[172:175], v[144:145], off offset:768
	global_load_dwordx4 v[220:223], v[148:149], off offset:768
	s_setprio 1
	s_waitcnt lgkmcnt(1)
	v_mfma_f32_32x32x16_bf16 v[112:127], v[158:161], v[224:227], v[112:127]
	v_mfma_f32_32x32x16_bf16 v[48:63], v[162:165], v[224:227], v[48:63]
	s_waitcnt lgkmcnt(0)
	v_mfma_f32_32x32x16_bf16 v[96:111], v[158:161], v[228:231], v[96:111]
	v_mfma_f32_32x32x16_bf16 v[32:47], v[162:165], v[228:231], v[32:47]
	ds_read_b128 v[224:227], v184 offset:9280
	ds_read_b128 v[228:231], v184 offset:13888
	s_waitcnt vmcnt(7)
	ds_write_b128 v171, v[198:201]
	s_waitcnt vmcnt(6)
	ds_write_b128 v170, v[202:205]
	ds_read_b128 v[198:201], v192 offset:36960
	ds_read_b128 v[202:205], v192 offset:41568
	s_waitcnt lgkmcnt(5)
	v_mfma_f32_32x32x16_bf16 v[80:95], v[158:161], v[224:227], v[80:95]
	v_mfma_f32_32x32x16_bf16 v[16:31], v[162:165], v[224:227], v[16:31]
	ds_read_b128 v[224:227], v184 offset:96
	s_waitcnt lgkmcnt(5)
	v_mfma_f32_32x32x16_bf16 v[64:79], v[158:161], v[228:231], v[64:79]
	v_mfma_f32_32x32x16_bf16 v[0:15], v[162:165], v[228:231], v[0:15]
	ds_read_b128 v[228:231], v184 offset:4704
	s_setprio 0
	global_load_dwordx4 v[158:161], v[152:153], off offset:768
	global_load_dwordx4 v[162:165], v[156:157], off offset:768
	s_setprio 1
	s_waitcnt lgkmcnt(1)
	v_mfma_f32_32x32x16_bf16 v[112:127], v[198:201], v[224:227], v[112:127]
	v_mfma_f32_32x32x16_bf16 v[48:63], v[202:205], v[224:227], v[48:63]
	s_waitcnt lgkmcnt(0)
	v_mfma_f32_32x32x16_bf16 v[96:111], v[198:201], v[228:231], v[96:111]
	v_mfma_f32_32x32x16_bf16 v[32:47], v[202:205], v[228:231], v[32:47]
	ds_read_b128 v[224:227], v184 offset:9312
	ds_read_b128 v[228:231], v184 offset:13920
	s_waitcnt lgkmcnt(1)
	v_mfma_f32_32x32x16_bf16 v[80:95], v[198:201], v[224:227], v[80:95]
	v_mfma_f32_32x32x16_bf16 v[16:31], v[202:205], v[224:227], v[16:31]
	s_waitcnt lgkmcnt(0)
	v_mfma_f32_32x32x16_bf16 v[64:79], v[198:201], v[228:231], v[64:79]
	v_mfma_f32_32x32x16_bf16 v[0:15], v[202:205], v[228:231], v[0:15]
	s_setprio 0
	global_load_dwordx4 v[198:201], v[128:129], off offset:896
	global_load_dwordx4 v[202:205], v[132:133], off offset:896
	s_barrier
; template <bool trans>
; DI void gemm_core(const GTile& tl, const GTile& nx, bool has_next  , bool chain  , bool pre, u32x4 (&ra)[4], u32x4 (&rb)[4], char* smem, f32x16 (&acc)[2][4]) {
;     ...
;   const int nk = K / 64;
;   if (!pre) { G_LOAD(0); G_STORE(0); G_LOAD(1); }
;   for (int kt = 0; kt < nk; ++kt) {
;     __syncthreads();
;     G_COMPUTE(kt & 1, kt);
	s_waitcnt vmcnt(9)
	ds_write_b128 v191, v[208:211]
	s_waitcnt vmcnt(8)
	ds_write_b128 v191, v[212:215] offset:36864
	ds_read_b128 v[208:211], v169
	ds_read_b128 v[212:215], v169 offset:4608
	ds_read_b128 v[224:227], v168
	ds_read_b128 v[228:231], v168 offset:4608
	s_setprio 1
	s_waitcnt lgkmcnt(1)
	v_mfma_f32_32x32x16_bf16 v[112:127], v[208:211], v[224:227], v[112:127]
	v_mfma_f32_32x32x16_bf16 v[48:63], v[212:215], v[224:227], v[48:63]
	s_waitcnt lgkmcnt(0)
	v_mfma_f32_32x32x16_bf16 v[96:111], v[208:211], v[228:231], v[96:111]
	v_mfma_f32_32x32x16_bf16 v[32:47], v[212:215], v[228:231], v[32:47]
	ds_read_b128 v[224:227], v168 offset:9216
	ds_read_b128 v[228:231], v168 offset:13824
	s_waitcnt vmcnt(7)
	ds_write_b128 v191, v[178:181] offset:9216
	s_waitcnt vmcnt(6)
	ds_write_b128 v191, v[216:219] offset:46080
	ds_read_b128 v[178:181], v169 offset:32
	ds_read_b128 v[216:219], v169 offset:4640
	s_waitcnt lgkmcnt(5)
	v_mfma_f32_32x32x16_bf16 v[80:95], v[208:211], v[224:227], v[80:95]
	v_mfma_f32_32x32x16_bf16 v[16:31], v[212:215], v[224:227], v[16:31]
	ds_read_b128 v[224:227], v168 offset:32
	s_waitcnt lgkmcnt(5)
	v_mfma_f32_32x32x16_bf16 v[64:79], v[208:211], v[228:231], v[64:79]
	v_mfma_f32_32x32x16_bf16 v[0:15], v[212:215], v[228:231], v[0:15]
	ds_read_b128 v[228:231], v168 offset:4640
	s_setprio 0
	global_load_dwordx4 v[208:211], v[136:137], off offset:896
	global_load_dwordx4 v[212:215], v[140:141], off offset:896
	s_setprio 1
	s_waitcnt lgkmcnt(1)
	v_mfma_f32_32x32x16_bf16 v[112:127], v[178:181], v[224:227], v[112:127]
	v_mfma_f32_32x32x16_bf16 v[48:63], v[216:219], v[224:227], v[48:63]
	s_waitcnt lgkmcnt(0)
	v_mfma_f32_32x32x16_bf16 v[96:111], v[178:181], v[228:231], v[96:111]
	v_mfma_f32_32x32x16_bf16 v[32:47], v[216:219], v[228:231], v[32:47]
	ds_read_b128 v[224:227], v168 offset:9248
	ds_read_b128 v[228:231], v168 offset:13856
	s_waitcnt vmcnt(7)
	ds_write_b128 v191, v[172:175] offset:18432
	s_waitcnt vmcnt(6)
	ds_write_b128 v191, v[220:223] offset:55296
	ds_read_b128 v[172:175], v169 offset:64
	ds_read_b128 v[220:223], v169 offset:4672
	s_waitcnt lgkmcnt(5)
	v_mfma_f32_32x32x16_bf16 v[80:95], v[178:181], v[224:227], v[80:95]
	v_mfma_f32_32x32x16_bf16 v[16:31], v[216:219], v[224:227], v[16:31]
	ds_read_b128 v[224:227], v168 offset:64
	s_waitcnt lgkmcnt(5)
	v_mfma_f32_32x32x16_bf16 v[64:79], v[178:181], v[228:231], v[64:79]
	v_mfma_f32_32x32x16_bf16 v[0:15], v[216:219], v[228:231], v[0:15]
	ds_read_b128 v[228:231], v168 offset:4672
	s_setprio 0
	global_load_dwordx4 v[178:181], v[144:145], off offset:896
	global_load_dwordx4 v[216:219], v[148:149], off offset:896
	s_setprio 1
	s_waitcnt lgkmcnt(1)
	v_mfma_f32_32x32x16_bf16 v[112:127], v[172:175], v[224:227], v[112:127]
	v_mfma_f32_32x32x16_bf16 v[48:63], v[220:223], v[224:227], v[48:63]
	s_waitcnt lgkmcnt(0)
	v_mfma_f32_32x32x16_bf16 v[96:111], v[172:175], v[228:231], v[96:111]
	v_mfma_f32_32x32x16_bf16 v[32:47], v[220:223], v[228:231], v[32:47]
	ds_read_b128 v[224:227], v168 offset:9280
	ds_read_b128 v[228:231], v168 offset:13888
	s_waitcnt vmcnt(7)
	ds_write_b128 v191, v[158:161] offset:27648
	s_waitcnt vmcnt(6)
	ds_write_b128 v191, v[162:165] offset:64512
	ds_read_b128 v[158:161], v169 offset:96
	ds_read_b128 v[162:165], v169 offset:4704
	s_waitcnt lgkmcnt(5)
	v_mfma_f32_32x32x16_bf16 v[80:95], v[172:175], v[224:227], v[80:95]
	v_mfma_f32_32x32x16_bf16 v[16:31], v[220:223], v[224:227], v[16:31]
	ds_read_b128 v[224:227], v168 offset:96
	s_waitcnt lgkmcnt(5)
	v_mfma_f32_32x32x16_bf16 v[64:79], v[172:175], v[228:231], v[64:79]
	v_mfma_f32_32x32x16_bf16 v[0:15], v[220:223], v[228:231], v[0:15]
	ds_read_b128 v[228:231], v168 offset:4704
	s_setprio 0
	global_load_dwordx4 v[172:175], v[152:153], off offset:896
	global_load_dwordx4 v[220:223], v[156:157], off offset:896
	s_setprio 1
	s_waitcnt lgkmcnt(1)
	v_mfma_f32_32x32x16_bf16 v[112:127], v[158:161], v[224:227], v[112:127]
	v_mfma_f32_32x32x16_bf16 v[48:63], v[162:165], v[224:227], v[48:63]
	s_waitcnt lgkmcnt(0)
	v_mfma_f32_32x32x16_bf16 v[96:111], v[158:161], v[228:231], v[96:111]
	v_mfma_f32_32x32x16_bf16 v[32:47], v[162:165], v[228:231], v[32:47]
	ds_read_b128 v[224:227], v168 offset:9312
	ds_read_b128 v[228:231], v168 offset:13920
	s_waitcnt lgkmcnt(1)
	v_mfma_f32_32x32x16_bf16 v[80:95], v[158:161], v[224:227], v[80:95]
	v_mfma_f32_32x32x16_bf16 v[16:31], v[162:165], v[224:227], v[16:31]
	s_waitcnt lgkmcnt(0)
	v_mfma_f32_32x32x16_bf16 v[64:79], v[158:161], v[228:231], v[64:79]
	v_mfma_f32_32x32x16_bf16 v[0:15], v[162:165], v[228:231], v[0:15]
	s_setprio 0
	global_load_dwordx4 v[158:161], v[128:129], off offset:1024
	global_load_dwordx4 v[162:165], v[132:133], off offset:1024
	s_barrier
; template <bool trans>
; DI void gemm_core(const GTile& tl, const GTile& nx, bool has_next  , bool chain  , bool pre, u32x4 (&ra)[4], u32x4 (&rb)[4], char* smem, f32x16 (&acc)[2][4]) {
;     ...
;   const int nk = K / 64;
;   if (!pre) { G_LOAD(0); G_STORE(0); G_LOAD(1); }
;   for (int kt = 0; kt < nk; ++kt) {
;     __syncthreads();
;     G_COMPUTE(kt & 1, kt);
	s_waitcnt vmcnt(9)
	ds_write_b128 v195, v[198:201]
	s_waitcnt vmcnt(8)
	ds_write_b128 v196, v[202:205]
	ds_read_b128 v[198:201], v192 offset:36864
	ds_read_b128 v[202:205], v192 offset:41472
	ds_read_b128 v[224:227], v184
	ds_read_b128 v[228:231], v184 offset:4608
	s_setprio 1
	s_waitcnt lgkmcnt(1)
	v_mfma_f32_32x32x16_bf16 v[112:127], v[198:201], v[224:227], v[112:127]
	v_mfma_f32_32x32x16_bf16 v[48:63], v[202:205], v[224:227], v[48:63]
	s_waitcnt lgkmcnt(0)
	v_mfma_f32_32x32x16_bf16 v[96:111], v[198:201], v[228:231], v[96:111]
	v_mfma_f32_32x32x16_bf16 v[32:47], v[202:205], v[228:231], v[32:47]
	ds_read_b128 v[224:227], v184 offset:9216
	ds_read_b128 v[228:231], v184 offset:13824
	s_waitcnt vmcnt(7)
	ds_write_b128 v194, v[208:211]
	s_waitcnt vmcnt(6)
	ds_write_b128 v193, v[212:215]
	ds_read_b128 v[208:211], v192 offset:36896
	ds_read_b128 v[212:215], v192 offset:41504
	s_waitcnt lgkmcnt(5)
	v_mfma_f32_32x32x16_bf16 v[80:95], v[198:201], v[224:227], v[80:95]
	v_mfma_f32_32x32x16_bf16 v[16:31], v[202:205], v[224:227], v[16:31]
	ds_read_b128 v[224:227], v184 offset:32
	s_waitcnt lgkmcnt(5)
	v_mfma_f32_32x32x16_bf16 v[64:79], v[198:201], v[228:231], v[64:79]
	v_mfma_f32_32x32x16_bf16 v[0:15], v[202:205], v[228:231], v[0:15]
	ds_read_b128 v[228:231], v184 offset:4640
	s_setprio 0
	global_load_dwordx4 v[198:201], v[136:137], off offset:1024
	global_load_dwordx4 v[202:205], v[140:141], off offset:1024
	s_setprio 1
	s_waitcnt lgkmcnt(1)
	v_mfma_f32_32x32x16_bf16 v[112:127], v[208:211], v[224:227], v[112:127]
	v_mfma_f32_32x32x16_bf16 v[48:63], v[212:215], v[224:227], v[48:63]
	s_waitcnt lgkmcnt(0)
	v_mfma_f32_32x32x16_bf16 v[96:111], v[208:211], v[228:231], v[96:111]
	v_mfma_f32_32x32x16_bf16 v[32:47], v[212:215], v[228:231], v[32:47]
	ds_read_b128 v[224:227], v184 offset:9248
	ds_read_b128 v[228:231], v184 offset:13856
	s_waitcnt vmcnt(7)
	ds_write_b128 v177, v[178:181]
	s_waitcnt vmcnt(6)
	ds_write_b128 v176, v[216:219]
	ds_read_b128 v[178:181], v192 offset:36928
	ds_read_b128 v[216:219], v192 offset:41536
	s_waitcnt lgkmcnt(5)
	v_mfma_f32_32x32x16_bf16 v[80:95], v[208:211], v[224:227], v[80:95]
	v_mfma_f32_32x32x16_bf16 v[16:31], v[212:215], v[224:227], v[16:31]
	ds_read_b128 v[224:227], v184 offset:64
	s_waitcnt lgkmcnt(5)
	v_mfma_f32_32x32x16_bf16 v[64:79], v[208:211], v[228:231], v[64:79]
	v_mfma_f32_32x32x16_bf16 v[0:15], v[212:215], v[228:231], v[0:15]
	ds_read_b128 v[228:231], v184 offset:4672
	s_setprio 0
	global_load_dwordx4 v[208:211], v[144:145], off offset:1024
	global_load_dwordx4 v[212:215], v[148:149], off offset:1024
	s_setprio 1
	s_waitcnt lgkmcnt(1)
	v_mfma_f32_32x32x16_bf16 v[112:127], v[178:181], v[224:227], v[112:127]
	v_mfma_f32_32x32x16_bf16 v[48:63], v[216:219], v[224:227], v[48:63]
	s_waitcnt lgkmcnt(0)
	v_mfma_f32_32x32x16_bf16 v[96:111], v[178:181], v[228:231], v[96:111]
	v_mfma_f32_32x32x16_bf16 v[32:47], v[216:219], v[228:231], v[32:47]
	ds_read_b128 v[224:227], v184 offset:9280
	ds_read_b128 v[228:231], v184 offset:13888
	s_waitcnt vmcnt(7)
	ds_write_b128 v171, v[172:175]
	s_waitcnt vmcnt(6)
	ds_write_b128 v170, v[220:223]
	ds_read_b128 v[172:175], v192 offset:36960
	ds_read_b128 v[220:223], v192 offset:41568
	s_waitcnt lgkmcnt(5)
	v_mfma_f32_32x32x16_bf16 v[80:95], v[178:181], v[224:227], v[80:95]
	v_mfma_f32_32x32x16_bf16 v[16:31], v[216:219], v[224:227], v[16:31]
	ds_read_b128 v[224:227], v184 offset:96
	s_waitcnt lgkmcnt(5)
	v_mfma_f32_32x32x16_bf16 v[64:79], v[178:181], v[228:231], v[64:79]
	v_mfma_f32_32x32x16_bf16 v[0:15], v[216:219], v[228:231], v[0:15]
	ds_read_b128 v[228:231], v184 offset:4704
	s_setprio 0
	global_load_dwordx4 v[178:181], v[152:153], off offset:1024
	global_load_dwordx4 v[216:219], v[156:157], off offset:1024
	s_setprio 1
	s_waitcnt lgkmcnt(1)
	v_mfma_f32_32x32x16_bf16 v[112:127], v[172:175], v[224:227], v[112:127]
	v_mfma_f32_32x32x16_bf16 v[48:63], v[220:223], v[224:227], v[48:63]
	s_waitcnt lgkmcnt(0)
	v_mfma_f32_32x32x16_bf16 v[96:111], v[172:175], v[228:231], v[96:111]
	v_mfma_f32_32x32x16_bf16 v[32:47], v[220:223], v[228:231], v[32:47]
	ds_read_b128 v[224:227], v184 offset:9312
	ds_read_b128 v[228:231], v184 offset:13920
	s_waitcnt lgkmcnt(1)
	v_mfma_f32_32x32x16_bf16 v[80:95], v[172:175], v[224:227], v[80:95]
	v_mfma_f32_32x32x16_bf16 v[16:31], v[220:223], v[224:227], v[16:31]
	s_waitcnt lgkmcnt(0)
	v_mfma_f32_32x32x16_bf16 v[64:79], v[172:175], v[228:231], v[64:79]
	v_mfma_f32_32x32x16_bf16 v[0:15], v[220:223], v[228:231], v[0:15]
	s_setprio 0
	global_load_dwordx4 v[172:175], v[128:129], off offset:1152
	global_load_dwordx4 v[220:223], v[132:133], off offset:1152
	s_barrier
; template <bool trans>
; DI void gemm_core(const GTile& tl, const GTile& nx, bool has_next  , bool chain  , bool pre, u32x4 (&ra)[4], u32x4 (&rb)[4], char* smem, f32x16 (&acc)[2][4]) {
;     ...
;   const int nk = K / 64;
;   if (!pre) { G_LOAD(0); G_STORE(0); G_LOAD(1); }
;   for (int kt = 0; kt < nk; ++kt) {
;     __syncthreads();
;     G_COMPUTE(kt & 1, kt);
	s_waitcnt vmcnt(9)
	ds_write_b128 v191, v[158:161]
	s_waitcnt vmcnt(8)
	ds_write_b128 v191, v[162:165] offset:36864
	ds_read_b128 v[158:161], v169
	ds_read_b128 v[162:165], v169 offset:4608
	ds_read_b128 v[224:227], v168
	ds_read_b128 v[228:231], v168 offset:4608
	s_setprio 1
	s_waitcnt lgkmcnt(1)
	v_mfma_f32_32x32x16_bf16 v[112:127], v[158:161], v[224:227], v[112:127]
	v_mfma_f32_32x32x16_bf16 v[48:63], v[162:165], v[224:227], v[48:63]
	s_waitcnt lgkmcnt(0)
	v_mfma_f32_32x32x16_bf16 v[96:111], v[158:161], v[228:231], v[96:111]
	v_mfma_f32_32x32x16_bf16 v[32:47], v[162:165], v[228:231], v[32:47]
	ds_read_b128 v[224:227], v168 offset:9216
	ds_read_b128 v[228:231], v168 offset:13824
	s_waitcnt vmcnt(7)
	ds_write_b128 v191, v[198:201] offset:9216
	s_waitcnt vmcnt(6)
	ds_write_b128 v191, v[202:205] offset:46080
	ds_read_b128 v[198:201], v169 offset:32
	ds_read_b128 v[202:205], v169 offset:4640
	s_waitcnt lgkmcnt(5)
	v_mfma_f32_32x32x16_bf16 v[80:95], v[158:161], v[224:227], v[80:95]
	v_mfma_f32_32x32x16_bf16 v[16:31], v[162:165], v[224:227], v[16:31]
	ds_read_b128 v[224:227], v168 offset:32
	s_waitcnt lgkmcnt(5)
	v_mfma_f32_32x32x16_bf16 v[64:79], v[158:161], v[228:231], v[64:79]
	v_mfma_f32_32x32x16_bf16 v[0:15], v[162:165], v[228:231], v[0:15]
	ds_read_b128 v[228:231], v168 offset:4640
	s_setprio 0
	global_load_dwordx4 v[158:161], v[136:137], off offset:1152
	global_load_dwordx4 v[162:165], v[140:141], off offset:1152
	s_setprio 1
	s_waitcnt lgkmcnt(1)
	v_mfma_f32_32x32x16_bf16 v[112:127], v[198:201], v[224:227], v[112:127]
	v_mfma_f32_32x32x16_bf16 v[48:63], v[202:205], v[224:227], v[48:63]
	s_waitcnt lgkmcnt(0)
	v_mfma_f32_32x32x16_bf16 v[96:111], v[198:201], v[228:231], v[96:111]
	v_mfma_f32_32x32x16_bf16 v[32:47], v[202:205], v[228:231], v[32:47]
	ds_read_b128 v[224:227], v168 offset:9248
	ds_read_b128 v[228:231], v168 offset:13856
	s_waitcnt vmcnt(7)
	ds_write_b128 v191, v[208:211] offset:18432
	s_waitcnt vmcnt(6)
	ds_write_b128 v191, v[212:215] offset:55296
	ds_read_b128 v[208:211], v169 offset:64
	ds_read_b128 v[212:215], v169 offset:4672
	s_waitcnt lgkmcnt(5)
	v_mfma_f32_32x32x16_bf16 v[80:95], v[198:201], v[224:227], v[80:95]
	v_mfma_f32_32x32x16_bf16 v[16:31], v[202:205], v[224:227], v[16:31]
	ds_read_b128 v[224:227], v168 offset:64
	s_waitcnt lgkmcnt(5)
	v_mfma_f32_32x32x16_bf16 v[64:79], v[198:201], v[228:231], v[64:79]
	v_mfma_f32_32x32x16_bf16 v[0:15], v[202:205], v[228:231], v[0:15]
	ds_read_b128 v[228:231], v168 offset:4672
	s_setprio 0
	global_load_dwordx4 v[198:201], v[144:145], off offset:1152
	global_load_dwordx4 v[202:205], v[148:149], off offset:1152
	s_setprio 1
	s_waitcnt lgkmcnt(1)
	v_mfma_f32_32x32x16_bf16 v[112:127], v[208:211], v[224:227], v[112:127]
	v_mfma_f32_32x32x16_bf16 v[48:63], v[212:215], v[224:227], v[48:63]
	s_waitcnt lgkmcnt(0)
	v_mfma_f32_32x32x16_bf16 v[96:111], v[208:211], v[228:231], v[96:111]
	v_mfma_f32_32x32x16_bf16 v[32:47], v[212:215], v[228:231], v[32:47]
	ds_read_b128 v[224:227], v168 offset:9280
	ds_read_b128 v[228:231], v168 offset:13888
	s_waitcnt vmcnt(7)
	ds_write_b128 v191, v[178:181] offset:27648
	s_waitcnt vmcnt(6)
	ds_write_b128 v191, v[216:219] offset:64512
	ds_read_b128 v[178:181], v169 offset:96
	ds_read_b128 v[216:219], v169 offset:4704
	s_waitcnt lgkmcnt(5)
	v_mfma_f32_32x32x16_bf16 v[80:95], v[208:211], v[224:227], v[80:95]
	v_mfma_f32_32x32x16_bf16 v[16:31], v[212:215], v[224:227], v[16:31]
	ds_read_b128 v[224:227], v168 offset:96
	s_waitcnt lgkmcnt(5)
	v_mfma_f32_32x32x16_bf16 v[64:79], v[208:211], v[228:231], v[64:79]
	v_mfma_f32_32x32x16_bf16 v[0:15], v[212:215], v[228:231], v[0:15]
	ds_read_b128 v[228:231], v168 offset:4704
	s_setprio 0
	global_load_dwordx4 v[208:211], v[152:153], off offset:1152
	global_load_dwordx4 v[212:215], v[156:157], off offset:1152
	s_setprio 1
	s_waitcnt lgkmcnt(1)
	v_mfma_f32_32x32x16_bf16 v[112:127], v[178:181], v[224:227], v[112:127]
	v_mfma_f32_32x32x16_bf16 v[48:63], v[216:219], v[224:227], v[48:63]
	s_waitcnt lgkmcnt(0)
	v_mfma_f32_32x32x16_bf16 v[96:111], v[178:181], v[228:231], v[96:111]
	v_mfma_f32_32x32x16_bf16 v[32:47], v[216:219], v[228:231], v[32:47]
	ds_read_b128 v[224:227], v168 offset:9312
	ds_read_b128 v[228:231], v168 offset:13920
	s_waitcnt lgkmcnt(1)
	v_mfma_f32_32x32x16_bf16 v[80:95], v[178:181], v[224:227], v[80:95]
	v_mfma_f32_32x32x16_bf16 v[16:31], v[216:219], v[224:227], v[16:31]
	s_waitcnt lgkmcnt(0)
	v_mfma_f32_32x32x16_bf16 v[64:79], v[178:181], v[228:231], v[64:79]
	v_mfma_f32_32x32x16_bf16 v[0:15], v[216:219], v[228:231], v[0:15]
	s_setprio 0
	global_load_dwordx4 v[178:181], v[128:129], off offset:1280
	global_load_dwordx4 v[216:219], v[132:133], off offset:1280
	s_barrier
; template <bool trans>
; DI void gemm_core(const GTile& tl, const GTile& nx, bool has_next  , bool chain  , bool pre, u32x4 (&ra)[4], u32x4 (&rb)[4], char* smem, f32x16 (&acc)[2][4]) {
;     ...
;   const int nk = K / 64;
;   if (!pre) { G_LOAD(0); G_STORE(0); G_LOAD(1); }
;   for (int kt = 0; kt < nk; ++kt) {
;     __syncthreads();
;     G_COMPUTE(kt & 1, kt);
	s_waitcnt vmcnt(9)
	ds_write_b128 v195, v[172:175]
	s_waitcnt vmcnt(8)
	ds_write_b128 v196, v[220:223]
	ds_read_b128 v[172:175], v192 offset:36864
	ds_read_b128 v[220:223], v192 offset:41472
	ds_read_b128 v[224:227], v184
	ds_read_b128 v[228:231], v184 offset:4608
	s_setprio 1
	s_waitcnt lgkmcnt(1)
	v_mfma_f32_32x32x16_bf16 v[112:127], v[172:175], v[224:227], v[112:127]
	v_mfma_f32_32x32x16_bf16 v[48:63], v[220:223], v[224:227], v[48:63]
	s_waitcnt lgkmcnt(0)
	v_mfma_f32_32x32x16_bf16 v[96:111], v[172:175], v[228:231], v[96:111]
	v_mfma_f32_32x32x16_bf16 v[32:47], v[220:223], v[228:231], v[32:47]
	ds_read_b128 v[224:227], v184 offset:9216
	ds_read_b128 v[228:231], v184 offset:13824
	s_waitcnt vmcnt(7)
	ds_write_b128 v194, v[158:161]
	s_waitcnt vmcnt(6)
	ds_write_b128 v193, v[162:165]
	ds_read_b128 v[158:161], v192 offset:36896
	ds_read_b128 v[162:165], v192 offset:41504
	s_waitcnt lgkmcnt(5)
	v_mfma_f32_32x32x16_bf16 v[80:95], v[172:175], v[224:227], v[80:95]
	v_mfma_f32_32x32x16_bf16 v[16:31], v[220:223], v[224:227], v[16:31]
	ds_read_b128 v[224:227], v184 offset:32
	s_waitcnt lgkmcnt(5)
	v_mfma_f32_32x32x16_bf16 v[64:79], v[172:175], v[228:231], v[64:79]
	v_mfma_f32_32x32x16_bf16 v[0:15], v[220:223], v[228:231], v[0:15]
	ds_read_b128 v[228:231], v184 offset:4640
	s_setprio 0
	global_load_dwordx4 v[172:175], v[136:137], off offset:1280
	global_load_dwordx4 v[220:223], v[140:141], off offset:1280
	s_setprio 1
	s_waitcnt lgkmcnt(1)
	v_mfma_f32_32x32x16_bf16 v[112:127], v[158:161], v[224:227], v[112:127]
	v_mfma_f32_32x32x16_bf16 v[48:63], v[162:165], v[224:227], v[48:63]
	s_waitcnt lgkmcnt(0)
	v_mfma_f32_32x32x16_bf16 v[96:111], v[158:161], v[228:231], v[96:111]
	v_mfma_f32_32x32x16_bf16 v[32:47], v[162:165], v[228:231], v[32:47]
	ds_read_b128 v[224:227], v184 offset:9248
	ds_read_b128 v[228:231], v184 offset:13856
	s_waitcnt vmcnt(7)
	ds_write_b128 v177, v[198:201]
	s_waitcnt vmcnt(6)
	ds_write_b128 v176, v[202:205]
	ds_read_b128 v[198:201], v192 offset:36928
	ds_read_b128 v[202:205], v192 offset:41536
	s_waitcnt lgkmcnt(5)
	v_mfma_f32_32x32x16_bf16 v[80:95], v[158:161], v[224:227], v[80:95]
	v_mfma_f32_32x32x16_bf16 v[16:31], v[162:165], v[224:227], v[16:31]
	ds_read_b128 v[224:227], v184 offset:64
	s_waitcnt lgkmcnt(5)
	v_mfma_f32_32x32x16_bf16 v[64:79], v[158:161], v[228:231], v[64:79]
	v_mfma_f32_32x32x16_bf16 v[0:15], v[162:165], v[228:231], v[0:15]
	ds_read_b128 v[228:231], v184 offset:4672
	s_setprio 0
	global_load_dwordx4 v[158:161], v[144:145], off offset:1280
	global_load_dwordx4 v[162:165], v[148:149], off offset:1280
	s_setprio 1
	s_waitcnt lgkmcnt(1)
	v_mfma_f32_32x32x16_bf16 v[112:127], v[198:201], v[224:227], v[112:127]
	v_mfma_f32_32x32x16_bf16 v[48:63], v[202:205], v[224:227], v[48:63]
	s_waitcnt lgkmcnt(0)
	v_mfma_f32_32x32x16_bf16 v[96:111], v[198:201], v[228:231], v[96:111]
	v_mfma_f32_32x32x16_bf16 v[32:47], v[202:205], v[228:231], v[32:47]
	ds_read_b128 v[224:227], v184 offset:9280
	ds_read_b128 v[228:231], v184 offset:13888
	s_waitcnt vmcnt(7)
	ds_write_b128 v171, v[208:211]
	s_waitcnt vmcnt(6)
	ds_write_b128 v170, v[212:215]
	ds_read_b128 v[208:211], v192 offset:36960
	ds_read_b128 v[212:215], v192 offset:41568
	s_waitcnt lgkmcnt(5)
	v_mfma_f32_32x32x16_bf16 v[80:95], v[198:201], v[224:227], v[80:95]
	v_mfma_f32_32x32x16_bf16 v[16:31], v[202:205], v[224:227], v[16:31]
	ds_read_b128 v[224:227], v184 offset:96
	s_waitcnt lgkmcnt(5)
	v_mfma_f32_32x32x16_bf16 v[64:79], v[198:201], v[228:231], v[64:79]
	v_mfma_f32_32x32x16_bf16 v[0:15], v[202:205], v[228:231], v[0:15]
	ds_read_b128 v[228:231], v184 offset:4704
	s_setprio 0
	global_load_dwordx4 v[198:201], v[152:153], off offset:1280
	global_load_dwordx4 v[202:205], v[156:157], off offset:1280
	s_setprio 1
	s_waitcnt lgkmcnt(1)
	v_mfma_f32_32x32x16_bf16 v[112:127], v[208:211], v[224:227], v[112:127]
	v_mfma_f32_32x32x16_bf16 v[48:63], v[212:215], v[224:227], v[48:63]
	s_waitcnt lgkmcnt(0)
	v_mfma_f32_32x32x16_bf16 v[96:111], v[208:211], v[228:231], v[96:111]
	v_mfma_f32_32x32x16_bf16 v[32:47], v[212:215], v[228:231], v[32:47]
	ds_read_b128 v[224:227], v184 offset:9312
	ds_read_b128 v[228:231], v184 offset:13920
	s_waitcnt lgkmcnt(1)
	v_mfma_f32_32x32x16_bf16 v[80:95], v[208:211], v[224:227], v[80:95]
	v_mfma_f32_32x32x16_bf16 v[16:31], v[212:215], v[224:227], v[16:31]
	s_waitcnt lgkmcnt(0)
	v_mfma_f32_32x32x16_bf16 v[64:79], v[208:211], v[228:231], v[64:79]
	v_mfma_f32_32x32x16_bf16 v[0:15], v[212:215], v[228:231], v[0:15]
	s_setprio 0
	global_load_dwordx4 v[208:211], v[128:129], off offset:1408
	global_load_dwordx4 v[212:215], v[132:133], off offset:1408
	s_barrier
; template <bool trans>
; DI void gemm_core(const GTile& tl, const GTile& nx, bool has_next  , bool chain  , bool pre, u32x4 (&ra)[4], u32x4 (&rb)[4], char* smem, f32x16 (&acc)[2][4]) {
;     ...
;   const int nk = K / 64;
;   if (!pre) { G_LOAD(0); G_STORE(0); G_LOAD(1); }
;   for (int kt = 0; kt < nk; ++kt) {
;     __syncthreads();
;     G_COMPUTE(kt & 1, kt);
	s_waitcnt vmcnt(9)
	ds_write_b128 v191, v[178:181]
	s_waitcnt vmcnt(8)
	ds_write_b128 v191, v[216:219] offset:36864
	ds_read_b128 v[178:181], v169
	ds_read_b128 v[216:219], v169 offset:4608
	ds_read_b128 v[224:227], v168
	ds_read_b128 v[228:231], v168 offset:4608
	s_setprio 1
	s_waitcnt lgkmcnt(1)
	v_mfma_f32_32x32x16_bf16 v[112:127], v[178:181], v[224:227], v[112:127]
	v_mfma_f32_32x32x16_bf16 v[48:63], v[216:219], v[224:227], v[48:63]
	s_waitcnt lgkmcnt(0)
	v_mfma_f32_32x32x16_bf16 v[96:111], v[178:181], v[228:231], v[96:111]
	v_mfma_f32_32x32x16_bf16 v[32:47], v[216:219], v[228:231], v[32:47]
	ds_read_b128 v[224:227], v168 offset:9216
	ds_read_b128 v[228:231], v168 offset:13824
	s_waitcnt vmcnt(7)
	ds_write_b128 v191, v[172:175] offset:9216
	s_waitcnt vmcnt(6)
	ds_write_b128 v191, v[220:223] offset:46080
	ds_read_b128 v[172:175], v169 offset:32
	ds_read_b128 v[220:223], v169 offset:4640
	s_waitcnt lgkmcnt(5)
	v_mfma_f32_32x32x16_bf16 v[80:95], v[178:181], v[224:227], v[80:95]
	v_mfma_f32_32x32x16_bf16 v[16:31], v[216:219], v[224:227], v[16:31]
	ds_read_b128 v[224:227], v168 offset:32
	s_waitcnt lgkmcnt(5)
	v_mfma_f32_32x32x16_bf16 v[64:79], v[178:181], v[228:231], v[64:79]
	v_mfma_f32_32x32x16_bf16 v[0:15], v[216:219], v[228:231], v[0:15]
	ds_read_b128 v[228:231], v168 offset:4640
	s_setprio 0
	global_load_dwordx4 v[178:181], v[136:137], off offset:1408
	global_load_dwordx4 v[216:219], v[140:141], off offset:1408
	s_setprio 1
	s_waitcnt lgkmcnt(1)
	v_mfma_f32_32x32x16_bf16 v[112:127], v[172:175], v[224:227], v[112:127]
	v_mfma_f32_32x32x16_bf16 v[48:63], v[220:223], v[224:227], v[48:63]
	s_waitcnt lgkmcnt(0)
	v_mfma_f32_32x32x16_bf16 v[96:111], v[172:175], v[228:231], v[96:111]
	v_mfma_f32_32x32x16_bf16 v[32:47], v[220:223], v[228:231], v[32:47]
	ds_read_b128 v[224:227], v168 offset:9248
	ds_read_b128 v[228:231], v168 offset:13856
	s_waitcnt vmcnt(7)
	ds_write_b128 v191, v[158:161] offset:18432
	s_waitcnt vmcnt(6)
	ds_write_b128 v191, v[162:165] offset:55296
	ds_read_b128 v[158:161], v169 offset:64
	ds_read_b128 v[162:165], v169 offset:4672
	s_waitcnt lgkmcnt(5)
	v_mfma_f32_32x32x16_bf16 v[80:95], v[172:175], v[224:227], v[80:95]
	v_mfma_f32_32x32x16_bf16 v[16:31], v[220:223], v[224:227], v[16:31]
	ds_read_b128 v[224:227], v168 offset:64
	s_waitcnt lgkmcnt(5)
	v_mfma_f32_32x32x16_bf16 v[64:79], v[172:175], v[228:231], v[64:79]
	v_mfma_f32_32x32x16_bf16 v[0:15], v[220:223], v[228:231], v[0:15]
	ds_read_b128 v[228:231], v168 offset:4672
	s_setprio 0
	global_load_dwordx4 v[172:175], v[144:145], off offset:1408
	global_load_dwordx4 v[220:223], v[148:149], off offset:1408
	s_setprio 1
	s_waitcnt lgkmcnt(1)
	v_mfma_f32_32x32x16_bf16 v[112:127], v[158:161], v[224:227], v[112:127]
	v_mfma_f32_32x32x16_bf16 v[48:63], v[162:165], v[224:227], v[48:63]
	s_waitcnt lgkmcnt(0)
	v_mfma_f32_32x32x16_bf16 v[96:111], v[158:161], v[228:231], v[96:111]
	v_mfma_f32_32x32x16_bf16 v[32:47], v[162:165], v[228:231], v[32:47]
	ds_read_b128 v[224:227], v168 offset:9280
	ds_read_b128 v[228:231], v168 offset:13888
	s_waitcnt vmcnt(7)
	ds_write_b128 v191, v[198:201] offset:27648
	s_waitcnt vmcnt(6)
	ds_write_b128 v191, v[202:205] offset:64512
	ds_read_b128 v[198:201], v169 offset:96
	ds_read_b128 v[202:205], v169 offset:4704
	s_waitcnt lgkmcnt(5)
	v_mfma_f32_32x32x16_bf16 v[80:95], v[158:161], v[224:227], v[80:95]
	v_mfma_f32_32x32x16_bf16 v[16:31], v[162:165], v[224:227], v[16:31]
	ds_read_b128 v[224:227], v168 offset:96
	s_waitcnt lgkmcnt(5)
	v_mfma_f32_32x32x16_bf16 v[64:79], v[158:161], v[228:231], v[64:79]
	v_mfma_f32_32x32x16_bf16 v[0:15], v[162:165], v[228:231], v[0:15]
	ds_read_b128 v[228:231], v168 offset:4704
	s_setprio 0
	global_load_dwordx4 v[158:161], v[152:153], off offset:1408
	global_load_dwordx4 v[162:165], v[156:157], off offset:1408
	s_setprio 1
	s_waitcnt lgkmcnt(1)
	v_mfma_f32_32x32x16_bf16 v[112:127], v[198:201], v[224:227], v[112:127]
	v_mfma_f32_32x32x16_bf16 v[48:63], v[202:205], v[224:227], v[48:63]
	s_waitcnt lgkmcnt(0)
	v_mfma_f32_32x32x16_bf16 v[96:111], v[198:201], v[228:231], v[96:111]
	v_mfma_f32_32x32x16_bf16 v[32:47], v[202:205], v[228:231], v[32:47]
	ds_read_b128 v[224:227], v168 offset:9312
	ds_read_b128 v[228:231], v168 offset:13920
	s_waitcnt lgkmcnt(1)
	v_mfma_f32_32x32x16_bf16 v[80:95], v[198:201], v[224:227], v[80:95]
	v_mfma_f32_32x32x16_bf16 v[16:31], v[202:205], v[224:227], v[16:31]
	s_waitcnt lgkmcnt(0)
	v_mfma_f32_32x32x16_bf16 v[64:79], v[198:201], v[228:231], v[64:79]
	v_mfma_f32_32x32x16_bf16 v[0:15], v[202:205], v[228:231], v[0:15]
	s_setprio 0
	global_load_dwordx4 v[198:201], v[128:129], off offset:1536
	global_load_dwordx4 v[202:205], v[132:133], off offset:1536
	s_barrier
; template <bool trans>
; DI void gemm_core(const GTile& tl, const GTile& nx, bool has_next  , bool chain  , bool pre, u32x4 (&ra)[4], u32x4 (&rb)[4], char* smem, f32x16 (&acc)[2][4]) {
;     ...
;   const int nk = K / 64;
;   if (!pre) { G_LOAD(0); G_STORE(0); G_LOAD(1); }
;   for (int kt = 0; kt < nk; ++kt) {
;     __syncthreads();
;     G_COMPUTE(kt & 1, kt);
	s_waitcnt vmcnt(9)
	ds_write_b128 v195, v[208:211]
	s_waitcnt vmcnt(8)
	ds_write_b128 v196, v[212:215]
	ds_read_b128 v[208:211], v192 offset:36864
	ds_read_b128 v[212:215], v192 offset:41472
	ds_read_b128 v[224:227], v184
	ds_read_b128 v[228:231], v184 offset:4608
	s_setprio 1
	s_waitcnt lgkmcnt(1)
	v_mfma_f32_32x32x16_bf16 v[112:127], v[208:211], v[224:227], v[112:127]
	v_mfma_f32_32x32x16_bf16 v[48:63], v[212:215], v[224:227], v[48:63]
	s_waitcnt lgkmcnt(0)
	v_mfma_f32_32x32x16_bf16 v[96:111], v[208:211], v[228:231], v[96:111]
	v_mfma_f32_32x32x16_bf16 v[32:47], v[212:215], v[228:231], v[32:47]
	ds_read_b128 v[224:227], v184 offset:9216
	ds_read_b128 v[228:231], v184 offset:13824
	s_waitcnt vmcnt(7)
	ds_write_b128 v194, v[178:181]
	s_waitcnt vmcnt(6)
	ds_write_b128 v193, v[216:219]
	ds_read_b128 v[178:181], v192 offset:36896
	ds_read_b128 v[216:219], v192 offset:41504
	s_waitcnt lgkmcnt(5)
	v_mfma_f32_32x32x16_bf16 v[80:95], v[208:211], v[224:227], v[80:95]
	v_mfma_f32_32x32x16_bf16 v[16:31], v[212:215], v[224:227], v[16:31]
	ds_read_b128 v[224:227], v184 offset:32
	s_waitcnt lgkmcnt(5)
	v_mfma_f32_32x32x16_bf16 v[64:79], v[208:211], v[228:231], v[64:79]
	v_mfma_f32_32x32x16_bf16 v[0:15], v[212:215], v[228:231], v[0:15]
	ds_read_b128 v[228:231], v184 offset:4640
	s_setprio 0
	global_load_dwordx4 v[208:211], v[136:137], off offset:1536
	global_load_dwordx4 v[212:215], v[140:141], off offset:1536
	s_setprio 1
	s_waitcnt lgkmcnt(1)
	v_mfma_f32_32x32x16_bf16 v[112:127], v[178:181], v[224:227], v[112:127]
	v_mfma_f32_32x32x16_bf16 v[48:63], v[216:219], v[224:227], v[48:63]
	s_waitcnt lgkmcnt(0)
	v_mfma_f32_32x32x16_bf16 v[96:111], v[178:181], v[228:231], v[96:111]
	v_mfma_f32_32x32x16_bf16 v[32:47], v[216:219], v[228:231], v[32:47]
	ds_read_b128 v[224:227], v184 offset:9248
	ds_read_b128 v[228:231], v184 offset:13856
	s_waitcnt vmcnt(7)
	ds_write_b128 v177, v[172:175]
	s_waitcnt vmcnt(6)
	ds_write_b128 v176, v[220:223]
	ds_read_b128 v[172:175], v192 offset:36928
	ds_read_b128 v[220:223], v192 offset:41536
	s_waitcnt lgkmcnt(5)
	v_mfma_f32_32x32x16_bf16 v[80:95], v[178:181], v[224:227], v[80:95]
	v_mfma_f32_32x32x16_bf16 v[16:31], v[216:219], v[224:227], v[16:31]
	ds_read_b128 v[224:227], v184 offset:64
	s_waitcnt lgkmcnt(5)
	v_mfma_f32_32x32x16_bf16 v[64:79], v[178:181], v[228:231], v[64:79]
	v_mfma_f32_32x32x16_bf16 v[0:15], v[216:219], v[228:231], v[0:15]
	ds_read_b128 v[228:231], v184 offset:4672
	s_setprio 0
	global_load_dwordx4 v[178:181], v[144:145], off offset:1536
	global_load_dwordx4 v[216:219], v[148:149], off offset:1536
	s_setprio 1
	s_waitcnt lgkmcnt(1)
	v_mfma_f32_32x32x16_bf16 v[112:127], v[172:175], v[224:227], v[112:127]
	v_mfma_f32_32x32x16_bf16 v[48:63], v[220:223], v[224:227], v[48:63]
	s_waitcnt lgkmcnt(0)
	v_mfma_f32_32x32x16_bf16 v[96:111], v[172:175], v[228:231], v[96:111]
	v_mfma_f32_32x32x16_bf16 v[32:47], v[220:223], v[228:231], v[32:47]
	ds_read_b128 v[224:227], v184 offset:9280
	ds_read_b128 v[228:231], v184 offset:13888
	s_waitcnt vmcnt(7)
	ds_write_b128 v171, v[158:161]
	s_waitcnt vmcnt(6)
	ds_write_b128 v170, v[162:165]
	ds_read_b128 v[158:161], v192 offset:36960
	ds_read_b128 v[162:165], v192 offset:41568
	s_waitcnt lgkmcnt(5)
	v_mfma_f32_32x32x16_bf16 v[80:95], v[172:175], v[224:227], v[80:95]
	v_mfma_f32_32x32x16_bf16 v[16:31], v[220:223], v[224:227], v[16:31]
	ds_read_b128 v[224:227], v184 offset:96
	s_waitcnt lgkmcnt(5)
	v_mfma_f32_32x32x16_bf16 v[64:79], v[172:175], v[228:231], v[64:79]
	v_mfma_f32_32x32x16_bf16 v[0:15], v[220:223], v[228:231], v[0:15]
	ds_read_b128 v[228:231], v184 offset:4704
	s_setprio 0
	global_load_dwordx4 v[172:175], v[152:153], off offset:1536
	global_load_dwordx4 v[220:223], v[156:157], off offset:1536
	s_setprio 1
	s_waitcnt lgkmcnt(1)
	v_mfma_f32_32x32x16_bf16 v[112:127], v[158:161], v[224:227], v[112:127]
	v_mfma_f32_32x32x16_bf16 v[48:63], v[162:165], v[224:227], v[48:63]
	s_waitcnt lgkmcnt(0)
	v_mfma_f32_32x32x16_bf16 v[96:111], v[158:161], v[228:231], v[96:111]
	v_mfma_f32_32x32x16_bf16 v[32:47], v[162:165], v[228:231], v[32:47]
	ds_read_b128 v[224:227], v184 offset:9312
	ds_read_b128 v[228:231], v184 offset:13920
	s_waitcnt lgkmcnt(1)
	v_mfma_f32_32x32x16_bf16 v[80:95], v[158:161], v[224:227], v[80:95]
	v_mfma_f32_32x32x16_bf16 v[16:31], v[162:165], v[224:227], v[16:31]
	s_waitcnt lgkmcnt(0)
	v_mfma_f32_32x32x16_bf16 v[64:79], v[158:161], v[228:231], v[64:79]
	v_mfma_f32_32x32x16_bf16 v[0:15], v[162:165], v[228:231], v[0:15]
	s_setprio 0
	global_load_dwordx4 v[158:161], v[128:129], off offset:1664
	global_load_dwordx4 v[162:165], v[132:133], off offset:1664
	s_barrier
; template <bool trans>
; DI void gemm_core(const GTile& tl, const GTile& nx, bool has_next  , bool chain  , bool pre, u32x4 (&ra)[4], u32x4 (&rb)[4], char* smem, f32x16 (&acc)[2][4]) {
;     ...
;   const int nk = K / 64;
;   if (!pre) { G_LOAD(0); G_STORE(0); G_LOAD(1); }
;   for (int kt = 0; kt < nk; ++kt) {
;     __syncthreads();
;     G_COMPUTE(kt & 1, kt);
	s_waitcnt vmcnt(9)
	ds_write_b128 v191, v[198:201]
	s_waitcnt vmcnt(8)
	ds_write_b128 v191, v[202:205] offset:36864
	ds_read_b128 v[198:201], v169
	ds_read_b128 v[202:205], v169 offset:4608
	ds_read_b128 v[224:227], v168
	ds_read_b128 v[228:231], v168 offset:4608
	s_setprio 1
	s_waitcnt lgkmcnt(1)
	v_mfma_f32_32x32x16_bf16 v[112:127], v[198:201], v[224:227], v[112:127]
	v_mfma_f32_32x32x16_bf16 v[48:63], v[202:205], v[224:227], v[48:63]
	s_waitcnt lgkmcnt(0)
	v_mfma_f32_32x32x16_bf16 v[96:111], v[198:201], v[228:231], v[96:111]
	v_mfma_f32_32x32x16_bf16 v[32:47], v[202:205], v[228:231], v[32:47]
	ds_read_b128 v[224:227], v168 offset:9216
	ds_read_b128 v[228:231], v168 offset:13824
	s_waitcnt vmcnt(7)
	ds_write_b128 v191, v[208:211] offset:9216
	s_waitcnt vmcnt(6)
	ds_write_b128 v191, v[212:215] offset:46080
	ds_read_b128 v[208:211], v169 offset:32
	ds_read_b128 v[212:215], v169 offset:4640
	s_waitcnt lgkmcnt(5)
	v_mfma_f32_32x32x16_bf16 v[80:95], v[198:201], v[224:227], v[80:95]
	v_mfma_f32_32x32x16_bf16 v[16:31], v[202:205], v[224:227], v[16:31]
	ds_read_b128 v[224:227], v168 offset:32
	s_waitcnt lgkmcnt(5)
	v_mfma_f32_32x32x16_bf16 v[64:79], v[198:201], v[228:231], v[64:79]
	v_mfma_f32_32x32x16_bf16 v[0:15], v[202:205], v[228:231], v[0:15]
	ds_read_b128 v[228:231], v168 offset:4640
	s_setprio 0
	global_load_dwordx4 v[198:201], v[136:137], off offset:1664
	global_load_dwordx4 v[202:205], v[140:141], off offset:1664
	s_setprio 1
	s_waitcnt lgkmcnt(1)
	v_mfma_f32_32x32x16_bf16 v[112:127], v[208:211], v[224:227], v[112:127]
	v_mfma_f32_32x32x16_bf16 v[48:63], v[212:215], v[224:227], v[48:63]
	s_waitcnt lgkmcnt(0)
	v_mfma_f32_32x32x16_bf16 v[96:111], v[208:211], v[228:231], v[96:111]
	v_mfma_f32_32x32x16_bf16 v[32:47], v[212:215], v[228:231], v[32:47]
	ds_read_b128 v[224:227], v168 offset:9248
	ds_read_b128 v[228:231], v168 offset:13856
	s_waitcnt vmcnt(7)
	ds_write_b128 v191, v[178:181] offset:18432
	s_waitcnt vmcnt(6)
	ds_write_b128 v191, v[216:219] offset:55296
	ds_read_b128 v[178:181], v169 offset:64
	ds_read_b128 v[216:219], v169 offset:4672
	s_waitcnt lgkmcnt(5)
	v_mfma_f32_32x32x16_bf16 v[80:95], v[208:211], v[224:227], v[80:95]
	v_mfma_f32_32x32x16_bf16 v[16:31], v[212:215], v[224:227], v[16:31]
	ds_read_b128 v[224:227], v168 offset:64
	s_waitcnt lgkmcnt(5)
	v_mfma_f32_32x32x16_bf16 v[64:79], v[208:211], v[228:231], v[64:79]
	v_mfma_f32_32x32x16_bf16 v[0:15], v[212:215], v[228:231], v[0:15]
	ds_read_b128 v[228:231], v168 offset:4672
	s_setprio 0
	global_load_dwordx4 v[208:211], v[144:145], off offset:1664
	global_load_dwordx4 v[212:215], v[148:149], off offset:1664
	s_setprio 1
	s_waitcnt lgkmcnt(1)
	v_mfma_f32_32x32x16_bf16 v[112:127], v[178:181], v[224:227], v[112:127]
	v_mfma_f32_32x32x16_bf16 v[48:63], v[216:219], v[224:227], v[48:63]
	s_waitcnt lgkmcnt(0)
	v_mfma_f32_32x32x16_bf16 v[96:111], v[178:181], v[228:231], v[96:111]
	v_mfma_f32_32x32x16_bf16 v[32:47], v[216:219], v[228:231], v[32:47]
	ds_read_b128 v[224:227], v168 offset:9280
	ds_read_b128 v[228:231], v168 offset:13888
	s_waitcnt vmcnt(7)
	ds_write_b128 v191, v[172:175] offset:27648
	s_waitcnt vmcnt(6)
	ds_write_b128 v191, v[220:223] offset:64512
	ds_read_b128 v[172:175], v169 offset:96
	ds_read_b128 v[220:223], v169 offset:4704
	s_waitcnt lgkmcnt(5)
	v_mfma_f32_32x32x16_bf16 v[80:95], v[178:181], v[224:227], v[80:95]
	v_mfma_f32_32x32x16_bf16 v[16:31], v[216:219], v[224:227], v[16:31]
	ds_read_b128 v[224:227], v168 offset:96
	s_waitcnt lgkmcnt(5)
	v_mfma_f32_32x32x16_bf16 v[64:79], v[178:181], v[228:231], v[64:79]
	v_mfma_f32_32x32x16_bf16 v[0:15], v[216:219], v[228:231], v[0:15]
	ds_read_b128 v[228:231], v168 offset:4704
	s_setprio 0
	global_load_dwordx4 v[178:181], v[152:153], off offset:1664
	global_load_dwordx4 v[216:219], v[156:157], off offset:1664
	s_setprio 1
	s_waitcnt lgkmcnt(1)
	v_mfma_f32_32x32x16_bf16 v[112:127], v[172:175], v[224:227], v[112:127]
	v_mfma_f32_32x32x16_bf16 v[48:63], v[220:223], v[224:227], v[48:63]
	s_waitcnt lgkmcnt(0)
	v_mfma_f32_32x32x16_bf16 v[96:111], v[172:175], v[228:231], v[96:111]
	v_mfma_f32_32x32x16_bf16 v[32:47], v[220:223], v[228:231], v[32:47]
	ds_read_b128 v[224:227], v168 offset:9312
	ds_read_b128 v[228:231], v168 offset:13920
	s_waitcnt lgkmcnt(1)
	v_mfma_f32_32x32x16_bf16 v[80:95], v[172:175], v[224:227], v[80:95]
	v_mfma_f32_32x32x16_bf16 v[16:31], v[220:223], v[224:227], v[16:31]
	s_waitcnt lgkmcnt(0)
	v_mfma_f32_32x32x16_bf16 v[64:79], v[172:175], v[228:231], v[64:79]
	v_mfma_f32_32x32x16_bf16 v[0:15], v[220:223], v[228:231], v[0:15]
	s_setprio 0
	global_load_dwordx4 v[172:175], v[128:129], off offset:1792
	global_load_dwordx4 v[220:223], v[132:133], off offset:1792
	s_barrier
; template <bool trans>
; DI void gemm_core(const GTile& tl, const GTile& nx, bool has_next  , bool chain  , bool pre, u32x4 (&ra)[4], u32x4 (&rb)[4], char* smem, f32x16 (&acc)[2][4]) {
;     ...
;   const int nk = K / 64;
;   if (!pre) { G_LOAD(0); G_STORE(0); G_LOAD(1); }
;   for (int kt = 0; kt < nk; ++kt) {
;     __syncthreads();
;     G_COMPUTE(kt & 1, kt);
	s_waitcnt vmcnt(9)
	ds_write_b128 v195, v[158:161]
	s_waitcnt vmcnt(8)
	ds_write_b128 v196, v[162:165]
	ds_read_b128 v[158:161], v192 offset:36864
	ds_read_b128 v[162:165], v192 offset:41472
	ds_read_b128 v[224:227], v184
	ds_read_b128 v[228:231], v184 offset:4608
	s_setprio 1
	s_waitcnt lgkmcnt(1)
	v_mfma_f32_32x32x16_bf16 v[112:127], v[158:161], v[224:227], v[112:127]
	v_mfma_f32_32x32x16_bf16 v[48:63], v[162:165], v[224:227], v[48:63]
	s_waitcnt lgkmcnt(0)
	v_mfma_f32_32x32x16_bf16 v[96:111], v[158:161], v[228:231], v[96:111]
	v_mfma_f32_32x32x16_bf16 v[32:47], v[162:165], v[228:231], v[32:47]
	ds_read_b128 v[224:227], v184 offset:9216
	ds_read_b128 v[228:231], v184 offset:13824
	s_waitcnt vmcnt(7)
	ds_write_b128 v194, v[198:201]
	s_waitcnt vmcnt(6)
	ds_write_b128 v193, v[202:205]
	ds_read_b128 v[198:201], v192 offset:36896
	ds_read_b128 v[202:205], v192 offset:41504
	s_waitcnt lgkmcnt(5)
	v_mfma_f32_32x32x16_bf16 v[80:95], v[158:161], v[224:227], v[80:95]
	v_mfma_f32_32x32x16_bf16 v[16:31], v[162:165], v[224:227], v[16:31]
	ds_read_b128 v[224:227], v184 offset:32
	s_waitcnt lgkmcnt(5)
	v_mfma_f32_32x32x16_bf16 v[64:79], v[158:161], v[228:231], v[64:79]
	v_mfma_f32_32x32x16_bf16 v[0:15], v[162:165], v[228:231], v[0:15]
	ds_read_b128 v[228:231], v184 offset:4640
	s_setprio 0
	global_load_dwordx4 v[158:161], v[136:137], off offset:1792
	global_load_dwordx4 v[162:165], v[140:141], off offset:1792
	s_setprio 1
	s_waitcnt lgkmcnt(1)
	v_mfma_f32_32x32x16_bf16 v[112:127], v[198:201], v[224:227], v[112:127]
	v_mfma_f32_32x32x16_bf16 v[48:63], v[202:205], v[224:227], v[48:63]
	s_waitcnt lgkmcnt(0)
	v_mfma_f32_32x32x16_bf16 v[96:111], v[198:201], v[228:231], v[96:111]
	v_mfma_f32_32x32x16_bf16 v[32:47], v[202:205], v[228:231], v[32:47]
	ds_read_b128 v[224:227], v184 offset:9248
	ds_read_b128 v[228:231], v184 offset:13856
	s_waitcnt vmcnt(7)
	ds_write_b128 v177, v[208:211]
	s_waitcnt vmcnt(6)
	ds_write_b128 v176, v[212:215]
	ds_read_b128 v[208:211], v192 offset:36928
	ds_read_b128 v[212:215], v192 offset:41536
	s_waitcnt lgkmcnt(5)
	v_mfma_f32_32x32x16_bf16 v[80:95], v[198:201], v[224:227], v[80:95]
	v_mfma_f32_32x32x16_bf16 v[16:31], v[202:205], v[224:227], v[16:31]
	ds_read_b128 v[224:227], v184 offset:64
	s_waitcnt lgkmcnt(5)
	v_mfma_f32_32x32x16_bf16 v[64:79], v[198:201], v[228:231], v[64:79]
	v_mfma_f32_32x32x16_bf16 v[0:15], v[202:205], v[228:231], v[0:15]
	ds_read_b128 v[228:231], v184 offset:4672
	s_setprio 0
	global_load_dwordx4 v[198:201], v[144:145], off offset:1792
	global_load_dwordx4 v[202:205], v[148:149], off offset:1792
	s_setprio 1
	s_waitcnt lgkmcnt(1)
	v_mfma_f32_32x32x16_bf16 v[112:127], v[208:211], v[224:227], v[112:127]
	v_mfma_f32_32x32x16_bf16 v[48:63], v[212:215], v[224:227], v[48:63]
	s_waitcnt lgkmcnt(0)
	v_mfma_f32_32x32x16_bf16 v[96:111], v[208:211], v[228:231], v[96:111]
	v_mfma_f32_32x32x16_bf16 v[32:47], v[212:215], v[228:231], v[32:47]
	ds_read_b128 v[224:227], v184 offset:9280
	ds_read_b128 v[228:231], v184 offset:13888
	s_waitcnt vmcnt(7)
	ds_write_b128 v171, v[178:181]
	s_waitcnt vmcnt(6)
	ds_write_b128 v170, v[216:219]
	ds_read_b128 v[178:181], v192 offset:36960
	ds_read_b128 v[216:219], v192 offset:41568
	s_waitcnt lgkmcnt(5)
	v_mfma_f32_32x32x16_bf16 v[80:95], v[208:211], v[224:227], v[80:95]
	v_mfma_f32_32x32x16_bf16 v[16:31], v[212:215], v[224:227], v[16:31]
	ds_read_b128 v[224:227], v184 offset:96
	s_waitcnt lgkmcnt(5)
	v_mfma_f32_32x32x16_bf16 v[64:79], v[208:211], v[228:231], v[64:79]
	v_mfma_f32_32x32x16_bf16 v[0:15], v[212:215], v[228:231], v[0:15]
	ds_read_b128 v[228:231], v184 offset:4704
	s_setprio 0
	global_load_dwordx4 v[208:211], v[152:153], off offset:1792
	global_load_dwordx4 v[212:215], v[156:157], off offset:1792
	s_setprio 1
	s_waitcnt lgkmcnt(1)
	v_mfma_f32_32x32x16_bf16 v[112:127], v[178:181], v[224:227], v[112:127]
	v_mfma_f32_32x32x16_bf16 v[48:63], v[216:219], v[224:227], v[48:63]
	s_waitcnt lgkmcnt(0)
	v_mfma_f32_32x32x16_bf16 v[96:111], v[178:181], v[228:231], v[96:111]
	v_mfma_f32_32x32x16_bf16 v[32:47], v[216:219], v[228:231], v[32:47]
	ds_read_b128 v[224:227], v184 offset:9312
	ds_read_b128 v[228:231], v184 offset:13920
	s_waitcnt lgkmcnt(1)
	v_mfma_f32_32x32x16_bf16 v[80:95], v[178:181], v[224:227], v[80:95]
	v_mfma_f32_32x32x16_bf16 v[16:31], v[216:219], v[224:227], v[16:31]
	s_waitcnt lgkmcnt(0)
	v_mfma_f32_32x32x16_bf16 v[64:79], v[178:181], v[228:231], v[64:79]
	v_mfma_f32_32x32x16_bf16 v[0:15], v[216:219], v[228:231], v[0:15]
	s_setprio 0
	global_load_dwordx4 v[178:181], v[128:129], off offset:1920
	global_load_dwordx4 v[216:219], v[132:133], off offset:1920
	s_barrier
; template <bool trans>
; DI void gemm_core(const GTile& tl, const GTile& nx, bool has_next  , bool chain  , bool pre, u32x4 (&ra)[4], u32x4 (&rb)[4], char* smem, f32x16 (&acc)[2][4]) {
;     ...
;   const int nk = K / 64;
;   if (!pre) { G_LOAD(0); G_STORE(0); G_LOAD(1); }
;   for (int kt = 0; kt < nk; ++kt) {
;     __syncthreads();
;     G_COMPUTE(kt & 1, kt);
	s_waitcnt vmcnt(9)
	ds_write_b128 v191, v[172:175]
	s_waitcnt vmcnt(8)
	ds_write_b128 v191, v[220:223] offset:36864
	ds_read_b128 v[172:175], v169
	ds_read_b128 v[220:223], v169 offset:4608
	ds_read_b128 v[224:227], v168
	ds_read_b128 v[228:231], v168 offset:4608
	s_setprio 1
	s_waitcnt lgkmcnt(1)
	v_mfma_f32_32x32x16_bf16 v[112:127], v[172:175], v[224:227], v[112:127]
	v_mfma_f32_32x32x16_bf16 v[48:63], v[220:223], v[224:227], v[48:63]
	s_waitcnt lgkmcnt(0)
	v_mfma_f32_32x32x16_bf16 v[96:111], v[172:175], v[228:231], v[96:111]
	v_mfma_f32_32x32x16_bf16 v[32:47], v[220:223], v[228:231], v[32:47]
	ds_read_b128 v[224:227], v168 offset:9216
	ds_read_b128 v[228:231], v168 offset:13824
	s_waitcnt vmcnt(7)
	ds_write_b128 v191, v[158:161] offset:9216
	s_waitcnt vmcnt(6)
	ds_write_b128 v191, v[162:165] offset:46080
	ds_read_b128 v[158:161], v169 offset:32
	ds_read_b128 v[162:165], v169 offset:4640
	s_waitcnt lgkmcnt(5)
	v_mfma_f32_32x32x16_bf16 v[80:95], v[172:175], v[224:227], v[80:95]
	v_mfma_f32_32x32x16_bf16 v[16:31], v[220:223], v[224:227], v[16:31]
	ds_read_b128 v[224:227], v168 offset:32
	s_waitcnt lgkmcnt(5)
	v_mfma_f32_32x32x16_bf16 v[64:79], v[172:175], v[228:231], v[64:79]
	v_mfma_f32_32x32x16_bf16 v[0:15], v[220:223], v[228:231], v[0:15]
	ds_read_b128 v[228:231], v168 offset:4640
	s_setprio 0
	global_load_dwordx4 v[172:175], v[136:137], off offset:1920
	global_load_dwordx4 v[220:223], v[140:141], off offset:1920
	s_setprio 1
	s_waitcnt lgkmcnt(1)
	v_mfma_f32_32x32x16_bf16 v[112:127], v[158:161], v[224:227], v[112:127]
	v_mfma_f32_32x32x16_bf16 v[48:63], v[162:165], v[224:227], v[48:63]
	s_waitcnt lgkmcnt(0)
	v_mfma_f32_32x32x16_bf16 v[96:111], v[158:161], v[228:231], v[96:111]
	v_mfma_f32_32x32x16_bf16 v[32:47], v[162:165], v[228:231], v[32:47]
	ds_read_b128 v[224:227], v168 offset:9248
	ds_read_b128 v[228:231], v168 offset:13856
	s_waitcnt vmcnt(7)
	ds_write_b128 v191, v[198:201] offset:18432
	s_waitcnt vmcnt(6)
	ds_write_b128 v191, v[202:205] offset:55296
	ds_read_b128 v[198:201], v169 offset:64
	ds_read_b128 v[202:205], v169 offset:4672
	s_waitcnt lgkmcnt(5)
	v_mfma_f32_32x32x16_bf16 v[80:95], v[158:161], v[224:227], v[80:95]
	v_mfma_f32_32x32x16_bf16 v[16:31], v[162:165], v[224:227], v[16:31]
	ds_read_b128 v[224:227], v168 offset:64
	s_waitcnt lgkmcnt(5)
	v_mfma_f32_32x32x16_bf16 v[64:79], v[158:161], v[228:231], v[64:79]
	v_mfma_f32_32x32x16_bf16 v[0:15], v[162:165], v[228:231], v[0:15]
	ds_read_b128 v[228:231], v168 offset:4672
	s_setprio 0
	global_load_dwordx4 v[158:161], v[144:145], off offset:1920
	global_load_dwordx4 v[162:165], v[148:149], off offset:1920
	s_setprio 1
	s_waitcnt lgkmcnt(1)
	v_mfma_f32_32x32x16_bf16 v[112:127], v[198:201], v[224:227], v[112:127]
	v_mfma_f32_32x32x16_bf16 v[48:63], v[202:205], v[224:227], v[48:63]
	s_waitcnt lgkmcnt(0)
	v_mfma_f32_32x32x16_bf16 v[96:111], v[198:201], v[228:231], v[96:111]
	v_mfma_f32_32x32x16_bf16 v[32:47], v[202:205], v[228:231], v[32:47]
	ds_read_b128 v[224:227], v168 offset:9280
	ds_read_b128 v[228:231], v168 offset:13888
	s_waitcnt vmcnt(7)
	ds_write_b128 v191, v[208:211] offset:27648
	s_waitcnt vmcnt(6)
	ds_write_b128 v191, v[212:215] offset:64512
	ds_read_b128 v[208:211], v169 offset:96
	ds_read_b128 v[212:215], v169 offset:4704
	s_waitcnt lgkmcnt(5)
	v_mfma_f32_32x32x16_bf16 v[80:95], v[198:201], v[224:227], v[80:95]
	v_mfma_f32_32x32x16_bf16 v[16:31], v[202:205], v[224:227], v[16:31]
	ds_read_b128 v[224:227], v168 offset:96
	s_waitcnt lgkmcnt(5)
	v_mfma_f32_32x32x16_bf16 v[64:79], v[198:201], v[228:231], v[64:79]
	v_mfma_f32_32x32x16_bf16 v[0:15], v[202:205], v[228:231], v[0:15]
	ds_read_b128 v[228:231], v168 offset:4704
	s_setprio 0
	global_load_dwordx4 v[198:201], v[152:153], off offset:1920
	global_load_dwordx4 v[202:205], v[156:157], off offset:1920
	s_setprio 1
	s_waitcnt lgkmcnt(1)
	v_mfma_f32_32x32x16_bf16 v[112:127], v[208:211], v[224:227], v[112:127]
	v_mfma_f32_32x32x16_bf16 v[48:63], v[212:215], v[224:227], v[48:63]
	s_waitcnt lgkmcnt(0)
	v_mfma_f32_32x32x16_bf16 v[96:111], v[208:211], v[228:231], v[96:111]
	v_mfma_f32_32x32x16_bf16 v[32:47], v[212:215], v[228:231], v[32:47]
	ds_read_b128 v[224:227], v168 offset:9312
	ds_read_b128 v[228:231], v168 offset:13920
	s_waitcnt lgkmcnt(1)
	v_mfma_f32_32x32x16_bf16 v[80:95], v[208:211], v[224:227], v[80:95]
	v_mfma_f32_32x32x16_bf16 v[16:31], v[212:215], v[224:227], v[16:31]
	s_waitcnt lgkmcnt(0)
	v_mfma_f32_32x32x16_bf16 v[64:79], v[208:211], v[228:231], v[64:79]
	v_mfma_f32_32x32x16_bf16 v[0:15], v[212:215], v[228:231], v[0:15]
	s_setprio 0
	global_load_dwordx4 v[208:211], v[128:129], off offset:2048
	global_load_dwordx4 v[212:215], v[132:133], off offset:2048
	s_barrier
; template <bool trans>
; DI void gemm_core(const GTile& tl, const GTile& nx, bool has_next  , bool chain  , bool pre, u32x4 (&ra)[4], u32x4 (&rb)[4], char* smem, f32x16 (&acc)[2][4]) {
;     ...
;   const int nk = K / 64;
;   if (!pre) { G_LOAD(0); G_STORE(0); G_LOAD(1); }
;   for (int kt = 0; kt < nk; ++kt) {
;     __syncthreads();
;     G_COMPUTE(kt & 1, kt);
	s_waitcnt vmcnt(9)
	ds_write_b128 v195, v[178:181]
	s_waitcnt vmcnt(8)
	ds_write_b128 v196, v[216:219]
	ds_read_b128 v[178:181], v192 offset:36864
	ds_read_b128 v[216:219], v192 offset:41472
	ds_read_b128 v[224:227], v184
	ds_read_b128 v[228:231], v184 offset:4608
	s_setprio 1
	s_waitcnt lgkmcnt(1)
	v_mfma_f32_32x32x16_bf16 v[112:127], v[178:181], v[224:227], v[112:127]
	v_mfma_f32_32x32x16_bf16 v[48:63], v[216:219], v[224:227], v[48:63]
	s_waitcnt lgkmcnt(0)
	v_mfma_f32_32x32x16_bf16 v[96:111], v[178:181], v[228:231], v[96:111]
	v_mfma_f32_32x32x16_bf16 v[32:47], v[216:219], v[228:231], v[32:47]
	ds_read_b128 v[224:227], v184 offset:9216
	ds_read_b128 v[228:231], v184 offset:13824
	s_waitcnt vmcnt(7)
	ds_write_b128 v194, v[172:175]
	s_waitcnt vmcnt(6)
	ds_write_b128 v193, v[220:223]
	ds_read_b128 v[172:175], v192 offset:36896
	ds_read_b128 v[220:223], v192 offset:41504
	s_waitcnt lgkmcnt(5)
	v_mfma_f32_32x32x16_bf16 v[80:95], v[178:181], v[224:227], v[80:95]
	v_mfma_f32_32x32x16_bf16 v[16:31], v[216:219], v[224:227], v[16:31]
	ds_read_b128 v[224:227], v184 offset:32
	s_waitcnt lgkmcnt(5)
	v_mfma_f32_32x32x16_bf16 v[64:79], v[178:181], v[228:231], v[64:79]
	v_mfma_f32_32x32x16_bf16 v[0:15], v[216:219], v[228:231], v[0:15]
	ds_read_b128 v[228:231], v184 offset:4640
	s_setprio 0
	global_load_dwordx4 v[178:181], v[136:137], off offset:2048
	global_load_dwordx4 v[216:219], v[140:141], off offset:2048
	s_setprio 1
	s_waitcnt lgkmcnt(1)
	v_mfma_f32_32x32x16_bf16 v[112:127], v[172:175], v[224:227], v[112:127]
	v_mfma_f32_32x32x16_bf16 v[48:63], v[220:223], v[224:227], v[48:63]
	s_waitcnt lgkmcnt(0)
	v_mfma_f32_32x32x16_bf16 v[96:111], v[172:175], v[228:231], v[96:111]
	v_mfma_f32_32x32x16_bf16 v[32:47], v[220:223], v[228:231], v[32:47]
	ds_read_b128 v[224:227], v184 offset:9248
	ds_read_b128 v[228:231], v184 offset:13856
	s_waitcnt vmcnt(7)
	ds_write_b128 v177, v[158:161]
	s_waitcnt vmcnt(6)
	ds_write_b128 v176, v[162:165]
	ds_read_b128 v[158:161], v192 offset:36928
	ds_read_b128 v[162:165], v192 offset:41536
	s_waitcnt lgkmcnt(5)
	v_mfma_f32_32x32x16_bf16 v[80:95], v[172:175], v[224:227], v[80:95]
	v_mfma_f32_32x32x16_bf16 v[16:31], v[220:223], v[224:227], v[16:31]
	ds_read_b128 v[224:227], v184 offset:64
	s_waitcnt lgkmcnt(5)
	v_mfma_f32_32x32x16_bf16 v[64:79], v[172:175], v[228:231], v[64:79]
	v_mfma_f32_32x32x16_bf16 v[0:15], v[220:223], v[228:231], v[0:15]
	ds_read_b128 v[228:231], v184 offset:4672
	s_setprio 0
	global_load_dwordx4 v[172:175], v[144:145], off offset:2048
	global_load_dwordx4 v[220:223], v[148:149], off offset:2048
	s_setprio 1
	s_waitcnt lgkmcnt(1)
	v_mfma_f32_32x32x16_bf16 v[112:127], v[158:161], v[224:227], v[112:127]
	v_mfma_f32_32x32x16_bf16 v[48:63], v[162:165], v[224:227], v[48:63]
	s_waitcnt lgkmcnt(0)
	v_mfma_f32_32x32x16_bf16 v[96:111], v[158:161], v[228:231], v[96:111]
	v_mfma_f32_32x32x16_bf16 v[32:47], v[162:165], v[228:231], v[32:47]
	ds_read_b128 v[224:227], v184 offset:9280
	ds_read_b128 v[228:231], v184 offset:13888
	s_waitcnt vmcnt(7)
	ds_write_b128 v171, v[198:201]
	s_waitcnt vmcnt(6)
	ds_write_b128 v170, v[202:205]
	ds_read_b128 v[198:201], v192 offset:36960
	ds_read_b128 v[202:205], v192 offset:41568
	s_waitcnt lgkmcnt(5)
	v_mfma_f32_32x32x16_bf16 v[80:95], v[158:161], v[224:227], v[80:95]
	v_mfma_f32_32x32x16_bf16 v[16:31], v[162:165], v[224:227], v[16:31]
	ds_read_b128 v[224:227], v184 offset:96
	s_waitcnt lgkmcnt(5)
	v_mfma_f32_32x32x16_bf16 v[64:79], v[158:161], v[228:231], v[64:79]
	v_mfma_f32_32x32x16_bf16 v[0:15], v[162:165], v[228:231], v[0:15]
	ds_read_b128 v[228:231], v184 offset:4704
	s_setprio 0
	global_load_dwordx4 v[158:161], v[152:153], off offset:2048
	global_load_dwordx4 v[162:165], v[156:157], off offset:2048
	s_setprio 1
	s_waitcnt lgkmcnt(1)
	v_mfma_f32_32x32x16_bf16 v[112:127], v[198:201], v[224:227], v[112:127]
	v_mfma_f32_32x32x16_bf16 v[48:63], v[202:205], v[224:227], v[48:63]
	s_waitcnt lgkmcnt(0)
	v_mfma_f32_32x32x16_bf16 v[96:111], v[198:201], v[228:231], v[96:111]
	v_mfma_f32_32x32x16_bf16 v[32:47], v[202:205], v[228:231], v[32:47]
	ds_read_b128 v[224:227], v184 offset:9312
	ds_read_b128 v[228:231], v184 offset:13920
	s_waitcnt lgkmcnt(1)
	v_mfma_f32_32x32x16_bf16 v[80:95], v[198:201], v[224:227], v[80:95]
	v_mfma_f32_32x32x16_bf16 v[16:31], v[202:205], v[224:227], v[16:31]
	s_waitcnt lgkmcnt(0)
	v_mfma_f32_32x32x16_bf16 v[64:79], v[198:201], v[228:231], v[64:79]
	v_mfma_f32_32x32x16_bf16 v[0:15], v[202:205], v[228:231], v[0:15]
	s_setprio 0
	global_load_dwordx4 v[198:201], v[128:129], off offset:2176
	global_load_dwordx4 v[202:205], v[132:133], off offset:2176
	s_barrier
; template <bool trans>
; DI void gemm_core(const GTile& tl, const GTile& nx, bool has_next  , bool chain  , bool pre, u32x4 (&ra)[4], u32x4 (&rb)[4], char* smem, f32x16 (&acc)[2][4]) {
;     ...
;   const int nk = K / 64;
;   if (!pre) { G_LOAD(0); G_STORE(0); G_LOAD(1); }
;   for (int kt = 0; kt < nk; ++kt) {
;     __syncthreads();
;     G_COMPUTE(kt & 1, kt);
	s_waitcnt vmcnt(9)
	ds_write_b128 v191, v[208:211]
	s_waitcnt vmcnt(8)
	ds_write_b128 v191, v[212:215] offset:36864
	ds_read_b128 v[208:211], v169
	ds_read_b128 v[212:215], v169 offset:4608
	ds_read_b128 v[224:227], v168
	ds_read_b128 v[228:231], v168 offset:4608
	s_setprio 1
	s_waitcnt lgkmcnt(1)
	v_mfma_f32_32x32x16_bf16 v[112:127], v[208:211], v[224:227], v[112:127]
	v_mfma_f32_32x32x16_bf16 v[48:63], v[212:215], v[224:227], v[48:63]
	s_waitcnt lgkmcnt(0)
	v_mfma_f32_32x32x16_bf16 v[96:111], v[208:211], v[228:231], v[96:111]
	v_mfma_f32_32x32x16_bf16 v[32:47], v[212:215], v[228:231], v[32:47]
	ds_read_b128 v[224:227], v168 offset:9216
	ds_read_b128 v[228:231], v168 offset:13824
	s_waitcnt vmcnt(7)
	ds_write_b128 v191, v[178:181] offset:9216
	s_waitcnt vmcnt(6)
	ds_write_b128 v191, v[216:219] offset:46080
	ds_read_b128 v[178:181], v169 offset:32
	ds_read_b128 v[216:219], v169 offset:4640
	s_waitcnt lgkmcnt(5)
	v_mfma_f32_32x32x16_bf16 v[80:95], v[208:211], v[224:227], v[80:95]
	v_mfma_f32_32x32x16_bf16 v[16:31], v[212:215], v[224:227], v[16:31]
	ds_read_b128 v[224:227], v168 offset:32
	s_waitcnt lgkmcnt(5)
	v_mfma_f32_32x32x16_bf16 v[64:79], v[208:211], v[228:231], v[64:79]
	v_mfma_f32_32x32x16_bf16 v[0:15], v[212:215], v[228:231], v[0:15]
	ds_read_b128 v[228:231], v168 offset:4640
	s_setprio 0
	global_load_dwordx4 v[208:211], v[136:137], off offset:2176
	global_load_dwordx4 v[212:215], v[140:141], off offset:2176
	s_setprio 1
	s_waitcnt lgkmcnt(1)
	v_mfma_f32_32x32x16_bf16 v[112:127], v[178:181], v[224:227], v[112:127]
	v_mfma_f32_32x32x16_bf16 v[48:63], v[216:219], v[224:227], v[48:63]
	s_waitcnt lgkmcnt(0)
	v_mfma_f32_32x32x16_bf16 v[96:111], v[178:181], v[228:231], v[96:111]
	v_mfma_f32_32x32x16_bf16 v[32:47], v[216:219], v[228:231], v[32:47]
	ds_read_b128 v[224:227], v168 offset:9248
	ds_read_b128 v[228:231], v168 offset:13856
	s_waitcnt vmcnt(7)
	ds_write_b128 v191, v[172:175] offset:18432
	s_waitcnt vmcnt(6)
	ds_write_b128 v191, v[220:223] offset:55296
	ds_read_b128 v[172:175], v169 offset:64
	ds_read_b128 v[220:223], v169 offset:4672
	s_waitcnt lgkmcnt(5)
	v_mfma_f32_32x32x16_bf16 v[80:95], v[178:181], v[224:227], v[80:95]
	v_mfma_f32_32x32x16_bf16 v[16:31], v[216:219], v[224:227], v[16:31]
	ds_read_b128 v[224:227], v168 offset:64
	s_waitcnt lgkmcnt(5)
	v_mfma_f32_32x32x16_bf16 v[64:79], v[178:181], v[228:231], v[64:79]
	v_mfma_f32_32x32x16_bf16 v[0:15], v[216:219], v[228:231], v[0:15]
	ds_read_b128 v[228:231], v168 offset:4672
	s_setprio 0
	global_load_dwordx4 v[178:181], v[144:145], off offset:2176
	global_load_dwordx4 v[216:219], v[148:149], off offset:2176
	s_setprio 1
	s_waitcnt lgkmcnt(1)
	v_mfma_f32_32x32x16_bf16 v[112:127], v[172:175], v[224:227], v[112:127]
	v_mfma_f32_32x32x16_bf16 v[48:63], v[220:223], v[224:227], v[48:63]
	s_waitcnt lgkmcnt(0)
	v_mfma_f32_32x32x16_bf16 v[96:111], v[172:175], v[228:231], v[96:111]
	v_mfma_f32_32x32x16_bf16 v[32:47], v[220:223], v[228:231], v[32:47]
	ds_read_b128 v[224:227], v168 offset:9280
	ds_read_b128 v[228:231], v168 offset:13888
	s_waitcnt vmcnt(7)
	ds_write_b128 v191, v[158:161] offset:27648
	s_waitcnt vmcnt(6)
	ds_write_b128 v191, v[162:165] offset:64512
	ds_read_b128 v[158:161], v169 offset:96
	ds_read_b128 v[162:165], v169 offset:4704
	s_waitcnt lgkmcnt(5)
	v_mfma_f32_32x32x16_bf16 v[80:95], v[172:175], v[224:227], v[80:95]
	v_mfma_f32_32x32x16_bf16 v[16:31], v[220:223], v[224:227], v[16:31]
	ds_read_b128 v[224:227], v168 offset:96
	s_waitcnt lgkmcnt(5)
	v_mfma_f32_32x32x16_bf16 v[64:79], v[172:175], v[228:231], v[64:79]
	v_mfma_f32_32x32x16_bf16 v[0:15], v[220:223], v[228:231], v[0:15]
	ds_read_b128 v[228:231], v168 offset:4704
	s_setprio 0
	global_load_dwordx4 v[172:175], v[152:153], off offset:2176
	global_load_dwordx4 v[220:223], v[156:157], off offset:2176
	s_setprio 1
	s_waitcnt lgkmcnt(1)
	v_mfma_f32_32x32x16_bf16 v[112:127], v[158:161], v[224:227], v[112:127]
	v_mfma_f32_32x32x16_bf16 v[48:63], v[162:165], v[224:227], v[48:63]
	s_waitcnt lgkmcnt(0)
	v_mfma_f32_32x32x16_bf16 v[96:111], v[158:161], v[228:231], v[96:111]
	v_mfma_f32_32x32x16_bf16 v[32:47], v[162:165], v[228:231], v[32:47]
	ds_read_b128 v[224:227], v168 offset:9312
	ds_read_b128 v[228:231], v168 offset:13920
	s_waitcnt lgkmcnt(1)
	v_mfma_f32_32x32x16_bf16 v[80:95], v[158:161], v[224:227], v[80:95]
	v_mfma_f32_32x32x16_bf16 v[16:31], v[162:165], v[224:227], v[16:31]
	s_waitcnt lgkmcnt(0)
	v_mfma_f32_32x32x16_bf16 v[64:79], v[158:161], v[228:231], v[64:79]
	v_mfma_f32_32x32x16_bf16 v[0:15], v[162:165], v[228:231], v[0:15]
	s_setprio 0
	global_load_dwordx4 v[158:161], v[128:129], off offset:2304
	global_load_dwordx4 v[162:165], v[132:133], off offset:2304
	s_barrier
; template <bool trans>
; DI void gemm_core(const GTile& tl, const GTile& nx, bool has_next  , bool chain  , bool pre, u32x4 (&ra)[4], u32x4 (&rb)[4], char* smem, f32x16 (&acc)[2][4]) {
;     ...
;   const int nk = K / 64;
;   if (!pre) { G_LOAD(0); G_STORE(0); G_LOAD(1); }
;   for (int kt = 0; kt < nk; ++kt) {
;     __syncthreads();
;     G_COMPUTE(kt & 1, kt);
	s_waitcnt vmcnt(9)
	ds_write_b128 v195, v[198:201]
	s_waitcnt vmcnt(8)
	ds_write_b128 v196, v[202:205]
	ds_read_b128 v[198:201], v192 offset:36864
	ds_read_b128 v[202:205], v192 offset:41472
	ds_read_b128 v[224:227], v184
	ds_read_b128 v[228:231], v184 offset:4608
	s_setprio 1
	s_waitcnt lgkmcnt(1)
	v_mfma_f32_32x32x16_bf16 v[112:127], v[198:201], v[224:227], v[112:127]
	v_mfma_f32_32x32x16_bf16 v[48:63], v[202:205], v[224:227], v[48:63]
	s_waitcnt lgkmcnt(0)
	v_mfma_f32_32x32x16_bf16 v[96:111], v[198:201], v[228:231], v[96:111]
	v_mfma_f32_32x32x16_bf16 v[32:47], v[202:205], v[228:231], v[32:47]
	ds_read_b128 v[224:227], v184 offset:9216
	ds_read_b128 v[228:231], v184 offset:13824
	s_waitcnt vmcnt(7)
	ds_write_b128 v194, v[208:211]
	s_waitcnt vmcnt(6)
	ds_write_b128 v193, v[212:215]
	ds_read_b128 v[208:211], v192 offset:36896
	ds_read_b128 v[212:215], v192 offset:41504
	s_waitcnt lgkmcnt(5)
	v_mfma_f32_32x32x16_bf16 v[80:95], v[198:201], v[224:227], v[80:95]
	v_mfma_f32_32x32x16_bf16 v[16:31], v[202:205], v[224:227], v[16:31]
	ds_read_b128 v[224:227], v184 offset:32
	s_waitcnt lgkmcnt(5)
	v_mfma_f32_32x32x16_bf16 v[64:79], v[198:201], v[228:231], v[64:79]
	v_mfma_f32_32x32x16_bf16 v[0:15], v[202:205], v[228:231], v[0:15]
	ds_read_b128 v[228:231], v184 offset:4640
	s_setprio 0
	global_load_dwordx4 v[198:201], v[136:137], off offset:2304
	global_load_dwordx4 v[202:205], v[140:141], off offset:2304
	s_setprio 1
	s_waitcnt lgkmcnt(1)
	v_mfma_f32_32x32x16_bf16 v[112:127], v[208:211], v[224:227], v[112:127]
	v_mfma_f32_32x32x16_bf16 v[48:63], v[212:215], v[224:227], v[48:63]
	s_waitcnt lgkmcnt(0)
	v_mfma_f32_32x32x16_bf16 v[96:111], v[208:211], v[228:231], v[96:111]
	v_mfma_f32_32x32x16_bf16 v[32:47], v[212:215], v[228:231], v[32:47]
	ds_read_b128 v[224:227], v184 offset:9248
	ds_read_b128 v[228:231], v184 offset:13856
	s_waitcnt vmcnt(7)
	ds_write_b128 v177, v[178:181]
	s_waitcnt vmcnt(6)
	ds_write_b128 v176, v[216:219]
	ds_read_b128 v[178:181], v192 offset:36928
	ds_read_b128 v[216:219], v192 offset:41536
	s_waitcnt lgkmcnt(5)
	v_mfma_f32_32x32x16_bf16 v[80:95], v[208:211], v[224:227], v[80:95]
	v_mfma_f32_32x32x16_bf16 v[16:31], v[212:215], v[224:227], v[16:31]
	ds_read_b128 v[224:227], v184 offset:64
	s_waitcnt lgkmcnt(5)
	v_mfma_f32_32x32x16_bf16 v[64:79], v[208:211], v[228:231], v[64:79]
	v_mfma_f32_32x32x16_bf16 v[0:15], v[212:215], v[228:231], v[0:15]
	ds_read_b128 v[228:231], v184 offset:4672
	s_setprio 0
	global_load_dwordx4 v[208:211], v[144:145], off offset:2304
	global_load_dwordx4 v[212:215], v[148:149], off offset:2304
	s_setprio 1
	s_waitcnt lgkmcnt(1)
	v_mfma_f32_32x32x16_bf16 v[112:127], v[178:181], v[224:227], v[112:127]
	v_mfma_f32_32x32x16_bf16 v[48:63], v[216:219], v[224:227], v[48:63]
	s_waitcnt lgkmcnt(0)
	v_mfma_f32_32x32x16_bf16 v[96:111], v[178:181], v[228:231], v[96:111]
	v_mfma_f32_32x32x16_bf16 v[32:47], v[216:219], v[228:231], v[32:47]
	ds_read_b128 v[224:227], v184 offset:9280
	ds_read_b128 v[228:231], v184 offset:13888
	s_waitcnt vmcnt(7)
	ds_write_b128 v171, v[172:175]
	s_waitcnt vmcnt(6)
	ds_write_b128 v170, v[220:223]
	ds_read_b128 v[172:175], v192 offset:36960
	ds_read_b128 v[220:223], v192 offset:41568
	s_waitcnt lgkmcnt(5)
	v_mfma_f32_32x32x16_bf16 v[80:95], v[178:181], v[224:227], v[80:95]
	v_mfma_f32_32x32x16_bf16 v[16:31], v[216:219], v[224:227], v[16:31]
	ds_read_b128 v[224:227], v184 offset:96
	s_waitcnt lgkmcnt(5)
	v_mfma_f32_32x32x16_bf16 v[64:79], v[178:181], v[228:231], v[64:79]
	v_mfma_f32_32x32x16_bf16 v[0:15], v[216:219], v[228:231], v[0:15]
	ds_read_b128 v[228:231], v184 offset:4704
	s_setprio 0
	global_load_dwordx4 v[178:181], v[152:153], off offset:2304
	global_load_dwordx4 v[216:219], v[156:157], off offset:2304
	s_setprio 1
	s_waitcnt lgkmcnt(1)
	v_mfma_f32_32x32x16_bf16 v[112:127], v[172:175], v[224:227], v[112:127]
	v_mfma_f32_32x32x16_bf16 v[48:63], v[220:223], v[224:227], v[48:63]
	s_waitcnt lgkmcnt(0)
	v_mfma_f32_32x32x16_bf16 v[96:111], v[172:175], v[228:231], v[96:111]
	v_mfma_f32_32x32x16_bf16 v[32:47], v[220:223], v[228:231], v[32:47]
	ds_read_b128 v[224:227], v184 offset:9312
	ds_read_b128 v[228:231], v184 offset:13920
	s_waitcnt lgkmcnt(1)
	v_mfma_f32_32x32x16_bf16 v[80:95], v[172:175], v[224:227], v[80:95]
	v_mfma_f32_32x32x16_bf16 v[16:31], v[220:223], v[224:227], v[16:31]
	s_waitcnt lgkmcnt(0)
	v_mfma_f32_32x32x16_bf16 v[64:79], v[172:175], v[228:231], v[64:79]
	v_mfma_f32_32x32x16_bf16 v[0:15], v[220:223], v[228:231], v[0:15]
	s_setprio 0
	global_load_dwordx4 v[172:175], v[128:129], off offset:2432
	global_load_dwordx4 v[220:223], v[132:133], off offset:2432
	s_barrier
; template <bool trans>
; DI void gemm_core(const GTile& tl, const GTile& nx, bool has_next  , bool chain  , bool pre, u32x4 (&ra)[4], u32x4 (&rb)[4], char* smem, f32x16 (&acc)[2][4]) {
;     ...
;   const int nk = K / 64;
;   if (!pre) { G_LOAD(0); G_STORE(0); G_LOAD(1); }
;   for (int kt = 0; kt < nk; ++kt) {
;     __syncthreads();
;     G_COMPUTE(kt & 1, kt);
	s_waitcnt vmcnt(9)
	ds_write_b128 v191, v[158:161]
	s_waitcnt vmcnt(8)
	ds_write_b128 v191, v[162:165] offset:36864
	ds_read_b128 v[158:161], v169
	ds_read_b128 v[162:165], v169 offset:4608
	ds_read_b128 v[224:227], v168
	ds_read_b128 v[228:231], v168 offset:4608
	s_setprio 1
	s_waitcnt lgkmcnt(1)
	v_mfma_f32_32x32x16_bf16 v[112:127], v[158:161], v[224:227], v[112:127]
	v_mfma_f32_32x32x16_bf16 v[48:63], v[162:165], v[224:227], v[48:63]
	s_waitcnt lgkmcnt(0)
	v_mfma_f32_32x32x16_bf16 v[96:111], v[158:161], v[228:231], v[96:111]
	v_mfma_f32_32x32x16_bf16 v[32:47], v[162:165], v[228:231], v[32:47]
	ds_read_b128 v[224:227], v168 offset:9216
	ds_read_b128 v[228:231], v168 offset:13824
	s_waitcnt vmcnt(7)
	ds_write_b128 v191, v[198:201] offset:9216
	s_waitcnt vmcnt(6)
	ds_write_b128 v191, v[202:205] offset:46080
	ds_read_b128 v[198:201], v169 offset:32
	ds_read_b128 v[202:205], v169 offset:4640
	s_waitcnt lgkmcnt(5)
	v_mfma_f32_32x32x16_bf16 v[80:95], v[158:161], v[224:227], v[80:95]
	v_mfma_f32_32x32x16_bf16 v[16:31], v[162:165], v[224:227], v[16:31]
	ds_read_b128 v[224:227], v168 offset:32
	s_waitcnt lgkmcnt(5)
	v_mfma_f32_32x32x16_bf16 v[64:79], v[158:161], v[228:231], v[64:79]
	v_mfma_f32_32x32x16_bf16 v[0:15], v[162:165], v[228:231], v[0:15]
	ds_read_b128 v[228:231], v168 offset:4640
	s_setprio 0
	global_load_dwordx4 v[158:161], v[136:137], off offset:2432
	global_load_dwordx4 v[162:165], v[140:141], off offset:2432
	s_setprio 1
	s_waitcnt lgkmcnt(1)
	v_mfma_f32_32x32x16_bf16 v[112:127], v[198:201], v[224:227], v[112:127]
	v_mfma_f32_32x32x16_bf16 v[48:63], v[202:205], v[224:227], v[48:63]
	s_waitcnt lgkmcnt(0)
	v_mfma_f32_32x32x16_bf16 v[96:111], v[198:201], v[228:231], v[96:111]
	v_mfma_f32_32x32x16_bf16 v[32:47], v[202:205], v[228:231], v[32:47]
	ds_read_b128 v[224:227], v168 offset:9248
	ds_read_b128 v[228:231], v168 offset:13856
	s_waitcnt vmcnt(7)
	ds_write_b128 v191, v[208:211] offset:18432
	s_waitcnt vmcnt(6)
	ds_write_b128 v191, v[212:215] offset:55296
	ds_read_b128 v[208:211], v169 offset:64
	ds_read_b128 v[212:215], v169 offset:4672
	s_waitcnt lgkmcnt(5)
	v_mfma_f32_32x32x16_bf16 v[80:95], v[198:201], v[224:227], v[80:95]
	v_mfma_f32_32x32x16_bf16 v[16:31], v[202:205], v[224:227], v[16:31]
	ds_read_b128 v[224:227], v168 offset:64
	s_waitcnt lgkmcnt(5)
	v_mfma_f32_32x32x16_bf16 v[64:79], v[198:201], v[228:231], v[64:79]
	v_mfma_f32_32x32x16_bf16 v[0:15], v[202:205], v[228:231], v[0:15]
	ds_read_b128 v[228:231], v168 offset:4672
	s_setprio 0
	global_load_dwordx4 v[198:201], v[144:145], off offset:2432
	global_load_dwordx4 v[202:205], v[148:149], off offset:2432
	s_setprio 1
	s_waitcnt lgkmcnt(1)
	v_mfma_f32_32x32x16_bf16 v[112:127], v[208:211], v[224:227], v[112:127]
	v_mfma_f32_32x32x16_bf16 v[48:63], v[212:215], v[224:227], v[48:63]
	s_waitcnt lgkmcnt(0)
	v_mfma_f32_32x32x16_bf16 v[96:111], v[208:211], v[228:231], v[96:111]
	v_mfma_f32_32x32x16_bf16 v[32:47], v[212:215], v[228:231], v[32:47]
	ds_read_b128 v[224:227], v168 offset:9280
	ds_read_b128 v[228:231], v168 offset:13888
	s_waitcnt vmcnt(7)
	ds_write_b128 v191, v[178:181] offset:27648
	s_waitcnt vmcnt(6)
	ds_write_b128 v191, v[216:219] offset:64512
	ds_read_b128 v[178:181], v169 offset:96
	ds_read_b128 v[216:219], v169 offset:4704
	s_waitcnt lgkmcnt(5)
	v_mfma_f32_32x32x16_bf16 v[80:95], v[208:211], v[224:227], v[80:95]
	v_mfma_f32_32x32x16_bf16 v[16:31], v[212:215], v[224:227], v[16:31]
	ds_read_b128 v[224:227], v168 offset:96
	s_waitcnt lgkmcnt(5)
	v_mfma_f32_32x32x16_bf16 v[64:79], v[208:211], v[228:231], v[64:79]
	v_mfma_f32_32x32x16_bf16 v[0:15], v[212:215], v[228:231], v[0:15]
	ds_read_b128 v[228:231], v168 offset:4704
	s_setprio 0
	global_load_dwordx4 v[208:211], v[152:153], off offset:2432
	global_load_dwordx4 v[212:215], v[156:157], off offset:2432
	s_setprio 1
	s_waitcnt lgkmcnt(1)
	v_mfma_f32_32x32x16_bf16 v[112:127], v[178:181], v[224:227], v[112:127]
	v_mfma_f32_32x32x16_bf16 v[48:63], v[216:219], v[224:227], v[48:63]
	s_waitcnt lgkmcnt(0)
	v_mfma_f32_32x32x16_bf16 v[96:111], v[178:181], v[228:231], v[96:111]
	v_mfma_f32_32x32x16_bf16 v[32:47], v[216:219], v[228:231], v[32:47]
	ds_read_b128 v[224:227], v168 offset:9312
	ds_read_b128 v[228:231], v168 offset:13920
	s_waitcnt lgkmcnt(1)
	v_mfma_f32_32x32x16_bf16 v[80:95], v[178:181], v[224:227], v[80:95]
	v_mfma_f32_32x32x16_bf16 v[16:31], v[216:219], v[224:227], v[16:31]
	s_waitcnt lgkmcnt(0)
	v_mfma_f32_32x32x16_bf16 v[64:79], v[178:181], v[228:231], v[64:79]
	v_mfma_f32_32x32x16_bf16 v[0:15], v[216:219], v[228:231], v[0:15]
	s_setprio 0
	global_load_dwordx4 v[178:181], v[128:129], off offset:2560
	global_load_dwordx4 v[216:219], v[132:133], off offset:2560
	s_barrier
; template <bool trans>
; DI void gemm_core(const GTile& tl, const GTile& nx, bool has_next  , bool chain  , bool pre, u32x4 (&ra)[4], u32x4 (&rb)[4], char* smem, f32x16 (&acc)[2][4]) {
;     ...
;   const int nk = K / 64;
;   if (!pre) { G_LOAD(0); G_STORE(0); G_LOAD(1); }
;   for (int kt = 0; kt < nk; ++kt) {
;     __syncthreads();
;     G_COMPUTE(kt & 1, kt);
	s_waitcnt vmcnt(9)
	ds_write_b128 v195, v[172:175]
	s_waitcnt vmcnt(8)
	ds_write_b128 v196, v[220:223]
	ds_read_b128 v[172:175], v192 offset:36864
	ds_read_b128 v[220:223], v192 offset:41472
	ds_read_b128 v[224:227], v184
	ds_read_b128 v[228:231], v184 offset:4608
	s_setprio 1
	s_waitcnt lgkmcnt(1)
	v_mfma_f32_32x32x16_bf16 v[112:127], v[172:175], v[224:227], v[112:127]
	v_mfma_f32_32x32x16_bf16 v[48:63], v[220:223], v[224:227], v[48:63]
	s_waitcnt lgkmcnt(0)
	v_mfma_f32_32x32x16_bf16 v[96:111], v[172:175], v[228:231], v[96:111]
	v_mfma_f32_32x32x16_bf16 v[32:47], v[220:223], v[228:231], v[32:47]
	ds_read_b128 v[224:227], v184 offset:9216
	ds_read_b128 v[228:231], v184 offset:13824
	s_waitcnt vmcnt(7)
	ds_write_b128 v194, v[158:161]
	s_waitcnt vmcnt(6)
	ds_write_b128 v193, v[162:165]
	ds_read_b128 v[158:161], v192 offset:36896
	ds_read_b128 v[162:165], v192 offset:41504
	s_waitcnt lgkmcnt(5)
	v_mfma_f32_32x32x16_bf16 v[80:95], v[172:175], v[224:227], v[80:95]
	v_mfma_f32_32x32x16_bf16 v[16:31], v[220:223], v[224:227], v[16:31]
	ds_read_b128 v[224:227], v184 offset:32
	s_waitcnt lgkmcnt(5)
	v_mfma_f32_32x32x16_bf16 v[64:79], v[172:175], v[228:231], v[64:79]
	v_mfma_f32_32x32x16_bf16 v[0:15], v[220:223], v[228:231], v[0:15]
	ds_read_b128 v[228:231], v184 offset:4640
	s_setprio 0
	global_load_dwordx4 v[172:175], v[136:137], off offset:2560
	global_load_dwordx4 v[220:223], v[140:141], off offset:2560
	s_setprio 1
	s_waitcnt lgkmcnt(1)
	v_mfma_f32_32x32x16_bf16 v[112:127], v[158:161], v[224:227], v[112:127]
	v_mfma_f32_32x32x16_bf16 v[48:63], v[162:165], v[224:227], v[48:63]
	s_waitcnt lgkmcnt(0)
	v_mfma_f32_32x32x16_bf16 v[96:111], v[158:161], v[228:231], v[96:111]
	v_mfma_f32_32x32x16_bf16 v[32:47], v[162:165], v[228:231], v[32:47]
	ds_read_b128 v[224:227], v184 offset:9248
	ds_read_b128 v[228:231], v184 offset:13856
	s_waitcnt vmcnt(7)
	ds_write_b128 v177, v[198:201]
	s_waitcnt vmcnt(6)
	ds_write_b128 v176, v[202:205]
	ds_read_b128 v[198:201], v192 offset:36928
	ds_read_b128 v[202:205], v192 offset:41536
	s_waitcnt lgkmcnt(5)
	v_mfma_f32_32x32x16_bf16 v[80:95], v[158:161], v[224:227], v[80:95]
	v_mfma_f32_32x32x16_bf16 v[16:31], v[162:165], v[224:227], v[16:31]
	ds_read_b128 v[224:227], v184 offset:64
	s_waitcnt lgkmcnt(5)
	v_mfma_f32_32x32x16_bf16 v[64:79], v[158:161], v[228:231], v[64:79]
	v_mfma_f32_32x32x16_bf16 v[0:15], v[162:165], v[228:231], v[0:15]
	ds_read_b128 v[228:231], v184 offset:4672
	s_setprio 0
	global_load_dwordx4 v[158:161], v[144:145], off offset:2560
	global_load_dwordx4 v[162:165], v[148:149], off offset:2560
	s_setprio 1
	s_waitcnt lgkmcnt(1)
	v_mfma_f32_32x32x16_bf16 v[112:127], v[198:201], v[224:227], v[112:127]
	v_mfma_f32_32x32x16_bf16 v[48:63], v[202:205], v[224:227], v[48:63]
	s_waitcnt lgkmcnt(0)
	v_mfma_f32_32x32x16_bf16 v[96:111], v[198:201], v[228:231], v[96:111]
	v_mfma_f32_32x32x16_bf16 v[32:47], v[202:205], v[228:231], v[32:47]
	ds_read_b128 v[224:227], v184 offset:9280
	ds_read_b128 v[228:231], v184 offset:13888
	s_waitcnt vmcnt(7)
	ds_write_b128 v171, v[208:211]
	s_waitcnt vmcnt(6)
	ds_write_b128 v170, v[212:215]
	ds_read_b128 v[208:211], v192 offset:36960
	ds_read_b128 v[212:215], v192 offset:41568
	s_waitcnt lgkmcnt(5)
	v_mfma_f32_32x32x16_bf16 v[80:95], v[198:201], v[224:227], v[80:95]
	v_mfma_f32_32x32x16_bf16 v[16:31], v[202:205], v[224:227], v[16:31]
	ds_read_b128 v[224:227], v184 offset:96
	s_waitcnt lgkmcnt(5)
	v_mfma_f32_32x32x16_bf16 v[64:79], v[198:201], v[228:231], v[64:79]
	v_mfma_f32_32x32x16_bf16 v[0:15], v[202:205], v[228:231], v[0:15]
	ds_read_b128 v[228:231], v184 offset:4704
	s_setprio 0
	global_load_dwordx4 v[198:201], v[152:153], off offset:2560
	global_load_dwordx4 v[202:205], v[156:157], off offset:2560
	s_setprio 1
	s_waitcnt lgkmcnt(1)
	v_mfma_f32_32x32x16_bf16 v[112:127], v[208:211], v[224:227], v[112:127]
	v_mfma_f32_32x32x16_bf16 v[48:63], v[212:215], v[224:227], v[48:63]
	s_waitcnt lgkmcnt(0)
	v_mfma_f32_32x32x16_bf16 v[96:111], v[208:211], v[228:231], v[96:111]
	v_mfma_f32_32x32x16_bf16 v[32:47], v[212:215], v[228:231], v[32:47]
	ds_read_b128 v[224:227], v184 offset:9312
	ds_read_b128 v[228:231], v184 offset:13920
	s_waitcnt lgkmcnt(1)
	v_mfma_f32_32x32x16_bf16 v[80:95], v[208:211], v[224:227], v[80:95]
	v_mfma_f32_32x32x16_bf16 v[16:31], v[212:215], v[224:227], v[16:31]
	s_waitcnt lgkmcnt(0)
	v_mfma_f32_32x32x16_bf16 v[64:79], v[208:211], v[228:231], v[64:79]
	v_mfma_f32_32x32x16_bf16 v[0:15], v[212:215], v[228:231], v[0:15]
	s_setprio 0
	global_load_dwordx4 v[208:211], v[128:129], off offset:2688
	global_load_dwordx4 v[212:215], v[132:133], off offset:2688
	s_barrier
; template <bool trans>
; DI void gemm_core(const GTile& tl, const GTile& nx, bool has_next  , bool chain  , bool pre, u32x4 (&ra)[4], u32x4 (&rb)[4], char* smem, f32x16 (&acc)[2][4]) {
;     ...
;   const int nk = K / 64;
;   if (!pre) { G_LOAD(0); G_STORE(0); G_LOAD(1); }
;   for (int kt = 0; kt < nk; ++kt) {
;     __syncthreads();
;     G_COMPUTE(kt & 1, kt);
	s_waitcnt vmcnt(9)
	ds_write_b128 v191, v[178:181]
	s_waitcnt vmcnt(8)
	ds_write_b128 v191, v[216:219] offset:36864
	ds_read_b128 v[178:181], v169
	ds_read_b128 v[216:219], v169 offset:4608
	ds_read_b128 v[224:227], v168
	ds_read_b128 v[228:231], v168 offset:4608
	s_setprio 1
	s_waitcnt lgkmcnt(1)
	v_mfma_f32_32x32x16_bf16 v[112:127], v[178:181], v[224:227], v[112:127]
	v_mfma_f32_32x32x16_bf16 v[48:63], v[216:219], v[224:227], v[48:63]
	s_waitcnt lgkmcnt(0)
	v_mfma_f32_32x32x16_bf16 v[96:111], v[178:181], v[228:231], v[96:111]
	v_mfma_f32_32x32x16_bf16 v[32:47], v[216:219], v[228:231], v[32:47]
	ds_read_b128 v[224:227], v168 offset:9216
	ds_read_b128 v[228:231], v168 offset:13824
	s_waitcnt vmcnt(7)
	ds_write_b128 v191, v[172:175] offset:9216
	s_waitcnt vmcnt(6)
	ds_write_b128 v191, v[220:223] offset:46080
	ds_read_b128 v[172:175], v169 offset:32
	ds_read_b128 v[220:223], v169 offset:4640
	s_waitcnt lgkmcnt(5)
	v_mfma_f32_32x32x16_bf16 v[80:95], v[178:181], v[224:227], v[80:95]
	v_mfma_f32_32x32x16_bf16 v[16:31], v[216:219], v[224:227], v[16:31]
	ds_read_b128 v[224:227], v168 offset:32
	s_waitcnt lgkmcnt(5)
	v_mfma_f32_32x32x16_bf16 v[64:79], v[178:181], v[228:231], v[64:79]
	v_mfma_f32_32x32x16_bf16 v[0:15], v[216:219], v[228:231], v[0:15]
	ds_read_b128 v[228:231], v168 offset:4640
	s_setprio 0
	global_load_dwordx4 v[178:181], v[136:137], off offset:2688
	global_load_dwordx4 v[216:219], v[140:141], off offset:2688
	s_setprio 1
	s_waitcnt lgkmcnt(1)
	v_mfma_f32_32x32x16_bf16 v[112:127], v[172:175], v[224:227], v[112:127]
	v_mfma_f32_32x32x16_bf16 v[48:63], v[220:223], v[224:227], v[48:63]
	s_waitcnt lgkmcnt(0)
	v_mfma_f32_32x32x16_bf16 v[96:111], v[172:175], v[228:231], v[96:111]
	v_mfma_f32_32x32x16_bf16 v[32:47], v[220:223], v[228:231], v[32:47]
	ds_read_b128 v[224:227], v168 offset:9248
	ds_read_b128 v[228:231], v168 offset:13856
	s_waitcnt vmcnt(7)
	ds_write_b128 v191, v[158:161] offset:18432
	s_waitcnt vmcnt(6)
	ds_write_b128 v191, v[162:165] offset:55296
	ds_read_b128 v[158:161], v169 offset:64
	ds_read_b128 v[162:165], v169 offset:4672
	s_waitcnt lgkmcnt(5)
	v_mfma_f32_32x32x16_bf16 v[80:95], v[172:175], v[224:227], v[80:95]
	v_mfma_f32_32x32x16_bf16 v[16:31], v[220:223], v[224:227], v[16:31]
	ds_read_b128 v[224:227], v168 offset:64
	s_waitcnt lgkmcnt(5)
	v_mfma_f32_32x32x16_bf16 v[64:79], v[172:175], v[228:231], v[64:79]
	v_mfma_f32_32x32x16_bf16 v[0:15], v[220:223], v[228:231], v[0:15]
	ds_read_b128 v[228:231], v168 offset:4672
	s_setprio 0
	global_load_dwordx4 v[172:175], v[144:145], off offset:2688
	global_load_dwordx4 v[220:223], v[148:149], off offset:2688
	s_setprio 1
	s_waitcnt lgkmcnt(1)
	v_mfma_f32_32x32x16_bf16 v[112:127], v[158:161], v[224:227], v[112:127]
	v_mfma_f32_32x32x16_bf16 v[48:63], v[162:165], v[224:227], v[48:63]
	s_waitcnt lgkmcnt(0)
	v_mfma_f32_32x32x16_bf16 v[96:111], v[158:161], v[228:231], v[96:111]
	v_mfma_f32_32x32x16_bf16 v[32:47], v[162:165], v[228:231], v[32:47]
	ds_read_b128 v[224:227], v168 offset:9280
	ds_read_b128 v[228:231], v168 offset:13888
	s_waitcnt vmcnt(7)
	ds_write_b128 v191, v[198:201] offset:27648
	s_waitcnt vmcnt(6)
	ds_write_b128 v191, v[202:205] offset:64512
	ds_read_b128 v[198:201], v169 offset:96
	ds_read_b128 v[202:205], v169 offset:4704
	s_waitcnt lgkmcnt(5)
	v_mfma_f32_32x32x16_bf16 v[80:95], v[158:161], v[224:227], v[80:95]
	v_mfma_f32_32x32x16_bf16 v[16:31], v[162:165], v[224:227], v[16:31]
	ds_read_b128 v[224:227], v168 offset:96
	s_waitcnt lgkmcnt(5)
	v_mfma_f32_32x32x16_bf16 v[64:79], v[158:161], v[228:231], v[64:79]
	v_mfma_f32_32x32x16_bf16 v[0:15], v[162:165], v[228:231], v[0:15]
	ds_read_b128 v[228:231], v168 offset:4704
	s_setprio 0
	global_load_dwordx4 v[158:161], v[152:153], off offset:2688
	global_load_dwordx4 v[162:165], v[156:157], off offset:2688
	s_setprio 1
	s_waitcnt lgkmcnt(1)
	v_mfma_f32_32x32x16_bf16 v[112:127], v[198:201], v[224:227], v[112:127]
	v_mfma_f32_32x32x16_bf16 v[48:63], v[202:205], v[224:227], v[48:63]
	s_waitcnt lgkmcnt(0)
	v_mfma_f32_32x32x16_bf16 v[96:111], v[198:201], v[228:231], v[96:111]
	v_mfma_f32_32x32x16_bf16 v[32:47], v[202:205], v[228:231], v[32:47]
	ds_read_b128 v[224:227], v168 offset:9312
	ds_read_b128 v[228:231], v168 offset:13920
	s_waitcnt lgkmcnt(1)
	v_mfma_f32_32x32x16_bf16 v[80:95], v[198:201], v[224:227], v[80:95]
	v_mfma_f32_32x32x16_bf16 v[16:31], v[202:205], v[224:227], v[16:31]
	s_waitcnt lgkmcnt(0)
	v_mfma_f32_32x32x16_bf16 v[64:79], v[198:201], v[228:231], v[64:79]
	v_mfma_f32_32x32x16_bf16 v[0:15], v[202:205], v[228:231], v[0:15]
	s_setprio 0
	global_load_dwordx4 v[198:201], v[128:129], off offset:2816
	global_load_dwordx4 v[202:205], v[132:133], off offset:2816
	s_barrier
; template <bool trans>
; DI void gemm_core(const GTile& tl, const GTile& nx, bool has_next  , bool chain  , bool pre, u32x4 (&ra)[4], u32x4 (&rb)[4], char* smem, f32x16 (&acc)[2][4]) {
;     ...
;   const int nk = K / 64;
;   if (!pre) { G_LOAD(0); G_STORE(0); G_LOAD(1); }
;   for (int kt = 0; kt < nk; ++kt) {
;     __syncthreads();
;     G_COMPUTE(kt & 1, kt);
	s_waitcnt vmcnt(9)
	ds_write_b128 v195, v[208:211]
	s_waitcnt vmcnt(8)
	ds_write_b128 v196, v[212:215]
	ds_read_b128 v[208:211], v192 offset:36864
	ds_read_b128 v[212:215], v192 offset:41472
	ds_read_b128 v[224:227], v184
	ds_read_b128 v[228:231], v184 offset:4608
	s_setprio 1
	s_waitcnt lgkmcnt(1)
	v_mfma_f32_32x32x16_bf16 v[112:127], v[208:211], v[224:227], v[112:127]
	v_mfma_f32_32x32x16_bf16 v[48:63], v[212:215], v[224:227], v[48:63]
	s_waitcnt lgkmcnt(0)
	v_mfma_f32_32x32x16_bf16 v[96:111], v[208:211], v[228:231], v[96:111]
	v_mfma_f32_32x32x16_bf16 v[32:47], v[212:215], v[228:231], v[32:47]
	ds_read_b128 v[224:227], v184 offset:9216
	ds_read_b128 v[228:231], v184 offset:13824
	s_waitcnt vmcnt(7)
	ds_write_b128 v194, v[178:181]
	s_waitcnt vmcnt(6)
	ds_write_b128 v193, v[216:219]
	ds_read_b128 v[178:181], v192 offset:36896
	ds_read_b128 v[216:219], v192 offset:41504
	s_waitcnt lgkmcnt(5)
	v_mfma_f32_32x32x16_bf16 v[80:95], v[208:211], v[224:227], v[80:95]
	v_mfma_f32_32x32x16_bf16 v[16:31], v[212:215], v[224:227], v[16:31]
	ds_read_b128 v[224:227], v184 offset:32
	s_waitcnt lgkmcnt(5)
	v_mfma_f32_32x32x16_bf16 v[64:79], v[208:211], v[228:231], v[64:79]
	v_mfma_f32_32x32x16_bf16 v[0:15], v[212:215], v[228:231], v[0:15]
	ds_read_b128 v[228:231], v184 offset:4640
	s_setprio 0
	global_load_dwordx4 v[208:211], v[136:137], off offset:2816
	global_load_dwordx4 v[212:215], v[140:141], off offset:2816
	s_setprio 1
	s_waitcnt lgkmcnt(1)
	v_mfma_f32_32x32x16_bf16 v[112:127], v[178:181], v[224:227], v[112:127]
	v_mfma_f32_32x32x16_bf16 v[48:63], v[216:219], v[224:227], v[48:63]
	s_waitcnt lgkmcnt(0)
	v_mfma_f32_32x32x16_bf16 v[96:111], v[178:181], v[228:231], v[96:111]
	v_mfma_f32_32x32x16_bf16 v[32:47], v[216:219], v[228:231], v[32:47]
	ds_read_b128 v[224:227], v184 offset:9248
	ds_read_b128 v[228:231], v184 offset:13856
	s_waitcnt vmcnt(7)
	ds_write_b128 v177, v[172:175]
	s_waitcnt vmcnt(6)
	ds_write_b128 v176, v[220:223]
	ds_read_b128 v[172:175], v192 offset:36928
	ds_read_b128 v[220:223], v192 offset:41536
	s_waitcnt lgkmcnt(5)
	v_mfma_f32_32x32x16_bf16 v[80:95], v[178:181], v[224:227], v[80:95]
	v_mfma_f32_32x32x16_bf16 v[16:31], v[216:219], v[224:227], v[16:31]
	ds_read_b128 v[224:227], v184 offset:64
	s_waitcnt lgkmcnt(5)
	v_mfma_f32_32x32x16_bf16 v[64:79], v[178:181], v[228:231], v[64:79]
	v_mfma_f32_32x32x16_bf16 v[0:15], v[216:219], v[228:231], v[0:15]
	ds_read_b128 v[228:231], v184 offset:4672
	s_setprio 0
	global_load_dwordx4 v[178:181], v[144:145], off offset:2816
	global_load_dwordx4 v[216:219], v[148:149], off offset:2816
	s_setprio 1
	s_waitcnt lgkmcnt(1)
	v_mfma_f32_32x32x16_bf16 v[112:127], v[172:175], v[224:227], v[112:127]
	v_mfma_f32_32x32x16_bf16 v[48:63], v[220:223], v[224:227], v[48:63]
	s_waitcnt lgkmcnt(0)
	v_mfma_f32_32x32x16_bf16 v[96:111], v[172:175], v[228:231], v[96:111]
	v_mfma_f32_32x32x16_bf16 v[32:47], v[220:223], v[228:231], v[32:47]
	ds_read_b128 v[224:227], v184 offset:9280
	ds_read_b128 v[228:231], v184 offset:13888
	s_waitcnt vmcnt(7)
	ds_write_b128 v171, v[158:161]
	s_waitcnt vmcnt(6)
	ds_write_b128 v170, v[162:165]
	ds_read_b128 v[158:161], v192 offset:36960
	ds_read_b128 v[162:165], v192 offset:41568
	s_waitcnt lgkmcnt(5)
	v_mfma_f32_32x32x16_bf16 v[80:95], v[172:175], v[224:227], v[80:95]
	v_mfma_f32_32x32x16_bf16 v[16:31], v[220:223], v[224:227], v[16:31]
	ds_read_b128 v[224:227], v184 offset:96
	s_waitcnt lgkmcnt(5)
	v_mfma_f32_32x32x16_bf16 v[64:79], v[172:175], v[228:231], v[64:79]
	v_mfma_f32_32x32x16_bf16 v[0:15], v[220:223], v[228:231], v[0:15]
	ds_read_b128 v[228:231], v184 offset:4704
	s_setprio 0
	global_load_dwordx4 v[172:175], v[152:153], off offset:2816
	global_load_dwordx4 v[220:223], v[156:157], off offset:2816
	s_setprio 1
	s_waitcnt lgkmcnt(1)
	v_mfma_f32_32x32x16_bf16 v[112:127], v[158:161], v[224:227], v[112:127]
	v_mfma_f32_32x32x16_bf16 v[48:63], v[162:165], v[224:227], v[48:63]
	s_waitcnt lgkmcnt(0)
	v_mfma_f32_32x32x16_bf16 v[96:111], v[158:161], v[228:231], v[96:111]
	v_mfma_f32_32x32x16_bf16 v[32:47], v[162:165], v[228:231], v[32:47]
	ds_read_b128 v[224:227], v184 offset:9312
	ds_read_b128 v[228:231], v184 offset:13920
	s_waitcnt lgkmcnt(1)
	v_mfma_f32_32x32x16_bf16 v[80:95], v[158:161], v[224:227], v[80:95]
	v_mfma_f32_32x32x16_bf16 v[16:31], v[162:165], v[224:227], v[16:31]
	s_waitcnt lgkmcnt(0)
	v_mfma_f32_32x32x16_bf16 v[64:79], v[158:161], v[228:231], v[64:79]
	v_mfma_f32_32x32x16_bf16 v[0:15], v[162:165], v[228:231], v[0:15]
	s_setprio 0
	global_load_dwordx4 v[158:161], v[128:129], off offset:2944
	global_load_dwordx4 v[162:165], v[132:133], off offset:2944
	s_barrier
; template <bool trans>
; DI void gemm_core(const GTile& tl, const GTile& nx, bool has_next  , bool chain  , bool pre, u32x4 (&ra)[4], u32x4 (&rb)[4], char* smem, f32x16 (&acc)[2][4]) {
;     ...
;   const int nk = K / 64;
;   if (!pre) { G_LOAD(0); G_STORE(0); G_LOAD(1); }
;   for (int kt = 0; kt < nk; ++kt) {
;     __syncthreads();
;     G_COMPUTE(kt & 1, kt);
	s_waitcnt vmcnt(9)
	ds_write_b128 v191, v[198:201]
	s_waitcnt vmcnt(8)
	ds_write_b128 v191, v[202:205] offset:36864
	ds_read_b128 v[198:201], v169
	ds_read_b128 v[202:205], v169 offset:4608
	ds_read_b128 v[224:227], v168
	ds_read_b128 v[228:231], v168 offset:4608
	s_setprio 1
	s_waitcnt lgkmcnt(1)
	v_mfma_f32_32x32x16_bf16 v[112:127], v[198:201], v[224:227], v[112:127]
	v_mfma_f32_32x32x16_bf16 v[48:63], v[202:205], v[224:227], v[48:63]
	s_waitcnt lgkmcnt(0)
	v_mfma_f32_32x32x16_bf16 v[96:111], v[198:201], v[228:231], v[96:111]
	v_mfma_f32_32x32x16_bf16 v[32:47], v[202:205], v[228:231], v[32:47]
	ds_read_b128 v[224:227], v168 offset:9216
	ds_read_b128 v[228:231], v168 offset:13824
	s_waitcnt vmcnt(7)
	ds_write_b128 v191, v[208:211] offset:9216
	s_waitcnt vmcnt(6)
	ds_write_b128 v191, v[212:215] offset:46080
	ds_read_b128 v[208:211], v169 offset:32
	ds_read_b128 v[212:215], v169 offset:4640
	s_waitcnt lgkmcnt(5)
	v_mfma_f32_32x32x16_bf16 v[80:95], v[198:201], v[224:227], v[80:95]
	v_mfma_f32_32x32x16_bf16 v[16:31], v[202:205], v[224:227], v[16:31]
	ds_read_b128 v[224:227], v168 offset:32
	s_waitcnt lgkmcnt(5)
	v_mfma_f32_32x32x16_bf16 v[64:79], v[198:201], v[228:231], v[64:79]
	v_mfma_f32_32x32x16_bf16 v[0:15], v[202:205], v[228:231], v[0:15]
	ds_read_b128 v[228:231], v168 offset:4640
	s_setprio 0
	global_load_dwordx4 v[198:201], v[136:137], off offset:2944
	global_load_dwordx4 v[202:205], v[140:141], off offset:2944
	s_setprio 1
	s_waitcnt lgkmcnt(1)
	v_mfma_f32_32x32x16_bf16 v[112:127], v[208:211], v[224:227], v[112:127]
	v_mfma_f32_32x32x16_bf16 v[48:63], v[212:215], v[224:227], v[48:63]
	s_waitcnt lgkmcnt(0)
	v_mfma_f32_32x32x16_bf16 v[96:111], v[208:211], v[228:231], v[96:111]
	v_mfma_f32_32x32x16_bf16 v[32:47], v[212:215], v[228:231], v[32:47]
	ds_read_b128 v[224:227], v168 offset:9248
	ds_read_b128 v[228:231], v168 offset:13856
	s_waitcnt vmcnt(7)
	ds_write_b128 v191, v[178:181] offset:18432
	s_waitcnt vmcnt(6)
	ds_write_b128 v191, v[216:219] offset:55296
	ds_read_b128 v[178:181], v169 offset:64
	ds_read_b128 v[216:219], v169 offset:4672
	s_waitcnt lgkmcnt(5)
	v_mfma_f32_32x32x16_bf16 v[80:95], v[208:211], v[224:227], v[80:95]
	v_mfma_f32_32x32x16_bf16 v[16:31], v[212:215], v[224:227], v[16:31]
	ds_read_b128 v[224:227], v168 offset:64
	s_waitcnt lgkmcnt(5)
	v_mfma_f32_32x32x16_bf16 v[64:79], v[208:211], v[228:231], v[64:79]
	v_mfma_f32_32x32x16_bf16 v[0:15], v[212:215], v[228:231], v[0:15]
	ds_read_b128 v[228:231], v168 offset:4672
	s_setprio 0
	global_load_dwordx4 v[208:211], v[144:145], off offset:2944
	global_load_dwordx4 v[212:215], v[148:149], off offset:2944
	s_setprio 1
	s_waitcnt lgkmcnt(1)
	v_mfma_f32_32x32x16_bf16 v[112:127], v[178:181], v[224:227], v[112:127]
	v_mfma_f32_32x32x16_bf16 v[48:63], v[216:219], v[224:227], v[48:63]
	s_waitcnt lgkmcnt(0)
	v_mfma_f32_32x32x16_bf16 v[96:111], v[178:181], v[228:231], v[96:111]
	v_mfma_f32_32x32x16_bf16 v[32:47], v[216:219], v[228:231], v[32:47]
	ds_read_b128 v[224:227], v168 offset:9280
	ds_read_b128 v[228:231], v168 offset:13888
	s_waitcnt vmcnt(7)
	ds_write_b128 v191, v[172:175] offset:27648
	s_waitcnt vmcnt(6)
	ds_write_b128 v191, v[220:223] offset:64512
	ds_read_b128 v[172:175], v169 offset:96
	ds_read_b128 v[220:223], v169 offset:4704
	s_waitcnt lgkmcnt(5)
	v_mfma_f32_32x32x16_bf16 v[80:95], v[178:181], v[224:227], v[80:95]
	v_mfma_f32_32x32x16_bf16 v[16:31], v[216:219], v[224:227], v[16:31]
	ds_read_b128 v[224:227], v168 offset:96
	s_waitcnt lgkmcnt(5)
	v_mfma_f32_32x32x16_bf16 v[64:79], v[178:181], v[228:231], v[64:79]
	v_mfma_f32_32x32x16_bf16 v[0:15], v[216:219], v[228:231], v[0:15]
	ds_read_b128 v[228:231], v168 offset:4704
	s_setprio 0
	global_load_dwordx4 v[178:181], v[152:153], off offset:2944
	global_load_dwordx4 v[216:219], v[156:157], off offset:2944
	s_setprio 1
	s_waitcnt lgkmcnt(1)
	v_mfma_f32_32x32x16_bf16 v[112:127], v[172:175], v[224:227], v[112:127]
	v_mfma_f32_32x32x16_bf16 v[48:63], v[220:223], v[224:227], v[48:63]
	s_waitcnt lgkmcnt(0)
	v_mfma_f32_32x32x16_bf16 v[96:111], v[172:175], v[228:231], v[96:111]
	v_mfma_f32_32x32x16_bf16 v[32:47], v[220:223], v[228:231], v[32:47]
	ds_read_b128 v[224:227], v168 offset:9312
	ds_read_b128 v[228:231], v168 offset:13920
	s_waitcnt lgkmcnt(1)
	v_mfma_f32_32x32x16_bf16 v[80:95], v[172:175], v[224:227], v[80:95]
	v_mfma_f32_32x32x16_bf16 v[16:31], v[220:223], v[224:227], v[16:31]
	s_waitcnt lgkmcnt(0)
	v_mfma_f32_32x32x16_bf16 v[64:79], v[172:175], v[228:231], v[64:79]
	v_mfma_f32_32x32x16_bf16 v[0:15], v[220:223], v[228:231], v[0:15]
	s_setprio 0
	global_load_dwordx4 v[172:175], v[128:129], off offset:3072
	global_load_dwordx4 v[220:223], v[132:133], off offset:3072
	s_barrier
; template <bool trans>
; DI void gemm_core(const GTile& tl, const GTile& nx, bool has_next  , bool chain  , bool pre, u32x4 (&ra)[4], u32x4 (&rb)[4], char* smem, f32x16 (&acc)[2][4]) {
;     ...
;   const int nk = K / 64;
;   if (!pre) { G_LOAD(0); G_STORE(0); G_LOAD(1); }
;   for (int kt = 0; kt < nk; ++kt) {
;     __syncthreads();
;     G_COMPUTE(kt & 1, kt);
	s_waitcnt vmcnt(9)
	ds_write_b128 v195, v[158:161]
	s_waitcnt vmcnt(8)
	ds_write_b128 v196, v[162:165]
	ds_read_b128 v[158:161], v192 offset:36864
	ds_read_b128 v[162:165], v192 offset:41472
	ds_read_b128 v[224:227], v184
	ds_read_b128 v[228:231], v184 offset:4608
	s_setprio 1
	s_waitcnt lgkmcnt(1)
	v_mfma_f32_32x32x16_bf16 v[112:127], v[158:161], v[224:227], v[112:127]
	v_mfma_f32_32x32x16_bf16 v[48:63], v[162:165], v[224:227], v[48:63]
	s_waitcnt lgkmcnt(0)
	v_mfma_f32_32x32x16_bf16 v[96:111], v[158:161], v[228:231], v[96:111]
	v_mfma_f32_32x32x16_bf16 v[32:47], v[162:165], v[228:231], v[32:47]
	ds_read_b128 v[224:227], v184 offset:9216
	ds_read_b128 v[228:231], v184 offset:13824
	s_waitcnt vmcnt(7)
	ds_write_b128 v194, v[198:201]
	s_waitcnt vmcnt(6)
	ds_write_b128 v193, v[202:205]
	ds_read_b128 v[198:201], v192 offset:36896
	ds_read_b128 v[202:205], v192 offset:41504
	s_waitcnt lgkmcnt(5)
	v_mfma_f32_32x32x16_bf16 v[80:95], v[158:161], v[224:227], v[80:95]
	v_mfma_f32_32x32x16_bf16 v[16:31], v[162:165], v[224:227], v[16:31]
	ds_read_b128 v[224:227], v184 offset:32
	s_waitcnt lgkmcnt(5)
	v_mfma_f32_32x32x16_bf16 v[64:79], v[158:161], v[228:231], v[64:79]
	v_mfma_f32_32x32x16_bf16 v[0:15], v[162:165], v[228:231], v[0:15]
	ds_read_b128 v[228:231], v184 offset:4640
	s_setprio 0
	global_load_dwordx4 v[158:161], v[136:137], off offset:3072
	global_load_dwordx4 v[162:165], v[140:141], off offset:3072
	s_setprio 1
	s_waitcnt lgkmcnt(1)
	v_mfma_f32_32x32x16_bf16 v[112:127], v[198:201], v[224:227], v[112:127]
	v_mfma_f32_32x32x16_bf16 v[48:63], v[202:205], v[224:227], v[48:63]
	s_waitcnt lgkmcnt(0)
	v_mfma_f32_32x32x16_bf16 v[96:111], v[198:201], v[228:231], v[96:111]
	v_mfma_f32_32x32x16_bf16 v[32:47], v[202:205], v[228:231], v[32:47]
	ds_read_b128 v[224:227], v184 offset:9248
	ds_read_b128 v[228:231], v184 offset:13856
	s_waitcnt vmcnt(7)
	ds_write_b128 v177, v[208:211]
	s_waitcnt vmcnt(6)
	ds_write_b128 v176, v[212:215]
	ds_read_b128 v[208:211], v192 offset:36928
	ds_read_b128 v[212:215], v192 offset:41536
	s_waitcnt lgkmcnt(5)
	v_mfma_f32_32x32x16_bf16 v[80:95], v[198:201], v[224:227], v[80:95]
	v_mfma_f32_32x32x16_bf16 v[16:31], v[202:205], v[224:227], v[16:31]
	ds_read_b128 v[224:227], v184 offset:64
	s_waitcnt lgkmcnt(5)
	v_mfma_f32_32x32x16_bf16 v[64:79], v[198:201], v[228:231], v[64:79]
	v_mfma_f32_32x32x16_bf16 v[0:15], v[202:205], v[228:231], v[0:15]
	ds_read_b128 v[228:231], v184 offset:4672
	s_setprio 0
	global_load_dwordx4 v[198:201], v[144:145], off offset:3072
	global_load_dwordx4 v[202:205], v[148:149], off offset:3072
	s_setprio 1
	s_waitcnt lgkmcnt(1)
	v_mfma_f32_32x32x16_bf16 v[112:127], v[208:211], v[224:227], v[112:127]
	v_mfma_f32_32x32x16_bf16 v[48:63], v[212:215], v[224:227], v[48:63]
	s_waitcnt lgkmcnt(0)
	v_mfma_f32_32x32x16_bf16 v[96:111], v[208:211], v[228:231], v[96:111]
	v_mfma_f32_32x32x16_bf16 v[32:47], v[212:215], v[228:231], v[32:47]
	ds_read_b128 v[224:227], v184 offset:9280
	ds_read_b128 v[228:231], v184 offset:13888
	s_waitcnt vmcnt(7)
	ds_write_b128 v171, v[178:181]
	s_waitcnt vmcnt(6)
	ds_write_b128 v170, v[216:219]
	ds_read_b128 v[178:181], v192 offset:36960
	ds_read_b128 v[216:219], v192 offset:41568
	s_waitcnt lgkmcnt(5)
	v_mfma_f32_32x32x16_bf16 v[80:95], v[208:211], v[224:227], v[80:95]
	v_mfma_f32_32x32x16_bf16 v[16:31], v[212:215], v[224:227], v[16:31]
	ds_read_b128 v[224:227], v184 offset:96
	s_waitcnt lgkmcnt(5)
	v_mfma_f32_32x32x16_bf16 v[64:79], v[208:211], v[228:231], v[64:79]
	v_mfma_f32_32x32x16_bf16 v[0:15], v[212:215], v[228:231], v[0:15]
	ds_read_b128 v[228:231], v184 offset:4704
	s_setprio 0
	global_load_dwordx4 v[208:211], v[152:153], off offset:3072
	global_load_dwordx4 v[212:215], v[156:157], off offset:3072
	s_setprio 1
	s_waitcnt lgkmcnt(1)
	v_mfma_f32_32x32x16_bf16 v[112:127], v[178:181], v[224:227], v[112:127]
	v_mfma_f32_32x32x16_bf16 v[48:63], v[216:219], v[224:227], v[48:63]
	s_waitcnt lgkmcnt(0)
	v_mfma_f32_32x32x16_bf16 v[96:111], v[178:181], v[228:231], v[96:111]
	v_mfma_f32_32x32x16_bf16 v[32:47], v[216:219], v[228:231], v[32:47]
	ds_read_b128 v[224:227], v184 offset:9312
	ds_read_b128 v[228:231], v184 offset:13920
	s_waitcnt lgkmcnt(1)
	v_mfma_f32_32x32x16_bf16 v[80:95], v[178:181], v[224:227], v[80:95]
	v_mfma_f32_32x32x16_bf16 v[16:31], v[216:219], v[224:227], v[16:31]
	s_waitcnt lgkmcnt(0)
	v_mfma_f32_32x32x16_bf16 v[64:79], v[178:181], v[228:231], v[64:79]
	v_mfma_f32_32x32x16_bf16 v[0:15], v[216:219], v[228:231], v[0:15]
	s_setprio 0
	global_load_dwordx4 v[178:181], v[128:129], off offset:3200
	global_load_dwordx4 v[216:219], v[132:133], off offset:3200
	s_barrier
; template <bool trans>
; DI void gemm_core(const GTile& tl, const GTile& nx, bool has_next  , bool chain  , bool pre, u32x4 (&ra)[4], u32x4 (&rb)[4], char* smem, f32x16 (&acc)[2][4]) {
;     ...
;   const int nk = K / 64;
;   if (!pre) { G_LOAD(0); G_STORE(0); G_LOAD(1); }
;   for (int kt = 0; kt < nk; ++kt) {
;     __syncthreads();
;     G_COMPUTE(kt & 1, kt);
	s_waitcnt vmcnt(9)
	ds_write_b128 v191, v[172:175]
	s_waitcnt vmcnt(8)
	ds_write_b128 v191, v[220:223] offset:36864
	ds_read_b128 v[172:175], v169
	ds_read_b128 v[220:223], v169 offset:4608
	ds_read_b128 v[224:227], v168
	ds_read_b128 v[228:231], v168 offset:4608
	s_setprio 1
	s_waitcnt lgkmcnt(1)
	v_mfma_f32_32x32x16_bf16 v[112:127], v[172:175], v[224:227], v[112:127]
	v_mfma_f32_32x32x16_bf16 v[48:63], v[220:223], v[224:227], v[48:63]
	s_waitcnt lgkmcnt(0)
	v_mfma_f32_32x32x16_bf16 v[96:111], v[172:175], v[228:231], v[96:111]
	v_mfma_f32_32x32x16_bf16 v[32:47], v[220:223], v[228:231], v[32:47]
	ds_read_b128 v[224:227], v168 offset:9216
	ds_read_b128 v[228:231], v168 offset:13824
	s_waitcnt vmcnt(7)
	ds_write_b128 v191, v[158:161] offset:9216
	s_waitcnt vmcnt(6)
	ds_write_b128 v191, v[162:165] offset:46080
	ds_read_b128 v[158:161], v169 offset:32
	ds_read_b128 v[162:165], v169 offset:4640
	s_waitcnt lgkmcnt(5)
	v_mfma_f32_32x32x16_bf16 v[80:95], v[172:175], v[224:227], v[80:95]
	v_mfma_f32_32x32x16_bf16 v[16:31], v[220:223], v[224:227], v[16:31]
	ds_read_b128 v[224:227], v168 offset:32
	s_waitcnt lgkmcnt(5)
	v_mfma_f32_32x32x16_bf16 v[64:79], v[172:175], v[228:231], v[64:79]
	v_mfma_f32_32x32x16_bf16 v[0:15], v[220:223], v[228:231], v[0:15]
	ds_read_b128 v[228:231], v168 offset:4640
	s_setprio 0
	global_load_dwordx4 v[172:175], v[136:137], off offset:3200
	global_load_dwordx4 v[220:223], v[140:141], off offset:3200
	s_setprio 1
	s_waitcnt lgkmcnt(1)
	v_mfma_f32_32x32x16_bf16 v[112:127], v[158:161], v[224:227], v[112:127]
	v_mfma_f32_32x32x16_bf16 v[48:63], v[162:165], v[224:227], v[48:63]
	s_waitcnt lgkmcnt(0)
	v_mfma_f32_32x32x16_bf16 v[96:111], v[158:161], v[228:231], v[96:111]
	v_mfma_f32_32x32x16_bf16 v[32:47], v[162:165], v[228:231], v[32:47]
	ds_read_b128 v[224:227], v168 offset:9248
	ds_read_b128 v[228:231], v168 offset:13856
	s_waitcnt vmcnt(7)
	ds_write_b128 v191, v[198:201] offset:18432
	s_waitcnt vmcnt(6)
	ds_write_b128 v191, v[202:205] offset:55296
	ds_read_b128 v[198:201], v169 offset:64
	ds_read_b128 v[202:205], v169 offset:4672
	s_waitcnt lgkmcnt(5)
	v_mfma_f32_32x32x16_bf16 v[80:95], v[158:161], v[224:227], v[80:95]
	v_mfma_f32_32x32x16_bf16 v[16:31], v[162:165], v[224:227], v[16:31]
	ds_read_b128 v[224:227], v168 offset:64
	s_waitcnt lgkmcnt(5)
	v_mfma_f32_32x32x16_bf16 v[64:79], v[158:161], v[228:231], v[64:79]
	v_mfma_f32_32x32x16_bf16 v[0:15], v[162:165], v[228:231], v[0:15]
	ds_read_b128 v[228:231], v168 offset:4672
	s_setprio 0
	global_load_dwordx4 v[158:161], v[144:145], off offset:3200
	global_load_dwordx4 v[162:165], v[148:149], off offset:3200
	s_setprio 1
	s_waitcnt lgkmcnt(1)
	v_mfma_f32_32x32x16_bf16 v[112:127], v[198:201], v[224:227], v[112:127]
	v_mfma_f32_32x32x16_bf16 v[48:63], v[202:205], v[224:227], v[48:63]
	s_waitcnt lgkmcnt(0)
	v_mfma_f32_32x32x16_bf16 v[96:111], v[198:201], v[228:231], v[96:111]
	v_mfma_f32_32x32x16_bf16 v[32:47], v[202:205], v[228:231], v[32:47]
	ds_read_b128 v[224:227], v168 offset:9280
	ds_read_b128 v[228:231], v168 offset:13888
	s_waitcnt vmcnt(7)
	ds_write_b128 v191, v[208:211] offset:27648
	s_waitcnt vmcnt(6)
	ds_write_b128 v191, v[212:215] offset:64512
	ds_read_b128 v[208:211], v169 offset:96
	ds_read_b128 v[212:215], v169 offset:4704
	s_waitcnt lgkmcnt(5)
	v_mfma_f32_32x32x16_bf16 v[80:95], v[198:201], v[224:227], v[80:95]
	v_mfma_f32_32x32x16_bf16 v[16:31], v[202:205], v[224:227], v[16:31]
	ds_read_b128 v[224:227], v168 offset:96
	s_waitcnt lgkmcnt(5)
	v_mfma_f32_32x32x16_bf16 v[64:79], v[198:201], v[228:231], v[64:79]
	v_mfma_f32_32x32x16_bf16 v[0:15], v[202:205], v[228:231], v[0:15]
	ds_read_b128 v[228:231], v168 offset:4704
	s_setprio 0
	global_load_dwordx4 v[198:201], v[152:153], off offset:3200
	global_load_dwordx4 v[202:205], v[156:157], off offset:3200
	s_setprio 1
	s_waitcnt lgkmcnt(1)
	v_mfma_f32_32x32x16_bf16 v[112:127], v[208:211], v[224:227], v[112:127]
	v_mfma_f32_32x32x16_bf16 v[48:63], v[212:215], v[224:227], v[48:63]
	s_waitcnt lgkmcnt(0)
	v_mfma_f32_32x32x16_bf16 v[96:111], v[208:211], v[228:231], v[96:111]
	v_mfma_f32_32x32x16_bf16 v[32:47], v[212:215], v[228:231], v[32:47]
	ds_read_b128 v[224:227], v168 offset:9312
	ds_read_b128 v[228:231], v168 offset:13920
	s_waitcnt lgkmcnt(1)
	v_mfma_f32_32x32x16_bf16 v[80:95], v[208:211], v[224:227], v[80:95]
	v_mfma_f32_32x32x16_bf16 v[16:31], v[212:215], v[224:227], v[16:31]
	s_waitcnt lgkmcnt(0)
	v_mfma_f32_32x32x16_bf16 v[64:79], v[208:211], v[228:231], v[64:79]
	v_mfma_f32_32x32x16_bf16 v[0:15], v[212:215], v[228:231], v[0:15]
	s_setprio 0
	global_load_dwordx4 v[208:211], v[128:129], off offset:3328
	global_load_dwordx4 v[212:215], v[132:133], off offset:3328
	s_barrier
; template <bool trans>
; DI void gemm_core(const GTile& tl, const GTile& nx, bool has_next  , bool chain  , bool pre, u32x4 (&ra)[4], u32x4 (&rb)[4], char* smem, f32x16 (&acc)[2][4]) {
;     ...
;   const int nk = K / 64;
;   if (!pre) { G_LOAD(0); G_STORE(0); G_LOAD(1); }
;   for (int kt = 0; kt < nk; ++kt) {
;     __syncthreads();
;     G_COMPUTE(kt & 1, kt);
	s_waitcnt vmcnt(9)
	ds_write_b128 v195, v[178:181]
	s_waitcnt vmcnt(8)
	ds_write_b128 v196, v[216:219]
	ds_read_b128 v[178:181], v192 offset:36864
	ds_read_b128 v[216:219], v192 offset:41472
	ds_read_b128 v[224:227], v184
	ds_read_b128 v[228:231], v184 offset:4608
	s_setprio 1
	s_waitcnt lgkmcnt(1)
	v_mfma_f32_32x32x16_bf16 v[112:127], v[178:181], v[224:227], v[112:127]
	v_mfma_f32_32x32x16_bf16 v[48:63], v[216:219], v[224:227], v[48:63]
	s_waitcnt lgkmcnt(0)
	v_mfma_f32_32x32x16_bf16 v[96:111], v[178:181], v[228:231], v[96:111]
	v_mfma_f32_32x32x16_bf16 v[32:47], v[216:219], v[228:231], v[32:47]
	ds_read_b128 v[224:227], v184 offset:9216
	ds_read_b128 v[228:231], v184 offset:13824
	s_waitcnt vmcnt(7)
	ds_write_b128 v194, v[172:175]
	s_waitcnt vmcnt(6)
	ds_write_b128 v193, v[220:223]
	ds_read_b128 v[172:175], v192 offset:36896
	ds_read_b128 v[220:223], v192 offset:41504
	s_waitcnt lgkmcnt(5)
	v_mfma_f32_32x32x16_bf16 v[80:95], v[178:181], v[224:227], v[80:95]
	v_mfma_f32_32x32x16_bf16 v[16:31], v[216:219], v[224:227], v[16:31]
	ds_read_b128 v[224:227], v184 offset:32
	s_waitcnt lgkmcnt(5)
	v_mfma_f32_32x32x16_bf16 v[64:79], v[178:181], v[228:231], v[64:79]
	v_mfma_f32_32x32x16_bf16 v[0:15], v[216:219], v[228:231], v[0:15]
	ds_read_b128 v[228:231], v184 offset:4640
	s_setprio 0
	global_load_dwordx4 v[178:181], v[136:137], off offset:3328
	global_load_dwordx4 v[216:219], v[140:141], off offset:3328
	s_setprio 1
	s_waitcnt lgkmcnt(1)
	v_mfma_f32_32x32x16_bf16 v[112:127], v[172:175], v[224:227], v[112:127]
	v_mfma_f32_32x32x16_bf16 v[48:63], v[220:223], v[224:227], v[48:63]
	s_waitcnt lgkmcnt(0)
	v_mfma_f32_32x32x16_bf16 v[96:111], v[172:175], v[228:231], v[96:111]
	v_mfma_f32_32x32x16_bf16 v[32:47], v[220:223], v[228:231], v[32:47]
	ds_read_b128 v[224:227], v184 offset:9248
	ds_read_b128 v[228:231], v184 offset:13856
	s_waitcnt vmcnt(7)
	ds_write_b128 v177, v[158:161]
	s_waitcnt vmcnt(6)
	ds_write_b128 v176, v[162:165]
	ds_read_b128 v[158:161], v192 offset:36928
	ds_read_b128 v[162:165], v192 offset:41536
	s_waitcnt lgkmcnt(5)
	v_mfma_f32_32x32x16_bf16 v[80:95], v[172:175], v[224:227], v[80:95]
	v_mfma_f32_32x32x16_bf16 v[16:31], v[220:223], v[224:227], v[16:31]
	ds_read_b128 v[224:227], v184 offset:64
	s_waitcnt lgkmcnt(5)
	v_mfma_f32_32x32x16_bf16 v[64:79], v[172:175], v[228:231], v[64:79]
	v_mfma_f32_32x32x16_bf16 v[0:15], v[220:223], v[228:231], v[0:15]
	ds_read_b128 v[228:231], v184 offset:4672
	s_setprio 0
	global_load_dwordx4 v[172:175], v[144:145], off offset:3328
	global_load_dwordx4 v[220:223], v[148:149], off offset:3328
	s_setprio 1
	s_waitcnt lgkmcnt(1)
	v_mfma_f32_32x32x16_bf16 v[112:127], v[158:161], v[224:227], v[112:127]
	v_mfma_f32_32x32x16_bf16 v[48:63], v[162:165], v[224:227], v[48:63]
	s_waitcnt lgkmcnt(0)
	v_mfma_f32_32x32x16_bf16 v[96:111], v[158:161], v[228:231], v[96:111]
	v_mfma_f32_32x32x16_bf16 v[32:47], v[162:165], v[228:231], v[32:47]
	ds_read_b128 v[224:227], v184 offset:9280
	ds_read_b128 v[228:231], v184 offset:13888
	s_waitcnt vmcnt(7)
	ds_write_b128 v171, v[198:201]
	s_waitcnt vmcnt(6)
	ds_write_b128 v170, v[202:205]
	ds_read_b128 v[198:201], v192 offset:36960
	ds_read_b128 v[202:205], v192 offset:41568
	s_waitcnt lgkmcnt(5)
	v_mfma_f32_32x32x16_bf16 v[80:95], v[158:161], v[224:227], v[80:95]
	v_mfma_f32_32x32x16_bf16 v[16:31], v[162:165], v[224:227], v[16:31]
	ds_read_b128 v[224:227], v184 offset:96
	s_waitcnt lgkmcnt(5)
	v_mfma_f32_32x32x16_bf16 v[64:79], v[158:161], v[228:231], v[64:79]
	v_mfma_f32_32x32x16_bf16 v[0:15], v[162:165], v[228:231], v[0:15]
	ds_read_b128 v[228:231], v184 offset:4704
	s_setprio 0
	global_load_dwordx4 v[158:161], v[152:153], off offset:3328
	global_load_dwordx4 v[162:165], v[156:157], off offset:3328
	s_setprio 1
	s_waitcnt lgkmcnt(1)
	v_mfma_f32_32x32x16_bf16 v[112:127], v[198:201], v[224:227], v[112:127]
	v_mfma_f32_32x32x16_bf16 v[48:63], v[202:205], v[224:227], v[48:63]
	s_waitcnt lgkmcnt(0)
	v_mfma_f32_32x32x16_bf16 v[96:111], v[198:201], v[228:231], v[96:111]
	v_mfma_f32_32x32x16_bf16 v[32:47], v[202:205], v[228:231], v[32:47]
	ds_read_b128 v[224:227], v184 offset:9312
	ds_read_b128 v[228:231], v184 offset:13920
	s_waitcnt lgkmcnt(1)
	v_mfma_f32_32x32x16_bf16 v[80:95], v[198:201], v[224:227], v[80:95]
	v_mfma_f32_32x32x16_bf16 v[16:31], v[202:205], v[224:227], v[16:31]
	s_waitcnt lgkmcnt(0)
	v_mfma_f32_32x32x16_bf16 v[64:79], v[198:201], v[228:231], v[64:79]
	v_mfma_f32_32x32x16_bf16 v[0:15], v[202:205], v[228:231], v[0:15]
	s_setprio 0
	global_load_dwordx4 v[198:201], v[128:129], off offset:3456
	global_load_dwordx4 v[202:205], v[132:133], off offset:3456
	s_barrier
; template <bool trans>
; DI void gemm_core(const GTile& tl, const GTile& nx, bool has_next  , bool chain  , bool pre, u32x4 (&ra)[4], u32x4 (&rb)[4], char* smem, f32x16 (&acc)[2][4]) {
;     ...
;   const int nk = K / 64;
;   if (!pre) { G_LOAD(0); G_STORE(0); G_LOAD(1); }
;   for (int kt = 0; kt < nk; ++kt) {
;     __syncthreads();
;     G_COMPUTE(kt & 1, kt);
	s_waitcnt vmcnt(9)
	ds_write_b128 v191, v[208:211]
	s_waitcnt vmcnt(8)
	ds_write_b128 v191, v[212:215] offset:36864
	ds_read_b128 v[208:211], v169
	ds_read_b128 v[212:215], v169 offset:4608
	ds_read_b128 v[224:227], v168
	ds_read_b128 v[228:231], v168 offset:4608
	s_setprio 1
	s_waitcnt lgkmcnt(1)
	v_mfma_f32_32x32x16_bf16 v[112:127], v[208:211], v[224:227], v[112:127]
	v_mfma_f32_32x32x16_bf16 v[48:63], v[212:215], v[224:227], v[48:63]
	s_waitcnt lgkmcnt(0)
	v_mfma_f32_32x32x16_bf16 v[96:111], v[208:211], v[228:231], v[96:111]
	v_mfma_f32_32x32x16_bf16 v[32:47], v[212:215], v[228:231], v[32:47]
	ds_read_b128 v[224:227], v168 offset:9216
	ds_read_b128 v[228:231], v168 offset:13824
	s_waitcnt vmcnt(7)
	ds_write_b128 v191, v[178:181] offset:9216
	s_waitcnt vmcnt(6)
	ds_write_b128 v191, v[216:219] offset:46080
	ds_read_b128 v[178:181], v169 offset:32
	ds_read_b128 v[216:219], v169 offset:4640
	s_waitcnt lgkmcnt(5)
	v_mfma_f32_32x32x16_bf16 v[80:95], v[208:211], v[224:227], v[80:95]
	v_mfma_f32_32x32x16_bf16 v[16:31], v[212:215], v[224:227], v[16:31]
	ds_read_b128 v[224:227], v168 offset:32
	s_waitcnt lgkmcnt(5)
	v_mfma_f32_32x32x16_bf16 v[64:79], v[208:211], v[228:231], v[64:79]
	v_mfma_f32_32x32x16_bf16 v[0:15], v[212:215], v[228:231], v[0:15]
	ds_read_b128 v[228:231], v168 offset:4640
	s_setprio 0
	global_load_dwordx4 v[208:211], v[136:137], off offset:3456
	global_load_dwordx4 v[212:215], v[140:141], off offset:3456
	s_setprio 1
	s_waitcnt lgkmcnt(1)
	v_mfma_f32_32x32x16_bf16 v[112:127], v[178:181], v[224:227], v[112:127]
	v_mfma_f32_32x32x16_bf16 v[48:63], v[216:219], v[224:227], v[48:63]
	s_waitcnt lgkmcnt(0)
	v_mfma_f32_32x32x16_bf16 v[96:111], v[178:181], v[228:231], v[96:111]
	v_mfma_f32_32x32x16_bf16 v[32:47], v[216:219], v[228:231], v[32:47]
	ds_read_b128 v[224:227], v168 offset:9248
	ds_read_b128 v[228:231], v168 offset:13856
	s_waitcnt vmcnt(7)
	ds_write_b128 v191, v[172:175] offset:18432
	s_waitcnt vmcnt(6)
	ds_write_b128 v191, v[220:223] offset:55296
	ds_read_b128 v[172:175], v169 offset:64
	ds_read_b128 v[220:223], v169 offset:4672
	s_waitcnt lgkmcnt(5)
	v_mfma_f32_32x32x16_bf16 v[80:95], v[178:181], v[224:227], v[80:95]
	v_mfma_f32_32x32x16_bf16 v[16:31], v[216:219], v[224:227], v[16:31]
	ds_read_b128 v[224:227], v168 offset:64
	s_waitcnt lgkmcnt(5)
	v_mfma_f32_32x32x16_bf16 v[64:79], v[178:181], v[228:231], v[64:79]
	v_mfma_f32_32x32x16_bf16 v[0:15], v[216:219], v[228:231], v[0:15]
	ds_read_b128 v[228:231], v168 offset:4672
	s_setprio 0
	global_load_dwordx4 v[178:181], v[144:145], off offset:3456
	global_load_dwordx4 v[216:219], v[148:149], off offset:3456
	s_setprio 1
	s_waitcnt lgkmcnt(1)
	v_mfma_f32_32x32x16_bf16 v[112:127], v[172:175], v[224:227], v[112:127]
	v_mfma_f32_32x32x16_bf16 v[48:63], v[220:223], v[224:227], v[48:63]
	s_waitcnt lgkmcnt(0)
	v_mfma_f32_32x32x16_bf16 v[96:111], v[172:175], v[228:231], v[96:111]
	v_mfma_f32_32x32x16_bf16 v[32:47], v[220:223], v[228:231], v[32:47]
	ds_read_b128 v[224:227], v168 offset:9280
	ds_read_b128 v[228:231], v168 offset:13888
	s_waitcnt vmcnt(7)
	ds_write_b128 v191, v[158:161] offset:27648
	s_waitcnt vmcnt(6)
	ds_write_b128 v191, v[162:165] offset:64512
	ds_read_b128 v[158:161], v169 offset:96
	ds_read_b128 v[162:165], v169 offset:4704
	s_waitcnt lgkmcnt(5)
	v_mfma_f32_32x32x16_bf16 v[80:95], v[172:175], v[224:227], v[80:95]
	v_mfma_f32_32x32x16_bf16 v[16:31], v[220:223], v[224:227], v[16:31]
	ds_read_b128 v[224:227], v168 offset:96
	s_waitcnt lgkmcnt(5)
	v_mfma_f32_32x32x16_bf16 v[64:79], v[172:175], v[228:231], v[64:79]
	v_mfma_f32_32x32x16_bf16 v[0:15], v[220:223], v[228:231], v[0:15]
	ds_read_b128 v[228:231], v168 offset:4704
	s_setprio 0
	global_load_dwordx4 v[172:175], v[152:153], off offset:3456
	global_load_dwordx4 v[220:223], v[156:157], off offset:3456
	s_setprio 1
	s_waitcnt lgkmcnt(1)
	v_mfma_f32_32x32x16_bf16 v[112:127], v[158:161], v[224:227], v[112:127]
	v_mfma_f32_32x32x16_bf16 v[48:63], v[162:165], v[224:227], v[48:63]
	s_waitcnt lgkmcnt(0)
	v_mfma_f32_32x32x16_bf16 v[96:111], v[158:161], v[228:231], v[96:111]
	v_mfma_f32_32x32x16_bf16 v[32:47], v[162:165], v[228:231], v[32:47]
	ds_read_b128 v[224:227], v168 offset:9312
	ds_read_b128 v[228:231], v168 offset:13920
	s_waitcnt lgkmcnt(1)
	v_mfma_f32_32x32x16_bf16 v[80:95], v[158:161], v[224:227], v[80:95]
	v_mfma_f32_32x32x16_bf16 v[16:31], v[162:165], v[224:227], v[16:31]
	s_waitcnt lgkmcnt(0)
	v_mfma_f32_32x32x16_bf16 v[64:79], v[158:161], v[228:231], v[64:79]
	v_mfma_f32_32x32x16_bf16 v[0:15], v[162:165], v[228:231], v[0:15]
	s_setprio 0
	global_load_dwordx4 v[158:161], v[128:129], off offset:3584
	global_load_dwordx4 v[162:165], v[132:133], off offset:3584
	s_barrier
; template <bool trans>
; DI void gemm_core(const GTile& tl, const GTile& nx, bool has_next  , bool chain  , bool pre, u32x4 (&ra)[4], u32x4 (&rb)[4], char* smem, f32x16 (&acc)[2][4]) {
;     ...
;   const int nk = K / 64;
;   if (!pre) { G_LOAD(0); G_STORE(0); G_LOAD(1); }
;   for (int kt = 0; kt < nk; ++kt) {
;     __syncthreads();
;     G_COMPUTE(kt & 1, kt);
;   }
	s_waitcnt vmcnt(9)
	ds_write_b128 v195, v[198:201]
	s_waitcnt vmcnt(8)
	ds_write_b128 v196, v[202:205]
	ds_read_b128 v[198:201], v192 offset:36864
	ds_read_b128 v[202:205], v192 offset:41472
	ds_read_b128 v[224:227], v184
	ds_read_b128 v[228:231], v184 offset:4608
	s_setprio 1
	s_waitcnt lgkmcnt(1)
	v_mfma_f32_32x32x16_bf16 v[112:127], v[198:201], v[224:227], v[112:127]
	v_mfma_f32_32x32x16_bf16 v[48:63], v[202:205], v[224:227], v[48:63]
	s_waitcnt lgkmcnt(0)
	v_mfma_f32_32x32x16_bf16 v[96:111], v[198:201], v[228:231], v[96:111]
	v_mfma_f32_32x32x16_bf16 v[32:47], v[202:205], v[228:231], v[32:47]
	ds_read_b128 v[224:227], v184 offset:9216
	ds_read_b128 v[228:231], v184 offset:13824
	s_waitcnt vmcnt(7)
	ds_write_b128 v194, v[208:211]
	s_waitcnt vmcnt(6)
	ds_write_b128 v193, v[212:215]
	ds_read_b128 v[208:211], v192 offset:36896
	ds_read_b128 v[212:215], v192 offset:41504
	s_waitcnt lgkmcnt(5)
	v_mfma_f32_32x32x16_bf16 v[80:95], v[198:201], v[224:227], v[80:95]
	v_mfma_f32_32x32x16_bf16 v[16:31], v[202:205], v[224:227], v[16:31]
	ds_read_b128 v[224:227], v184 offset:32
	s_waitcnt lgkmcnt(5)
	v_mfma_f32_32x32x16_bf16 v[64:79], v[198:201], v[228:231], v[64:79]
	v_mfma_f32_32x32x16_bf16 v[0:15], v[202:205], v[228:231], v[0:15]
	ds_read_b128 v[228:231], v184 offset:4640
	s_setprio 0
	global_load_dwordx4 v[198:201], v[136:137], off offset:3584
	global_load_dwordx4 v[202:205], v[140:141], off offset:3584
	s_setprio 1
	s_waitcnt lgkmcnt(1)
	v_mfma_f32_32x32x16_bf16 v[112:127], v[208:211], v[224:227], v[112:127]
	v_mfma_f32_32x32x16_bf16 v[48:63], v[212:215], v[224:227], v[48:63]
	s_waitcnt lgkmcnt(0)
	v_mfma_f32_32x32x16_bf16 v[96:111], v[208:211], v[228:231], v[96:111]
	v_mfma_f32_32x32x16_bf16 v[32:47], v[212:215], v[228:231], v[32:47]
	ds_read_b128 v[224:227], v184 offset:9248
	ds_read_b128 v[228:231], v184 offset:13856
	s_waitcnt vmcnt(7)
	ds_write_b128 v177, v[178:181]
	s_waitcnt vmcnt(6)
	ds_write_b128 v176, v[216:219]
	ds_read_b128 v[178:181], v192 offset:36928
	ds_read_b128 v[216:219], v192 offset:41536
	s_waitcnt lgkmcnt(5)
	v_mfma_f32_32x32x16_bf16 v[80:95], v[208:211], v[224:227], v[80:95]
	v_mfma_f32_32x32x16_bf16 v[16:31], v[212:215], v[224:227], v[16:31]
	ds_read_b128 v[224:227], v184 offset:64
	s_waitcnt lgkmcnt(5)
	v_mfma_f32_32x32x16_bf16 v[64:79], v[208:211], v[228:231], v[64:79]
	v_mfma_f32_32x32x16_bf16 v[0:15], v[212:215], v[228:231], v[0:15]
	ds_read_b128 v[228:231], v184 offset:4672
	s_setprio 0
	global_load_dwordx4 v[208:211], v[144:145], off offset:3584
	global_load_dwordx4 v[212:215], v[148:149], off offset:3584
	s_setprio 1
	s_waitcnt lgkmcnt(1)
	v_mfma_f32_32x32x16_bf16 v[112:127], v[178:181], v[224:227], v[112:127]
	v_mfma_f32_32x32x16_bf16 v[48:63], v[216:219], v[224:227], v[48:63]
	s_waitcnt lgkmcnt(0)
	v_mfma_f32_32x32x16_bf16 v[96:111], v[178:181], v[228:231], v[96:111]
	v_mfma_f32_32x32x16_bf16 v[32:47], v[216:219], v[228:231], v[32:47]
	ds_read_b128 v[224:227], v184 offset:9280
	ds_read_b128 v[228:231], v184 offset:13888
	s_waitcnt vmcnt(7)
	ds_write_b128 v171, v[172:175]
	s_waitcnt vmcnt(6)
	ds_write_b128 v170, v[220:223]
	ds_read_b128 v[172:175], v192 offset:36960
	ds_read_b128 v[220:223], v192 offset:41568
	s_waitcnt lgkmcnt(5)
	v_mfma_f32_32x32x16_bf16 v[80:95], v[178:181], v[224:227], v[80:95]
	v_mfma_f32_32x32x16_bf16 v[16:31], v[216:219], v[224:227], v[16:31]
	ds_read_b128 v[224:227], v184 offset:96
	s_waitcnt lgkmcnt(5)
	v_mfma_f32_32x32x16_bf16 v[64:79], v[178:181], v[228:231], v[64:79]
	v_mfma_f32_32x32x16_bf16 v[0:15], v[216:219], v[228:231], v[0:15]
	ds_read_b128 v[228:231], v184 offset:4704
	s_setprio 0
	global_load_dwordx4 v[178:181], v[152:153], off offset:3584
	global_load_dwordx4 v[216:219], v[156:157], off offset:3584
	s_setprio 1
	s_waitcnt lgkmcnt(1)
	v_mfma_f32_32x32x16_bf16 v[112:127], v[172:175], v[224:227], v[112:127]
	v_mfma_f32_32x32x16_bf16 v[48:63], v[220:223], v[224:227], v[48:63]
	s_waitcnt lgkmcnt(0)
	v_mfma_f32_32x32x16_bf16 v[96:111], v[172:175], v[228:231], v[96:111]
	v_mfma_f32_32x32x16_bf16 v[32:47], v[220:223], v[228:231], v[32:47]
	ds_read_b128 v[224:227], v184 offset:9312
	ds_read_b128 v[228:231], v184 offset:13920
	s_waitcnt lgkmcnt(1)
	v_mfma_f32_32x32x16_bf16 v[80:95], v[172:175], v[224:227], v[80:95]
	v_mfma_f32_32x32x16_bf16 v[16:31], v[220:223], v[224:227], v[16:31]
	s_waitcnt lgkmcnt(0)
	v_mfma_f32_32x32x16_bf16 v[64:79], v[172:175], v[228:231], v[64:79]
	v_mfma_f32_32x32x16_bf16 v[0:15], v[220:223], v[228:231], v[0:15]
	s_setprio 0
	global_load_dwordx4 v[172:175], v[128:129], off offset:3712
	global_load_dwordx4 v[220:223], v[132:133], off offset:3712
	s_barrier
; template <bool trans>
; DI void gemm_core(const GTile& tl, const GTile& nx, bool has_next  , bool chain  , bool pre, u32x4 (&ra)[4], u32x4 (&rb)[4], char* smem, f32x16 (&acc)[2][4]) {
;     ...
;   const int nk = K / 64;
;   if (!pre) { G_LOAD(0); G_STORE(0); G_LOAD(1); }
;   for (int kt = 0; kt < nk; ++kt) {
;     __syncthreads();
;     G_COMPUTE(kt & 1, kt);
;   }
	s_waitcnt vmcnt(9)
	ds_write_b128 v191, v[158:161]
	s_waitcnt vmcnt(8)
	ds_write_b128 v191, v[162:165] offset:36864
	ds_read_b128 v[158:161], v169
	ds_read_b128 v[162:165], v169 offset:4608
	ds_read_b128 v[224:227], v168
	ds_read_b128 v[228:231], v168 offset:4608
	s_setprio 1
	s_waitcnt lgkmcnt(1)
	v_mfma_f32_32x32x16_bf16 v[112:127], v[158:161], v[224:227], v[112:127]
	v_mfma_f32_32x32x16_bf16 v[48:63], v[162:165], v[224:227], v[48:63]
	s_waitcnt lgkmcnt(0)
	v_mfma_f32_32x32x16_bf16 v[96:111], v[158:161], v[228:231], v[96:111]
	v_mfma_f32_32x32x16_bf16 v[32:47], v[162:165], v[228:231], v[32:47]
	ds_read_b128 v[224:227], v168 offset:9216
	ds_read_b128 v[228:231], v168 offset:13824
	s_waitcnt vmcnt(7)
	ds_write_b128 v191, v[198:201] offset:9216
	s_waitcnt vmcnt(6)
	ds_write_b128 v191, v[202:205] offset:46080
	ds_read_b128 v[198:201], v169 offset:32
	ds_read_b128 v[202:205], v169 offset:4640
	s_waitcnt lgkmcnt(5)
	v_mfma_f32_32x32x16_bf16 v[80:95], v[158:161], v[224:227], v[80:95]
	v_mfma_f32_32x32x16_bf16 v[16:31], v[162:165], v[224:227], v[16:31]
	ds_read_b128 v[224:227], v168 offset:32
	s_waitcnt lgkmcnt(5)
	v_mfma_f32_32x32x16_bf16 v[64:79], v[158:161], v[228:231], v[64:79]
	v_mfma_f32_32x32x16_bf16 v[0:15], v[162:165], v[228:231], v[0:15]
	ds_read_b128 v[228:231], v168 offset:4640
	s_setprio 0
	global_load_dwordx4 v[158:161], v[136:137], off offset:3712
	global_load_dwordx4 v[162:165], v[140:141], off offset:3712
	s_setprio 1
	s_waitcnt lgkmcnt(1)
	v_mfma_f32_32x32x16_bf16 v[112:127], v[198:201], v[224:227], v[112:127]
	v_mfma_f32_32x32x16_bf16 v[48:63], v[202:205], v[224:227], v[48:63]
	s_waitcnt lgkmcnt(0)
	v_mfma_f32_32x32x16_bf16 v[96:111], v[198:201], v[228:231], v[96:111]
	v_mfma_f32_32x32x16_bf16 v[32:47], v[202:205], v[228:231], v[32:47]
	ds_read_b128 v[224:227], v168 offset:9248
	ds_read_b128 v[228:231], v168 offset:13856
	s_waitcnt vmcnt(7)
	ds_write_b128 v191, v[208:211] offset:18432
	s_waitcnt vmcnt(6)
	ds_write_b128 v191, v[212:215] offset:55296
	ds_read_b128 v[208:211], v169 offset:64
	ds_read_b128 v[212:215], v169 offset:4672
	s_waitcnt lgkmcnt(5)
	v_mfma_f32_32x32x16_bf16 v[80:95], v[198:201], v[224:227], v[80:95]
	v_mfma_f32_32x32x16_bf16 v[16:31], v[202:205], v[224:227], v[16:31]
	ds_read_b128 v[224:227], v168 offset:64
	s_waitcnt lgkmcnt(5)
	v_mfma_f32_32x32x16_bf16 v[64:79], v[198:201], v[228:231], v[64:79]
	v_mfma_f32_32x32x16_bf16 v[0:15], v[202:205], v[228:231], v[0:15]
	ds_read_b128 v[228:231], v168 offset:4672
	s_setprio 0
	global_load_dwordx4 v[198:201], v[144:145], off offset:3712
	global_load_dwordx4 v[202:205], v[148:149], off offset:3712
	s_setprio 1
	s_waitcnt lgkmcnt(1)
	v_mfma_f32_32x32x16_bf16 v[112:127], v[208:211], v[224:227], v[112:127]
	v_mfma_f32_32x32x16_bf16 v[48:63], v[212:215], v[224:227], v[48:63]
	s_waitcnt lgkmcnt(0)
	v_mfma_f32_32x32x16_bf16 v[96:111], v[208:211], v[228:231], v[96:111]
	v_mfma_f32_32x32x16_bf16 v[32:47], v[212:215], v[228:231], v[32:47]
	ds_read_b128 v[224:227], v168 offset:9280
	ds_read_b128 v[228:231], v168 offset:13888
	s_waitcnt vmcnt(7)
	ds_write_b128 v191, v[178:181] offset:27648
	s_waitcnt vmcnt(6)
	ds_write_b128 v191, v[216:219] offset:64512
	ds_read_b128 v[178:181], v169 offset:96
	ds_read_b128 v[216:219], v169 offset:4704
	s_waitcnt lgkmcnt(5)
	v_mfma_f32_32x32x16_bf16 v[80:95], v[208:211], v[224:227], v[80:95]
	v_mfma_f32_32x32x16_bf16 v[16:31], v[212:215], v[224:227], v[16:31]
	ds_read_b128 v[224:227], v168 offset:96
	s_waitcnt lgkmcnt(5)
	v_mfma_f32_32x32x16_bf16 v[64:79], v[208:211], v[228:231], v[64:79]
	v_mfma_f32_32x32x16_bf16 v[0:15], v[212:215], v[228:231], v[0:15]
	ds_read_b128 v[228:231], v168 offset:4704
	s_setprio 0
	global_load_dwordx4 v[208:211], v[152:153], off offset:3712
	global_load_dwordx4 v[212:215], v[156:157], off offset:3712
	s_setprio 1
	s_waitcnt lgkmcnt(1)
	v_mfma_f32_32x32x16_bf16 v[112:127], v[178:181], v[224:227], v[112:127]
	v_mfma_f32_32x32x16_bf16 v[48:63], v[216:219], v[224:227], v[48:63]
	s_waitcnt lgkmcnt(0)
	v_mfma_f32_32x32x16_bf16 v[96:111], v[178:181], v[228:231], v[96:111]
	v_mfma_f32_32x32x16_bf16 v[32:47], v[216:219], v[228:231], v[32:47]
	ds_read_b128 v[224:227], v168 offset:9312
	ds_read_b128 v[228:231], v168 offset:13920
	s_waitcnt lgkmcnt(1)
	v_mfma_f32_32x32x16_bf16 v[80:95], v[178:181], v[224:227], v[80:95]
	v_mfma_f32_32x32x16_bf16 v[16:31], v[216:219], v[224:227], v[16:31]
	s_waitcnt lgkmcnt(0)
	v_mfma_f32_32x32x16_bf16 v[64:79], v[178:181], v[228:231], v[64:79]
	v_mfma_f32_32x32x16_bf16 v[0:15], v[216:219], v[228:231], v[0:15]
	s_setprio 0
	global_load_dwordx4 v[178:181], v[128:129], off offset:3840
	global_load_dwordx4 v[216:219], v[132:133], off offset:3840
	s_barrier
; template <bool trans>
; DI void gemm_core(const GTile& tl, const GTile& nx, bool has_next  , bool chain  , bool pre, u32x4 (&ra)[4], u32x4 (&rb)[4], char* smem, f32x16 (&acc)[2][4]) {
;     ...
;   const int nk = K / 64;
;   if (!pre) { G_LOAD(0); G_STORE(0); G_LOAD(1); }
;   for (int kt = 0; kt < nk; ++kt) {
;     __syncthreads();
;     G_COMPUTE(kt & 1, kt);
;   }
	s_waitcnt vmcnt(9)
	ds_write_b128 v195, v[172:175]
	s_waitcnt vmcnt(8)
	ds_write_b128 v196, v[220:223]
	ds_read_b128 v[172:175], v192 offset:36864
	ds_read_b128 v[220:223], v192 offset:41472
	ds_read_b128 v[224:227], v184
	ds_read_b128 v[228:231], v184 offset:4608
	s_setprio 1
	s_waitcnt lgkmcnt(1)
	v_mfma_f32_32x32x16_bf16 v[112:127], v[172:175], v[224:227], v[112:127]
	v_mfma_f32_32x32x16_bf16 v[48:63], v[220:223], v[224:227], v[48:63]
	s_waitcnt lgkmcnt(0)
	v_mfma_f32_32x32x16_bf16 v[96:111], v[172:175], v[228:231], v[96:111]
	v_mfma_f32_32x32x16_bf16 v[32:47], v[220:223], v[228:231], v[32:47]
	ds_read_b128 v[224:227], v184 offset:9216
	ds_read_b128 v[228:231], v184 offset:13824
	s_waitcnt vmcnt(7)
	ds_write_b128 v194, v[158:161]
	s_waitcnt vmcnt(6)
	ds_write_b128 v193, v[162:165]
	ds_read_b128 v[158:161], v192 offset:36896
	ds_read_b128 v[162:165], v192 offset:41504
	s_waitcnt lgkmcnt(5)
	v_mfma_f32_32x32x16_bf16 v[80:95], v[172:175], v[224:227], v[80:95]
	v_mfma_f32_32x32x16_bf16 v[16:31], v[220:223], v[224:227], v[16:31]
	ds_read_b128 v[224:227], v184 offset:32
	s_waitcnt lgkmcnt(5)
	v_mfma_f32_32x32x16_bf16 v[64:79], v[172:175], v[228:231], v[64:79]
	v_mfma_f32_32x32x16_bf16 v[0:15], v[220:223], v[228:231], v[0:15]
	ds_read_b128 v[228:231], v184 offset:4640
	s_setprio 0
	global_load_dwordx4 v[172:175], v[136:137], off offset:3840
	global_load_dwordx4 v[220:223], v[140:141], off offset:3840
	s_setprio 1
	s_waitcnt lgkmcnt(1)
	v_mfma_f32_32x32x16_bf16 v[112:127], v[158:161], v[224:227], v[112:127]
	v_mfma_f32_32x32x16_bf16 v[48:63], v[162:165], v[224:227], v[48:63]
	s_waitcnt lgkmcnt(0)
	v_mfma_f32_32x32x16_bf16 v[96:111], v[158:161], v[228:231], v[96:111]
	v_mfma_f32_32x32x16_bf16 v[32:47], v[162:165], v[228:231], v[32:47]
	ds_read_b128 v[224:227], v184 offset:9248
	ds_read_b128 v[228:231], v184 offset:13856
	s_waitcnt vmcnt(7)
	ds_write_b128 v177, v[198:201]
	s_waitcnt vmcnt(6)
	ds_write_b128 v176, v[202:205]
	ds_read_b128 v[198:201], v192 offset:36928
	ds_read_b128 v[202:205], v192 offset:41536
	s_waitcnt lgkmcnt(5)
	v_mfma_f32_32x32x16_bf16 v[80:95], v[158:161], v[224:227], v[80:95]
	v_mfma_f32_32x32x16_bf16 v[16:31], v[162:165], v[224:227], v[16:31]
	ds_read_b128 v[224:227], v184 offset:64
	s_waitcnt lgkmcnt(5)
	v_mfma_f32_32x32x16_bf16 v[64:79], v[158:161], v[228:231], v[64:79]
	v_mfma_f32_32x32x16_bf16 v[0:15], v[162:165], v[228:231], v[0:15]
	ds_read_b128 v[228:231], v184 offset:4672
	s_setprio 0
	global_load_dwordx4 v[158:161], v[144:145], off offset:3840
	global_load_dwordx4 v[162:165], v[148:149], off offset:3840
	s_setprio 1
	s_waitcnt lgkmcnt(1)
	v_mfma_f32_32x32x16_bf16 v[112:127], v[198:201], v[224:227], v[112:127]
	v_mfma_f32_32x32x16_bf16 v[48:63], v[202:205], v[224:227], v[48:63]
	s_waitcnt lgkmcnt(0)
	v_mfma_f32_32x32x16_bf16 v[96:111], v[198:201], v[228:231], v[96:111]
	v_mfma_f32_32x32x16_bf16 v[32:47], v[202:205], v[228:231], v[32:47]
	ds_read_b128 v[224:227], v184 offset:9280
	ds_read_b128 v[228:231], v184 offset:13888
	s_waitcnt vmcnt(7)
	ds_write_b128 v171, v[208:211]
	s_waitcnt vmcnt(6)
	ds_write_b128 v170, v[212:215]
	ds_read_b128 v[208:211], v192 offset:36960
	ds_read_b128 v[212:215], v192 offset:41568
	s_waitcnt lgkmcnt(5)
	v_mfma_f32_32x32x16_bf16 v[80:95], v[198:201], v[224:227], v[80:95]
	v_mfma_f32_32x32x16_bf16 v[16:31], v[202:205], v[224:227], v[16:31]
	ds_read_b128 v[224:227], v184 offset:96
	s_waitcnt lgkmcnt(5)
	v_mfma_f32_32x32x16_bf16 v[64:79], v[198:201], v[228:231], v[64:79]
	v_mfma_f32_32x32x16_bf16 v[0:15], v[202:205], v[228:231], v[0:15]
	ds_read_b128 v[228:231], v184 offset:4704
	s_setprio 0
	global_load_dwordx4 v[198:201], v[152:153], off offset:3840
	global_load_dwordx4 v[202:205], v[156:157], off offset:3840
	s_setprio 1
	s_waitcnt lgkmcnt(1)
	v_mfma_f32_32x32x16_bf16 v[112:127], v[208:211], v[224:227], v[112:127]
	v_mfma_f32_32x32x16_bf16 v[48:63], v[212:215], v[224:227], v[48:63]
	s_waitcnt lgkmcnt(0)
	v_mfma_f32_32x32x16_bf16 v[96:111], v[208:211], v[228:231], v[96:111]
	v_mfma_f32_32x32x16_bf16 v[32:47], v[212:215], v[228:231], v[32:47]
	ds_read_b128 v[224:227], v184 offset:9312
	ds_read_b128 v[228:231], v184 offset:13920
	s_waitcnt lgkmcnt(1)
	v_mfma_f32_32x32x16_bf16 v[80:95], v[208:211], v[224:227], v[80:95]
	v_mfma_f32_32x32x16_bf16 v[16:31], v[212:215], v[224:227], v[16:31]
	s_waitcnt lgkmcnt(0)
	v_mfma_f32_32x32x16_bf16 v[64:79], v[208:211], v[228:231], v[64:79]
	v_mfma_f32_32x32x16_bf16 v[0:15], v[212:215], v[228:231], v[0:15]
	s_setprio 0
	s_barrier
; template <bool trans>
; DI void gemm_core(const GTile& tl, const GTile& nx, bool has_next  , bool chain  , bool pre, u32x4 (&ra)[4], u32x4 (&rb)[4], char* smem, f32x16 (&acc)[2][4]) {
;     ...
;   const int nk = K / 64;
;   if (!pre) { G_LOAD(0); G_STORE(0); G_LOAD(1); }
;   for (int kt = 0; kt < nk; ++kt) {
;     __syncthreads();
;     G_COMPUTE(kt & 1, kt);
;   }
;   if (!has_next) __syncthreads();
	global_load_dwordx4 v[128:131], v[128:129], off offset:3968
	s_nop 0
	global_load_dwordx4 v[132:135], v[132:133], off offset:3968
	s_waitcnt vmcnt(9)
	ds_write_b128 v191, v[178:181]
	s_waitcnt vmcnt(8)
	ds_write_b128 v191, v[216:219] offset:36864
	ds_read_b128 v[178:181], v169
	ds_read_b128 v[208:211], v169 offset:4608
	ds_read_b128 v[212:215], v168
	ds_read_b128 v[216:219], v168 offset:4608
	s_setprio 1
	s_waitcnt lgkmcnt(1)
	v_mfma_f32_32x32x16_bf16 v[112:127], v[178:181], v[212:215], v[112:127]
	v_mfma_f32_32x32x16_bf16 v[48:63], v[208:211], v[212:215], v[48:63]
	s_waitcnt lgkmcnt(0)
	v_mfma_f32_32x32x16_bf16 v[96:111], v[178:181], v[216:219], v[96:111]
	v_mfma_f32_32x32x16_bf16 v[32:47], v[208:211], v[216:219], v[32:47]
	ds_read_b128 v[212:215], v168 offset:9216
	ds_read_b128 v[216:219], v168 offset:13824
	s_waitcnt lgkmcnt(1)
	v_mfma_f32_32x32x16_bf16 v[80:95], v[178:181], v[212:215], v[80:95]
	v_mfma_f32_32x32x16_bf16 v[16:31], v[208:211], v[212:215], v[16:31]
	s_waitcnt lgkmcnt(0)
	v_mfma_f32_32x32x16_bf16 v[64:79], v[178:181], v[216:219], v[64:79]
	v_mfma_f32_32x32x16_bf16 v[0:15], v[208:211], v[216:219], v[0:15]
	s_setprio 0
	global_load_dwordx4 v[136:139], v[136:137], off offset:3968
	s_nop 0
	global_load_dwordx4 v[140:143], v[140:141], off offset:3968
	s_waitcnt vmcnt(9)
	ds_write_b128 v191, v[172:175] offset:9216
	s_waitcnt vmcnt(8)
	ds_write_b128 v191, v[220:223] offset:46080
	ds_read_b128 v[172:175], v169 offset:32
	ds_read_b128 v[178:181], v169 offset:4640
	ds_read_b128 v[208:211], v168 offset:32
	ds_read_b128 v[212:215], v168 offset:4640
	s_setprio 1
	s_waitcnt lgkmcnt(1)
	v_mfma_f32_32x32x16_bf16 v[112:127], v[172:175], v[208:211], v[112:127]
	v_mfma_f32_32x32x16_bf16 v[48:63], v[178:181], v[208:211], v[48:63]
	s_waitcnt lgkmcnt(0)
	v_mfma_f32_32x32x16_bf16 v[96:111], v[172:175], v[212:215], v[96:111]
	v_mfma_f32_32x32x16_bf16 v[32:47], v[178:181], v[212:215], v[32:47]
	ds_read_b128 v[208:211], v168 offset:9248
	ds_read_b128 v[212:215], v168 offset:13856
	s_waitcnt lgkmcnt(1)
	v_mfma_f32_32x32x16_bf16 v[80:95], v[172:175], v[208:211], v[80:95]
	v_mfma_f32_32x32x16_bf16 v[16:31], v[178:181], v[208:211], v[16:31]
	s_waitcnt lgkmcnt(0)
	v_mfma_f32_32x32x16_bf16 v[64:79], v[172:175], v[212:215], v[64:79]
	v_mfma_f32_32x32x16_bf16 v[0:15], v[178:181], v[212:215], v[0:15]
	s_setprio 0
	global_load_dwordx4 v[144:147], v[144:145], off offset:3968
	s_nop 0
	global_load_dwordx4 v[148:151], v[148:149], off offset:3968
	s_waitcnt vmcnt(9)
	ds_write_b128 v191, v[158:161] offset:18432
	s_waitcnt vmcnt(8)
	ds_write_b128 v191, v[162:165] offset:55296
	ds_read_b128 v[158:161], v169 offset:64
	ds_read_b128 v[162:165], v169 offset:4672
	ds_read_b128 v[172:175], v168 offset:64
	ds_read_b128 v[178:181], v168 offset:4672
	s_setprio 1
	s_waitcnt lgkmcnt(1)
	v_mfma_f32_32x32x16_bf16 v[112:127], v[158:161], v[172:175], v[112:127]
	v_mfma_f32_32x32x16_bf16 v[48:63], v[162:165], v[172:175], v[48:63]
	s_waitcnt lgkmcnt(0)
	v_mfma_f32_32x32x16_bf16 v[96:111], v[158:161], v[178:181], v[96:111]
	v_mfma_f32_32x32x16_bf16 v[32:47], v[162:165], v[178:181], v[32:47]
	ds_read_b128 v[172:175], v168 offset:9280
	ds_read_b128 v[178:181], v168 offset:13888
	s_waitcnt lgkmcnt(1)
	v_mfma_f32_32x32x16_bf16 v[80:95], v[158:161], v[172:175], v[80:95]
	v_mfma_f32_32x32x16_bf16 v[16:31], v[162:165], v[172:175], v[16:31]
	s_waitcnt lgkmcnt(0)
	v_mfma_f32_32x32x16_bf16 v[64:79], v[158:161], v[178:181], v[64:79]
	v_mfma_f32_32x32x16_bf16 v[0:15], v[162:165], v[178:181], v[0:15]
	s_setprio 0
	global_load_dwordx4 v[152:155], v[152:153], off offset:3968
	s_nop 0
	global_load_dwordx4 v[156:159], v[156:157], off offset:3968
	s_waitcnt vmcnt(9)
	ds_write_b128 v191, v[198:201] offset:27648
	s_waitcnt vmcnt(8)
	ds_write_b128 v191, v[202:205] offset:64512
	ds_read_b128 v[160:163], v169 offset:96
	ds_read_b128 v[164:167], v169 offset:4704
	ds_read_b128 v[172:175], v168 offset:96
	ds_read_b128 v[178:181], v168 offset:4704
	s_setprio 1
	s_waitcnt lgkmcnt(1)
	v_mfma_f32_32x32x16_bf16 v[112:127], v[160:163], v[172:175], v[112:127]
	v_mfma_f32_32x32x16_bf16 v[48:63], v[164:167], v[172:175], v[48:63]
	s_waitcnt lgkmcnt(0)
	v_mfma_f32_32x32x16_bf16 v[96:111], v[160:163], v[178:181], v[96:111]
	v_mfma_f32_32x32x16_bf16 v[32:47], v[164:167], v[178:181], v[32:47]
	ds_read_b128 v[172:175], v168 offset:9312
	ds_read_b128 v[178:181], v168 offset:13920
	s_waitcnt lgkmcnt(1)
	v_mfma_f32_32x32x16_bf16 v[80:95], v[160:163], v[172:175], v[80:95]
	v_mfma_f32_32x32x16_bf16 v[16:31], v[164:167], v[172:175], v[16:31]
	s_waitcnt lgkmcnt(0)
	v_mfma_f32_32x32x16_bf16 v[64:79], v[160:163], v[178:181], v[64:79]
	v_mfma_f32_32x32x16_bf16 v[0:15], v[164:167], v[178:181], v[0:15]
	s_setprio 0
	s_and_b64 vcc, exec, s[12:13]
	s_barrier
	s_waitcnt vmcnt(7)
	ds_write_b128 v195, v[128:131]
	s_waitcnt vmcnt(6)
	ds_write_b128 v196, v[132:135]
	s_cbranch_vccnz .LBB0_751
	global_load_dwordx4 v[128:131], v[188:189], off
	global_load_dwordx4 v[132:135], v[186:187], off

; DI int otid() { int t = threadIdx.x; asm volatile("" : "+v"(t)); return t; }
; template <bool trans>
; DI void gemm_core(const GTile& tl, const GTile& nx, bool has_next  , bool chain  , bool pre, u32x4 (&ra)[4], u32x4 (&rb)[4], char* smem, f32x16 (&acc)[2][4]) {
;   const bf16_t* __restrict__ A = tl.A; const bf16_t* __restrict__ Bt = tl.Bt; const int lda = tl.lda, ldb = tl.ldb, K = tl.K, m0 = tl.m0, n0 = tl.n0;
;   bf16_t* lds = (bf16_t*)smem;
;   const int tid = otid(), lane = tid & 63, w = __builtin_amdgcn_readfirstlane(tid >> 6), wm = w >> 2, wn = w & 3, l32 = lane & 31, g = lane >> 5;
; #pragma unroll
;   for (int a = 0; a < 2; ++a)
; #pragma unroll
;     for (int b = 0; b < 4; ++b)
; #pragma unroll
;       for (int r = 0; r < 16; ++r) acc[a][b][r] = 0.f;
;   const int lrow = tid >> 3, kc = tid & 7;
;   const unsigned aoff = (unsigned)(lrow * lda + kc * 8) * 2u, boff = (unsigned)(lrow * ldb + kc * 8) * 2u;
;   const char* ag = (const char*)(A + (size_t)m0 * lda);
;   const char* bg = (const char*)(Bt + (size_t)n0 * ldb);
;   const unsigned aoffn = (unsigned)(lrow * nx.lda + kc * 8) * 2u, boffn = (unsigned)(lrow * nx.ldb + kc * 8) * 2u;
;   const char* agn = (const char*)(nx.A + (size_t)nx.m0 * nx.lda);
;   const char* bgn = (const char*)(nx.Bt + (size_t)nx.n0 * nx.ldb);
;     ...
;   const int nk = K / 64;
;   if (!pre) { G_LOAD(0); G_STORE(0); G_LOAD(1); }
;   for (int kt = 0; kt < nk; ++kt) {
;     __syncthreads();
;     G_COMPUTE(kt & 1, kt);
;   }
.LBB0_882:
	v_lshl_add_u64 v[190:191], s[2:3], 0, v[192:193]
	v_lshl_add_u64 v[188:189], s[16:17], 0, v[192:193]
	s_waitcnt lgkmcnt(0)
	s_barrier
	global_load_dwordx4 v[218:221], v[190:191], off offset:256
	global_load_dwordx4 v[222:225], v[188:189], off offset:256
	s_lshr_b32 s3, s33, 1
	s_and_b32 s2, s33, 0xc0
	v_and_b32_e32 v10, 31, v8
	s_and_b32 s3, s3, 0xfffff80
	v_or_b32_e32 v12, s3, v10
	v_or_b32_e32 v10, s2, v10
	v_add3_u32 v215, 16, v11, v9
	v_lshrrev_b32_e32 v8, 1, v8
	v_mul_u32_u24_e32 v208, 0x90, v10
	v_and_b32_e32 v242, 16, v8
	v_add_u32_e32 v209, 0x12000, v215
	v_mul_lo_u32 v205, v12, s54
	v_add3_u32 v204, 16, v208, v242
	v_add_u32_e32 v210, 0x1b000, v215
	ds_write_b128 v209, v[0:3]
	s_waitcnt vmcnt(5)
	ds_write_b128 v210, v[4:7]
	v_add3_u32 v192, 16, v205, v242
	ds_read_b128 v[0:3], v204 offset:36864
	ds_read_b128 v[4:7], v204 offset:41472
	ds_read_b128 v[8:11], v192
	ds_read_b128 v[12:15], v192 offset:4608
	v_lshl_add_u64 v[184:185], v[190:191], 0, s[14:15]
	v_lshl_add_u64 v[186:187], v[188:189], 0, s[14:15]
	v_lshl_add_u64 v[194:195], v[190:191], 0, s[12:13]
	v_lshl_add_u64 v[196:197], v[188:189], 0, s[12:13]
	s_setprio 1
	s_waitcnt lgkmcnt(1)
	v_mfma_f32_32x32x16_bf16 v[112:127], v[8:11], v[0:3], 0
	v_mfma_f32_32x32x16_bf16 v[48:63], v[8:11], v[4:7], 0
	s_waitcnt lgkmcnt(0)
	v_mfma_f32_32x32x16_bf16 v[96:111], v[12:15], v[0:3], 0
	v_mfma_f32_32x32x16_bf16 v[32:47], v[12:15], v[4:7], 0
	ds_read_b128 v[8:11], v192 offset:9216
	ds_read_b128 v[12:15], v192 offset:13824
	s_waitcnt lgkmcnt(1)
	v_mfma_f32_32x32x16_bf16 v[80:95], v[8:11], v[0:3], 0
	v_mfma_f32_32x32x16_bf16 v[16:31], v[8:11], v[4:7], 0
	s_waitcnt lgkmcnt(0)
	v_mfma_f32_32x32x16_bf16 v[64:79], v[12:15], v[0:3], 0
	v_mfma_f32_32x32x16_bf16 v[0:15], v[12:15], v[4:7], 0
	s_setprio 0
	global_load_dwordx4 v[226:229], v[194:195], off offset:256
	global_load_dwordx4 v[230:233], v[196:197], off offset:256
	v_add_u32_e32 v212, 0x14400, v215
	v_add_u32_e32 v211, 0x1d400, v215
	ds_write_b128 v212, v[176:179]
	s_waitcnt vmcnt(6)
	ds_write_b128 v211, v[180:183]
	ds_read_b128 v[176:179], v204 offset:36896
	ds_read_b128 v[180:183], v204 offset:41504
	ds_read_b128 v[198:201], v192 offset:32
	ds_read_b128 v[234:237], v192 offset:4640
	s_setprio 1
	s_waitcnt lgkmcnt(1)
	v_mfma_f32_32x32x16_bf16 v[112:127], v[198:201], v[176:179], v[112:127]
	v_mfma_f32_32x32x16_bf16 v[48:63], v[198:201], v[180:183], v[48:63]
	s_waitcnt lgkmcnt(0)
	v_mfma_f32_32x32x16_bf16 v[96:111], v[234:237], v[176:179], v[96:111]
	v_mfma_f32_32x32x16_bf16 v[32:47], v[234:237], v[180:183], v[32:47]
	ds_read_b128 v[198:201], v192 offset:9248
	ds_read_b128 v[234:237], v192 offset:13856
	s_waitcnt lgkmcnt(1)
	v_mfma_f32_32x32x16_bf16 v[80:95], v[198:201], v[176:179], v[80:95]
	v_mfma_f32_32x32x16_bf16 v[16:31], v[198:201], v[180:183], v[16:31]
	s_waitcnt lgkmcnt(0)
	v_mfma_f32_32x32x16_bf16 v[64:79], v[234:237], v[176:179], v[64:79]
	v_mfma_f32_32x32x16_bf16 v[0:15], v[234:237], v[180:183], v[0:15]
	s_setprio 0
	global_load_dwordx4 v[176:179], v[184:185], off offset:256
	global_load_dwordx4 v[180:183], v[186:187], off offset:256
	v_add_u32_e32 v214, 0x16800, v215
	v_add_u32_e32 v213, 0x1f800, v215
	ds_write_b128 v214, v[168:171]
	s_waitcnt vmcnt(7)
	ds_write_b128 v213, v[172:175]
	ds_read_b128 v[168:171], v204 offset:36928
	ds_read_b128 v[172:175], v204 offset:41536
	ds_read_b128 v[198:201], v192 offset:64
	ds_read_b128 v[234:237], v192 offset:4672
	s_setprio 1
	s_waitcnt lgkmcnt(1)
	v_mfma_f32_32x32x16_bf16 v[112:127], v[198:201], v[168:171], v[112:127]
	v_mfma_f32_32x32x16_bf16 v[48:63], v[198:201], v[172:175], v[48:63]
	s_waitcnt lgkmcnt(0)
	v_mfma_f32_32x32x16_bf16 v[96:111], v[234:237], v[168:171], v[96:111]
	v_mfma_f32_32x32x16_bf16 v[32:47], v[234:237], v[172:175], v[32:47]
	ds_read_b128 v[198:201], v192 offset:9280
	ds_read_b128 v[234:237], v192 offset:13888
	s_waitcnt lgkmcnt(1)
	v_mfma_f32_32x32x16_bf16 v[80:95], v[198:201], v[168:171], v[80:95]
	v_mfma_f32_32x32x16_bf16 v[16:31], v[198:201], v[172:175], v[16:31]
	s_waitcnt lgkmcnt(0)
	v_mfma_f32_32x32x16_bf16 v[64:79], v[234:237], v[168:171], v[64:79]
	v_mfma_f32_32x32x16_bf16 v[0:15], v[234:237], v[172:175], v[0:15]
	s_setprio 0
	v_add_co_u32_e32 v198, vcc, s53, v190
	v_add_u32_e32 v217, 0x18c00, v215
	s_nop 0
	v_addc_co_u32_e32 v199, vcc, 0, v191, vcc
	v_add_co_u32_e32 v200, vcc, s53, v188
	v_add_u32_e32 v216, 0x21c00, v215
	s_nop 0
	v_addc_co_u32_e32 v201, vcc, 0, v189, vcc
	global_load_dwordx4 v[168:171], v[198:199], off offset:256
	global_load_dwordx4 v[172:175], v[200:201], off offset:256
	ds_write_b128 v217, v[160:163]
	s_waitcnt vmcnt(8)
	ds_write_b128 v216, v[164:167]
	ds_read_b128 v[160:163], v204 offset:36960
	ds_read_b128 v[164:167], v204 offset:41568
	ds_read_b128 v[234:237], v192 offset:96
	ds_read_b128 v[238:241], v192 offset:4704
	s_setprio 1
	s_waitcnt lgkmcnt(1)
	v_mfma_f32_32x32x16_bf16 v[112:127], v[234:237], v[160:163], v[112:127]
	v_mfma_f32_32x32x16_bf16 v[48:63], v[234:237], v[164:167], v[48:63]
	s_waitcnt lgkmcnt(0)
	v_mfma_f32_32x32x16_bf16 v[96:111], v[238:241], v[160:163], v[96:111]
	v_mfma_f32_32x32x16_bf16 v[32:47], v[238:241], v[164:167], v[32:47]
	ds_read_b128 v[234:237], v192 offset:9312
	ds_read_b128 v[238:241], v192 offset:13920
	s_waitcnt lgkmcnt(1)
	v_mfma_f32_32x32x16_bf16 v[80:95], v[234:237], v[160:163], v[80:95]
	v_mfma_f32_32x32x16_bf16 v[16:31], v[234:237], v[164:167], v[16:31]
	s_waitcnt lgkmcnt(0)
	v_mfma_f32_32x32x16_bf16 v[64:79], v[238:241], v[160:163], v[64:79]
	v_mfma_f32_32x32x16_bf16 v[0:15], v[238:241], v[164:167], v[0:15]
	s_setprio 0
	global_load_dwordx4 v[160:163], v[190:191], off offset:384
	global_load_dwordx4 v[164:167], v[188:189], off offset:384
	s_barrier
; template <bool trans>
; DI void gemm_core(const GTile& tl, const GTile& nx, bool has_next  , bool chain  , bool pre, u32x4 (&ra)[4], u32x4 (&rb)[4], char* smem, f32x16 (&acc)[2][4]) {
;     ...
;   const int nk = K / 64;
;   if (!pre) { G_LOAD(0); G_STORE(0); G_LOAD(1); }
;   for (int kt = 0; kt < nk; ++kt) {
;     __syncthreads();
;     G_COMPUTE(kt & 1, kt);
;   }
	s_add_i32 s2, 16, 0x12000
	v_add3_u32 v205, s2, v205, v242
	s_add_i32 s2, 16, 0x1b000
	v_add3_u32 v208, s2, v208, v242
	s_waitcnt vmcnt(9)
	ds_write_b128 v215, v[218:221]
	s_waitcnt vmcnt(8)
	ds_write_b128 v215, v[222:225] offset:36864
	ds_read_b128 v[218:221], v208
	ds_read_b128 v[222:225], v208 offset:4608
	ds_read_b128 v[234:237], v205
	ds_read_b128 v[238:241], v205 offset:4608
	s_setprio 1
	s_waitcnt lgkmcnt(1)
	v_mfma_f32_32x32x16_bf16 v[112:127], v[234:237], v[218:221], v[112:127]
	v_mfma_f32_32x32x16_bf16 v[48:63], v[234:237], v[222:225], v[48:63]
	s_waitcnt lgkmcnt(0)
	v_mfma_f32_32x32x16_bf16 v[96:111], v[238:241], v[218:221], v[96:111]
	v_mfma_f32_32x32x16_bf16 v[32:47], v[238:241], v[222:225], v[32:47]
	ds_read_b128 v[234:237], v205 offset:9216
	ds_read_b128 v[238:241], v205 offset:13824
	s_waitcnt lgkmcnt(1)
	v_mfma_f32_32x32x16_bf16 v[80:95], v[234:237], v[218:221], v[80:95]
	v_mfma_f32_32x32x16_bf16 v[16:31], v[234:237], v[222:225], v[16:31]
	s_waitcnt lgkmcnt(0)
	v_mfma_f32_32x32x16_bf16 v[64:79], v[238:241], v[218:221], v[64:79]
	v_mfma_f32_32x32x16_bf16 v[0:15], v[238:241], v[222:225], v[0:15]
	s_setprio 0
	global_load_dwordx4 v[218:221], v[194:195], off offset:384
	global_load_dwordx4 v[222:225], v[196:197], off offset:384
	s_waitcnt vmcnt(9)
	ds_write_b128 v215, v[226:229] offset:9216
	s_waitcnt vmcnt(8)
	ds_write_b128 v215, v[230:233] offset:46080
	ds_read_b128 v[226:229], v208 offset:32
	ds_read_b128 v[230:233], v208 offset:4640
	ds_read_b128 v[234:237], v205 offset:32
	ds_read_b128 v[238:241], v205 offset:4640
	s_setprio 1
	s_waitcnt lgkmcnt(1)
	v_mfma_f32_32x32x16_bf16 v[112:127], v[234:237], v[226:229], v[112:127]
	v_mfma_f32_32x32x16_bf16 v[48:63], v[234:237], v[230:233], v[48:63]
	s_waitcnt lgkmcnt(0)
	v_mfma_f32_32x32x16_bf16 v[96:111], v[238:241], v[226:229], v[96:111]
	v_mfma_f32_32x32x16_bf16 v[32:47], v[238:241], v[230:233], v[32:47]
	ds_read_b128 v[234:237], v205 offset:9248
	ds_read_b128 v[238:241], v205 offset:13856
	s_waitcnt lgkmcnt(1)
	v_mfma_f32_32x32x16_bf16 v[80:95], v[234:237], v[226:229], v[80:95]
	v_mfma_f32_32x32x16_bf16 v[16:31], v[234:237], v[230:233], v[16:31]
	s_waitcnt lgkmcnt(0)
	v_mfma_f32_32x32x16_bf16 v[64:79], v[238:241], v[226:229], v[64:79]
	v_mfma_f32_32x32x16_bf16 v[0:15], v[238:241], v[230:233], v[0:15]
	s_setprio 0
	global_load_dwordx4 v[226:229], v[184:185], off offset:384
	global_load_dwordx4 v[230:233], v[186:187], off offset:384
	s_waitcnt vmcnt(9)
	ds_write_b128 v215, v[176:179] offset:18432
	s_waitcnt vmcnt(8)
	ds_write_b128 v215, v[180:183] offset:55296
	ds_read_b128 v[176:179], v208 offset:64
	ds_read_b128 v[180:183], v208 offset:4672
	ds_read_b128 v[234:237], v205 offset:64
	ds_read_b128 v[238:241], v205 offset:4672
	s_setprio 1
	s_waitcnt lgkmcnt(1)
	v_mfma_f32_32x32x16_bf16 v[112:127], v[234:237], v[176:179], v[112:127]
	v_mfma_f32_32x32x16_bf16 v[48:63], v[234:237], v[180:183], v[48:63]
	s_waitcnt lgkmcnt(0)
	v_mfma_f32_32x32x16_bf16 v[96:111], v[238:241], v[176:179], v[96:111]
	v_mfma_f32_32x32x16_bf16 v[32:47], v[238:241], v[180:183], v[32:47]
	ds_read_b128 v[234:237], v205 offset:9280
	ds_read_b128 v[238:241], v205 offset:13888
	s_waitcnt lgkmcnt(1)
	v_mfma_f32_32x32x16_bf16 v[80:95], v[234:237], v[176:179], v[80:95]
	v_mfma_f32_32x32x16_bf16 v[16:31], v[234:237], v[180:183], v[16:31]
	s_waitcnt lgkmcnt(0)
	v_mfma_f32_32x32x16_bf16 v[64:79], v[238:241], v[176:179], v[64:79]
	v_mfma_f32_32x32x16_bf16 v[0:15], v[238:241], v[180:183], v[0:15]
	s_setprio 0
	global_load_dwordx4 v[176:179], v[198:199], off offset:384
	global_load_dwordx4 v[180:183], v[200:201], off offset:384
	s_waitcnt vmcnt(9)
	ds_write_b128 v215, v[168:171] offset:27648
	s_waitcnt vmcnt(8)
	ds_write_b128 v215, v[172:175] offset:64512
	ds_read_b128 v[168:171], v208 offset:96
	ds_read_b128 v[172:175], v208 offset:4704
	ds_read_b128 v[234:237], v205 offset:96
	ds_read_b128 v[238:241], v205 offset:4704
	s_setprio 1
	s_waitcnt lgkmcnt(1)
	v_mfma_f32_32x32x16_bf16 v[112:127], v[234:237], v[168:171], v[112:127]
	v_mfma_f32_32x32x16_bf16 v[48:63], v[234:237], v[172:175], v[48:63]
	s_waitcnt lgkmcnt(0)
	v_mfma_f32_32x32x16_bf16 v[96:111], v[238:241], v[168:171], v[96:111]
	v_mfma_f32_32x32x16_bf16 v[32:47], v[238:241], v[172:175], v[32:47]
	ds_read_b128 v[234:237], v205 offset:9312
	ds_read_b128 v[238:241], v205 offset:13920
	s_waitcnt lgkmcnt(1)
	v_mfma_f32_32x32x16_bf16 v[80:95], v[234:237], v[168:171], v[80:95]
	v_mfma_f32_32x32x16_bf16 v[16:31], v[234:237], v[172:175], v[16:31]
	s_waitcnt lgkmcnt(0)
	v_mfma_f32_32x32x16_bf16 v[64:79], v[238:241], v[168:171], v[64:79]
	v_mfma_f32_32x32x16_bf16 v[0:15], v[238:241], v[172:175], v[0:15]
	s_setprio 0
	global_load_dwordx4 v[168:171], v[190:191], off offset:512
	global_load_dwordx4 v[172:175], v[188:189], off offset:512
	s_barrier
; template <bool trans>
; DI void gemm_core(const GTile& tl, const GTile& nx, bool has_next  , bool chain  , bool pre, u32x4 (&ra)[4], u32x4 (&rb)[4], char* smem, f32x16 (&acc)[2][4]) {
;     ...
;   const int nk = K / 64;
;   if (!pre) { G_LOAD(0); G_STORE(0); G_LOAD(1); }
;   for (int kt = 0; kt < nk; ++kt) {
;     __syncthreads();
;     G_COMPUTE(kt & 1, kt);
;   }
	s_waitcnt vmcnt(9)
	ds_write_b128 v209, v[160:163]
	s_waitcnt vmcnt(8)
	ds_write_b128 v210, v[164:167]
	ds_read_b128 v[160:163], v204 offset:36864
	ds_read_b128 v[164:167], v204 offset:41472
	ds_read_b128 v[234:237], v192
	ds_read_b128 v[238:241], v192 offset:4608
	s_setprio 1
	s_waitcnt lgkmcnt(1)
	v_mfma_f32_32x32x16_bf16 v[112:127], v[234:237], v[160:163], v[112:127]
	v_mfma_f32_32x32x16_bf16 v[48:63], v[234:237], v[164:167], v[48:63]
	s_waitcnt lgkmcnt(0)
	v_mfma_f32_32x32x16_bf16 v[96:111], v[238:241], v[160:163], v[96:111]
	v_mfma_f32_32x32x16_bf16 v[32:47], v[238:241], v[164:167], v[32:47]
	ds_read_b128 v[234:237], v192 offset:9216
	ds_read_b128 v[238:241], v192 offset:13824
	s_waitcnt vmcnt(7)
	ds_write_b128 v212, v[218:221]
	s_waitcnt vmcnt(6)
	ds_write_b128 v211, v[222:225]
	ds_read_b128 v[218:221], v204 offset:36896
	ds_read_b128 v[222:225], v204 offset:41504
	s_waitcnt lgkmcnt(5)
	v_mfma_f32_32x32x16_bf16 v[80:95], v[234:237], v[160:163], v[80:95]
	v_mfma_f32_32x32x16_bf16 v[16:31], v[234:237], v[164:167], v[16:31]
	ds_read_b128 v[234:237], v192 offset:32
	s_waitcnt lgkmcnt(5)
	v_mfma_f32_32x32x16_bf16 v[64:79], v[238:241], v[160:163], v[64:79]
	v_mfma_f32_32x32x16_bf16 v[0:15], v[238:241], v[164:167], v[0:15]
	ds_read_b128 v[238:241], v192 offset:4640
	s_setprio 0
	global_load_dwordx4 v[160:163], v[194:195], off offset:512
	global_load_dwordx4 v[164:167], v[196:197], off offset:512
	s_setprio 1
	s_waitcnt lgkmcnt(1)
	v_mfma_f32_32x32x16_bf16 v[112:127], v[234:237], v[218:221], v[112:127]
	v_mfma_f32_32x32x16_bf16 v[48:63], v[234:237], v[222:225], v[48:63]
	s_waitcnt lgkmcnt(0)
	v_mfma_f32_32x32x16_bf16 v[96:111], v[238:241], v[218:221], v[96:111]
	v_mfma_f32_32x32x16_bf16 v[32:47], v[238:241], v[222:225], v[32:47]
	ds_read_b128 v[234:237], v192 offset:9248
	ds_read_b128 v[238:241], v192 offset:13856
	s_waitcnt vmcnt(7)
	ds_write_b128 v214, v[226:229]
	s_waitcnt vmcnt(6)
	ds_write_b128 v213, v[230:233]
	ds_read_b128 v[226:229], v204 offset:36928
	ds_read_b128 v[230:233], v204 offset:41536
	s_waitcnt lgkmcnt(5)
	v_mfma_f32_32x32x16_bf16 v[80:95], v[234:237], v[218:221], v[80:95]
	v_mfma_f32_32x32x16_bf16 v[16:31], v[234:237], v[222:225], v[16:31]
	ds_read_b128 v[234:237], v192 offset:64
	s_waitcnt lgkmcnt(5)
	v_mfma_f32_32x32x16_bf16 v[64:79], v[238:241], v[218:221], v[64:79]
	v_mfma_f32_32x32x16_bf16 v[0:15], v[238:241], v[222:225], v[0:15]
	ds_read_b128 v[238:241], v192 offset:4672
	s_setprio 0
	global_load_dwordx4 v[218:221], v[184:185], off offset:512
	global_load_dwordx4 v[222:225], v[186:187], off offset:512
	s_setprio 1
	s_waitcnt lgkmcnt(1)
	v_mfma_f32_32x32x16_bf16 v[112:127], v[234:237], v[226:229], v[112:127]
	v_mfma_f32_32x32x16_bf16 v[48:63], v[234:237], v[230:233], v[48:63]
	s_waitcnt lgkmcnt(0)
	v_mfma_f32_32x32x16_bf16 v[96:111], v[238:241], v[226:229], v[96:111]
	v_mfma_f32_32x32x16_bf16 v[32:47], v[238:241], v[230:233], v[32:47]
	ds_read_b128 v[234:237], v192 offset:9280
	ds_read_b128 v[238:241], v192 offset:13888
	s_waitcnt vmcnt(7)
	ds_write_b128 v217, v[176:179]
	s_waitcnt vmcnt(6)
	ds_write_b128 v216, v[180:183]
	ds_read_b128 v[176:179], v204 offset:36960
	ds_read_b128 v[180:183], v204 offset:41568
	s_waitcnt lgkmcnt(5)
	v_mfma_f32_32x32x16_bf16 v[80:95], v[234:237], v[226:229], v[80:95]
	v_mfma_f32_32x32x16_bf16 v[16:31], v[234:237], v[230:233], v[16:31]
	ds_read_b128 v[234:237], v192 offset:96
	s_waitcnt lgkmcnt(5)
	v_mfma_f32_32x32x16_bf16 v[64:79], v[238:241], v[226:229], v[64:79]
	v_mfma_f32_32x32x16_bf16 v[0:15], v[238:241], v[230:233], v[0:15]
	ds_read_b128 v[238:241], v192 offset:4704
	s_setprio 0
	global_load_dwordx4 v[226:229], v[198:199], off offset:512
	global_load_dwordx4 v[230:233], v[200:201], off offset:512
	s_setprio 1
	s_waitcnt lgkmcnt(1)
	v_mfma_f32_32x32x16_bf16 v[112:127], v[234:237], v[176:179], v[112:127]
	v_mfma_f32_32x32x16_bf16 v[48:63], v[234:237], v[180:183], v[48:63]
	s_waitcnt lgkmcnt(0)
	v_mfma_f32_32x32x16_bf16 v[96:111], v[238:241], v[176:179], v[96:111]
	v_mfma_f32_32x32x16_bf16 v[32:47], v[238:241], v[180:183], v[32:47]
	ds_read_b128 v[234:237], v192 offset:9312
	ds_read_b128 v[238:241], v192 offset:13920
	s_waitcnt lgkmcnt(1)
	v_mfma_f32_32x32x16_bf16 v[80:95], v[234:237], v[176:179], v[80:95]
	v_mfma_f32_32x32x16_bf16 v[16:31], v[234:237], v[180:183], v[16:31]
	s_waitcnt lgkmcnt(0)
	v_mfma_f32_32x32x16_bf16 v[64:79], v[238:241], v[176:179], v[64:79]
	v_mfma_f32_32x32x16_bf16 v[0:15], v[238:241], v[180:183], v[0:15]
	s_setprio 0
	global_load_dwordx4 v[176:179], v[190:191], off offset:640
	global_load_dwordx4 v[180:183], v[188:189], off offset:640
	s_barrier
; template <bool trans>
; DI void gemm_core(const GTile& tl, const GTile& nx, bool has_next  , bool chain  , bool pre, u32x4 (&ra)[4], u32x4 (&rb)[4], char* smem, f32x16 (&acc)[2][4]) {
;     ...
;   const int nk = K / 64;
;   if (!pre) { G_LOAD(0); G_STORE(0); G_LOAD(1); }
;   for (int kt = 0; kt < nk; ++kt) {
;     __syncthreads();
;     G_COMPUTE(kt & 1, kt);
;   }
	s_waitcnt vmcnt(9)
	ds_write_b128 v215, v[168:171]
	s_waitcnt vmcnt(8)
	ds_write_b128 v215, v[172:175] offset:36864
	ds_read_b128 v[168:171], v208
	ds_read_b128 v[172:175], v208 offset:4608
	ds_read_b128 v[234:237], v205
	ds_read_b128 v[238:241], v205 offset:4608
	s_setprio 1
	s_waitcnt lgkmcnt(1)
	v_mfma_f32_32x32x16_bf16 v[112:127], v[234:237], v[168:171], v[112:127]
	v_mfma_f32_32x32x16_bf16 v[48:63], v[234:237], v[172:175], v[48:63]
	s_waitcnt lgkmcnt(0)
	v_mfma_f32_32x32x16_bf16 v[96:111], v[238:241], v[168:171], v[96:111]
	v_mfma_f32_32x32x16_bf16 v[32:47], v[238:241], v[172:175], v[32:47]
	ds_read_b128 v[234:237], v205 offset:9216
	ds_read_b128 v[238:241], v205 offset:13824
	s_waitcnt vmcnt(7)
	ds_write_b128 v215, v[160:163] offset:9216
	s_waitcnt vmcnt(6)
	ds_write_b128 v215, v[164:167] offset:46080
	ds_read_b128 v[160:163], v208 offset:32
	ds_read_b128 v[164:167], v208 offset:4640
	s_waitcnt lgkmcnt(5)
	v_mfma_f32_32x32x16_bf16 v[80:95], v[234:237], v[168:171], v[80:95]
	v_mfma_f32_32x32x16_bf16 v[16:31], v[234:237], v[172:175], v[16:31]
	ds_read_b128 v[234:237], v205 offset:32
	s_waitcnt lgkmcnt(5)
	v_mfma_f32_32x32x16_bf16 v[64:79], v[238:241], v[168:171], v[64:79]
	v_mfma_f32_32x32x16_bf16 v[0:15], v[238:241], v[172:175], v[0:15]
	ds_read_b128 v[238:241], v205 offset:4640
	s_setprio 0
	global_load_dwordx4 v[168:171], v[194:195], off offset:640
	global_load_dwordx4 v[172:175], v[196:197], off offset:640
	s_setprio 1
	s_waitcnt lgkmcnt(1)
	v_mfma_f32_32x32x16_bf16 v[112:127], v[234:237], v[160:163], v[112:127]
	v_mfma_f32_32x32x16_bf16 v[48:63], v[234:237], v[164:167], v[48:63]
	s_waitcnt lgkmcnt(0)
	v_mfma_f32_32x32x16_bf16 v[96:111], v[238:241], v[160:163], v[96:111]
	v_mfma_f32_32x32x16_bf16 v[32:47], v[238:241], v[164:167], v[32:47]
	ds_read_b128 v[234:237], v205 offset:9248
	ds_read_b128 v[238:241], v205 offset:13856
	s_waitcnt vmcnt(7)
	ds_write_b128 v215, v[218:221] offset:18432
	s_waitcnt vmcnt(6)
	ds_write_b128 v215, v[222:225] offset:55296
	ds_read_b128 v[218:221], v208 offset:64
	ds_read_b128 v[222:225], v208 offset:4672
	s_waitcnt lgkmcnt(5)
	v_mfma_f32_32x32x16_bf16 v[80:95], v[234:237], v[160:163], v[80:95]
	v_mfma_f32_32x32x16_bf16 v[16:31], v[234:237], v[164:167], v[16:31]
	ds_read_b128 v[234:237], v205 offset:64
	s_waitcnt lgkmcnt(5)
	v_mfma_f32_32x32x16_bf16 v[64:79], v[238:241], v[160:163], v[64:79]
	v_mfma_f32_32x32x16_bf16 v[0:15], v[238:241], v[164:167], v[0:15]
	ds_read_b128 v[238:241], v205 offset:4672
	s_setprio 0
	global_load_dwordx4 v[160:163], v[184:185], off offset:640
	global_load_dwordx4 v[164:167], v[186:187], off offset:640
	s_setprio 1
	s_waitcnt lgkmcnt(1)
	v_mfma_f32_32x32x16_bf16 v[112:127], v[234:237], v[218:221], v[112:127]
	v_mfma_f32_32x32x16_bf16 v[48:63], v[234:237], v[222:225], v[48:63]
	s_waitcnt lgkmcnt(0)
	v_mfma_f32_32x32x16_bf16 v[96:111], v[238:241], v[218:221], v[96:111]
	v_mfma_f32_32x32x16_bf16 v[32:47], v[238:241], v[222:225], v[32:47]
	ds_read_b128 v[234:237], v205 offset:9280
	ds_read_b128 v[238:241], v205 offset:13888
	s_waitcnt vmcnt(7)
	ds_write_b128 v215, v[226:229] offset:27648
	s_waitcnt vmcnt(6)
	ds_write_b128 v215, v[230:233] offset:64512
	ds_read_b128 v[226:229], v208 offset:96
	ds_read_b128 v[230:233], v208 offset:4704
	s_waitcnt lgkmcnt(5)
	v_mfma_f32_32x32x16_bf16 v[80:95], v[234:237], v[218:221], v[80:95]
	v_mfma_f32_32x32x16_bf16 v[16:31], v[234:237], v[222:225], v[16:31]
	ds_read_b128 v[234:237], v205 offset:96
	s_waitcnt lgkmcnt(5)
	v_mfma_f32_32x32x16_bf16 v[64:79], v[238:241], v[218:221], v[64:79]
	v_mfma_f32_32x32x16_bf16 v[0:15], v[238:241], v[222:225], v[0:15]
	ds_read_b128 v[238:241], v205 offset:4704
	s_setprio 0
	global_load_dwordx4 v[218:221], v[198:199], off offset:640
	global_load_dwordx4 v[222:225], v[200:201], off offset:640
	s_setprio 1
	s_waitcnt lgkmcnt(1)
	v_mfma_f32_32x32x16_bf16 v[112:127], v[234:237], v[226:229], v[112:127]
	v_mfma_f32_32x32x16_bf16 v[48:63], v[234:237], v[230:233], v[48:63]
	s_waitcnt lgkmcnt(0)
	v_mfma_f32_32x32x16_bf16 v[96:111], v[238:241], v[226:229], v[96:111]
	v_mfma_f32_32x32x16_bf16 v[32:47], v[238:241], v[230:233], v[32:47]
	ds_read_b128 v[234:237], v205 offset:9312
	ds_read_b128 v[238:241], v205 offset:13920
	s_waitcnt lgkmcnt(1)
	v_mfma_f32_32x32x16_bf16 v[80:95], v[234:237], v[226:229], v[80:95]
	v_mfma_f32_32x32x16_bf16 v[16:31], v[234:237], v[230:233], v[16:31]
	s_waitcnt lgkmcnt(0)
	v_mfma_f32_32x32x16_bf16 v[64:79], v[238:241], v[226:229], v[64:79]
	v_mfma_f32_32x32x16_bf16 v[0:15], v[238:241], v[230:233], v[0:15]
	s_setprio 0
	global_load_dwordx4 v[226:229], v[190:191], off offset:768
	global_load_dwordx4 v[230:233], v[188:189], off offset:768
	s_barrier
; template <bool trans>
; DI void gemm_core(const GTile& tl, const GTile& nx, bool has_next  , bool chain  , bool pre, u32x4 (&ra)[4], u32x4 (&rb)[4], char* smem, f32x16 (&acc)[2][4]) {
;     ...
;   const int nk = K / 64;
;   if (!pre) { G_LOAD(0); G_STORE(0); G_LOAD(1); }
;   for (int kt = 0; kt < nk; ++kt) {
;     __syncthreads();
;     G_COMPUTE(kt & 1, kt);
;   }
	s_waitcnt vmcnt(9)
	ds_write_b128 v209, v[176:179]
	s_waitcnt vmcnt(8)
	ds_write_b128 v210, v[180:183]
	ds_read_b128 v[176:179], v204 offset:36864
	ds_read_b128 v[180:183], v204 offset:41472
	ds_read_b128 v[234:237], v192
	ds_read_b128 v[238:241], v192 offset:4608
	s_setprio 1
	s_waitcnt lgkmcnt(1)
	v_mfma_f32_32x32x16_bf16 v[112:127], v[234:237], v[176:179], v[112:127]
	v_mfma_f32_32x32x16_bf16 v[48:63], v[234:237], v[180:183], v[48:63]
	s_waitcnt lgkmcnt(0)
	v_mfma_f32_32x32x16_bf16 v[96:111], v[238:241], v[176:179], v[96:111]
	v_mfma_f32_32x32x16_bf16 v[32:47], v[238:241], v[180:183], v[32:47]
	ds_read_b128 v[234:237], v192 offset:9216
	ds_read_b128 v[238:241], v192 offset:13824
	s_waitcnt vmcnt(7)
	ds_write_b128 v212, v[168:171]
	s_waitcnt vmcnt(6)
	ds_write_b128 v211, v[172:175]
	ds_read_b128 v[168:171], v204 offset:36896
	ds_read_b128 v[172:175], v204 offset:41504
	s_waitcnt lgkmcnt(5)
	v_mfma_f32_32x32x16_bf16 v[80:95], v[234:237], v[176:179], v[80:95]
	v_mfma_f32_32x32x16_bf16 v[16:31], v[234:237], v[180:183], v[16:31]
	ds_read_b128 v[234:237], v192 offset:32
	s_waitcnt lgkmcnt(5)
	v_mfma_f32_32x32x16_bf16 v[64:79], v[238:241], v[176:179], v[64:79]
	v_mfma_f32_32x32x16_bf16 v[0:15], v[238:241], v[180:183], v[0:15]
	ds_read_b128 v[238:241], v192 offset:4640
	s_setprio 0
	global_load_dwordx4 v[176:179], v[194:195], off offset:768
	global_load_dwordx4 v[180:183], v[196:197], off offset:768
	s_setprio 1
	s_waitcnt lgkmcnt(1)
	v_mfma_f32_32x32x16_bf16 v[112:127], v[234:237], v[168:171], v[112:127]
	v_mfma_f32_32x32x16_bf16 v[48:63], v[234:237], v[172:175], v[48:63]
	s_waitcnt lgkmcnt(0)
	v_mfma_f32_32x32x16_bf16 v[96:111], v[238:241], v[168:171], v[96:111]
	v_mfma_f32_32x32x16_bf16 v[32:47], v[238:241], v[172:175], v[32:47]
	ds_read_b128 v[234:237], v192 offset:9248
	ds_read_b128 v[238:241], v192 offset:13856
	s_waitcnt vmcnt(7)
	ds_write_b128 v214, v[160:163]
	s_waitcnt vmcnt(6)
	ds_write_b128 v213, v[164:167]
	ds_read_b128 v[160:163], v204 offset:36928
	ds_read_b128 v[164:167], v204 offset:41536
	s_waitcnt lgkmcnt(5)
	v_mfma_f32_32x32x16_bf16 v[80:95], v[234:237], v[168:171], v[80:95]
	v_mfma_f32_32x32x16_bf16 v[16:31], v[234:237], v[172:175], v[16:31]
	ds_read_b128 v[234:237], v192 offset:64
	s_waitcnt lgkmcnt(5)
	v_mfma_f32_32x32x16_bf16 v[64:79], v[238:241], v[168:171], v[64:79]
	v_mfma_f32_32x32x16_bf16 v[0:15], v[238:241], v[172:175], v[0:15]
	ds_read_b128 v[238:241], v192 offset:4672
	s_setprio 0
	global_load_dwordx4 v[168:171], v[184:185], off offset:768
	global_load_dwordx4 v[172:175], v[186:187], off offset:768
	s_setprio 1
	s_waitcnt lgkmcnt(1)
	v_mfma_f32_32x32x16_bf16 v[112:127], v[234:237], v[160:163], v[112:127]
	v_mfma_f32_32x32x16_bf16 v[48:63], v[234:237], v[164:167], v[48:63]
	s_waitcnt lgkmcnt(0)
	v_mfma_f32_32x32x16_bf16 v[96:111], v[238:241], v[160:163], v[96:111]
	v_mfma_f32_32x32x16_bf16 v[32:47], v[238:241], v[164:167], v[32:47]
	ds_read_b128 v[234:237], v192 offset:9280
	ds_read_b128 v[238:241], v192 offset:13888
	s_waitcnt vmcnt(7)
	ds_write_b128 v217, v[218:221]
	s_waitcnt vmcnt(6)
	ds_write_b128 v216, v[222:225]
	ds_read_b128 v[218:221], v204 offset:36960
	ds_read_b128 v[222:225], v204 offset:41568
	s_waitcnt lgkmcnt(5)
	v_mfma_f32_32x32x16_bf16 v[80:95], v[234:237], v[160:163], v[80:95]
	v_mfma_f32_32x32x16_bf16 v[16:31], v[234:237], v[164:167], v[16:31]
	ds_read_b128 v[234:237], v192 offset:96
	s_waitcnt lgkmcnt(5)
	v_mfma_f32_32x32x16_bf16 v[64:79], v[238:241], v[160:163], v[64:79]
	v_mfma_f32_32x32x16_bf16 v[0:15], v[238:241], v[164:167], v[0:15]
	ds_read_b128 v[238:241], v192 offset:4704
	s_setprio 0
	global_load_dwordx4 v[160:163], v[198:199], off offset:768
	global_load_dwordx4 v[164:167], v[200:201], off offset:768
	s_setprio 1
	s_waitcnt lgkmcnt(1)
	v_mfma_f32_32x32x16_bf16 v[112:127], v[234:237], v[218:221], v[112:127]
	v_mfma_f32_32x32x16_bf16 v[48:63], v[234:237], v[222:225], v[48:63]
	s_waitcnt lgkmcnt(0)
	v_mfma_f32_32x32x16_bf16 v[96:111], v[238:241], v[218:221], v[96:111]
	v_mfma_f32_32x32x16_bf16 v[32:47], v[238:241], v[222:225], v[32:47]
	ds_read_b128 v[234:237], v192 offset:9312
	ds_read_b128 v[238:241], v192 offset:13920
	s_waitcnt lgkmcnt(1)
	v_mfma_f32_32x32x16_bf16 v[80:95], v[234:237], v[218:221], v[80:95]
	v_mfma_f32_32x32x16_bf16 v[16:31], v[234:237], v[222:225], v[16:31]
	s_waitcnt lgkmcnt(0)
	v_mfma_f32_32x32x16_bf16 v[64:79], v[238:241], v[218:221], v[64:79]
	v_mfma_f32_32x32x16_bf16 v[0:15], v[238:241], v[222:225], v[0:15]
	s_setprio 0
	global_load_dwordx4 v[218:221], v[190:191], off offset:896
	global_load_dwordx4 v[222:225], v[188:189], off offset:896
	s_barrier
; template <bool trans>
; DI void gemm_core(const GTile& tl, const GTile& nx, bool has_next  , bool chain  , bool pre, u32x4 (&ra)[4], u32x4 (&rb)[4], char* smem, f32x16 (&acc)[2][4]) {
;     ...
;   const int nk = K / 64;
;   if (!pre) { G_LOAD(0); G_STORE(0); G_LOAD(1); }
;   for (int kt = 0; kt < nk; ++kt) {
;     __syncthreads();
;     G_COMPUTE(kt & 1, kt);
;   }
	s_waitcnt vmcnt(9)
	ds_write_b128 v215, v[226:229]
	s_waitcnt vmcnt(8)
	ds_write_b128 v215, v[230:233] offset:36864
	ds_read_b128 v[226:229], v208
	ds_read_b128 v[230:233], v208 offset:4608
	ds_read_b128 v[234:237], v205
	ds_read_b128 v[238:241], v205 offset:4608
	s_setprio 1
	s_waitcnt lgkmcnt(1)
	v_mfma_f32_32x32x16_bf16 v[112:127], v[234:237], v[226:229], v[112:127]
	v_mfma_f32_32x32x16_bf16 v[48:63], v[234:237], v[230:233], v[48:63]
	s_waitcnt lgkmcnt(0)
	v_mfma_f32_32x32x16_bf16 v[96:111], v[238:241], v[226:229], v[96:111]
	v_mfma_f32_32x32x16_bf16 v[32:47], v[238:241], v[230:233], v[32:47]
	ds_read_b128 v[234:237], v205 offset:9216
	ds_read_b128 v[238:241], v205 offset:13824
	s_waitcnt vmcnt(7)
	ds_write_b128 v215, v[176:179] offset:9216
	s_waitcnt vmcnt(6)
	ds_write_b128 v215, v[180:183] offset:46080
	ds_read_b128 v[176:179], v208 offset:32
	ds_read_b128 v[180:183], v208 offset:4640
	s_waitcnt lgkmcnt(5)
	v_mfma_f32_32x32x16_bf16 v[80:95], v[234:237], v[226:229], v[80:95]
	v_mfma_f32_32x32x16_bf16 v[16:31], v[234:237], v[230:233], v[16:31]
	ds_read_b128 v[234:237], v205 offset:32
	s_waitcnt lgkmcnt(5)
	v_mfma_f32_32x32x16_bf16 v[64:79], v[238:241], v[226:229], v[64:79]
	v_mfma_f32_32x32x16_bf16 v[0:15], v[238:241], v[230:233], v[0:15]
	ds_read_b128 v[238:241], v205 offset:4640
	s_setprio 0
	global_load_dwordx4 v[226:229], v[194:195], off offset:896
	global_load_dwordx4 v[230:233], v[196:197], off offset:896
	s_setprio 1
	s_waitcnt lgkmcnt(1)
	v_mfma_f32_32x32x16_bf16 v[112:127], v[234:237], v[176:179], v[112:127]
	v_mfma_f32_32x32x16_bf16 v[48:63], v[234:237], v[180:183], v[48:63]
	s_waitcnt lgkmcnt(0)
	v_mfma_f32_32x32x16_bf16 v[96:111], v[238:241], v[176:179], v[96:111]
	v_mfma_f32_32x32x16_bf16 v[32:47], v[238:241], v[180:183], v[32:47]
	ds_read_b128 v[234:237], v205 offset:9248
	ds_read_b128 v[238:241], v205 offset:13856
	s_waitcnt vmcnt(7)
	ds_write_b128 v215, v[168:171] offset:18432
	s_waitcnt vmcnt(6)
	ds_write_b128 v215, v[172:175] offset:55296
	ds_read_b128 v[168:171], v208 offset:64
	ds_read_b128 v[172:175], v208 offset:4672
	s_waitcnt lgkmcnt(5)
	v_mfma_f32_32x32x16_bf16 v[80:95], v[234:237], v[176:179], v[80:95]
	v_mfma_f32_32x32x16_bf16 v[16:31], v[234:237], v[180:183], v[16:31]
	ds_read_b128 v[234:237], v205 offset:64
	s_waitcnt lgkmcnt(5)
	v_mfma_f32_32x32x16_bf16 v[64:79], v[238:241], v[176:179], v[64:79]
	v_mfma_f32_32x32x16_bf16 v[0:15], v[238:241], v[180:183], v[0:15]
	ds_read_b128 v[238:241], v205 offset:4672
	s_setprio 0
	global_load_dwordx4 v[176:179], v[184:185], off offset:896
	global_load_dwordx4 v[180:183], v[186:187], off offset:896
	s_setprio 1
	s_waitcnt lgkmcnt(1)
	v_mfma_f32_32x32x16_bf16 v[112:127], v[234:237], v[168:171], v[112:127]
	v_mfma_f32_32x32x16_bf16 v[48:63], v[234:237], v[172:175], v[48:63]
	s_waitcnt lgkmcnt(0)
	v_mfma_f32_32x32x16_bf16 v[96:111], v[238:241], v[168:171], v[96:111]
	v_mfma_f32_32x32x16_bf16 v[32:47], v[238:241], v[172:175], v[32:47]
	ds_read_b128 v[234:237], v205 offset:9280
	ds_read_b128 v[238:241], v205 offset:13888
	s_waitcnt vmcnt(7)
	ds_write_b128 v215, v[160:163] offset:27648
	s_waitcnt vmcnt(6)
	ds_write_b128 v215, v[164:167] offset:64512
	ds_read_b128 v[160:163], v208 offset:96
	ds_read_b128 v[164:167], v208 offset:4704
	s_waitcnt lgkmcnt(5)
	v_mfma_f32_32x32x16_bf16 v[80:95], v[234:237], v[168:171], v[80:95]
	v_mfma_f32_32x32x16_bf16 v[16:31], v[234:237], v[172:175], v[16:31]
	ds_read_b128 v[234:237], v205 offset:96
	s_waitcnt lgkmcnt(5)
	v_mfma_f32_32x32x16_bf16 v[64:79], v[238:241], v[168:171], v[64:79]
	v_mfma_f32_32x32x16_bf16 v[0:15], v[238:241], v[172:175], v[0:15]
	ds_read_b128 v[238:241], v205 offset:4704
	s_setprio 0
	global_load_dwordx4 v[168:171], v[198:199], off offset:896
	global_load_dwordx4 v[172:175], v[200:201], off offset:896
	s_setprio 1
	s_waitcnt lgkmcnt(1)
	v_mfma_f32_32x32x16_bf16 v[112:127], v[234:237], v[160:163], v[112:127]
	v_mfma_f32_32x32x16_bf16 v[48:63], v[234:237], v[164:167], v[48:63]
	s_waitcnt lgkmcnt(0)
	v_mfma_f32_32x32x16_bf16 v[96:111], v[238:241], v[160:163], v[96:111]
	v_mfma_f32_32x32x16_bf16 v[32:47], v[238:241], v[164:167], v[32:47]
	ds_read_b128 v[234:237], v205 offset:9312
	ds_read_b128 v[238:241], v205 offset:13920
	s_waitcnt lgkmcnt(1)
	v_mfma_f32_32x32x16_bf16 v[80:95], v[234:237], v[160:163], v[80:95]
	v_mfma_f32_32x32x16_bf16 v[16:31], v[234:237], v[164:167], v[16:31]
	s_waitcnt lgkmcnt(0)
	v_mfma_f32_32x32x16_bf16 v[64:79], v[238:241], v[160:163], v[64:79]
	v_mfma_f32_32x32x16_bf16 v[0:15], v[238:241], v[164:167], v[0:15]
	s_setprio 0
	global_load_dwordx4 v[160:163], v[190:191], off offset:1024
	global_load_dwordx4 v[164:167], v[188:189], off offset:1024
	s_barrier
; template <bool trans>
; DI void gemm_core(const GTile& tl, const GTile& nx, bool has_next  , bool chain  , bool pre, u32x4 (&ra)[4], u32x4 (&rb)[4], char* smem, f32x16 (&acc)[2][4]) {
;     ...
;   const int nk = K / 64;
;   if (!pre) { G_LOAD(0); G_STORE(0); G_LOAD(1); }
;   for (int kt = 0; kt < nk; ++kt) {
;     __syncthreads();
;     G_COMPUTE(kt & 1, kt);
;   }
	s_waitcnt vmcnt(9)
	ds_write_b128 v209, v[218:221]
	s_waitcnt vmcnt(8)
	ds_write_b128 v210, v[222:225]
	ds_read_b128 v[218:221], v204 offset:36864
	ds_read_b128 v[222:225], v204 offset:41472
	ds_read_b128 v[234:237], v192
	ds_read_b128 v[238:241], v192 offset:4608
	s_setprio 1
	s_waitcnt lgkmcnt(1)
	v_mfma_f32_32x32x16_bf16 v[112:127], v[234:237], v[218:221], v[112:127]
	v_mfma_f32_32x32x16_bf16 v[48:63], v[234:237], v[222:225], v[48:63]
	s_waitcnt lgkmcnt(0)
	v_mfma_f32_32x32x16_bf16 v[96:111], v[238:241], v[218:221], v[96:111]
	v_mfma_f32_32x32x16_bf16 v[32:47], v[238:241], v[222:225], v[32:47]
	ds_read_b128 v[234:237], v192 offset:9216
	ds_read_b128 v[238:241], v192 offset:13824
	s_waitcnt vmcnt(7)
	ds_write_b128 v212, v[226:229]
	s_waitcnt vmcnt(6)
	ds_write_b128 v211, v[230:233]
	ds_read_b128 v[226:229], v204 offset:36896
	ds_read_b128 v[230:233], v204 offset:41504
	s_waitcnt lgkmcnt(5)
	v_mfma_f32_32x32x16_bf16 v[80:95], v[234:237], v[218:221], v[80:95]
	v_mfma_f32_32x32x16_bf16 v[16:31], v[234:237], v[222:225], v[16:31]
	ds_read_b128 v[234:237], v192 offset:32
	s_waitcnt lgkmcnt(5)
	v_mfma_f32_32x32x16_bf16 v[64:79], v[238:241], v[218:221], v[64:79]
	v_mfma_f32_32x32x16_bf16 v[0:15], v[238:241], v[222:225], v[0:15]
	ds_read_b128 v[238:241], v192 offset:4640
	s_setprio 0
	global_load_dwordx4 v[218:221], v[194:195], off offset:1024
	global_load_dwordx4 v[222:225], v[196:197], off offset:1024
	s_setprio 1
	s_waitcnt lgkmcnt(1)
	v_mfma_f32_32x32x16_bf16 v[112:127], v[234:237], v[226:229], v[112:127]
	v_mfma_f32_32x32x16_bf16 v[48:63], v[234:237], v[230:233], v[48:63]
	s_waitcnt lgkmcnt(0)
	v_mfma_f32_32x32x16_bf16 v[96:111], v[238:241], v[226:229], v[96:111]
	v_mfma_f32_32x32x16_bf16 v[32:47], v[238:241], v[230:233], v[32:47]
	ds_read_b128 v[234:237], v192 offset:9248
	ds_read_b128 v[238:241], v192 offset:13856
	s_waitcnt vmcnt(7)
	ds_write_b128 v214, v[176:179]
	s_waitcnt vmcnt(6)
	ds_write_b128 v213, v[180:183]
	ds_read_b128 v[176:179], v204 offset:36928
	ds_read_b128 v[180:183], v204 offset:41536
	s_waitcnt lgkmcnt(5)
	v_mfma_f32_32x32x16_bf16 v[80:95], v[234:237], v[226:229], v[80:95]
	v_mfma_f32_32x32x16_bf16 v[16:31], v[234:237], v[230:233], v[16:31]
	ds_read_b128 v[234:237], v192 offset:64
	s_waitcnt lgkmcnt(5)
	v_mfma_f32_32x32x16_bf16 v[64:79], v[238:241], v[226:229], v[64:79]
	v_mfma_f32_32x32x16_bf16 v[0:15], v[238:241], v[230:233], v[0:15]
	ds_read_b128 v[238:241], v192 offset:4672
	s_setprio 0
	global_load_dwordx4 v[226:229], v[184:185], off offset:1024
	global_load_dwordx4 v[230:233], v[186:187], off offset:1024
	s_setprio 1
	s_waitcnt lgkmcnt(1)
	v_mfma_f32_32x32x16_bf16 v[112:127], v[234:237], v[176:179], v[112:127]
	v_mfma_f32_32x32x16_bf16 v[48:63], v[234:237], v[180:183], v[48:63]
	s_waitcnt lgkmcnt(0)
	v_mfma_f32_32x32x16_bf16 v[96:111], v[238:241], v[176:179], v[96:111]
	v_mfma_f32_32x32x16_bf16 v[32:47], v[238:241], v[180:183], v[32:47]
	ds_read_b128 v[234:237], v192 offset:9280
	ds_read_b128 v[238:241], v192 offset:13888
	s_waitcnt vmcnt(7)
	ds_write_b128 v217, v[168:171]
	s_waitcnt vmcnt(6)
	ds_write_b128 v216, v[172:175]
	ds_read_b128 v[168:171], v204 offset:36960
	ds_read_b128 v[172:175], v204 offset:41568
	s_waitcnt lgkmcnt(5)
	v_mfma_f32_32x32x16_bf16 v[80:95], v[234:237], v[176:179], v[80:95]
	v_mfma_f32_32x32x16_bf16 v[16:31], v[234:237], v[180:183], v[16:31]
	ds_read_b128 v[234:237], v192 offset:96
	s_waitcnt lgkmcnt(5)
	v_mfma_f32_32x32x16_bf16 v[64:79], v[238:241], v[176:179], v[64:79]
	v_mfma_f32_32x32x16_bf16 v[0:15], v[238:241], v[180:183], v[0:15]
	ds_read_b128 v[238:241], v192 offset:4704
	s_setprio 0
	global_load_dwordx4 v[176:179], v[198:199], off offset:1024
	global_load_dwordx4 v[180:183], v[200:201], off offset:1024
	s_setprio 1
	s_waitcnt lgkmcnt(1)
	v_mfma_f32_32x32x16_bf16 v[112:127], v[234:237], v[168:171], v[112:127]
	v_mfma_f32_32x32x16_bf16 v[48:63], v[234:237], v[172:175], v[48:63]
	s_waitcnt lgkmcnt(0)
	v_mfma_f32_32x32x16_bf16 v[96:111], v[238:241], v[168:171], v[96:111]
	v_mfma_f32_32x32x16_bf16 v[32:47], v[238:241], v[172:175], v[32:47]
	ds_read_b128 v[234:237], v192 offset:9312
	ds_read_b128 v[238:241], v192 offset:13920
	s_waitcnt lgkmcnt(1)
	v_mfma_f32_32x32x16_bf16 v[80:95], v[234:237], v[168:171], v[80:95]
	v_mfma_f32_32x32x16_bf16 v[16:31], v[234:237], v[172:175], v[16:31]
	s_waitcnt lgkmcnt(0)
	v_mfma_f32_32x32x16_bf16 v[64:79], v[238:241], v[168:171], v[64:79]
	v_mfma_f32_32x32x16_bf16 v[0:15], v[238:241], v[172:175], v[0:15]
	s_setprio 0
	global_load_dwordx4 v[168:171], v[190:191], off offset:1152
	global_load_dwordx4 v[172:175], v[188:189], off offset:1152
	s_barrier
; template <bool trans>
; DI void gemm_core(const GTile& tl, const GTile& nx, bool has_next  , bool chain  , bool pre, u32x4 (&ra)[4], u32x4 (&rb)[4], char* smem, f32x16 (&acc)[2][4]) {
;     ...
;   const int nk = K / 64;
;   if (!pre) { G_LOAD(0); G_STORE(0); G_LOAD(1); }
;   for (int kt = 0; kt < nk; ++kt) {
;     __syncthreads();
;     G_COMPUTE(kt & 1, kt);
;   }
	s_waitcnt vmcnt(9)
	ds_write_b128 v215, v[160:163]
	s_waitcnt vmcnt(8)
	ds_write_b128 v215, v[164:167] offset:36864
	ds_read_b128 v[160:163], v208
	ds_read_b128 v[164:167], v208 offset:4608
	ds_read_b128 v[234:237], v205
	ds_read_b128 v[238:241], v205 offset:4608
	s_setprio 1
	s_waitcnt lgkmcnt(1)
	v_mfma_f32_32x32x16_bf16 v[112:127], v[234:237], v[160:163], v[112:127]
	v_mfma_f32_32x32x16_bf16 v[48:63], v[234:237], v[164:167], v[48:63]
	s_waitcnt lgkmcnt(0)
	v_mfma_f32_32x32x16_bf16 v[96:111], v[238:241], v[160:163], v[96:111]
	v_mfma_f32_32x32x16_bf16 v[32:47], v[238:241], v[164:167], v[32:47]
	ds_read_b128 v[234:237], v205 offset:9216
	ds_read_b128 v[238:241], v205 offset:13824
	s_waitcnt vmcnt(7)
	ds_write_b128 v215, v[218:221] offset:9216
	s_waitcnt vmcnt(6)
	ds_write_b128 v215, v[222:225] offset:46080
	ds_read_b128 v[218:221], v208 offset:32
	ds_read_b128 v[222:225], v208 offset:4640
	s_waitcnt lgkmcnt(5)
	v_mfma_f32_32x32x16_bf16 v[80:95], v[234:237], v[160:163], v[80:95]
	v_mfma_f32_32x32x16_bf16 v[16:31], v[234:237], v[164:167], v[16:31]
	ds_read_b128 v[234:237], v205 offset:32
	s_waitcnt lgkmcnt(5)
	v_mfma_f32_32x32x16_bf16 v[64:79], v[238:241], v[160:163], v[64:79]
	v_mfma_f32_32x32x16_bf16 v[0:15], v[238:241], v[164:167], v[0:15]
	ds_read_b128 v[238:241], v205 offset:4640
	s_setprio 0
	global_load_dwordx4 v[160:163], v[194:195], off offset:1152
	global_load_dwordx4 v[164:167], v[196:197], off offset:1152
	s_setprio 1
	s_waitcnt lgkmcnt(1)
	v_mfma_f32_32x32x16_bf16 v[112:127], v[234:237], v[218:221], v[112:127]
	v_mfma_f32_32x32x16_bf16 v[48:63], v[234:237], v[222:225], v[48:63]
	s_waitcnt lgkmcnt(0)
	v_mfma_f32_32x32x16_bf16 v[96:111], v[238:241], v[218:221], v[96:111]
	v_mfma_f32_32x32x16_bf16 v[32:47], v[238:241], v[222:225], v[32:47]
	ds_read_b128 v[234:237], v205 offset:9248
	ds_read_b128 v[238:241], v205 offset:13856
	s_waitcnt vmcnt(7)
	ds_write_b128 v215, v[226:229] offset:18432
	s_waitcnt vmcnt(6)
	ds_write_b128 v215, v[230:233] offset:55296
	ds_read_b128 v[226:229], v208 offset:64
	ds_read_b128 v[230:233], v208 offset:4672
	s_waitcnt lgkmcnt(5)
	v_mfma_f32_32x32x16_bf16 v[80:95], v[234:237], v[218:221], v[80:95]
	v_mfma_f32_32x32x16_bf16 v[16:31], v[234:237], v[222:225], v[16:31]
	ds_read_b128 v[234:237], v205 offset:64
	s_waitcnt lgkmcnt(5)
	v_mfma_f32_32x32x16_bf16 v[64:79], v[238:241], v[218:221], v[64:79]
	v_mfma_f32_32x32x16_bf16 v[0:15], v[238:241], v[222:225], v[0:15]
	ds_read_b128 v[238:241], v205 offset:4672
	s_setprio 0
	global_load_dwordx4 v[218:221], v[184:185], off offset:1152
	global_load_dwordx4 v[222:225], v[186:187], off offset:1152
	s_setprio 1
	s_waitcnt lgkmcnt(1)
	v_mfma_f32_32x32x16_bf16 v[112:127], v[234:237], v[226:229], v[112:127]
	v_mfma_f32_32x32x16_bf16 v[48:63], v[234:237], v[230:233], v[48:63]
	s_waitcnt lgkmcnt(0)
	v_mfma_f32_32x32x16_bf16 v[96:111], v[238:241], v[226:229], v[96:111]
	v_mfma_f32_32x32x16_bf16 v[32:47], v[238:241], v[230:233], v[32:47]
	ds_read_b128 v[234:237], v205 offset:9280
	ds_read_b128 v[238:241], v205 offset:13888
	s_waitcnt vmcnt(7)
	ds_write_b128 v215, v[176:179] offset:27648
	s_waitcnt vmcnt(6)
	ds_write_b128 v215, v[180:183] offset:64512
	ds_read_b128 v[176:179], v208 offset:96
	ds_read_b128 v[180:183], v208 offset:4704
	s_waitcnt lgkmcnt(5)
	v_mfma_f32_32x32x16_bf16 v[80:95], v[234:237], v[226:229], v[80:95]
	v_mfma_f32_32x32x16_bf16 v[16:31], v[234:237], v[230:233], v[16:31]
	ds_read_b128 v[234:237], v205 offset:96
	s_waitcnt lgkmcnt(5)
	v_mfma_f32_32x32x16_bf16 v[64:79], v[238:241], v[226:229], v[64:79]
	v_mfma_f32_32x32x16_bf16 v[0:15], v[238:241], v[230:233], v[0:15]
	ds_read_b128 v[238:241], v205 offset:4704
	s_setprio 0
	global_load_dwordx4 v[226:229], v[198:199], off offset:1152
	global_load_dwordx4 v[230:233], v[200:201], off offset:1152
	s_setprio 1
	s_waitcnt lgkmcnt(1)
	v_mfma_f32_32x32x16_bf16 v[112:127], v[234:237], v[176:179], v[112:127]
	v_mfma_f32_32x32x16_bf16 v[48:63], v[234:237], v[180:183], v[48:63]
	s_waitcnt lgkmcnt(0)
	v_mfma_f32_32x32x16_bf16 v[96:111], v[238:241], v[176:179], v[96:111]
	v_mfma_f32_32x32x16_bf16 v[32:47], v[238:241], v[180:183], v[32:47]
	ds_read_b128 v[234:237], v205 offset:9312
	ds_read_b128 v[238:241], v205 offset:13920
	s_waitcnt lgkmcnt(1)
	v_mfma_f32_32x32x16_bf16 v[80:95], v[234:237], v[176:179], v[80:95]
	v_mfma_f32_32x32x16_bf16 v[16:31], v[234:237], v[180:183], v[16:31]
	s_waitcnt lgkmcnt(0)
	v_mfma_f32_32x32x16_bf16 v[64:79], v[238:241], v[176:179], v[64:79]
	v_mfma_f32_32x32x16_bf16 v[0:15], v[238:241], v[180:183], v[0:15]
	s_setprio 0
	global_load_dwordx4 v[176:179], v[190:191], off offset:1280
	global_load_dwordx4 v[180:183], v[188:189], off offset:1280
	s_barrier
; template <bool trans>
; DI void gemm_core(const GTile& tl, const GTile& nx, bool has_next  , bool chain  , bool pre, u32x4 (&ra)[4], u32x4 (&rb)[4], char* smem, f32x16 (&acc)[2][4]) {
;     ...
;   const int nk = K / 64;
;   if (!pre) { G_LOAD(0); G_STORE(0); G_LOAD(1); }
;   for (int kt = 0; kt < nk; ++kt) {
;     __syncthreads();
;     G_COMPUTE(kt & 1, kt);
;   }
	s_waitcnt vmcnt(9)
	ds_write_b128 v209, v[168:171]
	s_waitcnt vmcnt(8)
	ds_write_b128 v210, v[172:175]
	ds_read_b128 v[168:171], v204 offset:36864
	ds_read_b128 v[172:175], v204 offset:41472
	ds_read_b128 v[234:237], v192
	ds_read_b128 v[238:241], v192 offset:4608
	s_setprio 1
	s_waitcnt lgkmcnt(1)
	v_mfma_f32_32x32x16_bf16 v[112:127], v[234:237], v[168:171], v[112:127]
	v_mfma_f32_32x32x16_bf16 v[48:63], v[234:237], v[172:175], v[48:63]
	s_waitcnt lgkmcnt(0)
	v_mfma_f32_32x32x16_bf16 v[96:111], v[238:241], v[168:171], v[96:111]
	v_mfma_f32_32x32x16_bf16 v[32:47], v[238:241], v[172:175], v[32:47]
	ds_read_b128 v[234:237], v192 offset:9216
	ds_read_b128 v[238:241], v192 offset:13824
	s_waitcnt vmcnt(7)
	ds_write_b128 v212, v[160:163]
	s_waitcnt vmcnt(6)
	ds_write_b128 v211, v[164:167]
	ds_read_b128 v[160:163], v204 offset:36896
	ds_read_b128 v[164:167], v204 offset:41504
	s_waitcnt lgkmcnt(5)
	v_mfma_f32_32x32x16_bf16 v[80:95], v[234:237], v[168:171], v[80:95]
	v_mfma_f32_32x32x16_bf16 v[16:31], v[234:237], v[172:175], v[16:31]
	ds_read_b128 v[234:237], v192 offset:32
	s_waitcnt lgkmcnt(5)
	v_mfma_f32_32x32x16_bf16 v[64:79], v[238:241], v[168:171], v[64:79]
	v_mfma_f32_32x32x16_bf16 v[0:15], v[238:241], v[172:175], v[0:15]
	ds_read_b128 v[238:241], v192 offset:4640
	s_setprio 0
	global_load_dwordx4 v[168:171], v[194:195], off offset:1280
	global_load_dwordx4 v[172:175], v[196:197], off offset:1280
	s_setprio 1
	s_waitcnt lgkmcnt(1)
	v_mfma_f32_32x32x16_bf16 v[112:127], v[234:237], v[160:163], v[112:127]
	v_mfma_f32_32x32x16_bf16 v[48:63], v[234:237], v[164:167], v[48:63]
	s_waitcnt lgkmcnt(0)
	v_mfma_f32_32x32x16_bf16 v[96:111], v[238:241], v[160:163], v[96:111]
	v_mfma_f32_32x32x16_bf16 v[32:47], v[238:241], v[164:167], v[32:47]
	ds_read_b128 v[234:237], v192 offset:9248
	ds_read_b128 v[238:241], v192 offset:13856
	s_waitcnt vmcnt(7)
	ds_write_b128 v214, v[218:221]
	s_waitcnt vmcnt(6)
	ds_write_b128 v213, v[222:225]
	ds_read_b128 v[218:221], v204 offset:36928
	ds_read_b128 v[222:225], v204 offset:41536
	s_waitcnt lgkmcnt(5)
	v_mfma_f32_32x32x16_bf16 v[80:95], v[234:237], v[160:163], v[80:95]
	v_mfma_f32_32x32x16_bf16 v[16:31], v[234:237], v[164:167], v[16:31]
	ds_read_b128 v[234:237], v192 offset:64
	s_waitcnt lgkmcnt(5)
	v_mfma_f32_32x32x16_bf16 v[64:79], v[238:241], v[160:163], v[64:79]
	v_mfma_f32_32x32x16_bf16 v[0:15], v[238:241], v[164:167], v[0:15]
	ds_read_b128 v[238:241], v192 offset:4672
	s_setprio 0
	global_load_dwordx4 v[160:163], v[184:185], off offset:1280
	global_load_dwordx4 v[164:167], v[186:187], off offset:1280
	s_setprio 1
	s_waitcnt lgkmcnt(1)
	v_mfma_f32_32x32x16_bf16 v[112:127], v[234:237], v[218:221], v[112:127]
	v_mfma_f32_32x32x16_bf16 v[48:63], v[234:237], v[222:225], v[48:63]
	s_waitcnt lgkmcnt(0)
	v_mfma_f32_32x32x16_bf16 v[96:111], v[238:241], v[218:221], v[96:111]
	v_mfma_f32_32x32x16_bf16 v[32:47], v[238:241], v[222:225], v[32:47]
	ds_read_b128 v[234:237], v192 offset:9280
	ds_read_b128 v[238:241], v192 offset:13888
	s_waitcnt vmcnt(7)
	ds_write_b128 v217, v[226:229]
	s_waitcnt vmcnt(6)
	ds_write_b128 v216, v[230:233]
	ds_read_b128 v[226:229], v204 offset:36960
	ds_read_b128 v[230:233], v204 offset:41568
	s_waitcnt lgkmcnt(5)
	v_mfma_f32_32x32x16_bf16 v[80:95], v[234:237], v[218:221], v[80:95]
	v_mfma_f32_32x32x16_bf16 v[16:31], v[234:237], v[222:225], v[16:31]
	ds_read_b128 v[234:237], v192 offset:96
	s_waitcnt lgkmcnt(5)
	v_mfma_f32_32x32x16_bf16 v[64:79], v[238:241], v[218:221], v[64:79]
	v_mfma_f32_32x32x16_bf16 v[0:15], v[238:241], v[222:225], v[0:15]
	ds_read_b128 v[238:241], v192 offset:4704
	s_setprio 0
	global_load_dwordx4 v[218:221], v[198:199], off offset:1280
	global_load_dwordx4 v[222:225], v[200:201], off offset:1280
	s_setprio 1
	s_waitcnt lgkmcnt(1)
	v_mfma_f32_32x32x16_bf16 v[112:127], v[234:237], v[226:229], v[112:127]
	v_mfma_f32_32x32x16_bf16 v[48:63], v[234:237], v[230:233], v[48:63]
	s_waitcnt lgkmcnt(0)
	v_mfma_f32_32x32x16_bf16 v[96:111], v[238:241], v[226:229], v[96:111]
	v_mfma_f32_32x32x16_bf16 v[32:47], v[238:241], v[230:233], v[32:47]
	ds_read_b128 v[234:237], v192 offset:9312
	ds_read_b128 v[238:241], v192 offset:13920
	s_waitcnt lgkmcnt(1)
	v_mfma_f32_32x32x16_bf16 v[80:95], v[234:237], v[226:229], v[80:95]
	v_mfma_f32_32x32x16_bf16 v[16:31], v[234:237], v[230:233], v[16:31]
	s_waitcnt lgkmcnt(0)
	v_mfma_f32_32x32x16_bf16 v[64:79], v[238:241], v[226:229], v[64:79]
	v_mfma_f32_32x32x16_bf16 v[0:15], v[238:241], v[230:233], v[0:15]
	s_setprio 0
	global_load_dwordx4 v[226:229], v[190:191], off offset:1408
	global_load_dwordx4 v[230:233], v[188:189], off offset:1408
	s_barrier
; template <bool trans>
; DI void gemm_core(const GTile& tl, const GTile& nx, bool has_next  , bool chain  , bool pre, u32x4 (&ra)[4], u32x4 (&rb)[4], char* smem, f32x16 (&acc)[2][4]) {
;     ...
;   const int nk = K / 64;
;   if (!pre) { G_LOAD(0); G_STORE(0); G_LOAD(1); }
;   for (int kt = 0; kt < nk; ++kt) {
;     __syncthreads();
;     G_COMPUTE(kt & 1, kt);
;   }
	s_waitcnt vmcnt(9)
	ds_write_b128 v215, v[176:179]
	s_waitcnt vmcnt(8)
	ds_write_b128 v215, v[180:183] offset:36864
	ds_read_b128 v[176:179], v208
	ds_read_b128 v[180:183], v208 offset:4608
	ds_read_b128 v[234:237], v205
	ds_read_b128 v[238:241], v205 offset:4608
	s_setprio 1
	s_waitcnt lgkmcnt(1)
	v_mfma_f32_32x32x16_bf16 v[112:127], v[234:237], v[176:179], v[112:127]
	v_mfma_f32_32x32x16_bf16 v[48:63], v[234:237], v[180:183], v[48:63]
	s_waitcnt lgkmcnt(0)
	v_mfma_f32_32x32x16_bf16 v[96:111], v[238:241], v[176:179], v[96:111]
	v_mfma_f32_32x32x16_bf16 v[32:47], v[238:241], v[180:183], v[32:47]
	ds_read_b128 v[234:237], v205 offset:9216
	ds_read_b128 v[238:241], v205 offset:13824
	s_waitcnt vmcnt(7)
	ds_write_b128 v215, v[168:171] offset:9216
	s_waitcnt vmcnt(6)
	ds_write_b128 v215, v[172:175] offset:46080
	ds_read_b128 v[168:171], v208 offset:32
	ds_read_b128 v[172:175], v208 offset:4640
	s_waitcnt lgkmcnt(5)
	v_mfma_f32_32x32x16_bf16 v[80:95], v[234:237], v[176:179], v[80:95]
	v_mfma_f32_32x32x16_bf16 v[16:31], v[234:237], v[180:183], v[16:31]
	ds_read_b128 v[234:237], v205 offset:32
	s_waitcnt lgkmcnt(5)
	v_mfma_f32_32x32x16_bf16 v[64:79], v[238:241], v[176:179], v[64:79]
	v_mfma_f32_32x32x16_bf16 v[0:15], v[238:241], v[180:183], v[0:15]
	ds_read_b128 v[238:241], v205 offset:4640
	s_setprio 0
	global_load_dwordx4 v[176:179], v[194:195], off offset:1408
	global_load_dwordx4 v[180:183], v[196:197], off offset:1408
	s_setprio 1
	s_waitcnt lgkmcnt(1)
	v_mfma_f32_32x32x16_bf16 v[112:127], v[234:237], v[168:171], v[112:127]
	v_mfma_f32_32x32x16_bf16 v[48:63], v[234:237], v[172:175], v[48:63]
	s_waitcnt lgkmcnt(0)
	v_mfma_f32_32x32x16_bf16 v[96:111], v[238:241], v[168:171], v[96:111]
	v_mfma_f32_32x32x16_bf16 v[32:47], v[238:241], v[172:175], v[32:47]
	ds_read_b128 v[234:237], v205 offset:9248
	ds_read_b128 v[238:241], v205 offset:13856
	s_waitcnt vmcnt(7)
	ds_write_b128 v215, v[160:163] offset:18432
	s_waitcnt vmcnt(6)
	ds_write_b128 v215, v[164:167] offset:55296
	ds_read_b128 v[160:163], v208 offset:64
	ds_read_b128 v[164:167], v208 offset:4672
	s_waitcnt lgkmcnt(5)
	v_mfma_f32_32x32x16_bf16 v[80:95], v[234:237], v[168:171], v[80:95]
	v_mfma_f32_32x32x16_bf16 v[16:31], v[234:237], v[172:175], v[16:31]
	ds_read_b128 v[234:237], v205 offset:64
	s_waitcnt lgkmcnt(5)
	v_mfma_f32_32x32x16_bf16 v[64:79], v[238:241], v[168:171], v[64:79]
	v_mfma_f32_32x32x16_bf16 v[0:15], v[238:241], v[172:175], v[0:15]
	ds_read_b128 v[238:241], v205 offset:4672
	s_setprio 0
	global_load_dwordx4 v[168:171], v[184:185], off offset:1408
	global_load_dwordx4 v[172:175], v[186:187], off offset:1408
	s_setprio 1
	s_waitcnt lgkmcnt(1)
	v_mfma_f32_32x32x16_bf16 v[112:127], v[234:237], v[160:163], v[112:127]
	v_mfma_f32_32x32x16_bf16 v[48:63], v[234:237], v[164:167], v[48:63]
	s_waitcnt lgkmcnt(0)
	v_mfma_f32_32x32x16_bf16 v[96:111], v[238:241], v[160:163], v[96:111]
	v_mfma_f32_32x32x16_bf16 v[32:47], v[238:241], v[164:167], v[32:47]
	ds_read_b128 v[234:237], v205 offset:9280
	ds_read_b128 v[238:241], v205 offset:13888
	s_waitcnt vmcnt(7)
	ds_write_b128 v215, v[218:221] offset:27648
	s_waitcnt vmcnt(6)
	ds_write_b128 v215, v[222:225] offset:64512
	ds_read_b128 v[218:221], v208 offset:96
	ds_read_b128 v[222:225], v208 offset:4704
	s_waitcnt lgkmcnt(5)
	v_mfma_f32_32x32x16_bf16 v[80:95], v[234:237], v[160:163], v[80:95]
	v_mfma_f32_32x32x16_bf16 v[16:31], v[234:237], v[164:167], v[16:31]
	ds_read_b128 v[234:237], v205 offset:96
	s_waitcnt lgkmcnt(5)
	v_mfma_f32_32x32x16_bf16 v[64:79], v[238:241], v[160:163], v[64:79]
	v_mfma_f32_32x32x16_bf16 v[0:15], v[238:241], v[164:167], v[0:15]
	ds_read_b128 v[238:241], v205 offset:4704
	s_setprio 0
	global_load_dwordx4 v[160:163], v[198:199], off offset:1408
	global_load_dwordx4 v[164:167], v[200:201], off offset:1408
	s_setprio 1
	s_waitcnt lgkmcnt(1)
	v_mfma_f32_32x32x16_bf16 v[112:127], v[234:237], v[218:221], v[112:127]
	v_mfma_f32_32x32x16_bf16 v[48:63], v[234:237], v[222:225], v[48:63]
	s_waitcnt lgkmcnt(0)
	v_mfma_f32_32x32x16_bf16 v[96:111], v[238:241], v[218:221], v[96:111]
	v_mfma_f32_32x32x16_bf16 v[32:47], v[238:241], v[222:225], v[32:47]
	ds_read_b128 v[234:237], v205 offset:9312
	ds_read_b128 v[238:241], v205 offset:13920
	s_waitcnt lgkmcnt(1)
	v_mfma_f32_32x32x16_bf16 v[80:95], v[234:237], v[218:221], v[80:95]
	v_mfma_f32_32x32x16_bf16 v[16:31], v[234:237], v[222:225], v[16:31]
	s_waitcnt lgkmcnt(0)
	v_mfma_f32_32x32x16_bf16 v[64:79], v[238:241], v[218:221], v[64:79]
	v_mfma_f32_32x32x16_bf16 v[0:15], v[238:241], v[222:225], v[0:15]
	s_setprio 0
	global_load_dwordx4 v[218:221], v[190:191], off offset:1536
	global_load_dwordx4 v[222:225], v[188:189], off offset:1536
	s_barrier
; template <bool trans>
; DI void gemm_core(const GTile& tl, const GTile& nx, bool has_next  , bool chain  , bool pre, u32x4 (&ra)[4], u32x4 (&rb)[4], char* smem, f32x16 (&acc)[2][4]) {
;     ...
;   const int nk = K / 64;
;   if (!pre) { G_LOAD(0); G_STORE(0); G_LOAD(1); }
;   for (int kt = 0; kt < nk; ++kt) {
;     __syncthreads();
;     G_COMPUTE(kt & 1, kt);
;   }
	s_waitcnt vmcnt(9)
	ds_write_b128 v209, v[226:229]
	s_waitcnt vmcnt(8)
	ds_write_b128 v210, v[230:233]
	ds_read_b128 v[226:229], v204 offset:36864
	ds_read_b128 v[230:233], v204 offset:41472
	ds_read_b128 v[234:237], v192
	ds_read_b128 v[238:241], v192 offset:4608
	s_setprio 1
	s_waitcnt lgkmcnt(1)
	v_mfma_f32_32x32x16_bf16 v[112:127], v[234:237], v[226:229], v[112:127]
	v_mfma_f32_32x32x16_bf16 v[48:63], v[234:237], v[230:233], v[48:63]
	s_waitcnt lgkmcnt(0)
	v_mfma_f32_32x32x16_bf16 v[96:111], v[238:241], v[226:229], v[96:111]
	v_mfma_f32_32x32x16_bf16 v[32:47], v[238:241], v[230:233], v[32:47]
	ds_read_b128 v[234:237], v192 offset:9216
	ds_read_b128 v[238:241], v192 offset:13824
	s_waitcnt vmcnt(7)
	ds_write_b128 v212, v[176:179]
	s_waitcnt vmcnt(6)
	ds_write_b128 v211, v[180:183]
	ds_read_b128 v[176:179], v204 offset:36896
	ds_read_b128 v[180:183], v204 offset:41504
	s_waitcnt lgkmcnt(5)
	v_mfma_f32_32x32x16_bf16 v[80:95], v[234:237], v[226:229], v[80:95]
	v_mfma_f32_32x32x16_bf16 v[16:31], v[234:237], v[230:233], v[16:31]
	ds_read_b128 v[234:237], v192 offset:32
	s_waitcnt lgkmcnt(5)
	v_mfma_f32_32x32x16_bf16 v[64:79], v[238:241], v[226:229], v[64:79]
	v_mfma_f32_32x32x16_bf16 v[0:15], v[238:241], v[230:233], v[0:15]
	ds_read_b128 v[238:241], v192 offset:4640
	s_setprio 0
	global_load_dwordx4 v[226:229], v[194:195], off offset:1536
	global_load_dwordx4 v[230:233], v[196:197], off offset:1536
	s_setprio 1
	s_waitcnt lgkmcnt(1)
	v_mfma_f32_32x32x16_bf16 v[112:127], v[234:237], v[176:179], v[112:127]
	v_mfma_f32_32x32x16_bf16 v[48:63], v[234:237], v[180:183], v[48:63]
	s_waitcnt lgkmcnt(0)
	v_mfma_f32_32x32x16_bf16 v[96:111], v[238:241], v[176:179], v[96:111]
	v_mfma_f32_32x32x16_bf16 v[32:47], v[238:241], v[180:183], v[32:47]
	ds_read_b128 v[234:237], v192 offset:9248
	ds_read_b128 v[238:241], v192 offset:13856
	s_waitcnt vmcnt(7)
	ds_write_b128 v214, v[168:171]
	s_waitcnt vmcnt(6)
	ds_write_b128 v213, v[172:175]
	ds_read_b128 v[168:171], v204 offset:36928
	ds_read_b128 v[172:175], v204 offset:41536
	s_waitcnt lgkmcnt(5)
	v_mfma_f32_32x32x16_bf16 v[80:95], v[234:237], v[176:179], v[80:95]
	v_mfma_f32_32x32x16_bf16 v[16:31], v[234:237], v[180:183], v[16:31]
	ds_read_b128 v[234:237], v192 offset:64
	s_waitcnt lgkmcnt(5)
	v_mfma_f32_32x32x16_bf16 v[64:79], v[238:241], v[176:179], v[64:79]
	v_mfma_f32_32x32x16_bf16 v[0:15], v[238:241], v[180:183], v[0:15]
	ds_read_b128 v[238:241], v192 offset:4672
	s_setprio 0
	global_load_dwordx4 v[176:179], v[184:185], off offset:1536
	global_load_dwordx4 v[180:183], v[186:187], off offset:1536
	s_setprio 1
	s_waitcnt lgkmcnt(1)
	v_mfma_f32_32x32x16_bf16 v[112:127], v[234:237], v[168:171], v[112:127]
	v_mfma_f32_32x32x16_bf16 v[48:63], v[234:237], v[172:175], v[48:63]
	s_waitcnt lgkmcnt(0)
	v_mfma_f32_32x32x16_bf16 v[96:111], v[238:241], v[168:171], v[96:111]
	v_mfma_f32_32x32x16_bf16 v[32:47], v[238:241], v[172:175], v[32:47]
	ds_read_b128 v[234:237], v192 offset:9280
	ds_read_b128 v[238:241], v192 offset:13888
	s_waitcnt vmcnt(7)
	ds_write_b128 v217, v[160:163]
	s_waitcnt vmcnt(6)
	ds_write_b128 v216, v[164:167]
	ds_read_b128 v[160:163], v204 offset:36960
	ds_read_b128 v[164:167], v204 offset:41568
	s_waitcnt lgkmcnt(5)
	v_mfma_f32_32x32x16_bf16 v[80:95], v[234:237], v[168:171], v[80:95]
	v_mfma_f32_32x32x16_bf16 v[16:31], v[234:237], v[172:175], v[16:31]
	ds_read_b128 v[234:237], v192 offset:96
	s_waitcnt lgkmcnt(5)
	v_mfma_f32_32x32x16_bf16 v[64:79], v[238:241], v[168:171], v[64:79]
	v_mfma_f32_32x32x16_bf16 v[0:15], v[238:241], v[172:175], v[0:15]
	ds_read_b128 v[238:241], v192 offset:4704
	s_setprio 0
	global_load_dwordx4 v[168:171], v[198:199], off offset:1536
	global_load_dwordx4 v[172:175], v[200:201], off offset:1536
	s_setprio 1
	s_waitcnt lgkmcnt(1)
	v_mfma_f32_32x32x16_bf16 v[112:127], v[234:237], v[160:163], v[112:127]
	v_mfma_f32_32x32x16_bf16 v[48:63], v[234:237], v[164:167], v[48:63]
	s_waitcnt lgkmcnt(0)
	v_mfma_f32_32x32x16_bf16 v[96:111], v[238:241], v[160:163], v[96:111]
	v_mfma_f32_32x32x16_bf16 v[32:47], v[238:241], v[164:167], v[32:47]
	ds_read_b128 v[234:237], v192 offset:9312
	ds_read_b128 v[238:241], v192 offset:13920
	s_waitcnt lgkmcnt(1)
	v_mfma_f32_32x32x16_bf16 v[80:95], v[234:237], v[160:163], v[80:95]
	v_mfma_f32_32x32x16_bf16 v[16:31], v[234:237], v[164:167], v[16:31]
	s_waitcnt lgkmcnt(0)
	v_mfma_f32_32x32x16_bf16 v[64:79], v[238:241], v[160:163], v[64:79]
	v_mfma_f32_32x32x16_bf16 v[0:15], v[238:241], v[164:167], v[0:15]
	s_setprio 0
	global_load_dwordx4 v[160:163], v[190:191], off offset:1664
	global_load_dwordx4 v[164:167], v[188:189], off offset:1664
	s_barrier
; template <bool trans>
; DI void gemm_core(const GTile& tl, const GTile& nx, bool has_next  , bool chain  , bool pre, u32x4 (&ra)[4], u32x4 (&rb)[4], char* smem, f32x16 (&acc)[2][4]) {
;     ...
;   const int nk = K / 64;
;   if (!pre) { G_LOAD(0); G_STORE(0); G_LOAD(1); }
;   for (int kt = 0; kt < nk; ++kt) {
;     __syncthreads();
;     G_COMPUTE(kt & 1, kt);
;   }
	s_waitcnt vmcnt(9)
	ds_write_b128 v215, v[218:221]
	s_waitcnt vmcnt(8)
	ds_write_b128 v215, v[222:225] offset:36864
	ds_read_b128 v[218:221], v208
	ds_read_b128 v[222:225], v208 offset:4608
	ds_read_b128 v[234:237], v205
	ds_read_b128 v[238:241], v205 offset:4608
	s_setprio 1
	s_waitcnt lgkmcnt(1)
	v_mfma_f32_32x32x16_bf16 v[112:127], v[234:237], v[218:221], v[112:127]
	v_mfma_f32_32x32x16_bf16 v[48:63], v[234:237], v[222:225], v[48:63]
	s_waitcnt lgkmcnt(0)
	v_mfma_f32_32x32x16_bf16 v[96:111], v[238:241], v[218:221], v[96:111]
	v_mfma_f32_32x32x16_bf16 v[32:47], v[238:241], v[222:225], v[32:47]
	ds_read_b128 v[234:237], v205 offset:9216
	ds_read_b128 v[238:241], v205 offset:13824
	s_waitcnt vmcnt(7)
	ds_write_b128 v215, v[226:229] offset:9216
	s_waitcnt vmcnt(6)
	ds_write_b128 v215, v[230:233] offset:46080
	ds_read_b128 v[226:229], v208 offset:32
	ds_read_b128 v[230:233], v208 offset:4640
	s_waitcnt lgkmcnt(5)
	v_mfma_f32_32x32x16_bf16 v[80:95], v[234:237], v[218:221], v[80:95]
	v_mfma_f32_32x32x16_bf16 v[16:31], v[234:237], v[222:225], v[16:31]
	ds_read_b128 v[234:237], v205 offset:32
	s_waitcnt lgkmcnt(5)
	v_mfma_f32_32x32x16_bf16 v[64:79], v[238:241], v[218:221], v[64:79]
	v_mfma_f32_32x32x16_bf16 v[0:15], v[238:241], v[222:225], v[0:15]
	ds_read_b128 v[238:241], v205 offset:4640
	s_setprio 0
	global_load_dwordx4 v[218:221], v[194:195], off offset:1664
	global_load_dwordx4 v[222:225], v[196:197], off offset:1664
	s_setprio 1
	s_waitcnt lgkmcnt(1)
	v_mfma_f32_32x32x16_bf16 v[112:127], v[234:237], v[226:229], v[112:127]
	v_mfma_f32_32x32x16_bf16 v[48:63], v[234:237], v[230:233], v[48:63]
	s_waitcnt lgkmcnt(0)
	v_mfma_f32_32x32x16_bf16 v[96:111], v[238:241], v[226:229], v[96:111]
	v_mfma_f32_32x32x16_bf16 v[32:47], v[238:241], v[230:233], v[32:47]
	ds_read_b128 v[234:237], v205 offset:9248
	ds_read_b128 v[238:241], v205 offset:13856
	s_waitcnt vmcnt(7)
	ds_write_b128 v215, v[176:179] offset:18432
	s_waitcnt vmcnt(6)
	ds_write_b128 v215, v[180:183] offset:55296
	ds_read_b128 v[176:179], v208 offset:64
	ds_read_b128 v[180:183], v208 offset:4672
	s_waitcnt lgkmcnt(5)
	v_mfma_f32_32x32x16_bf16 v[80:95], v[234:237], v[226:229], v[80:95]
	v_mfma_f32_32x32x16_bf16 v[16:31], v[234:237], v[230:233], v[16:31]
	ds_read_b128 v[234:237], v205 offset:64
	s_waitcnt lgkmcnt(5)
	v_mfma_f32_32x32x16_bf16 v[64:79], v[238:241], v[226:229], v[64:79]
	v_mfma_f32_32x32x16_bf16 v[0:15], v[238:241], v[230:233], v[0:15]
	ds_read_b128 v[238:241], v205 offset:4672
	s_setprio 0
	global_load_dwordx4 v[226:229], v[184:185], off offset:1664
	global_load_dwordx4 v[230:233], v[186:187], off offset:1664
	s_setprio 1
	s_waitcnt lgkmcnt(1)
	v_mfma_f32_32x32x16_bf16 v[112:127], v[234:237], v[176:179], v[112:127]
	v_mfma_f32_32x32x16_bf16 v[48:63], v[234:237], v[180:183], v[48:63]
	s_waitcnt lgkmcnt(0)
	v_mfma_f32_32x32x16_bf16 v[96:111], v[238:241], v[176:179], v[96:111]
	v_mfma_f32_32x32x16_bf16 v[32:47], v[238:241], v[180:183], v[32:47]
	ds_read_b128 v[234:237], v205 offset:9280
	ds_read_b128 v[238:241], v205 offset:13888
	s_waitcnt vmcnt(7)
	ds_write_b128 v215, v[168:171] offset:27648
	s_waitcnt vmcnt(6)
	ds_write_b128 v215, v[172:175] offset:64512
	ds_read_b128 v[168:171], v208 offset:96
	ds_read_b128 v[172:175], v208 offset:4704
	s_waitcnt lgkmcnt(5)
	v_mfma_f32_32x32x16_bf16 v[80:95], v[234:237], v[176:179], v[80:95]
	v_mfma_f32_32x32x16_bf16 v[16:31], v[234:237], v[180:183], v[16:31]
	ds_read_b128 v[234:237], v205 offset:96
	s_waitcnt lgkmcnt(5)
	v_mfma_f32_32x32x16_bf16 v[64:79], v[238:241], v[176:179], v[64:79]
	v_mfma_f32_32x32x16_bf16 v[0:15], v[238:241], v[180:183], v[0:15]
	ds_read_b128 v[238:241], v205 offset:4704
	s_setprio 0
	global_load_dwordx4 v[176:179], v[198:199], off offset:1664
	global_load_dwordx4 v[180:183], v[200:201], off offset:1664
	s_setprio 1
	s_waitcnt lgkmcnt(1)
	v_mfma_f32_32x32x16_bf16 v[112:127], v[234:237], v[168:171], v[112:127]
	v_mfma_f32_32x32x16_bf16 v[48:63], v[234:237], v[172:175], v[48:63]
	s_waitcnt lgkmcnt(0)
	v_mfma_f32_32x32x16_bf16 v[96:111], v[238:241], v[168:171], v[96:111]
	v_mfma_f32_32x32x16_bf16 v[32:47], v[238:241], v[172:175], v[32:47]
	ds_read_b128 v[234:237], v205 offset:9312
	ds_read_b128 v[238:241], v205 offset:13920
	s_waitcnt lgkmcnt(1)
	v_mfma_f32_32x32x16_bf16 v[80:95], v[234:237], v[168:171], v[80:95]
	v_mfma_f32_32x32x16_bf16 v[16:31], v[234:237], v[172:175], v[16:31]
	s_waitcnt lgkmcnt(0)
	v_mfma_f32_32x32x16_bf16 v[64:79], v[238:241], v[168:171], v[64:79]
	v_mfma_f32_32x32x16_bf16 v[0:15], v[238:241], v[172:175], v[0:15]
	s_setprio 0
	global_load_dwordx4 v[168:171], v[190:191], off offset:1792
	global_load_dwordx4 v[172:175], v[188:189], off offset:1792
	s_barrier
; template <bool trans>
; DI void gemm_core(const GTile& tl, const GTile& nx, bool has_next  , bool chain  , bool pre, u32x4 (&ra)[4], u32x4 (&rb)[4], char* smem, f32x16 (&acc)[2][4]) {
;     ...
;   const int nk = K / 64;
;   if (!pre) { G_LOAD(0); G_STORE(0); G_LOAD(1); }
;   for (int kt = 0; kt < nk; ++kt) {
;     __syncthreads();
;     G_COMPUTE(kt & 1, kt);
;   }
	s_waitcnt vmcnt(9)
	ds_write_b128 v209, v[160:163]
	s_waitcnt vmcnt(8)
	ds_write_b128 v210, v[164:167]
	ds_read_b128 v[160:163], v204 offset:36864
	ds_read_b128 v[164:167], v204 offset:41472
	ds_read_b128 v[234:237], v192
	ds_read_b128 v[238:241], v192 offset:4608
	s_setprio 1
	s_waitcnt lgkmcnt(1)
	v_mfma_f32_32x32x16_bf16 v[112:127], v[234:237], v[160:163], v[112:127]
	v_mfma_f32_32x32x16_bf16 v[48:63], v[234:237], v[164:167], v[48:63]
	s_waitcnt lgkmcnt(0)
	v_mfma_f32_32x32x16_bf16 v[96:111], v[238:241], v[160:163], v[96:111]
	v_mfma_f32_32x32x16_bf16 v[32:47], v[238:241], v[164:167], v[32:47]
	ds_read_b128 v[234:237], v192 offset:9216
	ds_read_b128 v[238:241], v192 offset:13824
	s_waitcnt vmcnt(7)
	ds_write_b128 v212, v[218:221]
	s_waitcnt vmcnt(6)
	ds_write_b128 v211, v[222:225]
	ds_read_b128 v[218:221], v204 offset:36896
	ds_read_b128 v[222:225], v204 offset:41504
	s_waitcnt lgkmcnt(5)
	v_mfma_f32_32x32x16_bf16 v[80:95], v[234:237], v[160:163], v[80:95]
	v_mfma_f32_32x32x16_bf16 v[16:31], v[234:237], v[164:167], v[16:31]
	ds_read_b128 v[234:237], v192 offset:32
	s_waitcnt lgkmcnt(5)
	v_mfma_f32_32x32x16_bf16 v[64:79], v[238:241], v[160:163], v[64:79]
	v_mfma_f32_32x32x16_bf16 v[0:15], v[238:241], v[164:167], v[0:15]
	ds_read_b128 v[238:241], v192 offset:4640
	s_setprio 0
	global_load_dwordx4 v[160:163], v[194:195], off offset:1792
	global_load_dwordx4 v[164:167], v[196:197], off offset:1792
	s_setprio 1
	s_waitcnt lgkmcnt(1)
	v_mfma_f32_32x32x16_bf16 v[112:127], v[234:237], v[218:221], v[112:127]
	v_mfma_f32_32x32x16_bf16 v[48:63], v[234:237], v[222:225], v[48:63]
	s_waitcnt lgkmcnt(0)
	v_mfma_f32_32x32x16_bf16 v[96:111], v[238:241], v[218:221], v[96:111]
	v_mfma_f32_32x32x16_bf16 v[32:47], v[238:241], v[222:225], v[32:47]
	ds_read_b128 v[234:237], v192 offset:9248
	ds_read_b128 v[238:241], v192 offset:13856
	s_waitcnt vmcnt(7)
	ds_write_b128 v214, v[226:229]
	s_waitcnt vmcnt(6)
	ds_write_b128 v213, v[230:233]
	ds_read_b128 v[226:229], v204 offset:36928
	ds_read_b128 v[230:233], v204 offset:41536
	s_waitcnt lgkmcnt(5)
	v_mfma_f32_32x32x16_bf16 v[80:95], v[234:237], v[218:221], v[80:95]
	v_mfma_f32_32x32x16_bf16 v[16:31], v[234:237], v[222:225], v[16:31]
	ds_read_b128 v[234:237], v192 offset:64
	s_waitcnt lgkmcnt(5)
	v_mfma_f32_32x32x16_bf16 v[64:79], v[238:241], v[218:221], v[64:79]
	v_mfma_f32_32x32x16_bf16 v[0:15], v[238:241], v[222:225], v[0:15]
	ds_read_b128 v[238:241], v192 offset:4672
	s_setprio 0
	global_load_dwordx4 v[218:221], v[184:185], off offset:1792
	global_load_dwordx4 v[222:225], v[186:187], off offset:1792
	s_setprio 1
	s_waitcnt lgkmcnt(1)
	v_mfma_f32_32x32x16_bf16 v[112:127], v[234:237], v[226:229], v[112:127]
	v_mfma_f32_32x32x16_bf16 v[48:63], v[234:237], v[230:233], v[48:63]
	s_waitcnt lgkmcnt(0)
	v_mfma_f32_32x32x16_bf16 v[96:111], v[238:241], v[226:229], v[96:111]
	v_mfma_f32_32x32x16_bf16 v[32:47], v[238:241], v[230:233], v[32:47]
	ds_read_b128 v[234:237], v192 offset:9280
	ds_read_b128 v[238:241], v192 offset:13888
	s_waitcnt vmcnt(7)
	ds_write_b128 v217, v[176:179]
	s_waitcnt vmcnt(6)
	ds_write_b128 v216, v[180:183]
	ds_read_b128 v[176:179], v204 offset:36960
	ds_read_b128 v[180:183], v204 offset:41568
	s_waitcnt lgkmcnt(5)
	v_mfma_f32_32x32x16_bf16 v[80:95], v[234:237], v[226:229], v[80:95]
	v_mfma_f32_32x32x16_bf16 v[16:31], v[234:237], v[230:233], v[16:31]
	ds_read_b128 v[234:237], v192 offset:96
	s_waitcnt lgkmcnt(5)
	v_mfma_f32_32x32x16_bf16 v[64:79], v[238:241], v[226:229], v[64:79]
	v_mfma_f32_32x32x16_bf16 v[0:15], v[238:241], v[230:233], v[0:15]
	ds_read_b128 v[238:241], v192 offset:4704
	s_setprio 0
	global_load_dwordx4 v[226:229], v[198:199], off offset:1792
	global_load_dwordx4 v[230:233], v[200:201], off offset:1792
	s_setprio 1
	s_waitcnt lgkmcnt(1)
	v_mfma_f32_32x32x16_bf16 v[112:127], v[234:237], v[176:179], v[112:127]
	v_mfma_f32_32x32x16_bf16 v[48:63], v[234:237], v[180:183], v[48:63]
	s_waitcnt lgkmcnt(0)
	v_mfma_f32_32x32x16_bf16 v[96:111], v[238:241], v[176:179], v[96:111]
	v_mfma_f32_32x32x16_bf16 v[32:47], v[238:241], v[180:183], v[32:47]
	ds_read_b128 v[234:237], v192 offset:9312
	ds_read_b128 v[238:241], v192 offset:13920
	s_waitcnt lgkmcnt(1)
	v_mfma_f32_32x32x16_bf16 v[80:95], v[234:237], v[176:179], v[80:95]
	v_mfma_f32_32x32x16_bf16 v[16:31], v[234:237], v[180:183], v[16:31]
	s_waitcnt lgkmcnt(0)
	v_mfma_f32_32x32x16_bf16 v[64:79], v[238:241], v[176:179], v[64:79]
	v_mfma_f32_32x32x16_bf16 v[0:15], v[238:241], v[180:183], v[0:15]
	s_setprio 0
	global_load_dwordx4 v[176:179], v[190:191], off offset:1920
	global_load_dwordx4 v[180:183], v[188:189], off offset:1920
	s_barrier
; template <bool trans>
; DI void gemm_core(const GTile& tl, const GTile& nx, bool has_next  , bool chain  , bool pre, u32x4 (&ra)[4], u32x4 (&rb)[4], char* smem, f32x16 (&acc)[2][4]) {
;     ...
;   const int nk = K / 64;
;   if (!pre) { G_LOAD(0); G_STORE(0); G_LOAD(1); }
;   for (int kt = 0; kt < nk; ++kt) {
;     __syncthreads();
;     G_COMPUTE(kt & 1, kt);
;   }
	s_waitcnt vmcnt(9)
	ds_write_b128 v215, v[168:171]
	s_waitcnt vmcnt(8)
	ds_write_b128 v215, v[172:175] offset:36864
	ds_read_b128 v[168:171], v208
	ds_read_b128 v[172:175], v208 offset:4608
	ds_read_b128 v[234:237], v205
	ds_read_b128 v[238:241], v205 offset:4608
	s_setprio 1
	s_waitcnt lgkmcnt(1)
	v_mfma_f32_32x32x16_bf16 v[112:127], v[234:237], v[168:171], v[112:127]
	v_mfma_f32_32x32x16_bf16 v[48:63], v[234:237], v[172:175], v[48:63]
	s_waitcnt lgkmcnt(0)
	v_mfma_f32_32x32x16_bf16 v[96:111], v[238:241], v[168:171], v[96:111]
	v_mfma_f32_32x32x16_bf16 v[32:47], v[238:241], v[172:175], v[32:47]
	ds_read_b128 v[234:237], v205 offset:9216
	ds_read_b128 v[238:241], v205 offset:13824
	s_waitcnt vmcnt(7)
	ds_write_b128 v215, v[160:163] offset:9216
	s_waitcnt vmcnt(6)
	ds_write_b128 v215, v[164:167] offset:46080
	ds_read_b128 v[160:163], v208 offset:32
	ds_read_b128 v[164:167], v208 offset:4640
	s_waitcnt lgkmcnt(5)
	v_mfma_f32_32x32x16_bf16 v[80:95], v[234:237], v[168:171], v[80:95]
	v_mfma_f32_32x32x16_bf16 v[16:31], v[234:237], v[172:175], v[16:31]
	ds_read_b128 v[234:237], v205 offset:32
	s_waitcnt lgkmcnt(5)
	v_mfma_f32_32x32x16_bf16 v[64:79], v[238:241], v[168:171], v[64:79]
	v_mfma_f32_32x32x16_bf16 v[0:15], v[238:241], v[172:175], v[0:15]
	ds_read_b128 v[238:241], v205 offset:4640
	s_setprio 0
	global_load_dwordx4 v[168:171], v[194:195], off offset:1920
	global_load_dwordx4 v[172:175], v[196:197], off offset:1920
	s_setprio 1
	s_waitcnt lgkmcnt(1)
	v_mfma_f32_32x32x16_bf16 v[112:127], v[234:237], v[160:163], v[112:127]
	v_mfma_f32_32x32x16_bf16 v[48:63], v[234:237], v[164:167], v[48:63]
	s_waitcnt lgkmcnt(0)
	v_mfma_f32_32x32x16_bf16 v[96:111], v[238:241], v[160:163], v[96:111]
	v_mfma_f32_32x32x16_bf16 v[32:47], v[238:241], v[164:167], v[32:47]
	ds_read_b128 v[234:237], v205 offset:9248
	ds_read_b128 v[238:241], v205 offset:13856
	s_waitcnt vmcnt(7)
	ds_write_b128 v215, v[218:221] offset:18432
	s_waitcnt vmcnt(6)
	ds_write_b128 v215, v[222:225] offset:55296
	ds_read_b128 v[218:221], v208 offset:64
	ds_read_b128 v[222:225], v208 offset:4672
	s_waitcnt lgkmcnt(5)
	v_mfma_f32_32x32x16_bf16 v[80:95], v[234:237], v[160:163], v[80:95]
	v_mfma_f32_32x32x16_bf16 v[16:31], v[234:237], v[164:167], v[16:31]
	ds_read_b128 v[234:237], v205 offset:64
	s_waitcnt lgkmcnt(5)
	v_mfma_f32_32x32x16_bf16 v[64:79], v[238:241], v[160:163], v[64:79]
	v_mfma_f32_32x32x16_bf16 v[0:15], v[238:241], v[164:167], v[0:15]
	ds_read_b128 v[238:241], v205 offset:4672
	s_setprio 0
	global_load_dwordx4 v[160:163], v[184:185], off offset:1920
	global_load_dwordx4 v[164:167], v[186:187], off offset:1920
	s_setprio 1
	s_waitcnt lgkmcnt(1)
	v_mfma_f32_32x32x16_bf16 v[112:127], v[234:237], v[218:221], v[112:127]
	v_mfma_f32_32x32x16_bf16 v[48:63], v[234:237], v[222:225], v[48:63]
	s_waitcnt lgkmcnt(0)
	v_mfma_f32_32x32x16_bf16 v[96:111], v[238:241], v[218:221], v[96:111]
	v_mfma_f32_32x32x16_bf16 v[32:47], v[238:241], v[222:225], v[32:47]
	ds_read_b128 v[234:237], v205 offset:9280
	ds_read_b128 v[238:241], v205 offset:13888
	s_waitcnt vmcnt(7)
	ds_write_b128 v215, v[226:229] offset:27648
	s_waitcnt vmcnt(6)
	ds_write_b128 v215, v[230:233] offset:64512
	ds_read_b128 v[226:229], v208 offset:96
	ds_read_b128 v[230:233], v208 offset:4704
	s_waitcnt lgkmcnt(5)
	v_mfma_f32_32x32x16_bf16 v[80:95], v[234:237], v[218:221], v[80:95]
	v_mfma_f32_32x32x16_bf16 v[16:31], v[234:237], v[222:225], v[16:31]
	ds_read_b128 v[234:237], v205 offset:96
	s_waitcnt lgkmcnt(5)
	v_mfma_f32_32x32x16_bf16 v[64:79], v[238:241], v[218:221], v[64:79]
	v_mfma_f32_32x32x16_bf16 v[0:15], v[238:241], v[222:225], v[0:15]
	ds_read_b128 v[238:241], v205 offset:4704
	s_setprio 0
	global_load_dwordx4 v[218:221], v[198:199], off offset:1920
	global_load_dwordx4 v[222:225], v[200:201], off offset:1920
	s_setprio 1
	s_waitcnt lgkmcnt(1)
	v_mfma_f32_32x32x16_bf16 v[112:127], v[234:237], v[226:229], v[112:127]
	v_mfma_f32_32x32x16_bf16 v[48:63], v[234:237], v[230:233], v[48:63]
	s_waitcnt lgkmcnt(0)
	v_mfma_f32_32x32x16_bf16 v[96:111], v[238:241], v[226:229], v[96:111]
	v_mfma_f32_32x32x16_bf16 v[32:47], v[238:241], v[230:233], v[32:47]
	ds_read_b128 v[234:237], v205 offset:9312
	ds_read_b128 v[238:241], v205 offset:13920
	s_waitcnt lgkmcnt(1)
	v_mfma_f32_32x32x16_bf16 v[80:95], v[234:237], v[226:229], v[80:95]
	v_mfma_f32_32x32x16_bf16 v[16:31], v[234:237], v[230:233], v[16:31]
	s_waitcnt lgkmcnt(0)
	v_mfma_f32_32x32x16_bf16 v[64:79], v[238:241], v[226:229], v[64:79]
	v_mfma_f32_32x32x16_bf16 v[0:15], v[238:241], v[230:233], v[0:15]
	s_setprio 0
	global_load_dwordx4 v[226:229], v[190:191], off offset:2048
	global_load_dwordx4 v[230:233], v[188:189], off offset:2048
	s_barrier
; template <bool trans>
; DI void gemm_core(const GTile& tl, const GTile& nx, bool has_next  , bool chain  , bool pre, u32x4 (&ra)[4], u32x4 (&rb)[4], char* smem, f32x16 (&acc)[2][4]) {
;     ...
;   const int nk = K / 64;
;   if (!pre) { G_LOAD(0); G_STORE(0); G_LOAD(1); }
;   for (int kt = 0; kt < nk; ++kt) {
;     __syncthreads();
;     G_COMPUTE(kt & 1, kt);
;   }
	s_waitcnt vmcnt(9)
	ds_write_b128 v209, v[176:179]
	s_waitcnt vmcnt(8)
	ds_write_b128 v210, v[180:183]
	ds_read_b128 v[176:179], v204 offset:36864
	ds_read_b128 v[180:183], v204 offset:41472
	ds_read_b128 v[234:237], v192
	ds_read_b128 v[238:241], v192 offset:4608
	s_setprio 1
	s_waitcnt lgkmcnt(1)
	v_mfma_f32_32x32x16_bf16 v[112:127], v[234:237], v[176:179], v[112:127]
	v_mfma_f32_32x32x16_bf16 v[48:63], v[234:237], v[180:183], v[48:63]
	s_waitcnt lgkmcnt(0)
	v_mfma_f32_32x32x16_bf16 v[96:111], v[238:241], v[176:179], v[96:111]
	v_mfma_f32_32x32x16_bf16 v[32:47], v[238:241], v[180:183], v[32:47]
	ds_read_b128 v[234:237], v192 offset:9216
	ds_read_b128 v[238:241], v192 offset:13824
	s_waitcnt vmcnt(7)
	ds_write_b128 v212, v[168:171]
	s_waitcnt vmcnt(6)
	ds_write_b128 v211, v[172:175]
	ds_read_b128 v[168:171], v204 offset:36896
	ds_read_b128 v[172:175], v204 offset:41504
	s_waitcnt lgkmcnt(5)
	v_mfma_f32_32x32x16_bf16 v[80:95], v[234:237], v[176:179], v[80:95]
	v_mfma_f32_32x32x16_bf16 v[16:31], v[234:237], v[180:183], v[16:31]
	ds_read_b128 v[234:237], v192 offset:32
	s_waitcnt lgkmcnt(5)
	v_mfma_f32_32x32x16_bf16 v[64:79], v[238:241], v[176:179], v[64:79]
	v_mfma_f32_32x32x16_bf16 v[0:15], v[238:241], v[180:183], v[0:15]
	ds_read_b128 v[238:241], v192 offset:4640
	s_setprio 0
	global_load_dwordx4 v[176:179], v[194:195], off offset:2048
	global_load_dwordx4 v[180:183], v[196:197], off offset:2048
	s_setprio 1
	s_waitcnt lgkmcnt(1)
	v_mfma_f32_32x32x16_bf16 v[112:127], v[234:237], v[168:171], v[112:127]
	v_mfma_f32_32x32x16_bf16 v[48:63], v[234:237], v[172:175], v[48:63]
	s_waitcnt lgkmcnt(0)
	v_mfma_f32_32x32x16_bf16 v[96:111], v[238:241], v[168:171], v[96:111]
	v_mfma_f32_32x32x16_bf16 v[32:47], v[238:241], v[172:175], v[32:47]
	ds_read_b128 v[234:237], v192 offset:9248
	ds_read_b128 v[238:241], v192 offset:13856
	s_waitcnt vmcnt(7)
	ds_write_b128 v214, v[160:163]
	s_waitcnt vmcnt(6)
	ds_write_b128 v213, v[164:167]
	ds_read_b128 v[160:163], v204 offset:36928
	ds_read_b128 v[164:167], v204 offset:41536
	s_waitcnt lgkmcnt(5)
	v_mfma_f32_32x32x16_bf16 v[80:95], v[234:237], v[168:171], v[80:95]
	v_mfma_f32_32x32x16_bf16 v[16:31], v[234:237], v[172:175], v[16:31]
	ds_read_b128 v[234:237], v192 offset:64
	s_waitcnt lgkmcnt(5)
	v_mfma_f32_32x32x16_bf16 v[64:79], v[238:241], v[168:171], v[64:79]
	v_mfma_f32_32x32x16_bf16 v[0:15], v[238:241], v[172:175], v[0:15]
	ds_read_b128 v[238:241], v192 offset:4672
	s_setprio 0
	global_load_dwordx4 v[168:171], v[184:185], off offset:2048
	global_load_dwordx4 v[172:175], v[186:187], off offset:2048
	s_setprio 1
	s_waitcnt lgkmcnt(1)
	v_mfma_f32_32x32x16_bf16 v[112:127], v[234:237], v[160:163], v[112:127]
	v_mfma_f32_32x32x16_bf16 v[48:63], v[234:237], v[164:167], v[48:63]
	s_waitcnt lgkmcnt(0)
	v_mfma_f32_32x32x16_bf16 v[96:111], v[238:241], v[160:163], v[96:111]
	v_mfma_f32_32x32x16_bf16 v[32:47], v[238:241], v[164:167], v[32:47]
	ds_read_b128 v[234:237], v192 offset:9280
	ds_read_b128 v[238:241], v192 offset:13888
	s_waitcnt vmcnt(7)
	ds_write_b128 v217, v[218:221]
	s_waitcnt vmcnt(6)
	ds_write_b128 v216, v[222:225]
	ds_read_b128 v[218:221], v204 offset:36960
	ds_read_b128 v[222:225], v204 offset:41568
	s_waitcnt lgkmcnt(5)
	v_mfma_f32_32x32x16_bf16 v[80:95], v[234:237], v[160:163], v[80:95]
	v_mfma_f32_32x32x16_bf16 v[16:31], v[234:237], v[164:167], v[16:31]
	ds_read_b128 v[234:237], v192 offset:96
	s_waitcnt lgkmcnt(5)
	v_mfma_f32_32x32x16_bf16 v[64:79], v[238:241], v[160:163], v[64:79]
	v_mfma_f32_32x32x16_bf16 v[0:15], v[238:241], v[164:167], v[0:15]
	ds_read_b128 v[238:241], v192 offset:4704
	s_setprio 0
	global_load_dwordx4 v[160:163], v[198:199], off offset:2048
	global_load_dwordx4 v[164:167], v[200:201], off offset:2048
	s_setprio 1
	s_waitcnt lgkmcnt(1)
	v_mfma_f32_32x32x16_bf16 v[112:127], v[234:237], v[218:221], v[112:127]
	v_mfma_f32_32x32x16_bf16 v[48:63], v[234:237], v[222:225], v[48:63]
	s_waitcnt lgkmcnt(0)
	v_mfma_f32_32x32x16_bf16 v[96:111], v[238:241], v[218:221], v[96:111]
	v_mfma_f32_32x32x16_bf16 v[32:47], v[238:241], v[222:225], v[32:47]
	ds_read_b128 v[234:237], v192 offset:9312
	ds_read_b128 v[238:241], v192 offset:13920
	s_waitcnt lgkmcnt(1)
	v_mfma_f32_32x32x16_bf16 v[80:95], v[234:237], v[218:221], v[80:95]
	v_mfma_f32_32x32x16_bf16 v[16:31], v[234:237], v[222:225], v[16:31]
	s_waitcnt lgkmcnt(0)
	v_mfma_f32_32x32x16_bf16 v[64:79], v[238:241], v[218:221], v[64:79]
	v_mfma_f32_32x32x16_bf16 v[0:15], v[238:241], v[222:225], v[0:15]
	s_setprio 0
	global_load_dwordx4 v[218:221], v[190:191], off offset:2176
	global_load_dwordx4 v[222:225], v[188:189], off offset:2176
	s_barrier
; template <bool trans>
; DI void gemm_core(const GTile& tl, const GTile& nx, bool has_next  , bool chain  , bool pre, u32x4 (&ra)[4], u32x4 (&rb)[4], char* smem, f32x16 (&acc)[2][4]) {
;     ...
;   const int nk = K / 64;
;   if (!pre) { G_LOAD(0); G_STORE(0); G_LOAD(1); }
;   for (int kt = 0; kt < nk; ++kt) {
;     __syncthreads();
;     G_COMPUTE(kt & 1, kt);
;   }
	s_waitcnt vmcnt(9)
	ds_write_b128 v215, v[226:229]
	s_waitcnt vmcnt(8)
	ds_write_b128 v215, v[230:233] offset:36864
	ds_read_b128 v[226:229], v208
	ds_read_b128 v[230:233], v208 offset:4608
	ds_read_b128 v[234:237], v205
	ds_read_b128 v[238:241], v205 offset:4608
	s_setprio 1
	s_waitcnt lgkmcnt(1)
	v_mfma_f32_32x32x16_bf16 v[112:127], v[234:237], v[226:229], v[112:127]
	v_mfma_f32_32x32x16_bf16 v[48:63], v[234:237], v[230:233], v[48:63]
	s_waitcnt lgkmcnt(0)
	v_mfma_f32_32x32x16_bf16 v[96:111], v[238:241], v[226:229], v[96:111]
	v_mfma_f32_32x32x16_bf16 v[32:47], v[238:241], v[230:233], v[32:47]
	ds_read_b128 v[234:237], v205 offset:9216
	ds_read_b128 v[238:241], v205 offset:13824
	s_waitcnt vmcnt(7)
	ds_write_b128 v215, v[176:179] offset:9216
	s_waitcnt vmcnt(6)
	ds_write_b128 v215, v[180:183] offset:46080
	ds_read_b128 v[176:179], v208 offset:32
	ds_read_b128 v[180:183], v208 offset:4640
	s_waitcnt lgkmcnt(5)
	v_mfma_f32_32x32x16_bf16 v[80:95], v[234:237], v[226:229], v[80:95]
	v_mfma_f32_32x32x16_bf16 v[16:31], v[234:237], v[230:233], v[16:31]
	ds_read_b128 v[234:237], v205 offset:32
	s_waitcnt lgkmcnt(5)
	v_mfma_f32_32x32x16_bf16 v[64:79], v[238:241], v[226:229], v[64:79]
	v_mfma_f32_32x32x16_bf16 v[0:15], v[238:241], v[230:233], v[0:15]
	ds_read_b128 v[238:241], v205 offset:4640
	s_setprio 0
	global_load_dwordx4 v[226:229], v[194:195], off offset:2176
	global_load_dwordx4 v[230:233], v[196:197], off offset:2176
	s_setprio 1
	s_waitcnt lgkmcnt(1)
	v_mfma_f32_32x32x16_bf16 v[112:127], v[234:237], v[176:179], v[112:127]
	v_mfma_f32_32x32x16_bf16 v[48:63], v[234:237], v[180:183], v[48:63]
	s_waitcnt lgkmcnt(0)
	v_mfma_f32_32x32x16_bf16 v[96:111], v[238:241], v[176:179], v[96:111]
	v_mfma_f32_32x32x16_bf16 v[32:47], v[238:241], v[180:183], v[32:47]
	ds_read_b128 v[234:237], v205 offset:9248
	ds_read_b128 v[238:241], v205 offset:13856
	s_waitcnt vmcnt(7)
	ds_write_b128 v215, v[168:171] offset:18432
	s_waitcnt vmcnt(6)
	ds_write_b128 v215, v[172:175] offset:55296
	ds_read_b128 v[168:171], v208 offset:64
	ds_read_b128 v[172:175], v208 offset:4672
	s_waitcnt lgkmcnt(5)
	v_mfma_f32_32x32x16_bf16 v[80:95], v[234:237], v[176:179], v[80:95]
	v_mfma_f32_32x32x16_bf16 v[16:31], v[234:237], v[180:183], v[16:31]
	ds_read_b128 v[234:237], v205 offset:64
	s_waitcnt lgkmcnt(5)
	v_mfma_f32_32x32x16_bf16 v[64:79], v[238:241], v[176:179], v[64:79]
	v_mfma_f32_32x32x16_bf16 v[0:15], v[238:241], v[180:183], v[0:15]
	ds_read_b128 v[238:241], v205 offset:4672
	s_setprio 0
	global_load_dwordx4 v[176:179], v[184:185], off offset:2176
	global_load_dwordx4 v[180:183], v[186:187], off offset:2176
	s_setprio 1
	s_waitcnt lgkmcnt(1)
	v_mfma_f32_32x32x16_bf16 v[112:127], v[234:237], v[168:171], v[112:127]
	v_mfma_f32_32x32x16_bf16 v[48:63], v[234:237], v[172:175], v[48:63]
	s_waitcnt lgkmcnt(0)
	v_mfma_f32_32x32x16_bf16 v[96:111], v[238:241], v[168:171], v[96:111]
	v_mfma_f32_32x32x16_bf16 v[32:47], v[238:241], v[172:175], v[32:47]
	ds_read_b128 v[234:237], v205 offset:9280
	ds_read_b128 v[238:241], v205 offset:13888
	s_waitcnt vmcnt(7)
	ds_write_b128 v215, v[160:163] offset:27648
	s_waitcnt vmcnt(6)
	ds_write_b128 v215, v[164:167] offset:64512
	ds_read_b128 v[160:163], v208 offset:96
	ds_read_b128 v[164:167], v208 offset:4704
	s_waitcnt lgkmcnt(5)
	v_mfma_f32_32x32x16_bf16 v[80:95], v[234:237], v[168:171], v[80:95]
	v_mfma_f32_32x32x16_bf16 v[16:31], v[234:237], v[172:175], v[16:31]
	ds_read_b128 v[234:237], v205 offset:96
	s_waitcnt lgkmcnt(5)
	v_mfma_f32_32x32x16_bf16 v[64:79], v[238:241], v[168:171], v[64:79]
	v_mfma_f32_32x32x16_bf16 v[0:15], v[238:241], v[172:175], v[0:15]
	ds_read_b128 v[238:241], v205 offset:4704
	s_setprio 0
	global_load_dwordx4 v[168:171], v[198:199], off offset:2176
	global_load_dwordx4 v[172:175], v[200:201], off offset:2176
	s_setprio 1
	s_waitcnt lgkmcnt(1)
	v_mfma_f32_32x32x16_bf16 v[112:127], v[234:237], v[160:163], v[112:127]
	v_mfma_f32_32x32x16_bf16 v[48:63], v[234:237], v[164:167], v[48:63]
	s_waitcnt lgkmcnt(0)
	v_mfma_f32_32x32x16_bf16 v[96:111], v[238:241], v[160:163], v[96:111]
	v_mfma_f32_32x32x16_bf16 v[32:47], v[238:241], v[164:167], v[32:47]
	ds_read_b128 v[234:237], v205 offset:9312
	ds_read_b128 v[238:241], v205 offset:13920
	s_waitcnt lgkmcnt(1)
	v_mfma_f32_32x32x16_bf16 v[80:95], v[234:237], v[160:163], v[80:95]
	v_mfma_f32_32x32x16_bf16 v[16:31], v[234:237], v[164:167], v[16:31]
	s_waitcnt lgkmcnt(0)
	v_mfma_f32_32x32x16_bf16 v[64:79], v[238:241], v[160:163], v[64:79]
	v_mfma_f32_32x32x16_bf16 v[0:15], v[238:241], v[164:167], v[0:15]
	s_setprio 0
	global_load_dwordx4 v[160:163], v[190:191], off offset:2304
	global_load_dwordx4 v[164:167], v[188:189], off offset:2304
	s_barrier
; template <bool trans>
; DI void gemm_core(const GTile& tl, const GTile& nx, bool has_next  , bool chain  , bool pre, u32x4 (&ra)[4], u32x4 (&rb)[4], char* smem, f32x16 (&acc)[2][4]) {
;     ...
;   const int nk = K / 64;
;   if (!pre) { G_LOAD(0); G_STORE(0); G_LOAD(1); }
;   for (int kt = 0; kt < nk; ++kt) {
;     __syncthreads();
;     G_COMPUTE(kt & 1, kt);
;   }
	s_waitcnt vmcnt(9)
	ds_write_b128 v209, v[218:221]
	s_waitcnt vmcnt(8)
	ds_write_b128 v210, v[222:225]
	ds_read_b128 v[218:221], v204 offset:36864
	ds_read_b128 v[222:225], v204 offset:41472
	ds_read_b128 v[234:237], v192
	ds_read_b128 v[238:241], v192 offset:4608
	s_setprio 1
	s_waitcnt lgkmcnt(1)
	v_mfma_f32_32x32x16_bf16 v[112:127], v[234:237], v[218:221], v[112:127]
	v_mfma_f32_32x32x16_bf16 v[48:63], v[234:237], v[222:225], v[48:63]
	s_waitcnt lgkmcnt(0)
	v_mfma_f32_32x32x16_bf16 v[96:111], v[238:241], v[218:221], v[96:111]
	v_mfma_f32_32x32x16_bf16 v[32:47], v[238:241], v[222:225], v[32:47]
	ds_read_b128 v[234:237], v192 offset:9216
	ds_read_b128 v[238:241], v192 offset:13824
	s_waitcnt vmcnt(7)
	ds_write_b128 v212, v[226:229]
	s_waitcnt vmcnt(6)
	ds_write_b128 v211, v[230:233]
	ds_read_b128 v[226:229], v204 offset:36896
	ds_read_b128 v[230:233], v204 offset:41504
	s_waitcnt lgkmcnt(5)
	v_mfma_f32_32x32x16_bf16 v[80:95], v[234:237], v[218:221], v[80:95]
	v_mfma_f32_32x32x16_bf16 v[16:31], v[234:237], v[222:225], v[16:31]
	ds_read_b128 v[234:237], v192 offset:32
	s_waitcnt lgkmcnt(5)
	v_mfma_f32_32x32x16_bf16 v[64:79], v[238:241], v[218:221], v[64:79]
	v_mfma_f32_32x32x16_bf16 v[0:15], v[238:241], v[222:225], v[0:15]
	ds_read_b128 v[238:241], v192 offset:4640
	s_setprio 0
	global_load_dwordx4 v[218:221], v[194:195], off offset:2304
	global_load_dwordx4 v[222:225], v[196:197], off offset:2304
	s_setprio 1
	s_waitcnt lgkmcnt(1)
	v_mfma_f32_32x32x16_bf16 v[112:127], v[234:237], v[226:229], v[112:127]
	v_mfma_f32_32x32x16_bf16 v[48:63], v[234:237], v[230:233], v[48:63]
	s_waitcnt lgkmcnt(0)
	v_mfma_f32_32x32x16_bf16 v[96:111], v[238:241], v[226:229], v[96:111]
	v_mfma_f32_32x32x16_bf16 v[32:47], v[238:241], v[230:233], v[32:47]
	ds_read_b128 v[234:237], v192 offset:9248
	ds_read_b128 v[238:241], v192 offset:13856
	s_waitcnt vmcnt(7)
	ds_write_b128 v214, v[176:179]
	s_waitcnt vmcnt(6)
	ds_write_b128 v213, v[180:183]
	ds_read_b128 v[176:179], v204 offset:36928
	ds_read_b128 v[180:183], v204 offset:41536
	s_waitcnt lgkmcnt(5)
	v_mfma_f32_32x32x16_bf16 v[80:95], v[234:237], v[226:229], v[80:95]
	v_mfma_f32_32x32x16_bf16 v[16:31], v[234:237], v[230:233], v[16:31]
	ds_read_b128 v[234:237], v192 offset:64
	s_waitcnt lgkmcnt(5)
	v_mfma_f32_32x32x16_bf16 v[64:79], v[238:241], v[226:229], v[64:79]
	v_mfma_f32_32x32x16_bf16 v[0:15], v[238:241], v[230:233], v[0:15]
	ds_read_b128 v[238:241], v192 offset:4672
	s_setprio 0
	global_load_dwordx4 v[226:229], v[184:185], off offset:2304
	global_load_dwordx4 v[230:233], v[186:187], off offset:2304
	s_setprio 1
	s_waitcnt lgkmcnt(1)
	v_mfma_f32_32x32x16_bf16 v[112:127], v[234:237], v[176:179], v[112:127]
	v_mfma_f32_32x32x16_bf16 v[48:63], v[234:237], v[180:183], v[48:63]
	s_waitcnt lgkmcnt(0)
	v_mfma_f32_32x32x16_bf16 v[96:111], v[238:241], v[176:179], v[96:111]
	v_mfma_f32_32x32x16_bf16 v[32:47], v[238:241], v[180:183], v[32:47]
	ds_read_b128 v[234:237], v192 offset:9280
	ds_read_b128 v[238:241], v192 offset:13888
	s_waitcnt vmcnt(7)
	ds_write_b128 v217, v[168:171]
	s_waitcnt vmcnt(6)
	ds_write_b128 v216, v[172:175]
	ds_read_b128 v[168:171], v204 offset:36960
	ds_read_b128 v[172:175], v204 offset:41568
	s_waitcnt lgkmcnt(5)
	v_mfma_f32_32x32x16_bf16 v[80:95], v[234:237], v[176:179], v[80:95]
	v_mfma_f32_32x32x16_bf16 v[16:31], v[234:237], v[180:183], v[16:31]
	ds_read_b128 v[234:237], v192 offset:96
	s_waitcnt lgkmcnt(5)
	v_mfma_f32_32x32x16_bf16 v[64:79], v[238:241], v[176:179], v[64:79]
	v_mfma_f32_32x32x16_bf16 v[0:15], v[238:241], v[180:183], v[0:15]
	ds_read_b128 v[238:241], v192 offset:4704
	s_setprio 0
	global_load_dwordx4 v[176:179], v[198:199], off offset:2304
	global_load_dwordx4 v[180:183], v[200:201], off offset:2304
	s_setprio 1
	s_waitcnt lgkmcnt(1)
	v_mfma_f32_32x32x16_bf16 v[112:127], v[234:237], v[168:171], v[112:127]
	v_mfma_f32_32x32x16_bf16 v[48:63], v[234:237], v[172:175], v[48:63]
	s_waitcnt lgkmcnt(0)
	v_mfma_f32_32x32x16_bf16 v[96:111], v[238:241], v[168:171], v[96:111]
	v_mfma_f32_32x32x16_bf16 v[32:47], v[238:241], v[172:175], v[32:47]
	ds_read_b128 v[234:237], v192 offset:9312
	ds_read_b128 v[238:241], v192 offset:13920
	s_waitcnt lgkmcnt(1)
	v_mfma_f32_32x32x16_bf16 v[80:95], v[234:237], v[168:171], v[80:95]
	v_mfma_f32_32x32x16_bf16 v[16:31], v[234:237], v[172:175], v[16:31]
	s_waitcnt lgkmcnt(0)
	v_mfma_f32_32x32x16_bf16 v[64:79], v[238:241], v[168:171], v[64:79]
	v_mfma_f32_32x32x16_bf16 v[0:15], v[238:241], v[172:175], v[0:15]
	s_setprio 0
	global_load_dwordx4 v[168:171], v[190:191], off offset:2432
	global_load_dwordx4 v[172:175], v[188:189], off offset:2432
	s_barrier
; template <bool trans>
; DI void gemm_core(const GTile& tl, const GTile& nx, bool has_next  , bool chain  , bool pre, u32x4 (&ra)[4], u32x4 (&rb)[4], char* smem, f32x16 (&acc)[2][4]) {
;     ...
;   const int nk = K / 64;
;   if (!pre) { G_LOAD(0); G_STORE(0); G_LOAD(1); }
;   for (int kt = 0; kt < nk; ++kt) {
;     __syncthreads();
;     G_COMPUTE(kt & 1, kt);
;   }
	s_waitcnt vmcnt(9)
	ds_write_b128 v215, v[160:163]
	s_waitcnt vmcnt(8)
	ds_write_b128 v215, v[164:167] offset:36864
	ds_read_b128 v[160:163], v208
	ds_read_b128 v[164:167], v208 offset:4608
	ds_read_b128 v[234:237], v205
	ds_read_b128 v[238:241], v205 offset:4608
	s_setprio 1
	s_waitcnt lgkmcnt(1)
	v_mfma_f32_32x32x16_bf16 v[112:127], v[234:237], v[160:163], v[112:127]
	v_mfma_f32_32x32x16_bf16 v[48:63], v[234:237], v[164:167], v[48:63]
	s_waitcnt lgkmcnt(0)
	v_mfma_f32_32x32x16_bf16 v[96:111], v[238:241], v[160:163], v[96:111]
	v_mfma_f32_32x32x16_bf16 v[32:47], v[238:241], v[164:167], v[32:47]
	ds_read_b128 v[234:237], v205 offset:9216
	ds_read_b128 v[238:241], v205 offset:13824
	s_waitcnt vmcnt(7)
	ds_write_b128 v215, v[218:221] offset:9216
	s_waitcnt vmcnt(6)
	ds_write_b128 v215, v[222:225] offset:46080
	ds_read_b128 v[218:221], v208 offset:32
	ds_read_b128 v[222:225], v208 offset:4640
	s_waitcnt lgkmcnt(5)
	v_mfma_f32_32x32x16_bf16 v[80:95], v[234:237], v[160:163], v[80:95]
	v_mfma_f32_32x32x16_bf16 v[16:31], v[234:237], v[164:167], v[16:31]
	ds_read_b128 v[234:237], v205 offset:32
	s_waitcnt lgkmcnt(5)
	v_mfma_f32_32x32x16_bf16 v[64:79], v[238:241], v[160:163], v[64:79]
	v_mfma_f32_32x32x16_bf16 v[0:15], v[238:241], v[164:167], v[0:15]
	ds_read_b128 v[238:241], v205 offset:4640
	s_setprio 0
	global_load_dwordx4 v[160:163], v[194:195], off offset:2432
	global_load_dwordx4 v[164:167], v[196:197], off offset:2432
	s_setprio 1
	s_waitcnt lgkmcnt(1)
	v_mfma_f32_32x32x16_bf16 v[112:127], v[234:237], v[218:221], v[112:127]
	v_mfma_f32_32x32x16_bf16 v[48:63], v[234:237], v[222:225], v[48:63]
	s_waitcnt lgkmcnt(0)
	v_mfma_f32_32x32x16_bf16 v[96:111], v[238:241], v[218:221], v[96:111]
	v_mfma_f32_32x32x16_bf16 v[32:47], v[238:241], v[222:225], v[32:47]
	ds_read_b128 v[234:237], v205 offset:9248
	ds_read_b128 v[238:241], v205 offset:13856
	s_waitcnt vmcnt(7)
	ds_write_b128 v215, v[226:229] offset:18432
	s_waitcnt vmcnt(6)
	ds_write_b128 v215, v[230:233] offset:55296
	ds_read_b128 v[226:229], v208 offset:64
	ds_read_b128 v[230:233], v208 offset:4672
	s_waitcnt lgkmcnt(5)
	v_mfma_f32_32x32x16_bf16 v[80:95], v[234:237], v[218:221], v[80:95]
	v_mfma_f32_32x32x16_bf16 v[16:31], v[234:237], v[222:225], v[16:31]
	ds_read_b128 v[234:237], v205 offset:64
	s_waitcnt lgkmcnt(5)
	v_mfma_f32_32x32x16_bf16 v[64:79], v[238:241], v[218:221], v[64:79]
	v_mfma_f32_32x32x16_bf16 v[0:15], v[238:241], v[222:225], v[0:15]
	ds_read_b128 v[238:241], v205 offset:4672
	s_setprio 0
	global_load_dwordx4 v[218:221], v[184:185], off offset:2432
	global_load_dwordx4 v[222:225], v[186:187], off offset:2432
	s_setprio 1
	s_waitcnt lgkmcnt(1)
	v_mfma_f32_32x32x16_bf16 v[112:127], v[234:237], v[226:229], v[112:127]
	v_mfma_f32_32x32x16_bf16 v[48:63], v[234:237], v[230:233], v[48:63]
	s_waitcnt lgkmcnt(0)
	v_mfma_f32_32x32x16_bf16 v[96:111], v[238:241], v[226:229], v[96:111]
	v_mfma_f32_32x32x16_bf16 v[32:47], v[238:241], v[230:233], v[32:47]
	ds_read_b128 v[234:237], v205 offset:9280
	ds_read_b128 v[238:241], v205 offset:13888
	s_waitcnt vmcnt(7)
	ds_write_b128 v215, v[176:179] offset:27648
	s_waitcnt vmcnt(6)
	ds_write_b128 v215, v[180:183] offset:64512
	ds_read_b128 v[176:179], v208 offset:96
	ds_read_b128 v[180:183], v208 offset:4704
	s_waitcnt lgkmcnt(5)
	v_mfma_f32_32x32x16_bf16 v[80:95], v[234:237], v[226:229], v[80:95]
	v_mfma_f32_32x32x16_bf16 v[16:31], v[234:237], v[230:233], v[16:31]
	ds_read_b128 v[234:237], v205 offset:96
	s_waitcnt lgkmcnt(5)
	v_mfma_f32_32x32x16_bf16 v[64:79], v[238:241], v[226:229], v[64:79]
	v_mfma_f32_32x32x16_bf16 v[0:15], v[238:241], v[230:233], v[0:15]
	ds_read_b128 v[238:241], v205 offset:4704
	s_setprio 0
	global_load_dwordx4 v[226:229], v[198:199], off offset:2432
	global_load_dwordx4 v[230:233], v[200:201], off offset:2432
	s_setprio 1
	s_waitcnt lgkmcnt(1)
	v_mfma_f32_32x32x16_bf16 v[112:127], v[234:237], v[176:179], v[112:127]
	v_mfma_f32_32x32x16_bf16 v[48:63], v[234:237], v[180:183], v[48:63]
	s_waitcnt lgkmcnt(0)
	v_mfma_f32_32x32x16_bf16 v[96:111], v[238:241], v[176:179], v[96:111]
	v_mfma_f32_32x32x16_bf16 v[32:47], v[238:241], v[180:183], v[32:47]
	ds_read_b128 v[234:237], v205 offset:9312
	ds_read_b128 v[238:241], v205 offset:13920
	s_waitcnt lgkmcnt(1)
	v_mfma_f32_32x32x16_bf16 v[80:95], v[234:237], v[176:179], v[80:95]
	v_mfma_f32_32x32x16_bf16 v[16:31], v[234:237], v[180:183], v[16:31]
	s_waitcnt lgkmcnt(0)
	v_mfma_f32_32x32x16_bf16 v[64:79], v[238:241], v[176:179], v[64:79]
	v_mfma_f32_32x32x16_bf16 v[0:15], v[238:241], v[180:183], v[0:15]
	s_setprio 0
	global_load_dwordx4 v[176:179], v[190:191], off offset:2560
	global_load_dwordx4 v[180:183], v[188:189], off offset:2560
	s_barrier
; template <bool trans>
; DI void gemm_core(const GTile& tl, const GTile& nx, bool has_next  , bool chain  , bool pre, u32x4 (&ra)[4], u32x4 (&rb)[4], char* smem, f32x16 (&acc)[2][4]) {
;     ...
;   const int nk = K / 64;
;   if (!pre) { G_LOAD(0); G_STORE(0); G_LOAD(1); }
;   for (int kt = 0; kt < nk; ++kt) {
;     __syncthreads();
;     G_COMPUTE(kt & 1, kt);
;   }
	s_waitcnt vmcnt(9)
	ds_write_b128 v209, v[168:171]
	s_waitcnt vmcnt(8)
	ds_write_b128 v210, v[172:175]
	ds_read_b128 v[168:171], v204 offset:36864
	ds_read_b128 v[172:175], v204 offset:41472
	ds_read_b128 v[234:237], v192
	ds_read_b128 v[238:241], v192 offset:4608
	s_setprio 1
	s_waitcnt lgkmcnt(1)
	v_mfma_f32_32x32x16_bf16 v[112:127], v[234:237], v[168:171], v[112:127]
	v_mfma_f32_32x32x16_bf16 v[48:63], v[234:237], v[172:175], v[48:63]
	s_waitcnt lgkmcnt(0)
	v_mfma_f32_32x32x16_bf16 v[96:111], v[238:241], v[168:171], v[96:111]
	v_mfma_f32_32x32x16_bf16 v[32:47], v[238:241], v[172:175], v[32:47]
	ds_read_b128 v[234:237], v192 offset:9216
	ds_read_b128 v[238:241], v192 offset:13824
	s_waitcnt vmcnt(7)
	ds_write_b128 v212, v[160:163]
	s_waitcnt vmcnt(6)
	ds_write_b128 v211, v[164:167]
	ds_read_b128 v[160:163], v204 offset:36896
	ds_read_b128 v[164:167], v204 offset:41504
	s_waitcnt lgkmcnt(5)
	v_mfma_f32_32x32x16_bf16 v[80:95], v[234:237], v[168:171], v[80:95]
	v_mfma_f32_32x32x16_bf16 v[16:31], v[234:237], v[172:175], v[16:31]
	ds_read_b128 v[234:237], v192 offset:32
	s_waitcnt lgkmcnt(5)
	v_mfma_f32_32x32x16_bf16 v[64:79], v[238:241], v[168:171], v[64:79]
	v_mfma_f32_32x32x16_bf16 v[0:15], v[238:241], v[172:175], v[0:15]
	ds_read_b128 v[238:241], v192 offset:4640
	s_setprio 0
	global_load_dwordx4 v[168:171], v[194:195], off offset:2560
	global_load_dwordx4 v[172:175], v[196:197], off offset:2560
	s_setprio 1
	s_waitcnt lgkmcnt(1)
	v_mfma_f32_32x32x16_bf16 v[112:127], v[234:237], v[160:163], v[112:127]
	v_mfma_f32_32x32x16_bf16 v[48:63], v[234:237], v[164:167], v[48:63]
	s_waitcnt lgkmcnt(0)
	v_mfma_f32_32x32x16_bf16 v[96:111], v[238:241], v[160:163], v[96:111]
	v_mfma_f32_32x32x16_bf16 v[32:47], v[238:241], v[164:167], v[32:47]
	ds_read_b128 v[234:237], v192 offset:9248
	ds_read_b128 v[238:241], v192 offset:13856
	s_waitcnt vmcnt(7)
	ds_write_b128 v214, v[218:221]
	s_waitcnt vmcnt(6)
	ds_write_b128 v213, v[222:225]
	ds_read_b128 v[218:221], v204 offset:36928
	ds_read_b128 v[222:225], v204 offset:41536
	s_waitcnt lgkmcnt(5)
	v_mfma_f32_32x32x16_bf16 v[80:95], v[234:237], v[160:163], v[80:95]
	v_mfma_f32_32x32x16_bf16 v[16:31], v[234:237], v[164:167], v[16:31]
	ds_read_b128 v[234:237], v192 offset:64
	s_waitcnt lgkmcnt(5)
	v_mfma_f32_32x32x16_bf16 v[64:79], v[238:241], v[160:163], v[64:79]
	v_mfma_f32_32x32x16_bf16 v[0:15], v[238:241], v[164:167], v[0:15]
	ds_read_b128 v[238:241], v192 offset:4672
	s_setprio 0
	global_load_dwordx4 v[160:163], v[184:185], off offset:2560
	global_load_dwordx4 v[164:167], v[186:187], off offset:2560
	s_setprio 1
	s_waitcnt lgkmcnt(1)
	v_mfma_f32_32x32x16_bf16 v[112:127], v[234:237], v[218:221], v[112:127]
	v_mfma_f32_32x32x16_bf16 v[48:63], v[234:237], v[222:225], v[48:63]
	s_waitcnt lgkmcnt(0)
	v_mfma_f32_32x32x16_bf16 v[96:111], v[238:241], v[218:221], v[96:111]
	v_mfma_f32_32x32x16_bf16 v[32:47], v[238:241], v[222:225], v[32:47]
	ds_read_b128 v[234:237], v192 offset:9280
	ds_read_b128 v[238:241], v192 offset:13888
	s_waitcnt vmcnt(7)
	ds_write_b128 v217, v[226:229]
	s_waitcnt vmcnt(6)
	ds_write_b128 v216, v[230:233]
	ds_read_b128 v[226:229], v204 offset:36960
	ds_read_b128 v[230:233], v204 offset:41568
	s_waitcnt lgkmcnt(5)
	v_mfma_f32_32x32x16_bf16 v[80:95], v[234:237], v[218:221], v[80:95]
	v_mfma_f32_32x32x16_bf16 v[16:31], v[234:237], v[222:225], v[16:31]
	ds_read_b128 v[234:237], v192 offset:96
	s_waitcnt lgkmcnt(5)
	v_mfma_f32_32x32x16_bf16 v[64:79], v[238:241], v[218:221], v[64:79]
	v_mfma_f32_32x32x16_bf16 v[0:15], v[238:241], v[222:225], v[0:15]
	ds_read_b128 v[238:241], v192 offset:4704
	s_setprio 0
	global_load_dwordx4 v[218:221], v[198:199], off offset:2560
	global_load_dwordx4 v[222:225], v[200:201], off offset:2560
	s_setprio 1
	s_waitcnt lgkmcnt(1)
	v_mfma_f32_32x32x16_bf16 v[112:127], v[234:237], v[226:229], v[112:127]
	v_mfma_f32_32x32x16_bf16 v[48:63], v[234:237], v[230:233], v[48:63]
	s_waitcnt lgkmcnt(0)
	v_mfma_f32_32x32x16_bf16 v[96:111], v[238:241], v[226:229], v[96:111]
	v_mfma_f32_32x32x16_bf16 v[32:47], v[238:241], v[230:233], v[32:47]
	ds_read_b128 v[234:237], v192 offset:9312
	ds_read_b128 v[238:241], v192 offset:13920
	s_waitcnt lgkmcnt(1)
	v_mfma_f32_32x32x16_bf16 v[80:95], v[234:237], v[226:229], v[80:95]
	v_mfma_f32_32x32x16_bf16 v[16:31], v[234:237], v[230:233], v[16:31]
	s_waitcnt lgkmcnt(0)
	v_mfma_f32_32x32x16_bf16 v[64:79], v[238:241], v[226:229], v[64:79]
	v_mfma_f32_32x32x16_bf16 v[0:15], v[238:241], v[230:233], v[0:15]
	s_setprio 0
	global_load_dwordx4 v[226:229], v[190:191], off offset:2688
	global_load_dwordx4 v[230:233], v[188:189], off offset:2688
	s_barrier
; template <bool trans>
; DI void gemm_core(const GTile& tl, const GTile& nx, bool has_next  , bool chain  , bool pre, u32x4 (&ra)[4], u32x4 (&rb)[4], char* smem, f32x16 (&acc)[2][4]) {
;     ...
;   const int nk = K / 64;
;   if (!pre) { G_LOAD(0); G_STORE(0); G_LOAD(1); }
;   for (int kt = 0; kt < nk; ++kt) {
;     __syncthreads();
;     G_COMPUTE(kt & 1, kt);
;   }
	s_waitcnt vmcnt(9)
	ds_write_b128 v215, v[176:179]
	s_waitcnt vmcnt(8)
	ds_write_b128 v215, v[180:183] offset:36864
	ds_read_b128 v[176:179], v208
	ds_read_b128 v[180:183], v208 offset:4608
	ds_read_b128 v[234:237], v205
	ds_read_b128 v[238:241], v205 offset:4608
	s_setprio 1
	s_waitcnt lgkmcnt(1)
	v_mfma_f32_32x32x16_bf16 v[112:127], v[234:237], v[176:179], v[112:127]
	v_mfma_f32_32x32x16_bf16 v[48:63], v[234:237], v[180:183], v[48:63]
	s_waitcnt lgkmcnt(0)
	v_mfma_f32_32x32x16_bf16 v[96:111], v[238:241], v[176:179], v[96:111]
	v_mfma_f32_32x32x16_bf16 v[32:47], v[238:241], v[180:183], v[32:47]
	ds_read_b128 v[234:237], v205 offset:9216
	ds_read_b128 v[238:241], v205 offset:13824
	s_waitcnt vmcnt(7)
	ds_write_b128 v215, v[168:171] offset:9216
	s_waitcnt vmcnt(6)
	ds_write_b128 v215, v[172:175] offset:46080
	ds_read_b128 v[168:171], v208 offset:32
	ds_read_b128 v[172:175], v208 offset:4640
	s_waitcnt lgkmcnt(5)
	v_mfma_f32_32x32x16_bf16 v[80:95], v[234:237], v[176:179], v[80:95]
	v_mfma_f32_32x32x16_bf16 v[16:31], v[234:237], v[180:183], v[16:31]
	ds_read_b128 v[234:237], v205 offset:32
	s_waitcnt lgkmcnt(5)
	v_mfma_f32_32x32x16_bf16 v[64:79], v[238:241], v[176:179], v[64:79]
	v_mfma_f32_32x32x16_bf16 v[0:15], v[238:241], v[180:183], v[0:15]
	ds_read_b128 v[238:241], v205 offset:4640
	s_setprio 0
	global_load_dwordx4 v[176:179], v[194:195], off offset:2688
	global_load_dwordx4 v[180:183], v[196:197], off offset:2688
	s_setprio 1
	s_waitcnt lgkmcnt(1)
	v_mfma_f32_32x32x16_bf16 v[112:127], v[234:237], v[168:171], v[112:127]
	v_mfma_f32_32x32x16_bf16 v[48:63], v[234:237], v[172:175], v[48:63]
	s_waitcnt lgkmcnt(0)
	v_mfma_f32_32x32x16_bf16 v[96:111], v[238:241], v[168:171], v[96:111]
	v_mfma_f32_32x32x16_bf16 v[32:47], v[238:241], v[172:175], v[32:47]
	ds_read_b128 v[234:237], v205 offset:9248
	ds_read_b128 v[238:241], v205 offset:13856
	s_waitcnt vmcnt(7)
	ds_write_b128 v215, v[160:163] offset:18432
	s_waitcnt vmcnt(6)
	ds_write_b128 v215, v[164:167] offset:55296
	ds_read_b128 v[160:163], v208 offset:64
	ds_read_b128 v[164:167], v208 offset:4672
	s_waitcnt lgkmcnt(5)
	v_mfma_f32_32x32x16_bf16 v[80:95], v[234:237], v[168:171], v[80:95]
	v_mfma_f32_32x32x16_bf16 v[16:31], v[234:237], v[172:175], v[16:31]
	ds_read_b128 v[234:237], v205 offset:64
	s_waitcnt lgkmcnt(5)
	v_mfma_f32_32x32x16_bf16 v[64:79], v[238:241], v[168:171], v[64:79]
	v_mfma_f32_32x32x16_bf16 v[0:15], v[238:241], v[172:175], v[0:15]
	ds_read_b128 v[238:241], v205 offset:4672
	s_setprio 0
	global_load_dwordx4 v[168:171], v[184:185], off offset:2688
	global_load_dwordx4 v[172:175], v[186:187], off offset:2688
	s_setprio 1
	s_waitcnt lgkmcnt(1)
	v_mfma_f32_32x32x16_bf16 v[112:127], v[234:237], v[160:163], v[112:127]
	v_mfma_f32_32x32x16_bf16 v[48:63], v[234:237], v[164:167], v[48:63]
	s_waitcnt lgkmcnt(0)
	v_mfma_f32_32x32x16_bf16 v[96:111], v[238:241], v[160:163], v[96:111]
	v_mfma_f32_32x32x16_bf16 v[32:47], v[238:241], v[164:167], v[32:47]
	ds_read_b128 v[234:237], v205 offset:9280
	ds_read_b128 v[238:241], v205 offset:13888
	s_waitcnt vmcnt(7)
	ds_write_b128 v215, v[218:221] offset:27648
	s_waitcnt vmcnt(6)
	ds_write_b128 v215, v[222:225] offset:64512
	ds_read_b128 v[218:221], v208 offset:96
	ds_read_b128 v[222:225], v208 offset:4704
	s_waitcnt lgkmcnt(5)
	v_mfma_f32_32x32x16_bf16 v[80:95], v[234:237], v[160:163], v[80:95]
	v_mfma_f32_32x32x16_bf16 v[16:31], v[234:237], v[164:167], v[16:31]
	ds_read_b128 v[234:237], v205 offset:96
	s_waitcnt lgkmcnt(5)
	v_mfma_f32_32x32x16_bf16 v[64:79], v[238:241], v[160:163], v[64:79]
	v_mfma_f32_32x32x16_bf16 v[0:15], v[238:241], v[164:167], v[0:15]
	ds_read_b128 v[238:241], v205 offset:4704
	s_setprio 0
	global_load_dwordx4 v[160:163], v[198:199], off offset:2688
	global_load_dwordx4 v[164:167], v[200:201], off offset:2688
	s_setprio 1
	s_waitcnt lgkmcnt(1)
	v_mfma_f32_32x32x16_bf16 v[112:127], v[234:237], v[218:221], v[112:127]
	v_mfma_f32_32x32x16_bf16 v[48:63], v[234:237], v[222:225], v[48:63]
	s_waitcnt lgkmcnt(0)
	v_mfma_f32_32x32x16_bf16 v[96:111], v[238:241], v[218:221], v[96:111]
	v_mfma_f32_32x32x16_bf16 v[32:47], v[238:241], v[222:225], v[32:47]
	ds_read_b128 v[234:237], v205 offset:9312
	ds_read_b128 v[238:241], v205 offset:13920
	s_waitcnt lgkmcnt(1)
	v_mfma_f32_32x32x16_bf16 v[80:95], v[234:237], v[218:221], v[80:95]
	v_mfma_f32_32x32x16_bf16 v[16:31], v[234:237], v[222:225], v[16:31]
	s_waitcnt lgkmcnt(0)
	v_mfma_f32_32x32x16_bf16 v[64:79], v[238:241], v[218:221], v[64:79]
	v_mfma_f32_32x32x16_bf16 v[0:15], v[238:241], v[222:225], v[0:15]
	s_setprio 0
	global_load_dwordx4 v[218:221], v[190:191], off offset:2816
	global_load_dwordx4 v[222:225], v[188:189], off offset:2816
	s_barrier
; template <bool trans>
; DI void gemm_core(const GTile& tl, const GTile& nx, bool has_next  , bool chain  , bool pre, u32x4 (&ra)[4], u32x4 (&rb)[4], char* smem, f32x16 (&acc)[2][4]) {
;     ...
;   const int nk = K / 64;
;   if (!pre) { G_LOAD(0); G_STORE(0); G_LOAD(1); }
;   for (int kt = 0; kt < nk; ++kt) {
;     __syncthreads();
;     G_COMPUTE(kt & 1, kt);
;   }
	s_waitcnt vmcnt(9)
	ds_write_b128 v209, v[226:229]
	s_waitcnt vmcnt(8)
	ds_write_b128 v210, v[230:233]
	ds_read_b128 v[226:229], v204 offset:36864
	ds_read_b128 v[230:233], v204 offset:41472
	ds_read_b128 v[234:237], v192
	ds_read_b128 v[238:241], v192 offset:4608
	s_setprio 1
	s_waitcnt lgkmcnt(1)
	v_mfma_f32_32x32x16_bf16 v[112:127], v[234:237], v[226:229], v[112:127]
	v_mfma_f32_32x32x16_bf16 v[48:63], v[234:237], v[230:233], v[48:63]
	s_waitcnt lgkmcnt(0)
	v_mfma_f32_32x32x16_bf16 v[96:111], v[238:241], v[226:229], v[96:111]
	v_mfma_f32_32x32x16_bf16 v[32:47], v[238:241], v[230:233], v[32:47]
	ds_read_b128 v[234:237], v192 offset:9216
	ds_read_b128 v[238:241], v192 offset:13824
	s_waitcnt vmcnt(7)
	ds_write_b128 v212, v[176:179]
	s_waitcnt vmcnt(6)
	ds_write_b128 v211, v[180:183]
	ds_read_b128 v[176:179], v204 offset:36896
	ds_read_b128 v[180:183], v204 offset:41504
	s_waitcnt lgkmcnt(5)
	v_mfma_f32_32x32x16_bf16 v[80:95], v[234:237], v[226:229], v[80:95]
	v_mfma_f32_32x32x16_bf16 v[16:31], v[234:237], v[230:233], v[16:31]
	ds_read_b128 v[234:237], v192 offset:32
	s_waitcnt lgkmcnt(5)
	v_mfma_f32_32x32x16_bf16 v[64:79], v[238:241], v[226:229], v[64:79]
	v_mfma_f32_32x32x16_bf16 v[0:15], v[238:241], v[230:233], v[0:15]
	ds_read_b128 v[238:241], v192 offset:4640
	s_setprio 0
	global_load_dwordx4 v[226:229], v[194:195], off offset:2816
	global_load_dwordx4 v[230:233], v[196:197], off offset:2816
	s_setprio 1
	s_waitcnt lgkmcnt(1)
	v_mfma_f32_32x32x16_bf16 v[112:127], v[234:237], v[176:179], v[112:127]
	v_mfma_f32_32x32x16_bf16 v[48:63], v[234:237], v[180:183], v[48:63]
	s_waitcnt lgkmcnt(0)
	v_mfma_f32_32x32x16_bf16 v[96:111], v[238:241], v[176:179], v[96:111]
	v_mfma_f32_32x32x16_bf16 v[32:47], v[238:241], v[180:183], v[32:47]
	ds_read_b128 v[234:237], v192 offset:9248
	ds_read_b128 v[238:241], v192 offset:13856
	s_waitcnt vmcnt(7)
	ds_write_b128 v214, v[168:171]
	s_waitcnt vmcnt(6)
	ds_write_b128 v213, v[172:175]
	ds_read_b128 v[168:171], v204 offset:36928
	ds_read_b128 v[172:175], v204 offset:41536
	s_waitcnt lgkmcnt(5)
	v_mfma_f32_32x32x16_bf16 v[80:95], v[234:237], v[176:179], v[80:95]
	v_mfma_f32_32x32x16_bf16 v[16:31], v[234:237], v[180:183], v[16:31]
	ds_read_b128 v[234:237], v192 offset:64
	s_waitcnt lgkmcnt(5)
	v_mfma_f32_32x32x16_bf16 v[64:79], v[238:241], v[176:179], v[64:79]
	v_mfma_f32_32x32x16_bf16 v[0:15], v[238:241], v[180:183], v[0:15]
	ds_read_b128 v[238:241], v192 offset:4672
	s_setprio 0
	global_load_dwordx4 v[176:179], v[184:185], off offset:2816
	global_load_dwordx4 v[180:183], v[186:187], off offset:2816
	s_setprio 1
	s_waitcnt lgkmcnt(1)
	v_mfma_f32_32x32x16_bf16 v[112:127], v[234:237], v[168:171], v[112:127]
	v_mfma_f32_32x32x16_bf16 v[48:63], v[234:237], v[172:175], v[48:63]
	s_waitcnt lgkmcnt(0)
	v_mfma_f32_32x32x16_bf16 v[96:111], v[238:241], v[168:171], v[96:111]
	v_mfma_f32_32x32x16_bf16 v[32:47], v[238:241], v[172:175], v[32:47]
	ds_read_b128 v[234:237], v192 offset:9280
	ds_read_b128 v[238:241], v192 offset:13888
	s_waitcnt vmcnt(7)
	ds_write_b128 v217, v[160:163]
	s_waitcnt vmcnt(6)
	ds_write_b128 v216, v[164:167]
	ds_read_b128 v[160:163], v204 offset:36960
	ds_read_b128 v[164:167], v204 offset:41568
	s_waitcnt lgkmcnt(5)
	v_mfma_f32_32x32x16_bf16 v[80:95], v[234:237], v[168:171], v[80:95]
	v_mfma_f32_32x32x16_bf16 v[16:31], v[234:237], v[172:175], v[16:31]
	ds_read_b128 v[234:237], v192 offset:96
	s_waitcnt lgkmcnt(5)
	v_mfma_f32_32x32x16_bf16 v[64:79], v[238:241], v[168:171], v[64:79]
	v_mfma_f32_32x32x16_bf16 v[0:15], v[238:241], v[172:175], v[0:15]
	ds_read_b128 v[238:241], v192 offset:4704
	s_setprio 0
	global_load_dwordx4 v[168:171], v[198:199], off offset:2816
	global_load_dwordx4 v[172:175], v[200:201], off offset:2816
	s_setprio 1
	s_waitcnt lgkmcnt(1)
	v_mfma_f32_32x32x16_bf16 v[112:127], v[234:237], v[160:163], v[112:127]
	v_mfma_f32_32x32x16_bf16 v[48:63], v[234:237], v[164:167], v[48:63]
	s_waitcnt lgkmcnt(0)
	v_mfma_f32_32x32x16_bf16 v[96:111], v[238:241], v[160:163], v[96:111]
	v_mfma_f32_32x32x16_bf16 v[32:47], v[238:241], v[164:167], v[32:47]
	ds_read_b128 v[234:237], v192 offset:9312
	ds_read_b128 v[238:241], v192 offset:13920
	s_waitcnt lgkmcnt(1)
	v_mfma_f32_32x32x16_bf16 v[80:95], v[234:237], v[160:163], v[80:95]
	v_mfma_f32_32x32x16_bf16 v[16:31], v[234:237], v[164:167], v[16:31]
	s_waitcnt lgkmcnt(0)
	v_mfma_f32_32x32x16_bf16 v[64:79], v[238:241], v[160:163], v[64:79]
	v_mfma_f32_32x32x16_bf16 v[0:15], v[238:241], v[164:167], v[0:15]
	s_setprio 0
	global_load_dwordx4 v[160:163], v[190:191], off offset:2944
	global_load_dwordx4 v[164:167], v[188:189], off offset:2944
	s_barrier
; template <bool trans>
; DI void gemm_core(const GTile& tl, const GTile& nx, bool has_next  , bool chain  , bool pre, u32x4 (&ra)[4], u32x4 (&rb)[4], char* smem, f32x16 (&acc)[2][4]) {
;     ...
;   const int nk = K / 64;
;   if (!pre) { G_LOAD(0); G_STORE(0); G_LOAD(1); }
;   for (int kt = 0; kt < nk; ++kt) {
;     __syncthreads();
;     G_COMPUTE(kt & 1, kt);
;   }
	s_waitcnt vmcnt(9)
	ds_write_b128 v215, v[218:221]
	s_waitcnt vmcnt(8)
	ds_write_b128 v215, v[222:225] offset:36864
	ds_read_b128 v[218:221], v208
	ds_read_b128 v[222:225], v208 offset:4608
	ds_read_b128 v[234:237], v205
	ds_read_b128 v[238:241], v205 offset:4608
	s_setprio 1
	s_waitcnt lgkmcnt(1)
	v_mfma_f32_32x32x16_bf16 v[112:127], v[234:237], v[218:221], v[112:127]
	v_mfma_f32_32x32x16_bf16 v[48:63], v[234:237], v[222:225], v[48:63]
	s_waitcnt lgkmcnt(0)
	v_mfma_f32_32x32x16_bf16 v[96:111], v[238:241], v[218:221], v[96:111]
	v_mfma_f32_32x32x16_bf16 v[32:47], v[238:241], v[222:225], v[32:47]
	ds_read_b128 v[234:237], v205 offset:9216
	ds_read_b128 v[238:241], v205 offset:13824
	s_waitcnt vmcnt(7)
	ds_write_b128 v215, v[226:229] offset:9216
	s_waitcnt vmcnt(6)
	ds_write_b128 v215, v[230:233] offset:46080
	ds_read_b128 v[226:229], v208 offset:32
	ds_read_b128 v[230:233], v208 offset:4640
	s_waitcnt lgkmcnt(5)
	v_mfma_f32_32x32x16_bf16 v[80:95], v[234:237], v[218:221], v[80:95]
	v_mfma_f32_32x32x16_bf16 v[16:31], v[234:237], v[222:225], v[16:31]
	ds_read_b128 v[234:237], v205 offset:32
	s_waitcnt lgkmcnt(5)
	v_mfma_f32_32x32x16_bf16 v[64:79], v[238:241], v[218:221], v[64:79]
	v_mfma_f32_32x32x16_bf16 v[0:15], v[238:241], v[222:225], v[0:15]
	ds_read_b128 v[238:241], v205 offset:4640
	s_setprio 0
	global_load_dwordx4 v[218:221], v[194:195], off offset:2944
	global_load_dwordx4 v[222:225], v[196:197], off offset:2944
	s_setprio 1
	s_waitcnt lgkmcnt(1)
	v_mfma_f32_32x32x16_bf16 v[112:127], v[234:237], v[226:229], v[112:127]
	v_mfma_f32_32x32x16_bf16 v[48:63], v[234:237], v[230:233], v[48:63]
	s_waitcnt lgkmcnt(0)
	v_mfma_f32_32x32x16_bf16 v[96:111], v[238:241], v[226:229], v[96:111]
	v_mfma_f32_32x32x16_bf16 v[32:47], v[238:241], v[230:233], v[32:47]
	ds_read_b128 v[234:237], v205 offset:9248
	ds_read_b128 v[238:241], v205 offset:13856
	s_waitcnt vmcnt(7)
	ds_write_b128 v215, v[176:179] offset:18432
	s_waitcnt vmcnt(6)
	ds_write_b128 v215, v[180:183] offset:55296
	ds_read_b128 v[176:179], v208 offset:64
	ds_read_b128 v[180:183], v208 offset:4672
	s_waitcnt lgkmcnt(5)
	v_mfma_f32_32x32x16_bf16 v[80:95], v[234:237], v[226:229], v[80:95]
	v_mfma_f32_32x32x16_bf16 v[16:31], v[234:237], v[230:233], v[16:31]
	ds_read_b128 v[234:237], v205 offset:64
	s_waitcnt lgkmcnt(5)
	v_mfma_f32_32x32x16_bf16 v[64:79], v[238:241], v[226:229], v[64:79]
	v_mfma_f32_32x32x16_bf16 v[0:15], v[238:241], v[230:233], v[0:15]
	ds_read_b128 v[238:241], v205 offset:4672
	s_setprio 0
	global_load_dwordx4 v[226:229], v[184:185], off offset:2944
	global_load_dwordx4 v[230:233], v[186:187], off offset:2944
	s_setprio 1
	s_waitcnt lgkmcnt(1)
	v_mfma_f32_32x32x16_bf16 v[112:127], v[234:237], v[176:179], v[112:127]
	v_mfma_f32_32x32x16_bf16 v[48:63], v[234:237], v[180:183], v[48:63]
	s_waitcnt lgkmcnt(0)
	v_mfma_f32_32x32x16_bf16 v[96:111], v[238:241], v[176:179], v[96:111]
	v_mfma_f32_32x32x16_bf16 v[32:47], v[238:241], v[180:183], v[32:47]
	ds_read_b128 v[234:237], v205 offset:9280
	ds_read_b128 v[238:241], v205 offset:13888
	s_waitcnt vmcnt(7)
	ds_write_b128 v215, v[168:171] offset:27648
	s_waitcnt vmcnt(6)
	ds_write_b128 v215, v[172:175] offset:64512
	ds_read_b128 v[168:171], v208 offset:96
	ds_read_b128 v[172:175], v208 offset:4704
	s_waitcnt lgkmcnt(5)
	v_mfma_f32_32x32x16_bf16 v[80:95], v[234:237], v[176:179], v[80:95]
	v_mfma_f32_32x32x16_bf16 v[16:31], v[234:237], v[180:183], v[16:31]
	ds_read_b128 v[234:237], v205 offset:96
	s_waitcnt lgkmcnt(5)
	v_mfma_f32_32x32x16_bf16 v[64:79], v[238:241], v[176:179], v[64:79]
	v_mfma_f32_32x32x16_bf16 v[0:15], v[238:241], v[180:183], v[0:15]
	ds_read_b128 v[238:241], v205 offset:4704
	s_setprio 0
	global_load_dwordx4 v[176:179], v[198:199], off offset:2944
	global_load_dwordx4 v[180:183], v[200:201], off offset:2944
	s_setprio 1
	s_waitcnt lgkmcnt(1)
	v_mfma_f32_32x32x16_bf16 v[112:127], v[234:237], v[168:171], v[112:127]
	v_mfma_f32_32x32x16_bf16 v[48:63], v[234:237], v[172:175], v[48:63]
	s_waitcnt lgkmcnt(0)
	v_mfma_f32_32x32x16_bf16 v[96:111], v[238:241], v[168:171], v[96:111]
	v_mfma_f32_32x32x16_bf16 v[32:47], v[238:241], v[172:175], v[32:47]
	ds_read_b128 v[234:237], v205 offset:9312
	ds_read_b128 v[238:241], v205 offset:13920
	s_waitcnt lgkmcnt(1)
	v_mfma_f32_32x32x16_bf16 v[80:95], v[234:237], v[168:171], v[80:95]
	v_mfma_f32_32x32x16_bf16 v[16:31], v[234:237], v[172:175], v[16:31]
	s_waitcnt lgkmcnt(0)
	v_mfma_f32_32x32x16_bf16 v[64:79], v[238:241], v[168:171], v[64:79]
	v_mfma_f32_32x32x16_bf16 v[0:15], v[238:241], v[172:175], v[0:15]
	s_setprio 0
	global_load_dwordx4 v[168:171], v[190:191], off offset:3072
	global_load_dwordx4 v[172:175], v[188:189], off offset:3072
	s_barrier
; template <bool trans>
; DI void gemm_core(const GTile& tl, const GTile& nx, bool has_next  , bool chain  , bool pre, u32x4 (&ra)[4], u32x4 (&rb)[4], char* smem, f32x16 (&acc)[2][4]) {
;     ...
;   const int nk = K / 64;
;   if (!pre) { G_LOAD(0); G_STORE(0); G_LOAD(1); }
;   for (int kt = 0; kt < nk; ++kt) {
;     __syncthreads();
;     G_COMPUTE(kt & 1, kt);
;   }
	s_waitcnt vmcnt(9)
	ds_write_b128 v209, v[160:163]
	s_waitcnt vmcnt(8)
	ds_write_b128 v210, v[164:167]
	ds_read_b128 v[160:163], v204 offset:36864
	ds_read_b128 v[164:167], v204 offset:41472
	ds_read_b128 v[234:237], v192
	ds_read_b128 v[238:241], v192 offset:4608
	s_setprio 1
	s_waitcnt lgkmcnt(1)
	v_mfma_f32_32x32x16_bf16 v[112:127], v[234:237], v[160:163], v[112:127]
	v_mfma_f32_32x32x16_bf16 v[48:63], v[234:237], v[164:167], v[48:63]
	s_waitcnt lgkmcnt(0)
	v_mfma_f32_32x32x16_bf16 v[96:111], v[238:241], v[160:163], v[96:111]
	v_mfma_f32_32x32x16_bf16 v[32:47], v[238:241], v[164:167], v[32:47]
	ds_read_b128 v[234:237], v192 offset:9216
	ds_read_b128 v[238:241], v192 offset:13824
	s_waitcnt vmcnt(7)
	ds_write_b128 v212, v[218:221]
	s_waitcnt vmcnt(6)
	ds_write_b128 v211, v[222:225]
	ds_read_b128 v[218:221], v204 offset:36896
	ds_read_b128 v[222:225], v204 offset:41504
	s_waitcnt lgkmcnt(5)
	v_mfma_f32_32x32x16_bf16 v[80:95], v[234:237], v[160:163], v[80:95]
	v_mfma_f32_32x32x16_bf16 v[16:31], v[234:237], v[164:167], v[16:31]
	ds_read_b128 v[234:237], v192 offset:32
	s_waitcnt lgkmcnt(5)
	v_mfma_f32_32x32x16_bf16 v[64:79], v[238:241], v[160:163], v[64:79]
	v_mfma_f32_32x32x16_bf16 v[0:15], v[238:241], v[164:167], v[0:15]
	ds_read_b128 v[238:241], v192 offset:4640
	s_setprio 0
	global_load_dwordx4 v[160:163], v[194:195], off offset:3072
	global_load_dwordx4 v[164:167], v[196:197], off offset:3072
	s_setprio 1
	s_waitcnt lgkmcnt(1)
	v_mfma_f32_32x32x16_bf16 v[112:127], v[234:237], v[218:221], v[112:127]
	v_mfma_f32_32x32x16_bf16 v[48:63], v[234:237], v[222:225], v[48:63]
	s_waitcnt lgkmcnt(0)
	v_mfma_f32_32x32x16_bf16 v[96:111], v[238:241], v[218:221], v[96:111]
	v_mfma_f32_32x32x16_bf16 v[32:47], v[238:241], v[222:225], v[32:47]
	ds_read_b128 v[234:237], v192 offset:9248
	ds_read_b128 v[238:241], v192 offset:13856
	s_waitcnt vmcnt(7)
	ds_write_b128 v214, v[226:229]
	s_waitcnt vmcnt(6)
	ds_write_b128 v213, v[230:233]
	ds_read_b128 v[226:229], v204 offset:36928
	ds_read_b128 v[230:233], v204 offset:41536
	s_waitcnt lgkmcnt(5)
	v_mfma_f32_32x32x16_bf16 v[80:95], v[234:237], v[218:221], v[80:95]
	v_mfma_f32_32x32x16_bf16 v[16:31], v[234:237], v[222:225], v[16:31]
	ds_read_b128 v[234:237], v192 offset:64
	s_waitcnt lgkmcnt(5)
	v_mfma_f32_32x32x16_bf16 v[64:79], v[238:241], v[218:221], v[64:79]
	v_mfma_f32_32x32x16_bf16 v[0:15], v[238:241], v[222:225], v[0:15]
	ds_read_b128 v[238:241], v192 offset:4672
	s_setprio 0
	global_load_dwordx4 v[218:221], v[184:185], off offset:3072
	global_load_dwordx4 v[222:225], v[186:187], off offset:3072
	s_setprio 1
	s_waitcnt lgkmcnt(1)
	v_mfma_f32_32x32x16_bf16 v[112:127], v[234:237], v[226:229], v[112:127]
	v_mfma_f32_32x32x16_bf16 v[48:63], v[234:237], v[230:233], v[48:63]
	s_waitcnt lgkmcnt(0)
	v_mfma_f32_32x32x16_bf16 v[96:111], v[238:241], v[226:229], v[96:111]
	v_mfma_f32_32x32x16_bf16 v[32:47], v[238:241], v[230:233], v[32:47]
	ds_read_b128 v[234:237], v192 offset:9280
	ds_read_b128 v[238:241], v192 offset:13888
	s_waitcnt vmcnt(7)
	ds_write_b128 v217, v[176:179]
	s_waitcnt vmcnt(6)
	ds_write_b128 v216, v[180:183]
	ds_read_b128 v[176:179], v204 offset:36960
	ds_read_b128 v[180:183], v204 offset:41568
	s_waitcnt lgkmcnt(5)
	v_mfma_f32_32x32x16_bf16 v[80:95], v[234:237], v[226:229], v[80:95]
	v_mfma_f32_32x32x16_bf16 v[16:31], v[234:237], v[230:233], v[16:31]
	ds_read_b128 v[234:237], v192 offset:96
	s_waitcnt lgkmcnt(5)
	v_mfma_f32_32x32x16_bf16 v[64:79], v[238:241], v[226:229], v[64:79]
	v_mfma_f32_32x32x16_bf16 v[0:15], v[238:241], v[230:233], v[0:15]
	ds_read_b128 v[238:241], v192 offset:4704
	s_setprio 0
	global_load_dwordx4 v[226:229], v[198:199], off offset:3072
	global_load_dwordx4 v[230:233], v[200:201], off offset:3072
	s_setprio 1
	s_waitcnt lgkmcnt(1)
	v_mfma_f32_32x32x16_bf16 v[112:127], v[234:237], v[176:179], v[112:127]
	v_mfma_f32_32x32x16_bf16 v[48:63], v[234:237], v[180:183], v[48:63]
	s_waitcnt lgkmcnt(0)
	v_mfma_f32_32x32x16_bf16 v[96:111], v[238:241], v[176:179], v[96:111]
	v_mfma_f32_32x32x16_bf16 v[32:47], v[238:241], v[180:183], v[32:47]
	ds_read_b128 v[234:237], v192 offset:9312
	ds_read_b128 v[238:241], v192 offset:13920
	s_waitcnt lgkmcnt(1)
	v_mfma_f32_32x32x16_bf16 v[80:95], v[234:237], v[176:179], v[80:95]
	v_mfma_f32_32x32x16_bf16 v[16:31], v[234:237], v[180:183], v[16:31]
	s_waitcnt lgkmcnt(0)
	v_mfma_f32_32x32x16_bf16 v[64:79], v[238:241], v[176:179], v[64:79]
	v_mfma_f32_32x32x16_bf16 v[0:15], v[238:241], v[180:183], v[0:15]
	s_setprio 0
	global_load_dwordx4 v[176:179], v[190:191], off offset:3200
	global_load_dwordx4 v[180:183], v[188:189], off offset:3200
	s_barrier
; template <bool trans>
; DI void gemm_core(const GTile& tl, const GTile& nx, bool has_next  , bool chain  , bool pre, u32x4 (&ra)[4], u32x4 (&rb)[4], char* smem, f32x16 (&acc)[2][4]) {
;     ...
;   const int nk = K / 64;
;   if (!pre) { G_LOAD(0); G_STORE(0); G_LOAD(1); }
;   for (int kt = 0; kt < nk; ++kt) {
;     __syncthreads();
;     G_COMPUTE(kt & 1, kt);
;   }
	s_waitcnt vmcnt(9)
	ds_write_b128 v215, v[168:171]
	s_waitcnt vmcnt(8)
	ds_write_b128 v215, v[172:175] offset:36864
	ds_read_b128 v[168:171], v208
	ds_read_b128 v[172:175], v208 offset:4608
	ds_read_b128 v[234:237], v205
	ds_read_b128 v[238:241], v205 offset:4608
	s_setprio 1
	s_waitcnt lgkmcnt(1)
	v_mfma_f32_32x32x16_bf16 v[112:127], v[234:237], v[168:171], v[112:127]
	v_mfma_f32_32x32x16_bf16 v[48:63], v[234:237], v[172:175], v[48:63]
	s_waitcnt lgkmcnt(0)
	v_mfma_f32_32x32x16_bf16 v[96:111], v[238:241], v[168:171], v[96:111]
	v_mfma_f32_32x32x16_bf16 v[32:47], v[238:241], v[172:175], v[32:47]
	ds_read_b128 v[234:237], v205 offset:9216
	ds_read_b128 v[238:241], v205 offset:13824
	s_waitcnt vmcnt(7)
	ds_write_b128 v215, v[160:163] offset:9216
	s_waitcnt vmcnt(6)
	ds_write_b128 v215, v[164:167] offset:46080
	ds_read_b128 v[160:163], v208 offset:32
	ds_read_b128 v[164:167], v208 offset:4640
	s_waitcnt lgkmcnt(5)
	v_mfma_f32_32x32x16_bf16 v[80:95], v[234:237], v[168:171], v[80:95]
	v_mfma_f32_32x32x16_bf16 v[16:31], v[234:237], v[172:175], v[16:31]
	ds_read_b128 v[234:237], v205 offset:32
	s_waitcnt lgkmcnt(5)
	v_mfma_f32_32x32x16_bf16 v[64:79], v[238:241], v[168:171], v[64:79]
	v_mfma_f32_32x32x16_bf16 v[0:15], v[238:241], v[172:175], v[0:15]
	ds_read_b128 v[238:241], v205 offset:4640
	s_setprio 0
	global_load_dwordx4 v[168:171], v[194:195], off offset:3200
	global_load_dwordx4 v[172:175], v[196:197], off offset:3200
	s_setprio 1
	s_waitcnt lgkmcnt(1)
	v_mfma_f32_32x32x16_bf16 v[112:127], v[234:237], v[160:163], v[112:127]
	v_mfma_f32_32x32x16_bf16 v[48:63], v[234:237], v[164:167], v[48:63]
	s_waitcnt lgkmcnt(0)
	v_mfma_f32_32x32x16_bf16 v[96:111], v[238:241], v[160:163], v[96:111]
	v_mfma_f32_32x32x16_bf16 v[32:47], v[238:241], v[164:167], v[32:47]
	ds_read_b128 v[234:237], v205 offset:9248
	ds_read_b128 v[238:241], v205 offset:13856
	s_waitcnt vmcnt(7)
	ds_write_b128 v215, v[218:221] offset:18432
	s_waitcnt vmcnt(6)
	ds_write_b128 v215, v[222:225] offset:55296
	ds_read_b128 v[218:221], v208 offset:64
	ds_read_b128 v[222:225], v208 offset:4672
	s_waitcnt lgkmcnt(5)
	v_mfma_f32_32x32x16_bf16 v[80:95], v[234:237], v[160:163], v[80:95]
	v_mfma_f32_32x32x16_bf16 v[16:31], v[234:237], v[164:167], v[16:31]
	ds_read_b128 v[234:237], v205 offset:64
	s_waitcnt lgkmcnt(5)
	v_mfma_f32_32x32x16_bf16 v[64:79], v[238:241], v[160:163], v[64:79]
	v_mfma_f32_32x32x16_bf16 v[0:15], v[238:241], v[164:167], v[0:15]
	ds_read_b128 v[238:241], v205 offset:4672
	s_setprio 0
	global_load_dwordx4 v[160:163], v[184:185], off offset:3200
	global_load_dwordx4 v[164:167], v[186:187], off offset:3200
	s_setprio 1
	s_waitcnt lgkmcnt(1)
	v_mfma_f32_32x32x16_bf16 v[112:127], v[234:237], v[218:221], v[112:127]
	v_mfma_f32_32x32x16_bf16 v[48:63], v[234:237], v[222:225], v[48:63]
	s_waitcnt lgkmcnt(0)
	v_mfma_f32_32x32x16_bf16 v[96:111], v[238:241], v[218:221], v[96:111]
	v_mfma_f32_32x32x16_bf16 v[32:47], v[238:241], v[222:225], v[32:47]
	ds_read_b128 v[234:237], v205 offset:9280
	ds_read_b128 v[238:241], v205 offset:13888
	s_waitcnt vmcnt(7)
	ds_write_b128 v215, v[226:229] offset:27648
	s_waitcnt vmcnt(6)
	ds_write_b128 v215, v[230:233] offset:64512
	ds_read_b128 v[226:229], v208 offset:96
	ds_read_b128 v[230:233], v208 offset:4704
	s_waitcnt lgkmcnt(5)
	v_mfma_f32_32x32x16_bf16 v[80:95], v[234:237], v[218:221], v[80:95]
	v_mfma_f32_32x32x16_bf16 v[16:31], v[234:237], v[222:225], v[16:31]
	ds_read_b128 v[234:237], v205 offset:96
	s_waitcnt lgkmcnt(5)
	v_mfma_f32_32x32x16_bf16 v[64:79], v[238:241], v[218:221], v[64:79]
	v_mfma_f32_32x32x16_bf16 v[0:15], v[238:241], v[222:225], v[0:15]
	ds_read_b128 v[238:241], v205 offset:4704
	s_setprio 0
	global_load_dwordx4 v[218:221], v[198:199], off offset:3200
	global_load_dwordx4 v[222:225], v[200:201], off offset:3200
	s_setprio 1
	s_waitcnt lgkmcnt(1)
	v_mfma_f32_32x32x16_bf16 v[112:127], v[234:237], v[226:229], v[112:127]
	v_mfma_f32_32x32x16_bf16 v[48:63], v[234:237], v[230:233], v[48:63]
	s_waitcnt lgkmcnt(0)
	v_mfma_f32_32x32x16_bf16 v[96:111], v[238:241], v[226:229], v[96:111]
	v_mfma_f32_32x32x16_bf16 v[32:47], v[238:241], v[230:233], v[32:47]
	ds_read_b128 v[234:237], v205 offset:9312
	ds_read_b128 v[238:241], v205 offset:13920
	s_waitcnt lgkmcnt(1)
	v_mfma_f32_32x32x16_bf16 v[80:95], v[234:237], v[226:229], v[80:95]
	v_mfma_f32_32x32x16_bf16 v[16:31], v[234:237], v[230:233], v[16:31]
	s_waitcnt lgkmcnt(0)
	v_mfma_f32_32x32x16_bf16 v[64:79], v[238:241], v[226:229], v[64:79]
	v_mfma_f32_32x32x16_bf16 v[0:15], v[238:241], v[230:233], v[0:15]
	s_setprio 0
	global_load_dwordx4 v[226:229], v[190:191], off offset:3328
	global_load_dwordx4 v[230:233], v[188:189], off offset:3328
	s_barrier
; template <bool trans>
; DI void gemm_core(const GTile& tl, const GTile& nx, bool has_next  , bool chain  , bool pre, u32x4 (&ra)[4], u32x4 (&rb)[4], char* smem, f32x16 (&acc)[2][4]) {
;     ...
;   const int nk = K / 64;
;   if (!pre) { G_LOAD(0); G_STORE(0); G_LOAD(1); }
;   for (int kt = 0; kt < nk; ++kt) {
;     __syncthreads();
;     G_COMPUTE(kt & 1, kt);
;   }
	s_waitcnt vmcnt(9)
	ds_write_b128 v209, v[176:179]
	s_waitcnt vmcnt(8)
	ds_write_b128 v210, v[180:183]
	ds_read_b128 v[176:179], v204 offset:36864
	ds_read_b128 v[180:183], v204 offset:41472
	ds_read_b128 v[234:237], v192
	ds_read_b128 v[238:241], v192 offset:4608
	s_setprio 1
	s_waitcnt lgkmcnt(1)
	v_mfma_f32_32x32x16_bf16 v[112:127], v[234:237], v[176:179], v[112:127]
	v_mfma_f32_32x32x16_bf16 v[48:63], v[234:237], v[180:183], v[48:63]
	s_waitcnt lgkmcnt(0)
	v_mfma_f32_32x32x16_bf16 v[96:111], v[238:241], v[176:179], v[96:111]
	v_mfma_f32_32x32x16_bf16 v[32:47], v[238:241], v[180:183], v[32:47]
	ds_read_b128 v[234:237], v192 offset:9216
	ds_read_b128 v[238:241], v192 offset:13824
	s_waitcnt vmcnt(7)
	ds_write_b128 v212, v[168:171]
	s_waitcnt vmcnt(6)
	ds_write_b128 v211, v[172:175]
	ds_read_b128 v[168:171], v204 offset:36896
	ds_read_b128 v[172:175], v204 offset:41504
	s_waitcnt lgkmcnt(5)
	v_mfma_f32_32x32x16_bf16 v[80:95], v[234:237], v[176:179], v[80:95]
	v_mfma_f32_32x32x16_bf16 v[16:31], v[234:237], v[180:183], v[16:31]
	ds_read_b128 v[234:237], v192 offset:32
	s_waitcnt lgkmcnt(5)
	v_mfma_f32_32x32x16_bf16 v[64:79], v[238:241], v[176:179], v[64:79]
	v_mfma_f32_32x32x16_bf16 v[0:15], v[238:241], v[180:183], v[0:15]
	ds_read_b128 v[238:241], v192 offset:4640
	s_setprio 0
	global_load_dwordx4 v[176:179], v[194:195], off offset:3328
	global_load_dwordx4 v[180:183], v[196:197], off offset:3328
	s_setprio 1
	s_waitcnt lgkmcnt(1)
	v_mfma_f32_32x32x16_bf16 v[112:127], v[234:237], v[168:171], v[112:127]
	v_mfma_f32_32x32x16_bf16 v[48:63], v[234:237], v[172:175], v[48:63]
	s_waitcnt lgkmcnt(0)
	v_mfma_f32_32x32x16_bf16 v[96:111], v[238:241], v[168:171], v[96:111]
	v_mfma_f32_32x32x16_bf16 v[32:47], v[238:241], v[172:175], v[32:47]
	ds_read_b128 v[234:237], v192 offset:9248
	ds_read_b128 v[238:241], v192 offset:13856
	s_waitcnt vmcnt(7)
	ds_write_b128 v214, v[160:163]
	s_waitcnt vmcnt(6)
	ds_write_b128 v213, v[164:167]
	ds_read_b128 v[160:163], v204 offset:36928
	ds_read_b128 v[164:167], v204 offset:41536
	s_waitcnt lgkmcnt(5)
	v_mfma_f32_32x32x16_bf16 v[80:95], v[234:237], v[168:171], v[80:95]
	v_mfma_f32_32x32x16_bf16 v[16:31], v[234:237], v[172:175], v[16:31]
	ds_read_b128 v[234:237], v192 offset:64
	s_waitcnt lgkmcnt(5)
	v_mfma_f32_32x32x16_bf16 v[64:79], v[238:241], v[168:171], v[64:79]
	v_mfma_f32_32x32x16_bf16 v[0:15], v[238:241], v[172:175], v[0:15]
	ds_read_b128 v[238:241], v192 offset:4672
	s_setprio 0
	global_load_dwordx4 v[168:171], v[184:185], off offset:3328
	global_load_dwordx4 v[172:175], v[186:187], off offset:3328
	s_setprio 1
	s_waitcnt lgkmcnt(1)
	v_mfma_f32_32x32x16_bf16 v[112:127], v[234:237], v[160:163], v[112:127]
	v_mfma_f32_32x32x16_bf16 v[48:63], v[234:237], v[164:167], v[48:63]
	s_waitcnt lgkmcnt(0)
	v_mfma_f32_32x32x16_bf16 v[96:111], v[238:241], v[160:163], v[96:111]
	v_mfma_f32_32x32x16_bf16 v[32:47], v[238:241], v[164:167], v[32:47]
	ds_read_b128 v[234:237], v192 offset:9280
	ds_read_b128 v[238:241], v192 offset:13888
	s_waitcnt vmcnt(7)
	ds_write_b128 v217, v[218:221]
	s_waitcnt vmcnt(6)
	ds_write_b128 v216, v[222:225]
	ds_read_b128 v[218:221], v204 offset:36960
	ds_read_b128 v[222:225], v204 offset:41568
	s_waitcnt lgkmcnt(5)
	v_mfma_f32_32x32x16_bf16 v[80:95], v[234:237], v[160:163], v[80:95]
	v_mfma_f32_32x32x16_bf16 v[16:31], v[234:237], v[164:167], v[16:31]
	ds_read_b128 v[234:237], v192 offset:96
	s_waitcnt lgkmcnt(5)
	v_mfma_f32_32x32x16_bf16 v[64:79], v[238:241], v[160:163], v[64:79]
	v_mfma_f32_32x32x16_bf16 v[0:15], v[238:241], v[164:167], v[0:15]
	ds_read_b128 v[238:241], v192 offset:4704
	s_setprio 0
	global_load_dwordx4 v[160:163], v[198:199], off offset:3328
	global_load_dwordx4 v[164:167], v[200:201], off offset:3328
	s_setprio 1
	s_waitcnt lgkmcnt(1)
	v_mfma_f32_32x32x16_bf16 v[112:127], v[234:237], v[218:221], v[112:127]
	v_mfma_f32_32x32x16_bf16 v[48:63], v[234:237], v[222:225], v[48:63]
	s_waitcnt lgkmcnt(0)
	v_mfma_f32_32x32x16_bf16 v[96:111], v[238:241], v[218:221], v[96:111]
	v_mfma_f32_32x32x16_bf16 v[32:47], v[238:241], v[222:225], v[32:47]
	ds_read_b128 v[234:237], v192 offset:9312
	ds_read_b128 v[238:241], v192 offset:13920
	s_waitcnt lgkmcnt(1)
	v_mfma_f32_32x32x16_bf16 v[80:95], v[234:237], v[218:221], v[80:95]
	v_mfma_f32_32x32x16_bf16 v[16:31], v[234:237], v[222:225], v[16:31]
	s_waitcnt lgkmcnt(0)
	v_mfma_f32_32x32x16_bf16 v[64:79], v[238:241], v[218:221], v[64:79]
	v_mfma_f32_32x32x16_bf16 v[0:15], v[238:241], v[222:225], v[0:15]
	s_setprio 0
	global_load_dwordx4 v[218:221], v[190:191], off offset:3456
	global_load_dwordx4 v[222:225], v[188:189], off offset:3456
	s_barrier
; template <bool trans>
; DI void gemm_core(const GTile& tl, const GTile& nx, bool has_next  , bool chain  , bool pre, u32x4 (&ra)[4], u32x4 (&rb)[4], char* smem, f32x16 (&acc)[2][4]) {
;     ...
;   const int nk = K / 64;
;   if (!pre) { G_LOAD(0); G_STORE(0); G_LOAD(1); }
;   for (int kt = 0; kt < nk; ++kt) {
;     __syncthreads();
;     G_COMPUTE(kt & 1, kt);
;   }
	s_waitcnt vmcnt(9)
	ds_write_b128 v215, v[226:229]
	s_waitcnt vmcnt(8)
	ds_write_b128 v215, v[230:233] offset:36864
	ds_read_b128 v[226:229], v208
	ds_read_b128 v[230:233], v208 offset:4608
	ds_read_b128 v[234:237], v205
	ds_read_b128 v[238:241], v205 offset:4608
	s_setprio 1
	s_waitcnt lgkmcnt(1)
	v_mfma_f32_32x32x16_bf16 v[112:127], v[234:237], v[226:229], v[112:127]
	v_mfma_f32_32x32x16_bf16 v[48:63], v[234:237], v[230:233], v[48:63]
	s_waitcnt lgkmcnt(0)
	v_mfma_f32_32x32x16_bf16 v[96:111], v[238:241], v[226:229], v[96:111]
	v_mfma_f32_32x32x16_bf16 v[32:47], v[238:241], v[230:233], v[32:47]
	ds_read_b128 v[234:237], v205 offset:9216
	ds_read_b128 v[238:241], v205 offset:13824
	s_waitcnt vmcnt(7)
	ds_write_b128 v215, v[176:179] offset:9216
	s_waitcnt vmcnt(6)
	ds_write_b128 v215, v[180:183] offset:46080
	ds_read_b128 v[176:179], v208 offset:32
	ds_read_b128 v[180:183], v208 offset:4640
	s_waitcnt lgkmcnt(5)
	v_mfma_f32_32x32x16_bf16 v[80:95], v[234:237], v[226:229], v[80:95]
	v_mfma_f32_32x32x16_bf16 v[16:31], v[234:237], v[230:233], v[16:31]
	ds_read_b128 v[234:237], v205 offset:32
	s_waitcnt lgkmcnt(5)
	v_mfma_f32_32x32x16_bf16 v[64:79], v[238:241], v[226:229], v[64:79]
	v_mfma_f32_32x32x16_bf16 v[0:15], v[238:241], v[230:233], v[0:15]
	ds_read_b128 v[238:241], v205 offset:4640
	s_setprio 0
	global_load_dwordx4 v[226:229], v[194:195], off offset:3456
	global_load_dwordx4 v[230:233], v[196:197], off offset:3456
	s_setprio 1
	s_waitcnt lgkmcnt(1)
	v_mfma_f32_32x32x16_bf16 v[112:127], v[234:237], v[176:179], v[112:127]
	v_mfma_f32_32x32x16_bf16 v[48:63], v[234:237], v[180:183], v[48:63]
	s_waitcnt lgkmcnt(0)
	v_mfma_f32_32x32x16_bf16 v[96:111], v[238:241], v[176:179], v[96:111]
	v_mfma_f32_32x32x16_bf16 v[32:47], v[238:241], v[180:183], v[32:47]
	ds_read_b128 v[234:237], v205 offset:9248
	ds_read_b128 v[238:241], v205 offset:13856
	s_waitcnt vmcnt(7)
	ds_write_b128 v215, v[168:171] offset:18432
	s_waitcnt vmcnt(6)
	ds_write_b128 v215, v[172:175] offset:55296
	ds_read_b128 v[168:171], v208 offset:64
	ds_read_b128 v[172:175], v208 offset:4672
	s_waitcnt lgkmcnt(5)
	v_mfma_f32_32x32x16_bf16 v[80:95], v[234:237], v[176:179], v[80:95]
	v_mfma_f32_32x32x16_bf16 v[16:31], v[234:237], v[180:183], v[16:31]
	ds_read_b128 v[234:237], v205 offset:64
	s_waitcnt lgkmcnt(5)
	v_mfma_f32_32x32x16_bf16 v[64:79], v[238:241], v[176:179], v[64:79]
	v_mfma_f32_32x32x16_bf16 v[0:15], v[238:241], v[180:183], v[0:15]
	ds_read_b128 v[238:241], v205 offset:4672
	s_setprio 0
	global_load_dwordx4 v[176:179], v[184:185], off offset:3456
	global_load_dwordx4 v[180:183], v[186:187], off offset:3456
	s_setprio 1
	s_waitcnt lgkmcnt(1)
	v_mfma_f32_32x32x16_bf16 v[112:127], v[234:237], v[168:171], v[112:127]
	v_mfma_f32_32x32x16_bf16 v[48:63], v[234:237], v[172:175], v[48:63]
	s_waitcnt lgkmcnt(0)
	v_mfma_f32_32x32x16_bf16 v[96:111], v[238:241], v[168:171], v[96:111]
	v_mfma_f32_32x32x16_bf16 v[32:47], v[238:241], v[172:175], v[32:47]
	ds_read_b128 v[234:237], v205 offset:9280
	ds_read_b128 v[238:241], v205 offset:13888
	s_waitcnt vmcnt(7)
	ds_write_b128 v215, v[160:163] offset:27648
	s_waitcnt vmcnt(6)
	ds_write_b128 v215, v[164:167] offset:64512
	ds_read_b128 v[160:163], v208 offset:96
	ds_read_b128 v[164:167], v208 offset:4704
	s_waitcnt lgkmcnt(5)
	v_mfma_f32_32x32x16_bf16 v[80:95], v[234:237], v[168:171], v[80:95]
	v_mfma_f32_32x32x16_bf16 v[16:31], v[234:237], v[172:175], v[16:31]
	ds_read_b128 v[234:237], v205 offset:96
	s_waitcnt lgkmcnt(5)
	v_mfma_f32_32x32x16_bf16 v[64:79], v[238:241], v[168:171], v[64:79]
	v_mfma_f32_32x32x16_bf16 v[0:15], v[238:241], v[172:175], v[0:15]
	ds_read_b128 v[238:241], v205 offset:4704
	s_setprio 0
	global_load_dwordx4 v[168:171], v[198:199], off offset:3456
	global_load_dwordx4 v[172:175], v[200:201], off offset:3456
	s_setprio 1
	s_waitcnt lgkmcnt(1)
	v_mfma_f32_32x32x16_bf16 v[112:127], v[234:237], v[160:163], v[112:127]
	v_mfma_f32_32x32x16_bf16 v[48:63], v[234:237], v[164:167], v[48:63]
	s_waitcnt lgkmcnt(0)
	v_mfma_f32_32x32x16_bf16 v[96:111], v[238:241], v[160:163], v[96:111]
	v_mfma_f32_32x32x16_bf16 v[32:47], v[238:241], v[164:167], v[32:47]
	ds_read_b128 v[234:237], v205 offset:9312
	ds_read_b128 v[238:241], v205 offset:13920
	s_waitcnt lgkmcnt(1)
	v_mfma_f32_32x32x16_bf16 v[80:95], v[234:237], v[160:163], v[80:95]
	v_mfma_f32_32x32x16_bf16 v[16:31], v[234:237], v[164:167], v[16:31]
	s_waitcnt lgkmcnt(0)
	v_mfma_f32_32x32x16_bf16 v[64:79], v[238:241], v[160:163], v[64:79]
	v_mfma_f32_32x32x16_bf16 v[0:15], v[238:241], v[164:167], v[0:15]
	s_setprio 0
	global_load_dwordx4 v[160:163], v[190:191], off offset:3584
	global_load_dwordx4 v[164:167], v[188:189], off offset:3584
	s_barrier
; template <bool trans>
; DI void gemm_core(const GTile& tl, const GTile& nx, bool has_next  , bool chain  , bool pre, u32x4 (&ra)[4], u32x4 (&rb)[4], char* smem, f32x16 (&acc)[2][4]) {
;     ...
;   const int nk = K / 64;
;   if (!pre) { G_LOAD(0); G_STORE(0); G_LOAD(1); }
;   for (int kt = 0; kt < nk; ++kt) {
;     __syncthreads();
;     G_COMPUTE(kt & 1, kt);
;   }
	s_waitcnt vmcnt(9)
	ds_write_b128 v209, v[218:221]
	s_waitcnt vmcnt(8)
	ds_write_b128 v210, v[222:225]
	ds_read_b128 v[218:221], v204 offset:36864
	ds_read_b128 v[222:225], v204 offset:41472
	ds_read_b128 v[234:237], v192
	ds_read_b128 v[238:241], v192 offset:4608
	s_setprio 1
	s_waitcnt lgkmcnt(1)
	v_mfma_f32_32x32x16_bf16 v[112:127], v[234:237], v[218:221], v[112:127]
	v_mfma_f32_32x32x16_bf16 v[48:63], v[234:237], v[222:225], v[48:63]
	s_waitcnt lgkmcnt(0)
	v_mfma_f32_32x32x16_bf16 v[96:111], v[238:241], v[218:221], v[96:111]
	v_mfma_f32_32x32x16_bf16 v[32:47], v[238:241], v[222:225], v[32:47]
	ds_read_b128 v[234:237], v192 offset:9216
	ds_read_b128 v[238:241], v192 offset:13824
	s_waitcnt vmcnt(7)
	ds_write_b128 v212, v[226:229]
	s_waitcnt vmcnt(6)
	ds_write_b128 v211, v[230:233]
	ds_read_b128 v[226:229], v204 offset:36896
	ds_read_b128 v[230:233], v204 offset:41504
	s_waitcnt lgkmcnt(5)
	v_mfma_f32_32x32x16_bf16 v[80:95], v[234:237], v[218:221], v[80:95]
	v_mfma_f32_32x32x16_bf16 v[16:31], v[234:237], v[222:225], v[16:31]
	ds_read_b128 v[234:237], v192 offset:32
	s_waitcnt lgkmcnt(5)
	v_mfma_f32_32x32x16_bf16 v[64:79], v[238:241], v[218:221], v[64:79]
	v_mfma_f32_32x32x16_bf16 v[0:15], v[238:241], v[222:225], v[0:15]
	ds_read_b128 v[238:241], v192 offset:4640
	s_setprio 0
	global_load_dwordx4 v[218:221], v[194:195], off offset:3584
	global_load_dwordx4 v[222:225], v[196:197], off offset:3584
	s_setprio 1
	s_waitcnt lgkmcnt(1)
	v_mfma_f32_32x32x16_bf16 v[112:127], v[234:237], v[226:229], v[112:127]
	v_mfma_f32_32x32x16_bf16 v[48:63], v[234:237], v[230:233], v[48:63]
	s_waitcnt lgkmcnt(0)
	v_mfma_f32_32x32x16_bf16 v[96:111], v[238:241], v[226:229], v[96:111]
	v_mfma_f32_32x32x16_bf16 v[32:47], v[238:241], v[230:233], v[32:47]
	ds_read_b128 v[234:237], v192 offset:9248
	ds_read_b128 v[238:241], v192 offset:13856
	s_waitcnt vmcnt(7)
	ds_write_b128 v214, v[176:179]
	s_waitcnt vmcnt(6)
	ds_write_b128 v213, v[180:183]
	ds_read_b128 v[176:179], v204 offset:36928
	ds_read_b128 v[180:183], v204 offset:41536
	s_waitcnt lgkmcnt(5)
	v_mfma_f32_32x32x16_bf16 v[80:95], v[234:237], v[226:229], v[80:95]
	v_mfma_f32_32x32x16_bf16 v[16:31], v[234:237], v[230:233], v[16:31]
	ds_read_b128 v[234:237], v192 offset:64
	s_waitcnt lgkmcnt(5)
	v_mfma_f32_32x32x16_bf16 v[64:79], v[238:241], v[226:229], v[64:79]
	v_mfma_f32_32x32x16_bf16 v[0:15], v[238:241], v[230:233], v[0:15]
	ds_read_b128 v[238:241], v192 offset:4672
	s_setprio 0
	global_load_dwordx4 v[226:229], v[184:185], off offset:3584
	global_load_dwordx4 v[230:233], v[186:187], off offset:3584
	s_setprio 1
	s_waitcnt lgkmcnt(1)
	v_mfma_f32_32x32x16_bf16 v[112:127], v[234:237], v[176:179], v[112:127]
	v_mfma_f32_32x32x16_bf16 v[48:63], v[234:237], v[180:183], v[48:63]
	s_waitcnt lgkmcnt(0)
	v_mfma_f32_32x32x16_bf16 v[96:111], v[238:241], v[176:179], v[96:111]
	v_mfma_f32_32x32x16_bf16 v[32:47], v[238:241], v[180:183], v[32:47]
	ds_read_b128 v[234:237], v192 offset:9280
	ds_read_b128 v[238:241], v192 offset:13888
	s_waitcnt vmcnt(7)
	ds_write_b128 v217, v[168:171]
	s_waitcnt vmcnt(6)
	ds_write_b128 v216, v[172:175]
	ds_read_b128 v[168:171], v204 offset:36960
	ds_read_b128 v[172:175], v204 offset:41568
	s_waitcnt lgkmcnt(5)
	v_mfma_f32_32x32x16_bf16 v[80:95], v[234:237], v[176:179], v[80:95]
	v_mfma_f32_32x32x16_bf16 v[16:31], v[234:237], v[180:183], v[16:31]
	ds_read_b128 v[234:237], v192 offset:96
	s_waitcnt lgkmcnt(5)
	v_mfma_f32_32x32x16_bf16 v[64:79], v[238:241], v[176:179], v[64:79]
	v_mfma_f32_32x32x16_bf16 v[0:15], v[238:241], v[180:183], v[0:15]
	ds_read_b128 v[238:241], v192 offset:4704
	s_setprio 0
	global_load_dwordx4 v[176:179], v[198:199], off offset:3584
	global_load_dwordx4 v[180:183], v[200:201], off offset:3584
	s_setprio 1
	s_waitcnt lgkmcnt(1)
	v_mfma_f32_32x32x16_bf16 v[112:127], v[234:237], v[168:171], v[112:127]
	v_mfma_f32_32x32x16_bf16 v[48:63], v[234:237], v[172:175], v[48:63]
	s_waitcnt lgkmcnt(0)
	v_mfma_f32_32x32x16_bf16 v[96:111], v[238:241], v[168:171], v[96:111]
	v_mfma_f32_32x32x16_bf16 v[32:47], v[238:241], v[172:175], v[32:47]
	ds_read_b128 v[234:237], v192 offset:9312
	ds_read_b128 v[238:241], v192 offset:13920
	s_waitcnt lgkmcnt(1)
	v_mfma_f32_32x32x16_bf16 v[80:95], v[234:237], v[168:171], v[80:95]
	v_mfma_f32_32x32x16_bf16 v[16:31], v[234:237], v[172:175], v[16:31]
	s_waitcnt lgkmcnt(0)
	v_mfma_f32_32x32x16_bf16 v[64:79], v[238:241], v[168:171], v[64:79]
	v_mfma_f32_32x32x16_bf16 v[0:15], v[238:241], v[172:175], v[0:15]
	s_setprio 0
	global_load_dwordx4 v[168:171], v[190:191], off offset:3712
	global_load_dwordx4 v[172:175], v[188:189], off offset:3712
	s_barrier
; template <bool trans>
; DI void gemm_core(const GTile& tl, const GTile& nx, bool has_next  , bool chain  , bool pre, u32x4 (&ra)[4], u32x4 (&rb)[4], char* smem, f32x16 (&acc)[2][4]) {
;     ...
;   const int nk = K / 64;
;   if (!pre) { G_LOAD(0); G_STORE(0); G_LOAD(1); }
;   for (int kt = 0; kt < nk; ++kt) {
;     __syncthreads();
;     G_COMPUTE(kt & 1, kt);
;   }
	s_waitcnt vmcnt(9)
	ds_write_b128 v215, v[160:163]
	s_waitcnt vmcnt(8)
	ds_write_b128 v215, v[164:167] offset:36864
	ds_read_b128 v[160:163], v208
	ds_read_b128 v[164:167], v208 offset:4608
	ds_read_b128 v[234:237], v205
	ds_read_b128 v[238:241], v205 offset:4608
	s_setprio 1
	s_waitcnt lgkmcnt(1)
	v_mfma_f32_32x32x16_bf16 v[112:127], v[234:237], v[160:163], v[112:127]
	v_mfma_f32_32x32x16_bf16 v[48:63], v[234:237], v[164:167], v[48:63]
	s_waitcnt lgkmcnt(0)
	v_mfma_f32_32x32x16_bf16 v[96:111], v[238:241], v[160:163], v[96:111]
	v_mfma_f32_32x32x16_bf16 v[32:47], v[238:241], v[164:167], v[32:47]
	ds_read_b128 v[234:237], v205 offset:9216
	ds_read_b128 v[238:241], v205 offset:13824
	s_waitcnt vmcnt(7)
	ds_write_b128 v215, v[218:221] offset:9216
	s_waitcnt vmcnt(6)
	ds_write_b128 v215, v[222:225] offset:46080
	ds_read_b128 v[218:221], v208 offset:32
	ds_read_b128 v[222:225], v208 offset:4640
	s_waitcnt lgkmcnt(5)
	v_mfma_f32_32x32x16_bf16 v[80:95], v[234:237], v[160:163], v[80:95]
	v_mfma_f32_32x32x16_bf16 v[16:31], v[234:237], v[164:167], v[16:31]
	ds_read_b128 v[234:237], v205 offset:32
	s_waitcnt lgkmcnt(5)
	v_mfma_f32_32x32x16_bf16 v[64:79], v[238:241], v[160:163], v[64:79]
	v_mfma_f32_32x32x16_bf16 v[0:15], v[238:241], v[164:167], v[0:15]
	ds_read_b128 v[238:241], v205 offset:4640
	s_setprio 0
	global_load_dwordx4 v[160:163], v[194:195], off offset:3712
	global_load_dwordx4 v[164:167], v[196:197], off offset:3712
	s_setprio 1
	s_waitcnt lgkmcnt(1)
	v_mfma_f32_32x32x16_bf16 v[112:127], v[234:237], v[218:221], v[112:127]
	v_mfma_f32_32x32x16_bf16 v[48:63], v[234:237], v[222:225], v[48:63]
	s_waitcnt lgkmcnt(0)
	v_mfma_f32_32x32x16_bf16 v[96:111], v[238:241], v[218:221], v[96:111]
	v_mfma_f32_32x32x16_bf16 v[32:47], v[238:241], v[222:225], v[32:47]
	ds_read_b128 v[234:237], v205 offset:9248
	ds_read_b128 v[238:241], v205 offset:13856
	s_waitcnt vmcnt(7)
	ds_write_b128 v215, v[226:229] offset:18432
	s_waitcnt vmcnt(6)
	ds_write_b128 v215, v[230:233] offset:55296
	ds_read_b128 v[226:229], v208 offset:64
	ds_read_b128 v[230:233], v208 offset:4672
	s_waitcnt lgkmcnt(5)
	v_mfma_f32_32x32x16_bf16 v[80:95], v[234:237], v[218:221], v[80:95]
	v_mfma_f32_32x32x16_bf16 v[16:31], v[234:237], v[222:225], v[16:31]
	ds_read_b128 v[234:237], v205 offset:64
	s_waitcnt lgkmcnt(5)
	v_mfma_f32_32x32x16_bf16 v[64:79], v[238:241], v[218:221], v[64:79]
	v_mfma_f32_32x32x16_bf16 v[0:15], v[238:241], v[222:225], v[0:15]
	ds_read_b128 v[238:241], v205 offset:4672
	s_setprio 0
	global_load_dwordx4 v[218:221], v[184:185], off offset:3712
	global_load_dwordx4 v[222:225], v[186:187], off offset:3712
	s_setprio 1
	s_waitcnt lgkmcnt(1)
	v_mfma_f32_32x32x16_bf16 v[112:127], v[234:237], v[226:229], v[112:127]
	v_mfma_f32_32x32x16_bf16 v[48:63], v[234:237], v[230:233], v[48:63]
	s_waitcnt lgkmcnt(0)
	v_mfma_f32_32x32x16_bf16 v[96:111], v[238:241], v[226:229], v[96:111]
	v_mfma_f32_32x32x16_bf16 v[32:47], v[238:241], v[230:233], v[32:47]
	ds_read_b128 v[234:237], v205 offset:9280
	ds_read_b128 v[238:241], v205 offset:13888
	s_waitcnt vmcnt(7)
	ds_write_b128 v215, v[176:179] offset:27648
	s_waitcnt vmcnt(6)
	ds_write_b128 v215, v[180:183] offset:64512
	ds_read_b128 v[176:179], v208 offset:96
	ds_read_b128 v[180:183], v208 offset:4704
	s_waitcnt lgkmcnt(5)
	v_mfma_f32_32x32x16_bf16 v[80:95], v[234:237], v[226:229], v[80:95]
	v_mfma_f32_32x32x16_bf16 v[16:31], v[234:237], v[230:233], v[16:31]
	ds_read_b128 v[234:237], v205 offset:96
	s_waitcnt lgkmcnt(5)
	v_mfma_f32_32x32x16_bf16 v[64:79], v[238:241], v[226:229], v[64:79]
	v_mfma_f32_32x32x16_bf16 v[0:15], v[238:241], v[230:233], v[0:15]
	ds_read_b128 v[238:241], v205 offset:4704
	s_setprio 0
	global_load_dwordx4 v[226:229], v[198:199], off offset:3712
	global_load_dwordx4 v[230:233], v[200:201], off offset:3712
	s_setprio 1
	s_waitcnt lgkmcnt(1)
	v_mfma_f32_32x32x16_bf16 v[112:127], v[234:237], v[176:179], v[112:127]
	v_mfma_f32_32x32x16_bf16 v[48:63], v[234:237], v[180:183], v[48:63]
	s_waitcnt lgkmcnt(0)
	v_mfma_f32_32x32x16_bf16 v[96:111], v[238:241], v[176:179], v[96:111]
	v_mfma_f32_32x32x16_bf16 v[32:47], v[238:241], v[180:183], v[32:47]
	ds_read_b128 v[234:237], v205 offset:9312
	ds_read_b128 v[238:241], v205 offset:13920
	s_waitcnt lgkmcnt(1)
	v_mfma_f32_32x32x16_bf16 v[80:95], v[234:237], v[176:179], v[80:95]
	v_mfma_f32_32x32x16_bf16 v[16:31], v[234:237], v[180:183], v[16:31]
	s_waitcnt lgkmcnt(0)
	v_mfma_f32_32x32x16_bf16 v[64:79], v[238:241], v[176:179], v[64:79]
	v_mfma_f32_32x32x16_bf16 v[0:15], v[238:241], v[180:183], v[0:15]
	s_setprio 0
	global_load_dwordx4 v[176:179], v[190:191], off offset:3840
	global_load_dwordx4 v[180:183], v[188:189], off offset:3840
	s_barrier
; template <bool trans>
; DI void gemm_core(const GTile& tl, const GTile& nx, bool has_next  , bool chain  , bool pre, u32x4 (&ra)[4], u32x4 (&rb)[4], char* smem, f32x16 (&acc)[2][4]) {
;     ...
;   const int nk = K / 64;
;   if (!pre) { G_LOAD(0); G_STORE(0); G_LOAD(1); }
;   for (int kt = 0; kt < nk; ++kt) {
;     __syncthreads();
;     G_COMPUTE(kt & 1, kt);
;   }
	s_waitcnt vmcnt(9)
	ds_write_b128 v209, v[168:171]
	s_waitcnt vmcnt(8)
	ds_write_b128 v210, v[172:175]
	ds_read_b128 v[168:171], v204 offset:36864
	ds_read_b128 v[172:175], v204 offset:41472
	ds_read_b128 v[234:237], v192
	ds_read_b128 v[238:241], v192 offset:4608
	s_setprio 1
	s_waitcnt lgkmcnt(1)
	v_mfma_f32_32x32x16_bf16 v[112:127], v[234:237], v[168:171], v[112:127]
	v_mfma_f32_32x32x16_bf16 v[48:63], v[234:237], v[172:175], v[48:63]
	s_waitcnt lgkmcnt(0)
	v_mfma_f32_32x32x16_bf16 v[96:111], v[238:241], v[168:171], v[96:111]
	v_mfma_f32_32x32x16_bf16 v[32:47], v[238:241], v[172:175], v[32:47]
	ds_read_b128 v[234:237], v192 offset:9216
	ds_read_b128 v[238:241], v192 offset:13824
	s_waitcnt lgkmcnt(1)
	v_mfma_f32_32x32x16_bf16 v[80:95], v[234:237], v[168:171], v[80:95]
	v_mfma_f32_32x32x16_bf16 v[16:31], v[234:237], v[172:175], v[16:31]
	s_waitcnt lgkmcnt(0)
	v_mfma_f32_32x32x16_bf16 v[64:79], v[238:241], v[168:171], v[64:79]
	v_mfma_f32_32x32x16_bf16 v[0:15], v[238:241], v[172:175], v[0:15]
	s_setprio 0
	global_load_dwordx4 v[234:237], v[194:195], off offset:3840
	global_load_dwordx4 v[238:241], v[196:197], off offset:3840
	s_waitcnt vmcnt(9)
	ds_write_b128 v212, v[160:163]
	s_waitcnt vmcnt(8)
	ds_write_b128 v211, v[164:167]
	ds_read_b128 v[160:163], v204 offset:36896
	ds_read_b128 v[164:167], v204 offset:41504
	ds_read_b128 v[168:171], v192 offset:32
	ds_read_b128 v[172:175], v192 offset:4640
	s_setprio 1
	s_waitcnt lgkmcnt(1)
	v_mfma_f32_32x32x16_bf16 v[112:127], v[168:171], v[160:163], v[112:127]
	v_mfma_f32_32x32x16_bf16 v[48:63], v[168:171], v[164:167], v[48:63]
	s_waitcnt lgkmcnt(0)
	v_mfma_f32_32x32x16_bf16 v[96:111], v[172:175], v[160:163], v[96:111]
	v_mfma_f32_32x32x16_bf16 v[32:47], v[172:175], v[164:167], v[32:47]
	ds_read_b128 v[168:171], v192 offset:9248
	ds_read_b128 v[172:175], v192 offset:13856
	s_waitcnt lgkmcnt(1)
	v_mfma_f32_32x32x16_bf16 v[80:95], v[168:171], v[160:163], v[80:95]
	v_mfma_f32_32x32x16_bf16 v[16:31], v[168:171], v[164:167], v[16:31]
	s_waitcnt lgkmcnt(0)
	v_mfma_f32_32x32x16_bf16 v[64:79], v[172:175], v[160:163], v[64:79]
	v_mfma_f32_32x32x16_bf16 v[0:15], v[172:175], v[164:167], v[0:15]
	s_setprio 0
	global_load_dwordx4 v[242:245], v[184:185], off offset:3840
	global_load_dwordx4 v[246:249], v[186:187], off offset:3840
	s_waitcnt vmcnt(9)
	ds_write_b128 v214, v[218:221]
	s_waitcnt vmcnt(8)
	ds_write_b128 v213, v[222:225]
	ds_read_b128 v[160:163], v204 offset:36928
	ds_read_b128 v[164:167], v204 offset:41536
	ds_read_b128 v[168:171], v192 offset:64
	ds_read_b128 v[172:175], v192 offset:4672
	s_setprio 1
	s_waitcnt lgkmcnt(1)
	v_mfma_f32_32x32x16_bf16 v[112:127], v[168:171], v[160:163], v[112:127]
	v_mfma_f32_32x32x16_bf16 v[48:63], v[168:171], v[164:167], v[48:63]
	s_waitcnt lgkmcnt(0)
	v_mfma_f32_32x32x16_bf16 v[96:111], v[172:175], v[160:163], v[96:111]
	v_mfma_f32_32x32x16_bf16 v[32:47], v[172:175], v[164:167], v[32:47]
	ds_read_b128 v[168:171], v192 offset:9280
	ds_read_b128 v[172:175], v192 offset:13888
	s_waitcnt lgkmcnt(1)
	v_mfma_f32_32x32x16_bf16 v[80:95], v[168:171], v[160:163], v[80:95]
	v_mfma_f32_32x32x16_bf16 v[16:31], v[168:171], v[164:167], v[16:31]
	s_waitcnt lgkmcnt(0)
	v_mfma_f32_32x32x16_bf16 v[64:79], v[172:175], v[160:163], v[64:79]
	v_mfma_f32_32x32x16_bf16 v[0:15], v[172:175], v[164:167], v[0:15]
	s_setprio 0
	global_load_dwordx4 v[218:221], v[198:199], off offset:3840
	global_load_dwordx4 v[222:225], v[200:201], off offset:3840
	s_waitcnt vmcnt(9)
	ds_write_b128 v217, v[226:229]
	s_waitcnt vmcnt(8)
	ds_write_b128 v216, v[230:233]
	ds_read_b128 v[160:163], v204 offset:36960
	ds_read_b128 v[164:167], v204 offset:41568
	ds_read_b128 v[168:171], v192 offset:96
	ds_read_b128 v[172:175], v192 offset:4704
	s_setprio 1
	s_waitcnt lgkmcnt(1)
	v_mfma_f32_32x32x16_bf16 v[112:127], v[168:171], v[160:163], v[112:127]
	v_mfma_f32_32x32x16_bf16 v[48:63], v[168:171], v[164:167], v[48:63]
	s_waitcnt lgkmcnt(0)
	v_mfma_f32_32x32x16_bf16 v[96:111], v[172:175], v[160:163], v[96:111]
	v_mfma_f32_32x32x16_bf16 v[32:47], v[172:175], v[164:167], v[32:47]
	ds_read_b128 v[168:171], v192 offset:9312
	ds_read_b128 v[172:175], v192 offset:13920
	s_waitcnt lgkmcnt(1)
	v_mfma_f32_32x32x16_bf16 v[80:95], v[168:171], v[160:163], v[80:95]
	v_mfma_f32_32x32x16_bf16 v[16:31], v[168:171], v[164:167], v[16:31]
	s_waitcnt lgkmcnt(0)
	v_mfma_f32_32x32x16_bf16 v[64:79], v[172:175], v[160:163], v[64:79]
	v_mfma_f32_32x32x16_bf16 v[0:15], v[172:175], v[164:167], v[0:15]
	s_setprio 0
	global_load_dwordx4 v[160:163], v[190:191], off offset:3968
	global_load_dwordx4 v[164:167], v[188:189], off offset:3968
	s_barrier
; template <bool trans>
; DI void gemm_core(const GTile& tl, const GTile& nx, bool has_next  , bool chain  , bool pre, u32x4 (&ra)[4], u32x4 (&rb)[4], char* smem, f32x16 (&acc)[2][4]) {
;     ...
;   const int nk = K / 64;
;   if (!pre) { G_LOAD(0); G_STORE(0); G_LOAD(1); }
;   for (int kt = 0; kt < nk; ++kt) {
;     __syncthreads();
;     G_COMPUTE(kt & 1, kt);
;   }
	s_waitcnt vmcnt(9)
	ds_write_b128 v215, v[176:179]
	s_waitcnt vmcnt(8)
	ds_write_b128 v215, v[180:183] offset:36864
	ds_read_b128 v[168:171], v208
	ds_read_b128 v[172:175], v208 offset:4608
	ds_read_b128 v[176:179], v205
	ds_read_b128 v[180:183], v205 offset:4608
	s_setprio 1
	s_waitcnt lgkmcnt(1)
	v_mfma_f32_32x32x16_bf16 v[112:127], v[176:179], v[168:171], v[112:127]
	v_mfma_f32_32x32x16_bf16 v[48:63], v[176:179], v[172:175], v[48:63]
	s_waitcnt lgkmcnt(0)
	v_mfma_f32_32x32x16_bf16 v[96:111], v[180:183], v[168:171], v[96:111]
	v_mfma_f32_32x32x16_bf16 v[32:47], v[180:183], v[172:175], v[32:47]
	ds_read_b128 v[176:179], v205 offset:9216
	ds_read_b128 v[180:183], v205 offset:13824
	s_waitcnt lgkmcnt(1)
	v_mfma_f32_32x32x16_bf16 v[80:95], v[176:179], v[168:171], v[80:95]
	v_mfma_f32_32x32x16_bf16 v[16:31], v[176:179], v[172:175], v[16:31]
	s_waitcnt lgkmcnt(0)
	v_mfma_f32_32x32x16_bf16 v[64:79], v[180:183], v[168:171], v[64:79]
	v_mfma_f32_32x32x16_bf16 v[0:15], v[180:183], v[172:175], v[0:15]
	s_setprio 0
	global_load_dwordx4 v[168:171], v[194:195], off offset:3968
	global_load_dwordx4 v[172:175], v[196:197], off offset:3968
	s_waitcnt vmcnt(9)
	ds_write_b128 v215, v[234:237] offset:9216
	s_waitcnt vmcnt(8)
	ds_write_b128 v215, v[238:241] offset:46080
	ds_read_b128 v[176:179], v208 offset:32
	ds_read_b128 v[180:183], v208 offset:4640
	ds_read_b128 v[188:191], v205 offset:32
	ds_read_b128 v[194:197], v205 offset:4640
	s_setprio 1
	s_waitcnt lgkmcnt(1)
	v_mfma_f32_32x32x16_bf16 v[112:127], v[188:191], v[176:179], v[112:127]
	v_mfma_f32_32x32x16_bf16 v[48:63], v[188:191], v[180:183], v[48:63]
	s_waitcnt lgkmcnt(0)
	v_mfma_f32_32x32x16_bf16 v[96:111], v[194:197], v[176:179], v[96:111]
	v_mfma_f32_32x32x16_bf16 v[32:47], v[194:197], v[180:183], v[32:47]
	ds_read_b128 v[188:191], v205 offset:9248
	ds_read_b128 v[194:197], v205 offset:13856
	s_waitcnt lgkmcnt(1)
	v_mfma_f32_32x32x16_bf16 v[80:95], v[188:191], v[176:179], v[80:95]
	v_mfma_f32_32x32x16_bf16 v[16:31], v[188:191], v[180:183], v[16:31]
	s_waitcnt lgkmcnt(0)
	v_mfma_f32_32x32x16_bf16 v[64:79], v[194:197], v[176:179], v[64:79]
	v_mfma_f32_32x32x16_bf16 v[0:15], v[194:197], v[180:183], v[0:15]
	s_setprio 0
	global_load_dwordx4 v[176:179], v[184:185], off offset:3968
	global_load_dwordx4 v[180:183], v[186:187], off offset:3968
	s_waitcnt vmcnt(9)
	ds_write_b128 v215, v[242:245] offset:18432
	s_waitcnt vmcnt(8)
	ds_write_b128 v215, v[246:249] offset:55296
	ds_read_b128 v[184:187], v208 offset:64
	ds_read_b128 v[188:191], v208 offset:4672
	ds_read_b128 v[194:197], v205 offset:64
	ds_read_b128 v[226:229], v205 offset:4672
	s_setprio 1
	s_waitcnt lgkmcnt(1)
	v_mfma_f32_32x32x16_bf16 v[112:127], v[194:197], v[184:187], v[112:127]
	v_mfma_f32_32x32x16_bf16 v[48:63], v[194:197], v[188:191], v[48:63]
	s_waitcnt lgkmcnt(0)
	v_mfma_f32_32x32x16_bf16 v[96:111], v[226:229], v[184:187], v[96:111]
	v_mfma_f32_32x32x16_bf16 v[32:47], v[226:229], v[188:191], v[32:47]
	ds_read_b128 v[194:197], v205 offset:9280
	ds_read_b128 v[226:229], v205 offset:13888
	s_waitcnt lgkmcnt(1)
	v_mfma_f32_32x32x16_bf16 v[80:95], v[194:197], v[184:187], v[80:95]
	v_mfma_f32_32x32x16_bf16 v[16:31], v[194:197], v[188:191], v[16:31]
	s_waitcnt lgkmcnt(0)
	v_mfma_f32_32x32x16_bf16 v[64:79], v[226:229], v[184:187], v[64:79]
	v_mfma_f32_32x32x16_bf16 v[0:15], v[226:229], v[188:191], v[0:15]
	s_setprio 0
	global_load_dwordx4 v[184:187], v[198:199], off offset:3968
	global_load_dwordx4 v[188:191], v[200:201], off offset:3968
	s_waitcnt vmcnt(9)
	ds_write_b128 v215, v[218:221] offset:27648
	s_waitcnt vmcnt(8)
	ds_write_b128 v215, v[222:225] offset:64512
	ds_read_b128 v[194:197], v208 offset:96
	ds_read_b128 v[198:201], v208 offset:4704
	ds_read_b128 v[218:221], v205 offset:96
	ds_read_b128 v[222:225], v205 offset:4704
	s_setprio 1
	s_waitcnt lgkmcnt(1)
	v_mfma_f32_32x32x16_bf16 v[112:127], v[218:221], v[194:197], v[112:127]
	v_mfma_f32_32x32x16_bf16 v[48:63], v[218:221], v[198:201], v[48:63]
	s_waitcnt lgkmcnt(0)
	v_mfma_f32_32x32x16_bf16 v[96:111], v[222:225], v[194:197], v[96:111]
	v_mfma_f32_32x32x16_bf16 v[32:47], v[222:225], v[198:201], v[32:47]
	ds_read_b128 v[218:221], v205 offset:9312
	ds_read_b128 v[222:225], v205 offset:13920
	s_waitcnt lgkmcnt(1)
	v_mfma_f32_32x32x16_bf16 v[80:95], v[218:221], v[194:197], v[80:95]
	v_mfma_f32_32x32x16_bf16 v[16:31], v[218:221], v[198:201], v[16:31]
	s_waitcnt lgkmcnt(0)
	v_mfma_f32_32x32x16_bf16 v[64:79], v[222:225], v[194:197], v[64:79]
	v_mfma_f32_32x32x16_bf16 v[0:15], v[222:225], v[198:201], v[0:15]
	s_setprio 0
	s_barrier
; template <bool trans>
; DI void gemm_core(const GTile& tl, const GTile& nx, bool has_next  , bool chain  , bool pre, u32x4 (&ra)[4], u32x4 (&rb)[4], char* smem, f32x16 (&acc)[2][4]) {
;     ...
;   const int nk = K / 64;
;   if (!pre) { G_LOAD(0); G_STORE(0); G_LOAD(1); }
;   for (int kt = 0; kt < nk; ++kt) {
;     __syncthreads();
;     G_COMPUTE(kt & 1, kt);
;   }
	s_waitcnt vmcnt(7)
	ds_write_b128 v209, v[160:163]
	s_waitcnt vmcnt(6)
	ds_write_b128 v210, v[164:167]
	ds_read_b128 v[194:197], v204 offset:36864
	ds_read_b128 v[198:201], v204 offset:41472
	ds_read_b128 v[218:221], v192
	ds_read_b128 v[222:225], v192 offset:4608
	s_setprio 1
	s_waitcnt lgkmcnt(1)
	v_mfma_f32_32x32x16_bf16 v[112:127], v[218:221], v[194:197], v[112:127]
	v_mfma_f32_32x32x16_bf16 v[48:63], v[218:221], v[198:201], v[48:63]
	s_waitcnt lgkmcnt(0)
	v_mfma_f32_32x32x16_bf16 v[96:111], v[222:225], v[194:197], v[96:111]
	v_mfma_f32_32x32x16_bf16 v[32:47], v[222:225], v[198:201], v[32:47]
	ds_read_b128 v[218:221], v192 offset:9216
	ds_read_b128 v[222:225], v192 offset:13824
	s_waitcnt lgkmcnt(1)
	v_mfma_f32_32x32x16_bf16 v[80:95], v[218:221], v[194:197], v[80:95]
	v_mfma_f32_32x32x16_bf16 v[16:31], v[218:221], v[198:201], v[16:31]
	s_waitcnt lgkmcnt(0)
	v_mfma_f32_32x32x16_bf16 v[64:79], v[222:225], v[194:197], v[64:79]
	v_mfma_f32_32x32x16_bf16 v[0:15], v[222:225], v[198:201], v[0:15]
	s_setprio 0
	s_waitcnt vmcnt(5)
	ds_write_b128 v212, v[168:171]
	s_waitcnt vmcnt(4)
	ds_write_b128 v211, v[172:175]
	ds_read_b128 v[194:197], v204 offset:36896
	ds_read_b128 v[198:201], v204 offset:41504
	ds_read_b128 v[218:221], v192 offset:32
	ds_read_b128 v[222:225], v192 offset:4640
	s_setprio 1
	s_waitcnt lgkmcnt(1)
	v_mfma_f32_32x32x16_bf16 v[112:127], v[218:221], v[194:197], v[112:127]
	v_mfma_f32_32x32x16_bf16 v[48:63], v[218:221], v[198:201], v[48:63]
	s_waitcnt lgkmcnt(0)
	v_mfma_f32_32x32x16_bf16 v[96:111], v[222:225], v[194:197], v[96:111]
	v_mfma_f32_32x32x16_bf16 v[32:47], v[222:225], v[198:201], v[32:47]
	ds_read_b128 v[218:221], v192 offset:9248
	ds_read_b128 v[222:225], v192 offset:13856
	s_waitcnt lgkmcnt(1)
	v_mfma_f32_32x32x16_bf16 v[80:95], v[218:221], v[194:197], v[80:95]
	v_mfma_f32_32x32x16_bf16 v[16:31], v[218:221], v[198:201], v[16:31]
	s_waitcnt lgkmcnt(0)
	v_mfma_f32_32x32x16_bf16 v[64:79], v[222:225], v[194:197], v[64:79]
	v_mfma_f32_32x32x16_bf16 v[0:15], v[222:225], v[198:201], v[0:15]
	s_setprio 0
	s_waitcnt vmcnt(3)
	ds_write_b128 v214, v[176:179]
	s_waitcnt vmcnt(2)
	ds_write_b128 v213, v[180:183]
	ds_read_b128 v[194:197], v204 offset:36928
	ds_read_b128 v[198:201], v204 offset:41536
	ds_read_b128 v[210:213], v192 offset:64
	ds_read_b128 v[218:221], v192 offset:4672
	s_setprio 1
	s_waitcnt lgkmcnt(1)
	v_mfma_f32_32x32x16_bf16 v[112:127], v[210:213], v[194:197], v[112:127]
	v_mfma_f32_32x32x16_bf16 v[48:63], v[210:213], v[198:201], v[48:63]
	s_waitcnt lgkmcnt(0)
	v_mfma_f32_32x32x16_bf16 v[96:111], v[218:221], v[194:197], v[96:111]
	v_mfma_f32_32x32x16_bf16 v[32:47], v[218:221], v[198:201], v[32:47]
	ds_read_b128 v[210:213], v192 offset:9280
	ds_read_b128 v[218:221], v192 offset:13888
	s_waitcnt lgkmcnt(1)
	v_mfma_f32_32x32x16_bf16 v[80:95], v[210:213], v[194:197], v[80:95]
	v_mfma_f32_32x32x16_bf16 v[16:31], v[210:213], v[198:201], v[16:31]
	s_waitcnt lgkmcnt(0)
	v_mfma_f32_32x32x16_bf16 v[64:79], v[218:221], v[194:197], v[64:79]
	v_mfma_f32_32x32x16_bf16 v[0:15], v[218:221], v[198:201], v[0:15]
	s_setprio 0
	s_waitcnt vmcnt(1)
	ds_write_b128 v217, v[184:187]
	s_waitcnt vmcnt(0)
	ds_write_b128 v216, v[188:191]
	ds_read_b128 v[194:197], v204 offset:36960
	ds_read_b128 v[198:201], v204 offset:41568
	ds_read_b128 v[210:213], v192 offset:96
	ds_read_b128 v[214:217], v192 offset:4704
	s_setprio 1
	s_waitcnt lgkmcnt(1)
	v_mfma_f32_32x32x16_bf16 v[112:127], v[210:213], v[194:197], v[112:127]
	v_mfma_f32_32x32x16_bf16 v[48:63], v[210:213], v[198:201], v[48:63]
	s_waitcnt lgkmcnt(0)
	v_mfma_f32_32x32x16_bf16 v[96:111], v[214:217], v[194:197], v[96:111]
	v_mfma_f32_32x32x16_bf16 v[32:47], v[214:217], v[198:201], v[32:47]
	ds_read_b128 v[210:213], v192 offset:9312
	ds_read_b128 v[214:217], v192 offset:13920
	s_waitcnt lgkmcnt(1)
	v_mfma_f32_32x32x16_bf16 v[80:95], v[210:213], v[194:197], v[80:95]
	v_mfma_f32_32x32x16_bf16 v[16:31], v[210:213], v[198:201], v[16:31]
	s_waitcnt lgkmcnt(0)
	v_mfma_f32_32x32x16_bf16 v[64:79], v[214:217], v[194:197], v[64:79]
	v_mfma_f32_32x32x16_bf16 v[0:15], v[214:217], v[198:201], v[0:15]
	s_setprio 0
	s_barrier
; template <bool trans>
; DI void gemm_core(const GTile& tl, const GTile& nx, bool has_next  , bool chain  , bool pre, u32x4 (&ra)[4], u32x4 (&rb)[4], char* smem, f32x16 (&acc)[2][4]) {
;     ...
;   const int nk = K / 64;
;   if (!pre) { G_LOAD(0); G_STORE(0); G_LOAD(1); }
;   for (int kt = 0; kt < nk; ++kt) {
;     __syncthreads();
;     G_COMPUTE(kt & 1, kt);
;   }
;   if (!has_next) __syncthreads();
	ds_read_b128 v[194:197], v208
	ds_read_b128 v[198:201], v208 offset:4608
	ds_read_b128 v[210:213], v205
	ds_read_b128 v[214:217], v205 offset:4608
	s_setprio 1
	s_waitcnt lgkmcnt(1)
	v_mfma_f32_32x32x16_bf16 v[112:127], v[210:213], v[194:197], v[112:127]
	v_mfma_f32_32x32x16_bf16 v[48:63], v[210:213], v[198:201], v[48:63]
	s_waitcnt lgkmcnt(0)
	v_mfma_f32_32x32x16_bf16 v[96:111], v[214:217], v[194:197], v[96:111]
	v_mfma_f32_32x32x16_bf16 v[32:47], v[214:217], v[198:201], v[32:47]
	ds_read_b128 v[210:213], v205 offset:9216
	ds_read_b128 v[214:217], v205 offset:13824
	s_waitcnt lgkmcnt(1)
	v_mfma_f32_32x32x16_bf16 v[80:95], v[210:213], v[194:197], v[80:95]
	v_mfma_f32_32x32x16_bf16 v[16:31], v[210:213], v[198:201], v[16:31]
	s_waitcnt lgkmcnt(0)
	v_mfma_f32_32x32x16_bf16 v[64:79], v[214:217], v[194:197], v[64:79]
	v_mfma_f32_32x32x16_bf16 v[0:15], v[214:217], v[198:201], v[0:15]
	s_setprio 0
	ds_read_b128 v[194:197], v208 offset:32
	ds_read_b128 v[198:201], v208 offset:4640
	ds_read_b128 v[210:213], v205 offset:32
	ds_read_b128 v[214:217], v205 offset:4640
	s_setprio 1
	s_waitcnt lgkmcnt(1)
	v_mfma_f32_32x32x16_bf16 v[112:127], v[210:213], v[194:197], v[112:127]
	v_mfma_f32_32x32x16_bf16 v[48:63], v[210:213], v[198:201], v[48:63]
	s_waitcnt lgkmcnt(0)
	v_mfma_f32_32x32x16_bf16 v[96:111], v[214:217], v[194:197], v[96:111]
	v_mfma_f32_32x32x16_bf16 v[32:47], v[214:217], v[198:201], v[32:47]
	ds_read_b128 v[210:213], v205 offset:9248
	ds_read_b128 v[214:217], v205 offset:13856
	s_waitcnt lgkmcnt(1)
	v_mfma_f32_32x32x16_bf16 v[80:95], v[210:213], v[194:197], v[80:95]
	v_mfma_f32_32x32x16_bf16 v[16:31], v[210:213], v[198:201], v[16:31]
	s_waitcnt lgkmcnt(0)
	v_mfma_f32_32x32x16_bf16 v[64:79], v[214:217], v[194:197], v[64:79]
	v_mfma_f32_32x32x16_bf16 v[0:15], v[214:217], v[198:201], v[0:15]
	s_setprio 0
	ds_read_b128 v[194:197], v208 offset:64
	ds_read_b128 v[198:201], v208 offset:4672
	ds_read_b128 v[210:213], v205 offset:64
	ds_read_b128 v[214:217], v205 offset:4672
	s_setprio 1
	s_waitcnt lgkmcnt(1)
	v_mfma_f32_32x32x16_bf16 v[112:127], v[210:213], v[194:197], v[112:127]
	v_mfma_f32_32x32x16_bf16 v[48:63], v[210:213], v[198:201], v[48:63]
	s_waitcnt lgkmcnt(0)
	v_mfma_f32_32x32x16_bf16 v[96:111], v[214:217], v[194:197], v[96:111]
	v_mfma_f32_32x32x16_bf16 v[32:47], v[214:217], v[198:201], v[32:47]
	ds_read_b128 v[210:213], v205 offset:9280
	ds_read_b128 v[214:217], v205 offset:13888
	s_waitcnt lgkmcnt(1)
	v_mfma_f32_32x32x16_bf16 v[80:95], v[210:213], v[194:197], v[80:95]
	v_mfma_f32_32x32x16_bf16 v[16:31], v[210:213], v[198:201], v[16:31]
	s_waitcnt lgkmcnt(0)
	v_mfma_f32_32x32x16_bf16 v[64:79], v[214:217], v[194:197], v[64:79]
	v_mfma_f32_32x32x16_bf16 v[0:15], v[214:217], v[198:201], v[0:15]
	s_setprio 0
	ds_read_b128 v[194:197], v208 offset:96
	ds_read_b128 v[198:201], v208 offset:4704
	ds_read_b128 v[208:211], v205 offset:96
	ds_read_b128 v[212:215], v205 offset:4704
	s_setprio 1
	s_waitcnt lgkmcnt(1)
	v_mfma_f32_32x32x16_bf16 v[112:127], v[208:211], v[194:197], v[112:127]
	v_mfma_f32_32x32x16_bf16 v[48:63], v[208:211], v[198:201], v[48:63]
	s_waitcnt lgkmcnt(0)
	v_mfma_f32_32x32x16_bf16 v[96:111], v[212:215], v[194:197], v[96:111]
	v_mfma_f32_32x32x16_bf16 v[32:47], v[212:215], v[198:201], v[32:47]
	ds_read_b128 v[208:211], v205 offset:9312
	ds_read_b128 v[212:215], v205 offset:13920
	s_waitcnt lgkmcnt(1)
	v_mfma_f32_32x32x16_bf16 v[80:95], v[208:211], v[194:197], v[80:95]
	v_mfma_f32_32x32x16_bf16 v[16:31], v[208:211], v[198:201], v[16:31]
	s_waitcnt lgkmcnt(0)
	v_mfma_f32_32x32x16_bf16 v[64:79], v[212:215], v[194:197], v[64:79]
	v_mfma_f32_32x32x16_bf16 v[0:15], v[212:215], v[198:201], v[0:15]
	s_setprio 0
	s_andn2_b64 vcc, exec, s[30:31]
	s_cbranch_vccnz .LBB0_884
	s_barrier

; template <bool trans>
; DI void gemm_core(const GTile& tl, const GTile& nx, bool has_next  , bool chain  , bool pre, u32x4 (&ra)[4], u32x4 (&rb)[4], char* smem, f32x16 (&acc)[2][4]) {
;     ...
;   const int lrow = tid >> 3, kc = tid & 7;
;   const unsigned aoff = (unsigned)(lrow * lda + kc * 8) * 2u, boff = (unsigned)(lrow * ldb + kc * 8) * 2u;
;   const char* ag = (const char*)(A + (size_t)m0 * lda);
;   const char* bg = (const char*)(Bt + (size_t)n0 * ldb);
;   const unsigned aoffn = (unsigned)(lrow * nx.lda + kc * 8) * 2u, boffn = (unsigned)(lrow * nx.ldb + kc * 8) * 2u;
;   const char* agn = (const char*)(nx.A + (size_t)nx.m0 * nx.lda);
;   const char* bgn = (const char*)(nx.Bt + (size_t)nx.n0 * nx.ldb);
;     ...
;   const int nk = K / 64;
;   if (!pre) { G_LOAD(0); G_STORE(0); G_LOAD(1); }
;   for (int kt = 0; kt < nk; ++kt) {
;     __syncthreads();
;     G_COMPUTE(kt & 1, kt);
;   }
.LBB0_890:
	v_lshl_add_u64 v[136:137], s[2:3], 0, v[192:193]
	v_lshl_add_u64 v[138:139], s[16:17], 0, v[192:193]
	s_waitcnt lgkmcnt(0)
	s_barrier
	global_load_dwordx4 v[184:187], v[136:137], off offset:256
	global_load_dwordx4 v[188:191], v[138:139], off offset:256
	s_ashr_i32 s2, s56, 6
	s_lshl_b32 s3, s2, 8
	s_cmp_lt_i32 s2, 23
	s_cselect_b32 s2, s3, 0x1900
	s_and_b32 s3, s49, 0x1f80000
	s_and_b32 s16, s18, 0xc0
	s_lshl_b32 s3, s3, 1
	s_add_u32 s6, s24, s3
	s_addc_u32 s7, s25, 0
	s_ashr_i32 s3, s2, 31
	s_lshl_b64 s[2:3], s[2:3], 12
	s_add_u32 s2, s27, s2
	s_addc_u32 s3, s40, s3
	s_lshr_b32 s17, s18, 1
	v_and_b32_e32 v11, 31, v8
	s_and_b32 s17, s17, 0xfffff80
	v_or_b32_e32 v12, s17, v11
	v_or_b32_e32 v11, s16, v11
	v_add3_u32 v148, 16, v10, v9
	v_lshrrev_b32_e32 v8, 1, v8
	v_mul_u32_u24_e32 v150, 0x90, v11
	v_lshl_add_u64 v[130:131], s[6:7], 0, v[192:193]
	v_lshl_add_u64 v[128:129], s[2:3], 0, v[192:193]
	v_and_b32_e32 v204, 16, v8
	v_add_u32_e32 v192, 0x12000, v148
	v_mul_lo_u32 v149, v12, s54
	v_add3_u32 v152, 16, v150, v204
	v_add_u32_e32 v159, 0x1b000, v148
	ds_write_b128 v192, v[0:3]
	s_waitcnt vmcnt(5)
	ds_write_b128 v159, v[4:7]
	v_add3_u32 v151, 16, v149, v204
	ds_read_b128 v[0:3], v152 offset:36864
	ds_read_b128 v[16:19], v152 offset:41472
	ds_read_b128 v[4:7], v151
	ds_read_b128 v[8:11], v151 offset:4608
	v_lshl_add_u64 v[140:141], v[136:137], 0, s[12:13]
	v_lshl_add_u64 v[142:143], v[138:139], 0, s[12:13]
	v_lshl_add_u64 v[132:133], v[136:137], 0, s[14:15]
	v_lshl_add_u64 v[134:135], v[138:139], 0, s[14:15]
	s_setprio 1
	s_waitcnt lgkmcnt(1)
	v_mfma_f32_32x32x16_bf16 v[96:111], v[0:3], v[4:7], 0
	v_mfma_f32_32x32x16_bf16 v[112:127], v[16:19], v[4:7], 0
	ds_read_b128 v[4:7], v151 offset:9216
	ds_read_b128 v[20:23], v151 offset:13824
	s_waitcnt lgkmcnt(2)
	v_mfma_f32_32x32x16_bf16 v[64:79], v[0:3], v[8:11], 0
	v_mfma_f32_32x32x16_bf16 v[80:95], v[16:19], v[8:11], 0
	s_waitcnt lgkmcnt(1)
	v_mfma_f32_32x32x16_bf16 v[32:47], v[0:3], v[4:7], 0
	v_mfma_f32_32x32x16_bf16 v[48:63], v[16:19], v[4:7], 0
	s_waitcnt lgkmcnt(0)
	v_mfma_f32_32x32x16_bf16 v[0:15], v[0:3], v[20:23], 0
	v_mfma_f32_32x32x16_bf16 v[16:31], v[16:19], v[20:23], 0
	s_setprio 0
	global_load_dwordx4 v[194:197], v[140:141], off offset:256
	global_load_dwordx4 v[198:201], v[142:143], off offset:256
	v_add_u32_e32 v158, 0x14400, v148
	v_add_u32_e32 v157, 0x1d400, v148
	ds_write_b128 v158, v[176:179]
	s_waitcnt vmcnt(6)
	ds_write_b128 v157, v[180:183]
	ds_read_b128 v[144:147], v152 offset:36896
	ds_read_b128 v[176:179], v152 offset:41504
	ds_read_b128 v[180:183], v151 offset:32
	ds_read_b128 v[208:211], v151 offset:4640
	s_setprio 1
	s_waitcnt lgkmcnt(1)
	v_mfma_f32_32x32x16_bf16 v[96:111], v[144:147], v[180:183], v[96:111]
	v_mfma_f32_32x32x16_bf16 v[112:127], v[176:179], v[180:183], v[112:127]
	s_waitcnt lgkmcnt(0)
	v_mfma_f32_32x32x16_bf16 v[64:79], v[144:147], v[208:211], v[64:79]
	v_mfma_f32_32x32x16_bf16 v[80:95], v[176:179], v[208:211], v[80:95]
	ds_read_b128 v[180:183], v151 offset:9248
	ds_read_b128 v[208:211], v151 offset:13856
	s_waitcnt lgkmcnt(1)
	v_mfma_f32_32x32x16_bf16 v[32:47], v[144:147], v[180:183], v[32:47]
	v_mfma_f32_32x32x16_bf16 v[48:63], v[176:179], v[180:183], v[48:63]
	s_waitcnt lgkmcnt(0)
	v_mfma_f32_32x32x16_bf16 v[0:15], v[144:147], v[208:211], v[0:15]
	v_mfma_f32_32x32x16_bf16 v[16:31], v[176:179], v[208:211], v[16:31]
	s_setprio 0
	global_load_dwordx4 v[176:179], v[132:133], off offset:256
	global_load_dwordx4 v[180:183], v[134:135], off offset:256
	v_add_u32_e32 v154, 0x16800, v148
	v_add_u32_e32 v153, 0x1f800, v148
	ds_write_b128 v154, v[168:171]
	s_waitcnt vmcnt(7)
	ds_write_b128 v153, v[172:175]
	ds_read_b128 v[144:147], v152 offset:36928
	ds_read_b128 v[168:171], v152 offset:41536
	ds_read_b128 v[172:175], v151 offset:64
	ds_read_b128 v[208:211], v151 offset:4672
	s_setprio 1
	s_waitcnt lgkmcnt(1)
	v_mfma_f32_32x32x16_bf16 v[96:111], v[144:147], v[172:175], v[96:111]
	v_mfma_f32_32x32x16_bf16 v[112:127], v[168:171], v[172:175], v[112:127]
	s_waitcnt lgkmcnt(0)
	v_mfma_f32_32x32x16_bf16 v[64:79], v[144:147], v[208:211], v[64:79]
	v_mfma_f32_32x32x16_bf16 v[80:95], v[168:171], v[208:211], v[80:95]
	ds_read_b128 v[172:175], v151 offset:9280
	ds_read_b128 v[208:211], v151 offset:13888
	s_waitcnt lgkmcnt(1)
	v_mfma_f32_32x32x16_bf16 v[32:47], v[144:147], v[172:175], v[32:47]
	v_mfma_f32_32x32x16_bf16 v[48:63], v[168:171], v[172:175], v[48:63]
	s_waitcnt lgkmcnt(0)
	v_mfma_f32_32x32x16_bf16 v[0:15], v[144:147], v[208:211], v[0:15]
	v_mfma_f32_32x32x16_bf16 v[16:31], v[168:171], v[208:211], v[16:31]
	s_setprio 0
	v_add_co_u32_e32 v144, vcc, s53, v136
	v_add_u32_e32 v156, 0x18c00, v148
	s_nop 0
	v_addc_co_u32_e32 v145, vcc, 0, v137, vcc
	v_add_co_u32_e32 v146, vcc, s53, v138
	v_add_u32_e32 v155, 0x21c00, v148
	s_nop 0
	v_addc_co_u32_e32 v147, vcc, 0, v139, vcc
	global_load_dwordx4 v[168:171], v[144:145], off offset:256
	global_load_dwordx4 v[172:175], v[146:147], off offset:256
	ds_write_b128 v156, v[160:163]
	s_waitcnt vmcnt(8)
	ds_write_b128 v155, v[164:167]
	ds_read_b128 v[160:163], v152 offset:36960
	ds_read_b128 v[164:167], v152 offset:41568
	ds_read_b128 v[208:211], v151 offset:96
	ds_read_b128 v[212:215], v151 offset:4704
	s_setprio 1
	s_waitcnt lgkmcnt(1)
	v_mfma_f32_32x32x16_bf16 v[96:111], v[160:163], v[208:211], v[96:111]
	v_mfma_f32_32x32x16_bf16 v[112:127], v[164:167], v[208:211], v[112:127]
	s_waitcnt lgkmcnt(0)
	v_mfma_f32_32x32x16_bf16 v[64:79], v[160:163], v[212:215], v[64:79]
	v_mfma_f32_32x32x16_bf16 v[80:95], v[164:167], v[212:215], v[80:95]
	ds_read_b128 v[208:211], v151 offset:9312
	ds_read_b128 v[212:215], v151 offset:13920
	s_waitcnt lgkmcnt(1)
	v_mfma_f32_32x32x16_bf16 v[32:47], v[160:163], v[208:211], v[32:47]
	v_mfma_f32_32x32x16_bf16 v[48:63], v[164:167], v[208:211], v[48:63]
	s_waitcnt lgkmcnt(0)
	v_mfma_f32_32x32x16_bf16 v[0:15], v[160:163], v[212:215], v[0:15]
	v_mfma_f32_32x32x16_bf16 v[16:31], v[164:167], v[212:215], v[16:31]
	s_setprio 0
	global_load_dwordx4 v[160:163], v[136:137], off offset:384
	global_load_dwordx4 v[164:167], v[138:139], off offset:384
	s_barrier
; template <bool trans>
; DI void gemm_core(const GTile& tl, const GTile& nx, bool has_next  , bool chain  , bool pre, u32x4 (&ra)[4], u32x4 (&rb)[4], char* smem, f32x16 (&acc)[2][4]) {
;     ...
;   const int nk = K / 64;
;   if (!pre) { G_LOAD(0); G_STORE(0); G_LOAD(1); }
;   for (int kt = 0; kt < nk; ++kt) {
;     __syncthreads();
;     G_COMPUTE(kt & 1, kt);
;   }
	s_add_i32 s2, 16, 0x12000
	v_add3_u32 v149, s2, v149, v204
	s_add_i32 s2, 16, 0x1b000
	v_add3_u32 v150, s2, v150, v204
	s_waitcnt vmcnt(9)
	ds_write_b128 v148, v[184:187]
	s_waitcnt vmcnt(8)
	ds_write_b128 v148, v[188:191] offset:36864
	ds_read_b128 v[184:187], v150
	ds_read_b128 v[188:191], v150 offset:4608
	ds_read_b128 v[208:211], v149
	ds_read_b128 v[212:215], v149 offset:4608
	s_setprio 1
	s_waitcnt lgkmcnt(1)
	v_mfma_f32_32x32x16_bf16 v[96:111], v[184:187], v[208:211], v[96:111]
	v_mfma_f32_32x32x16_bf16 v[112:127], v[188:191], v[208:211], v[112:127]
	s_waitcnt lgkmcnt(0)
	v_mfma_f32_32x32x16_bf16 v[64:79], v[184:187], v[212:215], v[64:79]
	v_mfma_f32_32x32x16_bf16 v[80:95], v[188:191], v[212:215], v[80:95]
	ds_read_b128 v[208:211], v149 offset:9216
	ds_read_b128 v[212:215], v149 offset:13824
	s_waitcnt lgkmcnt(1)
	v_mfma_f32_32x32x16_bf16 v[32:47], v[184:187], v[208:211], v[32:47]
	v_mfma_f32_32x32x16_bf16 v[48:63], v[188:191], v[208:211], v[48:63]
	s_waitcnt lgkmcnt(0)
	v_mfma_f32_32x32x16_bf16 v[0:15], v[184:187], v[212:215], v[0:15]
	v_mfma_f32_32x32x16_bf16 v[16:31], v[188:191], v[212:215], v[16:31]
	s_setprio 0
	global_load_dwordx4 v[184:187], v[140:141], off offset:384
	global_load_dwordx4 v[188:191], v[142:143], off offset:384
	s_waitcnt vmcnt(9)
	ds_write_b128 v148, v[194:197] offset:9216
	s_waitcnt vmcnt(8)
	ds_write_b128 v148, v[198:201] offset:46080
	ds_read_b128 v[194:197], v150 offset:32
	ds_read_b128 v[198:201], v150 offset:4640
	ds_read_b128 v[208:211], v149 offset:32
	ds_read_b128 v[212:215], v149 offset:4640
	s_setprio 1
	s_waitcnt lgkmcnt(1)
	v_mfma_f32_32x32x16_bf16 v[96:111], v[194:197], v[208:211], v[96:111]
	v_mfma_f32_32x32x16_bf16 v[112:127], v[198:201], v[208:211], v[112:127]
	s_waitcnt lgkmcnt(0)
	v_mfma_f32_32x32x16_bf16 v[64:79], v[194:197], v[212:215], v[64:79]
	v_mfma_f32_32x32x16_bf16 v[80:95], v[198:201], v[212:215], v[80:95]
	ds_read_b128 v[208:211], v149 offset:9248
	ds_read_b128 v[212:215], v149 offset:13856
	s_waitcnt lgkmcnt(1)
	v_mfma_f32_32x32x16_bf16 v[32:47], v[194:197], v[208:211], v[32:47]
	v_mfma_f32_32x32x16_bf16 v[48:63], v[198:201], v[208:211], v[48:63]
	s_waitcnt lgkmcnt(0)
	v_mfma_f32_32x32x16_bf16 v[0:15], v[194:197], v[212:215], v[0:15]
	v_mfma_f32_32x32x16_bf16 v[16:31], v[198:201], v[212:215], v[16:31]
	s_setprio 0
	global_load_dwordx4 v[194:197], v[132:133], off offset:384
	global_load_dwordx4 v[198:201], v[134:135], off offset:384
	s_waitcnt vmcnt(9)
	ds_write_b128 v148, v[176:179] offset:18432
	s_waitcnt vmcnt(8)
	ds_write_b128 v148, v[180:183] offset:55296
	ds_read_b128 v[176:179], v150 offset:64
	ds_read_b128 v[180:183], v150 offset:4672
	ds_read_b128 v[208:211], v149 offset:64
	ds_read_b128 v[212:215], v149 offset:4672
	s_setprio 1
	s_waitcnt lgkmcnt(1)
	v_mfma_f32_32x32x16_bf16 v[96:111], v[176:179], v[208:211], v[96:111]
	v_mfma_f32_32x32x16_bf16 v[112:127], v[180:183], v[208:211], v[112:127]
	s_waitcnt lgkmcnt(0)
	v_mfma_f32_32x32x16_bf16 v[64:79], v[176:179], v[212:215], v[64:79]
	v_mfma_f32_32x32x16_bf16 v[80:95], v[180:183], v[212:215], v[80:95]
	ds_read_b128 v[208:211], v149 offset:9280
	ds_read_b128 v[212:215], v149 offset:13888
	s_waitcnt lgkmcnt(1)
	v_mfma_f32_32x32x16_bf16 v[32:47], v[176:179], v[208:211], v[32:47]
	v_mfma_f32_32x32x16_bf16 v[48:63], v[180:183], v[208:211], v[48:63]
	s_waitcnt lgkmcnt(0)
	v_mfma_f32_32x32x16_bf16 v[0:15], v[176:179], v[212:215], v[0:15]
	v_mfma_f32_32x32x16_bf16 v[16:31], v[180:183], v[212:215], v[16:31]
	s_setprio 0
	global_load_dwordx4 v[176:179], v[144:145], off offset:384
	global_load_dwordx4 v[180:183], v[146:147], off offset:384
	s_waitcnt vmcnt(9)
	ds_write_b128 v148, v[168:171] offset:27648
	s_waitcnt vmcnt(8)
	ds_write_b128 v148, v[172:175] offset:64512
	ds_read_b128 v[168:171], v150 offset:96
	ds_read_b128 v[172:175], v150 offset:4704
	ds_read_b128 v[208:211], v149 offset:96
	ds_read_b128 v[212:215], v149 offset:4704
	s_setprio 1
	s_waitcnt lgkmcnt(1)
	v_mfma_f32_32x32x16_bf16 v[96:111], v[168:171], v[208:211], v[96:111]
	v_mfma_f32_32x32x16_bf16 v[112:127], v[172:175], v[208:211], v[112:127]
	s_waitcnt lgkmcnt(0)
	v_mfma_f32_32x32x16_bf16 v[64:79], v[168:171], v[212:215], v[64:79]
	v_mfma_f32_32x32x16_bf16 v[80:95], v[172:175], v[212:215], v[80:95]
	ds_read_b128 v[208:211], v149 offset:9312
	ds_read_b128 v[212:215], v149 offset:13920
	s_waitcnt lgkmcnt(1)
	v_mfma_f32_32x32x16_bf16 v[32:47], v[168:171], v[208:211], v[32:47]
	v_mfma_f32_32x32x16_bf16 v[48:63], v[172:175], v[208:211], v[48:63]
	s_waitcnt lgkmcnt(0)
	v_mfma_f32_32x32x16_bf16 v[0:15], v[168:171], v[212:215], v[0:15]
	v_mfma_f32_32x32x16_bf16 v[16:31], v[172:175], v[212:215], v[16:31]
	s_setprio 0
	global_load_dwordx4 v[168:171], v[136:137], off offset:512
	global_load_dwordx4 v[172:175], v[138:139], off offset:512
	s_barrier
; template <bool trans>
; DI void gemm_core(const GTile& tl, const GTile& nx, bool has_next  , bool chain  , bool pre, u32x4 (&ra)[4], u32x4 (&rb)[4], char* smem, f32x16 (&acc)[2][4]) {
;     ...
;   const int nk = K / 64;
;   if (!pre) { G_LOAD(0); G_STORE(0); G_LOAD(1); }
;   for (int kt = 0; kt < nk; ++kt) {
;     __syncthreads();
;     G_COMPUTE(kt & 1, kt);
;   }
	s_waitcnt vmcnt(9)
	ds_write_b128 v192, v[160:163]
	s_waitcnt vmcnt(8)
	ds_write_b128 v159, v[164:167]
	ds_read_b128 v[160:163], v152 offset:36864
	ds_read_b128 v[164:167], v152 offset:41472
	ds_read_b128 v[208:211], v151
	ds_read_b128 v[212:215], v151 offset:4608
	s_setprio 1
	s_waitcnt lgkmcnt(1)
	v_mfma_f32_32x32x16_bf16 v[96:111], v[160:163], v[208:211], v[96:111]
	v_mfma_f32_32x32x16_bf16 v[112:127], v[164:167], v[208:211], v[112:127]
	s_waitcnt lgkmcnt(0)
	v_mfma_f32_32x32x16_bf16 v[64:79], v[160:163], v[212:215], v[64:79]
	v_mfma_f32_32x32x16_bf16 v[80:95], v[164:167], v[212:215], v[80:95]
	ds_read_b128 v[208:211], v151 offset:9216
	ds_read_b128 v[212:215], v151 offset:13824
	s_waitcnt vmcnt(7)
	ds_write_b128 v158, v[184:187]
	s_waitcnt vmcnt(6)
	ds_write_b128 v157, v[188:191]
	ds_read_b128 v[184:187], v152 offset:36896
	ds_read_b128 v[188:191], v152 offset:41504
	s_waitcnt lgkmcnt(5)
	v_mfma_f32_32x32x16_bf16 v[32:47], v[160:163], v[208:211], v[32:47]
	v_mfma_f32_32x32x16_bf16 v[48:63], v[164:167], v[208:211], v[48:63]
	ds_read_b128 v[208:211], v151 offset:32
	s_waitcnt lgkmcnt(5)
	v_mfma_f32_32x32x16_bf16 v[0:15], v[160:163], v[212:215], v[0:15]
	v_mfma_f32_32x32x16_bf16 v[16:31], v[164:167], v[212:215], v[16:31]
	ds_read_b128 v[212:215], v151 offset:4640
	s_setprio 0
	global_load_dwordx4 v[160:163], v[140:141], off offset:512
	global_load_dwordx4 v[164:167], v[142:143], off offset:512
	s_setprio 1
	s_waitcnt lgkmcnt(1)
	v_mfma_f32_32x32x16_bf16 v[96:111], v[184:187], v[208:211], v[96:111]
	v_mfma_f32_32x32x16_bf16 v[112:127], v[188:191], v[208:211], v[112:127]
	s_waitcnt lgkmcnt(0)
	v_mfma_f32_32x32x16_bf16 v[64:79], v[184:187], v[212:215], v[64:79]
	v_mfma_f32_32x32x16_bf16 v[80:95], v[188:191], v[212:215], v[80:95]
	ds_read_b128 v[208:211], v151 offset:9248
	ds_read_b128 v[212:215], v151 offset:13856
	s_waitcnt vmcnt(7)
	ds_write_b128 v154, v[194:197]
	s_waitcnt vmcnt(6)
	ds_write_b128 v153, v[198:201]
	ds_read_b128 v[194:197], v152 offset:36928
	ds_read_b128 v[198:201], v152 offset:41536
	s_waitcnt lgkmcnt(5)
	v_mfma_f32_32x32x16_bf16 v[32:47], v[184:187], v[208:211], v[32:47]
	v_mfma_f32_32x32x16_bf16 v[48:63], v[188:191], v[208:211], v[48:63]
	ds_read_b128 v[208:211], v151 offset:64
	s_waitcnt lgkmcnt(5)
	v_mfma_f32_32x32x16_bf16 v[0:15], v[184:187], v[212:215], v[0:15]
	v_mfma_f32_32x32x16_bf16 v[16:31], v[188:191], v[212:215], v[16:31]
	ds_read_b128 v[212:215], v151 offset:4672
	s_setprio 0
	global_load_dwordx4 v[184:187], v[132:133], off offset:512
	global_load_dwordx4 v[188:191], v[134:135], off offset:512
	s_setprio 1
	s_waitcnt lgkmcnt(1)
	v_mfma_f32_32x32x16_bf16 v[96:111], v[194:197], v[208:211], v[96:111]
	v_mfma_f32_32x32x16_bf16 v[112:127], v[198:201], v[208:211], v[112:127]
	s_waitcnt lgkmcnt(0)
	v_mfma_f32_32x32x16_bf16 v[64:79], v[194:197], v[212:215], v[64:79]
	v_mfma_f32_32x32x16_bf16 v[80:95], v[198:201], v[212:215], v[80:95]
	ds_read_b128 v[208:211], v151 offset:9280
	ds_read_b128 v[212:215], v151 offset:13888
	s_waitcnt vmcnt(7)
	ds_write_b128 v156, v[176:179]
	s_waitcnt vmcnt(6)
	ds_write_b128 v155, v[180:183]
	ds_read_b128 v[176:179], v152 offset:36960
	ds_read_b128 v[180:183], v152 offset:41568
	s_waitcnt lgkmcnt(5)
	v_mfma_f32_32x32x16_bf16 v[32:47], v[194:197], v[208:211], v[32:47]
	v_mfma_f32_32x32x16_bf16 v[48:63], v[198:201], v[208:211], v[48:63]
	ds_read_b128 v[208:211], v151 offset:96
	s_waitcnt lgkmcnt(5)
	v_mfma_f32_32x32x16_bf16 v[0:15], v[194:197], v[212:215], v[0:15]
	v_mfma_f32_32x32x16_bf16 v[16:31], v[198:201], v[212:215], v[16:31]
	ds_read_b128 v[212:215], v151 offset:4704
	s_setprio 0
	global_load_dwordx4 v[194:197], v[144:145], off offset:512
	global_load_dwordx4 v[198:201], v[146:147], off offset:512
	s_setprio 1
	s_waitcnt lgkmcnt(1)
	v_mfma_f32_32x32x16_bf16 v[96:111], v[176:179], v[208:211], v[96:111]
	v_mfma_f32_32x32x16_bf16 v[112:127], v[180:183], v[208:211], v[112:127]
	s_waitcnt lgkmcnt(0)
	v_mfma_f32_32x32x16_bf16 v[64:79], v[176:179], v[212:215], v[64:79]
	v_mfma_f32_32x32x16_bf16 v[80:95], v[180:183], v[212:215], v[80:95]
	ds_read_b128 v[208:211], v151 offset:9312
	ds_read_b128 v[212:215], v151 offset:13920
	s_waitcnt lgkmcnt(1)
	v_mfma_f32_32x32x16_bf16 v[32:47], v[176:179], v[208:211], v[32:47]
	v_mfma_f32_32x32x16_bf16 v[48:63], v[180:183], v[208:211], v[48:63]
	s_waitcnt lgkmcnt(0)
	v_mfma_f32_32x32x16_bf16 v[0:15], v[176:179], v[212:215], v[0:15]
	v_mfma_f32_32x32x16_bf16 v[16:31], v[180:183], v[212:215], v[16:31]
	s_setprio 0
	global_load_dwordx4 v[176:179], v[136:137], off offset:640
	global_load_dwordx4 v[180:183], v[138:139], off offset:640
	s_barrier
; template <bool trans>
; DI void gemm_core(const GTile& tl, const GTile& nx, bool has_next  , bool chain  , bool pre, u32x4 (&ra)[4], u32x4 (&rb)[4], char* smem, f32x16 (&acc)[2][4]) {
;     ...
;   const int nk = K / 64;
;   if (!pre) { G_LOAD(0); G_STORE(0); G_LOAD(1); }
;   for (int kt = 0; kt < nk; ++kt) {
;     __syncthreads();
;     G_COMPUTE(kt & 1, kt);
;   }
	s_waitcnt vmcnt(9)
	ds_write_b128 v148, v[168:171]
	s_waitcnt vmcnt(8)
	ds_write_b128 v148, v[172:175] offset:36864
	ds_read_b128 v[168:171], v150
	ds_read_b128 v[172:175], v150 offset:4608
	ds_read_b128 v[208:211], v149
	ds_read_b128 v[212:215], v149 offset:4608
	s_setprio 1
	s_waitcnt lgkmcnt(1)
	v_mfma_f32_32x32x16_bf16 v[96:111], v[168:171], v[208:211], v[96:111]
	v_mfma_f32_32x32x16_bf16 v[112:127], v[172:175], v[208:211], v[112:127]
	s_waitcnt lgkmcnt(0)
	v_mfma_f32_32x32x16_bf16 v[64:79], v[168:171], v[212:215], v[64:79]
	v_mfma_f32_32x32x16_bf16 v[80:95], v[172:175], v[212:215], v[80:95]
	ds_read_b128 v[208:211], v149 offset:9216
	ds_read_b128 v[212:215], v149 offset:13824
	s_waitcnt vmcnt(7)
	ds_write_b128 v148, v[160:163] offset:9216
	s_waitcnt vmcnt(6)
	ds_write_b128 v148, v[164:167] offset:46080
	ds_read_b128 v[160:163], v150 offset:32
	ds_read_b128 v[164:167], v150 offset:4640
	s_waitcnt lgkmcnt(5)
	v_mfma_f32_32x32x16_bf16 v[32:47], v[168:171], v[208:211], v[32:47]
	v_mfma_f32_32x32x16_bf16 v[48:63], v[172:175], v[208:211], v[48:63]
	ds_read_b128 v[208:211], v149 offset:32
	s_waitcnt lgkmcnt(5)
	v_mfma_f32_32x32x16_bf16 v[0:15], v[168:171], v[212:215], v[0:15]
	v_mfma_f32_32x32x16_bf16 v[16:31], v[172:175], v[212:215], v[16:31]
	ds_read_b128 v[212:215], v149 offset:4640
	s_setprio 0
	global_load_dwordx4 v[168:171], v[140:141], off offset:640
	global_load_dwordx4 v[172:175], v[142:143], off offset:640
	s_setprio 1
	s_waitcnt lgkmcnt(1)
	v_mfma_f32_32x32x16_bf16 v[96:111], v[160:163], v[208:211], v[96:111]
	v_mfma_f32_32x32x16_bf16 v[112:127], v[164:167], v[208:211], v[112:127]
	s_waitcnt lgkmcnt(0)
	v_mfma_f32_32x32x16_bf16 v[64:79], v[160:163], v[212:215], v[64:79]
	v_mfma_f32_32x32x16_bf16 v[80:95], v[164:167], v[212:215], v[80:95]
	ds_read_b128 v[208:211], v149 offset:9248
	ds_read_b128 v[212:215], v149 offset:13856
	s_waitcnt vmcnt(7)
	ds_write_b128 v148, v[184:187] offset:18432
	s_waitcnt vmcnt(6)
	ds_write_b128 v148, v[188:191] offset:55296
	ds_read_b128 v[184:187], v150 offset:64
	ds_read_b128 v[188:191], v150 offset:4672
	s_waitcnt lgkmcnt(5)
	v_mfma_f32_32x32x16_bf16 v[32:47], v[160:163], v[208:211], v[32:47]
	v_mfma_f32_32x32x16_bf16 v[48:63], v[164:167], v[208:211], v[48:63]
	ds_read_b128 v[208:211], v149 offset:64
	s_waitcnt lgkmcnt(5)
	v_mfma_f32_32x32x16_bf16 v[0:15], v[160:163], v[212:215], v[0:15]
	v_mfma_f32_32x32x16_bf16 v[16:31], v[164:167], v[212:215], v[16:31]
	ds_read_b128 v[212:215], v149 offset:4672
	s_setprio 0
	global_load_dwordx4 v[160:163], v[132:133], off offset:640
	global_load_dwordx4 v[164:167], v[134:135], off offset:640
	s_setprio 1
	s_waitcnt lgkmcnt(1)
	v_mfma_f32_32x32x16_bf16 v[96:111], v[184:187], v[208:211], v[96:111]
	v_mfma_f32_32x32x16_bf16 v[112:127], v[188:191], v[208:211], v[112:127]
	s_waitcnt lgkmcnt(0)
	v_mfma_f32_32x32x16_bf16 v[64:79], v[184:187], v[212:215], v[64:79]
	v_mfma_f32_32x32x16_bf16 v[80:95], v[188:191], v[212:215], v[80:95]
	ds_read_b128 v[208:211], v149 offset:9280
	ds_read_b128 v[212:215], v149 offset:13888
	s_waitcnt vmcnt(7)
	ds_write_b128 v148, v[194:197] offset:27648
	s_waitcnt vmcnt(6)
	ds_write_b128 v148, v[198:201] offset:64512
	ds_read_b128 v[194:197], v150 offset:96
	ds_read_b128 v[198:201], v150 offset:4704
	s_waitcnt lgkmcnt(5)
	v_mfma_f32_32x32x16_bf16 v[32:47], v[184:187], v[208:211], v[32:47]
	v_mfma_f32_32x32x16_bf16 v[48:63], v[188:191], v[208:211], v[48:63]
	ds_read_b128 v[208:211], v149 offset:96
	s_waitcnt lgkmcnt(5)
	v_mfma_f32_32x32x16_bf16 v[0:15], v[184:187], v[212:215], v[0:15]
	v_mfma_f32_32x32x16_bf16 v[16:31], v[188:191], v[212:215], v[16:31]
	ds_read_b128 v[212:215], v149 offset:4704
	s_setprio 0
	global_load_dwordx4 v[184:187], v[144:145], off offset:640
	global_load_dwordx4 v[188:191], v[146:147], off offset:640
	s_setprio 1
	s_waitcnt lgkmcnt(1)
	v_mfma_f32_32x32x16_bf16 v[96:111], v[194:197], v[208:211], v[96:111]
	v_mfma_f32_32x32x16_bf16 v[112:127], v[198:201], v[208:211], v[112:127]
	s_waitcnt lgkmcnt(0)
	v_mfma_f32_32x32x16_bf16 v[64:79], v[194:197], v[212:215], v[64:79]
	v_mfma_f32_32x32x16_bf16 v[80:95], v[198:201], v[212:215], v[80:95]
	ds_read_b128 v[208:211], v149 offset:9312
	ds_read_b128 v[212:215], v149 offset:13920
	s_waitcnt lgkmcnt(1)
	v_mfma_f32_32x32x16_bf16 v[32:47], v[194:197], v[208:211], v[32:47]
	v_mfma_f32_32x32x16_bf16 v[48:63], v[198:201], v[208:211], v[48:63]
	s_waitcnt lgkmcnt(0)
	v_mfma_f32_32x32x16_bf16 v[0:15], v[194:197], v[212:215], v[0:15]
	v_mfma_f32_32x32x16_bf16 v[16:31], v[198:201], v[212:215], v[16:31]
	s_setprio 0
	global_load_dwordx4 v[194:197], v[136:137], off offset:768
	global_load_dwordx4 v[198:201], v[138:139], off offset:768
	s_barrier
; template <bool trans>
; DI void gemm_core(const GTile& tl, const GTile& nx, bool has_next  , bool chain  , bool pre, u32x4 (&ra)[4], u32x4 (&rb)[4], char* smem, f32x16 (&acc)[2][4]) {
;     ...
;   const int nk = K / 64;
;   if (!pre) { G_LOAD(0); G_STORE(0); G_LOAD(1); }
;   for (int kt = 0; kt < nk; ++kt) {
;     __syncthreads();
;     G_COMPUTE(kt & 1, kt);
;   }
	s_waitcnt vmcnt(9)
	ds_write_b128 v192, v[176:179]
	s_waitcnt vmcnt(8)
	ds_write_b128 v159, v[180:183]
	ds_read_b128 v[176:179], v152 offset:36864
	ds_read_b128 v[180:183], v152 offset:41472
	ds_read_b128 v[208:211], v151
	ds_read_b128 v[212:215], v151 offset:4608
	s_setprio 1
	s_waitcnt lgkmcnt(1)
	v_mfma_f32_32x32x16_bf16 v[96:111], v[176:179], v[208:211], v[96:111]
	v_mfma_f32_32x32x16_bf16 v[112:127], v[180:183], v[208:211], v[112:127]
	s_waitcnt lgkmcnt(0)
	v_mfma_f32_32x32x16_bf16 v[64:79], v[176:179], v[212:215], v[64:79]
	v_mfma_f32_32x32x16_bf16 v[80:95], v[180:183], v[212:215], v[80:95]
	ds_read_b128 v[208:211], v151 offset:9216
	ds_read_b128 v[212:215], v151 offset:13824
	s_waitcnt vmcnt(7)
	ds_write_b128 v158, v[168:171]
	s_waitcnt vmcnt(6)
	ds_write_b128 v157, v[172:175]
	ds_read_b128 v[168:171], v152 offset:36896
	ds_read_b128 v[172:175], v152 offset:41504
	s_waitcnt lgkmcnt(5)
	v_mfma_f32_32x32x16_bf16 v[32:47], v[176:179], v[208:211], v[32:47]
	v_mfma_f32_32x32x16_bf16 v[48:63], v[180:183], v[208:211], v[48:63]
	ds_read_b128 v[208:211], v151 offset:32
	s_waitcnt lgkmcnt(5)
	v_mfma_f32_32x32x16_bf16 v[0:15], v[176:179], v[212:215], v[0:15]
	v_mfma_f32_32x32x16_bf16 v[16:31], v[180:183], v[212:215], v[16:31]
	ds_read_b128 v[212:215], v151 offset:4640
	s_setprio 0
	global_load_dwordx4 v[176:179], v[140:141], off offset:768
	global_load_dwordx4 v[180:183], v[142:143], off offset:768
	s_setprio 1
	s_waitcnt lgkmcnt(1)
	v_mfma_f32_32x32x16_bf16 v[96:111], v[168:171], v[208:211], v[96:111]
	v_mfma_f32_32x32x16_bf16 v[112:127], v[172:175], v[208:211], v[112:127]
	s_waitcnt lgkmcnt(0)
	v_mfma_f32_32x32x16_bf16 v[64:79], v[168:171], v[212:215], v[64:79]
	v_mfma_f32_32x32x16_bf16 v[80:95], v[172:175], v[212:215], v[80:95]
	ds_read_b128 v[208:211], v151 offset:9248
	ds_read_b128 v[212:215], v151 offset:13856
	s_waitcnt vmcnt(7)
	ds_write_b128 v154, v[160:163]
	s_waitcnt vmcnt(6)
	ds_write_b128 v153, v[164:167]
	ds_read_b128 v[160:163], v152 offset:36928
	ds_read_b128 v[164:167], v152 offset:41536
	s_waitcnt lgkmcnt(5)
	v_mfma_f32_32x32x16_bf16 v[32:47], v[168:171], v[208:211], v[32:47]
	v_mfma_f32_32x32x16_bf16 v[48:63], v[172:175], v[208:211], v[48:63]
	ds_read_b128 v[208:211], v151 offset:64
	s_waitcnt lgkmcnt(5)
	v_mfma_f32_32x32x16_bf16 v[0:15], v[168:171], v[212:215], v[0:15]
	v_mfma_f32_32x32x16_bf16 v[16:31], v[172:175], v[212:215], v[16:31]
	ds_read_b128 v[212:215], v151 offset:4672
	s_setprio 0
	global_load_dwordx4 v[168:171], v[132:133], off offset:768
	global_load_dwordx4 v[172:175], v[134:135], off offset:768
	s_setprio 1
	s_waitcnt lgkmcnt(1)
	v_mfma_f32_32x32x16_bf16 v[96:111], v[160:163], v[208:211], v[96:111]
	v_mfma_f32_32x32x16_bf16 v[112:127], v[164:167], v[208:211], v[112:127]
	s_waitcnt lgkmcnt(0)
	v_mfma_f32_32x32x16_bf16 v[64:79], v[160:163], v[212:215], v[64:79]
	v_mfma_f32_32x32x16_bf16 v[80:95], v[164:167], v[212:215], v[80:95]
	ds_read_b128 v[208:211], v151 offset:9280
	ds_read_b128 v[212:215], v151 offset:13888
	s_waitcnt vmcnt(7)
	ds_write_b128 v156, v[184:187]
	s_waitcnt vmcnt(6)
	ds_write_b128 v155, v[188:191]
	ds_read_b128 v[184:187], v152 offset:36960
	ds_read_b128 v[188:191], v152 offset:41568
	s_waitcnt lgkmcnt(5)
	v_mfma_f32_32x32x16_bf16 v[32:47], v[160:163], v[208:211], v[32:47]
	v_mfma_f32_32x32x16_bf16 v[48:63], v[164:167], v[208:211], v[48:63]
	ds_read_b128 v[208:211], v151 offset:96
	s_waitcnt lgkmcnt(5)
	v_mfma_f32_32x32x16_bf16 v[0:15], v[160:163], v[212:215], v[0:15]
	v_mfma_f32_32x32x16_bf16 v[16:31], v[164:167], v[212:215], v[16:31]
	ds_read_b128 v[212:215], v151 offset:4704
	s_setprio 0
	global_load_dwordx4 v[160:163], v[144:145], off offset:768
	global_load_dwordx4 v[164:167], v[146:147], off offset:768
	s_setprio 1
	s_waitcnt lgkmcnt(1)
	v_mfma_f32_32x32x16_bf16 v[96:111], v[184:187], v[208:211], v[96:111]
	v_mfma_f32_32x32x16_bf16 v[112:127], v[188:191], v[208:211], v[112:127]
	s_waitcnt lgkmcnt(0)
	v_mfma_f32_32x32x16_bf16 v[64:79], v[184:187], v[212:215], v[64:79]
	v_mfma_f32_32x32x16_bf16 v[80:95], v[188:191], v[212:215], v[80:95]
	ds_read_b128 v[208:211], v151 offset:9312
	ds_read_b128 v[212:215], v151 offset:13920
	s_waitcnt lgkmcnt(1)
	v_mfma_f32_32x32x16_bf16 v[32:47], v[184:187], v[208:211], v[32:47]
	v_mfma_f32_32x32x16_bf16 v[48:63], v[188:191], v[208:211], v[48:63]
	s_waitcnt lgkmcnt(0)
	v_mfma_f32_32x32x16_bf16 v[0:15], v[184:187], v[212:215], v[0:15]
	v_mfma_f32_32x32x16_bf16 v[16:31], v[188:191], v[212:215], v[16:31]
	s_setprio 0
	global_load_dwordx4 v[184:187], v[136:137], off offset:896
	global_load_dwordx4 v[188:191], v[138:139], off offset:896
	s_barrier
; template <bool trans>
; DI void gemm_core(const GTile& tl, const GTile& nx, bool has_next  , bool chain  , bool pre, u32x4 (&ra)[4], u32x4 (&rb)[4], char* smem, f32x16 (&acc)[2][4]) {
;     ...
;   const int nk = K / 64;
;   if (!pre) { G_LOAD(0); G_STORE(0); G_LOAD(1); }
;   for (int kt = 0; kt < nk; ++kt) {
;     __syncthreads();
;     G_COMPUTE(kt & 1, kt);
;   }
	s_waitcnt vmcnt(9)
	ds_write_b128 v148, v[194:197]
	s_waitcnt vmcnt(8)
	ds_write_b128 v148, v[198:201] offset:36864
	ds_read_b128 v[194:197], v150
	ds_read_b128 v[198:201], v150 offset:4608
	ds_read_b128 v[208:211], v149
	ds_read_b128 v[212:215], v149 offset:4608
	s_setprio 1
	s_waitcnt lgkmcnt(1)
	v_mfma_f32_32x32x16_bf16 v[96:111], v[194:197], v[208:211], v[96:111]
	v_mfma_f32_32x32x16_bf16 v[112:127], v[198:201], v[208:211], v[112:127]
	s_waitcnt lgkmcnt(0)
	v_mfma_f32_32x32x16_bf16 v[64:79], v[194:197], v[212:215], v[64:79]
	v_mfma_f32_32x32x16_bf16 v[80:95], v[198:201], v[212:215], v[80:95]
	ds_read_b128 v[208:211], v149 offset:9216
	ds_read_b128 v[212:215], v149 offset:13824
	s_waitcnt vmcnt(7)
	ds_write_b128 v148, v[176:179] offset:9216
	s_waitcnt vmcnt(6)
	ds_write_b128 v148, v[180:183] offset:46080
	ds_read_b128 v[176:179], v150 offset:32
	ds_read_b128 v[180:183], v150 offset:4640
	s_waitcnt lgkmcnt(5)
	v_mfma_f32_32x32x16_bf16 v[32:47], v[194:197], v[208:211], v[32:47]
	v_mfma_f32_32x32x16_bf16 v[48:63], v[198:201], v[208:211], v[48:63]
	ds_read_b128 v[208:211], v149 offset:32
	s_waitcnt lgkmcnt(5)
	v_mfma_f32_32x32x16_bf16 v[0:15], v[194:197], v[212:215], v[0:15]
	v_mfma_f32_32x32x16_bf16 v[16:31], v[198:201], v[212:215], v[16:31]
	ds_read_b128 v[212:215], v149 offset:4640
	s_setprio 0
	global_load_dwordx4 v[194:197], v[140:141], off offset:896
	global_load_dwordx4 v[198:201], v[142:143], off offset:896
	s_setprio 1
	s_waitcnt lgkmcnt(1)
	v_mfma_f32_32x32x16_bf16 v[96:111], v[176:179], v[208:211], v[96:111]
	v_mfma_f32_32x32x16_bf16 v[112:127], v[180:183], v[208:211], v[112:127]
	s_waitcnt lgkmcnt(0)
	v_mfma_f32_32x32x16_bf16 v[64:79], v[176:179], v[212:215], v[64:79]
	v_mfma_f32_32x32x16_bf16 v[80:95], v[180:183], v[212:215], v[80:95]
	ds_read_b128 v[208:211], v149 offset:9248
	ds_read_b128 v[212:215], v149 offset:13856
	s_waitcnt vmcnt(7)
	ds_write_b128 v148, v[168:171] offset:18432
	s_waitcnt vmcnt(6)
	ds_write_b128 v148, v[172:175] offset:55296
	ds_read_b128 v[168:171], v150 offset:64
	ds_read_b128 v[172:175], v150 offset:4672
	s_waitcnt lgkmcnt(5)
	v_mfma_f32_32x32x16_bf16 v[32:47], v[176:179], v[208:211], v[32:47]
	v_mfma_f32_32x32x16_bf16 v[48:63], v[180:183], v[208:211], v[48:63]
	ds_read_b128 v[208:211], v149 offset:64
	s_waitcnt lgkmcnt(5)
	v_mfma_f32_32x32x16_bf16 v[0:15], v[176:179], v[212:215], v[0:15]
	v_mfma_f32_32x32x16_bf16 v[16:31], v[180:183], v[212:215], v[16:31]
	ds_read_b128 v[212:215], v149 offset:4672
	s_setprio 0
	global_load_dwordx4 v[176:179], v[132:133], off offset:896
	global_load_dwordx4 v[180:183], v[134:135], off offset:896
	s_setprio 1
	s_waitcnt lgkmcnt(1)
	v_mfma_f32_32x32x16_bf16 v[96:111], v[168:171], v[208:211], v[96:111]
	v_mfma_f32_32x32x16_bf16 v[112:127], v[172:175], v[208:211], v[112:127]
	s_waitcnt lgkmcnt(0)
	v_mfma_f32_32x32x16_bf16 v[64:79], v[168:171], v[212:215], v[64:79]
	v_mfma_f32_32x32x16_bf16 v[80:95], v[172:175], v[212:215], v[80:95]
	ds_read_b128 v[208:211], v149 offset:9280
	ds_read_b128 v[212:215], v149 offset:13888
	s_waitcnt vmcnt(7)
	ds_write_b128 v148, v[160:163] offset:27648
	s_waitcnt vmcnt(6)
	ds_write_b128 v148, v[164:167] offset:64512
	ds_read_b128 v[160:163], v150 offset:96
	ds_read_b128 v[164:167], v150 offset:4704
	s_waitcnt lgkmcnt(5)
	v_mfma_f32_32x32x16_bf16 v[32:47], v[168:171], v[208:211], v[32:47]
	v_mfma_f32_32x32x16_bf16 v[48:63], v[172:175], v[208:211], v[48:63]
	ds_read_b128 v[208:211], v149 offset:96
	s_waitcnt lgkmcnt(5)
	v_mfma_f32_32x32x16_bf16 v[0:15], v[168:171], v[212:215], v[0:15]
	v_mfma_f32_32x32x16_bf16 v[16:31], v[172:175], v[212:215], v[16:31]
	ds_read_b128 v[212:215], v149 offset:4704
	s_setprio 0
	global_load_dwordx4 v[168:171], v[144:145], off offset:896
	global_load_dwordx4 v[172:175], v[146:147], off offset:896
	s_setprio 1
	s_waitcnt lgkmcnt(1)
	v_mfma_f32_32x32x16_bf16 v[96:111], v[160:163], v[208:211], v[96:111]
	v_mfma_f32_32x32x16_bf16 v[112:127], v[164:167], v[208:211], v[112:127]
	s_waitcnt lgkmcnt(0)
	v_mfma_f32_32x32x16_bf16 v[64:79], v[160:163], v[212:215], v[64:79]
	v_mfma_f32_32x32x16_bf16 v[80:95], v[164:167], v[212:215], v[80:95]
	ds_read_b128 v[208:211], v149 offset:9312
	ds_read_b128 v[212:215], v149 offset:13920
	s_waitcnt lgkmcnt(1)
	v_mfma_f32_32x32x16_bf16 v[32:47], v[160:163], v[208:211], v[32:47]
	v_mfma_f32_32x32x16_bf16 v[48:63], v[164:167], v[208:211], v[48:63]
	s_waitcnt lgkmcnt(0)
	v_mfma_f32_32x32x16_bf16 v[0:15], v[160:163], v[212:215], v[0:15]
	v_mfma_f32_32x32x16_bf16 v[16:31], v[164:167], v[212:215], v[16:31]
	s_setprio 0
	global_load_dwordx4 v[160:163], v[136:137], off offset:1024
	global_load_dwordx4 v[164:167], v[138:139], off offset:1024
	s_barrier
; template <bool trans>
; DI void gemm_core(const GTile& tl, const GTile& nx, bool has_next  , bool chain  , bool pre, u32x4 (&ra)[4], u32x4 (&rb)[4], char* smem, f32x16 (&acc)[2][4]) {
;     ...
;   const int nk = K / 64;
;   if (!pre) { G_LOAD(0); G_STORE(0); G_LOAD(1); }
;   for (int kt = 0; kt < nk; ++kt) {
;     __syncthreads();
;     G_COMPUTE(kt & 1, kt);
;   }
	s_waitcnt vmcnt(9)
	ds_write_b128 v192, v[184:187]
	s_waitcnt vmcnt(8)
	ds_write_b128 v159, v[188:191]
	ds_read_b128 v[184:187], v152 offset:36864
	ds_read_b128 v[188:191], v152 offset:41472
	ds_read_b128 v[208:211], v151
	ds_read_b128 v[212:215], v151 offset:4608
	s_setprio 1
	s_waitcnt lgkmcnt(1)
	v_mfma_f32_32x32x16_bf16 v[96:111], v[184:187], v[208:211], v[96:111]
	v_mfma_f32_32x32x16_bf16 v[112:127], v[188:191], v[208:211], v[112:127]
	s_waitcnt lgkmcnt(0)
	v_mfma_f32_32x32x16_bf16 v[64:79], v[184:187], v[212:215], v[64:79]
	v_mfma_f32_32x32x16_bf16 v[80:95], v[188:191], v[212:215], v[80:95]
	ds_read_b128 v[208:211], v151 offset:9216
	ds_read_b128 v[212:215], v151 offset:13824
	s_waitcnt vmcnt(7)
	ds_write_b128 v158, v[194:197]
	s_waitcnt vmcnt(6)
	ds_write_b128 v157, v[198:201]
	ds_read_b128 v[194:197], v152 offset:36896
	ds_read_b128 v[198:201], v152 offset:41504
	s_waitcnt lgkmcnt(5)
	v_mfma_f32_32x32x16_bf16 v[32:47], v[184:187], v[208:211], v[32:47]
	v_mfma_f32_32x32x16_bf16 v[48:63], v[188:191], v[208:211], v[48:63]
	ds_read_b128 v[208:211], v151 offset:32
	s_waitcnt lgkmcnt(5)
	v_mfma_f32_32x32x16_bf16 v[0:15], v[184:187], v[212:215], v[0:15]
	v_mfma_f32_32x32x16_bf16 v[16:31], v[188:191], v[212:215], v[16:31]
	ds_read_b128 v[212:215], v151 offset:4640
	s_setprio 0
	global_load_dwordx4 v[184:187], v[140:141], off offset:1024
	global_load_dwordx4 v[188:191], v[142:143], off offset:1024
	s_setprio 1
	s_waitcnt lgkmcnt(1)
	v_mfma_f32_32x32x16_bf16 v[96:111], v[194:197], v[208:211], v[96:111]
	v_mfma_f32_32x32x16_bf16 v[112:127], v[198:201], v[208:211], v[112:127]
	s_waitcnt lgkmcnt(0)
	v_mfma_f32_32x32x16_bf16 v[64:79], v[194:197], v[212:215], v[64:79]
	v_mfma_f32_32x32x16_bf16 v[80:95], v[198:201], v[212:215], v[80:95]
	ds_read_b128 v[208:211], v151 offset:9248
	ds_read_b128 v[212:215], v151 offset:13856
	s_waitcnt vmcnt(7)
	ds_write_b128 v154, v[176:179]
	s_waitcnt vmcnt(6)
	ds_write_b128 v153, v[180:183]
	ds_read_b128 v[176:179], v152 offset:36928
	ds_read_b128 v[180:183], v152 offset:41536
	s_waitcnt lgkmcnt(5)
	v_mfma_f32_32x32x16_bf16 v[32:47], v[194:197], v[208:211], v[32:47]
	v_mfma_f32_32x32x16_bf16 v[48:63], v[198:201], v[208:211], v[48:63]
	ds_read_b128 v[208:211], v151 offset:64
	s_waitcnt lgkmcnt(5)
	v_mfma_f32_32x32x16_bf16 v[0:15], v[194:197], v[212:215], v[0:15]
	v_mfma_f32_32x32x16_bf16 v[16:31], v[198:201], v[212:215], v[16:31]
	ds_read_b128 v[212:215], v151 offset:4672
	s_setprio 0
	global_load_dwordx4 v[194:197], v[132:133], off offset:1024
	global_load_dwordx4 v[198:201], v[134:135], off offset:1024
	s_setprio 1
	s_waitcnt lgkmcnt(1)
	v_mfma_f32_32x32x16_bf16 v[96:111], v[176:179], v[208:211], v[96:111]
	v_mfma_f32_32x32x16_bf16 v[112:127], v[180:183], v[208:211], v[112:127]
	s_waitcnt lgkmcnt(0)
	v_mfma_f32_32x32x16_bf16 v[64:79], v[176:179], v[212:215], v[64:79]
	v_mfma_f32_32x32x16_bf16 v[80:95], v[180:183], v[212:215], v[80:95]
	ds_read_b128 v[208:211], v151 offset:9280
	ds_read_b128 v[212:215], v151 offset:13888
	s_waitcnt vmcnt(7)
	ds_write_b128 v156, v[168:171]
	s_waitcnt vmcnt(6)
	ds_write_b128 v155, v[172:175]
	ds_read_b128 v[168:171], v152 offset:36960
	ds_read_b128 v[172:175], v152 offset:41568
	s_waitcnt lgkmcnt(5)
	v_mfma_f32_32x32x16_bf16 v[32:47], v[176:179], v[208:211], v[32:47]
	v_mfma_f32_32x32x16_bf16 v[48:63], v[180:183], v[208:211], v[48:63]
	ds_read_b128 v[208:211], v151 offset:96
	s_waitcnt lgkmcnt(5)
	v_mfma_f32_32x32x16_bf16 v[0:15], v[176:179], v[212:215], v[0:15]
	v_mfma_f32_32x32x16_bf16 v[16:31], v[180:183], v[212:215], v[16:31]
	ds_read_b128 v[212:215], v151 offset:4704
	s_setprio 0
	global_load_dwordx4 v[176:179], v[144:145], off offset:1024
	global_load_dwordx4 v[180:183], v[146:147], off offset:1024
	s_setprio 1
	s_waitcnt lgkmcnt(1)
	v_mfma_f32_32x32x16_bf16 v[96:111], v[168:171], v[208:211], v[96:111]
	v_mfma_f32_32x32x16_bf16 v[112:127], v[172:175], v[208:211], v[112:127]
	s_waitcnt lgkmcnt(0)
	v_mfma_f32_32x32x16_bf16 v[64:79], v[168:171], v[212:215], v[64:79]
	v_mfma_f32_32x32x16_bf16 v[80:95], v[172:175], v[212:215], v[80:95]
	ds_read_b128 v[208:211], v151 offset:9312
	ds_read_b128 v[212:215], v151 offset:13920
	s_waitcnt lgkmcnt(1)
	v_mfma_f32_32x32x16_bf16 v[32:47], v[168:171], v[208:211], v[32:47]
	v_mfma_f32_32x32x16_bf16 v[48:63], v[172:175], v[208:211], v[48:63]
	s_waitcnt lgkmcnt(0)
	v_mfma_f32_32x32x16_bf16 v[0:15], v[168:171], v[212:215], v[0:15]
	v_mfma_f32_32x32x16_bf16 v[16:31], v[172:175], v[212:215], v[16:31]
	s_setprio 0
	global_load_dwordx4 v[168:171], v[136:137], off offset:1152
	global_load_dwordx4 v[172:175], v[138:139], off offset:1152
	s_barrier
; template <bool trans>
; DI void gemm_core(const GTile& tl, const GTile& nx, bool has_next  , bool chain  , bool pre, u32x4 (&ra)[4], u32x4 (&rb)[4], char* smem, f32x16 (&acc)[2][4]) {
;     ...
;   const int nk = K / 64;
;   if (!pre) { G_LOAD(0); G_STORE(0); G_LOAD(1); }
;   for (int kt = 0; kt < nk; ++kt) {
;     __syncthreads();
;     G_COMPUTE(kt & 1, kt);
;   }
	s_waitcnt vmcnt(9)
	ds_write_b128 v148, v[160:163]
	s_waitcnt vmcnt(8)
	ds_write_b128 v148, v[164:167] offset:36864
	ds_read_b128 v[160:163], v150
	ds_read_b128 v[164:167], v150 offset:4608
	ds_read_b128 v[208:211], v149
	ds_read_b128 v[212:215], v149 offset:4608
	s_setprio 1
	s_waitcnt lgkmcnt(1)
	v_mfma_f32_32x32x16_bf16 v[96:111], v[160:163], v[208:211], v[96:111]
	v_mfma_f32_32x32x16_bf16 v[112:127], v[164:167], v[208:211], v[112:127]
	s_waitcnt lgkmcnt(0)
	v_mfma_f32_32x32x16_bf16 v[64:79], v[160:163], v[212:215], v[64:79]
	v_mfma_f32_32x32x16_bf16 v[80:95], v[164:167], v[212:215], v[80:95]
	ds_read_b128 v[208:211], v149 offset:9216
	ds_read_b128 v[212:215], v149 offset:13824
	s_waitcnt vmcnt(7)
	ds_write_b128 v148, v[184:187] offset:9216
	s_waitcnt vmcnt(6)
	ds_write_b128 v148, v[188:191] offset:46080
	ds_read_b128 v[184:187], v150 offset:32
	ds_read_b128 v[188:191], v150 offset:4640
	s_waitcnt lgkmcnt(5)
	v_mfma_f32_32x32x16_bf16 v[32:47], v[160:163], v[208:211], v[32:47]
	v_mfma_f32_32x32x16_bf16 v[48:63], v[164:167], v[208:211], v[48:63]
	ds_read_b128 v[208:211], v149 offset:32
	s_waitcnt lgkmcnt(5)
	v_mfma_f32_32x32x16_bf16 v[0:15], v[160:163], v[212:215], v[0:15]
	v_mfma_f32_32x32x16_bf16 v[16:31], v[164:167], v[212:215], v[16:31]
	ds_read_b128 v[212:215], v149 offset:4640
	s_setprio 0
	global_load_dwordx4 v[160:163], v[140:141], off offset:1152
	global_load_dwordx4 v[164:167], v[142:143], off offset:1152
	s_setprio 1
	s_waitcnt lgkmcnt(1)
	v_mfma_f32_32x32x16_bf16 v[96:111], v[184:187], v[208:211], v[96:111]
	v_mfma_f32_32x32x16_bf16 v[112:127], v[188:191], v[208:211], v[112:127]
	s_waitcnt lgkmcnt(0)
	v_mfma_f32_32x32x16_bf16 v[64:79], v[184:187], v[212:215], v[64:79]
	v_mfma_f32_32x32x16_bf16 v[80:95], v[188:191], v[212:215], v[80:95]
	ds_read_b128 v[208:211], v149 offset:9248
	ds_read_b128 v[212:215], v149 offset:13856
	s_waitcnt vmcnt(7)
	ds_write_b128 v148, v[194:197] offset:18432
	s_waitcnt vmcnt(6)
	ds_write_b128 v148, v[198:201] offset:55296
	ds_read_b128 v[194:197], v150 offset:64
	ds_read_b128 v[198:201], v150 offset:4672
	s_waitcnt lgkmcnt(5)
	v_mfma_f32_32x32x16_bf16 v[32:47], v[184:187], v[208:211], v[32:47]
	v_mfma_f32_32x32x16_bf16 v[48:63], v[188:191], v[208:211], v[48:63]
	ds_read_b128 v[208:211], v149 offset:64
	s_waitcnt lgkmcnt(5)
	v_mfma_f32_32x32x16_bf16 v[0:15], v[184:187], v[212:215], v[0:15]
	v_mfma_f32_32x32x16_bf16 v[16:31], v[188:191], v[212:215], v[16:31]
	ds_read_b128 v[212:215], v149 offset:4672
	s_setprio 0
	global_load_dwordx4 v[184:187], v[132:133], off offset:1152
	global_load_dwordx4 v[188:191], v[134:135], off offset:1152
	s_setprio 1
	s_waitcnt lgkmcnt(1)
	v_mfma_f32_32x32x16_bf16 v[96:111], v[194:197], v[208:211], v[96:111]
	v_mfma_f32_32x32x16_bf16 v[112:127], v[198:201], v[208:211], v[112:127]
	s_waitcnt lgkmcnt(0)
	v_mfma_f32_32x32x16_bf16 v[64:79], v[194:197], v[212:215], v[64:79]
	v_mfma_f32_32x32x16_bf16 v[80:95], v[198:201], v[212:215], v[80:95]
	ds_read_b128 v[208:211], v149 offset:9280
	ds_read_b128 v[212:215], v149 offset:13888
	s_waitcnt vmcnt(7)
	ds_write_b128 v148, v[176:179] offset:27648
	s_waitcnt vmcnt(6)
	ds_write_b128 v148, v[180:183] offset:64512
	ds_read_b128 v[176:179], v150 offset:96
	ds_read_b128 v[180:183], v150 offset:4704
	s_waitcnt lgkmcnt(5)
	v_mfma_f32_32x32x16_bf16 v[32:47], v[194:197], v[208:211], v[32:47]
	v_mfma_f32_32x32x16_bf16 v[48:63], v[198:201], v[208:211], v[48:63]
	ds_read_b128 v[208:211], v149 offset:96
	s_waitcnt lgkmcnt(5)
	v_mfma_f32_32x32x16_bf16 v[0:15], v[194:197], v[212:215], v[0:15]
	v_mfma_f32_32x32x16_bf16 v[16:31], v[198:201], v[212:215], v[16:31]
	ds_read_b128 v[212:215], v149 offset:4704
	s_setprio 0
	global_load_dwordx4 v[194:197], v[144:145], off offset:1152
	global_load_dwordx4 v[198:201], v[146:147], off offset:1152
	s_setprio 1
	s_waitcnt lgkmcnt(1)
	v_mfma_f32_32x32x16_bf16 v[96:111], v[176:179], v[208:211], v[96:111]
	v_mfma_f32_32x32x16_bf16 v[112:127], v[180:183], v[208:211], v[112:127]
	s_waitcnt lgkmcnt(0)
	v_mfma_f32_32x32x16_bf16 v[64:79], v[176:179], v[212:215], v[64:79]
	v_mfma_f32_32x32x16_bf16 v[80:95], v[180:183], v[212:215], v[80:95]
	ds_read_b128 v[208:211], v149 offset:9312
	ds_read_b128 v[212:215], v149 offset:13920
	s_waitcnt lgkmcnt(1)
	v_mfma_f32_32x32x16_bf16 v[32:47], v[176:179], v[208:211], v[32:47]
	v_mfma_f32_32x32x16_bf16 v[48:63], v[180:183], v[208:211], v[48:63]
	s_waitcnt lgkmcnt(0)
	v_mfma_f32_32x32x16_bf16 v[0:15], v[176:179], v[212:215], v[0:15]
	v_mfma_f32_32x32x16_bf16 v[16:31], v[180:183], v[212:215], v[16:31]
	s_setprio 0
	global_load_dwordx4 v[176:179], v[136:137], off offset:1280
	global_load_dwordx4 v[180:183], v[138:139], off offset:1280
	s_barrier
; template <bool trans>
; DI void gemm_core(const GTile& tl, const GTile& nx, bool has_next  , bool chain  , bool pre, u32x4 (&ra)[4], u32x4 (&rb)[4], char* smem, f32x16 (&acc)[2][4]) {
;     ...
;   const int nk = K / 64;
;   if (!pre) { G_LOAD(0); G_STORE(0); G_LOAD(1); }
;   for (int kt = 0; kt < nk; ++kt) {
;     __syncthreads();
;     G_COMPUTE(kt & 1, kt);
;   }
	s_waitcnt vmcnt(9)
	ds_write_b128 v192, v[168:171]
	s_waitcnt vmcnt(8)
	ds_write_b128 v159, v[172:175]
	ds_read_b128 v[168:171], v152 offset:36864
	ds_read_b128 v[172:175], v152 offset:41472
	ds_read_b128 v[208:211], v151
	ds_read_b128 v[212:215], v151 offset:4608
	s_setprio 1
	s_waitcnt lgkmcnt(1)
	v_mfma_f32_32x32x16_bf16 v[96:111], v[168:171], v[208:211], v[96:111]
	v_mfma_f32_32x32x16_bf16 v[112:127], v[172:175], v[208:211], v[112:127]
	s_waitcnt lgkmcnt(0)
	v_mfma_f32_32x32x16_bf16 v[64:79], v[168:171], v[212:215], v[64:79]
	v_mfma_f32_32x32x16_bf16 v[80:95], v[172:175], v[212:215], v[80:95]
	ds_read_b128 v[208:211], v151 offset:9216
	ds_read_b128 v[212:215], v151 offset:13824
	s_waitcnt vmcnt(7)
	ds_write_b128 v158, v[160:163]
	s_waitcnt vmcnt(6)
	ds_write_b128 v157, v[164:167]
	ds_read_b128 v[160:163], v152 offset:36896
	ds_read_b128 v[164:167], v152 offset:41504
	s_waitcnt lgkmcnt(5)
	v_mfma_f32_32x32x16_bf16 v[32:47], v[168:171], v[208:211], v[32:47]
	v_mfma_f32_32x32x16_bf16 v[48:63], v[172:175], v[208:211], v[48:63]
	ds_read_b128 v[208:211], v151 offset:32
	s_waitcnt lgkmcnt(5)
	v_mfma_f32_32x32x16_bf16 v[0:15], v[168:171], v[212:215], v[0:15]
	v_mfma_f32_32x32x16_bf16 v[16:31], v[172:175], v[212:215], v[16:31]
	ds_read_b128 v[212:215], v151 offset:4640
	s_setprio 0
	global_load_dwordx4 v[168:171], v[140:141], off offset:1280
	global_load_dwordx4 v[172:175], v[142:143], off offset:1280
	s_setprio 1
	s_waitcnt lgkmcnt(1)
	v_mfma_f32_32x32x16_bf16 v[96:111], v[160:163], v[208:211], v[96:111]
	v_mfma_f32_32x32x16_bf16 v[112:127], v[164:167], v[208:211], v[112:127]
	s_waitcnt lgkmcnt(0)
	v_mfma_f32_32x32x16_bf16 v[64:79], v[160:163], v[212:215], v[64:79]
	v_mfma_f32_32x32x16_bf16 v[80:95], v[164:167], v[212:215], v[80:95]
	ds_read_b128 v[208:211], v151 offset:9248
	ds_read_b128 v[212:215], v151 offset:13856
	s_waitcnt vmcnt(7)
	ds_write_b128 v154, v[184:187]
	s_waitcnt vmcnt(6)
	ds_write_b128 v153, v[188:191]
	ds_read_b128 v[184:187], v152 offset:36928
	ds_read_b128 v[188:191], v152 offset:41536
	s_waitcnt lgkmcnt(5)
	v_mfma_f32_32x32x16_bf16 v[32:47], v[160:163], v[208:211], v[32:47]
	v_mfma_f32_32x32x16_bf16 v[48:63], v[164:167], v[208:211], v[48:63]
	ds_read_b128 v[208:211], v151 offset:64
	s_waitcnt lgkmcnt(5)
	v_mfma_f32_32x32x16_bf16 v[0:15], v[160:163], v[212:215], v[0:15]
	v_mfma_f32_32x32x16_bf16 v[16:31], v[164:167], v[212:215], v[16:31]
	ds_read_b128 v[212:215], v151 offset:4672
	s_setprio 0
	global_load_dwordx4 v[160:163], v[132:133], off offset:1280
	global_load_dwordx4 v[164:167], v[134:135], off offset:1280
	s_setprio 1
	s_waitcnt lgkmcnt(1)
	v_mfma_f32_32x32x16_bf16 v[96:111], v[184:187], v[208:211], v[96:111]
	v_mfma_f32_32x32x16_bf16 v[112:127], v[188:191], v[208:211], v[112:127]
	s_waitcnt lgkmcnt(0)
	v_mfma_f32_32x32x16_bf16 v[64:79], v[184:187], v[212:215], v[64:79]
	v_mfma_f32_32x32x16_bf16 v[80:95], v[188:191], v[212:215], v[80:95]
	ds_read_b128 v[208:211], v151 offset:9280
	ds_read_b128 v[212:215], v151 offset:13888
	s_waitcnt vmcnt(7)
	ds_write_b128 v156, v[194:197]
	s_waitcnt vmcnt(6)
	ds_write_b128 v155, v[198:201]
	ds_read_b128 v[194:197], v152 offset:36960
	ds_read_b128 v[198:201], v152 offset:41568
	s_waitcnt lgkmcnt(5)
	v_mfma_f32_32x32x16_bf16 v[32:47], v[184:187], v[208:211], v[32:47]
	v_mfma_f32_32x32x16_bf16 v[48:63], v[188:191], v[208:211], v[48:63]
	ds_read_b128 v[208:211], v151 offset:96
	s_waitcnt lgkmcnt(5)
	v_mfma_f32_32x32x16_bf16 v[0:15], v[184:187], v[212:215], v[0:15]
	v_mfma_f32_32x32x16_bf16 v[16:31], v[188:191], v[212:215], v[16:31]
	ds_read_b128 v[212:215], v151 offset:4704
	s_setprio 0
	global_load_dwordx4 v[184:187], v[144:145], off offset:1280
	global_load_dwordx4 v[188:191], v[146:147], off offset:1280
	s_setprio 1
	s_waitcnt lgkmcnt(1)
	v_mfma_f32_32x32x16_bf16 v[96:111], v[194:197], v[208:211], v[96:111]
	v_mfma_f32_32x32x16_bf16 v[112:127], v[198:201], v[208:211], v[112:127]
	s_waitcnt lgkmcnt(0)
	v_mfma_f32_32x32x16_bf16 v[64:79], v[194:197], v[212:215], v[64:79]
	v_mfma_f32_32x32x16_bf16 v[80:95], v[198:201], v[212:215], v[80:95]
	ds_read_b128 v[208:211], v151 offset:9312
	ds_read_b128 v[212:215], v151 offset:13920
	s_waitcnt lgkmcnt(1)
	v_mfma_f32_32x32x16_bf16 v[32:47], v[194:197], v[208:211], v[32:47]
	v_mfma_f32_32x32x16_bf16 v[48:63], v[198:201], v[208:211], v[48:63]
	s_waitcnt lgkmcnt(0)
	v_mfma_f32_32x32x16_bf16 v[0:15], v[194:197], v[212:215], v[0:15]
	v_mfma_f32_32x32x16_bf16 v[16:31], v[198:201], v[212:215], v[16:31]
	s_setprio 0
	global_load_dwordx4 v[194:197], v[136:137], off offset:1408
	global_load_dwordx4 v[198:201], v[138:139], off offset:1408
	s_barrier
; template <bool trans>
; DI void gemm_core(const GTile& tl, const GTile& nx, bool has_next  , bool chain  , bool pre, u32x4 (&ra)[4], u32x4 (&rb)[4], char* smem, f32x16 (&acc)[2][4]) {
;     ...
;   const int nk = K / 64;
;   if (!pre) { G_LOAD(0); G_STORE(0); G_LOAD(1); }
;   for (int kt = 0; kt < nk; ++kt) {
;     __syncthreads();
;     G_COMPUTE(kt & 1, kt);
;   }
	s_waitcnt vmcnt(9)
	ds_write_b128 v148, v[176:179]
	s_waitcnt vmcnt(8)
	ds_write_b128 v148, v[180:183] offset:36864
	ds_read_b128 v[176:179], v150
	ds_read_b128 v[180:183], v150 offset:4608
	ds_read_b128 v[208:211], v149
	ds_read_b128 v[212:215], v149 offset:4608
	s_setprio 1
	s_waitcnt lgkmcnt(1)
	v_mfma_f32_32x32x16_bf16 v[96:111], v[176:179], v[208:211], v[96:111]
	v_mfma_f32_32x32x16_bf16 v[112:127], v[180:183], v[208:211], v[112:127]
	s_waitcnt lgkmcnt(0)
	v_mfma_f32_32x32x16_bf16 v[64:79], v[176:179], v[212:215], v[64:79]
	v_mfma_f32_32x32x16_bf16 v[80:95], v[180:183], v[212:215], v[80:95]
	ds_read_b128 v[208:211], v149 offset:9216
	ds_read_b128 v[212:215], v149 offset:13824
	s_waitcnt vmcnt(7)
	ds_write_b128 v148, v[168:171] offset:9216
	s_waitcnt vmcnt(6)
	ds_write_b128 v148, v[172:175] offset:46080
	ds_read_b128 v[168:171], v150 offset:32
	ds_read_b128 v[172:175], v150 offset:4640
	s_waitcnt lgkmcnt(5)
	v_mfma_f32_32x32x16_bf16 v[32:47], v[176:179], v[208:211], v[32:47]
	v_mfma_f32_32x32x16_bf16 v[48:63], v[180:183], v[208:211], v[48:63]
	ds_read_b128 v[208:211], v149 offset:32
	s_waitcnt lgkmcnt(5)
	v_mfma_f32_32x32x16_bf16 v[0:15], v[176:179], v[212:215], v[0:15]
	v_mfma_f32_32x32x16_bf16 v[16:31], v[180:183], v[212:215], v[16:31]
	ds_read_b128 v[212:215], v149 offset:4640
	s_setprio 0
	global_load_dwordx4 v[176:179], v[140:141], off offset:1408
	global_load_dwordx4 v[180:183], v[142:143], off offset:1408
	s_setprio 1
	s_waitcnt lgkmcnt(1)
	v_mfma_f32_32x32x16_bf16 v[96:111], v[168:171], v[208:211], v[96:111]
	v_mfma_f32_32x32x16_bf16 v[112:127], v[172:175], v[208:211], v[112:127]
	s_waitcnt lgkmcnt(0)
	v_mfma_f32_32x32x16_bf16 v[64:79], v[168:171], v[212:215], v[64:79]
	v_mfma_f32_32x32x16_bf16 v[80:95], v[172:175], v[212:215], v[80:95]
	ds_read_b128 v[208:211], v149 offset:9248
	ds_read_b128 v[212:215], v149 offset:13856
	s_waitcnt vmcnt(7)
	ds_write_b128 v148, v[160:163] offset:18432
	s_waitcnt vmcnt(6)
	ds_write_b128 v148, v[164:167] offset:55296
	ds_read_b128 v[160:163], v150 offset:64
	ds_read_b128 v[164:167], v150 offset:4672
	s_waitcnt lgkmcnt(5)
	v_mfma_f32_32x32x16_bf16 v[32:47], v[168:171], v[208:211], v[32:47]
	v_mfma_f32_32x32x16_bf16 v[48:63], v[172:175], v[208:211], v[48:63]
	ds_read_b128 v[208:211], v149 offset:64
	s_waitcnt lgkmcnt(5)
	v_mfma_f32_32x32x16_bf16 v[0:15], v[168:171], v[212:215], v[0:15]
	v_mfma_f32_32x32x16_bf16 v[16:31], v[172:175], v[212:215], v[16:31]
	ds_read_b128 v[212:215], v149 offset:4672
	s_setprio 0
	global_load_dwordx4 v[168:171], v[132:133], off offset:1408
	global_load_dwordx4 v[172:175], v[134:135], off offset:1408
	s_setprio 1
	s_waitcnt lgkmcnt(1)
	v_mfma_f32_32x32x16_bf16 v[96:111], v[160:163], v[208:211], v[96:111]
	v_mfma_f32_32x32x16_bf16 v[112:127], v[164:167], v[208:211], v[112:127]
	s_waitcnt lgkmcnt(0)
	v_mfma_f32_32x32x16_bf16 v[64:79], v[160:163], v[212:215], v[64:79]
	v_mfma_f32_32x32x16_bf16 v[80:95], v[164:167], v[212:215], v[80:95]
	ds_read_b128 v[208:211], v149 offset:9280
	ds_read_b128 v[212:215], v149 offset:13888
	s_waitcnt vmcnt(7)
	ds_write_b128 v148, v[184:187] offset:27648
	s_waitcnt vmcnt(6)
	ds_write_b128 v148, v[188:191] offset:64512
	ds_read_b128 v[184:187], v150 offset:96
	ds_read_b128 v[188:191], v150 offset:4704
	s_waitcnt lgkmcnt(5)
	v_mfma_f32_32x32x16_bf16 v[32:47], v[160:163], v[208:211], v[32:47]
	v_mfma_f32_32x32x16_bf16 v[48:63], v[164:167], v[208:211], v[48:63]
	ds_read_b128 v[208:211], v149 offset:96
	s_waitcnt lgkmcnt(5)
	v_mfma_f32_32x32x16_bf16 v[0:15], v[160:163], v[212:215], v[0:15]
	v_mfma_f32_32x32x16_bf16 v[16:31], v[164:167], v[212:215], v[16:31]
	ds_read_b128 v[212:215], v149 offset:4704
	s_setprio 0
	global_load_dwordx4 v[160:163], v[144:145], off offset:1408
	global_load_dwordx4 v[164:167], v[146:147], off offset:1408
	s_setprio 1
	s_waitcnt lgkmcnt(1)
	v_mfma_f32_32x32x16_bf16 v[96:111], v[184:187], v[208:211], v[96:111]
	v_mfma_f32_32x32x16_bf16 v[112:127], v[188:191], v[208:211], v[112:127]
	s_waitcnt lgkmcnt(0)
	v_mfma_f32_32x32x16_bf16 v[64:79], v[184:187], v[212:215], v[64:79]
	v_mfma_f32_32x32x16_bf16 v[80:95], v[188:191], v[212:215], v[80:95]
	ds_read_b128 v[208:211], v149 offset:9312
	ds_read_b128 v[212:215], v149 offset:13920
	s_waitcnt lgkmcnt(1)
	v_mfma_f32_32x32x16_bf16 v[32:47], v[184:187], v[208:211], v[32:47]
	v_mfma_f32_32x32x16_bf16 v[48:63], v[188:191], v[208:211], v[48:63]
	s_waitcnt lgkmcnt(0)
	v_mfma_f32_32x32x16_bf16 v[0:15], v[184:187], v[212:215], v[0:15]
	v_mfma_f32_32x32x16_bf16 v[16:31], v[188:191], v[212:215], v[16:31]
	s_setprio 0
	global_load_dwordx4 v[184:187], v[136:137], off offset:1536
	global_load_dwordx4 v[188:191], v[138:139], off offset:1536
	s_barrier
; template <bool trans>
; DI void gemm_core(const GTile& tl, const GTile& nx, bool has_next  , bool chain  , bool pre, u32x4 (&ra)[4], u32x4 (&rb)[4], char* smem, f32x16 (&acc)[2][4]) {
;     ...
;   const int nk = K / 64;
;   if (!pre) { G_LOAD(0); G_STORE(0); G_LOAD(1); }
;   for (int kt = 0; kt < nk; ++kt) {
;     __syncthreads();
;     G_COMPUTE(kt & 1, kt);
;   }
	s_waitcnt vmcnt(9)
	ds_write_b128 v192, v[194:197]
	s_waitcnt vmcnt(8)
	ds_write_b128 v159, v[198:201]
	ds_read_b128 v[194:197], v152 offset:36864
	ds_read_b128 v[198:201], v152 offset:41472
	ds_read_b128 v[208:211], v151
	ds_read_b128 v[212:215], v151 offset:4608
	s_setprio 1
	s_waitcnt lgkmcnt(1)
	v_mfma_f32_32x32x16_bf16 v[96:111], v[194:197], v[208:211], v[96:111]
	v_mfma_f32_32x32x16_bf16 v[112:127], v[198:201], v[208:211], v[112:127]
	s_waitcnt lgkmcnt(0)
	v_mfma_f32_32x32x16_bf16 v[64:79], v[194:197], v[212:215], v[64:79]
	v_mfma_f32_32x32x16_bf16 v[80:95], v[198:201], v[212:215], v[80:95]
	ds_read_b128 v[208:211], v151 offset:9216
	ds_read_b128 v[212:215], v151 offset:13824
	s_waitcnt vmcnt(7)
	ds_write_b128 v158, v[176:179]
	s_waitcnt vmcnt(6)
	ds_write_b128 v157, v[180:183]
	ds_read_b128 v[176:179], v152 offset:36896
	ds_read_b128 v[180:183], v152 offset:41504
	s_waitcnt lgkmcnt(5)
	v_mfma_f32_32x32x16_bf16 v[32:47], v[194:197], v[208:211], v[32:47]
	v_mfma_f32_32x32x16_bf16 v[48:63], v[198:201], v[208:211], v[48:63]
	ds_read_b128 v[208:211], v151 offset:32
	s_waitcnt lgkmcnt(5)
	v_mfma_f32_32x32x16_bf16 v[0:15], v[194:197], v[212:215], v[0:15]
	v_mfma_f32_32x32x16_bf16 v[16:31], v[198:201], v[212:215], v[16:31]
	ds_read_b128 v[212:215], v151 offset:4640
	s_setprio 0
	global_load_dwordx4 v[194:197], v[140:141], off offset:1536
	global_load_dwordx4 v[198:201], v[142:143], off offset:1536
	s_setprio 1
	s_waitcnt lgkmcnt(1)
	v_mfma_f32_32x32x16_bf16 v[96:111], v[176:179], v[208:211], v[96:111]
	v_mfma_f32_32x32x16_bf16 v[112:127], v[180:183], v[208:211], v[112:127]
	s_waitcnt lgkmcnt(0)
	v_mfma_f32_32x32x16_bf16 v[64:79], v[176:179], v[212:215], v[64:79]
	v_mfma_f32_32x32x16_bf16 v[80:95], v[180:183], v[212:215], v[80:95]
	ds_read_b128 v[208:211], v151 offset:9248
	ds_read_b128 v[212:215], v151 offset:13856
	s_waitcnt vmcnt(7)
	ds_write_b128 v154, v[168:171]
	s_waitcnt vmcnt(6)
	ds_write_b128 v153, v[172:175]
	ds_read_b128 v[168:171], v152 offset:36928
	ds_read_b128 v[172:175], v152 offset:41536
	s_waitcnt lgkmcnt(5)
	v_mfma_f32_32x32x16_bf16 v[32:47], v[176:179], v[208:211], v[32:47]
	v_mfma_f32_32x32x16_bf16 v[48:63], v[180:183], v[208:211], v[48:63]
	ds_read_b128 v[208:211], v151 offset:64
	s_waitcnt lgkmcnt(5)
	v_mfma_f32_32x32x16_bf16 v[0:15], v[176:179], v[212:215], v[0:15]
	v_mfma_f32_32x32x16_bf16 v[16:31], v[180:183], v[212:215], v[16:31]
	ds_read_b128 v[212:215], v151 offset:4672
	s_setprio 0
	global_load_dwordx4 v[176:179], v[132:133], off offset:1536
	global_load_dwordx4 v[180:183], v[134:135], off offset:1536
	s_setprio 1
	s_waitcnt lgkmcnt(1)
	v_mfma_f32_32x32x16_bf16 v[96:111], v[168:171], v[208:211], v[96:111]
	v_mfma_f32_32x32x16_bf16 v[112:127], v[172:175], v[208:211], v[112:127]
	s_waitcnt lgkmcnt(0)
	v_mfma_f32_32x32x16_bf16 v[64:79], v[168:171], v[212:215], v[64:79]
	v_mfma_f32_32x32x16_bf16 v[80:95], v[172:175], v[212:215], v[80:95]
	ds_read_b128 v[208:211], v151 offset:9280
	ds_read_b128 v[212:215], v151 offset:13888
	s_waitcnt vmcnt(7)
	ds_write_b128 v156, v[160:163]
	s_waitcnt vmcnt(6)
	ds_write_b128 v155, v[164:167]
	ds_read_b128 v[160:163], v152 offset:36960
	ds_read_b128 v[164:167], v152 offset:41568
	s_waitcnt lgkmcnt(5)
	v_mfma_f32_32x32x16_bf16 v[32:47], v[168:171], v[208:211], v[32:47]
	v_mfma_f32_32x32x16_bf16 v[48:63], v[172:175], v[208:211], v[48:63]
	ds_read_b128 v[208:211], v151 offset:96
	s_waitcnt lgkmcnt(5)
	v_mfma_f32_32x32x16_bf16 v[0:15], v[168:171], v[212:215], v[0:15]
	v_mfma_f32_32x32x16_bf16 v[16:31], v[172:175], v[212:215], v[16:31]
	ds_read_b128 v[212:215], v151 offset:4704
	s_setprio 0
	global_load_dwordx4 v[168:171], v[144:145], off offset:1536
	global_load_dwordx4 v[172:175], v[146:147], off offset:1536
	s_setprio 1
	s_waitcnt lgkmcnt(1)
	v_mfma_f32_32x32x16_bf16 v[96:111], v[160:163], v[208:211], v[96:111]
	v_mfma_f32_32x32x16_bf16 v[112:127], v[164:167], v[208:211], v[112:127]
	s_waitcnt lgkmcnt(0)
	v_mfma_f32_32x32x16_bf16 v[64:79], v[160:163], v[212:215], v[64:79]
	v_mfma_f32_32x32x16_bf16 v[80:95], v[164:167], v[212:215], v[80:95]
	ds_read_b128 v[208:211], v151 offset:9312
	ds_read_b128 v[212:215], v151 offset:13920
	s_waitcnt lgkmcnt(1)
	v_mfma_f32_32x32x16_bf16 v[32:47], v[160:163], v[208:211], v[32:47]
	v_mfma_f32_32x32x16_bf16 v[48:63], v[164:167], v[208:211], v[48:63]
	s_waitcnt lgkmcnt(0)
	v_mfma_f32_32x32x16_bf16 v[0:15], v[160:163], v[212:215], v[0:15]
	v_mfma_f32_32x32x16_bf16 v[16:31], v[164:167], v[212:215], v[16:31]
	s_setprio 0
	global_load_dwordx4 v[160:163], v[136:137], off offset:1664
	global_load_dwordx4 v[164:167], v[138:139], off offset:1664
	s_barrier
; template <bool trans>
; DI void gemm_core(const GTile& tl, const GTile& nx, bool has_next  , bool chain  , bool pre, u32x4 (&ra)[4], u32x4 (&rb)[4], char* smem, f32x16 (&acc)[2][4]) {
;     ...
;   const int nk = K / 64;
;   if (!pre) { G_LOAD(0); G_STORE(0); G_LOAD(1); }
;   for (int kt = 0; kt < nk; ++kt) {
;     __syncthreads();
;     G_COMPUTE(kt & 1, kt);
;   }
	s_waitcnt vmcnt(9)
	ds_write_b128 v148, v[184:187]
	s_waitcnt vmcnt(8)
	ds_write_b128 v148, v[188:191] offset:36864
	ds_read_b128 v[184:187], v150
	ds_read_b128 v[188:191], v150 offset:4608
	ds_read_b128 v[208:211], v149
	ds_read_b128 v[212:215], v149 offset:4608
	s_setprio 1
	s_waitcnt lgkmcnt(1)
	v_mfma_f32_32x32x16_bf16 v[96:111], v[184:187], v[208:211], v[96:111]
	v_mfma_f32_32x32x16_bf16 v[112:127], v[188:191], v[208:211], v[112:127]
	s_waitcnt lgkmcnt(0)
	v_mfma_f32_32x32x16_bf16 v[64:79], v[184:187], v[212:215], v[64:79]
	v_mfma_f32_32x32x16_bf16 v[80:95], v[188:191], v[212:215], v[80:95]
	ds_read_b128 v[208:211], v149 offset:9216
	ds_read_b128 v[212:215], v149 offset:13824
	s_waitcnt vmcnt(7)
	ds_write_b128 v148, v[194:197] offset:9216
	s_waitcnt vmcnt(6)
	ds_write_b128 v148, v[198:201] offset:46080
	ds_read_b128 v[194:197], v150 offset:32
	ds_read_b128 v[198:201], v150 offset:4640
	s_waitcnt lgkmcnt(5)
	v_mfma_f32_32x32x16_bf16 v[32:47], v[184:187], v[208:211], v[32:47]
	v_mfma_f32_32x32x16_bf16 v[48:63], v[188:191], v[208:211], v[48:63]
	ds_read_b128 v[208:211], v149 offset:32
	s_waitcnt lgkmcnt(5)
	v_mfma_f32_32x32x16_bf16 v[0:15], v[184:187], v[212:215], v[0:15]
	v_mfma_f32_32x32x16_bf16 v[16:31], v[188:191], v[212:215], v[16:31]
	ds_read_b128 v[212:215], v149 offset:4640
	s_setprio 0
	global_load_dwordx4 v[184:187], v[140:141], off offset:1664
	global_load_dwordx4 v[188:191], v[142:143], off offset:1664
	s_setprio 1
	s_waitcnt lgkmcnt(1)
	v_mfma_f32_32x32x16_bf16 v[96:111], v[194:197], v[208:211], v[96:111]
	v_mfma_f32_32x32x16_bf16 v[112:127], v[198:201], v[208:211], v[112:127]
	s_waitcnt lgkmcnt(0)
	v_mfma_f32_32x32x16_bf16 v[64:79], v[194:197], v[212:215], v[64:79]
	v_mfma_f32_32x32x16_bf16 v[80:95], v[198:201], v[212:215], v[80:95]
	ds_read_b128 v[208:211], v149 offset:9248
	ds_read_b128 v[212:215], v149 offset:13856
	s_waitcnt vmcnt(7)
	ds_write_b128 v148, v[176:179] offset:18432
	s_waitcnt vmcnt(6)
	ds_write_b128 v148, v[180:183] offset:55296
	ds_read_b128 v[176:179], v150 offset:64
	ds_read_b128 v[180:183], v150 offset:4672
	s_waitcnt lgkmcnt(5)
	v_mfma_f32_32x32x16_bf16 v[32:47], v[194:197], v[208:211], v[32:47]
	v_mfma_f32_32x32x16_bf16 v[48:63], v[198:201], v[208:211], v[48:63]
	ds_read_b128 v[208:211], v149 offset:64
	s_waitcnt lgkmcnt(5)
	v_mfma_f32_32x32x16_bf16 v[0:15], v[194:197], v[212:215], v[0:15]
	v_mfma_f32_32x32x16_bf16 v[16:31], v[198:201], v[212:215], v[16:31]
	ds_read_b128 v[212:215], v149 offset:4672
	s_setprio 0
	global_load_dwordx4 v[194:197], v[132:133], off offset:1664
	global_load_dwordx4 v[198:201], v[134:135], off offset:1664
	s_setprio 1
	s_waitcnt lgkmcnt(1)
	v_mfma_f32_32x32x16_bf16 v[96:111], v[176:179], v[208:211], v[96:111]
	v_mfma_f32_32x32x16_bf16 v[112:127], v[180:183], v[208:211], v[112:127]
	s_waitcnt lgkmcnt(0)
	v_mfma_f32_32x32x16_bf16 v[64:79], v[176:179], v[212:215], v[64:79]
	v_mfma_f32_32x32x16_bf16 v[80:95], v[180:183], v[212:215], v[80:95]
	ds_read_b128 v[208:211], v149 offset:9280
	ds_read_b128 v[212:215], v149 offset:13888
	s_waitcnt vmcnt(7)
	ds_write_b128 v148, v[168:171] offset:27648
	s_waitcnt vmcnt(6)
	ds_write_b128 v148, v[172:175] offset:64512
	ds_read_b128 v[168:171], v150 offset:96
	ds_read_b128 v[172:175], v150 offset:4704
	s_waitcnt lgkmcnt(5)
	v_mfma_f32_32x32x16_bf16 v[32:47], v[176:179], v[208:211], v[32:47]
	v_mfma_f32_32x32x16_bf16 v[48:63], v[180:183], v[208:211], v[48:63]
	ds_read_b128 v[208:211], v149 offset:96
	s_waitcnt lgkmcnt(5)
	v_mfma_f32_32x32x16_bf16 v[0:15], v[176:179], v[212:215], v[0:15]
	v_mfma_f32_32x32x16_bf16 v[16:31], v[180:183], v[212:215], v[16:31]
	ds_read_b128 v[212:215], v149 offset:4704
	s_setprio 0
	global_load_dwordx4 v[176:179], v[144:145], off offset:1664
	global_load_dwordx4 v[180:183], v[146:147], off offset:1664
	s_setprio 1
	s_waitcnt lgkmcnt(1)
	v_mfma_f32_32x32x16_bf16 v[96:111], v[168:171], v[208:211], v[96:111]
	v_mfma_f32_32x32x16_bf16 v[112:127], v[172:175], v[208:211], v[112:127]
	s_waitcnt lgkmcnt(0)
	v_mfma_f32_32x32x16_bf16 v[64:79], v[168:171], v[212:215], v[64:79]
	v_mfma_f32_32x32x16_bf16 v[80:95], v[172:175], v[212:215], v[80:95]
	ds_read_b128 v[208:211], v149 offset:9312
	ds_read_b128 v[212:215], v149 offset:13920
	s_waitcnt lgkmcnt(1)
	v_mfma_f32_32x32x16_bf16 v[32:47], v[168:171], v[208:211], v[32:47]
	v_mfma_f32_32x32x16_bf16 v[48:63], v[172:175], v[208:211], v[48:63]
	s_waitcnt lgkmcnt(0)
	v_mfma_f32_32x32x16_bf16 v[0:15], v[168:171], v[212:215], v[0:15]
	v_mfma_f32_32x32x16_bf16 v[16:31], v[172:175], v[212:215], v[16:31]
	s_setprio 0
	global_load_dwordx4 v[168:171], v[136:137], off offset:1792
	global_load_dwordx4 v[172:175], v[138:139], off offset:1792
	s_barrier
; template <bool trans>
; DI void gemm_core(const GTile& tl, const GTile& nx, bool has_next  , bool chain  , bool pre, u32x4 (&ra)[4], u32x4 (&rb)[4], char* smem, f32x16 (&acc)[2][4]) {
;     ...
;   const int nk = K / 64;
;   if (!pre) { G_LOAD(0); G_STORE(0); G_LOAD(1); }
;   for (int kt = 0; kt < nk; ++kt) {
;     __syncthreads();
;     G_COMPUTE(kt & 1, kt);
;   }
	s_waitcnt vmcnt(9)
	ds_write_b128 v192, v[160:163]
	s_waitcnt vmcnt(8)
	ds_write_b128 v159, v[164:167]
	ds_read_b128 v[160:163], v152 offset:36864
	ds_read_b128 v[164:167], v152 offset:41472
	ds_read_b128 v[208:211], v151
	ds_read_b128 v[212:215], v151 offset:4608
	s_setprio 1
	s_waitcnt lgkmcnt(1)
	v_mfma_f32_32x32x16_bf16 v[96:111], v[160:163], v[208:211], v[96:111]
	v_mfma_f32_32x32x16_bf16 v[112:127], v[164:167], v[208:211], v[112:127]
	s_waitcnt lgkmcnt(0)
	v_mfma_f32_32x32x16_bf16 v[64:79], v[160:163], v[212:215], v[64:79]
	v_mfma_f32_32x32x16_bf16 v[80:95], v[164:167], v[212:215], v[80:95]
	ds_read_b128 v[208:211], v151 offset:9216
	ds_read_b128 v[212:215], v151 offset:13824
	s_waitcnt vmcnt(7)
	ds_write_b128 v158, v[184:187]
	s_waitcnt vmcnt(6)
	ds_write_b128 v157, v[188:191]
	ds_read_b128 v[184:187], v152 offset:36896
	ds_read_b128 v[188:191], v152 offset:41504
	s_waitcnt lgkmcnt(5)
	v_mfma_f32_32x32x16_bf16 v[32:47], v[160:163], v[208:211], v[32:47]
	v_mfma_f32_32x32x16_bf16 v[48:63], v[164:167], v[208:211], v[48:63]
	ds_read_b128 v[208:211], v151 offset:32
	s_waitcnt lgkmcnt(5)
	v_mfma_f32_32x32x16_bf16 v[0:15], v[160:163], v[212:215], v[0:15]
	v_mfma_f32_32x32x16_bf16 v[16:31], v[164:167], v[212:215], v[16:31]
	ds_read_b128 v[212:215], v151 offset:4640
	s_setprio 0
	global_load_dwordx4 v[160:163], v[140:141], off offset:1792
	global_load_dwordx4 v[164:167], v[142:143], off offset:1792
	s_setprio 1
	s_waitcnt lgkmcnt(1)
	v_mfma_f32_32x32x16_bf16 v[96:111], v[184:187], v[208:211], v[96:111]
	v_mfma_f32_32x32x16_bf16 v[112:127], v[188:191], v[208:211], v[112:127]
	s_waitcnt lgkmcnt(0)
	v_mfma_f32_32x32x16_bf16 v[64:79], v[184:187], v[212:215], v[64:79]
	v_mfma_f32_32x32x16_bf16 v[80:95], v[188:191], v[212:215], v[80:95]
	ds_read_b128 v[208:211], v151 offset:9248
	ds_read_b128 v[212:215], v151 offset:13856
	s_waitcnt vmcnt(7)
	ds_write_b128 v154, v[194:197]
	s_waitcnt vmcnt(6)
	ds_write_b128 v153, v[198:201]
	ds_read_b128 v[194:197], v152 offset:36928
	ds_read_b128 v[198:201], v152 offset:41536
	s_waitcnt lgkmcnt(5)
	v_mfma_f32_32x32x16_bf16 v[32:47], v[184:187], v[208:211], v[32:47]
	v_mfma_f32_32x32x16_bf16 v[48:63], v[188:191], v[208:211], v[48:63]
	ds_read_b128 v[208:211], v151 offset:64
	s_waitcnt lgkmcnt(5)
	v_mfma_f32_32x32x16_bf16 v[0:15], v[184:187], v[212:215], v[0:15]
	v_mfma_f32_32x32x16_bf16 v[16:31], v[188:191], v[212:215], v[16:31]
	ds_read_b128 v[212:215], v151 offset:4672
	s_setprio 0
	global_load_dwordx4 v[184:187], v[132:133], off offset:1792
	global_load_dwordx4 v[188:191], v[134:135], off offset:1792
	s_setprio 1
	s_waitcnt lgkmcnt(1)
	v_mfma_f32_32x32x16_bf16 v[96:111], v[194:197], v[208:211], v[96:111]
	v_mfma_f32_32x32x16_bf16 v[112:127], v[198:201], v[208:211], v[112:127]
	s_waitcnt lgkmcnt(0)
	v_mfma_f32_32x32x16_bf16 v[64:79], v[194:197], v[212:215], v[64:79]
	v_mfma_f32_32x32x16_bf16 v[80:95], v[198:201], v[212:215], v[80:95]
	ds_read_b128 v[208:211], v151 offset:9280
	ds_read_b128 v[212:215], v151 offset:13888
	s_waitcnt vmcnt(7)
	ds_write_b128 v156, v[176:179]
	s_waitcnt vmcnt(6)
	ds_write_b128 v155, v[180:183]
	ds_read_b128 v[176:179], v152 offset:36960
	ds_read_b128 v[180:183], v152 offset:41568
	s_waitcnt lgkmcnt(5)
	v_mfma_f32_32x32x16_bf16 v[32:47], v[194:197], v[208:211], v[32:47]
	v_mfma_f32_32x32x16_bf16 v[48:63], v[198:201], v[208:211], v[48:63]
	ds_read_b128 v[208:211], v151 offset:96
	s_waitcnt lgkmcnt(5)
	v_mfma_f32_32x32x16_bf16 v[0:15], v[194:197], v[212:215], v[0:15]
	v_mfma_f32_32x32x16_bf16 v[16:31], v[198:201], v[212:215], v[16:31]
	ds_read_b128 v[212:215], v151 offset:4704
	s_setprio 0
	global_load_dwordx4 v[194:197], v[144:145], off offset:1792
	global_load_dwordx4 v[198:201], v[146:147], off offset:1792
	s_setprio 1
	s_waitcnt lgkmcnt(1)
	v_mfma_f32_32x32x16_bf16 v[96:111], v[176:179], v[208:211], v[96:111]
	v_mfma_f32_32x32x16_bf16 v[112:127], v[180:183], v[208:211], v[112:127]
	s_waitcnt lgkmcnt(0)
	v_mfma_f32_32x32x16_bf16 v[64:79], v[176:179], v[212:215], v[64:79]
	v_mfma_f32_32x32x16_bf16 v[80:95], v[180:183], v[212:215], v[80:95]
	ds_read_b128 v[208:211], v151 offset:9312
	ds_read_b128 v[212:215], v151 offset:13920
	s_waitcnt lgkmcnt(1)
	v_mfma_f32_32x32x16_bf16 v[32:47], v[176:179], v[208:211], v[32:47]
	v_mfma_f32_32x32x16_bf16 v[48:63], v[180:183], v[208:211], v[48:63]
	s_waitcnt lgkmcnt(0)
	v_mfma_f32_32x32x16_bf16 v[0:15], v[176:179], v[212:215], v[0:15]
	v_mfma_f32_32x32x16_bf16 v[16:31], v[180:183], v[212:215], v[16:31]
	s_setprio 0
	global_load_dwordx4 v[176:179], v[136:137], off offset:1920
	global_load_dwordx4 v[180:183], v[138:139], off offset:1920
	s_barrier
; template <bool trans>
; DI void gemm_core(const GTile& tl, const GTile& nx, bool has_next  , bool chain  , bool pre, u32x4 (&ra)[4], u32x4 (&rb)[4], char* smem, f32x16 (&acc)[2][4]) {
;     ...
;   const int nk = K / 64;
;   if (!pre) { G_LOAD(0); G_STORE(0); G_LOAD(1); }
;   for (int kt = 0; kt < nk; ++kt) {
;     __syncthreads();
;     G_COMPUTE(kt & 1, kt);
;   }
	s_waitcnt vmcnt(9)
	ds_write_b128 v148, v[168:171]
	s_waitcnt vmcnt(8)
	ds_write_b128 v148, v[172:175] offset:36864
	ds_read_b128 v[168:171], v150
	ds_read_b128 v[172:175], v150 offset:4608
	ds_read_b128 v[208:211], v149
	ds_read_b128 v[212:215], v149 offset:4608
	s_setprio 1
	s_waitcnt lgkmcnt(1)
	v_mfma_f32_32x32x16_bf16 v[96:111], v[168:171], v[208:211], v[96:111]
	v_mfma_f32_32x32x16_bf16 v[112:127], v[172:175], v[208:211], v[112:127]
	s_waitcnt lgkmcnt(0)
	v_mfma_f32_32x32x16_bf16 v[64:79], v[168:171], v[212:215], v[64:79]
	v_mfma_f32_32x32x16_bf16 v[80:95], v[172:175], v[212:215], v[80:95]
	ds_read_b128 v[208:211], v149 offset:9216
	ds_read_b128 v[212:215], v149 offset:13824
	s_waitcnt vmcnt(7)
	ds_write_b128 v148, v[160:163] offset:9216
	s_waitcnt vmcnt(6)
	ds_write_b128 v148, v[164:167] offset:46080
	ds_read_b128 v[160:163], v150 offset:32
	ds_read_b128 v[164:167], v150 offset:4640
	s_waitcnt lgkmcnt(5)
	v_mfma_f32_32x32x16_bf16 v[32:47], v[168:171], v[208:211], v[32:47]
	v_mfma_f32_32x32x16_bf16 v[48:63], v[172:175], v[208:211], v[48:63]
	ds_read_b128 v[208:211], v149 offset:32
	s_waitcnt lgkmcnt(5)
	v_mfma_f32_32x32x16_bf16 v[0:15], v[168:171], v[212:215], v[0:15]
	v_mfma_f32_32x32x16_bf16 v[16:31], v[172:175], v[212:215], v[16:31]
	ds_read_b128 v[212:215], v149 offset:4640
	s_setprio 0
	global_load_dwordx4 v[168:171], v[140:141], off offset:1920
	global_load_dwordx4 v[172:175], v[142:143], off offset:1920
	s_setprio 1
	s_waitcnt lgkmcnt(1)
	v_mfma_f32_32x32x16_bf16 v[96:111], v[160:163], v[208:211], v[96:111]
	v_mfma_f32_32x32x16_bf16 v[112:127], v[164:167], v[208:211], v[112:127]
	s_waitcnt lgkmcnt(0)
	v_mfma_f32_32x32x16_bf16 v[64:79], v[160:163], v[212:215], v[64:79]
	v_mfma_f32_32x32x16_bf16 v[80:95], v[164:167], v[212:215], v[80:95]
	ds_read_b128 v[208:211], v149 offset:9248
	ds_read_b128 v[212:215], v149 offset:13856
	s_waitcnt vmcnt(7)
	ds_write_b128 v148, v[184:187] offset:18432
	s_waitcnt vmcnt(6)
	ds_write_b128 v148, v[188:191] offset:55296
	ds_read_b128 v[184:187], v150 offset:64
	ds_read_b128 v[188:191], v150 offset:4672
	s_waitcnt lgkmcnt(5)
	v_mfma_f32_32x32x16_bf16 v[32:47], v[160:163], v[208:211], v[32:47]
	v_mfma_f32_32x32x16_bf16 v[48:63], v[164:167], v[208:211], v[48:63]
	ds_read_b128 v[208:211], v149 offset:64
	s_waitcnt lgkmcnt(5)
	v_mfma_f32_32x32x16_bf16 v[0:15], v[160:163], v[212:215], v[0:15]
	v_mfma_f32_32x32x16_bf16 v[16:31], v[164:167], v[212:215], v[16:31]
	ds_read_b128 v[212:215], v149 offset:4672
	s_setprio 0
	global_load_dwordx4 v[160:163], v[132:133], off offset:1920
	global_load_dwordx4 v[164:167], v[134:135], off offset:1920
	s_setprio 1
	s_waitcnt lgkmcnt(1)
	v_mfma_f32_32x32x16_bf16 v[96:111], v[184:187], v[208:211], v[96:111]
	v_mfma_f32_32x32x16_bf16 v[112:127], v[188:191], v[208:211], v[112:127]
	s_waitcnt lgkmcnt(0)
	v_mfma_f32_32x32x16_bf16 v[64:79], v[184:187], v[212:215], v[64:79]
	v_mfma_f32_32x32x16_bf16 v[80:95], v[188:191], v[212:215], v[80:95]
	ds_read_b128 v[208:211], v149 offset:9280
	ds_read_b128 v[212:215], v149 offset:13888
	s_waitcnt vmcnt(7)
	ds_write_b128 v148, v[194:197] offset:27648
	s_waitcnt vmcnt(6)
	ds_write_b128 v148, v[198:201] offset:64512
	ds_read_b128 v[194:197], v150 offset:96
	ds_read_b128 v[198:201], v150 offset:4704
	s_waitcnt lgkmcnt(5)
	v_mfma_f32_32x32x16_bf16 v[32:47], v[184:187], v[208:211], v[32:47]
	v_mfma_f32_32x32x16_bf16 v[48:63], v[188:191], v[208:211], v[48:63]
	ds_read_b128 v[208:211], v149 offset:96
	s_waitcnt lgkmcnt(5)
	v_mfma_f32_32x32x16_bf16 v[0:15], v[184:187], v[212:215], v[0:15]
	v_mfma_f32_32x32x16_bf16 v[16:31], v[188:191], v[212:215], v[16:31]
	ds_read_b128 v[212:215], v149 offset:4704
	s_setprio 0
	global_load_dwordx4 v[184:187], v[144:145], off offset:1920
	global_load_dwordx4 v[188:191], v[146:147], off offset:1920
	s_setprio 1
	s_waitcnt lgkmcnt(1)
	v_mfma_f32_32x32x16_bf16 v[96:111], v[194:197], v[208:211], v[96:111]
	v_mfma_f32_32x32x16_bf16 v[112:127], v[198:201], v[208:211], v[112:127]
	s_waitcnt lgkmcnt(0)
	v_mfma_f32_32x32x16_bf16 v[64:79], v[194:197], v[212:215], v[64:79]
	v_mfma_f32_32x32x16_bf16 v[80:95], v[198:201], v[212:215], v[80:95]
	ds_read_b128 v[208:211], v149 offset:9312
	ds_read_b128 v[212:215], v149 offset:13920
	s_waitcnt lgkmcnt(1)
	v_mfma_f32_32x32x16_bf16 v[32:47], v[194:197], v[208:211], v[32:47]
	v_mfma_f32_32x32x16_bf16 v[48:63], v[198:201], v[208:211], v[48:63]
	s_waitcnt lgkmcnt(0)
	v_mfma_f32_32x32x16_bf16 v[0:15], v[194:197], v[212:215], v[0:15]
	v_mfma_f32_32x32x16_bf16 v[16:31], v[198:201], v[212:215], v[16:31]
	s_setprio 0
	global_load_dwordx4 v[194:197], v[136:137], off offset:2048
	global_load_dwordx4 v[198:201], v[138:139], off offset:2048
	s_barrier
; template <bool trans>
; DI void gemm_core(const GTile& tl, const GTile& nx, bool has_next  , bool chain  , bool pre, u32x4 (&ra)[4], u32x4 (&rb)[4], char* smem, f32x16 (&acc)[2][4]) {
;     ...
;   const int nk = K / 64;
;   if (!pre) { G_LOAD(0); G_STORE(0); G_LOAD(1); }
;   for (int kt = 0; kt < nk; ++kt) {
;     __syncthreads();
;     G_COMPUTE(kt & 1, kt);
;   }
	s_waitcnt vmcnt(9)
	ds_write_b128 v192, v[176:179]
	s_waitcnt vmcnt(8)
	ds_write_b128 v159, v[180:183]
	ds_read_b128 v[176:179], v152 offset:36864
	ds_read_b128 v[180:183], v152 offset:41472
	ds_read_b128 v[208:211], v151
	ds_read_b128 v[212:215], v151 offset:4608
	s_setprio 1
	s_waitcnt lgkmcnt(1)
	v_mfma_f32_32x32x16_bf16 v[96:111], v[176:179], v[208:211], v[96:111]
	v_mfma_f32_32x32x16_bf16 v[112:127], v[180:183], v[208:211], v[112:127]
	s_waitcnt lgkmcnt(0)
	v_mfma_f32_32x32x16_bf16 v[64:79], v[176:179], v[212:215], v[64:79]
	v_mfma_f32_32x32x16_bf16 v[80:95], v[180:183], v[212:215], v[80:95]
	ds_read_b128 v[208:211], v151 offset:9216
	ds_read_b128 v[212:215], v151 offset:13824
	s_waitcnt vmcnt(7)
	ds_write_b128 v158, v[168:171]
	s_waitcnt vmcnt(6)
	ds_write_b128 v157, v[172:175]
	ds_read_b128 v[168:171], v152 offset:36896
	ds_read_b128 v[172:175], v152 offset:41504
	s_waitcnt lgkmcnt(5)
	v_mfma_f32_32x32x16_bf16 v[32:47], v[176:179], v[208:211], v[32:47]
	v_mfma_f32_32x32x16_bf16 v[48:63], v[180:183], v[208:211], v[48:63]
	ds_read_b128 v[208:211], v151 offset:32
	s_waitcnt lgkmcnt(5)
	v_mfma_f32_32x32x16_bf16 v[0:15], v[176:179], v[212:215], v[0:15]
	v_mfma_f32_32x32x16_bf16 v[16:31], v[180:183], v[212:215], v[16:31]
	ds_read_b128 v[212:215], v151 offset:4640
	s_setprio 0
	global_load_dwordx4 v[176:179], v[140:141], off offset:2048
	global_load_dwordx4 v[180:183], v[142:143], off offset:2048
	s_setprio 1
	s_waitcnt lgkmcnt(1)
	v_mfma_f32_32x32x16_bf16 v[96:111], v[168:171], v[208:211], v[96:111]
	v_mfma_f32_32x32x16_bf16 v[112:127], v[172:175], v[208:211], v[112:127]
	s_waitcnt lgkmcnt(0)
	v_mfma_f32_32x32x16_bf16 v[64:79], v[168:171], v[212:215], v[64:79]
	v_mfma_f32_32x32x16_bf16 v[80:95], v[172:175], v[212:215], v[80:95]
	ds_read_b128 v[208:211], v151 offset:9248
	ds_read_b128 v[212:215], v151 offset:13856
	s_waitcnt vmcnt(7)
	ds_write_b128 v154, v[160:163]
	s_waitcnt vmcnt(6)
	ds_write_b128 v153, v[164:167]
	ds_read_b128 v[160:163], v152 offset:36928
	ds_read_b128 v[164:167], v152 offset:41536
	s_waitcnt lgkmcnt(5)
	v_mfma_f32_32x32x16_bf16 v[32:47], v[168:171], v[208:211], v[32:47]
	v_mfma_f32_32x32x16_bf16 v[48:63], v[172:175], v[208:211], v[48:63]
	ds_read_b128 v[208:211], v151 offset:64
	s_waitcnt lgkmcnt(5)
	v_mfma_f32_32x32x16_bf16 v[0:15], v[168:171], v[212:215], v[0:15]
	v_mfma_f32_32x32x16_bf16 v[16:31], v[172:175], v[212:215], v[16:31]
	ds_read_b128 v[212:215], v151 offset:4672
	s_setprio 0
	global_load_dwordx4 v[168:171], v[132:133], off offset:2048
	global_load_dwordx4 v[172:175], v[134:135], off offset:2048
	s_setprio 1
	s_waitcnt lgkmcnt(1)
	v_mfma_f32_32x32x16_bf16 v[96:111], v[160:163], v[208:211], v[96:111]
	v_mfma_f32_32x32x16_bf16 v[112:127], v[164:167], v[208:211], v[112:127]
	s_waitcnt lgkmcnt(0)
	v_mfma_f32_32x32x16_bf16 v[64:79], v[160:163], v[212:215], v[64:79]
	v_mfma_f32_32x32x16_bf16 v[80:95], v[164:167], v[212:215], v[80:95]
	ds_read_b128 v[208:211], v151 offset:9280
	ds_read_b128 v[212:215], v151 offset:13888
	s_waitcnt vmcnt(7)
	ds_write_b128 v156, v[184:187]
	s_waitcnt vmcnt(6)
	ds_write_b128 v155, v[188:191]
	ds_read_b128 v[184:187], v152 offset:36960
	ds_read_b128 v[188:191], v152 offset:41568
	s_waitcnt lgkmcnt(5)
	v_mfma_f32_32x32x16_bf16 v[32:47], v[160:163], v[208:211], v[32:47]
	v_mfma_f32_32x32x16_bf16 v[48:63], v[164:167], v[208:211], v[48:63]
	ds_read_b128 v[208:211], v151 offset:96
	s_waitcnt lgkmcnt(5)
	v_mfma_f32_32x32x16_bf16 v[0:15], v[160:163], v[212:215], v[0:15]
	v_mfma_f32_32x32x16_bf16 v[16:31], v[164:167], v[212:215], v[16:31]
	ds_read_b128 v[212:215], v151 offset:4704
	s_setprio 0
	global_load_dwordx4 v[160:163], v[144:145], off offset:2048
	global_load_dwordx4 v[164:167], v[146:147], off offset:2048
	s_setprio 1
	s_waitcnt lgkmcnt(1)
	v_mfma_f32_32x32x16_bf16 v[96:111], v[184:187], v[208:211], v[96:111]
	v_mfma_f32_32x32x16_bf16 v[112:127], v[188:191], v[208:211], v[112:127]
	s_waitcnt lgkmcnt(0)
	v_mfma_f32_32x32x16_bf16 v[64:79], v[184:187], v[212:215], v[64:79]
	v_mfma_f32_32x32x16_bf16 v[80:95], v[188:191], v[212:215], v[80:95]
	ds_read_b128 v[208:211], v151 offset:9312
	ds_read_b128 v[212:215], v151 offset:13920
	s_waitcnt lgkmcnt(1)
	v_mfma_f32_32x32x16_bf16 v[32:47], v[184:187], v[208:211], v[32:47]
	v_mfma_f32_32x32x16_bf16 v[48:63], v[188:191], v[208:211], v[48:63]
	s_waitcnt lgkmcnt(0)
	v_mfma_f32_32x32x16_bf16 v[0:15], v[184:187], v[212:215], v[0:15]
	v_mfma_f32_32x32x16_bf16 v[16:31], v[188:191], v[212:215], v[16:31]
	s_setprio 0
	global_load_dwordx4 v[184:187], v[136:137], off offset:2176
	global_load_dwordx4 v[188:191], v[138:139], off offset:2176
	s_barrier
; template <bool trans>
; DI void gemm_core(const GTile& tl, const GTile& nx, bool has_next  , bool chain  , bool pre, u32x4 (&ra)[4], u32x4 (&rb)[4], char* smem, f32x16 (&acc)[2][4]) {
;     ...
;   const int nk = K / 64;
;   if (!pre) { G_LOAD(0); G_STORE(0); G_LOAD(1); }
;   for (int kt = 0; kt < nk; ++kt) {
;     __syncthreads();
;     G_COMPUTE(kt & 1, kt);
;   }
	s_waitcnt vmcnt(9)
	ds_write_b128 v148, v[194:197]
	s_waitcnt vmcnt(8)
	ds_write_b128 v148, v[198:201] offset:36864
	ds_read_b128 v[194:197], v150
	ds_read_b128 v[198:201], v150 offset:4608
	ds_read_b128 v[208:211], v149
	ds_read_b128 v[212:215], v149 offset:4608
	s_setprio 1
	s_waitcnt lgkmcnt(1)
	v_mfma_f32_32x32x16_bf16 v[96:111], v[194:197], v[208:211], v[96:111]
	v_mfma_f32_32x32x16_bf16 v[112:127], v[198:201], v[208:211], v[112:127]
	s_waitcnt lgkmcnt(0)
	v_mfma_f32_32x32x16_bf16 v[64:79], v[194:197], v[212:215], v[64:79]
	v_mfma_f32_32x32x16_bf16 v[80:95], v[198:201], v[212:215], v[80:95]
	ds_read_b128 v[208:211], v149 offset:9216
	ds_read_b128 v[212:215], v149 offset:13824
	s_waitcnt vmcnt(7)
	ds_write_b128 v148, v[176:179] offset:9216
	s_waitcnt vmcnt(6)
	ds_write_b128 v148, v[180:183] offset:46080
	ds_read_b128 v[176:179], v150 offset:32
	ds_read_b128 v[180:183], v150 offset:4640
	s_waitcnt lgkmcnt(5)
	v_mfma_f32_32x32x16_bf16 v[32:47], v[194:197], v[208:211], v[32:47]
	v_mfma_f32_32x32x16_bf16 v[48:63], v[198:201], v[208:211], v[48:63]
	ds_read_b128 v[208:211], v149 offset:32
	s_waitcnt lgkmcnt(5)
	v_mfma_f32_32x32x16_bf16 v[0:15], v[194:197], v[212:215], v[0:15]
	v_mfma_f32_32x32x16_bf16 v[16:31], v[198:201], v[212:215], v[16:31]
	ds_read_b128 v[212:215], v149 offset:4640
	s_setprio 0
	global_load_dwordx4 v[194:197], v[140:141], off offset:2176
	global_load_dwordx4 v[198:201], v[142:143], off offset:2176
	s_setprio 1
	s_waitcnt lgkmcnt(1)
	v_mfma_f32_32x32x16_bf16 v[96:111], v[176:179], v[208:211], v[96:111]
	v_mfma_f32_32x32x16_bf16 v[112:127], v[180:183], v[208:211], v[112:127]
	s_waitcnt lgkmcnt(0)
	v_mfma_f32_32x32x16_bf16 v[64:79], v[176:179], v[212:215], v[64:79]
	v_mfma_f32_32x32x16_bf16 v[80:95], v[180:183], v[212:215], v[80:95]
	ds_read_b128 v[208:211], v149 offset:9248
	ds_read_b128 v[212:215], v149 offset:13856
	s_waitcnt vmcnt(7)
	ds_write_b128 v148, v[168:171] offset:18432
	s_waitcnt vmcnt(6)
	ds_write_b128 v148, v[172:175] offset:55296
	ds_read_b128 v[168:171], v150 offset:64
	ds_read_b128 v[172:175], v150 offset:4672
	s_waitcnt lgkmcnt(5)
	v_mfma_f32_32x32x16_bf16 v[32:47], v[176:179], v[208:211], v[32:47]
	v_mfma_f32_32x32x16_bf16 v[48:63], v[180:183], v[208:211], v[48:63]
	ds_read_b128 v[208:211], v149 offset:64
	s_waitcnt lgkmcnt(5)
	v_mfma_f32_32x32x16_bf16 v[0:15], v[176:179], v[212:215], v[0:15]
	v_mfma_f32_32x32x16_bf16 v[16:31], v[180:183], v[212:215], v[16:31]
	ds_read_b128 v[212:215], v149 offset:4672
	s_setprio 0
	global_load_dwordx4 v[176:179], v[132:133], off offset:2176
	global_load_dwordx4 v[180:183], v[134:135], off offset:2176
	s_setprio 1
	s_waitcnt lgkmcnt(1)
	v_mfma_f32_32x32x16_bf16 v[96:111], v[168:171], v[208:211], v[96:111]
	v_mfma_f32_32x32x16_bf16 v[112:127], v[172:175], v[208:211], v[112:127]
	s_waitcnt lgkmcnt(0)
	v_mfma_f32_32x32x16_bf16 v[64:79], v[168:171], v[212:215], v[64:79]
	v_mfma_f32_32x32x16_bf16 v[80:95], v[172:175], v[212:215], v[80:95]
	ds_read_b128 v[208:211], v149 offset:9280
	ds_read_b128 v[212:215], v149 offset:13888
	s_waitcnt vmcnt(7)
	ds_write_b128 v148, v[160:163] offset:27648
	s_waitcnt vmcnt(6)
	ds_write_b128 v148, v[164:167] offset:64512
	ds_read_b128 v[160:163], v150 offset:96
	ds_read_b128 v[164:167], v150 offset:4704
	s_waitcnt lgkmcnt(5)
	v_mfma_f32_32x32x16_bf16 v[32:47], v[168:171], v[208:211], v[32:47]
	v_mfma_f32_32x32x16_bf16 v[48:63], v[172:175], v[208:211], v[48:63]
	ds_read_b128 v[208:211], v149 offset:96
	s_waitcnt lgkmcnt(5)
	v_mfma_f32_32x32x16_bf16 v[0:15], v[168:171], v[212:215], v[0:15]
	v_mfma_f32_32x32x16_bf16 v[16:31], v[172:175], v[212:215], v[16:31]
	ds_read_b128 v[212:215], v149 offset:4704
	s_setprio 0
	global_load_dwordx4 v[168:171], v[144:145], off offset:2176
	global_load_dwordx4 v[172:175], v[146:147], off offset:2176
	s_setprio 1
	s_waitcnt lgkmcnt(1)
	v_mfma_f32_32x32x16_bf16 v[96:111], v[160:163], v[208:211], v[96:111]
	v_mfma_f32_32x32x16_bf16 v[112:127], v[164:167], v[208:211], v[112:127]
	s_waitcnt lgkmcnt(0)
	v_mfma_f32_32x32x16_bf16 v[64:79], v[160:163], v[212:215], v[64:79]
	v_mfma_f32_32x32x16_bf16 v[80:95], v[164:167], v[212:215], v[80:95]
	ds_read_b128 v[208:211], v149 offset:9312
	ds_read_b128 v[212:215], v149 offset:13920
	s_waitcnt lgkmcnt(1)
	v_mfma_f32_32x32x16_bf16 v[32:47], v[160:163], v[208:211], v[32:47]
	v_mfma_f32_32x32x16_bf16 v[48:63], v[164:167], v[208:211], v[48:63]
	s_waitcnt lgkmcnt(0)
	v_mfma_f32_32x32x16_bf16 v[0:15], v[160:163], v[212:215], v[0:15]
	v_mfma_f32_32x32x16_bf16 v[16:31], v[164:167], v[212:215], v[16:31]
	s_setprio 0
	global_load_dwordx4 v[160:163], v[136:137], off offset:2304
	global_load_dwordx4 v[164:167], v[138:139], off offset:2304
	s_barrier
; template <bool trans>
; DI void gemm_core(const GTile& tl, const GTile& nx, bool has_next  , bool chain  , bool pre, u32x4 (&ra)[4], u32x4 (&rb)[4], char* smem, f32x16 (&acc)[2][4]) {
;     ...
;   const int nk = K / 64;
;   if (!pre) { G_LOAD(0); G_STORE(0); G_LOAD(1); }
;   for (int kt = 0; kt < nk; ++kt) {
;     __syncthreads();
;     G_COMPUTE(kt & 1, kt);
	s_waitcnt vmcnt(9)
	ds_write_b128 v192, v[184:187]
	s_waitcnt vmcnt(8)
	ds_write_b128 v159, v[188:191]
	ds_read_b128 v[184:187], v152 offset:36864
	ds_read_b128 v[188:191], v152 offset:41472
	ds_read_b128 v[208:211], v151
	ds_read_b128 v[212:215], v151 offset:4608
	s_setprio 1
	s_waitcnt lgkmcnt(1)
	v_mfma_f32_32x32x16_bf16 v[96:111], v[184:187], v[208:211], v[96:111]
	v_mfma_f32_32x32x16_bf16 v[112:127], v[188:191], v[208:211], v[112:127]
	s_waitcnt lgkmcnt(0)
	v_mfma_f32_32x32x16_bf16 v[64:79], v[184:187], v[212:215], v[64:79]
	v_mfma_f32_32x32x16_bf16 v[80:95], v[188:191], v[212:215], v[80:95]
	ds_read_b128 v[208:211], v151 offset:9216
	ds_read_b128 v[212:215], v151 offset:13824
	s_waitcnt vmcnt(7)
	ds_write_b128 v158, v[194:197]
	s_waitcnt vmcnt(6)
	ds_write_b128 v157, v[198:201]
	ds_read_b128 v[194:197], v152 offset:36896
	ds_read_b128 v[198:201], v152 offset:41504
	s_waitcnt lgkmcnt(5)
	v_mfma_f32_32x32x16_bf16 v[32:47], v[184:187], v[208:211], v[32:47]
	v_mfma_f32_32x32x16_bf16 v[48:63], v[188:191], v[208:211], v[48:63]
	ds_read_b128 v[208:211], v151 offset:32
	s_waitcnt lgkmcnt(5)
	v_mfma_f32_32x32x16_bf16 v[0:15], v[184:187], v[212:215], v[0:15]
	v_mfma_f32_32x32x16_bf16 v[16:31], v[188:191], v[212:215], v[16:31]
	ds_read_b128 v[212:215], v151 offset:4640
	s_setprio 0
	global_load_dwordx4 v[184:187], v[140:141], off offset:2304
	global_load_dwordx4 v[188:191], v[142:143], off offset:2304
	s_setprio 1
	s_waitcnt lgkmcnt(1)
	v_mfma_f32_32x32x16_bf16 v[96:111], v[194:197], v[208:211], v[96:111]
	v_mfma_f32_32x32x16_bf16 v[112:127], v[198:201], v[208:211], v[112:127]
	s_waitcnt lgkmcnt(0)
	v_mfma_f32_32x32x16_bf16 v[64:79], v[194:197], v[212:215], v[64:79]
	v_mfma_f32_32x32x16_bf16 v[80:95], v[198:201], v[212:215], v[80:95]
	ds_read_b128 v[208:211], v151 offset:9248
	ds_read_b128 v[212:215], v151 offset:13856
	s_waitcnt vmcnt(7)
	ds_write_b128 v154, v[176:179]
	s_waitcnt vmcnt(6)
	ds_write_b128 v153, v[180:183]
	ds_read_b128 v[176:179], v152 offset:36928
	ds_read_b128 v[180:183], v152 offset:41536
	s_waitcnt lgkmcnt(5)
	v_mfma_f32_32x32x16_bf16 v[32:47], v[194:197], v[208:211], v[32:47]
	v_mfma_f32_32x32x16_bf16 v[48:63], v[198:201], v[208:211], v[48:63]
	ds_read_b128 v[208:211], v151 offset:64
	s_waitcnt lgkmcnt(5)
	v_mfma_f32_32x32x16_bf16 v[0:15], v[194:197], v[212:215], v[0:15]
	v_mfma_f32_32x32x16_bf16 v[16:31], v[198:201], v[212:215], v[16:31]
	ds_read_b128 v[212:215], v151 offset:4672
	s_setprio 0
	global_load_dwordx4 v[194:197], v[132:133], off offset:2304
	global_load_dwordx4 v[198:201], v[134:135], off offset:2304
	s_setprio 1
	s_waitcnt lgkmcnt(1)
	v_mfma_f32_32x32x16_bf16 v[96:111], v[176:179], v[208:211], v[96:111]
	v_mfma_f32_32x32x16_bf16 v[112:127], v[180:183], v[208:211], v[112:127]
	s_waitcnt lgkmcnt(0)
	v_mfma_f32_32x32x16_bf16 v[64:79], v[176:179], v[212:215], v[64:79]
	v_mfma_f32_32x32x16_bf16 v[80:95], v[180:183], v[212:215], v[80:95]
	ds_read_b128 v[208:211], v151 offset:9280
	ds_read_b128 v[212:215], v151 offset:13888
	s_waitcnt vmcnt(7)
	ds_write_b128 v156, v[168:171]
	s_waitcnt vmcnt(6)
	ds_write_b128 v155, v[172:175]
	ds_read_b128 v[168:171], v152 offset:36960
	ds_read_b128 v[172:175], v152 offset:41568
	s_waitcnt lgkmcnt(5)
	v_mfma_f32_32x32x16_bf16 v[32:47], v[176:179], v[208:211], v[32:47]
	v_mfma_f32_32x32x16_bf16 v[48:63], v[180:183], v[208:211], v[48:63]
	ds_read_b128 v[208:211], v151 offset:96
	s_waitcnt lgkmcnt(5)
	v_mfma_f32_32x32x16_bf16 v[0:15], v[176:179], v[212:215], v[0:15]
	v_mfma_f32_32x32x16_bf16 v[16:31], v[180:183], v[212:215], v[16:31]
	ds_read_b128 v[212:215], v151 offset:4704
	s_setprio 0
	global_load_dwordx4 v[176:179], v[144:145], off offset:2304
	global_load_dwordx4 v[180:183], v[146:147], off offset:2304
	s_setprio 1
	s_waitcnt lgkmcnt(1)
	v_mfma_f32_32x32x16_bf16 v[96:111], v[168:171], v[208:211], v[96:111]
	v_mfma_f32_32x32x16_bf16 v[112:127], v[172:175], v[208:211], v[112:127]
	s_waitcnt lgkmcnt(0)
	v_mfma_f32_32x32x16_bf16 v[64:79], v[168:171], v[212:215], v[64:79]
	v_mfma_f32_32x32x16_bf16 v[80:95], v[172:175], v[212:215], v[80:95]
	ds_read_b128 v[208:211], v151 offset:9312
	ds_read_b128 v[212:215], v151 offset:13920
	s_waitcnt lgkmcnt(1)
	v_mfma_f32_32x32x16_bf16 v[32:47], v[168:171], v[208:211], v[32:47]
	v_mfma_f32_32x32x16_bf16 v[48:63], v[172:175], v[208:211], v[48:63]
	s_waitcnt lgkmcnt(0)
	v_mfma_f32_32x32x16_bf16 v[0:15], v[168:171], v[212:215], v[0:15]
	v_mfma_f32_32x32x16_bf16 v[16:31], v[172:175], v[212:215], v[16:31]
	s_setprio 0
	global_load_dwordx4 v[168:171], v[136:137], off offset:2432
	global_load_dwordx4 v[172:175], v[138:139], off offset:2432
	s_barrier
; template <bool trans>
; DI void gemm_core(const GTile& tl, const GTile& nx, bool has_next  , bool chain  , bool pre, u32x4 (&ra)[4], u32x4 (&rb)[4], char* smem, f32x16 (&acc)[2][4]) {
;     ...
;   const int nk = K / 64;
;   if (!pre) { G_LOAD(0); G_STORE(0); G_LOAD(1); }
;   for (int kt = 0; kt < nk; ++kt) {
;     __syncthreads();
;     G_COMPUTE(kt & 1, kt);
	s_waitcnt vmcnt(9)
	ds_write_b128 v148, v[160:163]
	s_waitcnt vmcnt(8)
	ds_write_b128 v148, v[164:167] offset:36864
	ds_read_b128 v[160:163], v150
	ds_read_b128 v[164:167], v150 offset:4608
	ds_read_b128 v[208:211], v149
	ds_read_b128 v[212:215], v149 offset:4608
	s_setprio 1
	s_waitcnt lgkmcnt(1)
	v_mfma_f32_32x32x16_bf16 v[96:111], v[160:163], v[208:211], v[96:111]
	v_mfma_f32_32x32x16_bf16 v[112:127], v[164:167], v[208:211], v[112:127]
	s_waitcnt lgkmcnt(0)
	v_mfma_f32_32x32x16_bf16 v[64:79], v[160:163], v[212:215], v[64:79]
	v_mfma_f32_32x32x16_bf16 v[80:95], v[164:167], v[212:215], v[80:95]
	ds_read_b128 v[208:211], v149 offset:9216
	ds_read_b128 v[212:215], v149 offset:13824
	s_waitcnt vmcnt(7)
	ds_write_b128 v148, v[184:187] offset:9216
	s_waitcnt vmcnt(6)
	ds_write_b128 v148, v[188:191] offset:46080
	ds_read_b128 v[184:187], v150 offset:32
	ds_read_b128 v[188:191], v150 offset:4640
	s_waitcnt lgkmcnt(5)
	v_mfma_f32_32x32x16_bf16 v[32:47], v[160:163], v[208:211], v[32:47]
	v_mfma_f32_32x32x16_bf16 v[48:63], v[164:167], v[208:211], v[48:63]
	ds_read_b128 v[208:211], v149 offset:32
	s_waitcnt lgkmcnt(5)
	v_mfma_f32_32x32x16_bf16 v[0:15], v[160:163], v[212:215], v[0:15]
	v_mfma_f32_32x32x16_bf16 v[16:31], v[164:167], v[212:215], v[16:31]
	ds_read_b128 v[212:215], v149 offset:4640
	s_setprio 0
	global_load_dwordx4 v[160:163], v[140:141], off offset:2432
	global_load_dwordx4 v[164:167], v[142:143], off offset:2432
	s_setprio 1
	s_waitcnt lgkmcnt(1)
	v_mfma_f32_32x32x16_bf16 v[96:111], v[184:187], v[208:211], v[96:111]
	v_mfma_f32_32x32x16_bf16 v[112:127], v[188:191], v[208:211], v[112:127]
	s_waitcnt lgkmcnt(0)
	v_mfma_f32_32x32x16_bf16 v[64:79], v[184:187], v[212:215], v[64:79]
	v_mfma_f32_32x32x16_bf16 v[80:95], v[188:191], v[212:215], v[80:95]
	ds_read_b128 v[208:211], v149 offset:9248
	ds_read_b128 v[212:215], v149 offset:13856
	s_waitcnt vmcnt(7)
	ds_write_b128 v148, v[194:197] offset:18432
	s_waitcnt vmcnt(6)
	ds_write_b128 v148, v[198:201] offset:55296
	ds_read_b128 v[194:197], v150 offset:64
	ds_read_b128 v[198:201], v150 offset:4672
	s_waitcnt lgkmcnt(5)
	v_mfma_f32_32x32x16_bf16 v[32:47], v[184:187], v[208:211], v[32:47]
	v_mfma_f32_32x32x16_bf16 v[48:63], v[188:191], v[208:211], v[48:63]
	ds_read_b128 v[208:211], v149 offset:64
	s_waitcnt lgkmcnt(5)
	v_mfma_f32_32x32x16_bf16 v[0:15], v[184:187], v[212:215], v[0:15]
	v_mfma_f32_32x32x16_bf16 v[16:31], v[188:191], v[212:215], v[16:31]
	ds_read_b128 v[212:215], v149 offset:4672
	s_setprio 0
	global_load_dwordx4 v[184:187], v[132:133], off offset:2432
	global_load_dwordx4 v[188:191], v[134:135], off offset:2432
	s_setprio 1
	s_waitcnt lgkmcnt(1)
	v_mfma_f32_32x32x16_bf16 v[96:111], v[194:197], v[208:211], v[96:111]
	v_mfma_f32_32x32x16_bf16 v[112:127], v[198:201], v[208:211], v[112:127]
	s_waitcnt lgkmcnt(0)
	v_mfma_f32_32x32x16_bf16 v[64:79], v[194:197], v[212:215], v[64:79]
	v_mfma_f32_32x32x16_bf16 v[80:95], v[198:201], v[212:215], v[80:95]
	ds_read_b128 v[208:211], v149 offset:9280
	ds_read_b128 v[212:215], v149 offset:13888
	s_waitcnt vmcnt(7)
	ds_write_b128 v148, v[176:179] offset:27648
	s_waitcnt vmcnt(6)
	ds_write_b128 v148, v[180:183] offset:64512
	ds_read_b128 v[176:179], v150 offset:96
	ds_read_b128 v[180:183], v150 offset:4704
	s_waitcnt lgkmcnt(5)
	v_mfma_f32_32x32x16_bf16 v[32:47], v[194:197], v[208:211], v[32:47]
	v_mfma_f32_32x32x16_bf16 v[48:63], v[198:201], v[208:211], v[48:63]
	ds_read_b128 v[208:211], v149 offset:96
	s_waitcnt lgkmcnt(5)
	v_mfma_f32_32x32x16_bf16 v[0:15], v[194:197], v[212:215], v[0:15]
	v_mfma_f32_32x32x16_bf16 v[16:31], v[198:201], v[212:215], v[16:31]
	ds_read_b128 v[212:215], v149 offset:4704
	s_setprio 0
	global_load_dwordx4 v[194:197], v[144:145], off offset:2432
	global_load_dwordx4 v[198:201], v[146:147], off offset:2432
	s_setprio 1
	s_waitcnt lgkmcnt(1)
	v_mfma_f32_32x32x16_bf16 v[96:111], v[176:179], v[208:211], v[96:111]
	v_mfma_f32_32x32x16_bf16 v[112:127], v[180:183], v[208:211], v[112:127]
	s_waitcnt lgkmcnt(0)
	v_mfma_f32_32x32x16_bf16 v[64:79], v[176:179], v[212:215], v[64:79]
	v_mfma_f32_32x32x16_bf16 v[80:95], v[180:183], v[212:215], v[80:95]
	ds_read_b128 v[208:211], v149 offset:9312
	ds_read_b128 v[212:215], v149 offset:13920
	s_waitcnt lgkmcnt(1)
	v_mfma_f32_32x32x16_bf16 v[32:47], v[176:179], v[208:211], v[32:47]
	v_mfma_f32_32x32x16_bf16 v[48:63], v[180:183], v[208:211], v[48:63]
	s_waitcnt lgkmcnt(0)
	v_mfma_f32_32x32x16_bf16 v[0:15], v[176:179], v[212:215], v[0:15]
	v_mfma_f32_32x32x16_bf16 v[16:31], v[180:183], v[212:215], v[16:31]
	s_setprio 0
	global_load_dwordx4 v[176:179], v[136:137], off offset:2560
	global_load_dwordx4 v[180:183], v[138:139], off offset:2560
	s_barrier
; template <bool trans>
; DI void gemm_core(const GTile& tl, const GTile& nx, bool has_next  , bool chain  , bool pre, u32x4 (&ra)[4], u32x4 (&rb)[4], char* smem, f32x16 (&acc)[2][4]) {
;     ...
;   const int nk = K / 64;
;   if (!pre) { G_LOAD(0); G_STORE(0); G_LOAD(1); }
;   for (int kt = 0; kt < nk; ++kt) {
;     __syncthreads();
;     G_COMPUTE(kt & 1, kt);
	s_waitcnt vmcnt(9)
	ds_write_b128 v192, v[168:171]
	s_waitcnt vmcnt(8)
	ds_write_b128 v159, v[172:175]
	ds_read_b128 v[168:171], v152 offset:36864
	ds_read_b128 v[172:175], v152 offset:41472
	ds_read_b128 v[208:211], v151
	ds_read_b128 v[212:215], v151 offset:4608
	s_setprio 1
	s_waitcnt lgkmcnt(1)
	v_mfma_f32_32x32x16_bf16 v[96:111], v[168:171], v[208:211], v[96:111]
	v_mfma_f32_32x32x16_bf16 v[112:127], v[172:175], v[208:211], v[112:127]
	s_waitcnt lgkmcnt(0)
	v_mfma_f32_32x32x16_bf16 v[64:79], v[168:171], v[212:215], v[64:79]
	v_mfma_f32_32x32x16_bf16 v[80:95], v[172:175], v[212:215], v[80:95]
	ds_read_b128 v[208:211], v151 offset:9216
	ds_read_b128 v[212:215], v151 offset:13824
	s_waitcnt vmcnt(7)
	ds_write_b128 v158, v[160:163]
	s_waitcnt vmcnt(6)
	ds_write_b128 v157, v[164:167]
	ds_read_b128 v[160:163], v152 offset:36896
	ds_read_b128 v[164:167], v152 offset:41504
	s_waitcnt lgkmcnt(5)
	v_mfma_f32_32x32x16_bf16 v[32:47], v[168:171], v[208:211], v[32:47]
	v_mfma_f32_32x32x16_bf16 v[48:63], v[172:175], v[208:211], v[48:63]
	ds_read_b128 v[208:211], v151 offset:32
	s_waitcnt lgkmcnt(5)
	v_mfma_f32_32x32x16_bf16 v[0:15], v[168:171], v[212:215], v[0:15]
	v_mfma_f32_32x32x16_bf16 v[16:31], v[172:175], v[212:215], v[16:31]
	ds_read_b128 v[212:215], v151 offset:4640
	s_setprio 0
	global_load_dwordx4 v[168:171], v[140:141], off offset:2560
	global_load_dwordx4 v[172:175], v[142:143], off offset:2560
	s_setprio 1
	s_waitcnt lgkmcnt(1)
	v_mfma_f32_32x32x16_bf16 v[96:111], v[160:163], v[208:211], v[96:111]
	v_mfma_f32_32x32x16_bf16 v[112:127], v[164:167], v[208:211], v[112:127]
	s_waitcnt lgkmcnt(0)
	v_mfma_f32_32x32x16_bf16 v[64:79], v[160:163], v[212:215], v[64:79]
	v_mfma_f32_32x32x16_bf16 v[80:95], v[164:167], v[212:215], v[80:95]
	ds_read_b128 v[208:211], v151 offset:9248
	ds_read_b128 v[212:215], v151 offset:13856
	s_waitcnt vmcnt(7)
	ds_write_b128 v154, v[184:187]
	s_waitcnt vmcnt(6)
	ds_write_b128 v153, v[188:191]
	ds_read_b128 v[184:187], v152 offset:36928
	ds_read_b128 v[188:191], v152 offset:41536
	s_waitcnt lgkmcnt(5)
	v_mfma_f32_32x32x16_bf16 v[32:47], v[160:163], v[208:211], v[32:47]
	v_mfma_f32_32x32x16_bf16 v[48:63], v[164:167], v[208:211], v[48:63]
	ds_read_b128 v[208:211], v151 offset:64
	s_waitcnt lgkmcnt(5)
	v_mfma_f32_32x32x16_bf16 v[0:15], v[160:163], v[212:215], v[0:15]
	v_mfma_f32_32x32x16_bf16 v[16:31], v[164:167], v[212:215], v[16:31]
	ds_read_b128 v[212:215], v151 offset:4672
	s_setprio 0
	global_load_dwordx4 v[160:163], v[132:133], off offset:2560
	global_load_dwordx4 v[164:167], v[134:135], off offset:2560
	s_setprio 1
	s_waitcnt lgkmcnt(1)
	v_mfma_f32_32x32x16_bf16 v[96:111], v[184:187], v[208:211], v[96:111]
	v_mfma_f32_32x32x16_bf16 v[112:127], v[188:191], v[208:211], v[112:127]
	s_waitcnt lgkmcnt(0)
	v_mfma_f32_32x32x16_bf16 v[64:79], v[184:187], v[212:215], v[64:79]
	v_mfma_f32_32x32x16_bf16 v[80:95], v[188:191], v[212:215], v[80:95]
	ds_read_b128 v[208:211], v151 offset:9280
	ds_read_b128 v[212:215], v151 offset:13888
	s_waitcnt vmcnt(7)
	ds_write_b128 v156, v[194:197]
	s_waitcnt vmcnt(6)
	ds_write_b128 v155, v[198:201]
	ds_read_b128 v[194:197], v152 offset:36960
	ds_read_b128 v[198:201], v152 offset:41568
	s_waitcnt lgkmcnt(5)
	v_mfma_f32_32x32x16_bf16 v[32:47], v[184:187], v[208:211], v[32:47]
	v_mfma_f32_32x32x16_bf16 v[48:63], v[188:191], v[208:211], v[48:63]
	ds_read_b128 v[208:211], v151 offset:96
	s_waitcnt lgkmcnt(5)
	v_mfma_f32_32x32x16_bf16 v[0:15], v[184:187], v[212:215], v[0:15]
	v_mfma_f32_32x32x16_bf16 v[16:31], v[188:191], v[212:215], v[16:31]
	ds_read_b128 v[212:215], v151 offset:4704
	s_setprio 0
	global_load_dwordx4 v[184:187], v[144:145], off offset:2560
	global_load_dwordx4 v[188:191], v[146:147], off offset:2560
	s_setprio 1
	s_waitcnt lgkmcnt(1)
	v_mfma_f32_32x32x16_bf16 v[96:111], v[194:197], v[208:211], v[96:111]
	v_mfma_f32_32x32x16_bf16 v[112:127], v[198:201], v[208:211], v[112:127]
	s_waitcnt lgkmcnt(0)
	v_mfma_f32_32x32x16_bf16 v[64:79], v[194:197], v[212:215], v[64:79]
	v_mfma_f32_32x32x16_bf16 v[80:95], v[198:201], v[212:215], v[80:95]
	ds_read_b128 v[208:211], v151 offset:9312
	ds_read_b128 v[212:215], v151 offset:13920
	s_waitcnt lgkmcnt(1)
	v_mfma_f32_32x32x16_bf16 v[32:47], v[194:197], v[208:211], v[32:47]
	v_mfma_f32_32x32x16_bf16 v[48:63], v[198:201], v[208:211], v[48:63]
	s_waitcnt lgkmcnt(0)
	v_mfma_f32_32x32x16_bf16 v[0:15], v[194:197], v[212:215], v[0:15]
	v_mfma_f32_32x32x16_bf16 v[16:31], v[198:201], v[212:215], v[16:31]
	s_setprio 0
	global_load_dwordx4 v[194:197], v[136:137], off offset:2688
	global_load_dwordx4 v[198:201], v[138:139], off offset:2688
	s_barrier
; template <bool trans>
; DI void gemm_core(const GTile& tl, const GTile& nx, bool has_next  , bool chain  , bool pre, u32x4 (&ra)[4], u32x4 (&rb)[4], char* smem, f32x16 (&acc)[2][4]) {
;     ...
;   const int nk = K / 64;
;   if (!pre) { G_LOAD(0); G_STORE(0); G_LOAD(1); }
;   for (int kt = 0; kt < nk; ++kt) {
;     __syncthreads();
;     G_COMPUTE(kt & 1, kt);
	s_waitcnt vmcnt(9)
	ds_write_b128 v148, v[176:179]
	s_waitcnt vmcnt(8)
	ds_write_b128 v148, v[180:183] offset:36864
	ds_read_b128 v[176:179], v150
	ds_read_b128 v[180:183], v150 offset:4608
	ds_read_b128 v[208:211], v149
	ds_read_b128 v[212:215], v149 offset:4608
	s_setprio 1
	s_waitcnt lgkmcnt(1)
	v_mfma_f32_32x32x16_bf16 v[96:111], v[176:179], v[208:211], v[96:111]
	v_mfma_f32_32x32x16_bf16 v[112:127], v[180:183], v[208:211], v[112:127]
	s_waitcnt lgkmcnt(0)
	v_mfma_f32_32x32x16_bf16 v[64:79], v[176:179], v[212:215], v[64:79]
	v_mfma_f32_32x32x16_bf16 v[80:95], v[180:183], v[212:215], v[80:95]
	ds_read_b128 v[208:211], v149 offset:9216
	ds_read_b128 v[212:215], v149 offset:13824
	s_waitcnt vmcnt(7)
	ds_write_b128 v148, v[168:171] offset:9216
	s_waitcnt vmcnt(6)
	ds_write_b128 v148, v[172:175] offset:46080
	ds_read_b128 v[168:171], v150 offset:32
	ds_read_b128 v[172:175], v150 offset:4640
	s_waitcnt lgkmcnt(5)
	v_mfma_f32_32x32x16_bf16 v[32:47], v[176:179], v[208:211], v[32:47]
	v_mfma_f32_32x32x16_bf16 v[48:63], v[180:183], v[208:211], v[48:63]
	ds_read_b128 v[208:211], v149 offset:32
	s_waitcnt lgkmcnt(5)
	v_mfma_f32_32x32x16_bf16 v[0:15], v[176:179], v[212:215], v[0:15]
	v_mfma_f32_32x32x16_bf16 v[16:31], v[180:183], v[212:215], v[16:31]
	ds_read_b128 v[212:215], v149 offset:4640
	s_setprio 0
	global_load_dwordx4 v[176:179], v[140:141], off offset:2688
	global_load_dwordx4 v[180:183], v[142:143], off offset:2688
	s_setprio 1
	s_waitcnt lgkmcnt(1)
	v_mfma_f32_32x32x16_bf16 v[96:111], v[168:171], v[208:211], v[96:111]
	v_mfma_f32_32x32x16_bf16 v[112:127], v[172:175], v[208:211], v[112:127]
	s_waitcnt lgkmcnt(0)
	v_mfma_f32_32x32x16_bf16 v[64:79], v[168:171], v[212:215], v[64:79]
	v_mfma_f32_32x32x16_bf16 v[80:95], v[172:175], v[212:215], v[80:95]
	ds_read_b128 v[208:211], v149 offset:9248
	ds_read_b128 v[212:215], v149 offset:13856
	s_waitcnt vmcnt(7)
	ds_write_b128 v148, v[160:163] offset:18432
	s_waitcnt vmcnt(6)
	ds_write_b128 v148, v[164:167] offset:55296
	ds_read_b128 v[160:163], v150 offset:64
	ds_read_b128 v[164:167], v150 offset:4672
	s_waitcnt lgkmcnt(5)
	v_mfma_f32_32x32x16_bf16 v[32:47], v[168:171], v[208:211], v[32:47]
	v_mfma_f32_32x32x16_bf16 v[48:63], v[172:175], v[208:211], v[48:63]
	ds_read_b128 v[208:211], v149 offset:64
	s_waitcnt lgkmcnt(5)
	v_mfma_f32_32x32x16_bf16 v[0:15], v[168:171], v[212:215], v[0:15]
	v_mfma_f32_32x32x16_bf16 v[16:31], v[172:175], v[212:215], v[16:31]
	ds_read_b128 v[212:215], v149 offset:4672
	s_setprio 0
	global_load_dwordx4 v[168:171], v[132:133], off offset:2688
	global_load_dwordx4 v[172:175], v[134:135], off offset:2688
	s_setprio 1
	s_waitcnt lgkmcnt(1)
	v_mfma_f32_32x32x16_bf16 v[96:111], v[160:163], v[208:211], v[96:111]
	v_mfma_f32_32x32x16_bf16 v[112:127], v[164:167], v[208:211], v[112:127]
	s_waitcnt lgkmcnt(0)
	v_mfma_f32_32x32x16_bf16 v[64:79], v[160:163], v[212:215], v[64:79]
	v_mfma_f32_32x32x16_bf16 v[80:95], v[164:167], v[212:215], v[80:95]
	ds_read_b128 v[208:211], v149 offset:9280
	ds_read_b128 v[212:215], v149 offset:13888
	s_waitcnt vmcnt(7)
	ds_write_b128 v148, v[184:187] offset:27648
	s_waitcnt vmcnt(6)
	ds_write_b128 v148, v[188:191] offset:64512
	ds_read_b128 v[184:187], v150 offset:96
	ds_read_b128 v[188:191], v150 offset:4704
	s_waitcnt lgkmcnt(5)
	v_mfma_f32_32x32x16_bf16 v[32:47], v[160:163], v[208:211], v[32:47]
	v_mfma_f32_32x32x16_bf16 v[48:63], v[164:167], v[208:211], v[48:63]
	ds_read_b128 v[208:211], v149 offset:96
	s_waitcnt lgkmcnt(5)
	v_mfma_f32_32x32x16_bf16 v[0:15], v[160:163], v[212:215], v[0:15]
	v_mfma_f32_32x32x16_bf16 v[16:31], v[164:167], v[212:215], v[16:31]
	ds_read_b128 v[212:215], v149 offset:4704
	s_setprio 0
	global_load_dwordx4 v[160:163], v[144:145], off offset:2688
	global_load_dwordx4 v[164:167], v[146:147], off offset:2688
	s_setprio 1
	s_waitcnt lgkmcnt(1)
	v_mfma_f32_32x32x16_bf16 v[96:111], v[184:187], v[208:211], v[96:111]
	v_mfma_f32_32x32x16_bf16 v[112:127], v[188:191], v[208:211], v[112:127]
	s_waitcnt lgkmcnt(0)
	v_mfma_f32_32x32x16_bf16 v[64:79], v[184:187], v[212:215], v[64:79]
	v_mfma_f32_32x32x16_bf16 v[80:95], v[188:191], v[212:215], v[80:95]
	ds_read_b128 v[208:211], v149 offset:9312
	ds_read_b128 v[212:215], v149 offset:13920
	s_waitcnt lgkmcnt(1)
	v_mfma_f32_32x32x16_bf16 v[32:47], v[184:187], v[208:211], v[32:47]
	v_mfma_f32_32x32x16_bf16 v[48:63], v[188:191], v[208:211], v[48:63]
	s_waitcnt lgkmcnt(0)
	v_mfma_f32_32x32x16_bf16 v[0:15], v[184:187], v[212:215], v[0:15]
	v_mfma_f32_32x32x16_bf16 v[16:31], v[188:191], v[212:215], v[16:31]
	s_setprio 0
	global_load_dwordx4 v[184:187], v[136:137], off offset:2816
	global_load_dwordx4 v[188:191], v[138:139], off offset:2816
	s_barrier
; template <bool trans>
; DI void gemm_core(const GTile& tl, const GTile& nx, bool has_next  , bool chain  , bool pre, u32x4 (&ra)[4], u32x4 (&rb)[4], char* smem, f32x16 (&acc)[2][4]) {
;     ...
;   const int nk = K / 64;
;   if (!pre) { G_LOAD(0); G_STORE(0); G_LOAD(1); }
;   for (int kt = 0; kt < nk; ++kt) {
;     __syncthreads();
;     G_COMPUTE(kt & 1, kt);
	s_waitcnt vmcnt(9)
	ds_write_b128 v192, v[194:197]
	s_waitcnt vmcnt(8)
	ds_write_b128 v159, v[198:201]
	ds_read_b128 v[194:197], v152 offset:36864
	ds_read_b128 v[198:201], v152 offset:41472
	ds_read_b128 v[208:211], v151
	ds_read_b128 v[212:215], v151 offset:4608
	s_setprio 1
	s_waitcnt lgkmcnt(1)
	v_mfma_f32_32x32x16_bf16 v[96:111], v[194:197], v[208:211], v[96:111]
	v_mfma_f32_32x32x16_bf16 v[112:127], v[198:201], v[208:211], v[112:127]
	s_waitcnt lgkmcnt(0)
	v_mfma_f32_32x32x16_bf16 v[64:79], v[194:197], v[212:215], v[64:79]
	v_mfma_f32_32x32x16_bf16 v[80:95], v[198:201], v[212:215], v[80:95]
	ds_read_b128 v[208:211], v151 offset:9216
	ds_read_b128 v[212:215], v151 offset:13824
	s_waitcnt vmcnt(7)
	ds_write_b128 v158, v[176:179]
	s_waitcnt vmcnt(6)
	ds_write_b128 v157, v[180:183]
	ds_read_b128 v[176:179], v152 offset:36896
	ds_read_b128 v[180:183], v152 offset:41504
	s_waitcnt lgkmcnt(5)
	v_mfma_f32_32x32x16_bf16 v[32:47], v[194:197], v[208:211], v[32:47]
	v_mfma_f32_32x32x16_bf16 v[48:63], v[198:201], v[208:211], v[48:63]
	ds_read_b128 v[208:211], v151 offset:32
	s_waitcnt lgkmcnt(5)
	v_mfma_f32_32x32x16_bf16 v[0:15], v[194:197], v[212:215], v[0:15]
	v_mfma_f32_32x32x16_bf16 v[16:31], v[198:201], v[212:215], v[16:31]
	ds_read_b128 v[212:215], v151 offset:4640
	s_setprio 0
	global_load_dwordx4 v[194:197], v[140:141], off offset:2816
	global_load_dwordx4 v[198:201], v[142:143], off offset:2816
	s_setprio 1
	s_waitcnt lgkmcnt(1)
	v_mfma_f32_32x32x16_bf16 v[96:111], v[176:179], v[208:211], v[96:111]
	v_mfma_f32_32x32x16_bf16 v[112:127], v[180:183], v[208:211], v[112:127]
	s_waitcnt lgkmcnt(0)
	v_mfma_f32_32x32x16_bf16 v[64:79], v[176:179], v[212:215], v[64:79]
	v_mfma_f32_32x32x16_bf16 v[80:95], v[180:183], v[212:215], v[80:95]
	ds_read_b128 v[208:211], v151 offset:9248
	ds_read_b128 v[212:215], v151 offset:13856
	s_waitcnt vmcnt(7)
	ds_write_b128 v154, v[168:171]
	s_waitcnt vmcnt(6)
	ds_write_b128 v153, v[172:175]
	ds_read_b128 v[168:171], v152 offset:36928
	ds_read_b128 v[172:175], v152 offset:41536
	s_waitcnt lgkmcnt(5)
	v_mfma_f32_32x32x16_bf16 v[32:47], v[176:179], v[208:211], v[32:47]
	v_mfma_f32_32x32x16_bf16 v[48:63], v[180:183], v[208:211], v[48:63]
	ds_read_b128 v[208:211], v151 offset:64
	s_waitcnt lgkmcnt(5)
	v_mfma_f32_32x32x16_bf16 v[0:15], v[176:179], v[212:215], v[0:15]
	v_mfma_f32_32x32x16_bf16 v[16:31], v[180:183], v[212:215], v[16:31]
	ds_read_b128 v[212:215], v151 offset:4672
	s_setprio 0
	global_load_dwordx4 v[176:179], v[132:133], off offset:2816
	global_load_dwordx4 v[180:183], v[134:135], off offset:2816
	s_setprio 1
	s_waitcnt lgkmcnt(1)
	v_mfma_f32_32x32x16_bf16 v[96:111], v[168:171], v[208:211], v[96:111]
	v_mfma_f32_32x32x16_bf16 v[112:127], v[172:175], v[208:211], v[112:127]
	s_waitcnt lgkmcnt(0)
	v_mfma_f32_32x32x16_bf16 v[64:79], v[168:171], v[212:215], v[64:79]
	v_mfma_f32_32x32x16_bf16 v[80:95], v[172:175], v[212:215], v[80:95]
	ds_read_b128 v[208:211], v151 offset:9280
	ds_read_b128 v[212:215], v151 offset:13888
	s_waitcnt vmcnt(7)
	ds_write_b128 v156, v[160:163]
	s_waitcnt vmcnt(6)
	ds_write_b128 v155, v[164:167]
	ds_read_b128 v[160:163], v152 offset:36960
	ds_read_b128 v[164:167], v152 offset:41568
	s_waitcnt lgkmcnt(5)
	v_mfma_f32_32x32x16_bf16 v[32:47], v[168:171], v[208:211], v[32:47]
	v_mfma_f32_32x32x16_bf16 v[48:63], v[172:175], v[208:211], v[48:63]
	ds_read_b128 v[208:211], v151 offset:96
	s_waitcnt lgkmcnt(5)
	v_mfma_f32_32x32x16_bf16 v[0:15], v[168:171], v[212:215], v[0:15]
	v_mfma_f32_32x32x16_bf16 v[16:31], v[172:175], v[212:215], v[16:31]
	ds_read_b128 v[212:215], v151 offset:4704
	s_setprio 0
	global_load_dwordx4 v[168:171], v[144:145], off offset:2816
	global_load_dwordx4 v[172:175], v[146:147], off offset:2816
	s_setprio 1
	s_waitcnt lgkmcnt(1)
	v_mfma_f32_32x32x16_bf16 v[96:111], v[160:163], v[208:211], v[96:111]
	v_mfma_f32_32x32x16_bf16 v[112:127], v[164:167], v[208:211], v[112:127]
	s_waitcnt lgkmcnt(0)
	v_mfma_f32_32x32x16_bf16 v[64:79], v[160:163], v[212:215], v[64:79]
	v_mfma_f32_32x32x16_bf16 v[80:95], v[164:167], v[212:215], v[80:95]
	ds_read_b128 v[208:211], v151 offset:9312
	ds_read_b128 v[212:215], v151 offset:13920
	s_waitcnt lgkmcnt(1)
	v_mfma_f32_32x32x16_bf16 v[32:47], v[160:163], v[208:211], v[32:47]
	v_mfma_f32_32x32x16_bf16 v[48:63], v[164:167], v[208:211], v[48:63]
	s_waitcnt lgkmcnt(0)
	v_mfma_f32_32x32x16_bf16 v[0:15], v[160:163], v[212:215], v[0:15]
	v_mfma_f32_32x32x16_bf16 v[16:31], v[164:167], v[212:215], v[16:31]
	s_setprio 0
	global_load_dwordx4 v[160:163], v[136:137], off offset:2944
	global_load_dwordx4 v[164:167], v[138:139], off offset:2944
	s_barrier
; template <bool trans>
; DI void gemm_core(const GTile& tl, const GTile& nx, bool has_next  , bool chain  , bool pre, u32x4 (&ra)[4], u32x4 (&rb)[4], char* smem, f32x16 (&acc)[2][4]) {
;     ...
;   const int nk = K / 64;
;   if (!pre) { G_LOAD(0); G_STORE(0); G_LOAD(1); }
;   for (int kt = 0; kt < nk; ++kt) {
;     __syncthreads();
;     G_COMPUTE(kt & 1, kt);
	s_waitcnt vmcnt(9)
	ds_write_b128 v148, v[184:187]
	s_waitcnt vmcnt(8)
	ds_write_b128 v148, v[188:191] offset:36864
	ds_read_b128 v[184:187], v150
	ds_read_b128 v[188:191], v150 offset:4608
	ds_read_b128 v[208:211], v149
	ds_read_b128 v[212:215], v149 offset:4608
	s_setprio 1
	s_waitcnt lgkmcnt(1)
	v_mfma_f32_32x32x16_bf16 v[96:111], v[184:187], v[208:211], v[96:111]
	v_mfma_f32_32x32x16_bf16 v[112:127], v[188:191], v[208:211], v[112:127]
	s_waitcnt lgkmcnt(0)
	v_mfma_f32_32x32x16_bf16 v[64:79], v[184:187], v[212:215], v[64:79]
	v_mfma_f32_32x32x16_bf16 v[80:95], v[188:191], v[212:215], v[80:95]
	ds_read_b128 v[208:211], v149 offset:9216
	ds_read_b128 v[212:215], v149 offset:13824
	s_waitcnt vmcnt(7)
	ds_write_b128 v148, v[194:197] offset:9216
	s_waitcnt vmcnt(6)
	ds_write_b128 v148, v[198:201] offset:46080
	ds_read_b128 v[194:197], v150 offset:32
	ds_read_b128 v[198:201], v150 offset:4640
	s_waitcnt lgkmcnt(5)
	v_mfma_f32_32x32x16_bf16 v[32:47], v[184:187], v[208:211], v[32:47]
	v_mfma_f32_32x32x16_bf16 v[48:63], v[188:191], v[208:211], v[48:63]
	ds_read_b128 v[208:211], v149 offset:32
	s_waitcnt lgkmcnt(5)
	v_mfma_f32_32x32x16_bf16 v[0:15], v[184:187], v[212:215], v[0:15]
	v_mfma_f32_32x32x16_bf16 v[16:31], v[188:191], v[212:215], v[16:31]
	ds_read_b128 v[212:215], v149 offset:4640
	s_setprio 0
	global_load_dwordx4 v[184:187], v[140:141], off offset:2944
	global_load_dwordx4 v[188:191], v[142:143], off offset:2944
	s_setprio 1
	s_waitcnt lgkmcnt(1)
	v_mfma_f32_32x32x16_bf16 v[96:111], v[194:197], v[208:211], v[96:111]
	v_mfma_f32_32x32x16_bf16 v[112:127], v[198:201], v[208:211], v[112:127]
	s_waitcnt lgkmcnt(0)
	v_mfma_f32_32x32x16_bf16 v[64:79], v[194:197], v[212:215], v[64:79]
	v_mfma_f32_32x32x16_bf16 v[80:95], v[198:201], v[212:215], v[80:95]
	ds_read_b128 v[208:211], v149 offset:9248
	ds_read_b128 v[212:215], v149 offset:13856
	s_waitcnt vmcnt(7)
	ds_write_b128 v148, v[176:179] offset:18432
	s_waitcnt vmcnt(6)
	ds_write_b128 v148, v[180:183] offset:55296
	ds_read_b128 v[176:179], v150 offset:64
	ds_read_b128 v[180:183], v150 offset:4672
	s_waitcnt lgkmcnt(5)
	v_mfma_f32_32x32x16_bf16 v[32:47], v[194:197], v[208:211], v[32:47]
	v_mfma_f32_32x32x16_bf16 v[48:63], v[198:201], v[208:211], v[48:63]
	ds_read_b128 v[208:211], v149 offset:64
	s_waitcnt lgkmcnt(5)
	v_mfma_f32_32x32x16_bf16 v[0:15], v[194:197], v[212:215], v[0:15]
	v_mfma_f32_32x32x16_bf16 v[16:31], v[198:201], v[212:215], v[16:31]
	ds_read_b128 v[212:215], v149 offset:4672
	s_setprio 0
	global_load_dwordx4 v[194:197], v[132:133], off offset:2944
	global_load_dwordx4 v[198:201], v[134:135], off offset:2944
	s_setprio 1
	s_waitcnt lgkmcnt(1)
	v_mfma_f32_32x32x16_bf16 v[96:111], v[176:179], v[208:211], v[96:111]
	v_mfma_f32_32x32x16_bf16 v[112:127], v[180:183], v[208:211], v[112:127]
	s_waitcnt lgkmcnt(0)
	v_mfma_f32_32x32x16_bf16 v[64:79], v[176:179], v[212:215], v[64:79]
	v_mfma_f32_32x32x16_bf16 v[80:95], v[180:183], v[212:215], v[80:95]
	ds_read_b128 v[208:211], v149 offset:9280
	ds_read_b128 v[212:215], v149 offset:13888
	s_waitcnt vmcnt(7)
	ds_write_b128 v148, v[168:171] offset:27648
	s_waitcnt vmcnt(6)
	ds_write_b128 v148, v[172:175] offset:64512
	ds_read_b128 v[168:171], v150 offset:96
	ds_read_b128 v[172:175], v150 offset:4704
	s_waitcnt lgkmcnt(5)
	v_mfma_f32_32x32x16_bf16 v[32:47], v[176:179], v[208:211], v[32:47]
	v_mfma_f32_32x32x16_bf16 v[48:63], v[180:183], v[208:211], v[48:63]
	ds_read_b128 v[208:211], v149 offset:96
	s_waitcnt lgkmcnt(5)
	v_mfma_f32_32x32x16_bf16 v[0:15], v[176:179], v[212:215], v[0:15]
	v_mfma_f32_32x32x16_bf16 v[16:31], v[180:183], v[212:215], v[16:31]
	ds_read_b128 v[212:215], v149 offset:4704
	s_setprio 0
	global_load_dwordx4 v[176:179], v[144:145], off offset:2944
	global_load_dwordx4 v[180:183], v[146:147], off offset:2944
	s_setprio 1
	s_waitcnt lgkmcnt(1)
	v_mfma_f32_32x32x16_bf16 v[96:111], v[168:171], v[208:211], v[96:111]
	v_mfma_f32_32x32x16_bf16 v[112:127], v[172:175], v[208:211], v[112:127]
	s_waitcnt lgkmcnt(0)
	v_mfma_f32_32x32x16_bf16 v[64:79], v[168:171], v[212:215], v[64:79]
	v_mfma_f32_32x32x16_bf16 v[80:95], v[172:175], v[212:215], v[80:95]
	ds_read_b128 v[208:211], v149 offset:9312
	ds_read_b128 v[212:215], v149 offset:13920
	s_waitcnt lgkmcnt(1)
	v_mfma_f32_32x32x16_bf16 v[32:47], v[168:171], v[208:211], v[32:47]
	v_mfma_f32_32x32x16_bf16 v[48:63], v[172:175], v[208:211], v[48:63]
	s_waitcnt lgkmcnt(0)
	v_mfma_f32_32x32x16_bf16 v[0:15], v[168:171], v[212:215], v[0:15]
	v_mfma_f32_32x32x16_bf16 v[16:31], v[172:175], v[212:215], v[16:31]
	s_setprio 0
	global_load_dwordx4 v[168:171], v[136:137], off offset:3072
	global_load_dwordx4 v[172:175], v[138:139], off offset:3072
	s_barrier
; template <bool trans>
; DI void gemm_core(const GTile& tl, const GTile& nx, bool has_next  , bool chain  , bool pre, u32x4 (&ra)[4], u32x4 (&rb)[4], char* smem, f32x16 (&acc)[2][4]) {
;     ...
;   const int nk = K / 64;
;   if (!pre) { G_LOAD(0); G_STORE(0); G_LOAD(1); }
;   for (int kt = 0; kt < nk; ++kt) {
;     __syncthreads();
;     G_COMPUTE(kt & 1, kt);
	s_waitcnt vmcnt(9)
	ds_write_b128 v192, v[160:163]
	s_waitcnt vmcnt(8)
	ds_write_b128 v159, v[164:167]
	ds_read_b128 v[160:163], v152 offset:36864
	ds_read_b128 v[164:167], v152 offset:41472
	ds_read_b128 v[208:211], v151
	ds_read_b128 v[212:215], v151 offset:4608
	s_setprio 1
	s_waitcnt lgkmcnt(1)
	v_mfma_f32_32x32x16_bf16 v[96:111], v[160:163], v[208:211], v[96:111]
	v_mfma_f32_32x32x16_bf16 v[112:127], v[164:167], v[208:211], v[112:127]
	s_waitcnt lgkmcnt(0)
	v_mfma_f32_32x32x16_bf16 v[64:79], v[160:163], v[212:215], v[64:79]
	v_mfma_f32_32x32x16_bf16 v[80:95], v[164:167], v[212:215], v[80:95]
	ds_read_b128 v[208:211], v151 offset:9216
	ds_read_b128 v[212:215], v151 offset:13824
	s_waitcnt vmcnt(7)
	ds_write_b128 v158, v[184:187]
	s_waitcnt vmcnt(6)
	ds_write_b128 v157, v[188:191]
	ds_read_b128 v[184:187], v152 offset:36896
	ds_read_b128 v[188:191], v152 offset:41504
	s_waitcnt lgkmcnt(5)
	v_mfma_f32_32x32x16_bf16 v[32:47], v[160:163], v[208:211], v[32:47]
	v_mfma_f32_32x32x16_bf16 v[48:63], v[164:167], v[208:211], v[48:63]
	ds_read_b128 v[208:211], v151 offset:32
	s_waitcnt lgkmcnt(5)
	v_mfma_f32_32x32x16_bf16 v[0:15], v[160:163], v[212:215], v[0:15]
	v_mfma_f32_32x32x16_bf16 v[16:31], v[164:167], v[212:215], v[16:31]
	ds_read_b128 v[212:215], v151 offset:4640
	s_setprio 0
	global_load_dwordx4 v[160:163], v[140:141], off offset:3072
	global_load_dwordx4 v[164:167], v[142:143], off offset:3072
	s_setprio 1
	s_waitcnt lgkmcnt(1)
	v_mfma_f32_32x32x16_bf16 v[96:111], v[184:187], v[208:211], v[96:111]
	v_mfma_f32_32x32x16_bf16 v[112:127], v[188:191], v[208:211], v[112:127]
	s_waitcnt lgkmcnt(0)
	v_mfma_f32_32x32x16_bf16 v[64:79], v[184:187], v[212:215], v[64:79]
	v_mfma_f32_32x32x16_bf16 v[80:95], v[188:191], v[212:215], v[80:95]
	ds_read_b128 v[208:211], v151 offset:9248
	ds_read_b128 v[212:215], v151 offset:13856
	s_waitcnt vmcnt(7)
	ds_write_b128 v154, v[194:197]
	s_waitcnt vmcnt(6)
	ds_write_b128 v153, v[198:201]
	ds_read_b128 v[194:197], v152 offset:36928
	ds_read_b128 v[198:201], v152 offset:41536
	s_waitcnt lgkmcnt(5)
	v_mfma_f32_32x32x16_bf16 v[32:47], v[184:187], v[208:211], v[32:47]
	v_mfma_f32_32x32x16_bf16 v[48:63], v[188:191], v[208:211], v[48:63]
	ds_read_b128 v[208:211], v151 offset:64
	s_waitcnt lgkmcnt(5)
	v_mfma_f32_32x32x16_bf16 v[0:15], v[184:187], v[212:215], v[0:15]
	v_mfma_f32_32x32x16_bf16 v[16:31], v[188:191], v[212:215], v[16:31]
	ds_read_b128 v[212:215], v151 offset:4672
	s_setprio 0
	global_load_dwordx4 v[184:187], v[132:133], off offset:3072
	global_load_dwordx4 v[188:191], v[134:135], off offset:3072
	s_setprio 1
	s_waitcnt lgkmcnt(1)
	v_mfma_f32_32x32x16_bf16 v[96:111], v[194:197], v[208:211], v[96:111]
	v_mfma_f32_32x32x16_bf16 v[112:127], v[198:201], v[208:211], v[112:127]
	s_waitcnt lgkmcnt(0)
	v_mfma_f32_32x32x16_bf16 v[64:79], v[194:197], v[212:215], v[64:79]
	v_mfma_f32_32x32x16_bf16 v[80:95], v[198:201], v[212:215], v[80:95]
	ds_read_b128 v[208:211], v151 offset:9280
	ds_read_b128 v[212:215], v151 offset:13888
	s_waitcnt vmcnt(7)
	ds_write_b128 v156, v[176:179]
	s_waitcnt vmcnt(6)
	ds_write_b128 v155, v[180:183]
	ds_read_b128 v[176:179], v152 offset:36960
	ds_read_b128 v[180:183], v152 offset:41568
	s_waitcnt lgkmcnt(5)
	v_mfma_f32_32x32x16_bf16 v[32:47], v[194:197], v[208:211], v[32:47]
	v_mfma_f32_32x32x16_bf16 v[48:63], v[198:201], v[208:211], v[48:63]
	ds_read_b128 v[208:211], v151 offset:96
	s_waitcnt lgkmcnt(5)
	v_mfma_f32_32x32x16_bf16 v[0:15], v[194:197], v[212:215], v[0:15]
	v_mfma_f32_32x32x16_bf16 v[16:31], v[198:201], v[212:215], v[16:31]
	ds_read_b128 v[212:215], v151 offset:4704
	s_setprio 0
	global_load_dwordx4 v[194:197], v[144:145], off offset:3072
	global_load_dwordx4 v[198:201], v[146:147], off offset:3072
	s_setprio 1
	s_waitcnt lgkmcnt(1)
	v_mfma_f32_32x32x16_bf16 v[96:111], v[176:179], v[208:211], v[96:111]
	v_mfma_f32_32x32x16_bf16 v[112:127], v[180:183], v[208:211], v[112:127]
	s_waitcnt lgkmcnt(0)
	v_mfma_f32_32x32x16_bf16 v[64:79], v[176:179], v[212:215], v[64:79]
	v_mfma_f32_32x32x16_bf16 v[80:95], v[180:183], v[212:215], v[80:95]
	ds_read_b128 v[208:211], v151 offset:9312
	ds_read_b128 v[212:215], v151 offset:13920
	s_waitcnt lgkmcnt(1)
	v_mfma_f32_32x32x16_bf16 v[32:47], v[176:179], v[208:211], v[32:47]
	v_mfma_f32_32x32x16_bf16 v[48:63], v[180:183], v[208:211], v[48:63]
	s_waitcnt lgkmcnt(0)
	v_mfma_f32_32x32x16_bf16 v[0:15], v[176:179], v[212:215], v[0:15]
	v_mfma_f32_32x32x16_bf16 v[16:31], v[180:183], v[212:215], v[16:31]
	s_setprio 0
	global_load_dwordx4 v[176:179], v[136:137], off offset:3200
	global_load_dwordx4 v[180:183], v[138:139], off offset:3200
	s_barrier
; template <bool trans>
; DI void gemm_core(const GTile& tl, const GTile& nx, bool has_next  , bool chain  , bool pre, u32x4 (&ra)[4], u32x4 (&rb)[4], char* smem, f32x16 (&acc)[2][4]) {
;     ...
;   const int nk = K / 64;
;   if (!pre) { G_LOAD(0); G_STORE(0); G_LOAD(1); }
;   for (int kt = 0; kt < nk; ++kt) {
;     __syncthreads();
;     G_COMPUTE(kt & 1, kt);
	s_waitcnt vmcnt(9)
	ds_write_b128 v148, v[168:171]
	s_waitcnt vmcnt(8)
	ds_write_b128 v148, v[172:175] offset:36864
	ds_read_b128 v[168:171], v150
	ds_read_b128 v[172:175], v150 offset:4608
	ds_read_b128 v[208:211], v149
	ds_read_b128 v[212:215], v149 offset:4608
	s_setprio 1
	s_waitcnt lgkmcnt(1)
	v_mfma_f32_32x32x16_bf16 v[96:111], v[168:171], v[208:211], v[96:111]
	v_mfma_f32_32x32x16_bf16 v[112:127], v[172:175], v[208:211], v[112:127]
	s_waitcnt lgkmcnt(0)
	v_mfma_f32_32x32x16_bf16 v[64:79], v[168:171], v[212:215], v[64:79]
	v_mfma_f32_32x32x16_bf16 v[80:95], v[172:175], v[212:215], v[80:95]
	ds_read_b128 v[208:211], v149 offset:9216
	ds_read_b128 v[212:215], v149 offset:13824
	s_waitcnt vmcnt(7)
	ds_write_b128 v148, v[160:163] offset:9216
	s_waitcnt vmcnt(6)
	ds_write_b128 v148, v[164:167] offset:46080
	ds_read_b128 v[160:163], v150 offset:32
	ds_read_b128 v[164:167], v150 offset:4640
	s_waitcnt lgkmcnt(5)
	v_mfma_f32_32x32x16_bf16 v[32:47], v[168:171], v[208:211], v[32:47]
	v_mfma_f32_32x32x16_bf16 v[48:63], v[172:175], v[208:211], v[48:63]
	ds_read_b128 v[208:211], v149 offset:32
	s_waitcnt lgkmcnt(5)
	v_mfma_f32_32x32x16_bf16 v[0:15], v[168:171], v[212:215], v[0:15]
	v_mfma_f32_32x32x16_bf16 v[16:31], v[172:175], v[212:215], v[16:31]
	ds_read_b128 v[212:215], v149 offset:4640
	s_setprio 0
	global_load_dwordx4 v[168:171], v[140:141], off offset:3200
	global_load_dwordx4 v[172:175], v[142:143], off offset:3200
	s_setprio 1
	s_waitcnt lgkmcnt(1)
	v_mfma_f32_32x32x16_bf16 v[96:111], v[160:163], v[208:211], v[96:111]
	v_mfma_f32_32x32x16_bf16 v[112:127], v[164:167], v[208:211], v[112:127]
	s_waitcnt lgkmcnt(0)
	v_mfma_f32_32x32x16_bf16 v[64:79], v[160:163], v[212:215], v[64:79]
	v_mfma_f32_32x32x16_bf16 v[80:95], v[164:167], v[212:215], v[80:95]
	ds_read_b128 v[208:211], v149 offset:9248
	ds_read_b128 v[212:215], v149 offset:13856
	s_waitcnt vmcnt(7)
	ds_write_b128 v148, v[184:187] offset:18432
	s_waitcnt vmcnt(6)
	ds_write_b128 v148, v[188:191] offset:55296
	ds_read_b128 v[184:187], v150 offset:64
	ds_read_b128 v[188:191], v150 offset:4672
	s_waitcnt lgkmcnt(5)
	v_mfma_f32_32x32x16_bf16 v[32:47], v[160:163], v[208:211], v[32:47]
	v_mfma_f32_32x32x16_bf16 v[48:63], v[164:167], v[208:211], v[48:63]
	ds_read_b128 v[208:211], v149 offset:64
	s_waitcnt lgkmcnt(5)
	v_mfma_f32_32x32x16_bf16 v[0:15], v[160:163], v[212:215], v[0:15]
	v_mfma_f32_32x32x16_bf16 v[16:31], v[164:167], v[212:215], v[16:31]
	ds_read_b128 v[212:215], v149 offset:4672
	s_setprio 0
	global_load_dwordx4 v[160:163], v[132:133], off offset:3200
	global_load_dwordx4 v[164:167], v[134:135], off offset:3200
	s_setprio 1
	s_waitcnt lgkmcnt(1)
	v_mfma_f32_32x32x16_bf16 v[96:111], v[184:187], v[208:211], v[96:111]
	v_mfma_f32_32x32x16_bf16 v[112:127], v[188:191], v[208:211], v[112:127]
	s_waitcnt lgkmcnt(0)
	v_mfma_f32_32x32x16_bf16 v[64:79], v[184:187], v[212:215], v[64:79]
	v_mfma_f32_32x32x16_bf16 v[80:95], v[188:191], v[212:215], v[80:95]
	ds_read_b128 v[208:211], v149 offset:9280
	ds_read_b128 v[212:215], v149 offset:13888
	s_waitcnt vmcnt(7)
	ds_write_b128 v148, v[194:197] offset:27648
	s_waitcnt vmcnt(6)
	ds_write_b128 v148, v[198:201] offset:64512
	ds_read_b128 v[194:197], v150 offset:96
	ds_read_b128 v[198:201], v150 offset:4704
	s_waitcnt lgkmcnt(5)
	v_mfma_f32_32x32x16_bf16 v[32:47], v[184:187], v[208:211], v[32:47]
	v_mfma_f32_32x32x16_bf16 v[48:63], v[188:191], v[208:211], v[48:63]
	ds_read_b128 v[208:211], v149 offset:96
	s_waitcnt lgkmcnt(5)
	v_mfma_f32_32x32x16_bf16 v[0:15], v[184:187], v[212:215], v[0:15]
	v_mfma_f32_32x32x16_bf16 v[16:31], v[188:191], v[212:215], v[16:31]
	ds_read_b128 v[212:215], v149 offset:4704
	s_setprio 0
	global_load_dwordx4 v[184:187], v[144:145], off offset:3200
	global_load_dwordx4 v[188:191], v[146:147], off offset:3200
	s_setprio 1
	s_waitcnt lgkmcnt(1)
	v_mfma_f32_32x32x16_bf16 v[96:111], v[194:197], v[208:211], v[96:111]
	v_mfma_f32_32x32x16_bf16 v[112:127], v[198:201], v[208:211], v[112:127]
	s_waitcnt lgkmcnt(0)
	v_mfma_f32_32x32x16_bf16 v[64:79], v[194:197], v[212:215], v[64:79]
	v_mfma_f32_32x32x16_bf16 v[80:95], v[198:201], v[212:215], v[80:95]
	ds_read_b128 v[208:211], v149 offset:9312
	ds_read_b128 v[212:215], v149 offset:13920
	s_waitcnt lgkmcnt(1)
	v_mfma_f32_32x32x16_bf16 v[32:47], v[194:197], v[208:211], v[32:47]
	v_mfma_f32_32x32x16_bf16 v[48:63], v[198:201], v[208:211], v[48:63]
	s_waitcnt lgkmcnt(0)
	v_mfma_f32_32x32x16_bf16 v[0:15], v[194:197], v[212:215], v[0:15]
	v_mfma_f32_32x32x16_bf16 v[16:31], v[198:201], v[212:215], v[16:31]
	s_setprio 0
	global_load_dwordx4 v[194:197], v[136:137], off offset:3328
	global_load_dwordx4 v[198:201], v[138:139], off offset:3328
	s_barrier
; template <bool trans>
; DI void gemm_core(const GTile& tl, const GTile& nx, bool has_next  , bool chain  , bool pre, u32x4 (&ra)[4], u32x4 (&rb)[4], char* smem, f32x16 (&acc)[2][4]) {
;     ...
;   const int nk = K / 64;
;   if (!pre) { G_LOAD(0); G_STORE(0); G_LOAD(1); }
;   for (int kt = 0; kt < nk; ++kt) {
;     __syncthreads();
;     G_COMPUTE(kt & 1, kt);
	s_waitcnt vmcnt(9)
	ds_write_b128 v192, v[176:179]
	s_waitcnt vmcnt(8)
	ds_write_b128 v159, v[180:183]
	ds_read_b128 v[176:179], v152 offset:36864
	ds_read_b128 v[180:183], v152 offset:41472
	ds_read_b128 v[208:211], v151
	ds_read_b128 v[212:215], v151 offset:4608
	s_setprio 1
	s_waitcnt lgkmcnt(1)
	v_mfma_f32_32x32x16_bf16 v[96:111], v[176:179], v[208:211], v[96:111]
	v_mfma_f32_32x32x16_bf16 v[112:127], v[180:183], v[208:211], v[112:127]
	s_waitcnt lgkmcnt(0)
	v_mfma_f32_32x32x16_bf16 v[64:79], v[176:179], v[212:215], v[64:79]
	v_mfma_f32_32x32x16_bf16 v[80:95], v[180:183], v[212:215], v[80:95]
	ds_read_b128 v[208:211], v151 offset:9216
	ds_read_b128 v[212:215], v151 offset:13824
	s_waitcnt vmcnt(7)
	ds_write_b128 v158, v[168:171]
	s_waitcnt vmcnt(6)
	ds_write_b128 v157, v[172:175]
	ds_read_b128 v[168:171], v152 offset:36896
	ds_read_b128 v[172:175], v152 offset:41504
	s_waitcnt lgkmcnt(5)
	v_mfma_f32_32x32x16_bf16 v[32:47], v[176:179], v[208:211], v[32:47]
	v_mfma_f32_32x32x16_bf16 v[48:63], v[180:183], v[208:211], v[48:63]
	ds_read_b128 v[208:211], v151 offset:32
	s_waitcnt lgkmcnt(5)
	v_mfma_f32_32x32x16_bf16 v[0:15], v[176:179], v[212:215], v[0:15]
	v_mfma_f32_32x32x16_bf16 v[16:31], v[180:183], v[212:215], v[16:31]
	ds_read_b128 v[212:215], v151 offset:4640
	s_setprio 0
	global_load_dwordx4 v[176:179], v[140:141], off offset:3328
	global_load_dwordx4 v[180:183], v[142:143], off offset:3328
	s_setprio 1
	s_waitcnt lgkmcnt(1)
	v_mfma_f32_32x32x16_bf16 v[96:111], v[168:171], v[208:211], v[96:111]
	v_mfma_f32_32x32x16_bf16 v[112:127], v[172:175], v[208:211], v[112:127]
	s_waitcnt lgkmcnt(0)
	v_mfma_f32_32x32x16_bf16 v[64:79], v[168:171], v[212:215], v[64:79]
	v_mfma_f32_32x32x16_bf16 v[80:95], v[172:175], v[212:215], v[80:95]
	ds_read_b128 v[208:211], v151 offset:9248
	ds_read_b128 v[212:215], v151 offset:13856
	s_waitcnt vmcnt(7)
	ds_write_b128 v154, v[160:163]
	s_waitcnt vmcnt(6)
	ds_write_b128 v153, v[164:167]
	ds_read_b128 v[160:163], v152 offset:36928
	ds_read_b128 v[164:167], v152 offset:41536
	s_waitcnt lgkmcnt(5)
	v_mfma_f32_32x32x16_bf16 v[32:47], v[168:171], v[208:211], v[32:47]
	v_mfma_f32_32x32x16_bf16 v[48:63], v[172:175], v[208:211], v[48:63]
	ds_read_b128 v[208:211], v151 offset:64
	s_waitcnt lgkmcnt(5)
	v_mfma_f32_32x32x16_bf16 v[0:15], v[168:171], v[212:215], v[0:15]
	v_mfma_f32_32x32x16_bf16 v[16:31], v[172:175], v[212:215], v[16:31]
	ds_read_b128 v[212:215], v151 offset:4672
	s_setprio 0
	global_load_dwordx4 v[168:171], v[132:133], off offset:3328
	global_load_dwordx4 v[172:175], v[134:135], off offset:3328
	s_setprio 1
	s_waitcnt lgkmcnt(1)
	v_mfma_f32_32x32x16_bf16 v[96:111], v[160:163], v[208:211], v[96:111]
	v_mfma_f32_32x32x16_bf16 v[112:127], v[164:167], v[208:211], v[112:127]
	s_waitcnt lgkmcnt(0)
	v_mfma_f32_32x32x16_bf16 v[64:79], v[160:163], v[212:215], v[64:79]
	v_mfma_f32_32x32x16_bf16 v[80:95], v[164:167], v[212:215], v[80:95]
	ds_read_b128 v[208:211], v151 offset:9280
	ds_read_b128 v[212:215], v151 offset:13888
	s_waitcnt vmcnt(7)
	ds_write_b128 v156, v[184:187]
	s_waitcnt vmcnt(6)
	ds_write_b128 v155, v[188:191]
	ds_read_b128 v[184:187], v152 offset:36960
	ds_read_b128 v[188:191], v152 offset:41568
	s_waitcnt lgkmcnt(5)
	v_mfma_f32_32x32x16_bf16 v[32:47], v[160:163], v[208:211], v[32:47]
	v_mfma_f32_32x32x16_bf16 v[48:63], v[164:167], v[208:211], v[48:63]
	ds_read_b128 v[208:211], v151 offset:96
	s_waitcnt lgkmcnt(5)
	v_mfma_f32_32x32x16_bf16 v[0:15], v[160:163], v[212:215], v[0:15]
	v_mfma_f32_32x32x16_bf16 v[16:31], v[164:167], v[212:215], v[16:31]
	ds_read_b128 v[212:215], v151 offset:4704
	s_setprio 0
	global_load_dwordx4 v[160:163], v[144:145], off offset:3328
	global_load_dwordx4 v[164:167], v[146:147], off offset:3328
	s_setprio 1
	s_waitcnt lgkmcnt(1)
	v_mfma_f32_32x32x16_bf16 v[96:111], v[184:187], v[208:211], v[96:111]
	v_mfma_f32_32x32x16_bf16 v[112:127], v[188:191], v[208:211], v[112:127]
	s_waitcnt lgkmcnt(0)
	v_mfma_f32_32x32x16_bf16 v[64:79], v[184:187], v[212:215], v[64:79]
	v_mfma_f32_32x32x16_bf16 v[80:95], v[188:191], v[212:215], v[80:95]
	ds_read_b128 v[208:211], v151 offset:9312
	ds_read_b128 v[212:215], v151 offset:13920
	s_waitcnt lgkmcnt(1)
	v_mfma_f32_32x32x16_bf16 v[32:47], v[184:187], v[208:211], v[32:47]
	v_mfma_f32_32x32x16_bf16 v[48:63], v[188:191], v[208:211], v[48:63]
	s_waitcnt lgkmcnt(0)
	v_mfma_f32_32x32x16_bf16 v[0:15], v[184:187], v[212:215], v[0:15]
	v_mfma_f32_32x32x16_bf16 v[16:31], v[188:191], v[212:215], v[16:31]
	s_setprio 0
	global_load_dwordx4 v[184:187], v[136:137], off offset:3456
	global_load_dwordx4 v[188:191], v[138:139], off offset:3456
	s_barrier
; template <bool trans>
; DI void gemm_core(const GTile& tl, const GTile& nx, bool has_next  , bool chain  , bool pre, u32x4 (&ra)[4], u32x4 (&rb)[4], char* smem, f32x16 (&acc)[2][4]) {
;     ...
;   const int nk = K / 64;
;   if (!pre) { G_LOAD(0); G_STORE(0); G_LOAD(1); }
;   for (int kt = 0; kt < nk; ++kt) {
;     __syncthreads();
;     G_COMPUTE(kt & 1, kt);
	s_waitcnt vmcnt(9)
	ds_write_b128 v148, v[194:197]
	s_waitcnt vmcnt(8)
	ds_write_b128 v148, v[198:201] offset:36864
	ds_read_b128 v[194:197], v150
	ds_read_b128 v[198:201], v150 offset:4608
	ds_read_b128 v[208:211], v149
	ds_read_b128 v[212:215], v149 offset:4608
	s_setprio 1
	s_waitcnt lgkmcnt(1)
	v_mfma_f32_32x32x16_bf16 v[96:111], v[194:197], v[208:211], v[96:111]
	v_mfma_f32_32x32x16_bf16 v[112:127], v[198:201], v[208:211], v[112:127]
	s_waitcnt lgkmcnt(0)
	v_mfma_f32_32x32x16_bf16 v[64:79], v[194:197], v[212:215], v[64:79]
	v_mfma_f32_32x32x16_bf16 v[80:95], v[198:201], v[212:215], v[80:95]
	ds_read_b128 v[208:211], v149 offset:9216
	ds_read_b128 v[212:215], v149 offset:13824
	s_waitcnt vmcnt(7)
	ds_write_b128 v148, v[176:179] offset:9216
	s_waitcnt vmcnt(6)
	ds_write_b128 v148, v[180:183] offset:46080
	ds_read_b128 v[176:179], v150 offset:32
	ds_read_b128 v[180:183], v150 offset:4640
	s_waitcnt lgkmcnt(5)
	v_mfma_f32_32x32x16_bf16 v[32:47], v[194:197], v[208:211], v[32:47]
	v_mfma_f32_32x32x16_bf16 v[48:63], v[198:201], v[208:211], v[48:63]
	ds_read_b128 v[208:211], v149 offset:32
	s_waitcnt lgkmcnt(5)
	v_mfma_f32_32x32x16_bf16 v[0:15], v[194:197], v[212:215], v[0:15]
	v_mfma_f32_32x32x16_bf16 v[16:31], v[198:201], v[212:215], v[16:31]
	ds_read_b128 v[212:215], v149 offset:4640
	s_setprio 0
	global_load_dwordx4 v[194:197], v[140:141], off offset:3456
	global_load_dwordx4 v[198:201], v[142:143], off offset:3456
	s_setprio 1
	s_waitcnt lgkmcnt(1)
	v_mfma_f32_32x32x16_bf16 v[96:111], v[176:179], v[208:211], v[96:111]
	v_mfma_f32_32x32x16_bf16 v[112:127], v[180:183], v[208:211], v[112:127]
	s_waitcnt lgkmcnt(0)
	v_mfma_f32_32x32x16_bf16 v[64:79], v[176:179], v[212:215], v[64:79]
	v_mfma_f32_32x32x16_bf16 v[80:95], v[180:183], v[212:215], v[80:95]
	ds_read_b128 v[208:211], v149 offset:9248
	ds_read_b128 v[212:215], v149 offset:13856
	s_waitcnt vmcnt(7)
	ds_write_b128 v148, v[168:171] offset:18432
	s_waitcnt vmcnt(6)
	ds_write_b128 v148, v[172:175] offset:55296
	ds_read_b128 v[168:171], v150 offset:64
	ds_read_b128 v[172:175], v150 offset:4672
	s_waitcnt lgkmcnt(5)
	v_mfma_f32_32x32x16_bf16 v[32:47], v[176:179], v[208:211], v[32:47]
	v_mfma_f32_32x32x16_bf16 v[48:63], v[180:183], v[208:211], v[48:63]
	ds_read_b128 v[208:211], v149 offset:64
	s_waitcnt lgkmcnt(5)
	v_mfma_f32_32x32x16_bf16 v[0:15], v[176:179], v[212:215], v[0:15]
	v_mfma_f32_32x32x16_bf16 v[16:31], v[180:183], v[212:215], v[16:31]
	ds_read_b128 v[212:215], v149 offset:4672
	s_setprio 0
	global_load_dwordx4 v[176:179], v[132:133], off offset:3456
	global_load_dwordx4 v[180:183], v[134:135], off offset:3456
	s_setprio 1
	s_waitcnt lgkmcnt(1)
	v_mfma_f32_32x32x16_bf16 v[96:111], v[168:171], v[208:211], v[96:111]
	v_mfma_f32_32x32x16_bf16 v[112:127], v[172:175], v[208:211], v[112:127]
	s_waitcnt lgkmcnt(0)
	v_mfma_f32_32x32x16_bf16 v[64:79], v[168:171], v[212:215], v[64:79]
	v_mfma_f32_32x32x16_bf16 v[80:95], v[172:175], v[212:215], v[80:95]
	ds_read_b128 v[208:211], v149 offset:9280
	ds_read_b128 v[212:215], v149 offset:13888
	s_waitcnt vmcnt(7)
	ds_write_b128 v148, v[160:163] offset:27648
	s_waitcnt vmcnt(6)
	ds_write_b128 v148, v[164:167] offset:64512
	ds_read_b128 v[160:163], v150 offset:96
	ds_read_b128 v[164:167], v150 offset:4704
	s_waitcnt lgkmcnt(5)
	v_mfma_f32_32x32x16_bf16 v[32:47], v[168:171], v[208:211], v[32:47]
	v_mfma_f32_32x32x16_bf16 v[48:63], v[172:175], v[208:211], v[48:63]
	ds_read_b128 v[208:211], v149 offset:96
	s_waitcnt lgkmcnt(5)
	v_mfma_f32_32x32x16_bf16 v[0:15], v[168:171], v[212:215], v[0:15]
	v_mfma_f32_32x32x16_bf16 v[16:31], v[172:175], v[212:215], v[16:31]
	ds_read_b128 v[212:215], v149 offset:4704
	s_setprio 0
	global_load_dwordx4 v[168:171], v[144:145], off offset:3456
	global_load_dwordx4 v[172:175], v[146:147], off offset:3456
	s_setprio 1
	s_waitcnt lgkmcnt(1)
	v_mfma_f32_32x32x16_bf16 v[96:111], v[160:163], v[208:211], v[96:111]
	v_mfma_f32_32x32x16_bf16 v[112:127], v[164:167], v[208:211], v[112:127]
	s_waitcnt lgkmcnt(0)
	v_mfma_f32_32x32x16_bf16 v[64:79], v[160:163], v[212:215], v[64:79]
	v_mfma_f32_32x32x16_bf16 v[80:95], v[164:167], v[212:215], v[80:95]
	ds_read_b128 v[208:211], v149 offset:9312
	ds_read_b128 v[212:215], v149 offset:13920
	s_waitcnt lgkmcnt(1)
	v_mfma_f32_32x32x16_bf16 v[32:47], v[160:163], v[208:211], v[32:47]
	v_mfma_f32_32x32x16_bf16 v[48:63], v[164:167], v[208:211], v[48:63]
	s_waitcnt lgkmcnt(0)
	v_mfma_f32_32x32x16_bf16 v[0:15], v[160:163], v[212:215], v[0:15]
	v_mfma_f32_32x32x16_bf16 v[16:31], v[164:167], v[212:215], v[16:31]
	s_setprio 0
	global_load_dwordx4 v[160:163], v[136:137], off offset:3584
	global_load_dwordx4 v[164:167], v[138:139], off offset:3584
	s_barrier
; template <bool trans>
; DI void gemm_core(const GTile& tl, const GTile& nx, bool has_next  , bool chain  , bool pre, u32x4 (&ra)[4], u32x4 (&rb)[4], char* smem, f32x16 (&acc)[2][4]) {
;     ...
;   const int nk = K / 64;
;   if (!pre) { G_LOAD(0); G_STORE(0); G_LOAD(1); }
;   for (int kt = 0; kt < nk; ++kt) {
;     __syncthreads();
;     G_COMPUTE(kt & 1, kt);
	s_waitcnt vmcnt(9)
	ds_write_b128 v192, v[184:187]
	s_waitcnt vmcnt(8)
	ds_write_b128 v159, v[188:191]
	ds_read_b128 v[184:187], v152 offset:36864
	ds_read_b128 v[188:191], v152 offset:41472
	ds_read_b128 v[208:211], v151
	ds_read_b128 v[212:215], v151 offset:4608
	s_setprio 1
	s_waitcnt lgkmcnt(1)
	v_mfma_f32_32x32x16_bf16 v[96:111], v[184:187], v[208:211], v[96:111]
	v_mfma_f32_32x32x16_bf16 v[112:127], v[188:191], v[208:211], v[112:127]
	s_waitcnt lgkmcnt(0)
	v_mfma_f32_32x32x16_bf16 v[64:79], v[184:187], v[212:215], v[64:79]
	v_mfma_f32_32x32x16_bf16 v[80:95], v[188:191], v[212:215], v[80:95]
	ds_read_b128 v[208:211], v151 offset:9216
	ds_read_b128 v[212:215], v151 offset:13824
	s_waitcnt vmcnt(7)
	ds_write_b128 v158, v[194:197]
	s_waitcnt vmcnt(6)
	ds_write_b128 v157, v[198:201]
	ds_read_b128 v[194:197], v152 offset:36896
	ds_read_b128 v[198:201], v152 offset:41504
	s_waitcnt lgkmcnt(5)
	v_mfma_f32_32x32x16_bf16 v[32:47], v[184:187], v[208:211], v[32:47]
	v_mfma_f32_32x32x16_bf16 v[48:63], v[188:191], v[208:211], v[48:63]
	ds_read_b128 v[208:211], v151 offset:32
	s_waitcnt lgkmcnt(5)
	v_mfma_f32_32x32x16_bf16 v[0:15], v[184:187], v[212:215], v[0:15]
	v_mfma_f32_32x32x16_bf16 v[16:31], v[188:191], v[212:215], v[16:31]
	ds_read_b128 v[212:215], v151 offset:4640
	s_setprio 0
	global_load_dwordx4 v[184:187], v[140:141], off offset:3584
	global_load_dwordx4 v[188:191], v[142:143], off offset:3584
	s_setprio 1
	s_waitcnt lgkmcnt(1)
	v_mfma_f32_32x32x16_bf16 v[96:111], v[194:197], v[208:211], v[96:111]
	v_mfma_f32_32x32x16_bf16 v[112:127], v[198:201], v[208:211], v[112:127]
	s_waitcnt lgkmcnt(0)
	v_mfma_f32_32x32x16_bf16 v[64:79], v[194:197], v[212:215], v[64:79]
	v_mfma_f32_32x32x16_bf16 v[80:95], v[198:201], v[212:215], v[80:95]
	ds_read_b128 v[208:211], v151 offset:9248
	ds_read_b128 v[212:215], v151 offset:13856
	s_waitcnt vmcnt(7)
	ds_write_b128 v154, v[176:179]
	s_waitcnt vmcnt(6)
	ds_write_b128 v153, v[180:183]
	ds_read_b128 v[176:179], v152 offset:36928
	ds_read_b128 v[180:183], v152 offset:41536
	s_waitcnt lgkmcnt(5)
	v_mfma_f32_32x32x16_bf16 v[32:47], v[194:197], v[208:211], v[32:47]
	v_mfma_f32_32x32x16_bf16 v[48:63], v[198:201], v[208:211], v[48:63]
	ds_read_b128 v[208:211], v151 offset:64
	s_waitcnt lgkmcnt(5)
	v_mfma_f32_32x32x16_bf16 v[0:15], v[194:197], v[212:215], v[0:15]
	v_mfma_f32_32x32x16_bf16 v[16:31], v[198:201], v[212:215], v[16:31]
	ds_read_b128 v[212:215], v151 offset:4672
	s_setprio 0
	global_load_dwordx4 v[194:197], v[132:133], off offset:3584
	global_load_dwordx4 v[198:201], v[134:135], off offset:3584
	s_setprio 1
	s_waitcnt lgkmcnt(1)
	v_mfma_f32_32x32x16_bf16 v[96:111], v[176:179], v[208:211], v[96:111]
	v_mfma_f32_32x32x16_bf16 v[112:127], v[180:183], v[208:211], v[112:127]
	s_waitcnt lgkmcnt(0)
	v_mfma_f32_32x32x16_bf16 v[64:79], v[176:179], v[212:215], v[64:79]
	v_mfma_f32_32x32x16_bf16 v[80:95], v[180:183], v[212:215], v[80:95]
	ds_read_b128 v[208:211], v151 offset:9280
	ds_read_b128 v[212:215], v151 offset:13888
	s_waitcnt vmcnt(7)
	ds_write_b128 v156, v[168:171]
	s_waitcnt vmcnt(6)
	ds_write_b128 v155, v[172:175]
	ds_read_b128 v[168:171], v152 offset:36960
	ds_read_b128 v[172:175], v152 offset:41568
	s_waitcnt lgkmcnt(5)
	v_mfma_f32_32x32x16_bf16 v[32:47], v[176:179], v[208:211], v[32:47]
	v_mfma_f32_32x32x16_bf16 v[48:63], v[180:183], v[208:211], v[48:63]
	ds_read_b128 v[208:211], v151 offset:96
	s_waitcnt lgkmcnt(5)
	v_mfma_f32_32x32x16_bf16 v[0:15], v[176:179], v[212:215], v[0:15]
	v_mfma_f32_32x32x16_bf16 v[16:31], v[180:183], v[212:215], v[16:31]
	ds_read_b128 v[212:215], v151 offset:4704
	s_setprio 0
	global_load_dwordx4 v[176:179], v[144:145], off offset:3584
	global_load_dwordx4 v[180:183], v[146:147], off offset:3584
	s_setprio 1
	s_waitcnt lgkmcnt(1)
	v_mfma_f32_32x32x16_bf16 v[96:111], v[168:171], v[208:211], v[96:111]
	v_mfma_f32_32x32x16_bf16 v[112:127], v[172:175], v[208:211], v[112:127]
	s_waitcnt lgkmcnt(0)
	v_mfma_f32_32x32x16_bf16 v[64:79], v[168:171], v[212:215], v[64:79]
	v_mfma_f32_32x32x16_bf16 v[80:95], v[172:175], v[212:215], v[80:95]
	ds_read_b128 v[208:211], v151 offset:9312
	ds_read_b128 v[212:215], v151 offset:13920
	s_waitcnt lgkmcnt(1)
	v_mfma_f32_32x32x16_bf16 v[32:47], v[168:171], v[208:211], v[32:47]
	v_mfma_f32_32x32x16_bf16 v[48:63], v[172:175], v[208:211], v[48:63]
	s_waitcnt lgkmcnt(0)
	v_mfma_f32_32x32x16_bf16 v[0:15], v[168:171], v[212:215], v[0:15]
	v_mfma_f32_32x32x16_bf16 v[16:31], v[172:175], v[212:215], v[16:31]
	s_setprio 0
	global_load_dwordx4 v[168:171], v[136:137], off offset:3712
	global_load_dwordx4 v[172:175], v[138:139], off offset:3712
	s_barrier
; template <bool trans>
; DI void gemm_core(const GTile& tl, const GTile& nx, bool has_next  , bool chain  , bool pre, u32x4 (&ra)[4], u32x4 (&rb)[4], char* smem, f32x16 (&acc)[2][4]) {
;     ...
;   const int nk = K / 64;
;   if (!pre) { G_LOAD(0); G_STORE(0); G_LOAD(1); }
;   for (int kt = 0; kt < nk; ++kt) {
;     __syncthreads();
;     G_COMPUTE(kt & 1, kt);
	s_waitcnt vmcnt(9)
	ds_write_b128 v148, v[160:163]
	s_waitcnt vmcnt(8)
	ds_write_b128 v148, v[164:167] offset:36864
	ds_read_b128 v[160:163], v150
	ds_read_b128 v[164:167], v150 offset:4608
	ds_read_b128 v[208:211], v149
	ds_read_b128 v[212:215], v149 offset:4608
	s_setprio 1
	s_waitcnt lgkmcnt(1)
	v_mfma_f32_32x32x16_bf16 v[96:111], v[160:163], v[208:211], v[96:111]
	v_mfma_f32_32x32x16_bf16 v[112:127], v[164:167], v[208:211], v[112:127]
	s_waitcnt lgkmcnt(0)
	v_mfma_f32_32x32x16_bf16 v[64:79], v[160:163], v[212:215], v[64:79]
	v_mfma_f32_32x32x16_bf16 v[80:95], v[164:167], v[212:215], v[80:95]
	ds_read_b128 v[208:211], v149 offset:9216
	ds_read_b128 v[212:215], v149 offset:13824
	s_waitcnt vmcnt(7)
	ds_write_b128 v148, v[184:187] offset:9216
	s_waitcnt vmcnt(6)
	ds_write_b128 v148, v[188:191] offset:46080
	ds_read_b128 v[184:187], v150 offset:32
	ds_read_b128 v[188:191], v150 offset:4640
	s_waitcnt lgkmcnt(5)
	v_mfma_f32_32x32x16_bf16 v[32:47], v[160:163], v[208:211], v[32:47]
	v_mfma_f32_32x32x16_bf16 v[48:63], v[164:167], v[208:211], v[48:63]
	ds_read_b128 v[208:211], v149 offset:32
	s_waitcnt lgkmcnt(5)
	v_mfma_f32_32x32x16_bf16 v[0:15], v[160:163], v[212:215], v[0:15]
	v_mfma_f32_32x32x16_bf16 v[16:31], v[164:167], v[212:215], v[16:31]
	ds_read_b128 v[212:215], v149 offset:4640
	s_setprio 0
	global_load_dwordx4 v[160:163], v[140:141], off offset:3712
	global_load_dwordx4 v[164:167], v[142:143], off offset:3712
	s_setprio 1
	s_waitcnt lgkmcnt(1)
	v_mfma_f32_32x32x16_bf16 v[96:111], v[184:187], v[208:211], v[96:111]
	v_mfma_f32_32x32x16_bf16 v[112:127], v[188:191], v[208:211], v[112:127]
	s_waitcnt lgkmcnt(0)
	v_mfma_f32_32x32x16_bf16 v[64:79], v[184:187], v[212:215], v[64:79]
	v_mfma_f32_32x32x16_bf16 v[80:95], v[188:191], v[212:215], v[80:95]
	ds_read_b128 v[208:211], v149 offset:9248
	ds_read_b128 v[212:215], v149 offset:13856
	s_waitcnt vmcnt(7)
	ds_write_b128 v148, v[194:197] offset:18432
	s_waitcnt vmcnt(6)
	ds_write_b128 v148, v[198:201] offset:55296
	ds_read_b128 v[194:197], v150 offset:64
	ds_read_b128 v[198:201], v150 offset:4672
	s_waitcnt lgkmcnt(5)
	v_mfma_f32_32x32x16_bf16 v[32:47], v[184:187], v[208:211], v[32:47]
	v_mfma_f32_32x32x16_bf16 v[48:63], v[188:191], v[208:211], v[48:63]
	ds_read_b128 v[208:211], v149 offset:64
	s_waitcnt lgkmcnt(5)
	v_mfma_f32_32x32x16_bf16 v[0:15], v[184:187], v[212:215], v[0:15]
	v_mfma_f32_32x32x16_bf16 v[16:31], v[188:191], v[212:215], v[16:31]
	ds_read_b128 v[212:215], v149 offset:4672
	s_setprio 0
	global_load_dwordx4 v[184:187], v[132:133], off offset:3712
	global_load_dwordx4 v[188:191], v[134:135], off offset:3712
	s_setprio 1
	s_waitcnt lgkmcnt(1)
	v_mfma_f32_32x32x16_bf16 v[96:111], v[194:197], v[208:211], v[96:111]
	v_mfma_f32_32x32x16_bf16 v[112:127], v[198:201], v[208:211], v[112:127]
	s_waitcnt lgkmcnt(0)
	v_mfma_f32_32x32x16_bf16 v[64:79], v[194:197], v[212:215], v[64:79]
	v_mfma_f32_32x32x16_bf16 v[80:95], v[198:201], v[212:215], v[80:95]
	ds_read_b128 v[208:211], v149 offset:9280
	ds_read_b128 v[212:215], v149 offset:13888
	s_waitcnt vmcnt(7)
	ds_write_b128 v148, v[176:179] offset:27648
	s_waitcnt vmcnt(6)
	ds_write_b128 v148, v[180:183] offset:64512
	ds_read_b128 v[176:179], v150 offset:96
	ds_read_b128 v[180:183], v150 offset:4704
	s_waitcnt lgkmcnt(5)
	v_mfma_f32_32x32x16_bf16 v[32:47], v[194:197], v[208:211], v[32:47]
	v_mfma_f32_32x32x16_bf16 v[48:63], v[198:201], v[208:211], v[48:63]
	ds_read_b128 v[208:211], v149 offset:96
	s_waitcnt lgkmcnt(5)
	v_mfma_f32_32x32x16_bf16 v[0:15], v[194:197], v[212:215], v[0:15]
	v_mfma_f32_32x32x16_bf16 v[16:31], v[198:201], v[212:215], v[16:31]
	ds_read_b128 v[212:215], v149 offset:4704
	s_setprio 0
	global_load_dwordx4 v[194:197], v[144:145], off offset:3712
	global_load_dwordx4 v[198:201], v[146:147], off offset:3712
	s_setprio 1
	s_waitcnt lgkmcnt(1)
	v_mfma_f32_32x32x16_bf16 v[96:111], v[176:179], v[208:211], v[96:111]
	v_mfma_f32_32x32x16_bf16 v[112:127], v[180:183], v[208:211], v[112:127]
	s_waitcnt lgkmcnt(0)
	v_mfma_f32_32x32x16_bf16 v[64:79], v[176:179], v[212:215], v[64:79]
	v_mfma_f32_32x32x16_bf16 v[80:95], v[180:183], v[212:215], v[80:95]
	ds_read_b128 v[208:211], v149 offset:9312
	ds_read_b128 v[212:215], v149 offset:13920
	s_waitcnt lgkmcnt(1)
	v_mfma_f32_32x32x16_bf16 v[32:47], v[176:179], v[208:211], v[32:47]
	v_mfma_f32_32x32x16_bf16 v[48:63], v[180:183], v[208:211], v[48:63]
	s_waitcnt lgkmcnt(0)
	v_mfma_f32_32x32x16_bf16 v[0:15], v[176:179], v[212:215], v[0:15]
	v_mfma_f32_32x32x16_bf16 v[16:31], v[180:183], v[212:215], v[16:31]
	s_setprio 0
	global_load_dwordx4 v[176:179], v[136:137], off offset:3840
	global_load_dwordx4 v[180:183], v[138:139], off offset:3840
	s_barrier
; template <bool trans>
; DI void gemm_core(const GTile& tl, const GTile& nx, bool has_next  , bool chain  , bool pre, u32x4 (&ra)[4], u32x4 (&rb)[4], char* smem, f32x16 (&acc)[2][4]) {
;     ...
;   const int nk = K / 64;
;   if (!pre) { G_LOAD(0); G_STORE(0); G_LOAD(1); }
;   for (int kt = 0; kt < nk; ++kt) {
;     __syncthreads();
;     G_COMPUTE(kt & 1, kt);
	s_waitcnt vmcnt(9)
	ds_write_b128 v192, v[168:171]
	s_waitcnt vmcnt(8)
	ds_write_b128 v159, v[172:175]
	ds_read_b128 v[168:171], v152 offset:36864
	ds_read_b128 v[172:175], v152 offset:41472
	ds_read_b128 v[208:211], v151
	ds_read_b128 v[212:215], v151 offset:4608
	s_setprio 1
	s_waitcnt lgkmcnt(1)
	v_mfma_f32_32x32x16_bf16 v[96:111], v[168:171], v[208:211], v[96:111]
	v_mfma_f32_32x32x16_bf16 v[112:127], v[172:175], v[208:211], v[112:127]
	s_waitcnt lgkmcnt(0)
	v_mfma_f32_32x32x16_bf16 v[64:79], v[168:171], v[212:215], v[64:79]
	v_mfma_f32_32x32x16_bf16 v[80:95], v[172:175], v[212:215], v[80:95]
	ds_read_b128 v[208:211], v151 offset:9216
	ds_read_b128 v[212:215], v151 offset:13824
	s_waitcnt lgkmcnt(1)
	v_mfma_f32_32x32x16_bf16 v[32:47], v[168:171], v[208:211], v[32:47]
	v_mfma_f32_32x32x16_bf16 v[48:63], v[172:175], v[208:211], v[48:63]
	s_waitcnt lgkmcnt(0)
	v_mfma_f32_32x32x16_bf16 v[0:15], v[168:171], v[212:215], v[0:15]
	v_mfma_f32_32x32x16_bf16 v[16:31], v[172:175], v[212:215], v[16:31]
	s_setprio 0
	global_load_dwordx4 v[208:211], v[140:141], off offset:3840
	global_load_dwordx4 v[212:215], v[142:143], off offset:3840
	s_waitcnt vmcnt(9)
	ds_write_b128 v158, v[160:163]
	s_waitcnt vmcnt(8)
	ds_write_b128 v157, v[164:167]
	ds_read_b128 v[160:163], v152 offset:36896
	ds_read_b128 v[164:167], v152 offset:41504
	ds_read_b128 v[168:171], v151 offset:32
	ds_read_b128 v[172:175], v151 offset:4640
	s_setprio 1
	s_waitcnt lgkmcnt(1)
	v_mfma_f32_32x32x16_bf16 v[96:111], v[160:163], v[168:171], v[96:111]
	v_mfma_f32_32x32x16_bf16 v[112:127], v[164:167], v[168:171], v[112:127]
	s_waitcnt lgkmcnt(0)
	v_mfma_f32_32x32x16_bf16 v[64:79], v[160:163], v[172:175], v[64:79]
	v_mfma_f32_32x32x16_bf16 v[80:95], v[164:167], v[172:175], v[80:95]
	ds_read_b128 v[168:171], v151 offset:9248
	ds_read_b128 v[172:175], v151 offset:13856
	s_waitcnt lgkmcnt(1)
	v_mfma_f32_32x32x16_bf16 v[32:47], v[160:163], v[168:171], v[32:47]
	v_mfma_f32_32x32x16_bf16 v[48:63], v[164:167], v[168:171], v[48:63]
	s_waitcnt lgkmcnt(0)
	v_mfma_f32_32x32x16_bf16 v[0:15], v[160:163], v[172:175], v[0:15]
	v_mfma_f32_32x32x16_bf16 v[16:31], v[164:167], v[172:175], v[16:31]
	s_setprio 0
	global_load_dwordx4 v[216:219], v[132:133], off offset:3840
	global_load_dwordx4 v[220:223], v[134:135], off offset:3840
	s_waitcnt vmcnt(9)
	ds_write_b128 v154, v[184:187]
	s_waitcnt vmcnt(8)
	ds_write_b128 v153, v[188:191]
	ds_read_b128 v[160:163], v152 offset:36928
	ds_read_b128 v[164:167], v152 offset:41536
	ds_read_b128 v[168:171], v151 offset:64
	ds_read_b128 v[172:175], v151 offset:4672
	s_setprio 1
	s_waitcnt lgkmcnt(1)
	v_mfma_f32_32x32x16_bf16 v[96:111], v[160:163], v[168:171], v[96:111]
	v_mfma_f32_32x32x16_bf16 v[112:127], v[164:167], v[168:171], v[112:127]
	s_waitcnt lgkmcnt(0)
	v_mfma_f32_32x32x16_bf16 v[64:79], v[160:163], v[172:175], v[64:79]
	v_mfma_f32_32x32x16_bf16 v[80:95], v[164:167], v[172:175], v[80:95]
	ds_read_b128 v[168:171], v151 offset:9280
	ds_read_b128 v[172:175], v151 offset:13888
	s_waitcnt lgkmcnt(1)
	v_mfma_f32_32x32x16_bf16 v[32:47], v[160:163], v[168:171], v[32:47]
	v_mfma_f32_32x32x16_bf16 v[48:63], v[164:167], v[168:171], v[48:63]
	s_waitcnt lgkmcnt(0)
	v_mfma_f32_32x32x16_bf16 v[0:15], v[160:163], v[172:175], v[0:15]
	v_mfma_f32_32x32x16_bf16 v[16:31], v[164:167], v[172:175], v[16:31]
	s_setprio 0
	global_load_dwordx4 v[224:227], v[144:145], off offset:3840
	global_load_dwordx4 v[228:231], v[146:147], off offset:3840
	s_waitcnt vmcnt(9)
	ds_write_b128 v156, v[194:197]
	s_waitcnt vmcnt(8)
	ds_write_b128 v155, v[198:201]
	ds_read_b128 v[160:163], v152 offset:36960
	ds_read_b128 v[164:167], v152 offset:41568
	ds_read_b128 v[168:171], v151 offset:96
	ds_read_b128 v[172:175], v151 offset:4704
	s_setprio 1
	s_waitcnt lgkmcnt(1)
	v_mfma_f32_32x32x16_bf16 v[96:111], v[160:163], v[168:171], v[96:111]
	v_mfma_f32_32x32x16_bf16 v[112:127], v[164:167], v[168:171], v[112:127]
	s_waitcnt lgkmcnt(0)
	v_mfma_f32_32x32x16_bf16 v[64:79], v[160:163], v[172:175], v[64:79]
	v_mfma_f32_32x32x16_bf16 v[80:95], v[164:167], v[172:175], v[80:95]
	ds_read_b128 v[168:171], v151 offset:9312
	ds_read_b128 v[172:175], v151 offset:13920
	s_waitcnt lgkmcnt(1)
	v_mfma_f32_32x32x16_bf16 v[32:47], v[160:163], v[168:171], v[32:47]
	v_mfma_f32_32x32x16_bf16 v[48:63], v[164:167], v[168:171], v[48:63]
	s_waitcnt lgkmcnt(0)
	v_mfma_f32_32x32x16_bf16 v[0:15], v[160:163], v[172:175], v[0:15]
	v_mfma_f32_32x32x16_bf16 v[16:31], v[164:167], v[172:175], v[16:31]
	s_setprio 0
	global_load_dwordx4 v[160:163], v[136:137], off offset:3968
	global_load_dwordx4 v[164:167], v[138:139], off offset:3968
	s_barrier
; template <bool trans>
; DI void gemm_core(const GTile& tl, const GTile& nx, bool has_next  , bool chain  , bool pre, u32x4 (&ra)[4], u32x4 (&rb)[4], char* smem, f32x16 (&acc)[2][4]) {
;     ...
;   const int nk = K / 64;
;   if (!pre) { G_LOAD(0); G_STORE(0); G_LOAD(1); }
;   for (int kt = 0; kt < nk; ++kt) {
;     __syncthreads();
;     G_COMPUTE(kt & 1, kt);
;   }
;   if (!has_next) __syncthreads();
	s_waitcnt vmcnt(9)
	ds_write_b128 v148, v[176:179]
	s_waitcnt vmcnt(8)
	ds_write_b128 v148, v[180:183] offset:36864
	ds_read_b128 v[136:139], v150
	ds_read_b128 v[168:171], v150 offset:4608
	ds_read_b128 v[172:175], v149
	ds_read_b128 v[176:179], v149 offset:4608
	s_setprio 1
	s_waitcnt lgkmcnt(1)
	v_mfma_f32_32x32x16_bf16 v[96:111], v[136:139], v[172:175], v[96:111]
	v_mfma_f32_32x32x16_bf16 v[112:127], v[168:171], v[172:175], v[112:127]
	s_waitcnt lgkmcnt(0)
	v_mfma_f32_32x32x16_bf16 v[64:79], v[136:139], v[176:179], v[64:79]
	v_mfma_f32_32x32x16_bf16 v[80:95], v[168:171], v[176:179], v[80:95]
	ds_read_b128 v[172:175], v149 offset:9216
	ds_read_b128 v[176:179], v149 offset:13824
	s_waitcnt lgkmcnt(1)
	v_mfma_f32_32x32x16_bf16 v[32:47], v[136:139], v[172:175], v[32:47]
	v_mfma_f32_32x32x16_bf16 v[48:63], v[168:171], v[172:175], v[48:63]
	s_waitcnt lgkmcnt(0)
	v_mfma_f32_32x32x16_bf16 v[0:15], v[136:139], v[176:179], v[0:15]
	v_mfma_f32_32x32x16_bf16 v[16:31], v[168:171], v[176:179], v[16:31]
	s_setprio 0
	global_load_dwordx4 v[168:171], v[140:141], off offset:3968
	global_load_dwordx4 v[172:175], v[142:143], off offset:3968
	s_waitcnt vmcnt(9)
	ds_write_b128 v148, v[208:211] offset:9216
	s_waitcnt vmcnt(8)
	ds_write_b128 v148, v[212:215] offset:46080
	ds_read_b128 v[136:139], v150 offset:32
	ds_read_b128 v[140:143], v150 offset:4640
	ds_read_b128 v[176:179], v149 offset:32
	ds_read_b128 v[180:183], v149 offset:4640
	s_setprio 1
	s_waitcnt lgkmcnt(1)
	v_mfma_f32_32x32x16_bf16 v[96:111], v[136:139], v[176:179], v[96:111]
	v_mfma_f32_32x32x16_bf16 v[112:127], v[140:143], v[176:179], v[112:127]
	s_waitcnt lgkmcnt(0)
	v_mfma_f32_32x32x16_bf16 v[64:79], v[136:139], v[180:183], v[64:79]
	v_mfma_f32_32x32x16_bf16 v[80:95], v[140:143], v[180:183], v[80:95]
	ds_read_b128 v[176:179], v149 offset:9248
	ds_read_b128 v[180:183], v149 offset:13856
	s_waitcnt lgkmcnt(1)
	v_mfma_f32_32x32x16_bf16 v[32:47], v[136:139], v[176:179], v[32:47]
	v_mfma_f32_32x32x16_bf16 v[48:63], v[140:143], v[176:179], v[48:63]
	s_waitcnt lgkmcnt(0)
	v_mfma_f32_32x32x16_bf16 v[0:15], v[136:139], v[180:183], v[0:15]
	v_mfma_f32_32x32x16_bf16 v[16:31], v[140:143], v[180:183], v[16:31]
	s_setprio 0
	global_load_dwordx4 v[176:179], v[132:133], off offset:3968
	global_load_dwordx4 v[180:183], v[134:135], off offset:3968
	s_waitcnt vmcnt(9)
	ds_write_b128 v148, v[216:219] offset:18432
	s_waitcnt vmcnt(8)
	ds_write_b128 v148, v[220:223] offset:55296
	ds_read_b128 v[132:135], v150 offset:64
	ds_read_b128 v[136:139], v150 offset:4672
	ds_read_b128 v[140:143], v149 offset:64
	ds_read_b128 v[184:187], v149 offset:4672
	s_setprio 1
	s_waitcnt lgkmcnt(1)
	v_mfma_f32_32x32x16_bf16 v[96:111], v[132:135], v[140:143], v[96:111]
	v_mfma_f32_32x32x16_bf16 v[112:127], v[136:139], v[140:143], v[112:127]
	s_waitcnt lgkmcnt(0)
	v_mfma_f32_32x32x16_bf16 v[64:79], v[132:135], v[184:187], v[64:79]
	v_mfma_f32_32x32x16_bf16 v[80:95], v[136:139], v[184:187], v[80:95]
	ds_read_b128 v[140:143], v149 offset:9280
	ds_read_b128 v[184:187], v149 offset:13888
	s_waitcnt lgkmcnt(1)
	v_mfma_f32_32x32x16_bf16 v[32:47], v[132:135], v[140:143], v[32:47]
	v_mfma_f32_32x32x16_bf16 v[48:63], v[136:139], v[140:143], v[48:63]
	s_waitcnt lgkmcnt(0)
	v_mfma_f32_32x32x16_bf16 v[0:15], v[132:135], v[184:187], v[0:15]
	v_mfma_f32_32x32x16_bf16 v[16:31], v[136:139], v[184:187], v[16:31]
	s_setprio 0
	global_load_dwordx4 v[184:187], v[144:145], off offset:3968
	global_load_dwordx4 v[188:191], v[146:147], off offset:3968
	s_waitcnt vmcnt(9)
	ds_write_b128 v148, v[224:227] offset:27648
	s_waitcnt vmcnt(8)
	ds_write_b128 v148, v[228:231] offset:64512
	ds_read_b128 v[132:135], v150 offset:96
	ds_read_b128 v[136:139], v150 offset:4704
	ds_read_b128 v[140:143], v149 offset:96
	ds_read_b128 v[144:147], v149 offset:4704
	s_setprio 1
	s_waitcnt lgkmcnt(1)
	v_mfma_f32_32x32x16_bf16 v[96:111], v[132:135], v[140:143], v[96:111]
	v_mfma_f32_32x32x16_bf16 v[112:127], v[136:139], v[140:143], v[112:127]
	s_waitcnt lgkmcnt(0)
	v_mfma_f32_32x32x16_bf16 v[64:79], v[132:135], v[144:147], v[64:79]
	v_mfma_f32_32x32x16_bf16 v[80:95], v[136:139], v[144:147], v[80:95]
	ds_read_b128 v[140:143], v149 offset:9312
	ds_read_b128 v[144:147], v149 offset:13920
	s_waitcnt lgkmcnt(1)
	v_mfma_f32_32x32x16_bf16 v[32:47], v[132:135], v[140:143], v[32:47]
	v_mfma_f32_32x32x16_bf16 v[48:63], v[136:139], v[140:143], v[48:63]
	s_waitcnt lgkmcnt(0)
	v_mfma_f32_32x32x16_bf16 v[0:15], v[132:135], v[144:147], v[0:15]
	v_mfma_f32_32x32x16_bf16 v[16:31], v[136:139], v[144:147], v[16:31]
	s_setprio 0
	v_cndmask_b32_e64 v132, 0, 1, s[34:35]
	v_cmp_ne_u32_e64 s[6:7], 1, v132
	s_andn2_b64 vcc, exec, s[34:35]
	s_barrier
	s_waitcnt vmcnt(7)
	ds_write_b128 v192, v[160:163]
	s_waitcnt vmcnt(6)
	ds_write_b128 v159, v[164:167]
	s_cbranch_vccnz .LBB0_892
	global_load_dwordx4 v[160:163], v[130:131], off
	global_load_dwordx4 v[164:167], v[128:129], off

; template <bool trans>
; DI void gemm_core(const GTile& tl, const GTile& nx, bool has_next  , bool chain  , bool pre, u32x4 (&ra)[4], u32x4 (&rb)[4], char* smem, f32x16 (&acc)[2][4]) {
;     ...
;   const int lrow = tid >> 3, kc = tid & 7;
;   const unsigned aoff = (unsigned)(lrow * lda + kc * 8) * 2u, boff = (unsigned)(lrow * ldb + kc * 8) * 2u;
;   const char* ag = (const char*)(A + (size_t)m0 * lda);
;   const char* bg = (const char*)(Bt + (size_t)n0 * ldb);
;   const unsigned aoffn = (unsigned)(lrow * nx.lda + kc * 8) * 2u, boffn = (unsigned)(lrow * nx.ldb + kc * 8) * 2u;
;   const char* agn = (const char*)(nx.A + (size_t)nx.m0 * nx.lda);
;   const char* bgn = (const char*)(nx.Bt + (size_t)nx.n0 * nx.ldb);
;     ...
;   const int nk = K / 64;
;   if (!pre) { G_LOAD(0); G_STORE(0); G_LOAD(1); }
;   for (int kt = 0; kt < nk; ++kt) {
;     __syncthreads();
;     G_COMPUTE(kt & 1, kt);
.LBB0_1637:
	v_lshl_add_u64 v[128:129], s[2:3], 0, v[184:185]
	v_lshl_add_u64 v[132:133], s[4:5], 0, v[184:185]
	s_waitcnt lgkmcnt(0)
	s_barrier
	global_load_dwordx4 v[200:203], v[128:129], off offset:256
	global_load_dwordx4 v[208:211], v[132:133], off offset:256
	s_add_i32 s84, s84, s96
	s_cmpk_lt_i32 s84, 0x200
	s_cselect_b64 s[12:13], -1, 0
	s_cmpk_gt_i32 s84, 0x1ff
	s_cselect_b64 s[10:11], -1, 0
	s_and_b32 s3, s24, 0x1f80000
	s_add_i32 s16, s17, s16
	s_and_b32 s2, s16, 0xffffff00
	s_and_b32 s38, s37, 0xc0
	s_lshl_b32 s3, s3, 1
	s_add_u32 s4, s28, s3
	s_addc_u32 s5, s29, 0
	s_ashr_i32 s3, s2, 31
	s_lshl_b64 s[2:3], s[2:3], 12
	s_add_u32 s2, s14, s2
	s_addc_u32 s3, s15, s3
	s_lshr_b32 s37, s37, 1
	v_and_b32_e32 v11, 31, v8
	s_and_b32 s37, s37, 0xfffff80
	v_or_b32_e32 v12, s37, v11
	v_or_b32_e32 v11, s38, v11
	v_add3_u32 v191, 16, v10, v9
	v_lshrrev_b32_e32 v8, 1, v8
	v_mul_u32_u24_e32 v131, 0x90, v11
	v_and_b32_e32 v134, 16, v8
	v_add_u32_e32 v195, 0x12000, v191
	v_mul_lo_u32 v130, v12, s33
	v_add3_u32 v192, 16, v131, v134
	v_add_u32_e32 v196, 0x1b000, v191
	ds_write_b128 v195, v[0:3]
	s_waitcnt vmcnt(5)
	ds_write_b128 v196, v[4:7]
	v_lshl_add_u64 v[188:189], s[4:5], 0, v[184:185]
	v_lshl_add_u64 v[186:187], s[2:3], 0, v[184:185]
	v_add3_u32 v184, 16, v130, v134
	ds_read_b128 v[0:3], v192 offset:36864
	ds_read_b128 v[4:7], v192 offset:41472
	ds_read_b128 v[8:11], v184
	ds_read_b128 v[12:15], v184 offset:4608
	v_lshl_add_u64 v[136:137], v[128:129], 0, s[0:1]
	v_lshl_add_u64 v[140:141], v[132:133], 0, s[0:1]
	v_lshl_add_u64 v[144:145], v[128:129], 0, s[6:7]
	v_lshl_add_u64 v[148:149], v[132:133], 0, s[6:7]
	s_setprio 1
	s_waitcnt lgkmcnt(1)
	v_mfma_f32_32x32x16_bf16 v[112:127], v[0:3], v[8:11], 0
	v_mfma_f32_32x32x16_bf16 v[48:63], v[4:7], v[8:11], 0
	s_waitcnt lgkmcnt(0)
	v_mfma_f32_32x32x16_bf16 v[96:111], v[0:3], v[12:15], 0
	v_mfma_f32_32x32x16_bf16 v[32:47], v[4:7], v[12:15], 0
	ds_read_b128 v[8:11], v184 offset:9216
	ds_read_b128 v[12:15], v184 offset:13824
	s_waitcnt lgkmcnt(1)
	v_mfma_f32_32x32x16_bf16 v[80:95], v[0:3], v[8:11], 0
	v_mfma_f32_32x32x16_bf16 v[16:31], v[4:7], v[8:11], 0
	s_waitcnt lgkmcnt(0)
	v_mfma_f32_32x32x16_bf16 v[64:79], v[0:3], v[12:15], 0
	v_mfma_f32_32x32x16_bf16 v[0:15], v[4:7], v[12:15], 0
	s_setprio 0
	global_load_dwordx4 v[212:215], v[136:137], off offset:256
	global_load_dwordx4 v[216:219], v[140:141], off offset:256
	v_add_u32_e32 v194, 0x14400, v191
	v_add_u32_e32 v193, 0x1d400, v191
	ds_write_b128 v194, v[176:179]
	s_waitcnt vmcnt(6)
	ds_write_b128 v193, v[180:183]
	ds_read_b128 v[150:153], v192 offset:36896
	ds_read_b128 v[154:157], v192 offset:41504
	ds_read_b128 v[176:179], v184 offset:32
	ds_read_b128 v[180:183], v184 offset:4640
	s_setprio 1
	s_waitcnt lgkmcnt(1)
	v_mfma_f32_32x32x16_bf16 v[112:127], v[150:153], v[176:179], v[112:127]
	v_mfma_f32_32x32x16_bf16 v[48:63], v[154:157], v[176:179], v[48:63]
	s_waitcnt lgkmcnt(0)
	v_mfma_f32_32x32x16_bf16 v[96:111], v[150:153], v[180:183], v[96:111]
	v_mfma_f32_32x32x16_bf16 v[32:47], v[154:157], v[180:183], v[32:47]
	ds_read_b128 v[176:179], v184 offset:9248
	ds_read_b128 v[180:183], v184 offset:13856
	s_waitcnt lgkmcnt(1)
	v_mfma_f32_32x32x16_bf16 v[80:95], v[150:153], v[176:179], v[80:95]
	v_mfma_f32_32x32x16_bf16 v[16:31], v[154:157], v[176:179], v[16:31]
	s_waitcnt lgkmcnt(0)
	v_mfma_f32_32x32x16_bf16 v[64:79], v[150:153], v[180:183], v[64:79]
	v_mfma_f32_32x32x16_bf16 v[0:15], v[154:157], v[180:183], v[0:15]
	s_setprio 0
	global_load_dwordx4 v[178:181], v[144:145], off offset:256
	global_load_dwordx4 v[220:223], v[148:149], off offset:256
	v_add_u32_e32 v177, 0x16800, v191
	v_add_u32_e32 v176, 0x1f800, v191
	ds_write_b128 v177, v[168:171]
	s_waitcnt vmcnt(7)
	ds_write_b128 v176, v[172:175]
	ds_read_b128 v[150:153], v192 offset:36928
	ds_read_b128 v[154:157], v192 offset:41536
	ds_read_b128 v[168:171], v184 offset:64
	ds_read_b128 v[172:175], v184 offset:4672
	s_setprio 1
	s_waitcnt lgkmcnt(1)
	v_mfma_f32_32x32x16_bf16 v[112:127], v[150:153], v[168:171], v[112:127]
	v_mfma_f32_32x32x16_bf16 v[48:63], v[154:157], v[168:171], v[48:63]
	s_waitcnt lgkmcnt(0)
	v_mfma_f32_32x32x16_bf16 v[96:111], v[150:153], v[172:175], v[96:111]
	v_mfma_f32_32x32x16_bf16 v[32:47], v[154:157], v[172:175], v[32:47]
	ds_read_b128 v[168:171], v184 offset:9280
	ds_read_b128 v[172:175], v184 offset:13888
	s_waitcnt lgkmcnt(1)
	v_mfma_f32_32x32x16_bf16 v[80:95], v[150:153], v[168:171], v[80:95]
	v_mfma_f32_32x32x16_bf16 v[16:31], v[154:157], v[168:171], v[16:31]
	s_waitcnt lgkmcnt(0)
	v_mfma_f32_32x32x16_bf16 v[64:79], v[150:153], v[172:175], v[64:79]
	v_mfma_f32_32x32x16_bf16 v[0:15], v[154:157], v[172:175], v[0:15]
	s_setprio 0
	v_add_co_u32_e32 v152, vcc, s31, v128
	v_add_u32_e32 v171, 0x18c00, v191
	s_nop 0
	v_addc_co_u32_e32 v153, vcc, 0, v129, vcc
	v_add_co_u32_e32 v156, vcc, s31, v132
	v_add_u32_e32 v170, 0x21c00, v191
	s_nop 0
	v_addc_co_u32_e32 v157, vcc, 0, v133, vcc
	global_load_dwordx4 v[172:175], v[152:153], off offset:256
	global_load_dwordx4 v[224:227], v[156:157], off offset:256
	ds_write_b128 v171, v[160:163]
	s_waitcnt vmcnt(8)
	ds_write_b128 v170, v[164:167]
	ds_read_b128 v[158:161], v192 offset:36960
	ds_read_b128 v[162:165], v192 offset:41568
	ds_read_b128 v[166:169], v184 offset:96
	ds_read_b128 v[228:231], v184 offset:4704
	s_setprio 1
	s_waitcnt lgkmcnt(1)
	v_mfma_f32_32x32x16_bf16 v[112:127], v[158:161], v[166:169], v[112:127]
	v_mfma_f32_32x32x16_bf16 v[48:63], v[162:165], v[166:169], v[48:63]
	s_waitcnt lgkmcnt(0)
	v_mfma_f32_32x32x16_bf16 v[96:111], v[158:161], v[228:231], v[96:111]
	v_mfma_f32_32x32x16_bf16 v[32:47], v[162:165], v[228:231], v[32:47]
	ds_read_b128 v[166:169], v184 offset:9312
	ds_read_b128 v[228:231], v184 offset:13920
	s_waitcnt lgkmcnt(1)
	v_mfma_f32_32x32x16_bf16 v[80:95], v[158:161], v[166:169], v[80:95]
	v_mfma_f32_32x32x16_bf16 v[16:31], v[162:165], v[166:169], v[16:31]
	s_waitcnt lgkmcnt(0)
	v_mfma_f32_32x32x16_bf16 v[64:79], v[158:161], v[228:231], v[64:79]
	v_mfma_f32_32x32x16_bf16 v[0:15], v[162:165], v[228:231], v[0:15]
	s_setprio 0
	global_load_dwordx4 v[158:161], v[128:129], off offset:384
	global_load_dwordx4 v[162:165], v[132:133], off offset:384
	s_barrier
; template <bool trans>
; DI void gemm_core(const GTile& tl, const GTile& nx, bool has_next  , bool chain  , bool pre, u32x4 (&ra)[4], u32x4 (&rb)[4], char* smem, f32x16 (&acc)[2][4]) {
;     ...
;   const int nk = K / 64;
;   if (!pre) { G_LOAD(0); G_STORE(0); G_LOAD(1); }
;   for (int kt = 0; kt < nk; ++kt) {
;     __syncthreads();
;     G_COMPUTE(kt & 1, kt);
	v_add3_u32 v169, s35, v131, v134
	s_waitcnt vmcnt(9)
	ds_write_b128 v191, v[200:203]
	s_waitcnt vmcnt(8)
	ds_write_b128 v191, v[208:211] offset:36864
	v_add3_u32 v168, s34, v130, v134
	ds_read_b128 v[200:203], v169
	ds_read_b128 v[208:211], v169 offset:4608
	ds_read_b128 v[228:231], v168
	ds_read_b128 v[232:235], v168 offset:4608
	s_setprio 1
	s_waitcnt lgkmcnt(1)
	v_mfma_f32_32x32x16_bf16 v[112:127], v[200:203], v[228:231], v[112:127]
	v_mfma_f32_32x32x16_bf16 v[48:63], v[208:211], v[228:231], v[48:63]
	s_waitcnt lgkmcnt(0)
	v_mfma_f32_32x32x16_bf16 v[96:111], v[200:203], v[232:235], v[96:111]
	v_mfma_f32_32x32x16_bf16 v[32:47], v[208:211], v[232:235], v[32:47]
	ds_read_b128 v[228:231], v168 offset:9216
	ds_read_b128 v[232:235], v168 offset:13824
	s_waitcnt lgkmcnt(1)
	v_mfma_f32_32x32x16_bf16 v[80:95], v[200:203], v[228:231], v[80:95]
	v_mfma_f32_32x32x16_bf16 v[16:31], v[208:211], v[228:231], v[16:31]
	s_waitcnt lgkmcnt(0)
	v_mfma_f32_32x32x16_bf16 v[64:79], v[200:203], v[232:235], v[64:79]
	v_mfma_f32_32x32x16_bf16 v[0:15], v[208:211], v[232:235], v[0:15]
	s_setprio 0
	global_load_dwordx4 v[200:203], v[136:137], off offset:384
	global_load_dwordx4 v[208:211], v[140:141], off offset:384
	s_waitcnt vmcnt(9)
	ds_write_b128 v191, v[212:215] offset:9216
	s_waitcnt vmcnt(8)
	ds_write_b128 v191, v[216:219] offset:46080
	ds_read_b128 v[212:215], v169 offset:32
	ds_read_b128 v[216:219], v169 offset:4640
	ds_read_b128 v[228:231], v168 offset:32
	ds_read_b128 v[232:235], v168 offset:4640
	s_setprio 1
	s_waitcnt lgkmcnt(1)
	v_mfma_f32_32x32x16_bf16 v[112:127], v[212:215], v[228:231], v[112:127]
	v_mfma_f32_32x32x16_bf16 v[48:63], v[216:219], v[228:231], v[48:63]
	s_waitcnt lgkmcnt(0)
	v_mfma_f32_32x32x16_bf16 v[96:111], v[212:215], v[232:235], v[96:111]
	v_mfma_f32_32x32x16_bf16 v[32:47], v[216:219], v[232:235], v[32:47]
	ds_read_b128 v[228:231], v168 offset:9248
	ds_read_b128 v[232:235], v168 offset:13856
	s_waitcnt lgkmcnt(1)
	v_mfma_f32_32x32x16_bf16 v[80:95], v[212:215], v[228:231], v[80:95]
	v_mfma_f32_32x32x16_bf16 v[16:31], v[216:219], v[228:231], v[16:31]
	s_waitcnt lgkmcnt(0)
	v_mfma_f32_32x32x16_bf16 v[64:79], v[212:215], v[232:235], v[64:79]
	v_mfma_f32_32x32x16_bf16 v[0:15], v[216:219], v[232:235], v[0:15]
	s_setprio 0
	global_load_dwordx4 v[212:215], v[144:145], off offset:384
	global_load_dwordx4 v[216:219], v[148:149], off offset:384
	s_waitcnt vmcnt(9)
	ds_write_b128 v191, v[178:181] offset:18432
	s_waitcnt vmcnt(8)
	ds_write_b128 v191, v[220:223] offset:55296
	ds_read_b128 v[178:181], v169 offset:64
	ds_read_b128 v[220:223], v169 offset:4672
	ds_read_b128 v[228:231], v168 offset:64
	ds_read_b128 v[232:235], v168 offset:4672
	s_setprio 1
	s_waitcnt lgkmcnt(1)
	v_mfma_f32_32x32x16_bf16 v[112:127], v[178:181], v[228:231], v[112:127]
	v_mfma_f32_32x32x16_bf16 v[48:63], v[220:223], v[228:231], v[48:63]
	s_waitcnt lgkmcnt(0)
	v_mfma_f32_32x32x16_bf16 v[96:111], v[178:181], v[232:235], v[96:111]
	v_mfma_f32_32x32x16_bf16 v[32:47], v[220:223], v[232:235], v[32:47]
	ds_read_b128 v[228:231], v168 offset:9280
	ds_read_b128 v[232:235], v168 offset:13888
	s_waitcnt lgkmcnt(1)
	v_mfma_f32_32x32x16_bf16 v[80:95], v[178:181], v[228:231], v[80:95]
	v_mfma_f32_32x32x16_bf16 v[16:31], v[220:223], v[228:231], v[16:31]
	s_waitcnt lgkmcnt(0)
	v_mfma_f32_32x32x16_bf16 v[64:79], v[178:181], v[232:235], v[64:79]
	v_mfma_f32_32x32x16_bf16 v[0:15], v[220:223], v[232:235], v[0:15]
	s_setprio 0
	global_load_dwordx4 v[178:181], v[152:153], off offset:384
	global_load_dwordx4 v[220:223], v[156:157], off offset:384
	s_waitcnt vmcnt(9)
	ds_write_b128 v191, v[172:175] offset:27648
	s_waitcnt vmcnt(8)
	ds_write_b128 v191, v[224:227] offset:64512
	ds_read_b128 v[172:175], v169 offset:96
	ds_read_b128 v[224:227], v169 offset:4704
	ds_read_b128 v[228:231], v168 offset:96
	ds_read_b128 v[232:235], v168 offset:4704
	s_setprio 1
	s_waitcnt lgkmcnt(1)
	v_mfma_f32_32x32x16_bf16 v[112:127], v[172:175], v[228:231], v[112:127]
	v_mfma_f32_32x32x16_bf16 v[48:63], v[224:227], v[228:231], v[48:63]
	s_waitcnt lgkmcnt(0)
	v_mfma_f32_32x32x16_bf16 v[96:111], v[172:175], v[232:235], v[96:111]
	v_mfma_f32_32x32x16_bf16 v[32:47], v[224:227], v[232:235], v[32:47]
	ds_read_b128 v[228:231], v168 offset:9312
	ds_read_b128 v[232:235], v168 offset:13920
	s_waitcnt lgkmcnt(1)
	v_mfma_f32_32x32x16_bf16 v[80:95], v[172:175], v[228:231], v[80:95]
	v_mfma_f32_32x32x16_bf16 v[16:31], v[224:227], v[228:231], v[16:31]
	s_waitcnt lgkmcnt(0)
	v_mfma_f32_32x32x16_bf16 v[64:79], v[172:175], v[232:235], v[64:79]
	v_mfma_f32_32x32x16_bf16 v[0:15], v[224:227], v[232:235], v[0:15]
	s_setprio 0
	global_load_dwordx4 v[172:175], v[128:129], off offset:512
	global_load_dwordx4 v[224:227], v[132:133], off offset:512
	s_barrier
; template <bool trans>
; DI void gemm_core(const GTile& tl, const GTile& nx, bool has_next  , bool chain  , bool pre, u32x4 (&ra)[4], u32x4 (&rb)[4], char* smem, f32x16 (&acc)[2][4]) {
;     ...
;   const int nk = K / 64;
;   if (!pre) { G_LOAD(0); G_STORE(0); G_LOAD(1); }
;   for (int kt = 0; kt < nk; ++kt) {
;     __syncthreads();
;     G_COMPUTE(kt & 1, kt);
	s_waitcnt vmcnt(9)
	ds_write_b128 v195, v[158:161]
	s_waitcnt vmcnt(8)
	ds_write_b128 v196, v[162:165]
	ds_read_b128 v[158:161], v192 offset:36864
	ds_read_b128 v[162:165], v192 offset:41472
	ds_read_b128 v[228:231], v184
	ds_read_b128 v[232:235], v184 offset:4608
	s_setprio 1
	s_waitcnt lgkmcnt(1)
	v_mfma_f32_32x32x16_bf16 v[112:127], v[158:161], v[228:231], v[112:127]
	v_mfma_f32_32x32x16_bf16 v[48:63], v[162:165], v[228:231], v[48:63]
	s_waitcnt lgkmcnt(0)
	v_mfma_f32_32x32x16_bf16 v[96:111], v[158:161], v[232:235], v[96:111]
	v_mfma_f32_32x32x16_bf16 v[32:47], v[162:165], v[232:235], v[32:47]
	ds_read_b128 v[228:231], v184 offset:9216
	ds_read_b128 v[232:235], v184 offset:13824
	s_waitcnt vmcnt(7)
	ds_write_b128 v194, v[200:203]
	s_waitcnt vmcnt(6)
	ds_write_b128 v193, v[208:211]
	ds_read_b128 v[200:203], v192 offset:36896
	ds_read_b128 v[208:211], v192 offset:41504
	s_waitcnt lgkmcnt(5)
	v_mfma_f32_32x32x16_bf16 v[80:95], v[158:161], v[228:231], v[80:95]
	v_mfma_f32_32x32x16_bf16 v[16:31], v[162:165], v[228:231], v[16:31]
	ds_read_b128 v[228:231], v184 offset:32
	s_waitcnt lgkmcnt(5)
	v_mfma_f32_32x32x16_bf16 v[64:79], v[158:161], v[232:235], v[64:79]
	v_mfma_f32_32x32x16_bf16 v[0:15], v[162:165], v[232:235], v[0:15]
	ds_read_b128 v[232:235], v184 offset:4640
	s_setprio 0
	global_load_dwordx4 v[158:161], v[136:137], off offset:512
	global_load_dwordx4 v[162:165], v[140:141], off offset:512
	s_setprio 1
	s_waitcnt lgkmcnt(1)
	v_mfma_f32_32x32x16_bf16 v[112:127], v[200:203], v[228:231], v[112:127]
	v_mfma_f32_32x32x16_bf16 v[48:63], v[208:211], v[228:231], v[48:63]
	s_waitcnt lgkmcnt(0)
	v_mfma_f32_32x32x16_bf16 v[96:111], v[200:203], v[232:235], v[96:111]
	v_mfma_f32_32x32x16_bf16 v[32:47], v[208:211], v[232:235], v[32:47]
	ds_read_b128 v[228:231], v184 offset:9248
	ds_read_b128 v[232:235], v184 offset:13856
	s_waitcnt vmcnt(7)
	ds_write_b128 v177, v[212:215]
	s_waitcnt vmcnt(6)
	ds_write_b128 v176, v[216:219]
	ds_read_b128 v[212:215], v192 offset:36928
	ds_read_b128 v[216:219], v192 offset:41536
	s_waitcnt lgkmcnt(5)
	v_mfma_f32_32x32x16_bf16 v[80:95], v[200:203], v[228:231], v[80:95]
	v_mfma_f32_32x32x16_bf16 v[16:31], v[208:211], v[228:231], v[16:31]
	ds_read_b128 v[228:231], v184 offset:64
	s_waitcnt lgkmcnt(5)
	v_mfma_f32_32x32x16_bf16 v[64:79], v[200:203], v[232:235], v[64:79]
	v_mfma_f32_32x32x16_bf16 v[0:15], v[208:211], v[232:235], v[0:15]
	ds_read_b128 v[232:235], v184 offset:4672
	s_setprio 0
	global_load_dwordx4 v[200:203], v[144:145], off offset:512
	global_load_dwordx4 v[208:211], v[148:149], off offset:512
	s_setprio 1
	s_waitcnt lgkmcnt(1)
	v_mfma_f32_32x32x16_bf16 v[112:127], v[212:215], v[228:231], v[112:127]
	v_mfma_f32_32x32x16_bf16 v[48:63], v[216:219], v[228:231], v[48:63]
	s_waitcnt lgkmcnt(0)
	v_mfma_f32_32x32x16_bf16 v[96:111], v[212:215], v[232:235], v[96:111]
	v_mfma_f32_32x32x16_bf16 v[32:47], v[216:219], v[232:235], v[32:47]
	ds_read_b128 v[228:231], v184 offset:9280
	ds_read_b128 v[232:235], v184 offset:13888
	s_waitcnt vmcnt(7)
	ds_write_b128 v171, v[178:181]
	s_waitcnt vmcnt(6)
	ds_write_b128 v170, v[220:223]
	ds_read_b128 v[178:181], v192 offset:36960
	ds_read_b128 v[220:223], v192 offset:41568
	s_waitcnt lgkmcnt(5)
	v_mfma_f32_32x32x16_bf16 v[80:95], v[212:215], v[228:231], v[80:95]
	v_mfma_f32_32x32x16_bf16 v[16:31], v[216:219], v[228:231], v[16:31]
	ds_read_b128 v[228:231], v184 offset:96
	s_waitcnt lgkmcnt(5)
	v_mfma_f32_32x32x16_bf16 v[64:79], v[212:215], v[232:235], v[64:79]
	v_mfma_f32_32x32x16_bf16 v[0:15], v[216:219], v[232:235], v[0:15]
	ds_read_b128 v[232:235], v184 offset:4704
	s_setprio 0
	global_load_dwordx4 v[212:215], v[152:153], off offset:512
	global_load_dwordx4 v[216:219], v[156:157], off offset:512
	s_setprio 1
	s_waitcnt lgkmcnt(1)
	v_mfma_f32_32x32x16_bf16 v[112:127], v[178:181], v[228:231], v[112:127]
	v_mfma_f32_32x32x16_bf16 v[48:63], v[220:223], v[228:231], v[48:63]
	s_waitcnt lgkmcnt(0)
	v_mfma_f32_32x32x16_bf16 v[96:111], v[178:181], v[232:235], v[96:111]
	v_mfma_f32_32x32x16_bf16 v[32:47], v[220:223], v[232:235], v[32:47]
	ds_read_b128 v[228:231], v184 offset:9312
	ds_read_b128 v[232:235], v184 offset:13920
	s_waitcnt lgkmcnt(1)
	v_mfma_f32_32x32x16_bf16 v[80:95], v[178:181], v[228:231], v[80:95]
	v_mfma_f32_32x32x16_bf16 v[16:31], v[220:223], v[228:231], v[16:31]
	s_waitcnt lgkmcnt(0)
	v_mfma_f32_32x32x16_bf16 v[64:79], v[178:181], v[232:235], v[64:79]
	v_mfma_f32_32x32x16_bf16 v[0:15], v[220:223], v[232:235], v[0:15]
	s_setprio 0
	global_load_dwordx4 v[178:181], v[128:129], off offset:640
	global_load_dwordx4 v[220:223], v[132:133], off offset:640
	s_barrier
; template <bool trans>
; DI void gemm_core(const GTile& tl, const GTile& nx, bool has_next  , bool chain  , bool pre, u32x4 (&ra)[4], u32x4 (&rb)[4], char* smem, f32x16 (&acc)[2][4]) {
;     ...
;   const int nk = K / 64;
;   if (!pre) { G_LOAD(0); G_STORE(0); G_LOAD(1); }
;   for (int kt = 0; kt < nk; ++kt) {
;     __syncthreads();
;     G_COMPUTE(kt & 1, kt);
	s_waitcnt vmcnt(9)
	ds_write_b128 v191, v[172:175]
	s_waitcnt vmcnt(8)
	ds_write_b128 v191, v[224:227] offset:36864
	ds_read_b128 v[172:175], v169
	ds_read_b128 v[224:227], v169 offset:4608
	ds_read_b128 v[228:231], v168
	ds_read_b128 v[232:235], v168 offset:4608
	s_setprio 1
	s_waitcnt lgkmcnt(1)
	v_mfma_f32_32x32x16_bf16 v[112:127], v[172:175], v[228:231], v[112:127]
	v_mfma_f32_32x32x16_bf16 v[48:63], v[224:227], v[228:231], v[48:63]
	s_waitcnt lgkmcnt(0)
	v_mfma_f32_32x32x16_bf16 v[96:111], v[172:175], v[232:235], v[96:111]
	v_mfma_f32_32x32x16_bf16 v[32:47], v[224:227], v[232:235], v[32:47]
	ds_read_b128 v[228:231], v168 offset:9216
	ds_read_b128 v[232:235], v168 offset:13824
	s_waitcnt vmcnt(7)
	ds_write_b128 v191, v[158:161] offset:9216
	s_waitcnt vmcnt(6)
	ds_write_b128 v191, v[162:165] offset:46080
	ds_read_b128 v[158:161], v169 offset:32
	ds_read_b128 v[162:165], v169 offset:4640
	s_waitcnt lgkmcnt(5)
	v_mfma_f32_32x32x16_bf16 v[80:95], v[172:175], v[228:231], v[80:95]
	v_mfma_f32_32x32x16_bf16 v[16:31], v[224:227], v[228:231], v[16:31]
	ds_read_b128 v[228:231], v168 offset:32
	s_waitcnt lgkmcnt(5)
	v_mfma_f32_32x32x16_bf16 v[64:79], v[172:175], v[232:235], v[64:79]
	v_mfma_f32_32x32x16_bf16 v[0:15], v[224:227], v[232:235], v[0:15]
	ds_read_b128 v[232:235], v168 offset:4640
	s_setprio 0
	global_load_dwordx4 v[172:175], v[136:137], off offset:640
	global_load_dwordx4 v[224:227], v[140:141], off offset:640
	s_setprio 1
	s_waitcnt lgkmcnt(1)
	v_mfma_f32_32x32x16_bf16 v[112:127], v[158:161], v[228:231], v[112:127]
	v_mfma_f32_32x32x16_bf16 v[48:63], v[162:165], v[228:231], v[48:63]
	s_waitcnt lgkmcnt(0)
	v_mfma_f32_32x32x16_bf16 v[96:111], v[158:161], v[232:235], v[96:111]
	v_mfma_f32_32x32x16_bf16 v[32:47], v[162:165], v[232:235], v[32:47]
	ds_read_b128 v[228:231], v168 offset:9248
	ds_read_b128 v[232:235], v168 offset:13856
	s_waitcnt vmcnt(7)
	ds_write_b128 v191, v[200:203] offset:18432
	s_waitcnt vmcnt(6)
	ds_write_b128 v191, v[208:211] offset:55296
	ds_read_b128 v[200:203], v169 offset:64
	ds_read_b128 v[208:211], v169 offset:4672
	s_waitcnt lgkmcnt(5)
	v_mfma_f32_32x32x16_bf16 v[80:95], v[158:161], v[228:231], v[80:95]
	v_mfma_f32_32x32x16_bf16 v[16:31], v[162:165], v[228:231], v[16:31]
	ds_read_b128 v[228:231], v168 offset:64
	s_waitcnt lgkmcnt(5)
	v_mfma_f32_32x32x16_bf16 v[64:79], v[158:161], v[232:235], v[64:79]
	v_mfma_f32_32x32x16_bf16 v[0:15], v[162:165], v[232:235], v[0:15]
	ds_read_b128 v[232:235], v168 offset:4672
	s_setprio 0
	global_load_dwordx4 v[158:161], v[144:145], off offset:640
	global_load_dwordx4 v[162:165], v[148:149], off offset:640
	s_setprio 1
	s_waitcnt lgkmcnt(1)
	v_mfma_f32_32x32x16_bf16 v[112:127], v[200:203], v[228:231], v[112:127]
	v_mfma_f32_32x32x16_bf16 v[48:63], v[208:211], v[228:231], v[48:63]
	s_waitcnt lgkmcnt(0)
	v_mfma_f32_32x32x16_bf16 v[96:111], v[200:203], v[232:235], v[96:111]
	v_mfma_f32_32x32x16_bf16 v[32:47], v[208:211], v[232:235], v[32:47]
	ds_read_b128 v[228:231], v168 offset:9280
	ds_read_b128 v[232:235], v168 offset:13888
	s_waitcnt vmcnt(7)
	ds_write_b128 v191, v[212:215] offset:27648
	s_waitcnt vmcnt(6)
	ds_write_b128 v191, v[216:219] offset:64512
	ds_read_b128 v[212:215], v169 offset:96
	ds_read_b128 v[216:219], v169 offset:4704
	s_waitcnt lgkmcnt(5)
	v_mfma_f32_32x32x16_bf16 v[80:95], v[200:203], v[228:231], v[80:95]
	v_mfma_f32_32x32x16_bf16 v[16:31], v[208:211], v[228:231], v[16:31]
	ds_read_b128 v[228:231], v168 offset:96
	s_waitcnt lgkmcnt(5)
	v_mfma_f32_32x32x16_bf16 v[64:79], v[200:203], v[232:235], v[64:79]
	v_mfma_f32_32x32x16_bf16 v[0:15], v[208:211], v[232:235], v[0:15]
	ds_read_b128 v[232:235], v168 offset:4704
	s_setprio 0
	global_load_dwordx4 v[200:203], v[152:153], off offset:640
	global_load_dwordx4 v[208:211], v[156:157], off offset:640
	s_setprio 1
	s_waitcnt lgkmcnt(1)
	v_mfma_f32_32x32x16_bf16 v[112:127], v[212:215], v[228:231], v[112:127]
	v_mfma_f32_32x32x16_bf16 v[48:63], v[216:219], v[228:231], v[48:63]
	s_waitcnt lgkmcnt(0)
	v_mfma_f32_32x32x16_bf16 v[96:111], v[212:215], v[232:235], v[96:111]
	v_mfma_f32_32x32x16_bf16 v[32:47], v[216:219], v[232:235], v[32:47]
	ds_read_b128 v[228:231], v168 offset:9312
	ds_read_b128 v[232:235], v168 offset:13920
	s_waitcnt lgkmcnt(1)
	v_mfma_f32_32x32x16_bf16 v[80:95], v[212:215], v[228:231], v[80:95]
	v_mfma_f32_32x32x16_bf16 v[16:31], v[216:219], v[228:231], v[16:31]
	s_waitcnt lgkmcnt(0)
	v_mfma_f32_32x32x16_bf16 v[64:79], v[212:215], v[232:235], v[64:79]
	v_mfma_f32_32x32x16_bf16 v[0:15], v[216:219], v[232:235], v[0:15]
	s_setprio 0
	global_load_dwordx4 v[212:215], v[128:129], off offset:768
	global_load_dwordx4 v[216:219], v[132:133], off offset:768
	s_barrier
; template <bool trans>
; DI void gemm_core(const GTile& tl, const GTile& nx, bool has_next  , bool chain  , bool pre, u32x4 (&ra)[4], u32x4 (&rb)[4], char* smem, f32x16 (&acc)[2][4]) {
;     ...
;   const int nk = K / 64;
;   if (!pre) { G_LOAD(0); G_STORE(0); G_LOAD(1); }
;   for (int kt = 0; kt < nk; ++kt) {
;     __syncthreads();
;     G_COMPUTE(kt & 1, kt);
	s_waitcnt vmcnt(9)
	ds_write_b128 v195, v[178:181]
	s_waitcnt vmcnt(8)
	ds_write_b128 v196, v[220:223]
	ds_read_b128 v[178:181], v192 offset:36864
	ds_read_b128 v[220:223], v192 offset:41472
	ds_read_b128 v[228:231], v184
	ds_read_b128 v[232:235], v184 offset:4608
	s_setprio 1
	s_waitcnt lgkmcnt(1)
	v_mfma_f32_32x32x16_bf16 v[112:127], v[178:181], v[228:231], v[112:127]
	v_mfma_f32_32x32x16_bf16 v[48:63], v[220:223], v[228:231], v[48:63]
	s_waitcnt lgkmcnt(0)
	v_mfma_f32_32x32x16_bf16 v[96:111], v[178:181], v[232:235], v[96:111]
	v_mfma_f32_32x32x16_bf16 v[32:47], v[220:223], v[232:235], v[32:47]
	ds_read_b128 v[228:231], v184 offset:9216
	ds_read_b128 v[232:235], v184 offset:13824
	s_waitcnt vmcnt(7)
	ds_write_b128 v194, v[172:175]
	s_waitcnt vmcnt(6)
	ds_write_b128 v193, v[224:227]
	ds_read_b128 v[172:175], v192 offset:36896
	ds_read_b128 v[224:227], v192 offset:41504
	s_waitcnt lgkmcnt(5)
	v_mfma_f32_32x32x16_bf16 v[80:95], v[178:181], v[228:231], v[80:95]
	v_mfma_f32_32x32x16_bf16 v[16:31], v[220:223], v[228:231], v[16:31]
	ds_read_b128 v[228:231], v184 offset:32
	s_waitcnt lgkmcnt(5)
	v_mfma_f32_32x32x16_bf16 v[64:79], v[178:181], v[232:235], v[64:79]
	v_mfma_f32_32x32x16_bf16 v[0:15], v[220:223], v[232:235], v[0:15]
	ds_read_b128 v[232:235], v184 offset:4640
	s_setprio 0
	global_load_dwordx4 v[178:181], v[136:137], off offset:768
	global_load_dwordx4 v[220:223], v[140:141], off offset:768
	s_setprio 1
	s_waitcnt lgkmcnt(1)
	v_mfma_f32_32x32x16_bf16 v[112:127], v[172:175], v[228:231], v[112:127]
	v_mfma_f32_32x32x16_bf16 v[48:63], v[224:227], v[228:231], v[48:63]
	s_waitcnt lgkmcnt(0)
	v_mfma_f32_32x32x16_bf16 v[96:111], v[172:175], v[232:235], v[96:111]
	v_mfma_f32_32x32x16_bf16 v[32:47], v[224:227], v[232:235], v[32:47]
	ds_read_b128 v[228:231], v184 offset:9248
	ds_read_b128 v[232:235], v184 offset:13856
	s_waitcnt vmcnt(7)
	ds_write_b128 v177, v[158:161]
	s_waitcnt vmcnt(6)
	ds_write_b128 v176, v[162:165]
	ds_read_b128 v[158:161], v192 offset:36928
	ds_read_b128 v[162:165], v192 offset:41536
	s_waitcnt lgkmcnt(5)
	v_mfma_f32_32x32x16_bf16 v[80:95], v[172:175], v[228:231], v[80:95]
	v_mfma_f32_32x32x16_bf16 v[16:31], v[224:227], v[228:231], v[16:31]
	ds_read_b128 v[228:231], v184 offset:64
	s_waitcnt lgkmcnt(5)
	v_mfma_f32_32x32x16_bf16 v[64:79], v[172:175], v[232:235], v[64:79]
	v_mfma_f32_32x32x16_bf16 v[0:15], v[224:227], v[232:235], v[0:15]
	ds_read_b128 v[232:235], v184 offset:4672
	s_setprio 0
	global_load_dwordx4 v[172:175], v[144:145], off offset:768
	global_load_dwordx4 v[224:227], v[148:149], off offset:768
	s_setprio 1
	s_waitcnt lgkmcnt(1)
	v_mfma_f32_32x32x16_bf16 v[112:127], v[158:161], v[228:231], v[112:127]
	v_mfma_f32_32x32x16_bf16 v[48:63], v[162:165], v[228:231], v[48:63]
	s_waitcnt lgkmcnt(0)
	v_mfma_f32_32x32x16_bf16 v[96:111], v[158:161], v[232:235], v[96:111]
	v_mfma_f32_32x32x16_bf16 v[32:47], v[162:165], v[232:235], v[32:47]
	ds_read_b128 v[228:231], v184 offset:9280
	ds_read_b128 v[232:235], v184 offset:13888
	s_waitcnt vmcnt(7)
	ds_write_b128 v171, v[200:203]
	s_waitcnt vmcnt(6)
	ds_write_b128 v170, v[208:211]
	ds_read_b128 v[200:203], v192 offset:36960
	ds_read_b128 v[208:211], v192 offset:41568
	s_waitcnt lgkmcnt(5)
	v_mfma_f32_32x32x16_bf16 v[80:95], v[158:161], v[228:231], v[80:95]
	v_mfma_f32_32x32x16_bf16 v[16:31], v[162:165], v[228:231], v[16:31]
	ds_read_b128 v[228:231], v184 offset:96
	s_waitcnt lgkmcnt(5)
	v_mfma_f32_32x32x16_bf16 v[64:79], v[158:161], v[232:235], v[64:79]
	v_mfma_f32_32x32x16_bf16 v[0:15], v[162:165], v[232:235], v[0:15]
	ds_read_b128 v[232:235], v184 offset:4704
	s_setprio 0
	global_load_dwordx4 v[158:161], v[152:153], off offset:768
	global_load_dwordx4 v[162:165], v[156:157], off offset:768
	s_setprio 1
	s_waitcnt lgkmcnt(1)
	v_mfma_f32_32x32x16_bf16 v[112:127], v[200:203], v[228:231], v[112:127]
	v_mfma_f32_32x32x16_bf16 v[48:63], v[208:211], v[228:231], v[48:63]
	s_waitcnt lgkmcnt(0)
	v_mfma_f32_32x32x16_bf16 v[96:111], v[200:203], v[232:235], v[96:111]
	v_mfma_f32_32x32x16_bf16 v[32:47], v[208:211], v[232:235], v[32:47]
	ds_read_b128 v[228:231], v184 offset:9312
	ds_read_b128 v[232:235], v184 offset:13920
	s_waitcnt lgkmcnt(1)
	v_mfma_f32_32x32x16_bf16 v[80:95], v[200:203], v[228:231], v[80:95]
	v_mfma_f32_32x32x16_bf16 v[16:31], v[208:211], v[228:231], v[16:31]
	s_waitcnt lgkmcnt(0)
	v_mfma_f32_32x32x16_bf16 v[64:79], v[200:203], v[232:235], v[64:79]
	v_mfma_f32_32x32x16_bf16 v[0:15], v[208:211], v[232:235], v[0:15]
	s_setprio 0
	global_load_dwordx4 v[200:203], v[128:129], off offset:896
	global_load_dwordx4 v[208:211], v[132:133], off offset:896
	s_barrier
; template <bool trans>
; DI void gemm_core(const GTile& tl, const GTile& nx, bool has_next  , bool chain  , bool pre, u32x4 (&ra)[4], u32x4 (&rb)[4], char* smem, f32x16 (&acc)[2][4]) {
;     ...
;   const int nk = K / 64;
;   if (!pre) { G_LOAD(0); G_STORE(0); G_LOAD(1); }
;   for (int kt = 0; kt < nk; ++kt) {
;     __syncthreads();
;     G_COMPUTE(kt & 1, kt);
	s_waitcnt vmcnt(9)
	ds_write_b128 v191, v[212:215]
	s_waitcnt vmcnt(8)
	ds_write_b128 v191, v[216:219] offset:36864
	ds_read_b128 v[212:215], v169
	ds_read_b128 v[216:219], v169 offset:4608
	ds_read_b128 v[228:231], v168
	ds_read_b128 v[232:235], v168 offset:4608
	s_setprio 1
	s_waitcnt lgkmcnt(1)
	v_mfma_f32_32x32x16_bf16 v[112:127], v[212:215], v[228:231], v[112:127]
	v_mfma_f32_32x32x16_bf16 v[48:63], v[216:219], v[228:231], v[48:63]
	s_waitcnt lgkmcnt(0)
	v_mfma_f32_32x32x16_bf16 v[96:111], v[212:215], v[232:235], v[96:111]
	v_mfma_f32_32x32x16_bf16 v[32:47], v[216:219], v[232:235], v[32:47]
	ds_read_b128 v[228:231], v168 offset:9216
	ds_read_b128 v[232:235], v168 offset:13824
	s_waitcnt vmcnt(7)
	ds_write_b128 v191, v[178:181] offset:9216
	s_waitcnt vmcnt(6)
	ds_write_b128 v191, v[220:223] offset:46080
	ds_read_b128 v[178:181], v169 offset:32
	ds_read_b128 v[220:223], v169 offset:4640
	s_waitcnt lgkmcnt(5)
	v_mfma_f32_32x32x16_bf16 v[80:95], v[212:215], v[228:231], v[80:95]
	v_mfma_f32_32x32x16_bf16 v[16:31], v[216:219], v[228:231], v[16:31]
	ds_read_b128 v[228:231], v168 offset:32
	s_waitcnt lgkmcnt(5)
	v_mfma_f32_32x32x16_bf16 v[64:79], v[212:215], v[232:235], v[64:79]
	v_mfma_f32_32x32x16_bf16 v[0:15], v[216:219], v[232:235], v[0:15]
	ds_read_b128 v[232:235], v168 offset:4640
	s_setprio 0
	global_load_dwordx4 v[212:215], v[136:137], off offset:896
	global_load_dwordx4 v[216:219], v[140:141], off offset:896
	s_setprio 1
	s_waitcnt lgkmcnt(1)
	v_mfma_f32_32x32x16_bf16 v[112:127], v[178:181], v[228:231], v[112:127]
	v_mfma_f32_32x32x16_bf16 v[48:63], v[220:223], v[228:231], v[48:63]
	s_waitcnt lgkmcnt(0)
	v_mfma_f32_32x32x16_bf16 v[96:111], v[178:181], v[232:235], v[96:111]
	v_mfma_f32_32x32x16_bf16 v[32:47], v[220:223], v[232:235], v[32:47]
	ds_read_b128 v[228:231], v168 offset:9248
	ds_read_b128 v[232:235], v168 offset:13856
	s_waitcnt vmcnt(7)
	ds_write_b128 v191, v[172:175] offset:18432
	s_waitcnt vmcnt(6)
	ds_write_b128 v191, v[224:227] offset:55296
	ds_read_b128 v[172:175], v169 offset:64
	ds_read_b128 v[224:227], v169 offset:4672
	s_waitcnt lgkmcnt(5)
	v_mfma_f32_32x32x16_bf16 v[80:95], v[178:181], v[228:231], v[80:95]
	v_mfma_f32_32x32x16_bf16 v[16:31], v[220:223], v[228:231], v[16:31]
	ds_read_b128 v[228:231], v168 offset:64
	s_waitcnt lgkmcnt(5)
	v_mfma_f32_32x32x16_bf16 v[64:79], v[178:181], v[232:235], v[64:79]
	v_mfma_f32_32x32x16_bf16 v[0:15], v[220:223], v[232:235], v[0:15]
	ds_read_b128 v[232:235], v168 offset:4672
	s_setprio 0
	global_load_dwordx4 v[178:181], v[144:145], off offset:896
	global_load_dwordx4 v[220:223], v[148:149], off offset:896
	s_setprio 1
	s_waitcnt lgkmcnt(1)
	v_mfma_f32_32x32x16_bf16 v[112:127], v[172:175], v[228:231], v[112:127]
	v_mfma_f32_32x32x16_bf16 v[48:63], v[224:227], v[228:231], v[48:63]
	s_waitcnt lgkmcnt(0)
	v_mfma_f32_32x32x16_bf16 v[96:111], v[172:175], v[232:235], v[96:111]
	v_mfma_f32_32x32x16_bf16 v[32:47], v[224:227], v[232:235], v[32:47]
	ds_read_b128 v[228:231], v168 offset:9280
	ds_read_b128 v[232:235], v168 offset:13888
	s_waitcnt vmcnt(7)
	ds_write_b128 v191, v[158:161] offset:27648
	s_waitcnt vmcnt(6)
	ds_write_b128 v191, v[162:165] offset:64512
	ds_read_b128 v[158:161], v169 offset:96
	ds_read_b128 v[162:165], v169 offset:4704
	s_waitcnt lgkmcnt(5)
	v_mfma_f32_32x32x16_bf16 v[80:95], v[172:175], v[228:231], v[80:95]
	v_mfma_f32_32x32x16_bf16 v[16:31], v[224:227], v[228:231], v[16:31]
	ds_read_b128 v[228:231], v168 offset:96
	s_waitcnt lgkmcnt(5)
	v_mfma_f32_32x32x16_bf16 v[64:79], v[172:175], v[232:235], v[64:79]
	v_mfma_f32_32x32x16_bf16 v[0:15], v[224:227], v[232:235], v[0:15]
	ds_read_b128 v[232:235], v168 offset:4704
	s_setprio 0
	global_load_dwordx4 v[172:175], v[152:153], off offset:896
	global_load_dwordx4 v[224:227], v[156:157], off offset:896
	s_setprio 1
	s_waitcnt lgkmcnt(1)
	v_mfma_f32_32x32x16_bf16 v[112:127], v[158:161], v[228:231], v[112:127]
	v_mfma_f32_32x32x16_bf16 v[48:63], v[162:165], v[228:231], v[48:63]
	s_waitcnt lgkmcnt(0)
	v_mfma_f32_32x32x16_bf16 v[96:111], v[158:161], v[232:235], v[96:111]
	v_mfma_f32_32x32x16_bf16 v[32:47], v[162:165], v[232:235], v[32:47]
	ds_read_b128 v[228:231], v168 offset:9312
	ds_read_b128 v[232:235], v168 offset:13920
	s_waitcnt lgkmcnt(1)
	v_mfma_f32_32x32x16_bf16 v[80:95], v[158:161], v[228:231], v[80:95]
	v_mfma_f32_32x32x16_bf16 v[16:31], v[162:165], v[228:231], v[16:31]
	s_waitcnt lgkmcnt(0)
	v_mfma_f32_32x32x16_bf16 v[64:79], v[158:161], v[232:235], v[64:79]
	v_mfma_f32_32x32x16_bf16 v[0:15], v[162:165], v[232:235], v[0:15]
	s_setprio 0
	global_load_dwordx4 v[158:161], v[128:129], off offset:1024
	global_load_dwordx4 v[162:165], v[132:133], off offset:1024
	s_barrier
; template <bool trans>
; DI void gemm_core(const GTile& tl, const GTile& nx, bool has_next  , bool chain  , bool pre, u32x4 (&ra)[4], u32x4 (&rb)[4], char* smem, f32x16 (&acc)[2][4]) {
;     ...
;   const int nk = K / 64;
;   if (!pre) { G_LOAD(0); G_STORE(0); G_LOAD(1); }
;   for (int kt = 0; kt < nk; ++kt) {
;     __syncthreads();
;     G_COMPUTE(kt & 1, kt);
	s_waitcnt vmcnt(9)
	ds_write_b128 v195, v[200:203]
	s_waitcnt vmcnt(8)
	ds_write_b128 v196, v[208:211]
	ds_read_b128 v[200:203], v192 offset:36864
	ds_read_b128 v[208:211], v192 offset:41472
	ds_read_b128 v[228:231], v184
	ds_read_b128 v[232:235], v184 offset:4608
	s_setprio 1
	s_waitcnt lgkmcnt(1)
	v_mfma_f32_32x32x16_bf16 v[112:127], v[200:203], v[228:231], v[112:127]
	v_mfma_f32_32x32x16_bf16 v[48:63], v[208:211], v[228:231], v[48:63]
	s_waitcnt lgkmcnt(0)
	v_mfma_f32_32x32x16_bf16 v[96:111], v[200:203], v[232:235], v[96:111]
	v_mfma_f32_32x32x16_bf16 v[32:47], v[208:211], v[232:235], v[32:47]
	ds_read_b128 v[228:231], v184 offset:9216
	ds_read_b128 v[232:235], v184 offset:13824
	s_waitcnt vmcnt(7)
	ds_write_b128 v194, v[212:215]
	s_waitcnt vmcnt(6)
	ds_write_b128 v193, v[216:219]
	ds_read_b128 v[212:215], v192 offset:36896
	ds_read_b128 v[216:219], v192 offset:41504
	s_waitcnt lgkmcnt(5)
	v_mfma_f32_32x32x16_bf16 v[80:95], v[200:203], v[228:231], v[80:95]
	v_mfma_f32_32x32x16_bf16 v[16:31], v[208:211], v[228:231], v[16:31]
	ds_read_b128 v[228:231], v184 offset:32
	s_waitcnt lgkmcnt(5)
	v_mfma_f32_32x32x16_bf16 v[64:79], v[200:203], v[232:235], v[64:79]
	v_mfma_f32_32x32x16_bf16 v[0:15], v[208:211], v[232:235], v[0:15]
	ds_read_b128 v[232:235], v184 offset:4640
	s_setprio 0
	global_load_dwordx4 v[200:203], v[136:137], off offset:1024
	global_load_dwordx4 v[208:211], v[140:141], off offset:1024
	s_setprio 1
	s_waitcnt lgkmcnt(1)
	v_mfma_f32_32x32x16_bf16 v[112:127], v[212:215], v[228:231], v[112:127]
	v_mfma_f32_32x32x16_bf16 v[48:63], v[216:219], v[228:231], v[48:63]
	s_waitcnt lgkmcnt(0)
	v_mfma_f32_32x32x16_bf16 v[96:111], v[212:215], v[232:235], v[96:111]
	v_mfma_f32_32x32x16_bf16 v[32:47], v[216:219], v[232:235], v[32:47]
	ds_read_b128 v[228:231], v184 offset:9248
	ds_read_b128 v[232:235], v184 offset:13856
	s_waitcnt vmcnt(7)
	ds_write_b128 v177, v[178:181]
	s_waitcnt vmcnt(6)
	ds_write_b128 v176, v[220:223]
	ds_read_b128 v[178:181], v192 offset:36928
	ds_read_b128 v[220:223], v192 offset:41536
	s_waitcnt lgkmcnt(5)
	v_mfma_f32_32x32x16_bf16 v[80:95], v[212:215], v[228:231], v[80:95]
	v_mfma_f32_32x32x16_bf16 v[16:31], v[216:219], v[228:231], v[16:31]
	ds_read_b128 v[228:231], v184 offset:64
	s_waitcnt lgkmcnt(5)
	v_mfma_f32_32x32x16_bf16 v[64:79], v[212:215], v[232:235], v[64:79]
	v_mfma_f32_32x32x16_bf16 v[0:15], v[216:219], v[232:235], v[0:15]
	ds_read_b128 v[232:235], v184 offset:4672
	s_setprio 0
	global_load_dwordx4 v[212:215], v[144:145], off offset:1024
	global_load_dwordx4 v[216:219], v[148:149], off offset:1024
	s_setprio 1
	s_waitcnt lgkmcnt(1)
	v_mfma_f32_32x32x16_bf16 v[112:127], v[178:181], v[228:231], v[112:127]
	v_mfma_f32_32x32x16_bf16 v[48:63], v[220:223], v[228:231], v[48:63]
	s_waitcnt lgkmcnt(0)
	v_mfma_f32_32x32x16_bf16 v[96:111], v[178:181], v[232:235], v[96:111]
	v_mfma_f32_32x32x16_bf16 v[32:47], v[220:223], v[232:235], v[32:47]
	ds_read_b128 v[228:231], v184 offset:9280
	ds_read_b128 v[232:235], v184 offset:13888
	s_waitcnt vmcnt(7)
	ds_write_b128 v171, v[172:175]
	s_waitcnt vmcnt(6)
	ds_write_b128 v170, v[224:227]
	ds_read_b128 v[172:175], v192 offset:36960
	ds_read_b128 v[224:227], v192 offset:41568
	s_waitcnt lgkmcnt(5)
	v_mfma_f32_32x32x16_bf16 v[80:95], v[178:181], v[228:231], v[80:95]
	v_mfma_f32_32x32x16_bf16 v[16:31], v[220:223], v[228:231], v[16:31]
	ds_read_b128 v[228:231], v184 offset:96
	s_waitcnt lgkmcnt(5)
	v_mfma_f32_32x32x16_bf16 v[64:79], v[178:181], v[232:235], v[64:79]
	v_mfma_f32_32x32x16_bf16 v[0:15], v[220:223], v[232:235], v[0:15]
	ds_read_b128 v[232:235], v184 offset:4704
	s_setprio 0
	global_load_dwordx4 v[178:181], v[152:153], off offset:1024
	global_load_dwordx4 v[220:223], v[156:157], off offset:1024
	s_setprio 1
	s_waitcnt lgkmcnt(1)
	v_mfma_f32_32x32x16_bf16 v[112:127], v[172:175], v[228:231], v[112:127]
	v_mfma_f32_32x32x16_bf16 v[48:63], v[224:227], v[228:231], v[48:63]
	s_waitcnt lgkmcnt(0)
	v_mfma_f32_32x32x16_bf16 v[96:111], v[172:175], v[232:235], v[96:111]
	v_mfma_f32_32x32x16_bf16 v[32:47], v[224:227], v[232:235], v[32:47]
	ds_read_b128 v[228:231], v184 offset:9312
	ds_read_b128 v[232:235], v184 offset:13920
	s_waitcnt lgkmcnt(1)
	v_mfma_f32_32x32x16_bf16 v[80:95], v[172:175], v[228:231], v[80:95]
	v_mfma_f32_32x32x16_bf16 v[16:31], v[224:227], v[228:231], v[16:31]
	s_waitcnt lgkmcnt(0)
	v_mfma_f32_32x32x16_bf16 v[64:79], v[172:175], v[232:235], v[64:79]
	v_mfma_f32_32x32x16_bf16 v[0:15], v[224:227], v[232:235], v[0:15]
	s_setprio 0
	global_load_dwordx4 v[172:175], v[128:129], off offset:1152
	global_load_dwordx4 v[224:227], v[132:133], off offset:1152
	s_barrier
; template <bool trans>
; DI void gemm_core(const GTile& tl, const GTile& nx, bool has_next  , bool chain  , bool pre, u32x4 (&ra)[4], u32x4 (&rb)[4], char* smem, f32x16 (&acc)[2][4]) {
;     ...
;   const int nk = K / 64;
;   if (!pre) { G_LOAD(0); G_STORE(0); G_LOAD(1); }
;   for (int kt = 0; kt < nk; ++kt) {
;     __syncthreads();
;     G_COMPUTE(kt & 1, kt);
	s_waitcnt vmcnt(9)
	ds_write_b128 v191, v[158:161]
	s_waitcnt vmcnt(8)
	ds_write_b128 v191, v[162:165] offset:36864
	ds_read_b128 v[158:161], v169
	ds_read_b128 v[162:165], v169 offset:4608
	ds_read_b128 v[228:231], v168
	ds_read_b128 v[232:235], v168 offset:4608
	s_setprio 1
	s_waitcnt lgkmcnt(1)
	v_mfma_f32_32x32x16_bf16 v[112:127], v[158:161], v[228:231], v[112:127]
	v_mfma_f32_32x32x16_bf16 v[48:63], v[162:165], v[228:231], v[48:63]
	s_waitcnt lgkmcnt(0)
	v_mfma_f32_32x32x16_bf16 v[96:111], v[158:161], v[232:235], v[96:111]
	v_mfma_f32_32x32x16_bf16 v[32:47], v[162:165], v[232:235], v[32:47]
	ds_read_b128 v[228:231], v168 offset:9216
	ds_read_b128 v[232:235], v168 offset:13824
	s_waitcnt vmcnt(7)
	ds_write_b128 v191, v[200:203] offset:9216
	s_waitcnt vmcnt(6)
	ds_write_b128 v191, v[208:211] offset:46080
	ds_read_b128 v[200:203], v169 offset:32
	ds_read_b128 v[208:211], v169 offset:4640
	s_waitcnt lgkmcnt(5)
	v_mfma_f32_32x32x16_bf16 v[80:95], v[158:161], v[228:231], v[80:95]
	v_mfma_f32_32x32x16_bf16 v[16:31], v[162:165], v[228:231], v[16:31]
	ds_read_b128 v[228:231], v168 offset:32
	s_waitcnt lgkmcnt(5)
	v_mfma_f32_32x32x16_bf16 v[64:79], v[158:161], v[232:235], v[64:79]
	v_mfma_f32_32x32x16_bf16 v[0:15], v[162:165], v[232:235], v[0:15]
	ds_read_b128 v[232:235], v168 offset:4640
	s_setprio 0
	global_load_dwordx4 v[158:161], v[136:137], off offset:1152
	global_load_dwordx4 v[162:165], v[140:141], off offset:1152
	s_setprio 1
	s_waitcnt lgkmcnt(1)
	v_mfma_f32_32x32x16_bf16 v[112:127], v[200:203], v[228:231], v[112:127]
	v_mfma_f32_32x32x16_bf16 v[48:63], v[208:211], v[228:231], v[48:63]
	s_waitcnt lgkmcnt(0)
	v_mfma_f32_32x32x16_bf16 v[96:111], v[200:203], v[232:235], v[96:111]
	v_mfma_f32_32x32x16_bf16 v[32:47], v[208:211], v[232:235], v[32:47]
	ds_read_b128 v[228:231], v168 offset:9248
	ds_read_b128 v[232:235], v168 offset:13856
	s_waitcnt vmcnt(7)
	ds_write_b128 v191, v[212:215] offset:18432
	s_waitcnt vmcnt(6)
	ds_write_b128 v191, v[216:219] offset:55296
	ds_read_b128 v[212:215], v169 offset:64
	ds_read_b128 v[216:219], v169 offset:4672
	s_waitcnt lgkmcnt(5)
	v_mfma_f32_32x32x16_bf16 v[80:95], v[200:203], v[228:231], v[80:95]
	v_mfma_f32_32x32x16_bf16 v[16:31], v[208:211], v[228:231], v[16:31]
	ds_read_b128 v[228:231], v168 offset:64
	s_waitcnt lgkmcnt(5)
	v_mfma_f32_32x32x16_bf16 v[64:79], v[200:203], v[232:235], v[64:79]
	v_mfma_f32_32x32x16_bf16 v[0:15], v[208:211], v[232:235], v[0:15]
	ds_read_b128 v[232:235], v168 offset:4672
	s_setprio 0
	global_load_dwordx4 v[200:203], v[144:145], off offset:1152
	global_load_dwordx4 v[208:211], v[148:149], off offset:1152
	s_setprio 1
	s_waitcnt lgkmcnt(1)
	v_mfma_f32_32x32x16_bf16 v[112:127], v[212:215], v[228:231], v[112:127]
	v_mfma_f32_32x32x16_bf16 v[48:63], v[216:219], v[228:231], v[48:63]
	s_waitcnt lgkmcnt(0)
	v_mfma_f32_32x32x16_bf16 v[96:111], v[212:215], v[232:235], v[96:111]
	v_mfma_f32_32x32x16_bf16 v[32:47], v[216:219], v[232:235], v[32:47]
	ds_read_b128 v[228:231], v168 offset:9280
	ds_read_b128 v[232:235], v168 offset:13888
	s_waitcnt vmcnt(7)
	ds_write_b128 v191, v[178:181] offset:27648
	s_waitcnt vmcnt(6)
	ds_write_b128 v191, v[220:223] offset:64512
	ds_read_b128 v[178:181], v169 offset:96
	ds_read_b128 v[220:223], v169 offset:4704
	s_waitcnt lgkmcnt(5)
	v_mfma_f32_32x32x16_bf16 v[80:95], v[212:215], v[228:231], v[80:95]
	v_mfma_f32_32x32x16_bf16 v[16:31], v[216:219], v[228:231], v[16:31]
	ds_read_b128 v[228:231], v168 offset:96
	s_waitcnt lgkmcnt(5)
	v_mfma_f32_32x32x16_bf16 v[64:79], v[212:215], v[232:235], v[64:79]
	v_mfma_f32_32x32x16_bf16 v[0:15], v[216:219], v[232:235], v[0:15]
	ds_read_b128 v[232:235], v168 offset:4704
	s_setprio 0
	global_load_dwordx4 v[212:215], v[152:153], off offset:1152
	global_load_dwordx4 v[216:219], v[156:157], off offset:1152
	s_setprio 1
	s_waitcnt lgkmcnt(1)
	v_mfma_f32_32x32x16_bf16 v[112:127], v[178:181], v[228:231], v[112:127]
	v_mfma_f32_32x32x16_bf16 v[48:63], v[220:223], v[228:231], v[48:63]
	s_waitcnt lgkmcnt(0)
	v_mfma_f32_32x32x16_bf16 v[96:111], v[178:181], v[232:235], v[96:111]
	v_mfma_f32_32x32x16_bf16 v[32:47], v[220:223], v[232:235], v[32:47]
	ds_read_b128 v[228:231], v168 offset:9312
	ds_read_b128 v[232:235], v168 offset:13920
	s_waitcnt lgkmcnt(1)
	v_mfma_f32_32x32x16_bf16 v[80:95], v[178:181], v[228:231], v[80:95]
	v_mfma_f32_32x32x16_bf16 v[16:31], v[220:223], v[228:231], v[16:31]
	s_waitcnt lgkmcnt(0)
	v_mfma_f32_32x32x16_bf16 v[64:79], v[178:181], v[232:235], v[64:79]
	v_mfma_f32_32x32x16_bf16 v[0:15], v[220:223], v[232:235], v[0:15]
	s_setprio 0
	global_load_dwordx4 v[178:181], v[128:129], off offset:1280
	global_load_dwordx4 v[220:223], v[132:133], off offset:1280
	s_barrier
; template <bool trans>
; DI void gemm_core(const GTile& tl, const GTile& nx, bool has_next  , bool chain  , bool pre, u32x4 (&ra)[4], u32x4 (&rb)[4], char* smem, f32x16 (&acc)[2][4]) {
;     ...
;   const int nk = K / 64;
;   if (!pre) { G_LOAD(0); G_STORE(0); G_LOAD(1); }
;   for (int kt = 0; kt < nk; ++kt) {
;     __syncthreads();
;     G_COMPUTE(kt & 1, kt);
	s_waitcnt vmcnt(9)
	ds_write_b128 v195, v[172:175]
	s_waitcnt vmcnt(8)
	ds_write_b128 v196, v[224:227]
	ds_read_b128 v[172:175], v192 offset:36864
	ds_read_b128 v[224:227], v192 offset:41472
	ds_read_b128 v[228:231], v184
	ds_read_b128 v[232:235], v184 offset:4608
	s_setprio 1
	s_waitcnt lgkmcnt(1)
	v_mfma_f32_32x32x16_bf16 v[112:127], v[172:175], v[228:231], v[112:127]
	v_mfma_f32_32x32x16_bf16 v[48:63], v[224:227], v[228:231], v[48:63]
	s_waitcnt lgkmcnt(0)
	v_mfma_f32_32x32x16_bf16 v[96:111], v[172:175], v[232:235], v[96:111]
	v_mfma_f32_32x32x16_bf16 v[32:47], v[224:227], v[232:235], v[32:47]
	ds_read_b128 v[228:231], v184 offset:9216
	ds_read_b128 v[232:235], v184 offset:13824
	s_waitcnt vmcnt(7)
	ds_write_b128 v194, v[158:161]
	s_waitcnt vmcnt(6)
	ds_write_b128 v193, v[162:165]
	ds_read_b128 v[158:161], v192 offset:36896
	ds_read_b128 v[162:165], v192 offset:41504
	s_waitcnt lgkmcnt(5)
	v_mfma_f32_32x32x16_bf16 v[80:95], v[172:175], v[228:231], v[80:95]
	v_mfma_f32_32x32x16_bf16 v[16:31], v[224:227], v[228:231], v[16:31]
	ds_read_b128 v[228:231], v184 offset:32
	s_waitcnt lgkmcnt(5)
	v_mfma_f32_32x32x16_bf16 v[64:79], v[172:175], v[232:235], v[64:79]
	v_mfma_f32_32x32x16_bf16 v[0:15], v[224:227], v[232:235], v[0:15]
	ds_read_b128 v[232:235], v184 offset:4640
	s_setprio 0
	global_load_dwordx4 v[172:175], v[136:137], off offset:1280
	global_load_dwordx4 v[224:227], v[140:141], off offset:1280
	s_setprio 1
	s_waitcnt lgkmcnt(1)
	v_mfma_f32_32x32x16_bf16 v[112:127], v[158:161], v[228:231], v[112:127]
	v_mfma_f32_32x32x16_bf16 v[48:63], v[162:165], v[228:231], v[48:63]
	s_waitcnt lgkmcnt(0)
	v_mfma_f32_32x32x16_bf16 v[96:111], v[158:161], v[232:235], v[96:111]
	v_mfma_f32_32x32x16_bf16 v[32:47], v[162:165], v[232:235], v[32:47]
	ds_read_b128 v[228:231], v184 offset:9248
	ds_read_b128 v[232:235], v184 offset:13856
	s_waitcnt vmcnt(7)
	ds_write_b128 v177, v[200:203]
	s_waitcnt vmcnt(6)
	ds_write_b128 v176, v[208:211]
	ds_read_b128 v[200:203], v192 offset:36928
	ds_read_b128 v[208:211], v192 offset:41536
	s_waitcnt lgkmcnt(5)
	v_mfma_f32_32x32x16_bf16 v[80:95], v[158:161], v[228:231], v[80:95]
	v_mfma_f32_32x32x16_bf16 v[16:31], v[162:165], v[228:231], v[16:31]
	ds_read_b128 v[228:231], v184 offset:64
	s_waitcnt lgkmcnt(5)
	v_mfma_f32_32x32x16_bf16 v[64:79], v[158:161], v[232:235], v[64:79]
	v_mfma_f32_32x32x16_bf16 v[0:15], v[162:165], v[232:235], v[0:15]
	ds_read_b128 v[232:235], v184 offset:4672
	s_setprio 0
	global_load_dwordx4 v[158:161], v[144:145], off offset:1280
	global_load_dwordx4 v[162:165], v[148:149], off offset:1280
	s_setprio 1
	s_waitcnt lgkmcnt(1)
	v_mfma_f32_32x32x16_bf16 v[112:127], v[200:203], v[228:231], v[112:127]
	v_mfma_f32_32x32x16_bf16 v[48:63], v[208:211], v[228:231], v[48:63]
	s_waitcnt lgkmcnt(0)
	v_mfma_f32_32x32x16_bf16 v[96:111], v[200:203], v[232:235], v[96:111]
	v_mfma_f32_32x32x16_bf16 v[32:47], v[208:211], v[232:235], v[32:47]
	ds_read_b128 v[228:231], v184 offset:9280
	ds_read_b128 v[232:235], v184 offset:13888
	s_waitcnt vmcnt(7)
	ds_write_b128 v171, v[212:215]
	s_waitcnt vmcnt(6)
	ds_write_b128 v170, v[216:219]
	ds_read_b128 v[212:215], v192 offset:36960
	ds_read_b128 v[216:219], v192 offset:41568
	s_waitcnt lgkmcnt(5)
	v_mfma_f32_32x32x16_bf16 v[80:95], v[200:203], v[228:231], v[80:95]
	v_mfma_f32_32x32x16_bf16 v[16:31], v[208:211], v[228:231], v[16:31]
	ds_read_b128 v[228:231], v184 offset:96
	s_waitcnt lgkmcnt(5)
	v_mfma_f32_32x32x16_bf16 v[64:79], v[200:203], v[232:235], v[64:79]
	v_mfma_f32_32x32x16_bf16 v[0:15], v[208:211], v[232:235], v[0:15]
	ds_read_b128 v[232:235], v184 offset:4704
	s_setprio 0
	global_load_dwordx4 v[200:203], v[152:153], off offset:1280
	global_load_dwordx4 v[208:211], v[156:157], off offset:1280
	s_setprio 1
	s_waitcnt lgkmcnt(1)
	v_mfma_f32_32x32x16_bf16 v[112:127], v[212:215], v[228:231], v[112:127]
	v_mfma_f32_32x32x16_bf16 v[48:63], v[216:219], v[228:231], v[48:63]
	s_waitcnt lgkmcnt(0)
	v_mfma_f32_32x32x16_bf16 v[96:111], v[212:215], v[232:235], v[96:111]
	v_mfma_f32_32x32x16_bf16 v[32:47], v[216:219], v[232:235], v[32:47]
	ds_read_b128 v[228:231], v184 offset:9312
	ds_read_b128 v[232:235], v184 offset:13920
	s_waitcnt lgkmcnt(1)
	v_mfma_f32_32x32x16_bf16 v[80:95], v[212:215], v[228:231], v[80:95]
	v_mfma_f32_32x32x16_bf16 v[16:31], v[216:219], v[228:231], v[16:31]
	s_waitcnt lgkmcnt(0)
	v_mfma_f32_32x32x16_bf16 v[64:79], v[212:215], v[232:235], v[64:79]
	v_mfma_f32_32x32x16_bf16 v[0:15], v[216:219], v[232:235], v[0:15]
	s_setprio 0
	global_load_dwordx4 v[212:215], v[128:129], off offset:1408
	global_load_dwordx4 v[216:219], v[132:133], off offset:1408
	s_barrier
; template <bool trans>
; DI void gemm_core(const GTile& tl, const GTile& nx, bool has_next  , bool chain  , bool pre, u32x4 (&ra)[4], u32x4 (&rb)[4], char* smem, f32x16 (&acc)[2][4]) {
;     ...
;   const int nk = K / 64;
;   if (!pre) { G_LOAD(0); G_STORE(0); G_LOAD(1); }
;   for (int kt = 0; kt < nk; ++kt) {
;     __syncthreads();
;     G_COMPUTE(kt & 1, kt);
	s_waitcnt vmcnt(9)
	ds_write_b128 v191, v[178:181]
	s_waitcnt vmcnt(8)
	ds_write_b128 v191, v[220:223] offset:36864
	ds_read_b128 v[178:181], v169
	ds_read_b128 v[220:223], v169 offset:4608
	ds_read_b128 v[228:231], v168
	ds_read_b128 v[232:235], v168 offset:4608
	s_setprio 1
	s_waitcnt lgkmcnt(1)
	v_mfma_f32_32x32x16_bf16 v[112:127], v[178:181], v[228:231], v[112:127]
	v_mfma_f32_32x32x16_bf16 v[48:63], v[220:223], v[228:231], v[48:63]
	s_waitcnt lgkmcnt(0)
	v_mfma_f32_32x32x16_bf16 v[96:111], v[178:181], v[232:235], v[96:111]
	v_mfma_f32_32x32x16_bf16 v[32:47], v[220:223], v[232:235], v[32:47]
	ds_read_b128 v[228:231], v168 offset:9216
	ds_read_b128 v[232:235], v168 offset:13824
	s_waitcnt vmcnt(7)
	ds_write_b128 v191, v[172:175] offset:9216
	s_waitcnt vmcnt(6)
	ds_write_b128 v191, v[224:227] offset:46080
	ds_read_b128 v[172:175], v169 offset:32
	ds_read_b128 v[224:227], v169 offset:4640
	s_waitcnt lgkmcnt(5)
	v_mfma_f32_32x32x16_bf16 v[80:95], v[178:181], v[228:231], v[80:95]
	v_mfma_f32_32x32x16_bf16 v[16:31], v[220:223], v[228:231], v[16:31]
	ds_read_b128 v[228:231], v168 offset:32
	s_waitcnt lgkmcnt(5)
	v_mfma_f32_32x32x16_bf16 v[64:79], v[178:181], v[232:235], v[64:79]
	v_mfma_f32_32x32x16_bf16 v[0:15], v[220:223], v[232:235], v[0:15]
	ds_read_b128 v[232:235], v168 offset:4640
	s_setprio 0
	global_load_dwordx4 v[178:181], v[136:137], off offset:1408
	global_load_dwordx4 v[220:223], v[140:141], off offset:1408
	s_setprio 1
	s_waitcnt lgkmcnt(1)
	v_mfma_f32_32x32x16_bf16 v[112:127], v[172:175], v[228:231], v[112:127]
	v_mfma_f32_32x32x16_bf16 v[48:63], v[224:227], v[228:231], v[48:63]
	s_waitcnt lgkmcnt(0)
	v_mfma_f32_32x32x16_bf16 v[96:111], v[172:175], v[232:235], v[96:111]
	v_mfma_f32_32x32x16_bf16 v[32:47], v[224:227], v[232:235], v[32:47]
	ds_read_b128 v[228:231], v168 offset:9248
	ds_read_b128 v[232:235], v168 offset:13856
	s_waitcnt vmcnt(7)
	ds_write_b128 v191, v[158:161] offset:18432
	s_waitcnt vmcnt(6)
	ds_write_b128 v191, v[162:165] offset:55296
	ds_read_b128 v[158:161], v169 offset:64
	ds_read_b128 v[162:165], v169 offset:4672
	s_waitcnt lgkmcnt(5)
	v_mfma_f32_32x32x16_bf16 v[80:95], v[172:175], v[228:231], v[80:95]
	v_mfma_f32_32x32x16_bf16 v[16:31], v[224:227], v[228:231], v[16:31]
	ds_read_b128 v[228:231], v168 offset:64
	s_waitcnt lgkmcnt(5)
	v_mfma_f32_32x32x16_bf16 v[64:79], v[172:175], v[232:235], v[64:79]
	v_mfma_f32_32x32x16_bf16 v[0:15], v[224:227], v[232:235], v[0:15]
	ds_read_b128 v[232:235], v168 offset:4672
	s_setprio 0
	global_load_dwordx4 v[172:175], v[144:145], off offset:1408
	global_load_dwordx4 v[224:227], v[148:149], off offset:1408
	s_setprio 1
	s_waitcnt lgkmcnt(1)
	v_mfma_f32_32x32x16_bf16 v[112:127], v[158:161], v[228:231], v[112:127]
	v_mfma_f32_32x32x16_bf16 v[48:63], v[162:165], v[228:231], v[48:63]
	s_waitcnt lgkmcnt(0)
	v_mfma_f32_32x32x16_bf16 v[96:111], v[158:161], v[232:235], v[96:111]
	v_mfma_f32_32x32x16_bf16 v[32:47], v[162:165], v[232:235], v[32:47]
	ds_read_b128 v[228:231], v168 offset:9280
	ds_read_b128 v[232:235], v168 offset:13888
	s_waitcnt vmcnt(7)
	ds_write_b128 v191, v[200:203] offset:27648
	s_waitcnt vmcnt(6)
	ds_write_b128 v191, v[208:211] offset:64512
	ds_read_b128 v[200:203], v169 offset:96
	ds_read_b128 v[208:211], v169 offset:4704
	s_waitcnt lgkmcnt(5)
	v_mfma_f32_32x32x16_bf16 v[80:95], v[158:161], v[228:231], v[80:95]
	v_mfma_f32_32x32x16_bf16 v[16:31], v[162:165], v[228:231], v[16:31]
	ds_read_b128 v[228:231], v168 offset:96
	s_waitcnt lgkmcnt(5)
	v_mfma_f32_32x32x16_bf16 v[64:79], v[158:161], v[232:235], v[64:79]
	v_mfma_f32_32x32x16_bf16 v[0:15], v[162:165], v[232:235], v[0:15]
	ds_read_b128 v[232:235], v168 offset:4704
	s_setprio 0
	global_load_dwordx4 v[158:161], v[152:153], off offset:1408
	global_load_dwordx4 v[162:165], v[156:157], off offset:1408
	s_setprio 1
	s_waitcnt lgkmcnt(1)
	v_mfma_f32_32x32x16_bf16 v[112:127], v[200:203], v[228:231], v[112:127]
	v_mfma_f32_32x32x16_bf16 v[48:63], v[208:211], v[228:231], v[48:63]
	s_waitcnt lgkmcnt(0)
	v_mfma_f32_32x32x16_bf16 v[96:111], v[200:203], v[232:235], v[96:111]
	v_mfma_f32_32x32x16_bf16 v[32:47], v[208:211], v[232:235], v[32:47]
	ds_read_b128 v[228:231], v168 offset:9312
	ds_read_b128 v[232:235], v168 offset:13920
	s_waitcnt lgkmcnt(1)
	v_mfma_f32_32x32x16_bf16 v[80:95], v[200:203], v[228:231], v[80:95]
	v_mfma_f32_32x32x16_bf16 v[16:31], v[208:211], v[228:231], v[16:31]
	s_waitcnt lgkmcnt(0)
	v_mfma_f32_32x32x16_bf16 v[64:79], v[200:203], v[232:235], v[64:79]
	v_mfma_f32_32x32x16_bf16 v[0:15], v[208:211], v[232:235], v[0:15]
	s_setprio 0
	global_load_dwordx4 v[200:203], v[128:129], off offset:1536
	global_load_dwordx4 v[208:211], v[132:133], off offset:1536
	s_barrier
; template <bool trans>
; DI void gemm_core(const GTile& tl, const GTile& nx, bool has_next  , bool chain  , bool pre, u32x4 (&ra)[4], u32x4 (&rb)[4], char* smem, f32x16 (&acc)[2][4]) {
;     ...
;   const int nk = K / 64;
;   if (!pre) { G_LOAD(0); G_STORE(0); G_LOAD(1); }
;   for (int kt = 0; kt < nk; ++kt) {
;     __syncthreads();
;     G_COMPUTE(kt & 1, kt);
	s_waitcnt vmcnt(9)
	ds_write_b128 v195, v[212:215]
	s_waitcnt vmcnt(8)
	ds_write_b128 v196, v[216:219]
	ds_read_b128 v[212:215], v192 offset:36864
	ds_read_b128 v[216:219], v192 offset:41472
	ds_read_b128 v[228:231], v184
	ds_read_b128 v[232:235], v184 offset:4608
	s_setprio 1
	s_waitcnt lgkmcnt(1)
	v_mfma_f32_32x32x16_bf16 v[112:127], v[212:215], v[228:231], v[112:127]
	v_mfma_f32_32x32x16_bf16 v[48:63], v[216:219], v[228:231], v[48:63]
	s_waitcnt lgkmcnt(0)
	v_mfma_f32_32x32x16_bf16 v[96:111], v[212:215], v[232:235], v[96:111]
	v_mfma_f32_32x32x16_bf16 v[32:47], v[216:219], v[232:235], v[32:47]
	ds_read_b128 v[228:231], v184 offset:9216
	ds_read_b128 v[232:235], v184 offset:13824
	s_waitcnt vmcnt(7)
	ds_write_b128 v194, v[178:181]
	s_waitcnt vmcnt(6)
	ds_write_b128 v193, v[220:223]
	ds_read_b128 v[178:181], v192 offset:36896
	ds_read_b128 v[220:223], v192 offset:41504
	s_waitcnt lgkmcnt(5)
	v_mfma_f32_32x32x16_bf16 v[80:95], v[212:215], v[228:231], v[80:95]
	v_mfma_f32_32x32x16_bf16 v[16:31], v[216:219], v[228:231], v[16:31]
	ds_read_b128 v[228:231], v184 offset:32
	s_waitcnt lgkmcnt(5)
	v_mfma_f32_32x32x16_bf16 v[64:79], v[212:215], v[232:235], v[64:79]
	v_mfma_f32_32x32x16_bf16 v[0:15], v[216:219], v[232:235], v[0:15]
	ds_read_b128 v[232:235], v184 offset:4640
	s_setprio 0
	global_load_dwordx4 v[212:215], v[136:137], off offset:1536
	global_load_dwordx4 v[216:219], v[140:141], off offset:1536
	s_setprio 1
	s_waitcnt lgkmcnt(1)
	v_mfma_f32_32x32x16_bf16 v[112:127], v[178:181], v[228:231], v[112:127]
	v_mfma_f32_32x32x16_bf16 v[48:63], v[220:223], v[228:231], v[48:63]
	s_waitcnt lgkmcnt(0)
	v_mfma_f32_32x32x16_bf16 v[96:111], v[178:181], v[232:235], v[96:111]
	v_mfma_f32_32x32x16_bf16 v[32:47], v[220:223], v[232:235], v[32:47]
	ds_read_b128 v[228:231], v184 offset:9248
	ds_read_b128 v[232:235], v184 offset:13856
	s_waitcnt vmcnt(7)
	ds_write_b128 v177, v[172:175]
	s_waitcnt vmcnt(6)
	ds_write_b128 v176, v[224:227]
	ds_read_b128 v[172:175], v192 offset:36928
	ds_read_b128 v[224:227], v192 offset:41536
	s_waitcnt lgkmcnt(5)
	v_mfma_f32_32x32x16_bf16 v[80:95], v[178:181], v[228:231], v[80:95]
	v_mfma_f32_32x32x16_bf16 v[16:31], v[220:223], v[228:231], v[16:31]
	ds_read_b128 v[228:231], v184 offset:64
	s_waitcnt lgkmcnt(5)
	v_mfma_f32_32x32x16_bf16 v[64:79], v[178:181], v[232:235], v[64:79]
	v_mfma_f32_32x32x16_bf16 v[0:15], v[220:223], v[232:235], v[0:15]
	ds_read_b128 v[232:235], v184 offset:4672
	s_setprio 0
	global_load_dwordx4 v[178:181], v[144:145], off offset:1536
	global_load_dwordx4 v[220:223], v[148:149], off offset:1536
	s_setprio 1
	s_waitcnt lgkmcnt(1)
	v_mfma_f32_32x32x16_bf16 v[112:127], v[172:175], v[228:231], v[112:127]
	v_mfma_f32_32x32x16_bf16 v[48:63], v[224:227], v[228:231], v[48:63]
	s_waitcnt lgkmcnt(0)
	v_mfma_f32_32x32x16_bf16 v[96:111], v[172:175], v[232:235], v[96:111]
	v_mfma_f32_32x32x16_bf16 v[32:47], v[224:227], v[232:235], v[32:47]
	ds_read_b128 v[228:231], v184 offset:9280
	ds_read_b128 v[232:235], v184 offset:13888
	s_waitcnt vmcnt(7)
	ds_write_b128 v171, v[158:161]
	s_waitcnt vmcnt(6)
	ds_write_b128 v170, v[162:165]
	ds_read_b128 v[158:161], v192 offset:36960
	ds_read_b128 v[162:165], v192 offset:41568
	s_waitcnt lgkmcnt(5)
	v_mfma_f32_32x32x16_bf16 v[80:95], v[172:175], v[228:231], v[80:95]
	v_mfma_f32_32x32x16_bf16 v[16:31], v[224:227], v[228:231], v[16:31]
	ds_read_b128 v[228:231], v184 offset:96
	s_waitcnt lgkmcnt(5)
	v_mfma_f32_32x32x16_bf16 v[64:79], v[172:175], v[232:235], v[64:79]
	v_mfma_f32_32x32x16_bf16 v[0:15], v[224:227], v[232:235], v[0:15]
	ds_read_b128 v[232:235], v184 offset:4704
	s_setprio 0
	global_load_dwordx4 v[172:175], v[152:153], off offset:1536
	global_load_dwordx4 v[224:227], v[156:157], off offset:1536
	s_setprio 1
	s_waitcnt lgkmcnt(1)
	v_mfma_f32_32x32x16_bf16 v[112:127], v[158:161], v[228:231], v[112:127]
	v_mfma_f32_32x32x16_bf16 v[48:63], v[162:165], v[228:231], v[48:63]
	s_waitcnt lgkmcnt(0)
	v_mfma_f32_32x32x16_bf16 v[96:111], v[158:161], v[232:235], v[96:111]
	v_mfma_f32_32x32x16_bf16 v[32:47], v[162:165], v[232:235], v[32:47]
	ds_read_b128 v[228:231], v184 offset:9312
	ds_read_b128 v[232:235], v184 offset:13920
	s_waitcnt lgkmcnt(1)
	v_mfma_f32_32x32x16_bf16 v[80:95], v[158:161], v[228:231], v[80:95]
	v_mfma_f32_32x32x16_bf16 v[16:31], v[162:165], v[228:231], v[16:31]
	s_waitcnt lgkmcnt(0)
	v_mfma_f32_32x32x16_bf16 v[64:79], v[158:161], v[232:235], v[64:79]
	v_mfma_f32_32x32x16_bf16 v[0:15], v[162:165], v[232:235], v[0:15]
	s_setprio 0
	global_load_dwordx4 v[158:161], v[128:129], off offset:1664
	global_load_dwordx4 v[162:165], v[132:133], off offset:1664
	s_barrier
; template <bool trans>
; DI void gemm_core(const GTile& tl, const GTile& nx, bool has_next  , bool chain  , bool pre, u32x4 (&ra)[4], u32x4 (&rb)[4], char* smem, f32x16 (&acc)[2][4]) {
;     ...
;   const int nk = K / 64;
;   if (!pre) { G_LOAD(0); G_STORE(0); G_LOAD(1); }
;   for (int kt = 0; kt < nk; ++kt) {
;     __syncthreads();
;     G_COMPUTE(kt & 1, kt);
	s_waitcnt vmcnt(9)
	ds_write_b128 v191, v[200:203]
	s_waitcnt vmcnt(8)
	ds_write_b128 v191, v[208:211] offset:36864
	ds_read_b128 v[200:203], v169
	ds_read_b128 v[208:211], v169 offset:4608
	ds_read_b128 v[228:231], v168
	ds_read_b128 v[232:235], v168 offset:4608
	s_setprio 1
	s_waitcnt lgkmcnt(1)
	v_mfma_f32_32x32x16_bf16 v[112:127], v[200:203], v[228:231], v[112:127]
	v_mfma_f32_32x32x16_bf16 v[48:63], v[208:211], v[228:231], v[48:63]
	s_waitcnt lgkmcnt(0)
	v_mfma_f32_32x32x16_bf16 v[96:111], v[200:203], v[232:235], v[96:111]
	v_mfma_f32_32x32x16_bf16 v[32:47], v[208:211], v[232:235], v[32:47]
	ds_read_b128 v[228:231], v168 offset:9216
	ds_read_b128 v[232:235], v168 offset:13824
	s_waitcnt vmcnt(7)
	ds_write_b128 v191, v[212:215] offset:9216
	s_waitcnt vmcnt(6)
	ds_write_b128 v191, v[216:219] offset:46080
	ds_read_b128 v[212:215], v169 offset:32
	ds_read_b128 v[216:219], v169 offset:4640
	s_waitcnt lgkmcnt(5)
	v_mfma_f32_32x32x16_bf16 v[80:95], v[200:203], v[228:231], v[80:95]
	v_mfma_f32_32x32x16_bf16 v[16:31], v[208:211], v[228:231], v[16:31]
	ds_read_b128 v[228:231], v168 offset:32
	s_waitcnt lgkmcnt(5)
	v_mfma_f32_32x32x16_bf16 v[64:79], v[200:203], v[232:235], v[64:79]
	v_mfma_f32_32x32x16_bf16 v[0:15], v[208:211], v[232:235], v[0:15]
	ds_read_b128 v[232:235], v168 offset:4640
	s_setprio 0
	global_load_dwordx4 v[200:203], v[136:137], off offset:1664
	global_load_dwordx4 v[208:211], v[140:141], off offset:1664
	s_setprio 1
	s_waitcnt lgkmcnt(1)
	v_mfma_f32_32x32x16_bf16 v[112:127], v[212:215], v[228:231], v[112:127]
	v_mfma_f32_32x32x16_bf16 v[48:63], v[216:219], v[228:231], v[48:63]
	s_waitcnt lgkmcnt(0)
	v_mfma_f32_32x32x16_bf16 v[96:111], v[212:215], v[232:235], v[96:111]
	v_mfma_f32_32x32x16_bf16 v[32:47], v[216:219], v[232:235], v[32:47]
	ds_read_b128 v[228:231], v168 offset:9248
	ds_read_b128 v[232:235], v168 offset:13856
	s_waitcnt vmcnt(7)
	ds_write_b128 v191, v[178:181] offset:18432
	s_waitcnt vmcnt(6)
	ds_write_b128 v191, v[220:223] offset:55296
	ds_read_b128 v[178:181], v169 offset:64
	ds_read_b128 v[220:223], v169 offset:4672
	s_waitcnt lgkmcnt(5)
	v_mfma_f32_32x32x16_bf16 v[80:95], v[212:215], v[228:231], v[80:95]
	v_mfma_f32_32x32x16_bf16 v[16:31], v[216:219], v[228:231], v[16:31]
	ds_read_b128 v[228:231], v168 offset:64
	s_waitcnt lgkmcnt(5)
	v_mfma_f32_32x32x16_bf16 v[64:79], v[212:215], v[232:235], v[64:79]
	v_mfma_f32_32x32x16_bf16 v[0:15], v[216:219], v[232:235], v[0:15]
	ds_read_b128 v[232:235], v168 offset:4672
	s_setprio 0
	global_load_dwordx4 v[212:215], v[144:145], off offset:1664
	global_load_dwordx4 v[216:219], v[148:149], off offset:1664
	s_setprio 1
	s_waitcnt lgkmcnt(1)
	v_mfma_f32_32x32x16_bf16 v[112:127], v[178:181], v[228:231], v[112:127]
	v_mfma_f32_32x32x16_bf16 v[48:63], v[220:223], v[228:231], v[48:63]
	s_waitcnt lgkmcnt(0)
	v_mfma_f32_32x32x16_bf16 v[96:111], v[178:181], v[232:235], v[96:111]
	v_mfma_f32_32x32x16_bf16 v[32:47], v[220:223], v[232:235], v[32:47]
	ds_read_b128 v[228:231], v168 offset:9280
	ds_read_b128 v[232:235], v168 offset:13888
	s_waitcnt vmcnt(7)
	ds_write_b128 v191, v[172:175] offset:27648
	s_waitcnt vmcnt(6)
	ds_write_b128 v191, v[224:227] offset:64512
	ds_read_b128 v[172:175], v169 offset:96
	ds_read_b128 v[224:227], v169 offset:4704
	s_waitcnt lgkmcnt(5)
	v_mfma_f32_32x32x16_bf16 v[80:95], v[178:181], v[228:231], v[80:95]
	v_mfma_f32_32x32x16_bf16 v[16:31], v[220:223], v[228:231], v[16:31]
	ds_read_b128 v[228:231], v168 offset:96
	s_waitcnt lgkmcnt(5)
	v_mfma_f32_32x32x16_bf16 v[64:79], v[178:181], v[232:235], v[64:79]
	v_mfma_f32_32x32x16_bf16 v[0:15], v[220:223], v[232:235], v[0:15]
	ds_read_b128 v[232:235], v168 offset:4704
	s_setprio 0
	global_load_dwordx4 v[178:181], v[152:153], off offset:1664
	global_load_dwordx4 v[220:223], v[156:157], off offset:1664
	s_setprio 1
	s_waitcnt lgkmcnt(1)
	v_mfma_f32_32x32x16_bf16 v[112:127], v[172:175], v[228:231], v[112:127]
	v_mfma_f32_32x32x16_bf16 v[48:63], v[224:227], v[228:231], v[48:63]
	s_waitcnt lgkmcnt(0)
	v_mfma_f32_32x32x16_bf16 v[96:111], v[172:175], v[232:235], v[96:111]
	v_mfma_f32_32x32x16_bf16 v[32:47], v[224:227], v[232:235], v[32:47]
	ds_read_b128 v[228:231], v168 offset:9312
	ds_read_b128 v[232:235], v168 offset:13920
	s_waitcnt lgkmcnt(1)
	v_mfma_f32_32x32x16_bf16 v[80:95], v[172:175], v[228:231], v[80:95]
	v_mfma_f32_32x32x16_bf16 v[16:31], v[224:227], v[228:231], v[16:31]
	s_waitcnt lgkmcnt(0)
	v_mfma_f32_32x32x16_bf16 v[64:79], v[172:175], v[232:235], v[64:79]
	v_mfma_f32_32x32x16_bf16 v[0:15], v[224:227], v[232:235], v[0:15]
	s_setprio 0
	global_load_dwordx4 v[172:175], v[128:129], off offset:1792
	global_load_dwordx4 v[224:227], v[132:133], off offset:1792
	s_barrier
; template <bool trans>
; DI void gemm_core(const GTile& tl, const GTile& nx, bool has_next  , bool chain  , bool pre, u32x4 (&ra)[4], u32x4 (&rb)[4], char* smem, f32x16 (&acc)[2][4]) {
;     ...
;   const int nk = K / 64;
;   if (!pre) { G_LOAD(0); G_STORE(0); G_LOAD(1); }
;   for (int kt = 0; kt < nk; ++kt) {
;     __syncthreads();
;     G_COMPUTE(kt & 1, kt);
;   }
	s_waitcnt vmcnt(9)
	ds_write_b128 v195, v[158:161]
	s_waitcnt vmcnt(8)
	ds_write_b128 v196, v[162:165]
	ds_read_b128 v[158:161], v192 offset:36864
	ds_read_b128 v[162:165], v192 offset:41472
	ds_read_b128 v[228:231], v184
	ds_read_b128 v[232:235], v184 offset:4608
	s_setprio 1
	s_waitcnt lgkmcnt(1)
	v_mfma_f32_32x32x16_bf16 v[112:127], v[158:161], v[228:231], v[112:127]
	v_mfma_f32_32x32x16_bf16 v[48:63], v[162:165], v[228:231], v[48:63]
	s_waitcnt lgkmcnt(0)
	v_mfma_f32_32x32x16_bf16 v[96:111], v[158:161], v[232:235], v[96:111]
	v_mfma_f32_32x32x16_bf16 v[32:47], v[162:165], v[232:235], v[32:47]
	ds_read_b128 v[228:231], v184 offset:9216
	ds_read_b128 v[232:235], v184 offset:13824
	s_waitcnt vmcnt(7)
	ds_write_b128 v194, v[200:203]
	s_waitcnt vmcnt(6)
	ds_write_b128 v193, v[208:211]
	ds_read_b128 v[200:203], v192 offset:36896
	ds_read_b128 v[208:211], v192 offset:41504
	s_waitcnt lgkmcnt(5)
	v_mfma_f32_32x32x16_bf16 v[80:95], v[158:161], v[228:231], v[80:95]
	v_mfma_f32_32x32x16_bf16 v[16:31], v[162:165], v[228:231], v[16:31]
	ds_read_b128 v[228:231], v184 offset:32
	s_waitcnt lgkmcnt(5)
	v_mfma_f32_32x32x16_bf16 v[64:79], v[158:161], v[232:235], v[64:79]
	v_mfma_f32_32x32x16_bf16 v[0:15], v[162:165], v[232:235], v[0:15]
	ds_read_b128 v[232:235], v184 offset:4640
	s_setprio 0
	global_load_dwordx4 v[158:161], v[136:137], off offset:1792
	global_load_dwordx4 v[162:165], v[140:141], off offset:1792
	s_setprio 1
	s_waitcnt lgkmcnt(1)
	v_mfma_f32_32x32x16_bf16 v[112:127], v[200:203], v[228:231], v[112:127]
	v_mfma_f32_32x32x16_bf16 v[48:63], v[208:211], v[228:231], v[48:63]
	s_waitcnt lgkmcnt(0)
	v_mfma_f32_32x32x16_bf16 v[96:111], v[200:203], v[232:235], v[96:111]
	v_mfma_f32_32x32x16_bf16 v[32:47], v[208:211], v[232:235], v[32:47]
	ds_read_b128 v[228:231], v184 offset:9248
	ds_read_b128 v[232:235], v184 offset:13856
	s_waitcnt vmcnt(7)
	ds_write_b128 v177, v[212:215]
	s_waitcnt vmcnt(6)
	ds_write_b128 v176, v[216:219]
	ds_read_b128 v[212:215], v192 offset:36928
	ds_read_b128 v[216:219], v192 offset:41536
	s_waitcnt lgkmcnt(5)
	v_mfma_f32_32x32x16_bf16 v[80:95], v[200:203], v[228:231], v[80:95]
	v_mfma_f32_32x32x16_bf16 v[16:31], v[208:211], v[228:231], v[16:31]
	ds_read_b128 v[228:231], v184 offset:64
	s_waitcnt lgkmcnt(5)
	v_mfma_f32_32x32x16_bf16 v[64:79], v[200:203], v[232:235], v[64:79]
	v_mfma_f32_32x32x16_bf16 v[0:15], v[208:211], v[232:235], v[0:15]
	ds_read_b128 v[232:235], v184 offset:4672
	s_setprio 0
	global_load_dwordx4 v[200:203], v[144:145], off offset:1792
	global_load_dwordx4 v[208:211], v[148:149], off offset:1792
	s_setprio 1
	s_waitcnt lgkmcnt(1)
	v_mfma_f32_32x32x16_bf16 v[112:127], v[212:215], v[228:231], v[112:127]
	v_mfma_f32_32x32x16_bf16 v[48:63], v[216:219], v[228:231], v[48:63]
	s_waitcnt lgkmcnt(0)
	v_mfma_f32_32x32x16_bf16 v[96:111], v[212:215], v[232:235], v[96:111]
	v_mfma_f32_32x32x16_bf16 v[32:47], v[216:219], v[232:235], v[32:47]
	ds_read_b128 v[228:231], v184 offset:9280
	ds_read_b128 v[232:235], v184 offset:13888
	s_waitcnt vmcnt(7)
	ds_write_b128 v171, v[178:181]
	s_waitcnt vmcnt(6)
	ds_write_b128 v170, v[220:223]
	ds_read_b128 v[178:181], v192 offset:36960
	ds_read_b128 v[220:223], v192 offset:41568
	s_waitcnt lgkmcnt(5)
	v_mfma_f32_32x32x16_bf16 v[80:95], v[212:215], v[228:231], v[80:95]
	v_mfma_f32_32x32x16_bf16 v[16:31], v[216:219], v[228:231], v[16:31]
	ds_read_b128 v[228:231], v184 offset:96
	s_waitcnt lgkmcnt(5)
	v_mfma_f32_32x32x16_bf16 v[64:79], v[212:215], v[232:235], v[64:79]
	v_mfma_f32_32x32x16_bf16 v[0:15], v[216:219], v[232:235], v[0:15]
	ds_read_b128 v[232:235], v184 offset:4704
	s_setprio 0
	global_load_dwordx4 v[212:215], v[152:153], off offset:1792
	global_load_dwordx4 v[216:219], v[156:157], off offset:1792
	s_setprio 1
	s_waitcnt lgkmcnt(1)
	v_mfma_f32_32x32x16_bf16 v[112:127], v[178:181], v[228:231], v[112:127]
	v_mfma_f32_32x32x16_bf16 v[48:63], v[220:223], v[228:231], v[48:63]
	s_waitcnt lgkmcnt(0)
	v_mfma_f32_32x32x16_bf16 v[96:111], v[178:181], v[232:235], v[96:111]
	v_mfma_f32_32x32x16_bf16 v[32:47], v[220:223], v[232:235], v[32:47]
	ds_read_b128 v[228:231], v184 offset:9312
	ds_read_b128 v[232:235], v184 offset:13920
	s_waitcnt lgkmcnt(1)
	v_mfma_f32_32x32x16_bf16 v[80:95], v[178:181], v[228:231], v[80:95]
	v_mfma_f32_32x32x16_bf16 v[16:31], v[220:223], v[228:231], v[16:31]
	s_waitcnt lgkmcnt(0)
	v_mfma_f32_32x32x16_bf16 v[64:79], v[178:181], v[232:235], v[64:79]
	v_mfma_f32_32x32x16_bf16 v[0:15], v[220:223], v[232:235], v[0:15]
	s_setprio 0
	global_load_dwordx4 v[178:181], v[128:129], off offset:1920
	global_load_dwordx4 v[220:223], v[132:133], off offset:1920
	s_barrier
; template <bool trans>
; DI void gemm_core(const GTile& tl, const GTile& nx, bool has_next  , bool chain  , bool pre, u32x4 (&ra)[4], u32x4 (&rb)[4], char* smem, f32x16 (&acc)[2][4]) {
;     ...
;   const int nk = K / 64;
;   if (!pre) { G_LOAD(0); G_STORE(0); G_LOAD(1); }
;   for (int kt = 0; kt < nk; ++kt) {
;     __syncthreads();
;     G_COMPUTE(kt & 1, kt);
;   }
	s_waitcnt vmcnt(9)
	ds_write_b128 v191, v[172:175]
	s_waitcnt vmcnt(8)
	ds_write_b128 v191, v[224:227] offset:36864
	ds_read_b128 v[172:175], v169
	ds_read_b128 v[224:227], v169 offset:4608
	ds_read_b128 v[228:231], v168
	ds_read_b128 v[232:235], v168 offset:4608
	s_setprio 1
	s_waitcnt lgkmcnt(1)
	v_mfma_f32_32x32x16_bf16 v[112:127], v[172:175], v[228:231], v[112:127]
	v_mfma_f32_32x32x16_bf16 v[48:63], v[224:227], v[228:231], v[48:63]
	s_waitcnt lgkmcnt(0)
	v_mfma_f32_32x32x16_bf16 v[96:111], v[172:175], v[232:235], v[96:111]
	v_mfma_f32_32x32x16_bf16 v[32:47], v[224:227], v[232:235], v[32:47]
	ds_read_b128 v[228:231], v168 offset:9216
	ds_read_b128 v[232:235], v168 offset:13824
	s_waitcnt vmcnt(7)
	ds_write_b128 v191, v[158:161] offset:9216
	s_waitcnt vmcnt(6)
	ds_write_b128 v191, v[162:165] offset:46080
	ds_read_b128 v[158:161], v169 offset:32
	ds_read_b128 v[162:165], v169 offset:4640
	s_waitcnt lgkmcnt(5)
	v_mfma_f32_32x32x16_bf16 v[80:95], v[172:175], v[228:231], v[80:95]
	v_mfma_f32_32x32x16_bf16 v[16:31], v[224:227], v[228:231], v[16:31]
	ds_read_b128 v[228:231], v168 offset:32
	s_waitcnt lgkmcnt(5)
	v_mfma_f32_32x32x16_bf16 v[64:79], v[172:175], v[232:235], v[64:79]
	v_mfma_f32_32x32x16_bf16 v[0:15], v[224:227], v[232:235], v[0:15]
	ds_read_b128 v[232:235], v168 offset:4640
	s_setprio 0
	global_load_dwordx4 v[172:175], v[136:137], off offset:1920
	global_load_dwordx4 v[224:227], v[140:141], off offset:1920
	s_setprio 1
	s_waitcnt lgkmcnt(1)
	v_mfma_f32_32x32x16_bf16 v[112:127], v[158:161], v[228:231], v[112:127]
	v_mfma_f32_32x32x16_bf16 v[48:63], v[162:165], v[228:231], v[48:63]
	s_waitcnt lgkmcnt(0)
	v_mfma_f32_32x32x16_bf16 v[96:111], v[158:161], v[232:235], v[96:111]
	v_mfma_f32_32x32x16_bf16 v[32:47], v[162:165], v[232:235], v[32:47]
	ds_read_b128 v[228:231], v168 offset:9248
	ds_read_b128 v[232:235], v168 offset:13856
	s_waitcnt vmcnt(7)
	ds_write_b128 v191, v[200:203] offset:18432
	s_waitcnt vmcnt(6)
	ds_write_b128 v191, v[208:211] offset:55296
	ds_read_b128 v[200:203], v169 offset:64
	ds_read_b128 v[208:211], v169 offset:4672
	s_waitcnt lgkmcnt(5)
	v_mfma_f32_32x32x16_bf16 v[80:95], v[158:161], v[228:231], v[80:95]
	v_mfma_f32_32x32x16_bf16 v[16:31], v[162:165], v[228:231], v[16:31]
	ds_read_b128 v[228:231], v168 offset:64
	s_waitcnt lgkmcnt(5)
	v_mfma_f32_32x32x16_bf16 v[64:79], v[158:161], v[232:235], v[64:79]
	v_mfma_f32_32x32x16_bf16 v[0:15], v[162:165], v[232:235], v[0:15]
	ds_read_b128 v[232:235], v168 offset:4672
	s_setprio 0
	global_load_dwordx4 v[158:161], v[144:145], off offset:1920
	global_load_dwordx4 v[162:165], v[148:149], off offset:1920
	s_setprio 1
	s_waitcnt lgkmcnt(1)
	v_mfma_f32_32x32x16_bf16 v[112:127], v[200:203], v[228:231], v[112:127]
	v_mfma_f32_32x32x16_bf16 v[48:63], v[208:211], v[228:231], v[48:63]
	s_waitcnt lgkmcnt(0)
	v_mfma_f32_32x32x16_bf16 v[96:111], v[200:203], v[232:235], v[96:111]
	v_mfma_f32_32x32x16_bf16 v[32:47], v[208:211], v[232:235], v[32:47]
	ds_read_b128 v[228:231], v168 offset:9280
	ds_read_b128 v[232:235], v168 offset:13888
	s_waitcnt vmcnt(7)
	ds_write_b128 v191, v[212:215] offset:27648
	s_waitcnt vmcnt(6)
	ds_write_b128 v191, v[216:219] offset:64512
	ds_read_b128 v[212:215], v169 offset:96
	ds_read_b128 v[216:219], v169 offset:4704
	s_waitcnt lgkmcnt(5)
	v_mfma_f32_32x32x16_bf16 v[80:95], v[200:203], v[228:231], v[80:95]
	v_mfma_f32_32x32x16_bf16 v[16:31], v[208:211], v[228:231], v[16:31]
	ds_read_b128 v[228:231], v168 offset:96
	s_waitcnt lgkmcnt(5)
	v_mfma_f32_32x32x16_bf16 v[64:79], v[200:203], v[232:235], v[64:79]
	v_mfma_f32_32x32x16_bf16 v[0:15], v[208:211], v[232:235], v[0:15]
	ds_read_b128 v[232:235], v168 offset:4704
	s_setprio 0
	global_load_dwordx4 v[200:203], v[152:153], off offset:1920
	global_load_dwordx4 v[208:211], v[156:157], off offset:1920
	s_setprio 1
	s_waitcnt lgkmcnt(1)
	v_mfma_f32_32x32x16_bf16 v[112:127], v[212:215], v[228:231], v[112:127]
	v_mfma_f32_32x32x16_bf16 v[48:63], v[216:219], v[228:231], v[48:63]
	s_waitcnt lgkmcnt(0)
	v_mfma_f32_32x32x16_bf16 v[96:111], v[212:215], v[232:235], v[96:111]
	v_mfma_f32_32x32x16_bf16 v[32:47], v[216:219], v[232:235], v[32:47]
	ds_read_b128 v[228:231], v168 offset:9312
	ds_read_b128 v[232:235], v168 offset:13920
	s_waitcnt lgkmcnt(1)
	v_mfma_f32_32x32x16_bf16 v[80:95], v[212:215], v[228:231], v[80:95]
	v_mfma_f32_32x32x16_bf16 v[16:31], v[216:219], v[228:231], v[16:31]
	s_waitcnt lgkmcnt(0)
	v_mfma_f32_32x32x16_bf16 v[64:79], v[212:215], v[232:235], v[64:79]
	v_mfma_f32_32x32x16_bf16 v[0:15], v[216:219], v[232:235], v[0:15]
	s_setprio 0
	global_load_dwordx4 v[212:215], v[128:129], off offset:2048
	global_load_dwordx4 v[216:219], v[132:133], off offset:2048
	s_barrier
; template <bool trans>
; DI void gemm_core(const GTile& tl, const GTile& nx, bool has_next  , bool chain  , bool pre, u32x4 (&ra)[4], u32x4 (&rb)[4], char* smem, f32x16 (&acc)[2][4]) {
;     ...
;   const int nk = K / 64;
;   if (!pre) { G_LOAD(0); G_STORE(0); G_LOAD(1); }
;   for (int kt = 0; kt < nk; ++kt) {
;     __syncthreads();
;     G_COMPUTE(kt & 1, kt);
;   }
	s_waitcnt vmcnt(9)
	ds_write_b128 v195, v[178:181]
	s_waitcnt vmcnt(8)
	ds_write_b128 v196, v[220:223]
	ds_read_b128 v[178:181], v192 offset:36864
	ds_read_b128 v[220:223], v192 offset:41472
	ds_read_b128 v[228:231], v184
	ds_read_b128 v[232:235], v184 offset:4608
	s_setprio 1
	s_waitcnt lgkmcnt(1)
	v_mfma_f32_32x32x16_bf16 v[112:127], v[178:181], v[228:231], v[112:127]
	v_mfma_f32_32x32x16_bf16 v[48:63], v[220:223], v[228:231], v[48:63]
	s_waitcnt lgkmcnt(0)
	v_mfma_f32_32x32x16_bf16 v[96:111], v[178:181], v[232:235], v[96:111]
	v_mfma_f32_32x32x16_bf16 v[32:47], v[220:223], v[232:235], v[32:47]
	ds_read_b128 v[228:231], v184 offset:9216
	ds_read_b128 v[232:235], v184 offset:13824
	s_waitcnt vmcnt(7)
	ds_write_b128 v194, v[172:175]
	s_waitcnt vmcnt(6)
	ds_write_b128 v193, v[224:227]
	ds_read_b128 v[172:175], v192 offset:36896
	ds_read_b128 v[224:227], v192 offset:41504
	s_waitcnt lgkmcnt(5)
	v_mfma_f32_32x32x16_bf16 v[80:95], v[178:181], v[228:231], v[80:95]
	v_mfma_f32_32x32x16_bf16 v[16:31], v[220:223], v[228:231], v[16:31]
	ds_read_b128 v[228:231], v184 offset:32
	s_waitcnt lgkmcnt(5)
	v_mfma_f32_32x32x16_bf16 v[64:79], v[178:181], v[232:235], v[64:79]
	v_mfma_f32_32x32x16_bf16 v[0:15], v[220:223], v[232:235], v[0:15]
	ds_read_b128 v[232:235], v184 offset:4640
	s_setprio 0
	global_load_dwordx4 v[178:181], v[136:137], off offset:2048
	global_load_dwordx4 v[220:223], v[140:141], off offset:2048
	s_setprio 1
	s_waitcnt lgkmcnt(1)
	v_mfma_f32_32x32x16_bf16 v[112:127], v[172:175], v[228:231], v[112:127]
	v_mfma_f32_32x32x16_bf16 v[48:63], v[224:227], v[228:231], v[48:63]
	s_waitcnt lgkmcnt(0)
	v_mfma_f32_32x32x16_bf16 v[96:111], v[172:175], v[232:235], v[96:111]
	v_mfma_f32_32x32x16_bf16 v[32:47], v[224:227], v[232:235], v[32:47]
	ds_read_b128 v[228:231], v184 offset:9248
	ds_read_b128 v[232:235], v184 offset:13856
	s_waitcnt vmcnt(7)
	ds_write_b128 v177, v[158:161]
	s_waitcnt vmcnt(6)
	ds_write_b128 v176, v[162:165]
	ds_read_b128 v[158:161], v192 offset:36928
	ds_read_b128 v[162:165], v192 offset:41536
	s_waitcnt lgkmcnt(5)
	v_mfma_f32_32x32x16_bf16 v[80:95], v[172:175], v[228:231], v[80:95]
	v_mfma_f32_32x32x16_bf16 v[16:31], v[224:227], v[228:231], v[16:31]
	ds_read_b128 v[228:231], v184 offset:64
	s_waitcnt lgkmcnt(5)
	v_mfma_f32_32x32x16_bf16 v[64:79], v[172:175], v[232:235], v[64:79]
	v_mfma_f32_32x32x16_bf16 v[0:15], v[224:227], v[232:235], v[0:15]
	ds_read_b128 v[232:235], v184 offset:4672
	s_setprio 0
	global_load_dwordx4 v[172:175], v[144:145], off offset:2048
	global_load_dwordx4 v[224:227], v[148:149], off offset:2048
	s_setprio 1
	s_waitcnt lgkmcnt(1)
	v_mfma_f32_32x32x16_bf16 v[112:127], v[158:161], v[228:231], v[112:127]
	v_mfma_f32_32x32x16_bf16 v[48:63], v[162:165], v[228:231], v[48:63]
	s_waitcnt lgkmcnt(0)
	v_mfma_f32_32x32x16_bf16 v[96:111], v[158:161], v[232:235], v[96:111]
	v_mfma_f32_32x32x16_bf16 v[32:47], v[162:165], v[232:235], v[32:47]
	ds_read_b128 v[228:231], v184 offset:9280
	ds_read_b128 v[232:235], v184 offset:13888
	s_waitcnt vmcnt(7)
	ds_write_b128 v171, v[200:203]
	s_waitcnt vmcnt(6)
	ds_write_b128 v170, v[208:211]
	ds_read_b128 v[200:203], v192 offset:36960
	ds_read_b128 v[208:211], v192 offset:41568
	s_waitcnt lgkmcnt(5)
	v_mfma_f32_32x32x16_bf16 v[80:95], v[158:161], v[228:231], v[80:95]
	v_mfma_f32_32x32x16_bf16 v[16:31], v[162:165], v[228:231], v[16:31]
	ds_read_b128 v[228:231], v184 offset:96
	s_waitcnt lgkmcnt(5)
	v_mfma_f32_32x32x16_bf16 v[64:79], v[158:161], v[232:235], v[64:79]
	v_mfma_f32_32x32x16_bf16 v[0:15], v[162:165], v[232:235], v[0:15]
	ds_read_b128 v[232:235], v184 offset:4704
	s_setprio 0
	global_load_dwordx4 v[158:161], v[152:153], off offset:2048
	global_load_dwordx4 v[162:165], v[156:157], off offset:2048
	s_setprio 1
	s_waitcnt lgkmcnt(1)
	v_mfma_f32_32x32x16_bf16 v[112:127], v[200:203], v[228:231], v[112:127]
	v_mfma_f32_32x32x16_bf16 v[48:63], v[208:211], v[228:231], v[48:63]
	s_waitcnt lgkmcnt(0)
	v_mfma_f32_32x32x16_bf16 v[96:111], v[200:203], v[232:235], v[96:111]
	v_mfma_f32_32x32x16_bf16 v[32:47], v[208:211], v[232:235], v[32:47]
	ds_read_b128 v[228:231], v184 offset:9312
	ds_read_b128 v[232:235], v184 offset:13920
	s_waitcnt lgkmcnt(1)
	v_mfma_f32_32x32x16_bf16 v[80:95], v[200:203], v[228:231], v[80:95]
	v_mfma_f32_32x32x16_bf16 v[16:31], v[208:211], v[228:231], v[16:31]
	s_waitcnt lgkmcnt(0)
	v_mfma_f32_32x32x16_bf16 v[64:79], v[200:203], v[232:235], v[64:79]
	v_mfma_f32_32x32x16_bf16 v[0:15], v[208:211], v[232:235], v[0:15]
	s_setprio 0
	global_load_dwordx4 v[200:203], v[128:129], off offset:2176
	global_load_dwordx4 v[208:211], v[132:133], off offset:2176
	s_barrier
; template <bool trans>
; DI void gemm_core(const GTile& tl, const GTile& nx, bool has_next  , bool chain  , bool pre, u32x4 (&ra)[4], u32x4 (&rb)[4], char* smem, f32x16 (&acc)[2][4]) {
;     ...
;   const int nk = K / 64;
;   if (!pre) { G_LOAD(0); G_STORE(0); G_LOAD(1); }
;   for (int kt = 0; kt < nk; ++kt) {
;     __syncthreads();
;     G_COMPUTE(kt & 1, kt);
;   }
	s_waitcnt vmcnt(9)
	ds_write_b128 v191, v[212:215]
	s_waitcnt vmcnt(8)
	ds_write_b128 v191, v[216:219] offset:36864
	ds_read_b128 v[212:215], v169
	ds_read_b128 v[216:219], v169 offset:4608
	ds_read_b128 v[228:231], v168
	ds_read_b128 v[232:235], v168 offset:4608
	s_setprio 1
	s_waitcnt lgkmcnt(1)
	v_mfma_f32_32x32x16_bf16 v[112:127], v[212:215], v[228:231], v[112:127]
	v_mfma_f32_32x32x16_bf16 v[48:63], v[216:219], v[228:231], v[48:63]
	s_waitcnt lgkmcnt(0)
	v_mfma_f32_32x32x16_bf16 v[96:111], v[212:215], v[232:235], v[96:111]
	v_mfma_f32_32x32x16_bf16 v[32:47], v[216:219], v[232:235], v[32:47]
	ds_read_b128 v[228:231], v168 offset:9216
	ds_read_b128 v[232:235], v168 offset:13824
	s_waitcnt vmcnt(7)
	ds_write_b128 v191, v[178:181] offset:9216
	s_waitcnt vmcnt(6)
	ds_write_b128 v191, v[220:223] offset:46080
	ds_read_b128 v[178:181], v169 offset:32
	ds_read_b128 v[220:223], v169 offset:4640
	s_waitcnt lgkmcnt(5)
	v_mfma_f32_32x32x16_bf16 v[80:95], v[212:215], v[228:231], v[80:95]
	v_mfma_f32_32x32x16_bf16 v[16:31], v[216:219], v[228:231], v[16:31]
	ds_read_b128 v[228:231], v168 offset:32
	s_waitcnt lgkmcnt(5)
	v_mfma_f32_32x32x16_bf16 v[64:79], v[212:215], v[232:235], v[64:79]
	v_mfma_f32_32x32x16_bf16 v[0:15], v[216:219], v[232:235], v[0:15]
	ds_read_b128 v[232:235], v168 offset:4640
	s_setprio 0
	global_load_dwordx4 v[212:215], v[136:137], off offset:2176
	global_load_dwordx4 v[216:219], v[140:141], off offset:2176
	s_setprio 1
	s_waitcnt lgkmcnt(1)
	v_mfma_f32_32x32x16_bf16 v[112:127], v[178:181], v[228:231], v[112:127]
	v_mfma_f32_32x32x16_bf16 v[48:63], v[220:223], v[228:231], v[48:63]
	s_waitcnt lgkmcnt(0)
	v_mfma_f32_32x32x16_bf16 v[96:111], v[178:181], v[232:235], v[96:111]
	v_mfma_f32_32x32x16_bf16 v[32:47], v[220:223], v[232:235], v[32:47]
	ds_read_b128 v[228:231], v168 offset:9248
	ds_read_b128 v[232:235], v168 offset:13856
	s_waitcnt vmcnt(7)
	ds_write_b128 v191, v[172:175] offset:18432
	s_waitcnt vmcnt(6)
	ds_write_b128 v191, v[224:227] offset:55296
	ds_read_b128 v[172:175], v169 offset:64
	ds_read_b128 v[224:227], v169 offset:4672
	s_waitcnt lgkmcnt(5)
	v_mfma_f32_32x32x16_bf16 v[80:95], v[178:181], v[228:231], v[80:95]
	v_mfma_f32_32x32x16_bf16 v[16:31], v[220:223], v[228:231], v[16:31]
	ds_read_b128 v[228:231], v168 offset:64
	s_waitcnt lgkmcnt(5)
	v_mfma_f32_32x32x16_bf16 v[64:79], v[178:181], v[232:235], v[64:79]
	v_mfma_f32_32x32x16_bf16 v[0:15], v[220:223], v[232:235], v[0:15]
	ds_read_b128 v[232:235], v168 offset:4672
	s_setprio 0
	global_load_dwordx4 v[178:181], v[144:145], off offset:2176
	global_load_dwordx4 v[220:223], v[148:149], off offset:2176
	s_setprio 1
	s_waitcnt lgkmcnt(1)
	v_mfma_f32_32x32x16_bf16 v[112:127], v[172:175], v[228:231], v[112:127]
	v_mfma_f32_32x32x16_bf16 v[48:63], v[224:227], v[228:231], v[48:63]
	s_waitcnt lgkmcnt(0)
	v_mfma_f32_32x32x16_bf16 v[96:111], v[172:175], v[232:235], v[96:111]
	v_mfma_f32_32x32x16_bf16 v[32:47], v[224:227], v[232:235], v[32:47]
	ds_read_b128 v[228:231], v168 offset:9280
	ds_read_b128 v[232:235], v168 offset:13888
	s_waitcnt vmcnt(7)
	ds_write_b128 v191, v[158:161] offset:27648
	s_waitcnt vmcnt(6)
	ds_write_b128 v191, v[162:165] offset:64512
	ds_read_b128 v[158:161], v169 offset:96
	ds_read_b128 v[162:165], v169 offset:4704
	s_waitcnt lgkmcnt(5)
	v_mfma_f32_32x32x16_bf16 v[80:95], v[172:175], v[228:231], v[80:95]
	v_mfma_f32_32x32x16_bf16 v[16:31], v[224:227], v[228:231], v[16:31]
	ds_read_b128 v[228:231], v168 offset:96
	s_waitcnt lgkmcnt(5)
	v_mfma_f32_32x32x16_bf16 v[64:79], v[172:175], v[232:235], v[64:79]
	v_mfma_f32_32x32x16_bf16 v[0:15], v[224:227], v[232:235], v[0:15]
	ds_read_b128 v[232:235], v168 offset:4704
	s_setprio 0
	global_load_dwordx4 v[172:175], v[152:153], off offset:2176
	global_load_dwordx4 v[224:227], v[156:157], off offset:2176
	s_setprio 1
	s_waitcnt lgkmcnt(1)
	v_mfma_f32_32x32x16_bf16 v[112:127], v[158:161], v[228:231], v[112:127]
	v_mfma_f32_32x32x16_bf16 v[48:63], v[162:165], v[228:231], v[48:63]
	s_waitcnt lgkmcnt(0)
	v_mfma_f32_32x32x16_bf16 v[96:111], v[158:161], v[232:235], v[96:111]
	v_mfma_f32_32x32x16_bf16 v[32:47], v[162:165], v[232:235], v[32:47]
	ds_read_b128 v[228:231], v168 offset:9312
	ds_read_b128 v[232:235], v168 offset:13920
	s_waitcnt lgkmcnt(1)
	v_mfma_f32_32x32x16_bf16 v[80:95], v[158:161], v[228:231], v[80:95]
	v_mfma_f32_32x32x16_bf16 v[16:31], v[162:165], v[228:231], v[16:31]
	s_waitcnt lgkmcnt(0)
	v_mfma_f32_32x32x16_bf16 v[64:79], v[158:161], v[232:235], v[64:79]
	v_mfma_f32_32x32x16_bf16 v[0:15], v[162:165], v[232:235], v[0:15]
	s_setprio 0
	global_load_dwordx4 v[158:161], v[128:129], off offset:2304
	global_load_dwordx4 v[162:165], v[132:133], off offset:2304
	s_barrier
; template <bool trans>
; DI void gemm_core(const GTile& tl, const GTile& nx, bool has_next  , bool chain  , bool pre, u32x4 (&ra)[4], u32x4 (&rb)[4], char* smem, f32x16 (&acc)[2][4]) {
;     ...
;   const int nk = K / 64;
;   if (!pre) { G_LOAD(0); G_STORE(0); G_LOAD(1); }
;   for (int kt = 0; kt < nk; ++kt) {
;     __syncthreads();
;     G_COMPUTE(kt & 1, kt);
;   }
	s_waitcnt vmcnt(9)
	ds_write_b128 v195, v[200:203]
	s_waitcnt vmcnt(8)
	ds_write_b128 v196, v[208:211]
	ds_read_b128 v[200:203], v192 offset:36864
	ds_read_b128 v[208:211], v192 offset:41472
	ds_read_b128 v[228:231], v184
	ds_read_b128 v[232:235], v184 offset:4608
	s_setprio 1
	s_waitcnt lgkmcnt(1)
	v_mfma_f32_32x32x16_bf16 v[112:127], v[200:203], v[228:231], v[112:127]
	v_mfma_f32_32x32x16_bf16 v[48:63], v[208:211], v[228:231], v[48:63]
	s_waitcnt lgkmcnt(0)
	v_mfma_f32_32x32x16_bf16 v[96:111], v[200:203], v[232:235], v[96:111]
	v_mfma_f32_32x32x16_bf16 v[32:47], v[208:211], v[232:235], v[32:47]
	ds_read_b128 v[228:231], v184 offset:9216
	ds_read_b128 v[232:235], v184 offset:13824
	s_waitcnt vmcnt(7)
	ds_write_b128 v194, v[212:215]
	s_waitcnt vmcnt(6)
	ds_write_b128 v193, v[216:219]
	ds_read_b128 v[212:215], v192 offset:36896
	ds_read_b128 v[216:219], v192 offset:41504
	s_waitcnt lgkmcnt(5)
	v_mfma_f32_32x32x16_bf16 v[80:95], v[200:203], v[228:231], v[80:95]
	v_mfma_f32_32x32x16_bf16 v[16:31], v[208:211], v[228:231], v[16:31]
	ds_read_b128 v[228:231], v184 offset:32
	s_waitcnt lgkmcnt(5)
	v_mfma_f32_32x32x16_bf16 v[64:79], v[200:203], v[232:235], v[64:79]
	v_mfma_f32_32x32x16_bf16 v[0:15], v[208:211], v[232:235], v[0:15]
	ds_read_b128 v[232:235], v184 offset:4640
	s_setprio 0
	global_load_dwordx4 v[200:203], v[136:137], off offset:2304
	global_load_dwordx4 v[208:211], v[140:141], off offset:2304
	s_setprio 1
	s_waitcnt lgkmcnt(1)
	v_mfma_f32_32x32x16_bf16 v[112:127], v[212:215], v[228:231], v[112:127]
	v_mfma_f32_32x32x16_bf16 v[48:63], v[216:219], v[228:231], v[48:63]
	s_waitcnt lgkmcnt(0)
	v_mfma_f32_32x32x16_bf16 v[96:111], v[212:215], v[232:235], v[96:111]
	v_mfma_f32_32x32x16_bf16 v[32:47], v[216:219], v[232:235], v[32:47]
	ds_read_b128 v[228:231], v184 offset:9248
	ds_read_b128 v[232:235], v184 offset:13856
	s_waitcnt vmcnt(7)
	ds_write_b128 v177, v[178:181]
	s_waitcnt vmcnt(6)
	ds_write_b128 v176, v[220:223]
	ds_read_b128 v[178:181], v192 offset:36928
	ds_read_b128 v[220:223], v192 offset:41536
	s_waitcnt lgkmcnt(5)
	v_mfma_f32_32x32x16_bf16 v[80:95], v[212:215], v[228:231], v[80:95]
	v_mfma_f32_32x32x16_bf16 v[16:31], v[216:219], v[228:231], v[16:31]
	ds_read_b128 v[228:231], v184 offset:64
	s_waitcnt lgkmcnt(5)
	v_mfma_f32_32x32x16_bf16 v[64:79], v[212:215], v[232:235], v[64:79]
	v_mfma_f32_32x32x16_bf16 v[0:15], v[216:219], v[232:235], v[0:15]
	ds_read_b128 v[232:235], v184 offset:4672
	s_setprio 0
	global_load_dwordx4 v[212:215], v[144:145], off offset:2304
	global_load_dwordx4 v[216:219], v[148:149], off offset:2304
	s_setprio 1
	s_waitcnt lgkmcnt(1)
	v_mfma_f32_32x32x16_bf16 v[112:127], v[178:181], v[228:231], v[112:127]
	v_mfma_f32_32x32x16_bf16 v[48:63], v[220:223], v[228:231], v[48:63]
	s_waitcnt lgkmcnt(0)
	v_mfma_f32_32x32x16_bf16 v[96:111], v[178:181], v[232:235], v[96:111]
	v_mfma_f32_32x32x16_bf16 v[32:47], v[220:223], v[232:235], v[32:47]
	ds_read_b128 v[228:231], v184 offset:9280
	ds_read_b128 v[232:235], v184 offset:13888
	s_waitcnt vmcnt(7)
	ds_write_b128 v171, v[172:175]
	s_waitcnt vmcnt(6)
	ds_write_b128 v170, v[224:227]
	ds_read_b128 v[172:175], v192 offset:36960
	ds_read_b128 v[224:227], v192 offset:41568
	s_waitcnt lgkmcnt(5)
	v_mfma_f32_32x32x16_bf16 v[80:95], v[178:181], v[228:231], v[80:95]
	v_mfma_f32_32x32x16_bf16 v[16:31], v[220:223], v[228:231], v[16:31]
	ds_read_b128 v[228:231], v184 offset:96
	s_waitcnt lgkmcnt(5)
	v_mfma_f32_32x32x16_bf16 v[64:79], v[178:181], v[232:235], v[64:79]
	v_mfma_f32_32x32x16_bf16 v[0:15], v[220:223], v[232:235], v[0:15]
	ds_read_b128 v[232:235], v184 offset:4704
	s_setprio 0
	global_load_dwordx4 v[178:181], v[152:153], off offset:2304
	global_load_dwordx4 v[220:223], v[156:157], off offset:2304
	s_setprio 1
	s_waitcnt lgkmcnt(1)
	v_mfma_f32_32x32x16_bf16 v[112:127], v[172:175], v[228:231], v[112:127]
	v_mfma_f32_32x32x16_bf16 v[48:63], v[224:227], v[228:231], v[48:63]
	s_waitcnt lgkmcnt(0)
	v_mfma_f32_32x32x16_bf16 v[96:111], v[172:175], v[232:235], v[96:111]
	v_mfma_f32_32x32x16_bf16 v[32:47], v[224:227], v[232:235], v[32:47]
	ds_read_b128 v[228:231], v184 offset:9312
	ds_read_b128 v[232:235], v184 offset:13920
	s_waitcnt lgkmcnt(1)
	v_mfma_f32_32x32x16_bf16 v[80:95], v[172:175], v[228:231], v[80:95]
	v_mfma_f32_32x32x16_bf16 v[16:31], v[224:227], v[228:231], v[16:31]
	s_waitcnt lgkmcnt(0)
	v_mfma_f32_32x32x16_bf16 v[64:79], v[172:175], v[232:235], v[64:79]
	v_mfma_f32_32x32x16_bf16 v[0:15], v[224:227], v[232:235], v[0:15]
	s_setprio 0
	global_load_dwordx4 v[172:175], v[128:129], off offset:2432
	global_load_dwordx4 v[224:227], v[132:133], off offset:2432
	s_barrier
; template <bool trans>
; DI void gemm_core(const GTile& tl, const GTile& nx, bool has_next  , bool chain  , bool pre, u32x4 (&ra)[4], u32x4 (&rb)[4], char* smem, f32x16 (&acc)[2][4]) {
;     ...
;   const int nk = K / 64;
;   if (!pre) { G_LOAD(0); G_STORE(0); G_LOAD(1); }
;   for (int kt = 0; kt < nk; ++kt) {
;     __syncthreads();
;     G_COMPUTE(kt & 1, kt);
;   }
	s_waitcnt vmcnt(9)
	ds_write_b128 v191, v[158:161]
	s_waitcnt vmcnt(8)
	ds_write_b128 v191, v[162:165] offset:36864
	ds_read_b128 v[158:161], v169
	ds_read_b128 v[162:165], v169 offset:4608
	ds_read_b128 v[228:231], v168
	ds_read_b128 v[232:235], v168 offset:4608
	s_setprio 1
	s_waitcnt lgkmcnt(1)
	v_mfma_f32_32x32x16_bf16 v[112:127], v[158:161], v[228:231], v[112:127]
	v_mfma_f32_32x32x16_bf16 v[48:63], v[162:165], v[228:231], v[48:63]
	s_waitcnt lgkmcnt(0)
	v_mfma_f32_32x32x16_bf16 v[96:111], v[158:161], v[232:235], v[96:111]
	v_mfma_f32_32x32x16_bf16 v[32:47], v[162:165], v[232:235], v[32:47]
	ds_read_b128 v[228:231], v168 offset:9216
	ds_read_b128 v[232:235], v168 offset:13824
	s_waitcnt vmcnt(7)
	ds_write_b128 v191, v[200:203] offset:9216
	s_waitcnt vmcnt(6)
	ds_write_b128 v191, v[208:211] offset:46080
	ds_read_b128 v[200:203], v169 offset:32
	ds_read_b128 v[208:211], v169 offset:4640
	s_waitcnt lgkmcnt(5)
	v_mfma_f32_32x32x16_bf16 v[80:95], v[158:161], v[228:231], v[80:95]
	v_mfma_f32_32x32x16_bf16 v[16:31], v[162:165], v[228:231], v[16:31]
	ds_read_b128 v[228:231], v168 offset:32
	s_waitcnt lgkmcnt(5)
	v_mfma_f32_32x32x16_bf16 v[64:79], v[158:161], v[232:235], v[64:79]
	v_mfma_f32_32x32x16_bf16 v[0:15], v[162:165], v[232:235], v[0:15]
	ds_read_b128 v[232:235], v168 offset:4640
	s_setprio 0
	global_load_dwordx4 v[158:161], v[136:137], off offset:2432
	global_load_dwordx4 v[162:165], v[140:141], off offset:2432
	s_setprio 1
	s_waitcnt lgkmcnt(1)
	v_mfma_f32_32x32x16_bf16 v[112:127], v[200:203], v[228:231], v[112:127]
	v_mfma_f32_32x32x16_bf16 v[48:63], v[208:211], v[228:231], v[48:63]
	s_waitcnt lgkmcnt(0)
	v_mfma_f32_32x32x16_bf16 v[96:111], v[200:203], v[232:235], v[96:111]
	v_mfma_f32_32x32x16_bf16 v[32:47], v[208:211], v[232:235], v[32:47]
	ds_read_b128 v[228:231], v168 offset:9248
	ds_read_b128 v[232:235], v168 offset:13856
	s_waitcnt vmcnt(7)
	ds_write_b128 v191, v[212:215] offset:18432
	s_waitcnt vmcnt(6)
	ds_write_b128 v191, v[216:219] offset:55296
	ds_read_b128 v[212:215], v169 offset:64
	ds_read_b128 v[216:219], v169 offset:4672
	s_waitcnt lgkmcnt(5)
	v_mfma_f32_32x32x16_bf16 v[80:95], v[200:203], v[228:231], v[80:95]
	v_mfma_f32_32x32x16_bf16 v[16:31], v[208:211], v[228:231], v[16:31]
	ds_read_b128 v[228:231], v168 offset:64
	s_waitcnt lgkmcnt(5)
	v_mfma_f32_32x32x16_bf16 v[64:79], v[200:203], v[232:235], v[64:79]
	v_mfma_f32_32x32x16_bf16 v[0:15], v[208:211], v[232:235], v[0:15]
	ds_read_b128 v[232:235], v168 offset:4672
	s_setprio 0
	global_load_dwordx4 v[200:203], v[144:145], off offset:2432
	global_load_dwordx4 v[208:211], v[148:149], off offset:2432
	s_setprio 1
	s_waitcnt lgkmcnt(1)
	v_mfma_f32_32x32x16_bf16 v[112:127], v[212:215], v[228:231], v[112:127]
	v_mfma_f32_32x32x16_bf16 v[48:63], v[216:219], v[228:231], v[48:63]
	s_waitcnt lgkmcnt(0)
	v_mfma_f32_32x32x16_bf16 v[96:111], v[212:215], v[232:235], v[96:111]
	v_mfma_f32_32x32x16_bf16 v[32:47], v[216:219], v[232:235], v[32:47]
	ds_read_b128 v[228:231], v168 offset:9280
	ds_read_b128 v[232:235], v168 offset:13888
	s_waitcnt vmcnt(7)
	ds_write_b128 v191, v[178:181] offset:27648
	s_waitcnt vmcnt(6)
	ds_write_b128 v191, v[220:223] offset:64512
	ds_read_b128 v[178:181], v169 offset:96
	ds_read_b128 v[220:223], v169 offset:4704
	s_waitcnt lgkmcnt(5)
	v_mfma_f32_32x32x16_bf16 v[80:95], v[212:215], v[228:231], v[80:95]
	v_mfma_f32_32x32x16_bf16 v[16:31], v[216:219], v[228:231], v[16:31]
	ds_read_b128 v[228:231], v168 offset:96
	s_waitcnt lgkmcnt(5)
	v_mfma_f32_32x32x16_bf16 v[64:79], v[212:215], v[232:235], v[64:79]
	v_mfma_f32_32x32x16_bf16 v[0:15], v[216:219], v[232:235], v[0:15]
	ds_read_b128 v[232:235], v168 offset:4704
	s_setprio 0
	global_load_dwordx4 v[212:215], v[152:153], off offset:2432
	global_load_dwordx4 v[216:219], v[156:157], off offset:2432
	s_setprio 1
	s_waitcnt lgkmcnt(1)
	v_mfma_f32_32x32x16_bf16 v[112:127], v[178:181], v[228:231], v[112:127]
	v_mfma_f32_32x32x16_bf16 v[48:63], v[220:223], v[228:231], v[48:63]
	s_waitcnt lgkmcnt(0)
	v_mfma_f32_32x32x16_bf16 v[96:111], v[178:181], v[232:235], v[96:111]
	v_mfma_f32_32x32x16_bf16 v[32:47], v[220:223], v[232:235], v[32:47]
	ds_read_b128 v[228:231], v168 offset:9312
	ds_read_b128 v[232:235], v168 offset:13920
	s_waitcnt lgkmcnt(1)
	v_mfma_f32_32x32x16_bf16 v[80:95], v[178:181], v[228:231], v[80:95]
	v_mfma_f32_32x32x16_bf16 v[16:31], v[220:223], v[228:231], v[16:31]
	s_waitcnt lgkmcnt(0)
	v_mfma_f32_32x32x16_bf16 v[64:79], v[178:181], v[232:235], v[64:79]
	v_mfma_f32_32x32x16_bf16 v[0:15], v[220:223], v[232:235], v[0:15]
	s_setprio 0
	global_load_dwordx4 v[178:181], v[128:129], off offset:2560
	global_load_dwordx4 v[220:223], v[132:133], off offset:2560
	s_barrier
; template <bool trans>
; DI void gemm_core(const GTile& tl, const GTile& nx, bool has_next  , bool chain  , bool pre, u32x4 (&ra)[4], u32x4 (&rb)[4], char* smem, f32x16 (&acc)[2][4]) {
;     ...
;   const int nk = K / 64;
;   if (!pre) { G_LOAD(0); G_STORE(0); G_LOAD(1); }
;   for (int kt = 0; kt < nk; ++kt) {
;     __syncthreads();
;     G_COMPUTE(kt & 1, kt);
;   }
	s_waitcnt vmcnt(9)
	ds_write_b128 v195, v[172:175]
	s_waitcnt vmcnt(8)
	ds_write_b128 v196, v[224:227]
	ds_read_b128 v[172:175], v192 offset:36864
	ds_read_b128 v[224:227], v192 offset:41472
	ds_read_b128 v[228:231], v184
	ds_read_b128 v[232:235], v184 offset:4608
	s_setprio 1
	s_waitcnt lgkmcnt(1)
	v_mfma_f32_32x32x16_bf16 v[112:127], v[172:175], v[228:231], v[112:127]
	v_mfma_f32_32x32x16_bf16 v[48:63], v[224:227], v[228:231], v[48:63]
	s_waitcnt lgkmcnt(0)
	v_mfma_f32_32x32x16_bf16 v[96:111], v[172:175], v[232:235], v[96:111]
	v_mfma_f32_32x32x16_bf16 v[32:47], v[224:227], v[232:235], v[32:47]
	ds_read_b128 v[228:231], v184 offset:9216
	ds_read_b128 v[232:235], v184 offset:13824
	s_waitcnt vmcnt(7)
	ds_write_b128 v194, v[158:161]
	s_waitcnt vmcnt(6)
	ds_write_b128 v193, v[162:165]
	ds_read_b128 v[158:161], v192 offset:36896
	ds_read_b128 v[162:165], v192 offset:41504
	s_waitcnt lgkmcnt(5)
	v_mfma_f32_32x32x16_bf16 v[80:95], v[172:175], v[228:231], v[80:95]
	v_mfma_f32_32x32x16_bf16 v[16:31], v[224:227], v[228:231], v[16:31]
	ds_read_b128 v[228:231], v184 offset:32
	s_waitcnt lgkmcnt(5)
	v_mfma_f32_32x32x16_bf16 v[64:79], v[172:175], v[232:235], v[64:79]
	v_mfma_f32_32x32x16_bf16 v[0:15], v[224:227], v[232:235], v[0:15]
	ds_read_b128 v[232:235], v184 offset:4640
	s_setprio 0
	global_load_dwordx4 v[172:175], v[136:137], off offset:2560
	global_load_dwordx4 v[224:227], v[140:141], off offset:2560
	s_setprio 1
	s_waitcnt lgkmcnt(1)
	v_mfma_f32_32x32x16_bf16 v[112:127], v[158:161], v[228:231], v[112:127]
	v_mfma_f32_32x32x16_bf16 v[48:63], v[162:165], v[228:231], v[48:63]
	s_waitcnt lgkmcnt(0)
	v_mfma_f32_32x32x16_bf16 v[96:111], v[158:161], v[232:235], v[96:111]
	v_mfma_f32_32x32x16_bf16 v[32:47], v[162:165], v[232:235], v[32:47]
	ds_read_b128 v[228:231], v184 offset:9248
	ds_read_b128 v[232:235], v184 offset:13856
	s_waitcnt vmcnt(7)
	ds_write_b128 v177, v[200:203]
	s_waitcnt vmcnt(6)
	ds_write_b128 v176, v[208:211]
	ds_read_b128 v[200:203], v192 offset:36928
	ds_read_b128 v[208:211], v192 offset:41536
	s_waitcnt lgkmcnt(5)
	v_mfma_f32_32x32x16_bf16 v[80:95], v[158:161], v[228:231], v[80:95]
	v_mfma_f32_32x32x16_bf16 v[16:31], v[162:165], v[228:231], v[16:31]
	ds_read_b128 v[228:231], v184 offset:64
	s_waitcnt lgkmcnt(5)
	v_mfma_f32_32x32x16_bf16 v[64:79], v[158:161], v[232:235], v[64:79]
	v_mfma_f32_32x32x16_bf16 v[0:15], v[162:165], v[232:235], v[0:15]
	ds_read_b128 v[232:235], v184 offset:4672
	s_setprio 0
	global_load_dwordx4 v[158:161], v[144:145], off offset:2560
	global_load_dwordx4 v[162:165], v[148:149], off offset:2560
	s_setprio 1
	s_waitcnt lgkmcnt(1)
	v_mfma_f32_32x32x16_bf16 v[112:127], v[200:203], v[228:231], v[112:127]
	v_mfma_f32_32x32x16_bf16 v[48:63], v[208:211], v[228:231], v[48:63]
	s_waitcnt lgkmcnt(0)
	v_mfma_f32_32x32x16_bf16 v[96:111], v[200:203], v[232:235], v[96:111]
	v_mfma_f32_32x32x16_bf16 v[32:47], v[208:211], v[232:235], v[32:47]
	ds_read_b128 v[228:231], v184 offset:9280
	ds_read_b128 v[232:235], v184 offset:13888
	s_waitcnt vmcnt(7)
	ds_write_b128 v171, v[212:215]
	s_waitcnt vmcnt(6)
	ds_write_b128 v170, v[216:219]
	ds_read_b128 v[212:215], v192 offset:36960
	ds_read_b128 v[216:219], v192 offset:41568
	s_waitcnt lgkmcnt(5)
	v_mfma_f32_32x32x16_bf16 v[80:95], v[200:203], v[228:231], v[80:95]
	v_mfma_f32_32x32x16_bf16 v[16:31], v[208:211], v[228:231], v[16:31]
	ds_read_b128 v[228:231], v184 offset:96
	s_waitcnt lgkmcnt(5)
	v_mfma_f32_32x32x16_bf16 v[64:79], v[200:203], v[232:235], v[64:79]
	v_mfma_f32_32x32x16_bf16 v[0:15], v[208:211], v[232:235], v[0:15]
	ds_read_b128 v[232:235], v184 offset:4704
	s_setprio 0
	global_load_dwordx4 v[200:203], v[152:153], off offset:2560
	global_load_dwordx4 v[208:211], v[156:157], off offset:2560
	s_setprio 1
	s_waitcnt lgkmcnt(1)
	v_mfma_f32_32x32x16_bf16 v[112:127], v[212:215], v[228:231], v[112:127]
	v_mfma_f32_32x32x16_bf16 v[48:63], v[216:219], v[228:231], v[48:63]
	s_waitcnt lgkmcnt(0)
	v_mfma_f32_32x32x16_bf16 v[96:111], v[212:215], v[232:235], v[96:111]
	v_mfma_f32_32x32x16_bf16 v[32:47], v[216:219], v[232:235], v[32:47]
	ds_read_b128 v[228:231], v184 offset:9312
	ds_read_b128 v[232:235], v184 offset:13920
	s_waitcnt lgkmcnt(1)
	v_mfma_f32_32x32x16_bf16 v[80:95], v[212:215], v[228:231], v[80:95]
	v_mfma_f32_32x32x16_bf16 v[16:31], v[216:219], v[228:231], v[16:31]
	s_waitcnt lgkmcnt(0)
	v_mfma_f32_32x32x16_bf16 v[64:79], v[212:215], v[232:235], v[64:79]
	v_mfma_f32_32x32x16_bf16 v[0:15], v[216:219], v[232:235], v[0:15]
	s_setprio 0
	global_load_dwordx4 v[212:215], v[128:129], off offset:2688
	global_load_dwordx4 v[216:219], v[132:133], off offset:2688
	s_barrier
; template <bool trans>
; DI void gemm_core(const GTile& tl, const GTile& nx, bool has_next  , bool chain  , bool pre, u32x4 (&ra)[4], u32x4 (&rb)[4], char* smem, f32x16 (&acc)[2][4]) {
;     ...
;   const int nk = K / 64;
;   if (!pre) { G_LOAD(0); G_STORE(0); G_LOAD(1); }
;   for (int kt = 0; kt < nk; ++kt) {
;     __syncthreads();
;     G_COMPUTE(kt & 1, kt);
;   }
	s_waitcnt vmcnt(9)
	ds_write_b128 v191, v[178:181]
	s_waitcnt vmcnt(8)
	ds_write_b128 v191, v[220:223] offset:36864
	ds_read_b128 v[178:181], v169
	ds_read_b128 v[220:223], v169 offset:4608
	ds_read_b128 v[228:231], v168
	ds_read_b128 v[232:235], v168 offset:4608
	s_setprio 1
	s_waitcnt lgkmcnt(1)
	v_mfma_f32_32x32x16_bf16 v[112:127], v[178:181], v[228:231], v[112:127]
	v_mfma_f32_32x32x16_bf16 v[48:63], v[220:223], v[228:231], v[48:63]
	s_waitcnt lgkmcnt(0)
	v_mfma_f32_32x32x16_bf16 v[96:111], v[178:181], v[232:235], v[96:111]
	v_mfma_f32_32x32x16_bf16 v[32:47], v[220:223], v[232:235], v[32:47]
	ds_read_b128 v[228:231], v168 offset:9216
	ds_read_b128 v[232:235], v168 offset:13824
	s_waitcnt vmcnt(7)
	ds_write_b128 v191, v[172:175] offset:9216
	s_waitcnt vmcnt(6)
	ds_write_b128 v191, v[224:227] offset:46080
	ds_read_b128 v[172:175], v169 offset:32
	ds_read_b128 v[224:227], v169 offset:4640
	s_waitcnt lgkmcnt(5)
	v_mfma_f32_32x32x16_bf16 v[80:95], v[178:181], v[228:231], v[80:95]
	v_mfma_f32_32x32x16_bf16 v[16:31], v[220:223], v[228:231], v[16:31]
	ds_read_b128 v[228:231], v168 offset:32
	s_waitcnt lgkmcnt(5)
	v_mfma_f32_32x32x16_bf16 v[64:79], v[178:181], v[232:235], v[64:79]
	v_mfma_f32_32x32x16_bf16 v[0:15], v[220:223], v[232:235], v[0:15]
	ds_read_b128 v[232:235], v168 offset:4640
	s_setprio 0
	global_load_dwordx4 v[178:181], v[136:137], off offset:2688
	global_load_dwordx4 v[220:223], v[140:141], off offset:2688
	s_setprio 1
	s_waitcnt lgkmcnt(1)
	v_mfma_f32_32x32x16_bf16 v[112:127], v[172:175], v[228:231], v[112:127]
	v_mfma_f32_32x32x16_bf16 v[48:63], v[224:227], v[228:231], v[48:63]
	s_waitcnt lgkmcnt(0)
	v_mfma_f32_32x32x16_bf16 v[96:111], v[172:175], v[232:235], v[96:111]
	v_mfma_f32_32x32x16_bf16 v[32:47], v[224:227], v[232:235], v[32:47]
	ds_read_b128 v[228:231], v168 offset:9248
	ds_read_b128 v[232:235], v168 offset:13856
	s_waitcnt vmcnt(7)
	ds_write_b128 v191, v[158:161] offset:18432
	s_waitcnt vmcnt(6)
	ds_write_b128 v191, v[162:165] offset:55296
	ds_read_b128 v[158:161], v169 offset:64
	ds_read_b128 v[162:165], v169 offset:4672
	s_waitcnt lgkmcnt(5)
	v_mfma_f32_32x32x16_bf16 v[80:95], v[172:175], v[228:231], v[80:95]
	v_mfma_f32_32x32x16_bf16 v[16:31], v[224:227], v[228:231], v[16:31]
	ds_read_b128 v[228:231], v168 offset:64
	s_waitcnt lgkmcnt(5)
	v_mfma_f32_32x32x16_bf16 v[64:79], v[172:175], v[232:235], v[64:79]
	v_mfma_f32_32x32x16_bf16 v[0:15], v[224:227], v[232:235], v[0:15]
	ds_read_b128 v[232:235], v168 offset:4672
	s_setprio 0
	global_load_dwordx4 v[172:175], v[144:145], off offset:2688
	global_load_dwordx4 v[224:227], v[148:149], off offset:2688
	s_setprio 1
	s_waitcnt lgkmcnt(1)
	v_mfma_f32_32x32x16_bf16 v[112:127], v[158:161], v[228:231], v[112:127]
	v_mfma_f32_32x32x16_bf16 v[48:63], v[162:165], v[228:231], v[48:63]
	s_waitcnt lgkmcnt(0)
	v_mfma_f32_32x32x16_bf16 v[96:111], v[158:161], v[232:235], v[96:111]
	v_mfma_f32_32x32x16_bf16 v[32:47], v[162:165], v[232:235], v[32:47]
	ds_read_b128 v[228:231], v168 offset:9280
	ds_read_b128 v[232:235], v168 offset:13888
	s_waitcnt vmcnt(7)
	ds_write_b128 v191, v[200:203] offset:27648
	s_waitcnt vmcnt(6)
	ds_write_b128 v191, v[208:211] offset:64512
	ds_read_b128 v[200:203], v169 offset:96
	ds_read_b128 v[208:211], v169 offset:4704
	s_waitcnt lgkmcnt(5)
	v_mfma_f32_32x32x16_bf16 v[80:95], v[158:161], v[228:231], v[80:95]
	v_mfma_f32_32x32x16_bf16 v[16:31], v[162:165], v[228:231], v[16:31]
	ds_read_b128 v[228:231], v168 offset:96
	s_waitcnt lgkmcnt(5)
	v_mfma_f32_32x32x16_bf16 v[64:79], v[158:161], v[232:235], v[64:79]
	v_mfma_f32_32x32x16_bf16 v[0:15], v[162:165], v[232:235], v[0:15]
	ds_read_b128 v[232:235], v168 offset:4704
	s_setprio 0
	global_load_dwordx4 v[158:161], v[152:153], off offset:2688
	global_load_dwordx4 v[162:165], v[156:157], off offset:2688
	s_setprio 1
	s_waitcnt lgkmcnt(1)
	v_mfma_f32_32x32x16_bf16 v[112:127], v[200:203], v[228:231], v[112:127]
	v_mfma_f32_32x32x16_bf16 v[48:63], v[208:211], v[228:231], v[48:63]
	s_waitcnt lgkmcnt(0)
	v_mfma_f32_32x32x16_bf16 v[96:111], v[200:203], v[232:235], v[96:111]
	v_mfma_f32_32x32x16_bf16 v[32:47], v[208:211], v[232:235], v[32:47]
	ds_read_b128 v[228:231], v168 offset:9312
	ds_read_b128 v[232:235], v168 offset:13920
	s_waitcnt lgkmcnt(1)
	v_mfma_f32_32x32x16_bf16 v[80:95], v[200:203], v[228:231], v[80:95]
	v_mfma_f32_32x32x16_bf16 v[16:31], v[208:211], v[228:231], v[16:31]
	s_waitcnt lgkmcnt(0)
	v_mfma_f32_32x32x16_bf16 v[64:79], v[200:203], v[232:235], v[64:79]
	v_mfma_f32_32x32x16_bf16 v[0:15], v[208:211], v[232:235], v[0:15]
	s_setprio 0
	global_load_dwordx4 v[200:203], v[128:129], off offset:2816
	global_load_dwordx4 v[208:211], v[132:133], off offset:2816
	s_barrier
; template <bool trans>
; DI void gemm_core(const GTile& tl, const GTile& nx, bool has_next  , bool chain  , bool pre, u32x4 (&ra)[4], u32x4 (&rb)[4], char* smem, f32x16 (&acc)[2][4]) {
;     ...
;   const int nk = K / 64;
;   if (!pre) { G_LOAD(0); G_STORE(0); G_LOAD(1); }
;   for (int kt = 0; kt < nk; ++kt) {
;     __syncthreads();
;     G_COMPUTE(kt & 1, kt);
;   }
	s_waitcnt vmcnt(9)
	ds_write_b128 v195, v[212:215]
	s_waitcnt vmcnt(8)
	ds_write_b128 v196, v[216:219]
	ds_read_b128 v[212:215], v192 offset:36864
	ds_read_b128 v[216:219], v192 offset:41472
	ds_read_b128 v[228:231], v184
	ds_read_b128 v[232:235], v184 offset:4608
	s_setprio 1
	s_waitcnt lgkmcnt(1)
	v_mfma_f32_32x32x16_bf16 v[112:127], v[212:215], v[228:231], v[112:127]
	v_mfma_f32_32x32x16_bf16 v[48:63], v[216:219], v[228:231], v[48:63]
	s_waitcnt lgkmcnt(0)
	v_mfma_f32_32x32x16_bf16 v[96:111], v[212:215], v[232:235], v[96:111]
	v_mfma_f32_32x32x16_bf16 v[32:47], v[216:219], v[232:235], v[32:47]
	ds_read_b128 v[228:231], v184 offset:9216
	ds_read_b128 v[232:235], v184 offset:13824
	s_waitcnt vmcnt(7)
	ds_write_b128 v194, v[178:181]
	s_waitcnt vmcnt(6)
	ds_write_b128 v193, v[220:223]
	ds_read_b128 v[178:181], v192 offset:36896
	ds_read_b128 v[220:223], v192 offset:41504
	s_waitcnt lgkmcnt(5)
	v_mfma_f32_32x32x16_bf16 v[80:95], v[212:215], v[228:231], v[80:95]
	v_mfma_f32_32x32x16_bf16 v[16:31], v[216:219], v[228:231], v[16:31]
	ds_read_b128 v[228:231], v184 offset:32
	s_waitcnt lgkmcnt(5)
	v_mfma_f32_32x32x16_bf16 v[64:79], v[212:215], v[232:235], v[64:79]
	v_mfma_f32_32x32x16_bf16 v[0:15], v[216:219], v[232:235], v[0:15]
	ds_read_b128 v[232:235], v184 offset:4640
	s_setprio 0
	global_load_dwordx4 v[212:215], v[136:137], off offset:2816
	global_load_dwordx4 v[216:219], v[140:141], off offset:2816
	s_setprio 1
	s_waitcnt lgkmcnt(1)
	v_mfma_f32_32x32x16_bf16 v[112:127], v[178:181], v[228:231], v[112:127]
	v_mfma_f32_32x32x16_bf16 v[48:63], v[220:223], v[228:231], v[48:63]
	s_waitcnt lgkmcnt(0)
	v_mfma_f32_32x32x16_bf16 v[96:111], v[178:181], v[232:235], v[96:111]
	v_mfma_f32_32x32x16_bf16 v[32:47], v[220:223], v[232:235], v[32:47]
	ds_read_b128 v[228:231], v184 offset:9248
	ds_read_b128 v[232:235], v184 offset:13856
	s_waitcnt vmcnt(7)
	ds_write_b128 v177, v[172:175]
	s_waitcnt vmcnt(6)
	ds_write_b128 v176, v[224:227]
	ds_read_b128 v[172:175], v192 offset:36928
	ds_read_b128 v[224:227], v192 offset:41536
	s_waitcnt lgkmcnt(5)
	v_mfma_f32_32x32x16_bf16 v[80:95], v[178:181], v[228:231], v[80:95]
	v_mfma_f32_32x32x16_bf16 v[16:31], v[220:223], v[228:231], v[16:31]
	ds_read_b128 v[228:231], v184 offset:64
	s_waitcnt lgkmcnt(5)
	v_mfma_f32_32x32x16_bf16 v[64:79], v[178:181], v[232:235], v[64:79]
	v_mfma_f32_32x32x16_bf16 v[0:15], v[220:223], v[232:235], v[0:15]
	ds_read_b128 v[232:235], v184 offset:4672
	s_setprio 0
	global_load_dwordx4 v[178:181], v[144:145], off offset:2816
	global_load_dwordx4 v[220:223], v[148:149], off offset:2816
	s_setprio 1
	s_waitcnt lgkmcnt(1)
	v_mfma_f32_32x32x16_bf16 v[112:127], v[172:175], v[228:231], v[112:127]
	v_mfma_f32_32x32x16_bf16 v[48:63], v[224:227], v[228:231], v[48:63]
	s_waitcnt lgkmcnt(0)
	v_mfma_f32_32x32x16_bf16 v[96:111], v[172:175], v[232:235], v[96:111]
	v_mfma_f32_32x32x16_bf16 v[32:47], v[224:227], v[232:235], v[32:47]
	ds_read_b128 v[228:231], v184 offset:9280
	ds_read_b128 v[232:235], v184 offset:13888
	s_waitcnt vmcnt(7)
	ds_write_b128 v171, v[158:161]
	s_waitcnt vmcnt(6)
	ds_write_b128 v170, v[162:165]
	ds_read_b128 v[158:161], v192 offset:36960
	ds_read_b128 v[162:165], v192 offset:41568
	s_waitcnt lgkmcnt(5)
	v_mfma_f32_32x32x16_bf16 v[80:95], v[172:175], v[228:231], v[80:95]
	v_mfma_f32_32x32x16_bf16 v[16:31], v[224:227], v[228:231], v[16:31]
	ds_read_b128 v[228:231], v184 offset:96
	s_waitcnt lgkmcnt(5)
	v_mfma_f32_32x32x16_bf16 v[64:79], v[172:175], v[232:235], v[64:79]
	v_mfma_f32_32x32x16_bf16 v[0:15], v[224:227], v[232:235], v[0:15]
	ds_read_b128 v[232:235], v184 offset:4704
	s_setprio 0
	global_load_dwordx4 v[172:175], v[152:153], off offset:2816
	global_load_dwordx4 v[224:227], v[156:157], off offset:2816
	s_setprio 1
	s_waitcnt lgkmcnt(1)
	v_mfma_f32_32x32x16_bf16 v[112:127], v[158:161], v[228:231], v[112:127]
	v_mfma_f32_32x32x16_bf16 v[48:63], v[162:165], v[228:231], v[48:63]
	s_waitcnt lgkmcnt(0)
	v_mfma_f32_32x32x16_bf16 v[96:111], v[158:161], v[232:235], v[96:111]
	v_mfma_f32_32x32x16_bf16 v[32:47], v[162:165], v[232:235], v[32:47]
	ds_read_b128 v[228:231], v184 offset:9312
	ds_read_b128 v[232:235], v184 offset:13920
	s_waitcnt lgkmcnt(1)
	v_mfma_f32_32x32x16_bf16 v[80:95], v[158:161], v[228:231], v[80:95]
	v_mfma_f32_32x32x16_bf16 v[16:31], v[162:165], v[228:231], v[16:31]
	s_waitcnt lgkmcnt(0)
	v_mfma_f32_32x32x16_bf16 v[64:79], v[158:161], v[232:235], v[64:79]
	v_mfma_f32_32x32x16_bf16 v[0:15], v[162:165], v[232:235], v[0:15]
	s_setprio 0
	global_load_dwordx4 v[158:161], v[128:129], off offset:2944
	global_load_dwordx4 v[162:165], v[132:133], off offset:2944
	s_barrier
; template <bool trans>
; DI void gemm_core(const GTile& tl, const GTile& nx, bool has_next  , bool chain  , bool pre, u32x4 (&ra)[4], u32x4 (&rb)[4], char* smem, f32x16 (&acc)[2][4]) {
;     ...
;   const int nk = K / 64;
;   if (!pre) { G_LOAD(0); G_STORE(0); G_LOAD(1); }
;   for (int kt = 0; kt < nk; ++kt) {
;     __syncthreads();
;     G_COMPUTE(kt & 1, kt);
;   }
	s_waitcnt vmcnt(9)
	ds_write_b128 v191, v[200:203]
	s_waitcnt vmcnt(8)
	ds_write_b128 v191, v[208:211] offset:36864
	ds_read_b128 v[200:203], v169
	ds_read_b128 v[208:211], v169 offset:4608
	ds_read_b128 v[228:231], v168
	ds_read_b128 v[232:235], v168 offset:4608
	s_setprio 1
	s_waitcnt lgkmcnt(1)
	v_mfma_f32_32x32x16_bf16 v[112:127], v[200:203], v[228:231], v[112:127]
	v_mfma_f32_32x32x16_bf16 v[48:63], v[208:211], v[228:231], v[48:63]
	s_waitcnt lgkmcnt(0)
	v_mfma_f32_32x32x16_bf16 v[96:111], v[200:203], v[232:235], v[96:111]
	v_mfma_f32_32x32x16_bf16 v[32:47], v[208:211], v[232:235], v[32:47]
	ds_read_b128 v[228:231], v168 offset:9216
	ds_read_b128 v[232:235], v168 offset:13824
	s_waitcnt vmcnt(7)
	ds_write_b128 v191, v[212:215] offset:9216
	s_waitcnt vmcnt(6)
	ds_write_b128 v191, v[216:219] offset:46080
	ds_read_b128 v[212:215], v169 offset:32
	ds_read_b128 v[216:219], v169 offset:4640
	s_waitcnt lgkmcnt(5)
	v_mfma_f32_32x32x16_bf16 v[80:95], v[200:203], v[228:231], v[80:95]
	v_mfma_f32_32x32x16_bf16 v[16:31], v[208:211], v[228:231], v[16:31]
	ds_read_b128 v[228:231], v168 offset:32
	s_waitcnt lgkmcnt(5)
	v_mfma_f32_32x32x16_bf16 v[64:79], v[200:203], v[232:235], v[64:79]
	v_mfma_f32_32x32x16_bf16 v[0:15], v[208:211], v[232:235], v[0:15]
	ds_read_b128 v[232:235], v168 offset:4640
	s_setprio 0
	global_load_dwordx4 v[200:203], v[136:137], off offset:2944
	global_load_dwordx4 v[208:211], v[140:141], off offset:2944
	s_setprio 1
	s_waitcnt lgkmcnt(1)
	v_mfma_f32_32x32x16_bf16 v[112:127], v[212:215], v[228:231], v[112:127]
	v_mfma_f32_32x32x16_bf16 v[48:63], v[216:219], v[228:231], v[48:63]
	s_waitcnt lgkmcnt(0)
	v_mfma_f32_32x32x16_bf16 v[96:111], v[212:215], v[232:235], v[96:111]
	v_mfma_f32_32x32x16_bf16 v[32:47], v[216:219], v[232:235], v[32:47]
	ds_read_b128 v[228:231], v168 offset:9248
	ds_read_b128 v[232:235], v168 offset:13856
	s_waitcnt vmcnt(7)
	ds_write_b128 v191, v[178:181] offset:18432
	s_waitcnt vmcnt(6)
	ds_write_b128 v191, v[220:223] offset:55296
	ds_read_b128 v[178:181], v169 offset:64
	ds_read_b128 v[220:223], v169 offset:4672
	s_waitcnt lgkmcnt(5)
	v_mfma_f32_32x32x16_bf16 v[80:95], v[212:215], v[228:231], v[80:95]
	v_mfma_f32_32x32x16_bf16 v[16:31], v[216:219], v[228:231], v[16:31]
	ds_read_b128 v[228:231], v168 offset:64
	s_waitcnt lgkmcnt(5)
	v_mfma_f32_32x32x16_bf16 v[64:79], v[212:215], v[232:235], v[64:79]
	v_mfma_f32_32x32x16_bf16 v[0:15], v[216:219], v[232:235], v[0:15]
	ds_read_b128 v[232:235], v168 offset:4672
	s_setprio 0
	global_load_dwordx4 v[212:215], v[144:145], off offset:2944
	global_load_dwordx4 v[216:219], v[148:149], off offset:2944
	s_setprio 1
	s_waitcnt lgkmcnt(1)
	v_mfma_f32_32x32x16_bf16 v[112:127], v[178:181], v[228:231], v[112:127]
	v_mfma_f32_32x32x16_bf16 v[48:63], v[220:223], v[228:231], v[48:63]
	s_waitcnt lgkmcnt(0)
	v_mfma_f32_32x32x16_bf16 v[96:111], v[178:181], v[232:235], v[96:111]
	v_mfma_f32_32x32x16_bf16 v[32:47], v[220:223], v[232:235], v[32:47]
	ds_read_b128 v[228:231], v168 offset:9280
	ds_read_b128 v[232:235], v168 offset:13888
	s_waitcnt vmcnt(7)
	ds_write_b128 v191, v[172:175] offset:27648
	s_waitcnt vmcnt(6)
	ds_write_b128 v191, v[224:227] offset:64512
	ds_read_b128 v[172:175], v169 offset:96
	ds_read_b128 v[224:227], v169 offset:4704
	s_waitcnt lgkmcnt(5)
	v_mfma_f32_32x32x16_bf16 v[80:95], v[178:181], v[228:231], v[80:95]
	v_mfma_f32_32x32x16_bf16 v[16:31], v[220:223], v[228:231], v[16:31]
	ds_read_b128 v[228:231], v168 offset:96
	s_waitcnt lgkmcnt(5)
	v_mfma_f32_32x32x16_bf16 v[64:79], v[178:181], v[232:235], v[64:79]
	v_mfma_f32_32x32x16_bf16 v[0:15], v[220:223], v[232:235], v[0:15]
	ds_read_b128 v[232:235], v168 offset:4704
	s_setprio 0
	global_load_dwordx4 v[178:181], v[152:153], off offset:2944
	global_load_dwordx4 v[220:223], v[156:157], off offset:2944
	s_setprio 1
	s_waitcnt lgkmcnt(1)
	v_mfma_f32_32x32x16_bf16 v[112:127], v[172:175], v[228:231], v[112:127]
	v_mfma_f32_32x32x16_bf16 v[48:63], v[224:227], v[228:231], v[48:63]
	s_waitcnt lgkmcnt(0)
	v_mfma_f32_32x32x16_bf16 v[96:111], v[172:175], v[232:235], v[96:111]
	v_mfma_f32_32x32x16_bf16 v[32:47], v[224:227], v[232:235], v[32:47]
	ds_read_b128 v[228:231], v168 offset:9312
	ds_read_b128 v[232:235], v168 offset:13920
	s_waitcnt lgkmcnt(1)
	v_mfma_f32_32x32x16_bf16 v[80:95], v[172:175], v[228:231], v[80:95]
	v_mfma_f32_32x32x16_bf16 v[16:31], v[224:227], v[228:231], v[16:31]
	s_waitcnt lgkmcnt(0)
	v_mfma_f32_32x32x16_bf16 v[64:79], v[172:175], v[232:235], v[64:79]
	v_mfma_f32_32x32x16_bf16 v[0:15], v[224:227], v[232:235], v[0:15]
	s_setprio 0
	global_load_dwordx4 v[172:175], v[128:129], off offset:3072
	global_load_dwordx4 v[224:227], v[132:133], off offset:3072
	s_barrier
; template <bool trans>
; DI void gemm_core(const GTile& tl, const GTile& nx, bool has_next  , bool chain  , bool pre, u32x4 (&ra)[4], u32x4 (&rb)[4], char* smem, f32x16 (&acc)[2][4]) {
;     ...
;   const int nk = K / 64;
;   if (!pre) { G_LOAD(0); G_STORE(0); G_LOAD(1); }
;   for (int kt = 0; kt < nk; ++kt) {
;     __syncthreads();
;     G_COMPUTE(kt & 1, kt);
;   }
	s_waitcnt vmcnt(9)
	ds_write_b128 v195, v[158:161]
	s_waitcnt vmcnt(8)
	ds_write_b128 v196, v[162:165]
	ds_read_b128 v[158:161], v192 offset:36864
	ds_read_b128 v[162:165], v192 offset:41472
	ds_read_b128 v[228:231], v184
	ds_read_b128 v[232:235], v184 offset:4608
	s_setprio 1
	s_waitcnt lgkmcnt(1)
	v_mfma_f32_32x32x16_bf16 v[112:127], v[158:161], v[228:231], v[112:127]
	v_mfma_f32_32x32x16_bf16 v[48:63], v[162:165], v[228:231], v[48:63]
	s_waitcnt lgkmcnt(0)
	v_mfma_f32_32x32x16_bf16 v[96:111], v[158:161], v[232:235], v[96:111]
	v_mfma_f32_32x32x16_bf16 v[32:47], v[162:165], v[232:235], v[32:47]
	ds_read_b128 v[228:231], v184 offset:9216
	ds_read_b128 v[232:235], v184 offset:13824
	s_waitcnt vmcnt(7)
	ds_write_b128 v194, v[200:203]
	s_waitcnt vmcnt(6)
	ds_write_b128 v193, v[208:211]
	ds_read_b128 v[200:203], v192 offset:36896
	ds_read_b128 v[208:211], v192 offset:41504
	s_waitcnt lgkmcnt(5)
	v_mfma_f32_32x32x16_bf16 v[80:95], v[158:161], v[228:231], v[80:95]
	v_mfma_f32_32x32x16_bf16 v[16:31], v[162:165], v[228:231], v[16:31]
	ds_read_b128 v[228:231], v184 offset:32
	s_waitcnt lgkmcnt(5)
	v_mfma_f32_32x32x16_bf16 v[64:79], v[158:161], v[232:235], v[64:79]
	v_mfma_f32_32x32x16_bf16 v[0:15], v[162:165], v[232:235], v[0:15]
	ds_read_b128 v[232:235], v184 offset:4640
	s_setprio 0
	global_load_dwordx4 v[158:161], v[136:137], off offset:3072
	global_load_dwordx4 v[162:165], v[140:141], off offset:3072
	s_setprio 1
	s_waitcnt lgkmcnt(1)
	v_mfma_f32_32x32x16_bf16 v[112:127], v[200:203], v[228:231], v[112:127]
	v_mfma_f32_32x32x16_bf16 v[48:63], v[208:211], v[228:231], v[48:63]
	s_waitcnt lgkmcnt(0)
	v_mfma_f32_32x32x16_bf16 v[96:111], v[200:203], v[232:235], v[96:111]
	v_mfma_f32_32x32x16_bf16 v[32:47], v[208:211], v[232:235], v[32:47]
	ds_read_b128 v[228:231], v184 offset:9248
	ds_read_b128 v[232:235], v184 offset:13856
	s_waitcnt vmcnt(7)
	ds_write_b128 v177, v[212:215]
	s_waitcnt vmcnt(6)
	ds_write_b128 v176, v[216:219]
	ds_read_b128 v[212:215], v192 offset:36928
	ds_read_b128 v[216:219], v192 offset:41536
	s_waitcnt lgkmcnt(5)
	v_mfma_f32_32x32x16_bf16 v[80:95], v[200:203], v[228:231], v[80:95]
	v_mfma_f32_32x32x16_bf16 v[16:31], v[208:211], v[228:231], v[16:31]
	ds_read_b128 v[228:231], v184 offset:64
	s_waitcnt lgkmcnt(5)
	v_mfma_f32_32x32x16_bf16 v[64:79], v[200:203], v[232:235], v[64:79]
	v_mfma_f32_32x32x16_bf16 v[0:15], v[208:211], v[232:235], v[0:15]
	ds_read_b128 v[232:235], v184 offset:4672
	s_setprio 0
	global_load_dwordx4 v[200:203], v[144:145], off offset:3072
	global_load_dwordx4 v[208:211], v[148:149], off offset:3072
	s_setprio 1
	s_waitcnt lgkmcnt(1)
	v_mfma_f32_32x32x16_bf16 v[112:127], v[212:215], v[228:231], v[112:127]
	v_mfma_f32_32x32x16_bf16 v[48:63], v[216:219], v[228:231], v[48:63]
	s_waitcnt lgkmcnt(0)
	v_mfma_f32_32x32x16_bf16 v[96:111], v[212:215], v[232:235], v[96:111]
	v_mfma_f32_32x32x16_bf16 v[32:47], v[216:219], v[232:235], v[32:47]
	ds_read_b128 v[228:231], v184 offset:9280
	ds_read_b128 v[232:235], v184 offset:13888
	s_waitcnt vmcnt(7)
	ds_write_b128 v171, v[178:181]
	s_waitcnt vmcnt(6)
	ds_write_b128 v170, v[220:223]
	ds_read_b128 v[178:181], v192 offset:36960
	ds_read_b128 v[220:223], v192 offset:41568
	s_waitcnt lgkmcnt(5)
	v_mfma_f32_32x32x16_bf16 v[80:95], v[212:215], v[228:231], v[80:95]
	v_mfma_f32_32x32x16_bf16 v[16:31], v[216:219], v[228:231], v[16:31]
	ds_read_b128 v[228:231], v184 offset:96
	s_waitcnt lgkmcnt(5)
	v_mfma_f32_32x32x16_bf16 v[64:79], v[212:215], v[232:235], v[64:79]
	v_mfma_f32_32x32x16_bf16 v[0:15], v[216:219], v[232:235], v[0:15]
	ds_read_b128 v[232:235], v184 offset:4704
	s_setprio 0
	global_load_dwordx4 v[212:215], v[152:153], off offset:3072
	global_load_dwordx4 v[216:219], v[156:157], off offset:3072
	s_setprio 1
	s_waitcnt lgkmcnt(1)
	v_mfma_f32_32x32x16_bf16 v[112:127], v[178:181], v[228:231], v[112:127]
	v_mfma_f32_32x32x16_bf16 v[48:63], v[220:223], v[228:231], v[48:63]
	s_waitcnt lgkmcnt(0)
	v_mfma_f32_32x32x16_bf16 v[96:111], v[178:181], v[232:235], v[96:111]
	v_mfma_f32_32x32x16_bf16 v[32:47], v[220:223], v[232:235], v[32:47]
	ds_read_b128 v[228:231], v184 offset:9312
	ds_read_b128 v[232:235], v184 offset:13920
	s_waitcnt lgkmcnt(1)
	v_mfma_f32_32x32x16_bf16 v[80:95], v[178:181], v[228:231], v[80:95]
	v_mfma_f32_32x32x16_bf16 v[16:31], v[220:223], v[228:231], v[16:31]
	s_waitcnt lgkmcnt(0)
	v_mfma_f32_32x32x16_bf16 v[64:79], v[178:181], v[232:235], v[64:79]
	v_mfma_f32_32x32x16_bf16 v[0:15], v[220:223], v[232:235], v[0:15]
	s_setprio 0
	global_load_dwordx4 v[178:181], v[128:129], off offset:3200
	global_load_dwordx4 v[220:223], v[132:133], off offset:3200
	s_barrier
; template <bool trans>
; DI void gemm_core(const GTile& tl, const GTile& nx, bool has_next  , bool chain  , bool pre, u32x4 (&ra)[4], u32x4 (&rb)[4], char* smem, f32x16 (&acc)[2][4]) {
;     ...
;   const int nk = K / 64;
;   if (!pre) { G_LOAD(0); G_STORE(0); G_LOAD(1); }
;   for (int kt = 0; kt < nk; ++kt) {
;     __syncthreads();
;     G_COMPUTE(kt & 1, kt);
;   }
	s_waitcnt vmcnt(9)
	ds_write_b128 v191, v[172:175]
	s_waitcnt vmcnt(8)
	ds_write_b128 v191, v[224:227] offset:36864
	ds_read_b128 v[172:175], v169
	ds_read_b128 v[224:227], v169 offset:4608
	ds_read_b128 v[228:231], v168
	ds_read_b128 v[232:235], v168 offset:4608
	s_setprio 1
	s_waitcnt lgkmcnt(1)
	v_mfma_f32_32x32x16_bf16 v[112:127], v[172:175], v[228:231], v[112:127]
	v_mfma_f32_32x32x16_bf16 v[48:63], v[224:227], v[228:231], v[48:63]
	s_waitcnt lgkmcnt(0)
	v_mfma_f32_32x32x16_bf16 v[96:111], v[172:175], v[232:235], v[96:111]
	v_mfma_f32_32x32x16_bf16 v[32:47], v[224:227], v[232:235], v[32:47]
	ds_read_b128 v[228:231], v168 offset:9216
	ds_read_b128 v[232:235], v168 offset:13824
	s_waitcnt vmcnt(7)
	ds_write_b128 v191, v[158:161] offset:9216
	s_waitcnt vmcnt(6)
	ds_write_b128 v191, v[162:165] offset:46080
	ds_read_b128 v[158:161], v169 offset:32
	ds_read_b128 v[162:165], v169 offset:4640
	s_waitcnt lgkmcnt(5)
	v_mfma_f32_32x32x16_bf16 v[80:95], v[172:175], v[228:231], v[80:95]
	v_mfma_f32_32x32x16_bf16 v[16:31], v[224:227], v[228:231], v[16:31]
	ds_read_b128 v[228:231], v168 offset:32
	s_waitcnt lgkmcnt(5)
	v_mfma_f32_32x32x16_bf16 v[64:79], v[172:175], v[232:235], v[64:79]
	v_mfma_f32_32x32x16_bf16 v[0:15], v[224:227], v[232:235], v[0:15]
	ds_read_b128 v[232:235], v168 offset:4640
	s_setprio 0
	global_load_dwordx4 v[172:175], v[136:137], off offset:3200
	global_load_dwordx4 v[224:227], v[140:141], off offset:3200
	s_setprio 1
	s_waitcnt lgkmcnt(1)
	v_mfma_f32_32x32x16_bf16 v[112:127], v[158:161], v[228:231], v[112:127]
	v_mfma_f32_32x32x16_bf16 v[48:63], v[162:165], v[228:231], v[48:63]
	s_waitcnt lgkmcnt(0)
	v_mfma_f32_32x32x16_bf16 v[96:111], v[158:161], v[232:235], v[96:111]
	v_mfma_f32_32x32x16_bf16 v[32:47], v[162:165], v[232:235], v[32:47]
	ds_read_b128 v[228:231], v168 offset:9248
	ds_read_b128 v[232:235], v168 offset:13856
	s_waitcnt vmcnt(7)
	ds_write_b128 v191, v[200:203] offset:18432
	s_waitcnt vmcnt(6)
	ds_write_b128 v191, v[208:211] offset:55296
	ds_read_b128 v[200:203], v169 offset:64
	ds_read_b128 v[208:211], v169 offset:4672
	s_waitcnt lgkmcnt(5)
	v_mfma_f32_32x32x16_bf16 v[80:95], v[158:161], v[228:231], v[80:95]
	v_mfma_f32_32x32x16_bf16 v[16:31], v[162:165], v[228:231], v[16:31]
	ds_read_b128 v[228:231], v168 offset:64
	s_waitcnt lgkmcnt(5)
	v_mfma_f32_32x32x16_bf16 v[64:79], v[158:161], v[232:235], v[64:79]
	v_mfma_f32_32x32x16_bf16 v[0:15], v[162:165], v[232:235], v[0:15]
	ds_read_b128 v[232:235], v168 offset:4672
	s_setprio 0
	global_load_dwordx4 v[158:161], v[144:145], off offset:3200
	global_load_dwordx4 v[162:165], v[148:149], off offset:3200
	s_setprio 1
	s_waitcnt lgkmcnt(1)
	v_mfma_f32_32x32x16_bf16 v[112:127], v[200:203], v[228:231], v[112:127]
	v_mfma_f32_32x32x16_bf16 v[48:63], v[208:211], v[228:231], v[48:63]
	s_waitcnt lgkmcnt(0)
	v_mfma_f32_32x32x16_bf16 v[96:111], v[200:203], v[232:235], v[96:111]
	v_mfma_f32_32x32x16_bf16 v[32:47], v[208:211], v[232:235], v[32:47]
	ds_read_b128 v[228:231], v168 offset:9280
	ds_read_b128 v[232:235], v168 offset:13888
	s_waitcnt vmcnt(7)
	ds_write_b128 v191, v[212:215] offset:27648
	s_waitcnt vmcnt(6)
	ds_write_b128 v191, v[216:219] offset:64512
	ds_read_b128 v[212:215], v169 offset:96
	ds_read_b128 v[216:219], v169 offset:4704
	s_waitcnt lgkmcnt(5)
	v_mfma_f32_32x32x16_bf16 v[80:95], v[200:203], v[228:231], v[80:95]
	v_mfma_f32_32x32x16_bf16 v[16:31], v[208:211], v[228:231], v[16:31]
	ds_read_b128 v[228:231], v168 offset:96
	s_waitcnt lgkmcnt(5)
	v_mfma_f32_32x32x16_bf16 v[64:79], v[200:203], v[232:235], v[64:79]
	v_mfma_f32_32x32x16_bf16 v[0:15], v[208:211], v[232:235], v[0:15]
	ds_read_b128 v[232:235], v168 offset:4704
	s_setprio 0
	global_load_dwordx4 v[200:203], v[152:153], off offset:3200
	global_load_dwordx4 v[208:211], v[156:157], off offset:3200
	s_setprio 1
	s_waitcnt lgkmcnt(1)
	v_mfma_f32_32x32x16_bf16 v[112:127], v[212:215], v[228:231], v[112:127]
	v_mfma_f32_32x32x16_bf16 v[48:63], v[216:219], v[228:231], v[48:63]
	s_waitcnt lgkmcnt(0)
	v_mfma_f32_32x32x16_bf16 v[96:111], v[212:215], v[232:235], v[96:111]
	v_mfma_f32_32x32x16_bf16 v[32:47], v[216:219], v[232:235], v[32:47]
	ds_read_b128 v[228:231], v168 offset:9312
	ds_read_b128 v[232:235], v168 offset:13920
	s_waitcnt lgkmcnt(1)
	v_mfma_f32_32x32x16_bf16 v[80:95], v[212:215], v[228:231], v[80:95]
	v_mfma_f32_32x32x16_bf16 v[16:31], v[216:219], v[228:231], v[16:31]
	s_waitcnt lgkmcnt(0)
	v_mfma_f32_32x32x16_bf16 v[64:79], v[212:215], v[232:235], v[64:79]
	v_mfma_f32_32x32x16_bf16 v[0:15], v[216:219], v[232:235], v[0:15]
	s_setprio 0
	global_load_dwordx4 v[212:215], v[128:129], off offset:3328
	global_load_dwordx4 v[216:219], v[132:133], off offset:3328
	s_barrier
; template <bool trans>
; DI void gemm_core(const GTile& tl, const GTile& nx, bool has_next  , bool chain  , bool pre, u32x4 (&ra)[4], u32x4 (&rb)[4], char* smem, f32x16 (&acc)[2][4]) {
;     ...
;   const int nk = K / 64;
;   if (!pre) { G_LOAD(0); G_STORE(0); G_LOAD(1); }
;   for (int kt = 0; kt < nk; ++kt) {
;     __syncthreads();
;     G_COMPUTE(kt & 1, kt);
;   }
	s_waitcnt vmcnt(9)
	ds_write_b128 v195, v[178:181]
	s_waitcnt vmcnt(8)
	ds_write_b128 v196, v[220:223]
	ds_read_b128 v[178:181], v192 offset:36864
	ds_read_b128 v[220:223], v192 offset:41472
	ds_read_b128 v[228:231], v184
	ds_read_b128 v[232:235], v184 offset:4608
	s_setprio 1
	s_waitcnt lgkmcnt(1)
	v_mfma_f32_32x32x16_bf16 v[112:127], v[178:181], v[228:231], v[112:127]
	v_mfma_f32_32x32x16_bf16 v[48:63], v[220:223], v[228:231], v[48:63]
	s_waitcnt lgkmcnt(0)
	v_mfma_f32_32x32x16_bf16 v[96:111], v[178:181], v[232:235], v[96:111]
	v_mfma_f32_32x32x16_bf16 v[32:47], v[220:223], v[232:235], v[32:47]
	ds_read_b128 v[228:231], v184 offset:9216
	ds_read_b128 v[232:235], v184 offset:13824
	s_waitcnt vmcnt(7)
	ds_write_b128 v194, v[172:175]
	s_waitcnt vmcnt(6)
	ds_write_b128 v193, v[224:227]
	ds_read_b128 v[172:175], v192 offset:36896
	ds_read_b128 v[224:227], v192 offset:41504
	s_waitcnt lgkmcnt(5)
	v_mfma_f32_32x32x16_bf16 v[80:95], v[178:181], v[228:231], v[80:95]
	v_mfma_f32_32x32x16_bf16 v[16:31], v[220:223], v[228:231], v[16:31]
	ds_read_b128 v[228:231], v184 offset:32
	s_waitcnt lgkmcnt(5)
	v_mfma_f32_32x32x16_bf16 v[64:79], v[178:181], v[232:235], v[64:79]
	v_mfma_f32_32x32x16_bf16 v[0:15], v[220:223], v[232:235], v[0:15]
	ds_read_b128 v[232:235], v184 offset:4640
	s_setprio 0
	global_load_dwordx4 v[178:181], v[136:137], off offset:3328
	global_load_dwordx4 v[220:223], v[140:141], off offset:3328
	s_setprio 1
	s_waitcnt lgkmcnt(1)
	v_mfma_f32_32x32x16_bf16 v[112:127], v[172:175], v[228:231], v[112:127]
	v_mfma_f32_32x32x16_bf16 v[48:63], v[224:227], v[228:231], v[48:63]
	s_waitcnt lgkmcnt(0)
	v_mfma_f32_32x32x16_bf16 v[96:111], v[172:175], v[232:235], v[96:111]
	v_mfma_f32_32x32x16_bf16 v[32:47], v[224:227], v[232:235], v[32:47]
	ds_read_b128 v[228:231], v184 offset:9248
	ds_read_b128 v[232:235], v184 offset:13856
	s_waitcnt vmcnt(7)
	ds_write_b128 v177, v[158:161]
	s_waitcnt vmcnt(6)
	ds_write_b128 v176, v[162:165]
	ds_read_b128 v[158:161], v192 offset:36928
	ds_read_b128 v[162:165], v192 offset:41536
	s_waitcnt lgkmcnt(5)
	v_mfma_f32_32x32x16_bf16 v[80:95], v[172:175], v[228:231], v[80:95]
	v_mfma_f32_32x32x16_bf16 v[16:31], v[224:227], v[228:231], v[16:31]
	ds_read_b128 v[228:231], v184 offset:64
	s_waitcnt lgkmcnt(5)
	v_mfma_f32_32x32x16_bf16 v[64:79], v[172:175], v[232:235], v[64:79]
	v_mfma_f32_32x32x16_bf16 v[0:15], v[224:227], v[232:235], v[0:15]
	ds_read_b128 v[232:235], v184 offset:4672
	s_setprio 0
	global_load_dwordx4 v[172:175], v[144:145], off offset:3328
	global_load_dwordx4 v[224:227], v[148:149], off offset:3328
	s_setprio 1
	s_waitcnt lgkmcnt(1)
	v_mfma_f32_32x32x16_bf16 v[112:127], v[158:161], v[228:231], v[112:127]
	v_mfma_f32_32x32x16_bf16 v[48:63], v[162:165], v[228:231], v[48:63]
	s_waitcnt lgkmcnt(0)
	v_mfma_f32_32x32x16_bf16 v[96:111], v[158:161], v[232:235], v[96:111]
	v_mfma_f32_32x32x16_bf16 v[32:47], v[162:165], v[232:235], v[32:47]
	ds_read_b128 v[228:231], v184 offset:9280
	ds_read_b128 v[232:235], v184 offset:13888
	s_waitcnt vmcnt(7)
	ds_write_b128 v171, v[200:203]
	s_waitcnt vmcnt(6)
	ds_write_b128 v170, v[208:211]
	ds_read_b128 v[200:203], v192 offset:36960
	ds_read_b128 v[208:211], v192 offset:41568
	s_waitcnt lgkmcnt(5)
	v_mfma_f32_32x32x16_bf16 v[80:95], v[158:161], v[228:231], v[80:95]
	v_mfma_f32_32x32x16_bf16 v[16:31], v[162:165], v[228:231], v[16:31]
	ds_read_b128 v[228:231], v184 offset:96
	s_waitcnt lgkmcnt(5)
	v_mfma_f32_32x32x16_bf16 v[64:79], v[158:161], v[232:235], v[64:79]
	v_mfma_f32_32x32x16_bf16 v[0:15], v[162:165], v[232:235], v[0:15]
	ds_read_b128 v[232:235], v184 offset:4704
	s_setprio 0
	global_load_dwordx4 v[158:161], v[152:153], off offset:3328
	global_load_dwordx4 v[162:165], v[156:157], off offset:3328
	s_setprio 1
	s_waitcnt lgkmcnt(1)
	v_mfma_f32_32x32x16_bf16 v[112:127], v[200:203], v[228:231], v[112:127]
	v_mfma_f32_32x32x16_bf16 v[48:63], v[208:211], v[228:231], v[48:63]
	s_waitcnt lgkmcnt(0)
	v_mfma_f32_32x32x16_bf16 v[96:111], v[200:203], v[232:235], v[96:111]
	v_mfma_f32_32x32x16_bf16 v[32:47], v[208:211], v[232:235], v[32:47]
	ds_read_b128 v[228:231], v184 offset:9312
	ds_read_b128 v[232:235], v184 offset:13920
	s_waitcnt lgkmcnt(1)
	v_mfma_f32_32x32x16_bf16 v[80:95], v[200:203], v[228:231], v[80:95]
	v_mfma_f32_32x32x16_bf16 v[16:31], v[208:211], v[228:231], v[16:31]
	s_waitcnt lgkmcnt(0)
	v_mfma_f32_32x32x16_bf16 v[64:79], v[200:203], v[232:235], v[64:79]
	v_mfma_f32_32x32x16_bf16 v[0:15], v[208:211], v[232:235], v[0:15]
	s_setprio 0
	global_load_dwordx4 v[200:203], v[128:129], off offset:3456
	global_load_dwordx4 v[208:211], v[132:133], off offset:3456
	s_barrier
; template <bool trans>
; DI void gemm_core(const GTile& tl, const GTile& nx, bool has_next  , bool chain  , bool pre, u32x4 (&ra)[4], u32x4 (&rb)[4], char* smem, f32x16 (&acc)[2][4]) {
;     ...
;   const int nk = K / 64;
;   if (!pre) { G_LOAD(0); G_STORE(0); G_LOAD(1); }
;   for (int kt = 0; kt < nk; ++kt) {
;     __syncthreads();
;     G_COMPUTE(kt & 1, kt);
;   }
	s_waitcnt vmcnt(9)
	ds_write_b128 v191, v[212:215]
	s_waitcnt vmcnt(8)
	ds_write_b128 v191, v[216:219] offset:36864
	ds_read_b128 v[212:215], v169
	ds_read_b128 v[216:219], v169 offset:4608
	ds_read_b128 v[228:231], v168
	ds_read_b128 v[232:235], v168 offset:4608
	s_setprio 1
	s_waitcnt lgkmcnt(1)
	v_mfma_f32_32x32x16_bf16 v[112:127], v[212:215], v[228:231], v[112:127]
	v_mfma_f32_32x32x16_bf16 v[48:63], v[216:219], v[228:231], v[48:63]
	s_waitcnt lgkmcnt(0)
	v_mfma_f32_32x32x16_bf16 v[96:111], v[212:215], v[232:235], v[96:111]
	v_mfma_f32_32x32x16_bf16 v[32:47], v[216:219], v[232:235], v[32:47]
	ds_read_b128 v[228:231], v168 offset:9216
	ds_read_b128 v[232:235], v168 offset:13824
	s_waitcnt vmcnt(7)
	ds_write_b128 v191, v[178:181] offset:9216
	s_waitcnt vmcnt(6)
	ds_write_b128 v191, v[220:223] offset:46080
	ds_read_b128 v[178:181], v169 offset:32
	ds_read_b128 v[220:223], v169 offset:4640
	s_waitcnt lgkmcnt(5)
	v_mfma_f32_32x32x16_bf16 v[80:95], v[212:215], v[228:231], v[80:95]
	v_mfma_f32_32x32x16_bf16 v[16:31], v[216:219], v[228:231], v[16:31]
	ds_read_b128 v[228:231], v168 offset:32
	s_waitcnt lgkmcnt(5)
	v_mfma_f32_32x32x16_bf16 v[64:79], v[212:215], v[232:235], v[64:79]
	v_mfma_f32_32x32x16_bf16 v[0:15], v[216:219], v[232:235], v[0:15]
	ds_read_b128 v[232:235], v168 offset:4640
	s_setprio 0
	global_load_dwordx4 v[212:215], v[136:137], off offset:3456
	global_load_dwordx4 v[216:219], v[140:141], off offset:3456
	s_setprio 1
	s_waitcnt lgkmcnt(1)
	v_mfma_f32_32x32x16_bf16 v[112:127], v[178:181], v[228:231], v[112:127]
	v_mfma_f32_32x32x16_bf16 v[48:63], v[220:223], v[228:231], v[48:63]
	s_waitcnt lgkmcnt(0)
	v_mfma_f32_32x32x16_bf16 v[96:111], v[178:181], v[232:235], v[96:111]
	v_mfma_f32_32x32x16_bf16 v[32:47], v[220:223], v[232:235], v[32:47]
	ds_read_b128 v[228:231], v168 offset:9248
	ds_read_b128 v[232:235], v168 offset:13856
	s_waitcnt vmcnt(7)
	ds_write_b128 v191, v[172:175] offset:18432
	s_waitcnt vmcnt(6)
	ds_write_b128 v191, v[224:227] offset:55296
	ds_read_b128 v[172:175], v169 offset:64
	ds_read_b128 v[224:227], v169 offset:4672
	s_waitcnt lgkmcnt(5)
	v_mfma_f32_32x32x16_bf16 v[80:95], v[178:181], v[228:231], v[80:95]
	v_mfma_f32_32x32x16_bf16 v[16:31], v[220:223], v[228:231], v[16:31]
	ds_read_b128 v[228:231], v168 offset:64
	s_waitcnt lgkmcnt(5)
	v_mfma_f32_32x32x16_bf16 v[64:79], v[178:181], v[232:235], v[64:79]
	v_mfma_f32_32x32x16_bf16 v[0:15], v[220:223], v[232:235], v[0:15]
	ds_read_b128 v[232:235], v168 offset:4672
	s_setprio 0
	global_load_dwordx4 v[178:181], v[144:145], off offset:3456
	global_load_dwordx4 v[220:223], v[148:149], off offset:3456
	s_setprio 1
	s_waitcnt lgkmcnt(1)
	v_mfma_f32_32x32x16_bf16 v[112:127], v[172:175], v[228:231], v[112:127]
	v_mfma_f32_32x32x16_bf16 v[48:63], v[224:227], v[228:231], v[48:63]
	s_waitcnt lgkmcnt(0)
	v_mfma_f32_32x32x16_bf16 v[96:111], v[172:175], v[232:235], v[96:111]
	v_mfma_f32_32x32x16_bf16 v[32:47], v[224:227], v[232:235], v[32:47]
	ds_read_b128 v[228:231], v168 offset:9280
	ds_read_b128 v[232:235], v168 offset:13888
	s_waitcnt vmcnt(7)
	ds_write_b128 v191, v[158:161] offset:27648
	s_waitcnt vmcnt(6)
	ds_write_b128 v191, v[162:165] offset:64512
	ds_read_b128 v[158:161], v169 offset:96
	ds_read_b128 v[162:165], v169 offset:4704
	s_waitcnt lgkmcnt(5)
	v_mfma_f32_32x32x16_bf16 v[80:95], v[172:175], v[228:231], v[80:95]
	v_mfma_f32_32x32x16_bf16 v[16:31], v[224:227], v[228:231], v[16:31]
	ds_read_b128 v[228:231], v168 offset:96
	s_waitcnt lgkmcnt(5)
	v_mfma_f32_32x32x16_bf16 v[64:79], v[172:175], v[232:235], v[64:79]
	v_mfma_f32_32x32x16_bf16 v[0:15], v[224:227], v[232:235], v[0:15]
	ds_read_b128 v[232:235], v168 offset:4704
	s_setprio 0
	global_load_dwordx4 v[172:175], v[152:153], off offset:3456
	global_load_dwordx4 v[224:227], v[156:157], off offset:3456
	s_setprio 1
	s_waitcnt lgkmcnt(1)
	v_mfma_f32_32x32x16_bf16 v[112:127], v[158:161], v[228:231], v[112:127]
	v_mfma_f32_32x32x16_bf16 v[48:63], v[162:165], v[228:231], v[48:63]
	s_waitcnt lgkmcnt(0)
	v_mfma_f32_32x32x16_bf16 v[96:111], v[158:161], v[232:235], v[96:111]
	v_mfma_f32_32x32x16_bf16 v[32:47], v[162:165], v[232:235], v[32:47]
	ds_read_b128 v[228:231], v168 offset:9312
	ds_read_b128 v[232:235], v168 offset:13920
	s_waitcnt lgkmcnt(1)
	v_mfma_f32_32x32x16_bf16 v[80:95], v[158:161], v[228:231], v[80:95]
	v_mfma_f32_32x32x16_bf16 v[16:31], v[162:165], v[228:231], v[16:31]
	s_waitcnt lgkmcnt(0)
	v_mfma_f32_32x32x16_bf16 v[64:79], v[158:161], v[232:235], v[64:79]
	v_mfma_f32_32x32x16_bf16 v[0:15], v[162:165], v[232:235], v[0:15]
	s_setprio 0
	global_load_dwordx4 v[158:161], v[128:129], off offset:3584
	global_load_dwordx4 v[162:165], v[132:133], off offset:3584
	s_barrier
; template <bool trans>
; DI void gemm_core(const GTile& tl, const GTile& nx, bool has_next  , bool chain  , bool pre, u32x4 (&ra)[4], u32x4 (&rb)[4], char* smem, f32x16 (&acc)[2][4]) {
;     ...
;   const int nk = K / 64;
;   if (!pre) { G_LOAD(0); G_STORE(0); G_LOAD(1); }
;   for (int kt = 0; kt < nk; ++kt) {
;     __syncthreads();
;     G_COMPUTE(kt & 1, kt);
;   }
	s_waitcnt vmcnt(9)
	ds_write_b128 v195, v[200:203]
	s_waitcnt vmcnt(8)
	ds_write_b128 v196, v[208:211]
	ds_read_b128 v[200:203], v192 offset:36864
	ds_read_b128 v[208:211], v192 offset:41472
	ds_read_b128 v[228:231], v184
	ds_read_b128 v[232:235], v184 offset:4608
	s_setprio 1
	s_waitcnt lgkmcnt(1)
	v_mfma_f32_32x32x16_bf16 v[112:127], v[200:203], v[228:231], v[112:127]
	v_mfma_f32_32x32x16_bf16 v[48:63], v[208:211], v[228:231], v[48:63]
	s_waitcnt lgkmcnt(0)
	v_mfma_f32_32x32x16_bf16 v[96:111], v[200:203], v[232:235], v[96:111]
	v_mfma_f32_32x32x16_bf16 v[32:47], v[208:211], v[232:235], v[32:47]
	ds_read_b128 v[228:231], v184 offset:9216
	ds_read_b128 v[232:235], v184 offset:13824
	s_waitcnt vmcnt(7)
	ds_write_b128 v194, v[212:215]
	s_waitcnt vmcnt(6)
	ds_write_b128 v193, v[216:219]
	ds_read_b128 v[212:215], v192 offset:36896
	ds_read_b128 v[216:219], v192 offset:41504
	s_waitcnt lgkmcnt(5)
	v_mfma_f32_32x32x16_bf16 v[80:95], v[200:203], v[228:231], v[80:95]
	v_mfma_f32_32x32x16_bf16 v[16:31], v[208:211], v[228:231], v[16:31]
	ds_read_b128 v[228:231], v184 offset:32
	s_waitcnt lgkmcnt(5)
	v_mfma_f32_32x32x16_bf16 v[64:79], v[200:203], v[232:235], v[64:79]
	v_mfma_f32_32x32x16_bf16 v[0:15], v[208:211], v[232:235], v[0:15]
	ds_read_b128 v[232:235], v184 offset:4640
	s_setprio 0
	global_load_dwordx4 v[200:203], v[136:137], off offset:3584
	global_load_dwordx4 v[208:211], v[140:141], off offset:3584
	s_setprio 1
	s_waitcnt lgkmcnt(1)
	v_mfma_f32_32x32x16_bf16 v[112:127], v[212:215], v[228:231], v[112:127]
	v_mfma_f32_32x32x16_bf16 v[48:63], v[216:219], v[228:231], v[48:63]
	s_waitcnt lgkmcnt(0)
	v_mfma_f32_32x32x16_bf16 v[96:111], v[212:215], v[232:235], v[96:111]
	v_mfma_f32_32x32x16_bf16 v[32:47], v[216:219], v[232:235], v[32:47]
	ds_read_b128 v[228:231], v184 offset:9248
	ds_read_b128 v[232:235], v184 offset:13856
	s_waitcnt vmcnt(7)
	ds_write_b128 v177, v[178:181]
	s_waitcnt vmcnt(6)
	ds_write_b128 v176, v[220:223]
	ds_read_b128 v[178:181], v192 offset:36928
	ds_read_b128 v[220:223], v192 offset:41536
	s_waitcnt lgkmcnt(5)
	v_mfma_f32_32x32x16_bf16 v[80:95], v[212:215], v[228:231], v[80:95]
	v_mfma_f32_32x32x16_bf16 v[16:31], v[216:219], v[228:231], v[16:31]
	ds_read_b128 v[228:231], v184 offset:64
	s_waitcnt lgkmcnt(5)
	v_mfma_f32_32x32x16_bf16 v[64:79], v[212:215], v[232:235], v[64:79]
	v_mfma_f32_32x32x16_bf16 v[0:15], v[216:219], v[232:235], v[0:15]
	ds_read_b128 v[232:235], v184 offset:4672
	s_setprio 0
	global_load_dwordx4 v[212:215], v[144:145], off offset:3584
	global_load_dwordx4 v[216:219], v[148:149], off offset:3584
	s_setprio 1
	s_waitcnt lgkmcnt(1)
	v_mfma_f32_32x32x16_bf16 v[112:127], v[178:181], v[228:231], v[112:127]
	v_mfma_f32_32x32x16_bf16 v[48:63], v[220:223], v[228:231], v[48:63]
	s_waitcnt lgkmcnt(0)
	v_mfma_f32_32x32x16_bf16 v[96:111], v[178:181], v[232:235], v[96:111]
	v_mfma_f32_32x32x16_bf16 v[32:47], v[220:223], v[232:235], v[32:47]
	ds_read_b128 v[228:231], v184 offset:9280
	ds_read_b128 v[232:235], v184 offset:13888
	s_waitcnt vmcnt(7)
	ds_write_b128 v171, v[172:175]
	s_waitcnt vmcnt(6)
	ds_write_b128 v170, v[224:227]
	ds_read_b128 v[172:175], v192 offset:36960
	ds_read_b128 v[224:227], v192 offset:41568
	s_waitcnt lgkmcnt(5)
	v_mfma_f32_32x32x16_bf16 v[80:95], v[178:181], v[228:231], v[80:95]
	v_mfma_f32_32x32x16_bf16 v[16:31], v[220:223], v[228:231], v[16:31]
	ds_read_b128 v[228:231], v184 offset:96
	s_waitcnt lgkmcnt(5)
	v_mfma_f32_32x32x16_bf16 v[64:79], v[178:181], v[232:235], v[64:79]
	v_mfma_f32_32x32x16_bf16 v[0:15], v[220:223], v[232:235], v[0:15]
	ds_read_b128 v[232:235], v184 offset:4704
	s_setprio 0
	global_load_dwordx4 v[178:181], v[152:153], off offset:3584
	global_load_dwordx4 v[220:223], v[156:157], off offset:3584
	s_setprio 1
	s_waitcnt lgkmcnt(1)
	v_mfma_f32_32x32x16_bf16 v[112:127], v[172:175], v[228:231], v[112:127]
	v_mfma_f32_32x32x16_bf16 v[48:63], v[224:227], v[228:231], v[48:63]
	s_waitcnt lgkmcnt(0)
	v_mfma_f32_32x32x16_bf16 v[96:111], v[172:175], v[232:235], v[96:111]
	v_mfma_f32_32x32x16_bf16 v[32:47], v[224:227], v[232:235], v[32:47]
	ds_read_b128 v[228:231], v184 offset:9312
	ds_read_b128 v[232:235], v184 offset:13920
	s_waitcnt lgkmcnt(1)
	v_mfma_f32_32x32x16_bf16 v[80:95], v[172:175], v[228:231], v[80:95]
	v_mfma_f32_32x32x16_bf16 v[16:31], v[224:227], v[228:231], v[16:31]
	s_waitcnt lgkmcnt(0)
	v_mfma_f32_32x32x16_bf16 v[64:79], v[172:175], v[232:235], v[64:79]
	v_mfma_f32_32x32x16_bf16 v[0:15], v[224:227], v[232:235], v[0:15]
	s_setprio 0
	global_load_dwordx4 v[172:175], v[128:129], off offset:3712
	global_load_dwordx4 v[224:227], v[132:133], off offset:3712
	s_barrier
; template <bool trans>
; DI void gemm_core(const GTile& tl, const GTile& nx, bool has_next  , bool chain  , bool pre, u32x4 (&ra)[4], u32x4 (&rb)[4], char* smem, f32x16 (&acc)[2][4]) {
;     ...
;   const int nk = K / 64;
;   if (!pre) { G_LOAD(0); G_STORE(0); G_LOAD(1); }
;   for (int kt = 0; kt < nk; ++kt) {
;     __syncthreads();
;     G_COMPUTE(kt & 1, kt);
;   }
	s_waitcnt vmcnt(9)
	ds_write_b128 v191, v[158:161]
	s_waitcnt vmcnt(8)
	ds_write_b128 v191, v[162:165] offset:36864
	ds_read_b128 v[158:161], v169
	ds_read_b128 v[162:165], v169 offset:4608
	ds_read_b128 v[228:231], v168
	ds_read_b128 v[232:235], v168 offset:4608
	s_setprio 1
	s_waitcnt lgkmcnt(1)
	v_mfma_f32_32x32x16_bf16 v[112:127], v[158:161], v[228:231], v[112:127]
	v_mfma_f32_32x32x16_bf16 v[48:63], v[162:165], v[228:231], v[48:63]
	s_waitcnt lgkmcnt(0)
	v_mfma_f32_32x32x16_bf16 v[96:111], v[158:161], v[232:235], v[96:111]
	v_mfma_f32_32x32x16_bf16 v[32:47], v[162:165], v[232:235], v[32:47]
	ds_read_b128 v[228:231], v168 offset:9216
	ds_read_b128 v[232:235], v168 offset:13824
	s_waitcnt vmcnt(7)
	ds_write_b128 v191, v[200:203] offset:9216
	s_waitcnt vmcnt(6)
	ds_write_b128 v191, v[208:211] offset:46080
	ds_read_b128 v[200:203], v169 offset:32
	ds_read_b128 v[208:211], v169 offset:4640
	s_waitcnt lgkmcnt(5)
	v_mfma_f32_32x32x16_bf16 v[80:95], v[158:161], v[228:231], v[80:95]
	v_mfma_f32_32x32x16_bf16 v[16:31], v[162:165], v[228:231], v[16:31]
	ds_read_b128 v[228:231], v168 offset:32
	s_waitcnt lgkmcnt(5)
	v_mfma_f32_32x32x16_bf16 v[64:79], v[158:161], v[232:235], v[64:79]
	v_mfma_f32_32x32x16_bf16 v[0:15], v[162:165], v[232:235], v[0:15]
	ds_read_b128 v[232:235], v168 offset:4640
	s_setprio 0
	global_load_dwordx4 v[158:161], v[136:137], off offset:3712
	global_load_dwordx4 v[162:165], v[140:141], off offset:3712
	s_setprio 1
	s_waitcnt lgkmcnt(1)
	v_mfma_f32_32x32x16_bf16 v[112:127], v[200:203], v[228:231], v[112:127]
	v_mfma_f32_32x32x16_bf16 v[48:63], v[208:211], v[228:231], v[48:63]
	s_waitcnt lgkmcnt(0)
	v_mfma_f32_32x32x16_bf16 v[96:111], v[200:203], v[232:235], v[96:111]
	v_mfma_f32_32x32x16_bf16 v[32:47], v[208:211], v[232:235], v[32:47]
	ds_read_b128 v[228:231], v168 offset:9248
	ds_read_b128 v[232:235], v168 offset:13856
	s_waitcnt vmcnt(7)
	ds_write_b128 v191, v[212:215] offset:18432
	s_waitcnt vmcnt(6)
	ds_write_b128 v191, v[216:219] offset:55296
	ds_read_b128 v[212:215], v169 offset:64
	ds_read_b128 v[216:219], v169 offset:4672
	s_waitcnt lgkmcnt(5)
	v_mfma_f32_32x32x16_bf16 v[80:95], v[200:203], v[228:231], v[80:95]
	v_mfma_f32_32x32x16_bf16 v[16:31], v[208:211], v[228:231], v[16:31]
	ds_read_b128 v[228:231], v168 offset:64
	s_waitcnt lgkmcnt(5)
	v_mfma_f32_32x32x16_bf16 v[64:79], v[200:203], v[232:235], v[64:79]
	v_mfma_f32_32x32x16_bf16 v[0:15], v[208:211], v[232:235], v[0:15]
	ds_read_b128 v[232:235], v168 offset:4672
	s_setprio 0
	global_load_dwordx4 v[200:203], v[144:145], off offset:3712
	global_load_dwordx4 v[208:211], v[148:149], off offset:3712
	s_setprio 1
	s_waitcnt lgkmcnt(1)
	v_mfma_f32_32x32x16_bf16 v[112:127], v[212:215], v[228:231], v[112:127]
	v_mfma_f32_32x32x16_bf16 v[48:63], v[216:219], v[228:231], v[48:63]
	s_waitcnt lgkmcnt(0)
	v_mfma_f32_32x32x16_bf16 v[96:111], v[212:215], v[232:235], v[96:111]
	v_mfma_f32_32x32x16_bf16 v[32:47], v[216:219], v[232:235], v[32:47]
	ds_read_b128 v[228:231], v168 offset:9280
	ds_read_b128 v[232:235], v168 offset:13888
	s_waitcnt vmcnt(7)
	ds_write_b128 v191, v[178:181] offset:27648
	s_waitcnt vmcnt(6)
	ds_write_b128 v191, v[220:223] offset:64512
	ds_read_b128 v[178:181], v169 offset:96
	ds_read_b128 v[220:223], v169 offset:4704
	s_waitcnt lgkmcnt(5)
	v_mfma_f32_32x32x16_bf16 v[80:95], v[212:215], v[228:231], v[80:95]
	v_mfma_f32_32x32x16_bf16 v[16:31], v[216:219], v[228:231], v[16:31]
	ds_read_b128 v[228:231], v168 offset:96
	s_waitcnt lgkmcnt(5)
	v_mfma_f32_32x32x16_bf16 v[64:79], v[212:215], v[232:235], v[64:79]
	v_mfma_f32_32x32x16_bf16 v[0:15], v[216:219], v[232:235], v[0:15]
	ds_read_b128 v[232:235], v168 offset:4704
	s_setprio 0
	global_load_dwordx4 v[212:215], v[152:153], off offset:3712
	global_load_dwordx4 v[216:219], v[156:157], off offset:3712
	s_setprio 1
	s_waitcnt lgkmcnt(1)
	v_mfma_f32_32x32x16_bf16 v[112:127], v[178:181], v[228:231], v[112:127]
	v_mfma_f32_32x32x16_bf16 v[48:63], v[220:223], v[228:231], v[48:63]
	s_waitcnt lgkmcnt(0)
	v_mfma_f32_32x32x16_bf16 v[96:111], v[178:181], v[232:235], v[96:111]
	v_mfma_f32_32x32x16_bf16 v[32:47], v[220:223], v[232:235], v[32:47]
	ds_read_b128 v[228:231], v168 offset:9312
	ds_read_b128 v[232:235], v168 offset:13920
	s_waitcnt lgkmcnt(1)
	v_mfma_f32_32x32x16_bf16 v[80:95], v[178:181], v[228:231], v[80:95]
	v_mfma_f32_32x32x16_bf16 v[16:31], v[220:223], v[228:231], v[16:31]
	s_waitcnt lgkmcnt(0)
	v_mfma_f32_32x32x16_bf16 v[64:79], v[178:181], v[232:235], v[64:79]
	v_mfma_f32_32x32x16_bf16 v[0:15], v[220:223], v[232:235], v[0:15]
	s_setprio 0
	global_load_dwordx4 v[178:181], v[128:129], off offset:3840
	global_load_dwordx4 v[220:223], v[132:133], off offset:3840
	s_barrier
; template <bool trans>
; DI void gemm_core(const GTile& tl, const GTile& nx, bool has_next  , bool chain  , bool pre, u32x4 (&ra)[4], u32x4 (&rb)[4], char* smem, f32x16 (&acc)[2][4]) {
;     ...
;   const int nk = K / 64;
;   if (!pre) { G_LOAD(0); G_STORE(0); G_LOAD(1); }
;   for (int kt = 0; kt < nk; ++kt) {
;     __syncthreads();
;     G_COMPUTE(kt & 1, kt);
;   }
	s_waitcnt vmcnt(9)
	ds_write_b128 v195, v[172:175]
	s_waitcnt vmcnt(8)
	ds_write_b128 v196, v[224:227]
	ds_read_b128 v[172:175], v192 offset:36864
	ds_read_b128 v[224:227], v192 offset:41472
	ds_read_b128 v[228:231], v184
	ds_read_b128 v[232:235], v184 offset:4608
	s_setprio 1
	s_waitcnt lgkmcnt(1)
	v_mfma_f32_32x32x16_bf16 v[112:127], v[172:175], v[228:231], v[112:127]
	v_mfma_f32_32x32x16_bf16 v[48:63], v[224:227], v[228:231], v[48:63]
	s_waitcnt lgkmcnt(0)
	v_mfma_f32_32x32x16_bf16 v[96:111], v[172:175], v[232:235], v[96:111]
	v_mfma_f32_32x32x16_bf16 v[32:47], v[224:227], v[232:235], v[32:47]
	ds_read_b128 v[228:231], v184 offset:9216
	ds_read_b128 v[232:235], v184 offset:13824
	s_waitcnt vmcnt(7)
	ds_write_b128 v194, v[158:161]
	s_waitcnt vmcnt(6)
	ds_write_b128 v193, v[162:165]
	ds_read_b128 v[158:161], v192 offset:36896
	ds_read_b128 v[162:165], v192 offset:41504
	s_waitcnt lgkmcnt(5)
	v_mfma_f32_32x32x16_bf16 v[80:95], v[172:175], v[228:231], v[80:95]
	v_mfma_f32_32x32x16_bf16 v[16:31], v[224:227], v[228:231], v[16:31]
	ds_read_b128 v[228:231], v184 offset:32
	s_waitcnt lgkmcnt(5)
	v_mfma_f32_32x32x16_bf16 v[64:79], v[172:175], v[232:235], v[64:79]
	v_mfma_f32_32x32x16_bf16 v[0:15], v[224:227], v[232:235], v[0:15]
	ds_read_b128 v[232:235], v184 offset:4640
	s_setprio 0
	global_load_dwordx4 v[172:175], v[136:137], off offset:3840
	global_load_dwordx4 v[224:227], v[140:141], off offset:3840
	s_setprio 1
	s_waitcnt lgkmcnt(1)
	v_mfma_f32_32x32x16_bf16 v[112:127], v[158:161], v[228:231], v[112:127]
	v_mfma_f32_32x32x16_bf16 v[48:63], v[162:165], v[228:231], v[48:63]
	s_waitcnt lgkmcnt(0)
	v_mfma_f32_32x32x16_bf16 v[96:111], v[158:161], v[232:235], v[96:111]
	v_mfma_f32_32x32x16_bf16 v[32:47], v[162:165], v[232:235], v[32:47]
	ds_read_b128 v[228:231], v184 offset:9248
	ds_read_b128 v[232:235], v184 offset:13856
	s_waitcnt vmcnt(7)
	ds_write_b128 v177, v[200:203]
	s_waitcnt vmcnt(6)
	ds_write_b128 v176, v[208:211]
	ds_read_b128 v[200:203], v192 offset:36928
	ds_read_b128 v[208:211], v192 offset:41536
	s_waitcnt lgkmcnt(5)
	v_mfma_f32_32x32x16_bf16 v[80:95], v[158:161], v[228:231], v[80:95]
	v_mfma_f32_32x32x16_bf16 v[16:31], v[162:165], v[228:231], v[16:31]
	ds_read_b128 v[228:231], v184 offset:64
	s_waitcnt lgkmcnt(5)
	v_mfma_f32_32x32x16_bf16 v[64:79], v[158:161], v[232:235], v[64:79]
	v_mfma_f32_32x32x16_bf16 v[0:15], v[162:165], v[232:235], v[0:15]
	ds_read_b128 v[232:235], v184 offset:4672
	s_setprio 0
	global_load_dwordx4 v[158:161], v[144:145], off offset:3840
	global_load_dwordx4 v[162:165], v[148:149], off offset:3840
	s_setprio 1
	s_waitcnt lgkmcnt(1)
	v_mfma_f32_32x32x16_bf16 v[112:127], v[200:203], v[228:231], v[112:127]
	v_mfma_f32_32x32x16_bf16 v[48:63], v[208:211], v[228:231], v[48:63]
	s_waitcnt lgkmcnt(0)
	v_mfma_f32_32x32x16_bf16 v[96:111], v[200:203], v[232:235], v[96:111]
	v_mfma_f32_32x32x16_bf16 v[32:47], v[208:211], v[232:235], v[32:47]
	ds_read_b128 v[228:231], v184 offset:9280
	ds_read_b128 v[232:235], v184 offset:13888
	s_waitcnt vmcnt(7)
	ds_write_b128 v171, v[212:215]
	s_waitcnt vmcnt(6)
	ds_write_b128 v170, v[216:219]
	ds_read_b128 v[212:215], v192 offset:36960
	ds_read_b128 v[216:219], v192 offset:41568
	s_waitcnt lgkmcnt(5)
	v_mfma_f32_32x32x16_bf16 v[80:95], v[200:203], v[228:231], v[80:95]
	v_mfma_f32_32x32x16_bf16 v[16:31], v[208:211], v[228:231], v[16:31]
	ds_read_b128 v[228:231], v184 offset:96
	s_waitcnt lgkmcnt(5)
	v_mfma_f32_32x32x16_bf16 v[64:79], v[200:203], v[232:235], v[64:79]
	v_mfma_f32_32x32x16_bf16 v[0:15], v[208:211], v[232:235], v[0:15]
	ds_read_b128 v[232:235], v184 offset:4704
	s_setprio 0
	global_load_dwordx4 v[200:203], v[152:153], off offset:3840
	global_load_dwordx4 v[208:211], v[156:157], off offset:3840
	s_setprio 1
	s_waitcnt lgkmcnt(1)
	v_mfma_f32_32x32x16_bf16 v[112:127], v[212:215], v[228:231], v[112:127]
	v_mfma_f32_32x32x16_bf16 v[48:63], v[216:219], v[228:231], v[48:63]
	s_waitcnt lgkmcnt(0)
	v_mfma_f32_32x32x16_bf16 v[96:111], v[212:215], v[232:235], v[96:111]
	v_mfma_f32_32x32x16_bf16 v[32:47], v[216:219], v[232:235], v[32:47]
	ds_read_b128 v[228:231], v184 offset:9312
	ds_read_b128 v[232:235], v184 offset:13920
	s_waitcnt lgkmcnt(1)
	v_mfma_f32_32x32x16_bf16 v[80:95], v[212:215], v[228:231], v[80:95]
	v_mfma_f32_32x32x16_bf16 v[16:31], v[216:219], v[228:231], v[16:31]
	s_waitcnt lgkmcnt(0)
	v_mfma_f32_32x32x16_bf16 v[64:79], v[212:215], v[232:235], v[64:79]
	v_mfma_f32_32x32x16_bf16 v[0:15], v[216:219], v[232:235], v[0:15]
	s_setprio 0
	s_barrier
; template <bool trans>
; DI void gemm_core(const GTile& tl, const GTile& nx, bool has_next  , bool chain  , bool pre, u32x4 (&ra)[4], u32x4 (&rb)[4], char* smem, f32x16 (&acc)[2][4]) {
;     ...
;   const int nk = K / 64;
;   if (!pre) { G_LOAD(0); G_STORE(0); G_LOAD(1); }
;   for (int kt = 0; kt < nk; ++kt) {
;     __syncthreads();
;     G_COMPUTE(kt & 1, kt);
;   }
;   if (!has_next) __syncthreads();
	global_load_dwordx4 v[128:131], v[128:129], off offset:3968
	s_nop 0
	global_load_dwordx4 v[132:135], v[132:133], off offset:3968
	s_waitcnt vmcnt(9)
	ds_write_b128 v191, v[178:181]
	s_waitcnt vmcnt(8)
	ds_write_b128 v191, v[220:223] offset:36864
	ds_read_b128 v[178:181], v169
	ds_read_b128 v[212:215], v169 offset:4608
	ds_read_b128 v[216:219], v168
	ds_read_b128 v[220:223], v168 offset:4608
	s_setprio 1
	s_waitcnt lgkmcnt(1)
	v_mfma_f32_32x32x16_bf16 v[112:127], v[178:181], v[216:219], v[112:127]
	v_mfma_f32_32x32x16_bf16 v[48:63], v[212:215], v[216:219], v[48:63]
	s_waitcnt lgkmcnt(0)
	v_mfma_f32_32x32x16_bf16 v[96:111], v[178:181], v[220:223], v[96:111]
	v_mfma_f32_32x32x16_bf16 v[32:47], v[212:215], v[220:223], v[32:47]
	ds_read_b128 v[216:219], v168 offset:9216
	ds_read_b128 v[220:223], v168 offset:13824
	s_waitcnt lgkmcnt(1)
	v_mfma_f32_32x32x16_bf16 v[80:95], v[178:181], v[216:219], v[80:95]
	v_mfma_f32_32x32x16_bf16 v[16:31], v[212:215], v[216:219], v[16:31]
	s_waitcnt lgkmcnt(0)
	v_mfma_f32_32x32x16_bf16 v[64:79], v[178:181], v[220:223], v[64:79]
	v_mfma_f32_32x32x16_bf16 v[0:15], v[212:215], v[220:223], v[0:15]
	s_setprio 0
	global_load_dwordx4 v[136:139], v[136:137], off offset:3968
	s_nop 0
	global_load_dwordx4 v[140:143], v[140:141], off offset:3968
	s_waitcnt vmcnt(9)
	ds_write_b128 v191, v[172:175] offset:9216
	s_waitcnt vmcnt(8)
	ds_write_b128 v191, v[224:227] offset:46080
	ds_read_b128 v[172:175], v169 offset:32
	ds_read_b128 v[178:181], v169 offset:4640
	ds_read_b128 v[212:215], v168 offset:32
	ds_read_b128 v[216:219], v168 offset:4640
	s_setprio 1
	s_waitcnt lgkmcnt(1)
	v_mfma_f32_32x32x16_bf16 v[112:127], v[172:175], v[212:215], v[112:127]
	v_mfma_f32_32x32x16_bf16 v[48:63], v[178:181], v[212:215], v[48:63]
	s_waitcnt lgkmcnt(0)
	v_mfma_f32_32x32x16_bf16 v[96:111], v[172:175], v[216:219], v[96:111]
	v_mfma_f32_32x32x16_bf16 v[32:47], v[178:181], v[216:219], v[32:47]
	ds_read_b128 v[212:215], v168 offset:9248
	ds_read_b128 v[216:219], v168 offset:13856
	s_waitcnt lgkmcnt(1)
	v_mfma_f32_32x32x16_bf16 v[80:95], v[172:175], v[212:215], v[80:95]
	v_mfma_f32_32x32x16_bf16 v[16:31], v[178:181], v[212:215], v[16:31]
	s_waitcnt lgkmcnt(0)
	v_mfma_f32_32x32x16_bf16 v[64:79], v[172:175], v[216:219], v[64:79]
	v_mfma_f32_32x32x16_bf16 v[0:15], v[178:181], v[216:219], v[0:15]
	s_setprio 0
	global_load_dwordx4 v[144:147], v[144:145], off offset:3968
	s_nop 0
	global_load_dwordx4 v[148:151], v[148:149], off offset:3968
	s_waitcnt vmcnt(9)
	ds_write_b128 v191, v[158:161] offset:18432
	s_waitcnt vmcnt(8)
	ds_write_b128 v191, v[162:165] offset:55296
	ds_read_b128 v[158:161], v169 offset:64
	ds_read_b128 v[162:165], v169 offset:4672
	ds_read_b128 v[172:175], v168 offset:64
	ds_read_b128 v[178:181], v168 offset:4672
	s_setprio 1
	s_waitcnt lgkmcnt(1)
	v_mfma_f32_32x32x16_bf16 v[112:127], v[158:161], v[172:175], v[112:127]
	v_mfma_f32_32x32x16_bf16 v[48:63], v[162:165], v[172:175], v[48:63]
	s_waitcnt lgkmcnt(0)
	v_mfma_f32_32x32x16_bf16 v[96:111], v[158:161], v[178:181], v[96:111]
	v_mfma_f32_32x32x16_bf16 v[32:47], v[162:165], v[178:181], v[32:47]
	ds_read_b128 v[172:175], v168 offset:9280
	ds_read_b128 v[178:181], v168 offset:13888
	s_waitcnt lgkmcnt(1)
	v_mfma_f32_32x32x16_bf16 v[80:95], v[158:161], v[172:175], v[80:95]
	v_mfma_f32_32x32x16_bf16 v[16:31], v[162:165], v[172:175], v[16:31]
	s_waitcnt lgkmcnt(0)
	v_mfma_f32_32x32x16_bf16 v[64:79], v[158:161], v[178:181], v[64:79]
	v_mfma_f32_32x32x16_bf16 v[0:15], v[162:165], v[178:181], v[0:15]
	s_setprio 0
	global_load_dwordx4 v[152:155], v[152:153], off offset:3968
	s_nop 0
	global_load_dwordx4 v[156:159], v[156:157], off offset:3968
	s_waitcnt vmcnt(9)
	ds_write_b128 v191, v[200:203] offset:27648
	s_waitcnt vmcnt(8)
	ds_write_b128 v191, v[208:211] offset:64512
	ds_read_b128 v[160:163], v169 offset:96
	ds_read_b128 v[164:167], v169 offset:4704
	ds_read_b128 v[172:175], v168 offset:96
	ds_read_b128 v[178:181], v168 offset:4704
	s_setprio 1
	s_waitcnt lgkmcnt(1)
	v_mfma_f32_32x32x16_bf16 v[112:127], v[160:163], v[172:175], v[112:127]
	v_mfma_f32_32x32x16_bf16 v[48:63], v[164:167], v[172:175], v[48:63]
	s_waitcnt lgkmcnt(0)
	v_mfma_f32_32x32x16_bf16 v[96:111], v[160:163], v[178:181], v[96:111]
	v_mfma_f32_32x32x16_bf16 v[32:47], v[164:167], v[178:181], v[32:47]
	ds_read_b128 v[172:175], v168 offset:9312
	ds_read_b128 v[178:181], v168 offset:13920
	s_waitcnt lgkmcnt(1)
	v_mfma_f32_32x32x16_bf16 v[80:95], v[160:163], v[172:175], v[80:95]
	v_mfma_f32_32x32x16_bf16 v[16:31], v[164:167], v[172:175], v[16:31]
	s_waitcnt lgkmcnt(0)
	v_mfma_f32_32x32x16_bf16 v[64:79], v[160:163], v[178:181], v[64:79]
	v_mfma_f32_32x32x16_bf16 v[0:15], v[164:167], v[178:181], v[0:15]
	s_setprio 0
	s_and_b64 vcc, exec, s[10:11]
	s_barrier
	s_waitcnt vmcnt(7)
	ds_write_b128 v195, v[128:131]
	s_waitcnt vmcnt(6)
	ds_write_b128 v196, v[132:135]
	s_cbranch_vccnz .LBB0_1639
	global_load_dwordx4 v[128:131], v[188:189], off
	global_load_dwordx4 v[132:135], v[186:187], off
